# GEMM MMA segments without any s_setprio (equal priority for the MFMA and loading waves)
# speedup vs baseline: 1.0064x; 1.0012x over previous
; #define G_STAGE(bufoff, gbase, voff) do { _Pragma("unroll") for (int _i = 0; _i < 2; ++_i) \
;         __builtin_amdgcn_global_load_lds((const unsigned*)((const char*)(gbase) + voff[_i]), (LAS unsigned*)(lds + (bufoff) + ldsw + _i * 8192), 16, 0, 0); } while (0)
; #define G_LDA(dst, b, h) do { _Pragma("unroll") for (int m = 0; m < 4; ++m) _Pragma("unroll") for (int k = 0; k < 2; ++k) dst[m][k] = *(const LAS bf16x8*)(lds + G_SA(b, h) + aoff + m * 2048 + k * 1024); } while (0)
; #define G_LDB(dst, b, h) do { _Pragma("unroll") for (int n = 0; n < 2; ++n) _Pragma("unroll") for (int k = 0; k < 2; ++k) dst[n][k] = *(const LAS bf16x8*)(lds + G_SB(b, h) + boff + n * 2048 + k * 1024); } while (0)
; #define G_MMA(ai, bj, At_, Bt_) do { __builtin_amdgcn_s_setprio(1); _Pragma("unroll") for (int m = 0; m < 4; ++m) _Pragma("unroll") for (int n = 0; n < 2; ++n) _Pragma("unroll") for (int k = 0; k < 2; ++k) \
;         acc[ai][bj][m][n] = __builtin_amdgcn_mfma_f32_16x16x32_bf16(Bt_[n][k], At_[m][k], acc[ai][bj][m][n], 0, 0, 0); __builtin_amdgcn_s_setprio(0); } while (0)
; #define WAIT_V(n) asm volatile("s_waitcnt vmcnt(" #n ")" ::: "memory")
; #define WAIT_L(n) asm volatile("s_waitcnt lgkmcnt(" #n ")" ::: "memory")
; #define BAR __builtin_amdgcn_s_barrier()
; template <class Get, class Epi>
; DI void gemm_loop(int ntiles, int ld, char* shm, const Get& get, const Epi& epi) {
;     ...
;         const int Ln = L + gridDim.x; const bool has_next = Ln < ntiles; if (has_next) nxt = get(Ln);
;         const char* nA = has_next ? (const char*)nxt.A + (size_t)nxt.brow * ld * 2 : cA; const char* nB = has_next ? (const char*)nxt.Bt + (size_t)nxt.bcol * ld * 2 : cB;
;         const int nt = cur.K / BK;
;         for (int t = 0; t < nt; t += 2) {
;             const bool last = (t == nt - 2);
;             const char* a1 = cA + (size_t)(t + 1) * kstep;
;             const char* a2 = last ? nA : cA + (size_t)(t + 2) * kstep; const char* b2 = last ? nB : cB + (size_t)(t + 2) * kstep;
;             const char* a3 = a2 + kstep; const char* b3 = b2 + kstep;
;             G_LDB(B0, 0, 0); G_LDB(B1, 0, 1); SCHED; G_LDA(At, 0, 0); G_STAGE(G_SA(1, 1), a1 + hstep, voffA);
;             WAIT_V(8); WAIT_L(0); BAR; G_MMA(0, 0, At, B0); G_MMA(0, 1, At, B1); BAR; SCHED;
;             G_LDA(At, 0, 1); G_STAGE(G_SB(0, 0), b2, voffB); G_STAGE(G_SB(0, 1), b2 + hstep, voffB); G_STAGE(G_SA(0, 0), a2, voffA);
.LBB0_332:
	ds_read_b128 v[0:3], v142
	ds_read_b128 v[4:7], v142 offset:1024
	ds_read_b128 v[8:11], v142 offset:2048
	ds_read_b128 v[12:15], v142 offset:3072
	ds_read_b128 v[16:19], v143
	ds_read_b128 v[20:23], v143 offset:1024
	ds_read_b128 v[24:27], v143 offset:2048
	ds_read_b128 v[28:31], v143 offset:3072
	s_ashr_i32 s37, s36, 31
	s_lshl_b64 s[42:43], s[36:37], 11
	s_add_u32 s42, s73, s42
	s_addc_u32 s43, s74, s43
	s_and_b64 s[44:45], s[38:39], exec
	s_cselect_b32 s55, s43, s15
	s_cselect_b32 s54, s42, s14
	s_ashr_i32 s41, s40, 31
	s_lshl_b64 s[44:45], s[40:41], 11
	s_add_u32 s44, s59, s44
	s_addc_u32 s45, s72, s45
	s_and_b64 s[46:47], s[38:39], exec
	s_cselect_b32 s47, s45, s51
	s_cselect_b32 s46, s44, s50
	s_add_u32 s94, s14, 0x40080
	s_addc_u32 s95, s15, 0
	s_mov_b32 m0, s81
	v_lshl_add_u64 v[64:65], s[94:95], 0, v[134:135]
	ds_read_b128 v[32:35], v144
	ds_read_b128 v[36:39], v144 offset:1024
	ds_read_b128 v[40:43], v144 offset:2048
	ds_read_b128 v[44:47], v144 offset:3072
	ds_read_b128 v[48:51], v144 offset:4096
	ds_read_b128 v[52:55], v144 offset:5120
	ds_read_b128 v[56:59], v144 offset:6144
	ds_read_b128 v[60:63], v144 offset:7168
	global_load_lds_dwordx4 v[64:65], off
	v_lshl_add_u64 v[64:65], s[94:95], 0, v[130:131]
	s_mov_b32 m0, s82
	s_nop 0
	global_load_lds_dwordx4 v[64:65], off
	s_waitcnt vmcnt(8)
	s_waitcnt lgkmcnt(0)
	s_barrier
	s_waitcnt lgkmcnt(0)
	v_mfma_f32_16x16x32_bf16 v[64:67], v[0:3], v[32:35], 0
	v_mfma_f32_16x16x32_bf16 v[68:71], v[8:11], v[32:35], 0
	v_mfma_f32_16x16x32_bf16 v[72:75], v[0:3], v[40:43], 0
	v_mfma_f32_16x16x32_bf16 v[76:79], v[8:11], v[40:43], 0
	v_mfma_f32_16x16x32_bf16 v[80:83], v[0:3], v[48:51], 0
	v_mfma_f32_16x16x32_bf16 v[84:87], v[8:11], v[48:51], 0
	v_mfma_f32_16x16x32_bf16 v[88:91], v[0:3], v[56:59], 0
	v_mfma_f32_16x16x32_bf16 v[92:95], v[8:11], v[56:59], 0
	v_mfma_f32_16x16x32_bf16 v[64:67], v[4:7], v[36:39], v[64:67]
	v_mfma_f32_16x16x32_bf16 v[68:71], v[12:15], v[36:39], v[68:71]
	v_mfma_f32_16x16x32_bf16 v[72:75], v[4:7], v[44:47], v[72:75]
	v_mfma_f32_16x16x32_bf16 v[76:79], v[12:15], v[44:47], v[76:79]
	v_mfma_f32_16x16x32_bf16 v[80:83], v[4:7], v[52:55], v[80:83]
	v_mfma_f32_16x16x32_bf16 v[84:87], v[12:15], v[52:55], v[84:87]
	v_mfma_f32_16x16x32_bf16 v[88:91], v[4:7], v[60:63], v[88:91]
	v_mfma_f32_16x16x32_bf16 v[92:95], v[12:15], v[60:63], v[92:95]
	v_mfma_f32_16x16x32_bf16 v[96:99], v[16:19], v[32:35], 0
	v_mfma_f32_16x16x32_bf16 v[32:35], v[24:27], v[32:35], 0
	v_mfma_f32_16x16x32_bf16 v[96:99], v[20:23], v[36:39], v[96:99]
	v_mfma_f32_16x16x32_bf16 v[32:35], v[28:31], v[36:39], v[32:35]
	v_mfma_f32_16x16x32_bf16 v[36:39], v[16:19], v[40:43], 0
	v_mfma_f32_16x16x32_bf16 v[40:43], v[24:27], v[40:43], 0
	v_mfma_f32_16x16x32_bf16 v[36:39], v[20:23], v[44:47], v[36:39]
	v_mfma_f32_16x16x32_bf16 v[40:43], v[28:31], v[44:47], v[40:43]
	v_mfma_f32_16x16x32_bf16 v[44:47], v[16:19], v[48:51], 0
	v_mfma_f32_16x16x32_bf16 v[48:51], v[24:27], v[48:51], 0
	v_mfma_f32_16x16x32_bf16 v[44:47], v[20:23], v[52:55], v[44:47]
	v_mfma_f32_16x16x32_bf16 v[48:51], v[28:31], v[52:55], v[48:51]
	v_mfma_f32_16x16x32_bf16 v[52:55], v[16:19], v[56:59], 0
	v_mfma_f32_16x16x32_bf16 v[56:59], v[24:27], v[56:59], 0
	v_mfma_f32_16x16x32_bf16 v[52:55], v[20:23], v[60:63], v[52:55]
	v_mfma_f32_16x16x32_bf16 v[56:59], v[28:31], v[60:63], v[56:59]
	s_barrier
	v_lshl_add_u64 v[140:141], s[50:51], 0, v[132:133]
	s_mov_b32 m0, s83
	v_lshl_add_u64 v[136:137], v[140:141], 0, s[28:29]
	v_lshl_add_u64 v[184:185], s[50:51], 0, v[128:129]
	s_add_u32 s94, s50, 0x40100
	ds_read_b128 v[60:63], v144 offset:16384
	ds_read_b128 v[100:103], v144 offset:17408
	ds_read_b128 v[104:107], v144 offset:18432
	ds_read_b128 v[108:111], v144 offset:19456
	ds_read_b128 v[112:115], v144 offset:20480
	ds_read_b128 v[116:119], v144 offset:21504
	ds_read_b128 v[120:123], v144 offset:22528
	ds_read_b128 v[124:127], v144 offset:23552
	global_load_lds_dwordx4 v[136:137], off
	v_lshl_add_u64 v[136:137], v[184:185], 0, s[28:29]
	s_mov_b32 m0, s84
	s_addc_u32 s95, s51, 0
	global_load_lds_dwordx4 v[136:137], off
	v_lshl_add_u64 v[136:137], s[94:95], 0, v[132:133]
	s_mov_b32 m0, s85
	v_lshl_add_u64 v[186:187], s[14:15], 0, v[134:135]
	global_load_lds_dwordx4 v[136:137], off
	v_lshl_add_u64 v[136:137], s[94:95], 0, v[128:129]
	s_mov_b32 m0, s86
	v_lshl_add_u64 v[212:213], s[14:15], 0, v[130:131]
	global_load_lds_dwordx4 v[136:137], off
	v_lshl_add_u64 v[136:137], v[186:187], 0, s[28:29]
	s_mov_b32 m0, s58
	s_nop 0
	global_load_lds_dwordx4 v[136:137], off
	v_lshl_add_u64 v[136:137], v[212:213], 0, s[28:29]
	s_mov_b32 m0, s75
	s_nop 0
	global_load_lds_dwordx4 v[136:137], off
	s_waitcnt vmcnt(8)
	s_waitcnt lgkmcnt(0)
	s_barrier
; #define G_STAGE(bufoff, gbase, voff) do { _Pragma("unroll") for (int _i = 0; _i < 2; ++_i) \
;         __builtin_amdgcn_global_load_lds((const unsigned*)((const char*)(gbase) + voff[_i]), (LAS unsigned*)(lds + (bufoff) + ldsw + _i * 8192), 16, 0, 0); } while (0)
; #define G_LDA(dst, b, h) do { _Pragma("unroll") for (int m = 0; m < 4; ++m) _Pragma("unroll") for (int k = 0; k < 2; ++k) dst[m][k] = *(const LAS bf16x8*)(lds + G_SA(b, h) + aoff + m * 2048 + k * 1024); } while (0)
; #define G_LDB(dst, b, h) do { _Pragma("unroll") for (int n = 0; n < 2; ++n) _Pragma("unroll") for (int k = 0; k < 2; ++k) dst[n][k] = *(const LAS bf16x8*)(lds + G_SB(b, h) + boff + n * 2048 + k * 1024); } while (0)
; #define G_MMA(ai, bj, At_, Bt_) do { __builtin_amdgcn_s_setprio(1); _Pragma("unroll") for (int m = 0; m < 4; ++m) _Pragma("unroll") for (int n = 0; n < 2; ++n) _Pragma("unroll") for (int k = 0; k < 2; ++k) \
;         acc[ai][bj][m][n] = __builtin_amdgcn_mfma_f32_16x16x32_bf16(Bt_[n][k], At_[m][k], acc[ai][bj][m][n], 0, 0, 0); __builtin_amdgcn_s_setprio(0); } while (0)
; #define WAIT_V(n) asm volatile("s_waitcnt vmcnt(" #n ")" ::: "memory")
; #define WAIT_L(n) asm volatile("s_waitcnt lgkmcnt(" #n ")" ::: "memory")
; #define BAR __builtin_amdgcn_s_barrier()
; #define SCHED __builtin_amdgcn_sched_barrier(0)
; template <class Get, class Epi>
; DI void gemm_loop(int ntiles, int ld, char* shm, const Get& get, const Epi& epi) {
;     ...
;             WAIT_V(8); WAIT_L(0); BAR; G_MMA(1, 0, At, B0); G_MMA(1, 1, At, B1); BAR; SCHED;
;             G_LDB(B0, 1, 0); G_LDB(B1, 1, 1); SCHED; G_LDA(At, 1, 0); G_STAGE(G_SA(0, 1), a2 + hstep, voffA);
;             WAIT_V(8); WAIT_L(0); BAR; G_MMA(0, 0, At, B0); G_MMA(0, 1, At, B1); BAR; SCHED;
	s_waitcnt lgkmcnt(0)
	v_mfma_f32_16x16x32_bf16 v[136:139], v[0:3], v[60:63], 0
	v_mfma_f32_16x16x32_bf16 v[152:155], v[0:3], v[104:107], 0
	v_mfma_f32_16x16x32_bf16 v[160:163], v[0:3], v[112:115], 0
	v_mfma_f32_16x16x32_bf16 v[0:3], v[0:3], v[120:123], 0
	v_mfma_f32_16x16x32_bf16 v[136:139], v[4:7], v[100:103], v[136:139]
	v_mfma_f32_16x16x32_bf16 v[152:155], v[4:7], v[108:111], v[152:155]
	v_mfma_f32_16x16x32_bf16 v[160:163], v[4:7], v[116:119], v[160:163]
	v_mfma_f32_16x16x32_bf16 v[0:3], v[4:7], v[124:127], v[0:3]
	v_mfma_f32_16x16x32_bf16 v[4:7], v[8:11], v[120:123], 0
	v_mfma_f32_16x16x32_bf16 v[148:151], v[8:11], v[60:63], 0
	v_mfma_f32_16x16x32_bf16 v[156:159], v[8:11], v[104:107], 0
	v_mfma_f32_16x16x32_bf16 v[164:167], v[8:11], v[112:115], 0
	v_mfma_f32_16x16x32_bf16 v[4:7], v[12:15], v[124:127], v[4:7]
	v_mfma_f32_16x16x32_bf16 v[148:151], v[12:15], v[100:103], v[148:151]
	v_mfma_f32_16x16x32_bf16 v[156:159], v[12:15], v[108:111], v[156:159]
	v_mfma_f32_16x16x32_bf16 v[164:167], v[12:15], v[116:119], v[164:167]
	v_mfma_f32_16x16x32_bf16 v[8:11], v[16:19], v[60:63], 0
	v_mfma_f32_16x16x32_bf16 v[12:15], v[24:27], v[60:63], 0
	v_mfma_f32_16x16x32_bf16 v[8:11], v[20:23], v[100:103], v[8:11]
	v_mfma_f32_16x16x32_bf16 v[12:15], v[28:31], v[100:103], v[12:15]
	v_mfma_f32_16x16x32_bf16 v[60:63], v[16:19], v[104:107], 0
	v_mfma_f32_16x16x32_bf16 v[100:103], v[24:27], v[104:107], 0
	v_mfma_f32_16x16x32_bf16 v[104:107], v[16:19], v[112:115], 0
	v_mfma_f32_16x16x32_bf16 v[16:19], v[16:19], v[120:123], 0
	v_mfma_f32_16x16x32_bf16 v[60:63], v[20:23], v[108:111], v[60:63]
	v_mfma_f32_16x16x32_bf16 v[100:103], v[28:31], v[108:111], v[100:103]
	v_mfma_f32_16x16x32_bf16 v[104:107], v[20:23], v[116:119], v[104:107]
	v_mfma_f32_16x16x32_bf16 v[108:111], v[24:27], v[112:115], 0
	v_mfma_f32_16x16x32_bf16 v[16:19], v[20:23], v[124:127], v[16:19]
	v_mfma_f32_16x16x32_bf16 v[20:23], v[24:27], v[120:123], 0
	v_mfma_f32_16x16x32_bf16 v[108:111], v[28:31], v[116:119], v[108:111]
	v_mfma_f32_16x16x32_bf16 v[20:23], v[28:31], v[124:127], v[20:23]
	s_barrier
	ds_read_b128 v[24:27], v145
	ds_read_b128 v[28:31], v145 offset:1024
	ds_read_b128 v[112:115], v145 offset:2048
	ds_read_b128 v[116:119], v145 offset:3072
	ds_read_b128 v[120:123], v146
	ds_read_b128 v[124:127], v146 offset:1024
	ds_read_b128 v[168:171], v146 offset:2048
	ds_read_b128 v[172:175], v146 offset:3072
	s_add_u32 s94, s14, 0x40100
	s_addc_u32 s95, s15, 0
	s_mov_b32 m0, s76
	v_lshl_add_u64 v[214:215], s[94:95], 0, v[134:135]
	ds_read_b128 v[176:179], v144 offset:32768
	ds_read_b128 v[180:183], v144 offset:33792
	ds_read_b128 v[188:191], v144 offset:34816
	ds_read_b128 v[192:195], v144 offset:35840
	ds_read_b128 v[196:199], v144 offset:36864
	ds_read_b128 v[200:203], v144 offset:37888
	ds_read_b128 v[204:207], v144 offset:38912
	ds_read_b128 v[208:211], v144 offset:39936
	global_load_lds_dwordx4 v[214:215], off
	v_lshl_add_u64 v[214:215], s[94:95], 0, v[130:131]
	s_mov_b32 m0, s78
	s_nop 0
	global_load_lds_dwordx4 v[214:215], off
	s_waitcnt vmcnt(8)
	s_waitcnt lgkmcnt(0)
	s_barrier
	s_waitcnt lgkmcnt(0)
	v_mfma_f32_16x16x32_bf16 v[64:67], v[24:27], v[176:179], v[64:67]
	v_mfma_f32_16x16x32_bf16 v[68:71], v[112:115], v[176:179], v[68:71]
	v_mfma_f32_16x16x32_bf16 v[72:75], v[24:27], v[188:191], v[72:75]
	v_mfma_f32_16x16x32_bf16 v[76:79], v[112:115], v[188:191], v[76:79]
	v_mfma_f32_16x16x32_bf16 v[80:83], v[24:27], v[196:199], v[80:83]
	v_mfma_f32_16x16x32_bf16 v[84:87], v[112:115], v[196:199], v[84:87]
	v_mfma_f32_16x16x32_bf16 v[88:91], v[24:27], v[204:207], v[88:91]
	v_mfma_f32_16x16x32_bf16 v[92:95], v[112:115], v[204:207], v[92:95]
	v_mfma_f32_16x16x32_bf16 v[64:67], v[28:31], v[180:183], v[64:67]
	v_mfma_f32_16x16x32_bf16 v[68:71], v[116:119], v[180:183], v[68:71]
	v_mfma_f32_16x16x32_bf16 v[72:75], v[28:31], v[192:195], v[72:75]
	v_mfma_f32_16x16x32_bf16 v[76:79], v[116:119], v[192:195], v[76:79]
	v_mfma_f32_16x16x32_bf16 v[80:83], v[28:31], v[200:203], v[80:83]
	v_mfma_f32_16x16x32_bf16 v[84:87], v[116:119], v[200:203], v[84:87]
	v_mfma_f32_16x16x32_bf16 v[88:91], v[28:31], v[208:211], v[88:91]
	v_mfma_f32_16x16x32_bf16 v[92:95], v[116:119], v[208:211], v[92:95]
	v_mfma_f32_16x16x32_bf16 v[96:99], v[120:123], v[176:179], v[96:99]
	v_mfma_f32_16x16x32_bf16 v[32:35], v[168:171], v[176:179], v[32:35]
	v_mfma_f32_16x16x32_bf16 v[36:39], v[120:123], v[188:191], v[36:39]
	v_mfma_f32_16x16x32_bf16 v[40:43], v[168:171], v[188:191], v[40:43]
	v_mfma_f32_16x16x32_bf16 v[44:47], v[120:123], v[196:199], v[44:47]
	v_mfma_f32_16x16x32_bf16 v[48:51], v[168:171], v[196:199], v[48:51]
	v_mfma_f32_16x16x32_bf16 v[52:55], v[120:123], v[204:207], v[52:55]
	v_mfma_f32_16x16x32_bf16 v[56:59], v[168:171], v[204:207], v[56:59]
	v_mfma_f32_16x16x32_bf16 v[96:99], v[124:127], v[180:183], v[96:99]
	v_mfma_f32_16x16x32_bf16 v[32:35], v[172:175], v[180:183], v[32:35]
	v_mfma_f32_16x16x32_bf16 v[36:39], v[124:127], v[192:195], v[36:39]
	v_mfma_f32_16x16x32_bf16 v[40:43], v[172:175], v[192:195], v[40:43]
	v_mfma_f32_16x16x32_bf16 v[44:47], v[124:127], v[200:203], v[44:47]
	v_mfma_f32_16x16x32_bf16 v[48:51], v[172:175], v[200:203], v[48:51]
	v_mfma_f32_16x16x32_bf16 v[52:55], v[124:127], v[208:211], v[52:55]
	v_mfma_f32_16x16x32_bf16 v[56:59], v[172:175], v[208:211], v[56:59]
	s_barrier
; #define G_STAGE(bufoff, gbase, voff) do { _Pragma("unroll") for (int _i = 0; _i < 2; ++_i) \
;         __builtin_amdgcn_global_load_lds((const unsigned*)((const char*)(gbase) + voff[_i]), (LAS unsigned*)(lds + (bufoff) + ldsw + _i * 8192), 16, 0, 0); } while (0)
; #define G_LDA(dst, b, h) do { _Pragma("unroll") for (int m = 0; m < 4; ++m) _Pragma("unroll") for (int k = 0; k < 2; ++k) dst[m][k] = *(const LAS bf16x8*)(lds + G_SA(b, h) + aoff + m * 2048 + k * 1024); } while (0)
; #define G_LDB(dst, b, h) do { _Pragma("unroll") for (int n = 0; n < 2; ++n) _Pragma("unroll") for (int k = 0; k < 2; ++k) dst[n][k] = *(const LAS bf16x8*)(lds + G_SB(b, h) + boff + n * 2048 + k * 1024); } while (0)
; #define WAIT_V(n) asm volatile("s_waitcnt vmcnt(" #n ")" ::: "memory")
; #define WAIT_L(n) asm volatile("s_waitcnt lgkmcnt(" #n ")" ::: "memory")
; #define BAR __builtin_amdgcn_s_barrier()
; #define SCHED __builtin_amdgcn_sched_barrier(0)
; template <class Get, class Epi>
; DI void gemm_loop(int ntiles, int ld, char* shm, const Get& get, const Epi& epi) {
;     ...
;         for (int t = 0; t < nt; t += 2) {
;             const bool last = (t == nt - 2);
;             const char* a1 = cA + (size_t)(t + 1) * kstep;
;             const char* a2 = last ? nA : cA + (size_t)(t + 2) * kstep; const char* b2 = last ? nB : cB + (size_t)(t + 2) * kstep;
;             const char* a3 = a2 + kstep; const char* b3 = b2 + kstep;
;             G_LDB(B0, 0, 0); G_LDB(B1, 0, 1); SCHED; G_LDA(At, 0, 0); G_STAGE(G_SA(1, 1), a1 + hstep, voffA);
;             WAIT_V(8); WAIT_L(0); BAR; G_MMA(0, 0, At, B0); G_MMA(0, 1, At, B1); BAR; SCHED;
;             G_LDA(At, 0, 1); G_STAGE(G_SB(0, 0), b2, voffB); G_STAGE(G_SB(0, 1), b2 + hstep, voffB); G_STAGE(G_SA(0, 0), a2, voffA);
;             WAIT_V(8); WAIT_L(0); BAR; G_MMA(1, 0, At, B0); G_MMA(1, 1, At, B1); BAR; SCHED;
;             G_LDB(B0, 1, 0); G_LDB(B1, 1, 1); SCHED; G_LDA(At, 1, 0); G_STAGE(G_SA(0, 1), a2 + hstep, voffA);
;             WAIT_V(8); WAIT_L(0); BAR; G_MMA(0, 0, At, B0); G_MMA(0, 1, At, B1); BAR; SCHED;
;             G_LDA(At, 1, 1); G_STAGE(G_SB(1, 0), b3, voffB); G_STAGE(G_SB(1, 1), b3 + hstep, voffB); G_STAGE(G_SA(1, 0), a3, voffA);
;             WAIT_V(8); WAIT_L(0); BAR; G_MMA(1, 0, At, B0); G_MMA(1, 1, At, B1); BAR; SCHED;
	s_mov_b32 m0, s87
	v_lshl_add_u64 v[140:141], v[140:141], 0, s[30:31]
	s_add_u32 s50, s50, 0x40180
	ds_read_b128 v[176:179], v144 offset:49152
	ds_read_b128 v[180:183], v144 offset:50176
	ds_read_b128 v[188:191], v144 offset:51200
	ds_read_b128 v[192:195], v144 offset:52224
	ds_read_b128 v[196:199], v144 offset:53248
	ds_read_b128 v[200:203], v144 offset:54272
	ds_read_b128 v[204:207], v144 offset:55296
	ds_read_b128 v[208:211], v144 offset:56320
	global_load_lds_dwordx4 v[140:141], off
	v_lshl_add_u64 v[140:141], v[184:185], 0, s[30:31]
	s_mov_b32 m0, s88
	s_addc_u32 s51, s51, 0
	global_load_lds_dwordx4 v[140:141], off
	v_lshl_add_u64 v[140:141], s[50:51], 0, v[132:133]
	s_mov_b32 m0, s89
	s_nop 0
	global_load_lds_dwordx4 v[140:141], off
	v_lshl_add_u64 v[140:141], s[50:51], 0, v[128:129]
	s_mov_b32 m0, s90
	s_nop 0
	global_load_lds_dwordx4 v[140:141], off
	v_lshl_add_u64 v[140:141], v[186:187], 0, s[30:31]
	s_mov_b32 m0, s79
	s_nop 0
	global_load_lds_dwordx4 v[140:141], off
	v_lshl_add_u64 v[140:141], v[212:213], 0, s[30:31]
	s_mov_b32 m0, s80
	s_nop 0
	global_load_lds_dwordx4 v[140:141], off
	s_waitcnt vmcnt(8)
	s_waitcnt lgkmcnt(0)
	s_barrier
	s_waitcnt lgkmcnt(0)
	v_mfma_f32_16x16x32_bf16 v[0:3], v[24:27], v[204:207], v[0:3]
	v_mfma_f32_16x16x32_bf16 v[4:7], v[112:115], v[204:207], v[4:7]
	v_mfma_f32_16x16x32_bf16 v[136:139], v[24:27], v[176:179], v[136:139]
	v_mfma_f32_16x16x32_bf16 v[148:151], v[112:115], v[176:179], v[148:151]
	v_mfma_f32_16x16x32_bf16 v[152:155], v[24:27], v[188:191], v[152:155]
	v_mfma_f32_16x16x32_bf16 v[156:159], v[112:115], v[188:191], v[156:159]
	v_mfma_f32_16x16x32_bf16 v[160:163], v[24:27], v[196:199], v[160:163]
	v_mfma_f32_16x16x32_bf16 v[164:167], v[112:115], v[196:199], v[164:167]
	v_mfma_f32_16x16x32_bf16 v[0:3], v[28:31], v[208:211], v[0:3]
	v_mfma_f32_16x16x32_bf16 v[4:7], v[116:119], v[208:211], v[4:7]
	v_mfma_f32_16x16x32_bf16 v[136:139], v[28:31], v[180:183], v[136:139]
	v_mfma_f32_16x16x32_bf16 v[148:151], v[116:119], v[180:183], v[148:151]
	v_mfma_f32_16x16x32_bf16 v[152:155], v[28:31], v[192:195], v[152:155]
	v_mfma_f32_16x16x32_bf16 v[156:159], v[116:119], v[192:195], v[156:159]
	v_mfma_f32_16x16x32_bf16 v[160:163], v[28:31], v[200:203], v[160:163]
	v_mfma_f32_16x16x32_bf16 v[164:167], v[116:119], v[200:203], v[164:167]
	v_mfma_f32_16x16x32_bf16 v[8:11], v[120:123], v[176:179], v[8:11]
	v_mfma_f32_16x16x32_bf16 v[12:15], v[168:171], v[176:179], v[12:15]
	v_mfma_f32_16x16x32_bf16 v[24:27], v[120:123], v[188:191], v[60:63]
	v_mfma_f32_16x16x32_bf16 v[28:31], v[168:171], v[188:191], v[100:103]
	v_mfma_f32_16x16x32_bf16 v[60:63], v[120:123], v[196:199], v[104:107]
	v_mfma_f32_16x16x32_bf16 v[100:103], v[168:171], v[196:199], v[108:111]
	v_mfma_f32_16x16x32_bf16 v[16:19], v[120:123], v[204:207], v[16:19]
	v_mfma_f32_16x16x32_bf16 v[20:23], v[168:171], v[204:207], v[20:23]
	v_mfma_f32_16x16x32_bf16 v[8:11], v[124:127], v[180:183], v[8:11]
	v_mfma_f32_16x16x32_bf16 v[12:15], v[172:175], v[180:183], v[12:15]
	v_mfma_f32_16x16x32_bf16 v[24:27], v[124:127], v[192:195], v[24:27]
	v_mfma_f32_16x16x32_bf16 v[28:31], v[172:175], v[192:195], v[28:31]
	v_mfma_f32_16x16x32_bf16 v[60:63], v[124:127], v[200:203], v[60:63]
	v_mfma_f32_16x16x32_bf16 v[100:103], v[172:175], v[200:203], v[100:103]
	v_mfma_f32_16x16x32_bf16 v[16:19], v[124:127], v[208:211], v[16:19]
	v_mfma_f32_16x16x32_bf16 v[20:23], v[172:175], v[208:211], v[20:23]
	s_barrier
	ds_read_b128 v[104:107], v142
	ds_read_b128 v[108:111], v142 offset:1024
	ds_read_b128 v[112:115], v142 offset:2048
	ds_read_b128 v[116:119], v142 offset:3072
	ds_read_b128 v[120:123], v143
	ds_read_b128 v[124:127], v143 offset:1024
	ds_read_b128 v[168:171], v143 offset:2048
	ds_read_b128 v[172:175], v143 offset:3072
	s_add_u32 s14, s14, 0x40180
	s_addc_u32 s15, s15, 0
	s_mov_b32 m0, s81
	v_lshl_add_u64 v[140:141], s[14:15], 0, v[134:135]
	ds_read_b128 v[176:179], v144
	ds_read_b128 v[180:183], v144 offset:1024
	ds_read_b128 v[188:191], v144 offset:2048
	ds_read_b128 v[192:195], v144 offset:3072
	ds_read_b128 v[196:199], v144 offset:4096
	ds_read_b128 v[200:203], v144 offset:5120
	ds_read_b128 v[204:207], v144 offset:6144
	ds_read_b128 v[208:211], v144 offset:7168
	global_load_lds_dwordx4 v[140:141], off
	v_lshl_add_u64 v[140:141], s[14:15], 0, v[130:131]
	s_mov_b32 m0, s82
	s_nop 0
	global_load_lds_dwordx4 v[140:141], off
	s_waitcnt vmcnt(8)
	s_waitcnt lgkmcnt(0)
	s_barrier
	s_waitcnt lgkmcnt(0)
	v_mfma_f32_16x16x32_bf16 v[64:67], v[104:107], v[176:179], v[64:67]
	v_mfma_f32_16x16x32_bf16 v[68:71], v[112:115], v[176:179], v[68:71]
	v_mfma_f32_16x16x32_bf16 v[72:75], v[104:107], v[188:191], v[72:75]
	v_mfma_f32_16x16x32_bf16 v[76:79], v[112:115], v[188:191], v[76:79]
	v_mfma_f32_16x16x32_bf16 v[80:83], v[104:107], v[196:199], v[80:83]
	v_mfma_f32_16x16x32_bf16 v[84:87], v[112:115], v[196:199], v[84:87]
	v_mfma_f32_16x16x32_bf16 v[88:91], v[104:107], v[204:207], v[88:91]
	v_mfma_f32_16x16x32_bf16 v[92:95], v[112:115], v[204:207], v[92:95]
	v_mfma_f32_16x16x32_bf16 v[64:67], v[108:111], v[180:183], v[64:67]
	v_mfma_f32_16x16x32_bf16 v[68:71], v[116:119], v[180:183], v[68:71]
	v_mfma_f32_16x16x32_bf16 v[72:75], v[108:111], v[192:195], v[72:75]
	v_mfma_f32_16x16x32_bf16 v[76:79], v[116:119], v[192:195], v[76:79]
	v_mfma_f32_16x16x32_bf16 v[80:83], v[108:111], v[200:203], v[80:83]
	v_mfma_f32_16x16x32_bf16 v[84:87], v[116:119], v[200:203], v[84:87]
	v_mfma_f32_16x16x32_bf16 v[88:91], v[108:111], v[208:211], v[88:91]
	v_mfma_f32_16x16x32_bf16 v[92:95], v[116:119], v[208:211], v[92:95]
	v_mfma_f32_16x16x32_bf16 v[48:51], v[168:171], v[196:199], v[48:51]
	v_mfma_f32_16x16x32_bf16 v[96:99], v[120:123], v[176:179], v[96:99]
	v_mfma_f32_16x16x32_bf16 v[32:35], v[168:171], v[176:179], v[32:35]
	v_mfma_f32_16x16x32_bf16 v[176:179], v[172:175], v[200:203], v[48:51]
	v_mfma_f32_16x16x32_bf16 v[48:51], v[120:123], v[204:207], v[52:55]
	v_mfma_f32_16x16x32_bf16 v[212:215], v[124:127], v[180:183], v[96:99]
	v_mfma_f32_16x16x32_bf16 v[32:35], v[172:175], v[180:183], v[32:35]
	v_mfma_f32_16x16x32_bf16 v[36:39], v[120:123], v[188:191], v[36:39]
	v_mfma_f32_16x16x32_bf16 v[40:43], v[168:171], v[188:191], v[40:43]
	v_mfma_f32_16x16x32_bf16 v[44:47], v[120:123], v[196:199], v[44:47]
	v_mfma_f32_16x16x32_bf16 v[180:183], v[124:127], v[208:211], v[48:51]
	v_mfma_f32_16x16x32_bf16 v[48:51], v[168:171], v[204:207], v[56:59]
	v_mfma_f32_16x16x32_bf16 v[36:39], v[124:127], v[192:195], v[36:39]
	v_mfma_f32_16x16x32_bf16 v[40:43], v[172:175], v[192:195], v[40:43]
	v_mfma_f32_16x16x32_bf16 v[44:47], v[124:127], v[200:203], v[44:47]
	v_mfma_f32_16x16x32_bf16 v[56:59], v[172:175], v[208:211], v[48:51]
	s_barrier
; #define G_STAGE(bufoff, gbase, voff) do { _Pragma("unroll") for (int _i = 0; _i < 2; ++_i) \
;         __builtin_amdgcn_global_load_lds((const unsigned*)((const char*)(gbase) + voff[_i]), (LAS unsigned*)(lds + (bufoff) + ldsw + _i * 8192), 16, 0, 0); } while (0)
; #define G_LDA(dst, b, h) do { _Pragma("unroll") for (int m = 0; m < 4; ++m) _Pragma("unroll") for (int k = 0; k < 2; ++k) dst[m][k] = *(const LAS bf16x8*)(lds + G_SA(b, h) + aoff + m * 2048 + k * 1024); } while (0)
; #define G_LDB(dst, b, h) do { _Pragma("unroll") for (int n = 0; n < 2; ++n) _Pragma("unroll") for (int k = 0; k < 2; ++k) dst[n][k] = *(const LAS bf16x8*)(lds + G_SB(b, h) + boff + n * 2048 + k * 1024); } while (0)
; #define WAIT_V(n) asm volatile("s_waitcnt vmcnt(" #n ")" ::: "memory")
; #define WAIT_L(n) asm volatile("s_waitcnt lgkmcnt(" #n ")" ::: "memory")
; #define BAR __builtin_amdgcn_s_barrier()
; #define SCHED __builtin_amdgcn_sched_barrier(0)
; template <class Get, class Epi>
; DI void gemm_loop(int ntiles, int ld, char* shm, const Get& get, const Epi& epi) {
;     ...
;         for (int t = 0; t < nt; t += 2) {
;             const bool last = (t == nt - 2);
;             const char* a1 = cA + (size_t)(t + 1) * kstep;
;             const char* a2 = last ? nA : cA + (size_t)(t + 2) * kstep; const char* b2 = last ? nB : cB + (size_t)(t + 2) * kstep;
;             const char* a3 = a2 + kstep; const char* b3 = b2 + kstep;
;             G_LDB(B0, 0, 0); G_LDB(B1, 0, 1); SCHED; G_LDA(At, 0, 0); G_STAGE(G_SA(1, 1), a1 + hstep, voffA);
;             WAIT_V(8); WAIT_L(0); BAR; G_MMA(0, 0, At, B0); G_MMA(0, 1, At, B1); BAR; SCHED;
;             G_LDA(At, 0, 1); G_STAGE(G_SB(0, 0), b2, voffB); G_STAGE(G_SB(0, 1), b2 + hstep, voffB); G_STAGE(G_SA(0, 0), a2, voffA);
;             WAIT_V(8); WAIT_L(0); BAR; G_MMA(1, 0, At, B0); G_MMA(1, 1, At, B1); BAR; SCHED;
;             G_LDB(B0, 1, 0); G_LDB(B1, 1, 1); SCHED; G_LDA(At, 1, 0); G_STAGE(G_SA(0, 1), a2 + hstep, voffA);
;             WAIT_V(8); WAIT_L(0); BAR; G_MMA(0, 0, At, B0); G_MMA(0, 1, At, B1); BAR; SCHED;
;             G_LDA(At, 1, 1); G_STAGE(G_SB(1, 0), b3, voffB); G_STAGE(G_SB(1, 1), b3 + hstep, voffB); G_STAGE(G_SA(1, 0), a3, voffA);
;             WAIT_V(8); WAIT_L(0); BAR; G_MMA(1, 0, At, B0); G_MMA(1, 1, At, B1); BAR; SCHED;
	s_mov_b32 m0, s83
	v_lshl_add_u64 v[140:141], s[46:47], 0, v[132:133]
	s_add_u32 s14, s46, 0x40000
	ds_read_b128 v[48:51], v144 offset:16384
	ds_read_b128 v[52:55], v144 offset:17408
	ds_read_b128 v[96:99], v144 offset:18432
	ds_read_b128 v[188:191], v144 offset:19456
	ds_read_b128 v[192:195], v144 offset:20480
	ds_read_b128 v[196:199], v144 offset:21504
	ds_read_b128 v[200:203], v144 offset:22528
	ds_read_b128 v[204:207], v144 offset:23552
	global_load_lds_dwordx4 v[140:141], off
	v_lshl_add_u64 v[184:185], s[46:47], 0, v[128:129]
	s_mov_b32 m0, s84
	s_addc_u32 s15, s47, 0
	global_load_lds_dwordx4 v[184:185], off
	v_lshl_add_u64 v[186:187], s[14:15], 0, v[132:133]
	s_mov_b32 m0, s85
	v_lshl_add_u64 v[248:249], s[54:55], 0, v[130:131]
	global_load_lds_dwordx4 v[186:187], off
	v_lshl_add_u64 v[186:187], s[14:15], 0, v[128:129]
	s_mov_b32 m0, s86
	s_nop 0
	global_load_lds_dwordx4 v[186:187], off
	v_lshl_add_u64 v[186:187], s[54:55], 0, v[134:135]
	s_mov_b32 m0, s58
	s_nop 0
	global_load_lds_dwordx4 v[186:187], off
	s_mov_b32 m0, s75
	s_nop 0
	global_load_lds_dwordx4 v[248:249], off
	s_waitcnt vmcnt(8)
	s_waitcnt lgkmcnt(0)
	s_barrier
	s_waitcnt lgkmcnt(0)
	v_mfma_f32_16x16x32_bf16 v[0:3], v[104:107], v[200:203], v[0:3]
	v_mfma_f32_16x16x32_bf16 v[4:7], v[112:115], v[200:203], v[4:7]
	v_mfma_f32_16x16x32_bf16 v[136:139], v[104:107], v[48:51], v[136:139]
	v_mfma_f32_16x16x32_bf16 v[148:151], v[112:115], v[48:51], v[148:151]
	v_mfma_f32_16x16x32_bf16 v[152:155], v[104:107], v[96:99], v[152:155]
	v_mfma_f32_16x16x32_bf16 v[156:159], v[112:115], v[96:99], v[156:159]
	v_mfma_f32_16x16x32_bf16 v[160:163], v[104:107], v[192:195], v[160:163]
	v_mfma_f32_16x16x32_bf16 v[164:167], v[112:115], v[192:195], v[164:167]
	v_mfma_f32_16x16x32_bf16 v[0:3], v[108:111], v[204:207], v[0:3]
	v_mfma_f32_16x16x32_bf16 v[4:7], v[116:119], v[204:207], v[4:7]
	v_mfma_f32_16x16x32_bf16 v[136:139], v[108:111], v[52:55], v[136:139]
	v_mfma_f32_16x16x32_bf16 v[148:151], v[116:119], v[52:55], v[148:151]
	v_mfma_f32_16x16x32_bf16 v[152:155], v[108:111], v[188:191], v[152:155]
	v_mfma_f32_16x16x32_bf16 v[156:159], v[116:119], v[188:191], v[156:159]
	v_mfma_f32_16x16x32_bf16 v[160:163], v[108:111], v[196:199], v[160:163]
	v_mfma_f32_16x16x32_bf16 v[164:167], v[116:119], v[196:199], v[164:167]
	v_mfma_f32_16x16x32_bf16 v[8:11], v[120:123], v[48:51], v[8:11]
	v_mfma_f32_16x16x32_bf16 v[12:15], v[168:171], v[48:51], v[12:15]
	v_mfma_f32_16x16x32_bf16 v[24:27], v[120:123], v[96:99], v[24:27]
	v_mfma_f32_16x16x32_bf16 v[28:31], v[168:171], v[96:99], v[28:31]
	v_mfma_f32_16x16x32_bf16 v[48:51], v[120:123], v[192:195], v[60:63]
	v_mfma_f32_16x16x32_bf16 v[24:27], v[124:127], v[188:191], v[24:27]
	v_mfma_f32_16x16x32_bf16 v[28:31], v[172:175], v[188:191], v[28:31]
	v_mfma_f32_16x16x32_bf16 v[188:191], v[124:127], v[196:199], v[48:51]
	v_mfma_f32_16x16x32_bf16 v[48:51], v[168:171], v[192:195], v[100:103]
	v_mfma_f32_16x16x32_bf16 v[16:19], v[120:123], v[200:203], v[16:19]
	v_mfma_f32_16x16x32_bf16 v[8:11], v[124:127], v[52:55], v[8:11]
	v_mfma_f32_16x16x32_bf16 v[12:15], v[172:175], v[52:55], v[12:15]
	v_mfma_f32_16x16x32_bf16 v[192:195], v[172:175], v[196:199], v[48:51]
	v_mfma_f32_16x16x32_bf16 v[196:199], v[124:127], v[204:207], v[16:19]
	v_mfma_f32_16x16x32_bf16 v[16:19], v[168:171], v[200:203], v[20:23]
	v_mfma_f32_16x16x32_bf16 v[168:171], v[172:175], v[204:207], v[16:19]
	s_barrier
	ds_read_b128 v[172:175], v145
	ds_read_b128 v[200:203], v145 offset:1024
	ds_read_b128 v[204:207], v145 offset:2048
	ds_read_b128 v[208:211], v145 offset:3072
	ds_read_b128 v[216:219], v146
	ds_read_b128 v[220:223], v146 offset:1024
	ds_read_b128 v[224:227], v146 offset:2048
	ds_read_b128 v[228:231], v146 offset:3072
	s_add_u32 s14, s54, 0x40000
	s_addc_u32 s15, s55, 0
	s_mov_b32 m0, s76
	v_lshl_add_u64 v[48:49], s[14:15], 0, v[134:135]
	ds_read_b128 v[16:19], v144 offset:32768
	ds_read_b128 v[20:23], v144 offset:33792
	ds_read_b128 v[60:63], v144 offset:34816
	ds_read_b128 v[108:111], v144 offset:35840
	ds_read_b128 v[232:235], v144 offset:36864
	ds_read_b128 v[236:239], v144 offset:37888
	ds_read_b128 v[240:243], v144 offset:38912
	ds_read_b128 v[244:247], v144 offset:39936
	global_load_lds_dwordx4 v[48:49], off
	v_lshl_add_u64 v[48:49], s[14:15], 0, v[130:131]
	s_mov_b32 m0, s78
	s_nop 0
	global_load_lds_dwordx4 v[48:49], off
	s_waitcnt vmcnt(8)
	s_waitcnt lgkmcnt(0)
	s_barrier
; #define G_STAGE(bufoff, gbase, voff) do { _Pragma("unroll") for (int _i = 0; _i < 2; ++_i) \
;         __builtin_amdgcn_global_load_lds((const unsigned*)((const char*)(gbase) + voff[_i]), (LAS unsigned*)(lds + (bufoff) + ldsw + _i * 8192), 16, 0, 0); } while (0)
; #define G_LDA(dst, b, h) do { _Pragma("unroll") for (int m = 0; m < 4; ++m) _Pragma("unroll") for (int k = 0; k < 2; ++k) dst[m][k] = *(const LAS bf16x8*)(lds + G_SA(b, h) + aoff + m * 2048 + k * 1024); } while (0)
; #define G_LDB(dst, b, h) do { _Pragma("unroll") for (int n = 0; n < 2; ++n) _Pragma("unroll") for (int k = 0; k < 2; ++k) dst[n][k] = *(const LAS bf16x8*)(lds + G_SB(b, h) + boff + n * 2048 + k * 1024); } while (0)
; #define WAIT_V(n) asm volatile("s_waitcnt vmcnt(" #n ")" ::: "memory")
; #define WAIT_L(n) asm volatile("s_waitcnt lgkmcnt(" #n ")" ::: "memory")
; #define BAR __builtin_amdgcn_s_barrier()
; #define SCHED __builtin_amdgcn_sched_barrier(0)
; template <class Get, class Epi>
; DI void gemm_loop(int ntiles, int ld, char* shm, const Get& get, const Epi& epi) {
;     ...
;         for (int t = 0; t < nt; t += 2) {
;             const bool last = (t == nt - 2);
;             const char* a1 = cA + (size_t)(t + 1) * kstep;
;             const char* a2 = last ? nA : cA + (size_t)(t + 2) * kstep; const char* b2 = last ? nB : cB + (size_t)(t + 2) * kstep;
;             const char* a3 = a2 + kstep; const char* b3 = b2 + kstep;
;             G_LDB(B0, 0, 0); G_LDB(B1, 0, 1); SCHED; G_LDA(At, 0, 0); G_STAGE(G_SA(1, 1), a1 + hstep, voffA);
;             WAIT_V(8); WAIT_L(0); BAR; G_MMA(0, 0, At, B0); G_MMA(0, 1, At, B1); BAR; SCHED;
;             G_LDA(At, 0, 1); G_STAGE(G_SB(0, 0), b2, voffB); G_STAGE(G_SB(0, 1), b2 + hstep, voffB); G_STAGE(G_SA(0, 0), a2, voffA);
;             WAIT_V(8); WAIT_L(0); BAR; G_MMA(1, 0, At, B0); G_MMA(1, 1, At, B1); BAR; SCHED;
;             G_LDB(B0, 1, 0); G_LDB(B1, 1, 1); SCHED; G_LDA(At, 1, 0); G_STAGE(G_SA(0, 1), a2 + hstep, voffA);
;             WAIT_V(8); WAIT_L(0); BAR; G_MMA(0, 0, At, B0); G_MMA(0, 1, At, B1); BAR; SCHED;
;             G_LDA(At, 1, 1); G_STAGE(G_SB(1, 0), b3, voffB); G_STAGE(G_SB(1, 1), b3 + hstep, voffB); G_STAGE(G_SA(1, 0), a3, voffA);
;             WAIT_V(8); WAIT_L(0); BAR; G_MMA(1, 0, At, B0); G_MMA(1, 1, At, B1); BAR; SCHED;
;         }
;         if (wr == 0) BAR;
	s_waitcnt lgkmcnt(0)
	v_mfma_f32_16x16x32_bf16 v[48:51], v[172:175], v[16:19], v[64:67]
	v_mfma_f32_16x16x32_bf16 v[112:115], v[200:203], v[20:23], v[48:51]
	v_mfma_f32_16x16x32_bf16 v[48:51], v[204:207], v[16:19], v[68:71]
	v_mfma_f32_16x16x32_bf16 v[116:119], v[208:211], v[20:23], v[48:51]
	v_mfma_f32_16x16x32_bf16 v[48:51], v[172:175], v[60:63], v[72:75]
	v_mfma_f32_16x16x32_bf16 v[96:99], v[200:203], v[108:111], v[48:51]
	v_mfma_f32_16x16x32_bf16 v[48:51], v[204:207], v[60:63], v[76:79]
	v_mfma_f32_16x16x32_bf16 v[100:103], v[208:211], v[108:111], v[48:51]
	v_mfma_f32_16x16x32_bf16 v[48:51], v[172:175], v[232:235], v[80:83]
	v_mfma_f32_16x16x32_bf16 v[80:83], v[200:203], v[236:239], v[48:51]
	v_mfma_f32_16x16x32_bf16 v[48:51], v[204:207], v[232:235], v[84:87]
	v_mfma_f32_16x16x32_bf16 v[84:87], v[208:211], v[236:239], v[48:51]
	v_mfma_f32_16x16x32_bf16 v[48:51], v[172:175], v[240:243], v[88:91]
	v_mfma_f32_16x16x32_bf16 v[52:55], v[204:207], v[240:243], v[92:95]
	v_mfma_f32_16x16x32_bf16 v[48:51], v[200:203], v[244:247], v[48:51]
	v_mfma_f32_16x16x32_bf16 v[52:55], v[208:211], v[244:247], v[52:55]
	v_mfma_f32_16x16x32_bf16 v[64:67], v[216:219], v[16:19], v[212:215]
	v_mfma_f32_16x16x32_bf16 v[16:19], v[224:227], v[16:19], v[32:35]
	v_mfma_f32_16x16x32_bf16 v[124:127], v[228:231], v[20:23], v[16:19]
	v_mfma_f32_16x16x32_bf16 v[16:19], v[216:219], v[60:63], v[36:39]
	v_mfma_f32_16x16x32_bf16 v[104:107], v[220:223], v[108:111], v[16:19]
	v_mfma_f32_16x16x32_bf16 v[16:19], v[224:227], v[60:63], v[40:43]
	v_mfma_f32_16x16x32_bf16 v[108:111], v[228:231], v[108:111], v[16:19]
	v_mfma_f32_16x16x32_bf16 v[16:19], v[216:219], v[232:235], v[44:47]
	v_mfma_f32_16x16x32_bf16 v[88:91], v[220:223], v[236:239], v[16:19]
	v_mfma_f32_16x16x32_bf16 v[16:19], v[224:227], v[232:235], v[176:179]
	v_mfma_f32_16x16x32_bf16 v[92:95], v[228:231], v[236:239], v[16:19]
	v_mfma_f32_16x16x32_bf16 v[16:19], v[216:219], v[240:243], v[180:183]
	v_mfma_f32_16x16x32_bf16 v[120:123], v[220:223], v[20:23], v[64:67]
	v_mfma_f32_16x16x32_bf16 v[64:67], v[220:223], v[244:247], v[16:19]
	v_mfma_f32_16x16x32_bf16 v[16:19], v[224:227], v[240:243], v[56:59]
	v_mfma_f32_16x16x32_bf16 v[68:71], v[228:231], v[244:247], v[16:19]
	s_barrier
	s_mov_b32 m0, s87
	s_nop 3
	v_lshl_add_u64 v[16:17], v[140:141], 0, s[12:13]
	s_add_u32 s14, s46, 0x40080
	ds_read_b128 v[40:43], v144 offset:49152
	ds_read_b128 v[44:47], v144 offset:50176
	ds_read_b128 v[176:179], v144 offset:51200
	ds_read_b128 v[180:183], v144 offset:52224
	ds_read_b128 v[212:215], v144 offset:53248
	ds_read_b128 v[232:235], v144 offset:54272
	ds_read_b128 v[236:239], v144 offset:55296
	ds_read_b128 v[240:243], v144 offset:56320
	global_load_lds_dwordx4 v[16:17], off
	v_lshl_add_u64 v[16:17], v[184:185], 0, s[12:13]
	s_mov_b32 m0, s88
	s_addc_u32 s15, s47, 0
	global_load_lds_dwordx4 v[16:17], off
	v_lshl_add_u64 v[16:17], s[14:15], 0, v[132:133]
	s_mov_b32 m0, s89
	s_nop 0
	global_load_lds_dwordx4 v[16:17], off
	v_lshl_add_u64 v[16:17], s[14:15], 0, v[128:129]
	s_mov_b32 m0, s90
	s_nop 0
	global_load_lds_dwordx4 v[16:17], off
	v_lshl_add_u64 v[16:17], v[186:187], 0, s[12:13]
	s_mov_b32 m0, s79
	s_nop 0
	global_load_lds_dwordx4 v[16:17], off
	v_lshl_add_u64 v[16:17], v[248:249], 0, s[12:13]
	s_mov_b32 m0, s80
	s_nop 0
	global_load_lds_dwordx4 v[16:17], off
	s_waitcnt vmcnt(8)
	s_waitcnt lgkmcnt(0)
	s_barrier
	s_waitcnt lgkmcnt(0)
	v_mfma_f32_16x16x32_bf16 v[16:19], v[172:175], v[40:43], v[136:139]
	v_mfma_f32_16x16x32_bf16 v[56:59], v[200:203], v[44:47], v[16:19]
	v_mfma_f32_16x16x32_bf16 v[16:19], v[204:207], v[40:43], v[148:151]
	v_mfma_f32_16x16x32_bf16 v[60:63], v[208:211], v[44:47], v[16:19]
	v_mfma_f32_16x16x32_bf16 v[16:19], v[172:175], v[176:179], v[152:155]
	v_mfma_f32_16x16x32_bf16 v[32:35], v[200:203], v[180:183], v[16:19]
	v_mfma_f32_16x16x32_bf16 v[16:19], v[204:207], v[176:179], v[156:159]
	v_mfma_f32_16x16x32_bf16 v[36:39], v[208:211], v[180:183], v[16:19]
	v_mfma_f32_16x16x32_bf16 v[16:19], v[172:175], v[212:215], v[160:163]
	v_mfma_f32_16x16x32_bf16 v[20:23], v[204:207], v[212:215], v[164:167]
	v_mfma_f32_16x16x32_bf16 v[0:3], v[172:175], v[236:239], v[0:3]
	v_mfma_f32_16x16x32_bf16 v[4:7], v[204:207], v[236:239], v[4:7]
	v_mfma_f32_16x16x32_bf16 v[16:19], v[200:203], v[232:235], v[16:19]
	v_mfma_f32_16x16x32_bf16 v[20:23], v[208:211], v[232:235], v[20:23]
	v_mfma_f32_16x16x32_bf16 v[0:3], v[200:203], v[240:243], v[0:3]
	v_mfma_f32_16x16x32_bf16 v[4:7], v[208:211], v[240:243], v[4:7]
	v_mfma_f32_16x16x32_bf16 v[8:11], v[216:219], v[40:43], v[8:11]
	v_mfma_f32_16x16x32_bf16 v[72:75], v[220:223], v[44:47], v[8:11]
	v_mfma_f32_16x16x32_bf16 v[8:11], v[224:227], v[40:43], v[12:15]
	v_mfma_f32_16x16x32_bf16 v[76:79], v[228:231], v[44:47], v[8:11]
	v_mfma_f32_16x16x32_bf16 v[8:11], v[216:219], v[176:179], v[24:27]
	v_mfma_f32_16x16x32_bf16 v[40:43], v[220:223], v[180:183], v[8:11]
	v_mfma_f32_16x16x32_bf16 v[8:11], v[224:227], v[176:179], v[28:31]
	v_mfma_f32_16x16x32_bf16 v[44:47], v[228:231], v[180:183], v[8:11]
	v_mfma_f32_16x16x32_bf16 v[8:11], v[216:219], v[212:215], v[188:191]
	v_mfma_f32_16x16x32_bf16 v[24:27], v[220:223], v[232:235], v[8:11]
	v_mfma_f32_16x16x32_bf16 v[8:11], v[224:227], v[212:215], v[192:195]
	v_mfma_f32_16x16x32_bf16 v[28:31], v[228:231], v[232:235], v[8:11]
	v_mfma_f32_16x16x32_bf16 v[8:11], v[216:219], v[236:239], v[196:199]
	v_mfma_f32_16x16x32_bf16 v[12:15], v[224:227], v[236:239], v[168:171]
	v_mfma_f32_16x16x32_bf16 v[8:11], v[220:223], v[240:243], v[8:11]
	v_mfma_f32_16x16x32_bf16 v[12:15], v[228:231], v[240:243], v[12:15]
	s_barrier
	s_and_b64 vcc, exec, s[2:3]
	s_cbranch_vccnz .LBB0_334
	s_barrier

; #define G_STAGE(bufoff, gbase, voff) do { _Pragma("unroll") for (int _i = 0; _i < 2; ++_i) \
;         __builtin_amdgcn_global_load_lds((const unsigned*)((const char*)(gbase) + voff[_i]), (LAS unsigned*)(lds + (bufoff) + ldsw + _i * 8192), 16, 0, 0); } while (0)
; #define G_LDA(dst, b, h) do { _Pragma("unroll") for (int m = 0; m < 4; ++m) _Pragma("unroll") for (int k = 0; k < 2; ++k) dst[m][k] = *(const LAS bf16x8*)(lds + G_SA(b, h) + aoff + m * 2048 + k * 1024); } while (0)
; #define G_LDB(dst, b, h) do { _Pragma("unroll") for (int n = 0; n < 2; ++n) _Pragma("unroll") for (int k = 0; k < 2; ++k) dst[n][k] = *(const LAS bf16x8*)(lds + G_SB(b, h) + boff + n * 2048 + k * 1024); } while (0)
; template <class Get, class Epi>
; DI void gemm_loop(int ntiles, int ld, char* shm, const Get& get, const Epi& epi) {
;     ...
;     for (;;) {
;         const int Ln = L + gridDim.x; const bool has_next = Ln < ntiles; if (has_next) nxt = get(Ln);
;         const char* nA = has_next ? (const char*)nxt.A + (size_t)nxt.brow * ld * 2 : cA; const char* nB = has_next ? (const char*)nxt.Bt + (size_t)nxt.bcol * ld * 2 : cB;
;         const int nt = cur.K / BK;
;         for (int t = 0; t < nt; t += 2) {
;             const bool last = (t == nt - 2);
;             const char* a1 = cA + (size_t)(t + 1) * kstep;
;             const char* a2 = last ? nA : cA + (size_t)(t + 2) * kstep; const char* b2 = last ? nB : cB + (size_t)(t + 2) * kstep;
;             const char* a3 = a2 + kstep; const char* b3 = b2 + kstep;
;             G_LDB(B0, 0, 0); G_LDB(B1, 0, 1); SCHED; G_LDA(At, 0, 0); G_STAGE(G_SA(1, 1), a1 + hstep, voffA);
;             WAIT_V(8); WAIT_L(0); BAR; G_MMA(0, 0, At, B0); G_MMA(0, 1, At, B1); BAR; SCHED;
;             G_LDA(At, 0, 1); G_STAGE(G_SB(0, 0), b2, voffB); G_STAGE(G_SB(0, 1), b2 + hstep, voffB); G_STAGE(G_SA(0, 0), a2, voffA);
;             WAIT_V(8); WAIT_L(0); BAR; G_MMA(1, 0, At, B0); G_MMA(1, 1, At, B1); BAR; SCHED;
;             G_LDB(B0, 1, 0); G_LDB(B1, 1, 1); SCHED; G_LDA(At, 1, 0); G_STAGE(G_SA(0, 1), a2 + hstep, voffA);
;             WAIT_V(8); WAIT_L(0); BAR; G_MMA(0, 0, At, B0); G_MMA(0, 1, At, B1); BAR; SCHED;
;             G_LDA(At, 1, 1); G_STAGE(G_SB(1, 0), b3, voffB); G_STAGE(G_SB(1, 1), b3 + hstep, voffB); G_STAGE(G_SA(1, 0), a3, voffA);
;             WAIT_V(8); WAIT_L(0); BAR; G_MMA(1, 0, At, B0); G_MMA(1, 1, At, B1); BAR; SCHED;
.Lrj_431_0:
	s_waitcnt lgkmcnt(0)
	s_barrier
	s_waitcnt lgkmcnt(0)
	v_mfma_f32_16x16x32_bf16 v[124:127], v[146:149], v[178:181], 0
	v_mfma_f32_16x16x32_bf16 v[120:123], v[154:157], v[178:181], 0
	v_mfma_f32_16x16x32_bf16 v[116:119], v[146:149], v[192:195], 0
	v_mfma_f32_16x16x32_bf16 v[112:115], v[154:157], v[192:195], 0
	v_mfma_f32_16x16x32_bf16 v[100:103], v[146:149], v[200:203], 0
	v_mfma_f32_16x16x32_bf16 v[96:99], v[154:157], v[200:203], 0
	v_mfma_f32_16x16x32_bf16 v[84:87], v[146:149], v[208:211], 0
	v_mfma_f32_16x16x32_bf16 v[80:83], v[154:157], v[208:211], 0
	v_mfma_f32_16x16x32_bf16 v[124:127], v[150:153], v[188:191], v[124:127]
	v_mfma_f32_16x16x32_bf16 v[120:123], v[158:161], v[188:191], v[120:123]
	v_mfma_f32_16x16x32_bf16 v[116:119], v[150:153], v[196:199], v[116:119]
	v_mfma_f32_16x16x32_bf16 v[112:115], v[158:161], v[196:199], v[112:115]
	v_mfma_f32_16x16x32_bf16 v[100:103], v[150:153], v[204:207], v[100:103]
	v_mfma_f32_16x16x32_bf16 v[96:99], v[158:161], v[204:207], v[96:99]
	v_mfma_f32_16x16x32_bf16 v[84:87], v[150:153], v[212:215], v[84:87]
	v_mfma_f32_16x16x32_bf16 v[80:83], v[158:161], v[212:215], v[80:83]
	v_mfma_f32_16x16x32_bf16 v[108:111], v[162:165], v[178:181], 0
	v_mfma_f32_16x16x32_bf16 v[104:107], v[170:173], v[178:181], 0
	v_mfma_f32_16x16x32_bf16 v[92:95], v[162:165], v[192:195], 0
	v_mfma_f32_16x16x32_bf16 v[88:91], v[170:173], v[192:195], 0
	v_mfma_f32_16x16x32_bf16 v[76:79], v[162:165], v[200:203], 0
	v_mfma_f32_16x16x32_bf16 v[72:75], v[170:173], v[200:203], 0
	v_mfma_f32_16x16x32_bf16 v[68:71], v[162:165], v[208:211], 0
	v_mfma_f32_16x16x32_bf16 v[64:67], v[170:173], v[208:211], 0
	v_mfma_f32_16x16x32_bf16 v[108:111], v[166:169], v[188:191], v[108:111]
	v_mfma_f32_16x16x32_bf16 v[104:107], v[174:177], v[188:191], v[104:107]
	v_mfma_f32_16x16x32_bf16 v[92:95], v[166:169], v[196:199], v[92:95]
	v_mfma_f32_16x16x32_bf16 v[88:91], v[174:177], v[196:199], v[88:91]
	v_mfma_f32_16x16x32_bf16 v[76:79], v[166:169], v[204:207], v[76:79]
	v_mfma_f32_16x16x32_bf16 v[72:75], v[174:177], v[204:207], v[72:75]
	v_mfma_f32_16x16x32_bf16 v[68:71], v[166:169], v[212:215], v[68:71]
	v_mfma_f32_16x16x32_bf16 v[64:67], v[174:177], v[212:215], v[64:67]
	s_barrier
	s_add_i32 s82, s54, s38
	v_lshl_add_u64 v[182:183], s[14:15], 0, v[132:133]
	s_mov_b32 m0, s82
	ds_read_b128 v[178:181], v143 offset:16384
	ds_read_b128 v[188:191], v143 offset:17408
	ds_read_b128 v[192:195], v143 offset:18432
	ds_read_b128 v[196:199], v143 offset:19456
	ds_read_b128 v[200:203], v143 offset:20480
	ds_read_b128 v[204:207], v143 offset:21504
	ds_read_b128 v[208:211], v143 offset:22528
	ds_read_b128 v[212:215], v143 offset:23552
	global_load_lds_dwordx4 v[182:183], off
	s_add_i32 m0, s82, 0x2000
	s_add_u32 s82, s14, 0x100000
	v_lshl_add_u64 v[184:185], s[14:15], 0, v[128:129]
	s_addc_u32 s83, s15, 0
	s_add_i32 s84, s55, s38
	global_load_lds_dwordx4 v[184:185], off
	v_lshl_add_u64 v[186:187], s[82:83], 0, v[132:133]
	s_mov_b32 m0, s84
	v_lshl_add_u64 v[216:217], s[36:37], 0, v[130:131]
	global_load_lds_dwordx4 v[186:187], off
	v_lshl_add_u64 v[186:187], s[82:83], 0, v[128:129]
	s_add_i32 m0, s84, 0x2000
	s_nop 0
	global_load_lds_dwordx4 v[186:187], off
	v_lshl_add_u64 v[186:187], s[36:37], 0, v[134:135]
	s_mov_b32 m0, s43
	s_nop 0
	global_load_lds_dwordx4 v[186:187], off
	s_mov_b32 m0, s44
	s_nop 0
	global_load_lds_dwordx4 v[216:217], off
	s_cmp_lg_u32 s100, 0
	s_cbranch_scc0 .Lrf_431_1
	s_waitcnt vmcnt(16)
	s_branch .Lrj_431_1

; #define G_STAGE(bufoff, gbase, voff) do { _Pragma("unroll") for (int _i = 0; _i < 2; ++_i) \
;         __builtin_amdgcn_global_load_lds((const unsigned*)((const char*)(gbase) + voff[_i]), (LAS unsigned*)(lds + (bufoff) + ldsw + _i * 8192), 16, 0, 0); } while (0)
; #define G_LDA(dst, b, h) do { _Pragma("unroll") for (int m = 0; m < 4; ++m) _Pragma("unroll") for (int k = 0; k < 2; ++k) dst[m][k] = *(const LAS bf16x8*)(lds + G_SA(b, h) + aoff + m * 2048 + k * 1024); } while (0)
; #define G_LDB(dst, b, h) do { _Pragma("unroll") for (int n = 0; n < 2; ++n) _Pragma("unroll") for (int k = 0; k < 2; ++k) dst[n][k] = *(const LAS bf16x8*)(lds + G_SB(b, h) + boff + n * 2048 + k * 1024); } while (0)
; template <class Get, class Epi>
; DI void gemm_loop(int ntiles, int ld, char* shm, const Get& get, const Epi& epi) {
;     ...
;     for (;;) {
;         const int Ln = L + gridDim.x; const bool has_next = Ln < ntiles; if (has_next) nxt = get(Ln);
;         const char* nA = has_next ? (const char*)nxt.A + (size_t)nxt.brow * ld * 2 : cA; const char* nB = has_next ? (const char*)nxt.Bt + (size_t)nxt.bcol * ld * 2 : cB;
;         const int nt = cur.K / BK;
;         for (int t = 0; t < nt; t += 2) {
;             const bool last = (t == nt - 2);
;             const char* a1 = cA + (size_t)(t + 1) * kstep;
;             const char* a2 = last ? nA : cA + (size_t)(t + 2) * kstep; const char* b2 = last ? nB : cB + (size_t)(t + 2) * kstep;
;             const char* a3 = a2 + kstep; const char* b3 = b2 + kstep;
;             G_LDB(B0, 0, 0); G_LDB(B1, 0, 1); SCHED; G_LDA(At, 0, 0); G_STAGE(G_SA(1, 1), a1 + hstep, voffA);
;             WAIT_V(8); WAIT_L(0); BAR; G_MMA(0, 0, At, B0); G_MMA(0, 1, At, B1); BAR; SCHED;
;             G_LDA(At, 0, 1); G_STAGE(G_SB(0, 0), b2, voffB); G_STAGE(G_SB(0, 1), b2 + hstep, voffB); G_STAGE(G_SA(0, 0), a2, voffA);
;             WAIT_V(8); WAIT_L(0); BAR; G_MMA(1, 0, At, B0); G_MMA(1, 1, At, B1); BAR; SCHED;
;             G_LDB(B0, 1, 0); G_LDB(B1, 1, 1); SCHED; G_LDA(At, 1, 0); G_STAGE(G_SA(0, 1), a2 + hstep, voffA);
;             WAIT_V(8); WAIT_L(0); BAR; G_MMA(0, 0, At, B0); G_MMA(0, 1, At, B1); BAR; SCHED;
;             G_LDA(At, 1, 1); G_STAGE(G_SB(1, 0), b3, voffB); G_STAGE(G_SB(1, 1), b3 + hstep, voffB); G_STAGE(G_SA(1, 0), a3, voffA);
;             WAIT_V(8); WAIT_L(0); BAR; G_MMA(1, 0, At, B0); G_MMA(1, 1, At, B1); BAR; SCHED;
.Lrj_431_1:
	s_waitcnt lgkmcnt(0)
	s_barrier
	s_waitcnt lgkmcnt(0)
	v_mfma_f32_16x16x32_bf16 v[60:63], v[146:149], v[178:181], 0
	v_mfma_f32_16x16x32_bf16 v[56:59], v[154:157], v[178:181], 0
	v_mfma_f32_16x16x32_bf16 v[52:55], v[146:149], v[192:195], 0
	v_mfma_f32_16x16x32_bf16 v[48:51], v[154:157], v[192:195], 0
	v_mfma_f32_16x16x32_bf16 v[36:39], v[146:149], v[200:203], 0
	v_mfma_f32_16x16x32_bf16 v[32:35], v[154:157], v[200:203], 0
	v_mfma_f32_16x16x32_bf16 v[20:23], v[146:149], v[208:211], 0
	v_mfma_f32_16x16x32_bf16 v[16:19], v[154:157], v[208:211], 0
	v_mfma_f32_16x16x32_bf16 v[60:63], v[150:153], v[188:191], v[60:63]
	v_mfma_f32_16x16x32_bf16 v[56:59], v[158:161], v[188:191], v[56:59]
	v_mfma_f32_16x16x32_bf16 v[52:55], v[150:153], v[196:199], v[52:55]
	v_mfma_f32_16x16x32_bf16 v[48:51], v[158:161], v[196:199], v[48:51]
	v_mfma_f32_16x16x32_bf16 v[36:39], v[150:153], v[204:207], v[36:39]
	v_mfma_f32_16x16x32_bf16 v[32:35], v[158:161], v[204:207], v[32:35]
	v_mfma_f32_16x16x32_bf16 v[20:23], v[150:153], v[212:215], v[20:23]
	v_mfma_f32_16x16x32_bf16 v[16:19], v[158:161], v[212:215], v[16:19]
	v_mfma_f32_16x16x32_bf16 v[44:47], v[162:165], v[178:181], 0
	v_mfma_f32_16x16x32_bf16 v[40:43], v[170:173], v[178:181], 0
	v_mfma_f32_16x16x32_bf16 v[28:31], v[162:165], v[192:195], 0
	v_mfma_f32_16x16x32_bf16 v[24:27], v[170:173], v[192:195], 0
	v_mfma_f32_16x16x32_bf16 v[12:15], v[162:165], v[200:203], 0
	v_mfma_f32_16x16x32_bf16 v[8:11], v[170:173], v[200:203], 0
	v_mfma_f32_16x16x32_bf16 v[4:7], v[162:165], v[208:211], 0
	v_mfma_f32_16x16x32_bf16 v[0:3], v[170:173], v[208:211], 0
	v_mfma_f32_16x16x32_bf16 v[44:47], v[166:169], v[188:191], v[44:47]
	v_mfma_f32_16x16x32_bf16 v[40:43], v[174:177], v[188:191], v[40:43]
	v_mfma_f32_16x16x32_bf16 v[28:31], v[166:169], v[196:199], v[28:31]
	v_mfma_f32_16x16x32_bf16 v[24:27], v[174:177], v[196:199], v[24:27]
	v_mfma_f32_16x16x32_bf16 v[12:15], v[166:169], v[204:207], v[12:15]
	v_mfma_f32_16x16x32_bf16 v[8:11], v[174:177], v[204:207], v[8:11]
	v_mfma_f32_16x16x32_bf16 v[4:7], v[166:169], v[212:215], v[4:7]
	v_mfma_f32_16x16x32_bf16 v[0:3], v[174:177], v[212:215], v[0:3]
	s_barrier
	s_add_i32 s82, 0, 0x18000
	v_add_u32_e32 v145, s82, v140
	s_add_i32 s83, 0, 0x1c000
	ds_read_b128 v[146:149], v145
	ds_read_b128 v[150:153], v145 offset:1024
	ds_read_b128 v[154:157], v145 offset:2048
	ds_read_b128 v[158:161], v145 offset:3072
	v_add_u32_e32 v145, s83, v140
	ds_read_b128 v[162:165], v145
	ds_read_b128 v[166:169], v145 offset:1024
	ds_read_b128 v[170:173], v145 offset:2048
	ds_read_b128 v[174:177], v145 offset:3072
	s_add_u32 s36, s36, 0x100000
	s_addc_u32 s37, s37, 0
	s_mov_b32 m0, s45
	v_lshl_add_u64 v[218:219], s[36:37], 0, v[134:135]
	ds_read_b128 v[178:181], v143 offset:32768
	ds_read_b128 v[188:191], v143 offset:33792
	ds_read_b128 v[192:195], v143 offset:34816
	ds_read_b128 v[196:199], v143 offset:35840
	ds_read_b128 v[200:203], v143 offset:36864
	ds_read_b128 v[204:207], v143 offset:37888
	ds_read_b128 v[208:211], v143 offset:38912
	ds_read_b128 v[212:215], v143 offset:39936
	global_load_lds_dwordx4 v[218:219], off
	v_lshl_add_u64 v[218:219], s[36:37], 0, v[130:131]
	s_mov_b32 m0, s46
	s_nop 0
	global_load_lds_dwordx4 v[218:219], off
	s_waitcnt vmcnt(8)
	s_waitcnt lgkmcnt(0)
	s_barrier
	s_waitcnt lgkmcnt(0)
	v_mfma_f32_16x16x32_bf16 v[124:127], v[146:149], v[178:181], v[124:127]
	v_mfma_f32_16x16x32_bf16 v[120:123], v[154:157], v[178:181], v[120:123]
	v_mfma_f32_16x16x32_bf16 v[116:119], v[146:149], v[192:195], v[116:119]
	v_mfma_f32_16x16x32_bf16 v[112:115], v[154:157], v[192:195], v[112:115]
	v_mfma_f32_16x16x32_bf16 v[100:103], v[146:149], v[200:203], v[100:103]
	v_mfma_f32_16x16x32_bf16 v[96:99], v[154:157], v[200:203], v[96:99]
	v_mfma_f32_16x16x32_bf16 v[84:87], v[146:149], v[208:211], v[84:87]
	v_mfma_f32_16x16x32_bf16 v[80:83], v[154:157], v[208:211], v[80:83]
	v_mfma_f32_16x16x32_bf16 v[124:127], v[150:153], v[188:191], v[124:127]
	v_mfma_f32_16x16x32_bf16 v[120:123], v[158:161], v[188:191], v[120:123]
	v_mfma_f32_16x16x32_bf16 v[116:119], v[150:153], v[196:199], v[116:119]
	v_mfma_f32_16x16x32_bf16 v[112:115], v[158:161], v[196:199], v[112:115]
	v_mfma_f32_16x16x32_bf16 v[100:103], v[150:153], v[204:207], v[100:103]
	v_mfma_f32_16x16x32_bf16 v[96:99], v[158:161], v[204:207], v[96:99]
	v_mfma_f32_16x16x32_bf16 v[84:87], v[150:153], v[212:215], v[84:87]
	v_mfma_f32_16x16x32_bf16 v[80:83], v[158:161], v[212:215], v[80:83]
	v_mfma_f32_16x16x32_bf16 v[108:111], v[162:165], v[178:181], v[108:111]
	v_mfma_f32_16x16x32_bf16 v[104:107], v[170:173], v[178:181], v[104:107]
	v_mfma_f32_16x16x32_bf16 v[92:95], v[162:165], v[192:195], v[92:95]
	v_mfma_f32_16x16x32_bf16 v[88:91], v[170:173], v[192:195], v[88:91]
	v_mfma_f32_16x16x32_bf16 v[76:79], v[162:165], v[200:203], v[76:79]
	v_mfma_f32_16x16x32_bf16 v[72:75], v[170:173], v[200:203], v[72:75]
	v_mfma_f32_16x16x32_bf16 v[68:71], v[162:165], v[208:211], v[68:71]
	v_mfma_f32_16x16x32_bf16 v[64:67], v[170:173], v[208:211], v[64:67]
	v_mfma_f32_16x16x32_bf16 v[108:111], v[166:169], v[188:191], v[108:111]
	v_mfma_f32_16x16x32_bf16 v[104:107], v[174:177], v[188:191], v[104:107]
	v_mfma_f32_16x16x32_bf16 v[92:95], v[166:169], v[196:199], v[92:95]
	v_mfma_f32_16x16x32_bf16 v[88:91], v[174:177], v[196:199], v[88:91]
	v_mfma_f32_16x16x32_bf16 v[76:79], v[166:169], v[204:207], v[76:79]
	v_mfma_f32_16x16x32_bf16 v[72:75], v[174:177], v[204:207], v[72:75]
	v_mfma_f32_16x16x32_bf16 v[68:71], v[166:169], v[212:215], v[68:71]
	v_mfma_f32_16x16x32_bf16 v[64:67], v[174:177], v[212:215], v[64:67]
	s_barrier
; #define G_STAGE(bufoff, gbase, voff) do { _Pragma("unroll") for (int _i = 0; _i < 2; ++_i) \
;         __builtin_amdgcn_global_load_lds((const unsigned*)((const char*)(gbase) + voff[_i]), (LAS unsigned*)(lds + (bufoff) + ldsw + _i * 8192), 16, 0, 0); } while (0)
; #define G_LDA(dst, b, h) do { _Pragma("unroll") for (int m = 0; m < 4; ++m) _Pragma("unroll") for (int k = 0; k < 2; ++k) dst[m][k] = *(const LAS bf16x8*)(lds + G_SA(b, h) + aoff + m * 2048 + k * 1024); } while (0)
; #define G_LDB(dst, b, h) do { _Pragma("unroll") for (int n = 0; n < 2; ++n) _Pragma("unroll") for (int k = 0; k < 2; ++k) dst[n][k] = *(const LAS bf16x8*)(lds + G_SB(b, h) + boff + n * 2048 + k * 1024); } while (0)
; #define WAIT_V(n) asm volatile("s_waitcnt vmcnt(" #n ")" ::: "memory")
; #define WAIT_L(n) asm volatile("s_waitcnt lgkmcnt(" #n ")" ::: "memory")
; #define BAR __builtin_amdgcn_s_barrier()
; #define SCHED __builtin_amdgcn_sched_barrier(0)
; template <class Get, class Epi>
; DI void gemm_loop(int ntiles, int ld, char* shm, const Get& get, const Epi& epi) {
;     ...
;         for (int t = 0; t < nt; t += 2) {
;             const bool last = (t == nt - 2);
;             const char* a1 = cA + (size_t)(t + 1) * kstep;
;             const char* a2 = last ? nA : cA + (size_t)(t + 2) * kstep; const char* b2 = last ? nB : cB + (size_t)(t + 2) * kstep;
;             const char* a3 = a2 + kstep; const char* b3 = b2 + kstep;
;             G_LDB(B0, 0, 0); G_LDB(B1, 0, 1); SCHED; G_LDA(At, 0, 0); G_STAGE(G_SA(1, 1), a1 + hstep, voffA);
;             WAIT_V(8); WAIT_L(0); BAR; G_MMA(0, 0, At, B0); G_MMA(0, 1, At, B1); BAR; SCHED;
;             G_LDA(At, 0, 1); G_STAGE(G_SB(0, 0), b2, voffB); G_STAGE(G_SB(0, 1), b2 + hstep, voffB); G_STAGE(G_SA(0, 0), a2, voffA);
;             WAIT_V(8); WAIT_L(0); BAR; G_MMA(1, 0, At, B0); G_MMA(1, 1, At, B1); BAR; SCHED;
;             G_LDB(B0, 1, 0); G_LDB(B1, 1, 1); SCHED; G_LDA(At, 1, 0); G_STAGE(G_SA(0, 1), a2 + hstep, voffA);
;             WAIT_V(8); WAIT_L(0); BAR; G_MMA(0, 0, At, B0); G_MMA(0, 1, At, B1); BAR; SCHED;
;             G_LDA(At, 1, 1); G_STAGE(G_SB(1, 0), b3, voffB); G_STAGE(G_SB(1, 1), b3 + hstep, voffB); G_STAGE(G_SA(1, 0), a3, voffA);
;             WAIT_V(8); WAIT_L(0); BAR; G_MMA(1, 0, At, B0); G_MMA(1, 1, At, B1); BAR; SCHED;
	s_add_i32 s36, s82, s38
	v_lshl_add_u64 v[182:183], v[182:183], 0, s[8:9]
	s_mov_b32 m0, s36
	ds_read_b128 v[178:181], v143 offset:49152
	ds_read_b128 v[188:191], v143 offset:50176
	ds_read_b128 v[192:195], v143 offset:51200
	ds_read_b128 v[196:199], v143 offset:52224
	ds_read_b128 v[200:203], v143 offset:53248
	ds_read_b128 v[204:207], v143 offset:54272
	ds_read_b128 v[208:211], v143 offset:55296
	ds_read_b128 v[212:215], v143 offset:56320
	global_load_lds_dwordx4 v[182:183], off
	s_add_i32 m0, s36, 0x2000
	s_add_u32 s14, s14, 0x100080
	v_lshl_add_u64 v[182:183], v[184:185], 0, s[8:9]
	s_addc_u32 s15, s15, 0
	s_add_i32 s36, s83, s38
	global_load_lds_dwordx4 v[182:183], off
	v_lshl_add_u64 v[182:183], s[14:15], 0, v[132:133]
	s_mov_b32 m0, s36
	s_nop 0
	global_load_lds_dwordx4 v[182:183], off
	v_lshl_add_u64 v[182:183], s[14:15], 0, v[128:129]
	s_add_i32 m0, s36, 0x2000
	s_nop 0
	global_load_lds_dwordx4 v[182:183], off
	v_lshl_add_u64 v[182:183], v[186:187], 0, s[8:9]
	s_mov_b32 m0, s47
	s_nop 0
	global_load_lds_dwordx4 v[182:183], off
	v_lshl_add_u64 v[182:183], v[216:217], 0, s[8:9]
	s_mov_b32 m0, s50
	s_nop 0
	global_load_lds_dwordx4 v[182:183], off
	s_waitcnt vmcnt(8)
	s_waitcnt lgkmcnt(0)
	s_barrier
	s_waitcnt lgkmcnt(0)
	v_mfma_f32_16x16x32_bf16 v[60:63], v[146:149], v[178:181], v[60:63]
	v_mfma_f32_16x16x32_bf16 v[56:59], v[154:157], v[178:181], v[56:59]
	v_mfma_f32_16x16x32_bf16 v[52:55], v[146:149], v[192:195], v[52:55]
	v_mfma_f32_16x16x32_bf16 v[48:51], v[154:157], v[192:195], v[48:51]
	v_mfma_f32_16x16x32_bf16 v[36:39], v[146:149], v[200:203], v[36:39]
	v_mfma_f32_16x16x32_bf16 v[32:35], v[154:157], v[200:203], v[32:35]
	v_mfma_f32_16x16x32_bf16 v[20:23], v[146:149], v[208:211], v[20:23]
	v_mfma_f32_16x16x32_bf16 v[16:19], v[154:157], v[208:211], v[16:19]
	v_mfma_f32_16x16x32_bf16 v[60:63], v[150:153], v[188:191], v[60:63]
	v_mfma_f32_16x16x32_bf16 v[56:59], v[158:161], v[188:191], v[56:59]
	v_mfma_f32_16x16x32_bf16 v[52:55], v[150:153], v[196:199], v[52:55]
	v_mfma_f32_16x16x32_bf16 v[48:51], v[158:161], v[196:199], v[48:51]
	v_mfma_f32_16x16x32_bf16 v[36:39], v[150:153], v[204:207], v[36:39]
	v_mfma_f32_16x16x32_bf16 v[32:35], v[158:161], v[204:207], v[32:35]
	v_mfma_f32_16x16x32_bf16 v[20:23], v[150:153], v[212:215], v[20:23]
	v_mfma_f32_16x16x32_bf16 v[16:19], v[158:161], v[212:215], v[16:19]
	v_mfma_f32_16x16x32_bf16 v[44:47], v[162:165], v[178:181], v[44:47]
	v_mfma_f32_16x16x32_bf16 v[40:43], v[170:173], v[178:181], v[40:43]
	v_mfma_f32_16x16x32_bf16 v[28:31], v[162:165], v[192:195], v[28:31]
	v_mfma_f32_16x16x32_bf16 v[24:27], v[170:173], v[192:195], v[24:27]
	v_mfma_f32_16x16x32_bf16 v[12:15], v[162:165], v[200:203], v[12:15]
	v_mfma_f32_16x16x32_bf16 v[8:11], v[170:173], v[200:203], v[8:11]
	v_mfma_f32_16x16x32_bf16 v[4:7], v[162:165], v[208:211], v[4:7]
	v_mfma_f32_16x16x32_bf16 v[0:3], v[170:173], v[208:211], v[0:3]
	v_mfma_f32_16x16x32_bf16 v[44:47], v[166:169], v[188:191], v[44:47]
	v_mfma_f32_16x16x32_bf16 v[40:43], v[174:177], v[188:191], v[40:43]
	v_mfma_f32_16x16x32_bf16 v[28:31], v[166:169], v[196:199], v[28:31]
	v_mfma_f32_16x16x32_bf16 v[24:27], v[174:177], v[196:199], v[24:27]
	v_mfma_f32_16x16x32_bf16 v[12:15], v[166:169], v[204:207], v[12:15]
	v_mfma_f32_16x16x32_bf16 v[8:11], v[174:177], v[204:207], v[8:11]
	v_mfma_f32_16x16x32_bf16 v[4:7], v[166:169], v[212:215], v[4:7]
	v_mfma_f32_16x16x32_bf16 v[0:3], v[174:177], v[212:215], v[0:3]
	s_barrier
	s_add_i32 s81, s81, 2
	s_add_u32 s34, s34, 0x100
	s_addc_u32 s35, s35, 0
	s_add_u32 s79, s79, 0x100
	s_addc_u32 s80, s80, 0
	s_cmp_gt_u32 s81, 61
	s_cbranch_scc0 .LBB0_431
	s_branch .Lpost_431
.LBB0_431:
	ds_read_b128 v[146:149], v141
	ds_read_b128 v[150:153], v141 offset:1024
	ds_read_b128 v[154:157], v141 offset:2048
	ds_read_b128 v[158:161], v141 offset:3072
	ds_read_b128 v[162:165], v142
	ds_read_b128 v[166:169], v142 offset:1024
	ds_read_b128 v[170:173], v142 offset:2048
	ds_read_b128 v[174:177], v142 offset:3072
	s_add_u32 s14, s34, 0xfff00080
	s_addc_u32 s15, s35, -1
	s_cmp_eq_u32 s81, 60
	s_cselect_b32 s37, s74, s15
	s_cselect_b32 s36, s75, s14
	s_cselect_b32 s15, s76, s80
	s_cselect_b32 s14, s78, s79
	s_mov_b32 m0, s56
	v_lshl_add_u64 v[182:183], s[34:35], 0, v[136:137]
	ds_read_b128 v[178:181], v143
	ds_read_b128 v[188:191], v143 offset:1024
	ds_read_b128 v[192:195], v143 offset:2048
	ds_read_b128 v[196:199], v143 offset:3072
	ds_read_b128 v[200:203], v143 offset:4096
	ds_read_b128 v[204:207], v143 offset:5120
	ds_read_b128 v[208:211], v143 offset:6144
	ds_read_b128 v[212:215], v143 offset:7168
	global_load_lds_dwordx4 v[182:183], off
	v_lshl_add_u64 v[182:183], s[34:35], 0, v[138:139]
	s_add_i32 m0, s43, 0xe000
	s_nop 0
	global_load_lds_dwordx4 v[182:183], off
	s_waitcnt vmcnt(8)
	s_waitcnt lgkmcnt(0)
	s_barrier
; #define G_STAGE(bufoff, gbase, voff) do { _Pragma("unroll") for (int _i = 0; _i < 2; ++_i) \
;         __builtin_amdgcn_global_load_lds((const unsigned*)((const char*)(gbase) + voff[_i]), (LAS unsigned*)(lds + (bufoff) + ldsw + _i * 8192), 16, 0, 0); } while (0)
; #define G_LDA(dst, b, h) do { _Pragma("unroll") for (int m = 0; m < 4; ++m) _Pragma("unroll") for (int k = 0; k < 2; ++k) dst[m][k] = *(const LAS bf16x8*)(lds + G_SA(b, h) + aoff + m * 2048 + k * 1024); } while (0)
; #define G_LDB(dst, b, h) do { _Pragma("unroll") for (int n = 0; n < 2; ++n) _Pragma("unroll") for (int k = 0; k < 2; ++k) dst[n][k] = *(const LAS bf16x8*)(lds + G_SB(b, h) + boff + n * 2048 + k * 1024); } while (0)
; #define WAIT_V(n) asm volatile("s_waitcnt vmcnt(" #n ")" ::: "memory")
; #define WAIT_L(n) asm volatile("s_waitcnt lgkmcnt(" #n ")" ::: "memory")
; #define BAR __builtin_amdgcn_s_barrier()
; #define SCHED __builtin_amdgcn_sched_barrier(0)
; template <class Get, class Epi>
; DI void gemm_loop(int ntiles, int ld, char* shm, const Get& get, const Epi& epi) {
;     ...
;         for (int t = 0; t < nt; t += 2) {
;             const bool last = (t == nt - 2);
;             const char* a1 = cA + (size_t)(t + 1) * kstep;
;             const char* a2 = last ? nA : cA + (size_t)(t + 2) * kstep; const char* b2 = last ? nB : cB + (size_t)(t + 2) * kstep;
;             const char* a3 = a2 + kstep; const char* b3 = b2 + kstep;
;             G_LDB(B0, 0, 0); G_LDB(B1, 0, 1); SCHED; G_LDA(At, 0, 0); G_STAGE(G_SA(1, 1), a1 + hstep, voffA);
;             WAIT_V(8); WAIT_L(0); BAR; G_MMA(0, 0, At, B0); G_MMA(0, 1, At, B1); BAR; SCHED;
;             G_LDA(At, 0, 1); G_STAGE(G_SB(0, 0), b2, voffB); G_STAGE(G_SB(0, 1), b2 + hstep, voffB); G_STAGE(G_SA(0, 0), a2, voffA);
;             WAIT_V(8); WAIT_L(0); BAR; G_MMA(1, 0, At, B0); G_MMA(1, 1, At, B1); BAR; SCHED;
;             G_LDB(B0, 1, 0); G_LDB(B1, 1, 1); SCHED; G_LDA(At, 1, 0); G_STAGE(G_SA(0, 1), a2 + hstep, voffA);
;             WAIT_V(8); WAIT_L(0); BAR; G_MMA(0, 0, At, B0); G_MMA(0, 1, At, B1); BAR; SCHED;
;             G_LDA(At, 1, 1); G_STAGE(G_SB(1, 0), b3, voffB); G_STAGE(G_SB(1, 1), b3 + hstep, voffB); G_STAGE(G_SA(1, 0), a3, voffA);
;             WAIT_V(8); WAIT_L(0); BAR; G_MMA(1, 0, At, B0); G_MMA(1, 1, At, B1); BAR; SCHED;
	s_waitcnt lgkmcnt(0)
	v_mfma_f32_16x16x32_bf16 v[124:127], v[146:149], v[178:181], v[124:127]
	v_mfma_f32_16x16x32_bf16 v[120:123], v[154:157], v[178:181], v[120:123]
	v_mfma_f32_16x16x32_bf16 v[116:119], v[146:149], v[192:195], v[116:119]
	v_mfma_f32_16x16x32_bf16 v[112:115], v[154:157], v[192:195], v[112:115]
	v_mfma_f32_16x16x32_bf16 v[100:103], v[146:149], v[200:203], v[100:103]
	v_mfma_f32_16x16x32_bf16 v[96:99], v[154:157], v[200:203], v[96:99]
	v_mfma_f32_16x16x32_bf16 v[84:87], v[146:149], v[208:211], v[84:87]
	v_mfma_f32_16x16x32_bf16 v[80:83], v[154:157], v[208:211], v[80:83]
	v_mfma_f32_16x16x32_bf16 v[124:127], v[150:153], v[188:191], v[124:127]
	v_mfma_f32_16x16x32_bf16 v[120:123], v[158:161], v[188:191], v[120:123]
	v_mfma_f32_16x16x32_bf16 v[116:119], v[150:153], v[196:199], v[116:119]
	v_mfma_f32_16x16x32_bf16 v[112:115], v[158:161], v[196:199], v[112:115]
	v_mfma_f32_16x16x32_bf16 v[100:103], v[150:153], v[204:207], v[100:103]
	v_mfma_f32_16x16x32_bf16 v[96:99], v[158:161], v[204:207], v[96:99]
	v_mfma_f32_16x16x32_bf16 v[84:87], v[150:153], v[212:215], v[84:87]
	v_mfma_f32_16x16x32_bf16 v[80:83], v[158:161], v[212:215], v[80:83]
	v_mfma_f32_16x16x32_bf16 v[108:111], v[162:165], v[178:181], v[108:111]
	v_mfma_f32_16x16x32_bf16 v[104:107], v[170:173], v[178:181], v[104:107]
	v_mfma_f32_16x16x32_bf16 v[92:95], v[162:165], v[192:195], v[92:95]
	v_mfma_f32_16x16x32_bf16 v[88:91], v[170:173], v[192:195], v[88:91]
	v_mfma_f32_16x16x32_bf16 v[76:79], v[162:165], v[200:203], v[76:79]
	v_mfma_f32_16x16x32_bf16 v[72:75], v[170:173], v[200:203], v[72:75]
	v_mfma_f32_16x16x32_bf16 v[68:71], v[162:165], v[208:211], v[68:71]
	v_mfma_f32_16x16x32_bf16 v[64:67], v[170:173], v[208:211], v[64:67]
	v_mfma_f32_16x16x32_bf16 v[108:111], v[166:169], v[188:191], v[108:111]
	v_mfma_f32_16x16x32_bf16 v[104:107], v[174:177], v[188:191], v[104:107]
	v_mfma_f32_16x16x32_bf16 v[92:95], v[166:169], v[196:199], v[92:95]
	v_mfma_f32_16x16x32_bf16 v[88:91], v[174:177], v[196:199], v[88:91]
	v_mfma_f32_16x16x32_bf16 v[76:79], v[166:169], v[204:207], v[76:79]
	v_mfma_f32_16x16x32_bf16 v[72:75], v[174:177], v[204:207], v[72:75]
	v_mfma_f32_16x16x32_bf16 v[68:71], v[166:169], v[212:215], v[68:71]
	v_mfma_f32_16x16x32_bf16 v[64:67], v[174:177], v[212:215], v[64:67]
	s_barrier
	s_add_i32 s82, s54, s38
	v_lshl_add_u64 v[182:183], s[14:15], 0, v[132:133]
	s_mov_b32 m0, s82
	ds_read_b128 v[178:181], v143 offset:16384
	ds_read_b128 v[188:191], v143 offset:17408
	ds_read_b128 v[192:195], v143 offset:18432
	ds_read_b128 v[196:199], v143 offset:19456
	ds_read_b128 v[200:203], v143 offset:20480
	ds_read_b128 v[204:207], v143 offset:21504
	ds_read_b128 v[208:211], v143 offset:22528
	ds_read_b128 v[212:215], v143 offset:23552
	global_load_lds_dwordx4 v[182:183], off
	s_add_i32 m0, s82, 0x2000
	s_add_u32 s82, s14, 0x100000
	v_lshl_add_u64 v[184:185], s[14:15], 0, v[128:129]
	s_addc_u32 s83, s15, 0
	s_add_i32 s84, s55, s38
	global_load_lds_dwordx4 v[184:185], off
	v_lshl_add_u64 v[186:187], s[82:83], 0, v[132:133]
	s_mov_b32 m0, s84
	v_lshl_add_u64 v[216:217], s[36:37], 0, v[130:131]
	global_load_lds_dwordx4 v[186:187], off
	v_lshl_add_u64 v[186:187], s[82:83], 0, v[128:129]
	s_add_i32 m0, s84, 0x2000
	s_nop 0
	global_load_lds_dwordx4 v[186:187], off
	v_lshl_add_u64 v[186:187], s[36:37], 0, v[134:135]
	s_mov_b32 m0, s43
	s_nop 0
	global_load_lds_dwordx4 v[186:187], off
	s_mov_b32 m0, s44
	s_nop 0
	global_load_lds_dwordx4 v[216:217], off
	s_waitcnt vmcnt(8)
	s_waitcnt lgkmcnt(0)
	s_barrier
	s_waitcnt lgkmcnt(0)
	v_mfma_f32_16x16x32_bf16 v[60:63], v[146:149], v[178:181], v[60:63]
	v_mfma_f32_16x16x32_bf16 v[56:59], v[154:157], v[178:181], v[56:59]
	v_mfma_f32_16x16x32_bf16 v[52:55], v[146:149], v[192:195], v[52:55]
	v_mfma_f32_16x16x32_bf16 v[48:51], v[154:157], v[192:195], v[48:51]
	v_mfma_f32_16x16x32_bf16 v[36:39], v[146:149], v[200:203], v[36:39]
	v_mfma_f32_16x16x32_bf16 v[32:35], v[154:157], v[200:203], v[32:35]
	v_mfma_f32_16x16x32_bf16 v[20:23], v[146:149], v[208:211], v[20:23]
	v_mfma_f32_16x16x32_bf16 v[16:19], v[154:157], v[208:211], v[16:19]
	v_mfma_f32_16x16x32_bf16 v[60:63], v[150:153], v[188:191], v[60:63]
	v_mfma_f32_16x16x32_bf16 v[56:59], v[158:161], v[188:191], v[56:59]
	v_mfma_f32_16x16x32_bf16 v[52:55], v[150:153], v[196:199], v[52:55]
	v_mfma_f32_16x16x32_bf16 v[48:51], v[158:161], v[196:199], v[48:51]
	v_mfma_f32_16x16x32_bf16 v[36:39], v[150:153], v[204:207], v[36:39]
	v_mfma_f32_16x16x32_bf16 v[32:35], v[158:161], v[204:207], v[32:35]
	v_mfma_f32_16x16x32_bf16 v[20:23], v[150:153], v[212:215], v[20:23]
	v_mfma_f32_16x16x32_bf16 v[16:19], v[158:161], v[212:215], v[16:19]
	v_mfma_f32_16x16x32_bf16 v[44:47], v[162:165], v[178:181], v[44:47]
	v_mfma_f32_16x16x32_bf16 v[40:43], v[170:173], v[178:181], v[40:43]
	v_mfma_f32_16x16x32_bf16 v[28:31], v[162:165], v[192:195], v[28:31]
	v_mfma_f32_16x16x32_bf16 v[24:27], v[170:173], v[192:195], v[24:27]
	v_mfma_f32_16x16x32_bf16 v[12:15], v[162:165], v[200:203], v[12:15]
	v_mfma_f32_16x16x32_bf16 v[8:11], v[170:173], v[200:203], v[8:11]
	v_mfma_f32_16x16x32_bf16 v[4:7], v[162:165], v[208:211], v[4:7]
	v_mfma_f32_16x16x32_bf16 v[0:3], v[170:173], v[208:211], v[0:3]
	v_mfma_f32_16x16x32_bf16 v[44:47], v[166:169], v[188:191], v[44:47]
	v_mfma_f32_16x16x32_bf16 v[40:43], v[174:177], v[188:191], v[40:43]
	v_mfma_f32_16x16x32_bf16 v[28:31], v[166:169], v[196:199], v[28:31]
	v_mfma_f32_16x16x32_bf16 v[24:27], v[174:177], v[196:199], v[24:27]
	v_mfma_f32_16x16x32_bf16 v[12:15], v[166:169], v[204:207], v[12:15]
	v_mfma_f32_16x16x32_bf16 v[8:11], v[174:177], v[204:207], v[8:11]
	v_mfma_f32_16x16x32_bf16 v[4:7], v[166:169], v[212:215], v[4:7]
	v_mfma_f32_16x16x32_bf16 v[0:3], v[174:177], v[212:215], v[0:3]
	s_barrier
; #define G_STAGE(bufoff, gbase, voff) do { _Pragma("unroll") for (int _i = 0; _i < 2; ++_i) \
;         __builtin_amdgcn_global_load_lds((const unsigned*)((const char*)(gbase) + voff[_i]), (LAS unsigned*)(lds + (bufoff) + ldsw + _i * 8192), 16, 0, 0); } while (0)
; #define G_LDA(dst, b, h) do { _Pragma("unroll") for (int m = 0; m < 4; ++m) _Pragma("unroll") for (int k = 0; k < 2; ++k) dst[m][k] = *(const LAS bf16x8*)(lds + G_SA(b, h) + aoff + m * 2048 + k * 1024); } while (0)
; #define G_LDB(dst, b, h) do { _Pragma("unroll") for (int n = 0; n < 2; ++n) _Pragma("unroll") for (int k = 0; k < 2; ++k) dst[n][k] = *(const LAS bf16x8*)(lds + G_SB(b, h) + boff + n * 2048 + k * 1024); } while (0)
; #define WAIT_V(n) asm volatile("s_waitcnt vmcnt(" #n ")" ::: "memory")
; #define WAIT_L(n) asm volatile("s_waitcnt lgkmcnt(" #n ")" ::: "memory")
; #define BAR __builtin_amdgcn_s_barrier()
; #define SCHED __builtin_amdgcn_sched_barrier(0)
; template <class Get, class Epi>
; DI void gemm_loop(int ntiles, int ld, char* shm, const Get& get, const Epi& epi) {
;     ...
;         for (int t = 0; t < nt; t += 2) {
;             const bool last = (t == nt - 2);
;             const char* a1 = cA + (size_t)(t + 1) * kstep;
;             const char* a2 = last ? nA : cA + (size_t)(t + 2) * kstep; const char* b2 = last ? nB : cB + (size_t)(t + 2) * kstep;
;             const char* a3 = a2 + kstep; const char* b3 = b2 + kstep;
;             G_LDB(B0, 0, 0); G_LDB(B1, 0, 1); SCHED; G_LDA(At, 0, 0); G_STAGE(G_SA(1, 1), a1 + hstep, voffA);
;             WAIT_V(8); WAIT_L(0); BAR; G_MMA(0, 0, At, B0); G_MMA(0, 1, At, B1); BAR; SCHED;
;             G_LDA(At, 0, 1); G_STAGE(G_SB(0, 0), b2, voffB); G_STAGE(G_SB(0, 1), b2 + hstep, voffB); G_STAGE(G_SA(0, 0), a2, voffA);
;             WAIT_V(8); WAIT_L(0); BAR; G_MMA(1, 0, At, B0); G_MMA(1, 1, At, B1); BAR; SCHED;
;             G_LDB(B0, 1, 0); G_LDB(B1, 1, 1); SCHED; G_LDA(At, 1, 0); G_STAGE(G_SA(0, 1), a2 + hstep, voffA);
;             WAIT_V(8); WAIT_L(0); BAR; G_MMA(0, 0, At, B0); G_MMA(0, 1, At, B1); BAR; SCHED;
;             G_LDA(At, 1, 1); G_STAGE(G_SB(1, 0), b3, voffB); G_STAGE(G_SB(1, 1), b3 + hstep, voffB); G_STAGE(G_SA(1, 0), a3, voffA);
;             WAIT_V(8); WAIT_L(0); BAR; G_MMA(1, 0, At, B0); G_MMA(1, 1, At, B1); BAR; SCHED;
	s_add_i32 s82, 0, 0x18000
	v_add_u32_e32 v145, s82, v140
	s_add_i32 s83, 0, 0x1c000
	ds_read_b128 v[146:149], v145
	ds_read_b128 v[150:153], v145 offset:1024
	ds_read_b128 v[154:157], v145 offset:2048
	ds_read_b128 v[158:161], v145 offset:3072
	v_add_u32_e32 v145, s83, v140
	ds_read_b128 v[162:165], v145
	ds_read_b128 v[166:169], v145 offset:1024
	ds_read_b128 v[170:173], v145 offset:2048
	ds_read_b128 v[174:177], v145 offset:3072
	s_add_u32 s36, s36, 0x100000
	s_addc_u32 s37, s37, 0
	s_mov_b32 m0, s45
	v_lshl_add_u64 v[218:219], s[36:37], 0, v[134:135]
	ds_read_b128 v[178:181], v143 offset:32768
	ds_read_b128 v[188:191], v143 offset:33792
	ds_read_b128 v[192:195], v143 offset:34816
	ds_read_b128 v[196:199], v143 offset:35840
	ds_read_b128 v[200:203], v143 offset:36864
	ds_read_b128 v[204:207], v143 offset:37888
	ds_read_b128 v[208:211], v143 offset:38912
	ds_read_b128 v[212:215], v143 offset:39936
	global_load_lds_dwordx4 v[218:219], off
	v_lshl_add_u64 v[218:219], s[36:37], 0, v[130:131]
	s_mov_b32 m0, s46
	s_nop 0
	global_load_lds_dwordx4 v[218:219], off
	s_waitcnt vmcnt(8)
	s_waitcnt lgkmcnt(0)
	s_barrier
	s_waitcnt lgkmcnt(0)
	v_mfma_f32_16x16x32_bf16 v[124:127], v[146:149], v[178:181], v[124:127]
	v_mfma_f32_16x16x32_bf16 v[120:123], v[154:157], v[178:181], v[120:123]
	v_mfma_f32_16x16x32_bf16 v[116:119], v[146:149], v[192:195], v[116:119]
	v_mfma_f32_16x16x32_bf16 v[112:115], v[154:157], v[192:195], v[112:115]
	v_mfma_f32_16x16x32_bf16 v[100:103], v[146:149], v[200:203], v[100:103]
	v_mfma_f32_16x16x32_bf16 v[96:99], v[154:157], v[200:203], v[96:99]
	v_mfma_f32_16x16x32_bf16 v[84:87], v[146:149], v[208:211], v[84:87]
	v_mfma_f32_16x16x32_bf16 v[80:83], v[154:157], v[208:211], v[80:83]
	v_mfma_f32_16x16x32_bf16 v[124:127], v[150:153], v[188:191], v[124:127]
	v_mfma_f32_16x16x32_bf16 v[120:123], v[158:161], v[188:191], v[120:123]
	v_mfma_f32_16x16x32_bf16 v[116:119], v[150:153], v[196:199], v[116:119]
	v_mfma_f32_16x16x32_bf16 v[112:115], v[158:161], v[196:199], v[112:115]
	v_mfma_f32_16x16x32_bf16 v[100:103], v[150:153], v[204:207], v[100:103]
	v_mfma_f32_16x16x32_bf16 v[96:99], v[158:161], v[204:207], v[96:99]
	v_mfma_f32_16x16x32_bf16 v[84:87], v[150:153], v[212:215], v[84:87]
	v_mfma_f32_16x16x32_bf16 v[80:83], v[158:161], v[212:215], v[80:83]
	v_mfma_f32_16x16x32_bf16 v[108:111], v[162:165], v[178:181], v[108:111]
	v_mfma_f32_16x16x32_bf16 v[104:107], v[170:173], v[178:181], v[104:107]
	v_mfma_f32_16x16x32_bf16 v[92:95], v[162:165], v[192:195], v[92:95]
	v_mfma_f32_16x16x32_bf16 v[88:91], v[170:173], v[192:195], v[88:91]
	v_mfma_f32_16x16x32_bf16 v[76:79], v[162:165], v[200:203], v[76:79]
	v_mfma_f32_16x16x32_bf16 v[72:75], v[170:173], v[200:203], v[72:75]
	v_mfma_f32_16x16x32_bf16 v[68:71], v[162:165], v[208:211], v[68:71]
	v_mfma_f32_16x16x32_bf16 v[64:67], v[170:173], v[208:211], v[64:67]
	v_mfma_f32_16x16x32_bf16 v[108:111], v[166:169], v[188:191], v[108:111]
	v_mfma_f32_16x16x32_bf16 v[104:107], v[174:177], v[188:191], v[104:107]
	v_mfma_f32_16x16x32_bf16 v[92:95], v[166:169], v[196:199], v[92:95]
	v_mfma_f32_16x16x32_bf16 v[88:91], v[174:177], v[196:199], v[88:91]
	v_mfma_f32_16x16x32_bf16 v[76:79], v[166:169], v[204:207], v[76:79]
	v_mfma_f32_16x16x32_bf16 v[72:75], v[174:177], v[204:207], v[72:75]
	v_mfma_f32_16x16x32_bf16 v[68:71], v[166:169], v[212:215], v[68:71]
	v_mfma_f32_16x16x32_bf16 v[64:67], v[174:177], v[212:215], v[64:67]
	s_barrier
	s_add_i32 s36, s82, s38
	v_lshl_add_u64 v[182:183], v[182:183], 0, s[8:9]
	s_mov_b32 m0, s36
	ds_read_b128 v[178:181], v143 offset:49152
	ds_read_b128 v[188:191], v143 offset:50176
	ds_read_b128 v[192:195], v143 offset:51200
	ds_read_b128 v[196:199], v143 offset:52224
	ds_read_b128 v[200:203], v143 offset:53248
	ds_read_b128 v[204:207], v143 offset:54272
	ds_read_b128 v[208:211], v143 offset:55296
	ds_read_b128 v[212:215], v143 offset:56320
	global_load_lds_dwordx4 v[182:183], off
	s_add_i32 m0, s36, 0x2000
	s_add_u32 s14, s14, 0x100080
	v_lshl_add_u64 v[182:183], v[184:185], 0, s[8:9]
	s_addc_u32 s15, s15, 0
	s_add_i32 s36, s83, s38
	global_load_lds_dwordx4 v[182:183], off
	v_lshl_add_u64 v[182:183], s[14:15], 0, v[132:133]
	s_mov_b32 m0, s36
	s_nop 0
	global_load_lds_dwordx4 v[182:183], off
	v_lshl_add_u64 v[182:183], s[14:15], 0, v[128:129]
	s_add_i32 m0, s36, 0x2000
	s_nop 0
	global_load_lds_dwordx4 v[182:183], off
	v_lshl_add_u64 v[182:183], v[186:187], 0, s[8:9]
	s_mov_b32 m0, s47
	s_nop 0
	global_load_lds_dwordx4 v[182:183], off
	v_lshl_add_u64 v[182:183], v[216:217], 0, s[8:9]
	s_mov_b32 m0, s50
	s_nop 0
	global_load_lds_dwordx4 v[182:183], off
	s_waitcnt vmcnt(8)
	s_waitcnt lgkmcnt(0)
	s_barrier
	s_waitcnt lgkmcnt(0)
	v_mfma_f32_16x16x32_bf16 v[60:63], v[146:149], v[178:181], v[60:63]
	v_mfma_f32_16x16x32_bf16 v[56:59], v[154:157], v[178:181], v[56:59]
	v_mfma_f32_16x16x32_bf16 v[52:55], v[146:149], v[192:195], v[52:55]
	v_mfma_f32_16x16x32_bf16 v[48:51], v[154:157], v[192:195], v[48:51]
	v_mfma_f32_16x16x32_bf16 v[36:39], v[146:149], v[200:203], v[36:39]
	v_mfma_f32_16x16x32_bf16 v[32:35], v[154:157], v[200:203], v[32:35]
	v_mfma_f32_16x16x32_bf16 v[20:23], v[146:149], v[208:211], v[20:23]
	v_mfma_f32_16x16x32_bf16 v[16:19], v[154:157], v[208:211], v[16:19]
	v_mfma_f32_16x16x32_bf16 v[60:63], v[150:153], v[188:191], v[60:63]
	v_mfma_f32_16x16x32_bf16 v[56:59], v[158:161], v[188:191], v[56:59]
	v_mfma_f32_16x16x32_bf16 v[52:55], v[150:153], v[196:199], v[52:55]
	v_mfma_f32_16x16x32_bf16 v[48:51], v[158:161], v[196:199], v[48:51]
	v_mfma_f32_16x16x32_bf16 v[36:39], v[150:153], v[204:207], v[36:39]
	v_mfma_f32_16x16x32_bf16 v[32:35], v[158:161], v[204:207], v[32:35]
	v_mfma_f32_16x16x32_bf16 v[20:23], v[150:153], v[212:215], v[20:23]
	v_mfma_f32_16x16x32_bf16 v[16:19], v[158:161], v[212:215], v[16:19]
	v_mfma_f32_16x16x32_bf16 v[44:47], v[162:165], v[178:181], v[44:47]
	v_mfma_f32_16x16x32_bf16 v[40:43], v[170:173], v[178:181], v[40:43]
	v_mfma_f32_16x16x32_bf16 v[28:31], v[162:165], v[192:195], v[28:31]
	v_mfma_f32_16x16x32_bf16 v[24:27], v[170:173], v[192:195], v[24:27]
	v_mfma_f32_16x16x32_bf16 v[12:15], v[162:165], v[200:203], v[12:15]
	v_mfma_f32_16x16x32_bf16 v[8:11], v[170:173], v[200:203], v[8:11]
	v_mfma_f32_16x16x32_bf16 v[4:7], v[162:165], v[208:211], v[4:7]
	v_mfma_f32_16x16x32_bf16 v[0:3], v[170:173], v[208:211], v[0:3]
	v_mfma_f32_16x16x32_bf16 v[44:47], v[166:169], v[188:191], v[44:47]
	v_mfma_f32_16x16x32_bf16 v[40:43], v[174:177], v[188:191], v[40:43]
	v_mfma_f32_16x16x32_bf16 v[28:31], v[166:169], v[196:199], v[28:31]
	v_mfma_f32_16x16x32_bf16 v[24:27], v[174:177], v[196:199], v[24:27]
	v_mfma_f32_16x16x32_bf16 v[12:15], v[166:169], v[204:207], v[12:15]
	v_mfma_f32_16x16x32_bf16 v[8:11], v[174:177], v[204:207], v[8:11]
	v_mfma_f32_16x16x32_bf16 v[4:7], v[166:169], v[212:215], v[4:7]
	v_mfma_f32_16x16x32_bf16 v[0:3], v[174:177], v[212:215], v[0:3]
	s_barrier
	s_add_i32 s81, s81, 2
	s_add_u32 s34, s34, 0x100
	s_addc_u32 s35, s35, 0
	s_add_u32 s79, s79, 0x100
	s_addc_u32 s80, s80, 0
	s_cmp_gt_u32 s81, 61
	s_cbranch_scc0 .LBB0_431

; #define G_STAGE(bufoff, gbase, voff) do { _Pragma("unroll") for (int _i = 0; _i < 2; ++_i) \
;         __builtin_amdgcn_global_load_lds((const unsigned*)((const char*)(gbase) + voff[_i]), (LAS unsigned*)(lds + (bufoff) + ldsw + _i * 8192), 16, 0, 0); } while (0)
; #define G_LDA(dst, b, h) do { _Pragma("unroll") for (int m = 0; m < 4; ++m) _Pragma("unroll") for (int k = 0; k < 2; ++k) dst[m][k] = *(const LAS bf16x8*)(lds + G_SA(b, h) + aoff + m * 2048 + k * 1024); } while (0)
; #define G_LDB(dst, b, h) do { _Pragma("unroll") for (int n = 0; n < 2; ++n) _Pragma("unroll") for (int k = 0; k < 2; ++k) dst[n][k] = *(const LAS bf16x8*)(lds + G_SB(b, h) + boff + n * 2048 + k * 1024); } while (0)
; template <class Get, class Epi>
; DI void gemm_loop(int ntiles, int ld, char* shm, const Get& get, const Epi& epi) {
;     ...
;     for (;;) {
;         const int Ln = L + gridDim.x; const bool has_next = Ln < ntiles; if (has_next) nxt = get(Ln);
;         const char* nA = has_next ? (const char*)nxt.A + (size_t)nxt.brow * ld * 2 : cA; const char* nB = has_next ? (const char*)nxt.Bt + (size_t)nxt.bcol * ld * 2 : cB;
;         const int nt = cur.K / BK;
;         for (int t = 0; t < nt; t += 2) {
;             const bool last = (t == nt - 2);
;             const char* a1 = cA + (size_t)(t + 1) * kstep;
;             const char* a2 = last ? nA : cA + (size_t)(t + 2) * kstep; const char* b2 = last ? nB : cB + (size_t)(t + 2) * kstep;
;             const char* a3 = a2 + kstep; const char* b3 = b2 + kstep;
;             G_LDB(B0, 0, 0); G_LDB(B1, 0, 1); SCHED; G_LDA(At, 0, 0); G_STAGE(G_SA(1, 1), a1 + hstep, voffA);
;             WAIT_V(8); WAIT_L(0); BAR; G_MMA(0, 0, At, B0); G_MMA(0, 1, At, B1); BAR; SCHED;
;             G_LDA(At, 0, 1); G_STAGE(G_SB(0, 0), b2, voffB); G_STAGE(G_SB(0, 1), b2 + hstep, voffB); G_STAGE(G_SA(0, 0), a2, voffA);
;             WAIT_V(8); WAIT_L(0); BAR; G_MMA(1, 0, At, B0); G_MMA(1, 1, At, B1); BAR; SCHED;
;             G_LDB(B0, 1, 0); G_LDB(B1, 1, 1); SCHED; G_LDA(At, 1, 0); G_STAGE(G_SA(0, 1), a2 + hstep, voffA);
;             WAIT_V(8); WAIT_L(0); BAR; G_MMA(0, 0, At, B0); G_MMA(0, 1, At, B1); BAR; SCHED;
;             G_LDA(At, 1, 1); G_STAGE(G_SB(1, 0), b3, voffB); G_STAGE(G_SB(1, 1), b3 + hstep, voffB); G_STAGE(G_SA(1, 0), a3, voffA);
;             WAIT_V(8); WAIT_L(0); BAR; G_MMA(1, 0, At, B0); G_MMA(1, 1, At, B1); BAR; SCHED;
.Lrj_445_0:
	s_waitcnt lgkmcnt(0)
	s_barrier
	s_waitcnt lgkmcnt(0)
	v_mfma_f32_16x16x32_bf16 v[124:127], v[146:149], v[178:181], 0
	v_mfma_f32_16x16x32_bf16 v[120:123], v[154:157], v[178:181], 0
	v_mfma_f32_16x16x32_bf16 v[116:119], v[146:149], v[192:195], 0
	v_mfma_f32_16x16x32_bf16 v[112:115], v[154:157], v[192:195], 0
	v_mfma_f32_16x16x32_bf16 v[100:103], v[146:149], v[200:203], 0
	v_mfma_f32_16x16x32_bf16 v[96:99], v[154:157], v[200:203], 0
	v_mfma_f32_16x16x32_bf16 v[84:87], v[146:149], v[208:211], 0
	v_mfma_f32_16x16x32_bf16 v[80:83], v[154:157], v[208:211], 0
	v_mfma_f32_16x16x32_bf16 v[124:127], v[150:153], v[188:191], v[124:127]
	v_mfma_f32_16x16x32_bf16 v[120:123], v[158:161], v[188:191], v[120:123]
	v_mfma_f32_16x16x32_bf16 v[116:119], v[150:153], v[196:199], v[116:119]
	v_mfma_f32_16x16x32_bf16 v[112:115], v[158:161], v[196:199], v[112:115]
	v_mfma_f32_16x16x32_bf16 v[100:103], v[150:153], v[204:207], v[100:103]
	v_mfma_f32_16x16x32_bf16 v[96:99], v[158:161], v[204:207], v[96:99]
	v_mfma_f32_16x16x32_bf16 v[84:87], v[150:153], v[212:215], v[84:87]
	v_mfma_f32_16x16x32_bf16 v[80:83], v[158:161], v[212:215], v[80:83]
	v_mfma_f32_16x16x32_bf16 v[108:111], v[162:165], v[178:181], 0
	v_mfma_f32_16x16x32_bf16 v[104:107], v[170:173], v[178:181], 0
	v_mfma_f32_16x16x32_bf16 v[92:95], v[162:165], v[192:195], 0
	v_mfma_f32_16x16x32_bf16 v[88:91], v[170:173], v[192:195], 0
	v_mfma_f32_16x16x32_bf16 v[76:79], v[162:165], v[200:203], 0
	v_mfma_f32_16x16x32_bf16 v[72:75], v[170:173], v[200:203], 0
	v_mfma_f32_16x16x32_bf16 v[68:71], v[162:165], v[208:211], 0
	v_mfma_f32_16x16x32_bf16 v[64:67], v[170:173], v[208:211], 0
	v_mfma_f32_16x16x32_bf16 v[108:111], v[166:169], v[188:191], v[108:111]
	v_mfma_f32_16x16x32_bf16 v[104:107], v[174:177], v[188:191], v[104:107]
	v_mfma_f32_16x16x32_bf16 v[92:95], v[166:169], v[196:199], v[92:95]
	v_mfma_f32_16x16x32_bf16 v[88:91], v[174:177], v[196:199], v[88:91]
	v_mfma_f32_16x16x32_bf16 v[76:79], v[166:169], v[204:207], v[76:79]
	v_mfma_f32_16x16x32_bf16 v[72:75], v[174:177], v[204:207], v[72:75]
	v_mfma_f32_16x16x32_bf16 v[68:71], v[166:169], v[212:215], v[68:71]
	v_mfma_f32_16x16x32_bf16 v[64:67], v[174:177], v[212:215], v[64:67]
	s_barrier
	s_mov_b32 m0, s54
	v_lshl_add_u64 v[182:183], s[14:15], 0, v[132:133]
	s_add_u32 s82, s14, 0x20000
	ds_read_b128 v[178:181], v142 offset:16384
	ds_read_b128 v[188:191], v142 offset:17408
	ds_read_b128 v[192:195], v142 offset:18432
	ds_read_b128 v[196:199], v142 offset:19456
	ds_read_b128 v[200:203], v142 offset:20480
	ds_read_b128 v[204:207], v142 offset:21504
	ds_read_b128 v[208:211], v142 offset:22528
	ds_read_b128 v[212:215], v142 offset:23552
	global_load_lds_dwordx4 v[182:183], off
	v_lshl_add_u64 v[184:185], s[14:15], 0, v[128:129]
	s_mov_b32 m0, s55
	s_addc_u32 s83, s15, 0
	global_load_lds_dwordx4 v[184:185], off
	v_lshl_add_u64 v[186:187], s[82:83], 0, v[132:133]
	s_mov_b32 m0, s56
	v_lshl_add_u64 v[216:217], s[38:39], 0, v[130:131]
	global_load_lds_dwordx4 v[186:187], off
	v_lshl_add_u64 v[186:187], s[82:83], 0, v[128:129]
	s_mov_b32 m0, s57
	s_nop 0
	global_load_lds_dwordx4 v[186:187], off
	v_lshl_add_u64 v[186:187], s[38:39], 0, v[134:135]
	s_mov_b32 m0, s41
	s_nop 0
	global_load_lds_dwordx4 v[186:187], off
	s_mov_b32 m0, s43
	s_nop 0
	global_load_lds_dwordx4 v[216:217], off
	s_cmp_lg_u32 s100, 0
	s_cbranch_scc0 .Lrf_445_1
	s_waitcnt vmcnt(16)
	s_branch .Lrj_445_1

; #define G_STAGE(bufoff, gbase, voff) do { _Pragma("unroll") for (int _i = 0; _i < 2; ++_i) \
;         __builtin_amdgcn_global_load_lds((const unsigned*)((const char*)(gbase) + voff[_i]), (LAS unsigned*)(lds + (bufoff) + ldsw + _i * 8192), 16, 0, 0); } while (0)
; #define G_LDA(dst, b, h) do { _Pragma("unroll") for (int m = 0; m < 4; ++m) _Pragma("unroll") for (int k = 0; k < 2; ++k) dst[m][k] = *(const LAS bf16x8*)(lds + G_SA(b, h) + aoff + m * 2048 + k * 1024); } while (0)
; #define G_LDB(dst, b, h) do { _Pragma("unroll") for (int n = 0; n < 2; ++n) _Pragma("unroll") for (int k = 0; k < 2; ++k) dst[n][k] = *(const LAS bf16x8*)(lds + G_SB(b, h) + boff + n * 2048 + k * 1024); } while (0)
; template <class Get, class Epi>
; DI void gemm_loop(int ntiles, int ld, char* shm, const Get& get, const Epi& epi) {
;     ...
;     for (;;) {
;         const int Ln = L + gridDim.x; const bool has_next = Ln < ntiles; if (has_next) nxt = get(Ln);
;         const char* nA = has_next ? (const char*)nxt.A + (size_t)nxt.brow * ld * 2 : cA; const char* nB = has_next ? (const char*)nxt.Bt + (size_t)nxt.bcol * ld * 2 : cB;
;         const int nt = cur.K / BK;
;         for (int t = 0; t < nt; t += 2) {
;             const bool last = (t == nt - 2);
;             const char* a1 = cA + (size_t)(t + 1) * kstep;
;             const char* a2 = last ? nA : cA + (size_t)(t + 2) * kstep; const char* b2 = last ? nB : cB + (size_t)(t + 2) * kstep;
;             const char* a3 = a2 + kstep; const char* b3 = b2 + kstep;
;             G_LDB(B0, 0, 0); G_LDB(B1, 0, 1); SCHED; G_LDA(At, 0, 0); G_STAGE(G_SA(1, 1), a1 + hstep, voffA);
;             WAIT_V(8); WAIT_L(0); BAR; G_MMA(0, 0, At, B0); G_MMA(0, 1, At, B1); BAR; SCHED;
;             G_LDA(At, 0, 1); G_STAGE(G_SB(0, 0), b2, voffB); G_STAGE(G_SB(0, 1), b2 + hstep, voffB); G_STAGE(G_SA(0, 0), a2, voffA);
;             WAIT_V(8); WAIT_L(0); BAR; G_MMA(1, 0, At, B0); G_MMA(1, 1, At, B1); BAR; SCHED;
;             G_LDB(B0, 1, 0); G_LDB(B1, 1, 1); SCHED; G_LDA(At, 1, 0); G_STAGE(G_SA(0, 1), a2 + hstep, voffA);
;             WAIT_V(8); WAIT_L(0); BAR; G_MMA(0, 0, At, B0); G_MMA(0, 1, At, B1); BAR; SCHED;
;             G_LDA(At, 1, 1); G_STAGE(G_SB(1, 0), b3, voffB); G_STAGE(G_SB(1, 1), b3 + hstep, voffB); G_STAGE(G_SA(1, 0), a3, voffA);
;             WAIT_V(8); WAIT_L(0); BAR; G_MMA(1, 0, At, B0); G_MMA(1, 1, At, B1); BAR; SCHED;
.Lrj_445_1:
	s_waitcnt lgkmcnt(0)
	s_barrier
	s_waitcnt lgkmcnt(0)
	v_mfma_f32_16x16x32_bf16 v[60:63], v[146:149], v[178:181], 0
	v_mfma_f32_16x16x32_bf16 v[56:59], v[154:157], v[178:181], 0
	v_mfma_f32_16x16x32_bf16 v[52:55], v[146:149], v[192:195], 0
	v_mfma_f32_16x16x32_bf16 v[48:51], v[154:157], v[192:195], 0
	v_mfma_f32_16x16x32_bf16 v[36:39], v[146:149], v[200:203], 0
	v_mfma_f32_16x16x32_bf16 v[32:35], v[154:157], v[200:203], 0
	v_mfma_f32_16x16x32_bf16 v[20:23], v[146:149], v[208:211], 0
	v_mfma_f32_16x16x32_bf16 v[16:19], v[154:157], v[208:211], 0
	v_mfma_f32_16x16x32_bf16 v[60:63], v[150:153], v[188:191], v[60:63]
	v_mfma_f32_16x16x32_bf16 v[56:59], v[158:161], v[188:191], v[56:59]
	v_mfma_f32_16x16x32_bf16 v[52:55], v[150:153], v[196:199], v[52:55]
	v_mfma_f32_16x16x32_bf16 v[48:51], v[158:161], v[196:199], v[48:51]
	v_mfma_f32_16x16x32_bf16 v[36:39], v[150:153], v[204:207], v[36:39]
	v_mfma_f32_16x16x32_bf16 v[32:35], v[158:161], v[204:207], v[32:35]
	v_mfma_f32_16x16x32_bf16 v[20:23], v[150:153], v[212:215], v[20:23]
	v_mfma_f32_16x16x32_bf16 v[16:19], v[158:161], v[212:215], v[16:19]
	v_mfma_f32_16x16x32_bf16 v[44:47], v[162:165], v[178:181], 0
	v_mfma_f32_16x16x32_bf16 v[40:43], v[170:173], v[178:181], 0
	v_mfma_f32_16x16x32_bf16 v[28:31], v[162:165], v[192:195], 0
	v_mfma_f32_16x16x32_bf16 v[24:27], v[170:173], v[192:195], 0
	v_mfma_f32_16x16x32_bf16 v[12:15], v[162:165], v[200:203], 0
	v_mfma_f32_16x16x32_bf16 v[8:11], v[170:173], v[200:203], 0
	v_mfma_f32_16x16x32_bf16 v[4:7], v[162:165], v[208:211], 0
	v_mfma_f32_16x16x32_bf16 v[0:3], v[170:173], v[208:211], 0
	v_mfma_f32_16x16x32_bf16 v[44:47], v[166:169], v[188:191], v[44:47]
	v_mfma_f32_16x16x32_bf16 v[40:43], v[174:177], v[188:191], v[40:43]
	v_mfma_f32_16x16x32_bf16 v[28:31], v[166:169], v[196:199], v[28:31]
	v_mfma_f32_16x16x32_bf16 v[24:27], v[174:177], v[196:199], v[24:27]
	v_mfma_f32_16x16x32_bf16 v[12:15], v[166:169], v[204:207], v[12:15]
	v_mfma_f32_16x16x32_bf16 v[8:11], v[174:177], v[204:207], v[8:11]
	v_mfma_f32_16x16x32_bf16 v[4:7], v[166:169], v[212:215], v[4:7]
	v_mfma_f32_16x16x32_bf16 v[0:3], v[174:177], v[212:215], v[0:3]
	s_barrier
	ds_read_b128 v[146:149], v143
	ds_read_b128 v[150:153], v143 offset:1024
	ds_read_b128 v[154:157], v143 offset:2048
	ds_read_b128 v[158:161], v143 offset:3072
	ds_read_b128 v[162:165], v144
	ds_read_b128 v[166:169], v144 offset:1024
	ds_read_b128 v[170:173], v144 offset:2048
	ds_read_b128 v[174:177], v144 offset:3072
	s_add_u32 s38, s38, 0x20000
	s_addc_u32 s39, s39, 0
	s_mov_b32 m0, s44
	v_lshl_add_u64 v[218:219], s[38:39], 0, v[134:135]
	ds_read_b128 v[178:181], v142 offset:32768
	ds_read_b128 v[188:191], v142 offset:33792
	ds_read_b128 v[192:195], v142 offset:34816
	ds_read_b128 v[196:199], v142 offset:35840
	ds_read_b128 v[200:203], v142 offset:36864
	ds_read_b128 v[204:207], v142 offset:37888
	ds_read_b128 v[208:211], v142 offset:38912
	ds_read_b128 v[212:215], v142 offset:39936
	global_load_lds_dwordx4 v[218:219], off
	v_lshl_add_u64 v[218:219], s[38:39], 0, v[130:131]
	s_mov_b32 m0, s45
	s_nop 0
	global_load_lds_dwordx4 v[218:219], off
	s_waitcnt vmcnt(8)
	s_waitcnt lgkmcnt(0)
	s_barrier
	s_waitcnt lgkmcnt(0)
	v_mfma_f32_16x16x32_bf16 v[124:127], v[146:149], v[178:181], v[124:127]
	v_mfma_f32_16x16x32_bf16 v[120:123], v[154:157], v[178:181], v[120:123]
	v_mfma_f32_16x16x32_bf16 v[116:119], v[146:149], v[192:195], v[116:119]
	v_mfma_f32_16x16x32_bf16 v[112:115], v[154:157], v[192:195], v[112:115]
	v_mfma_f32_16x16x32_bf16 v[100:103], v[146:149], v[200:203], v[100:103]
	v_mfma_f32_16x16x32_bf16 v[96:99], v[154:157], v[200:203], v[96:99]
	v_mfma_f32_16x16x32_bf16 v[84:87], v[146:149], v[208:211], v[84:87]
	v_mfma_f32_16x16x32_bf16 v[80:83], v[154:157], v[208:211], v[80:83]
	v_mfma_f32_16x16x32_bf16 v[124:127], v[150:153], v[188:191], v[124:127]
	v_mfma_f32_16x16x32_bf16 v[120:123], v[158:161], v[188:191], v[120:123]
	v_mfma_f32_16x16x32_bf16 v[116:119], v[150:153], v[196:199], v[116:119]
	v_mfma_f32_16x16x32_bf16 v[112:115], v[158:161], v[196:199], v[112:115]
	v_mfma_f32_16x16x32_bf16 v[100:103], v[150:153], v[204:207], v[100:103]
	v_mfma_f32_16x16x32_bf16 v[96:99], v[158:161], v[204:207], v[96:99]
	v_mfma_f32_16x16x32_bf16 v[84:87], v[150:153], v[212:215], v[84:87]
	v_mfma_f32_16x16x32_bf16 v[80:83], v[158:161], v[212:215], v[80:83]
	v_mfma_f32_16x16x32_bf16 v[108:111], v[162:165], v[178:181], v[108:111]
	v_mfma_f32_16x16x32_bf16 v[104:107], v[170:173], v[178:181], v[104:107]
	v_mfma_f32_16x16x32_bf16 v[92:95], v[162:165], v[192:195], v[92:95]
	v_mfma_f32_16x16x32_bf16 v[88:91], v[170:173], v[192:195], v[88:91]
	v_mfma_f32_16x16x32_bf16 v[76:79], v[162:165], v[200:203], v[76:79]
	v_mfma_f32_16x16x32_bf16 v[72:75], v[170:173], v[200:203], v[72:75]
	v_mfma_f32_16x16x32_bf16 v[68:71], v[162:165], v[208:211], v[68:71]
	v_mfma_f32_16x16x32_bf16 v[64:67], v[170:173], v[208:211], v[64:67]
	v_mfma_f32_16x16x32_bf16 v[108:111], v[166:169], v[188:191], v[108:111]
	v_mfma_f32_16x16x32_bf16 v[104:107], v[174:177], v[188:191], v[104:107]
	v_mfma_f32_16x16x32_bf16 v[92:95], v[166:169], v[196:199], v[92:95]
	v_mfma_f32_16x16x32_bf16 v[88:91], v[174:177], v[196:199], v[88:91]
	v_mfma_f32_16x16x32_bf16 v[76:79], v[166:169], v[204:207], v[76:79]
	v_mfma_f32_16x16x32_bf16 v[72:75], v[174:177], v[204:207], v[72:75]
	v_mfma_f32_16x16x32_bf16 v[68:71], v[166:169], v[212:215], v[68:71]
	v_mfma_f32_16x16x32_bf16 v[64:67], v[174:177], v[212:215], v[64:67]
	s_barrier
; #define G_STAGE(bufoff, gbase, voff) do { _Pragma("unroll") for (int _i = 0; _i < 2; ++_i) \
;         __builtin_amdgcn_global_load_lds((const unsigned*)((const char*)(gbase) + voff[_i]), (LAS unsigned*)(lds + (bufoff) + ldsw + _i * 8192), 16, 0, 0); } while (0)
; #define G_LDA(dst, b, h) do { _Pragma("unroll") for (int m = 0; m < 4; ++m) _Pragma("unroll") for (int k = 0; k < 2; ++k) dst[m][k] = *(const LAS bf16x8*)(lds + G_SA(b, h) + aoff + m * 2048 + k * 1024); } while (0)
; #define G_LDB(dst, b, h) do { _Pragma("unroll") for (int n = 0; n < 2; ++n) _Pragma("unroll") for (int k = 0; k < 2; ++k) dst[n][k] = *(const LAS bf16x8*)(lds + G_SB(b, h) + boff + n * 2048 + k * 1024); } while (0)
; #define WAIT_V(n) asm volatile("s_waitcnt vmcnt(" #n ")" ::: "memory")
; #define WAIT_L(n) asm volatile("s_waitcnt lgkmcnt(" #n ")" ::: "memory")
; #define BAR __builtin_amdgcn_s_barrier()
; #define SCHED __builtin_amdgcn_sched_barrier(0)
; template <class Get, class Epi>
; DI void gemm_loop(int ntiles, int ld, char* shm, const Get& get, const Epi& epi) {
;     ...
;         for (int t = 0; t < nt; t += 2) {
;             const bool last = (t == nt - 2);
;             const char* a1 = cA + (size_t)(t + 1) * kstep;
;             const char* a2 = last ? nA : cA + (size_t)(t + 2) * kstep; const char* b2 = last ? nB : cB + (size_t)(t + 2) * kstep;
;             const char* a3 = a2 + kstep; const char* b3 = b2 + kstep;
;             G_LDB(B0, 0, 0); G_LDB(B1, 0, 1); SCHED; G_LDA(At, 0, 0); G_STAGE(G_SA(1, 1), a1 + hstep, voffA);
;             WAIT_V(8); WAIT_L(0); BAR; G_MMA(0, 0, At, B0); G_MMA(0, 1, At, B1); BAR; SCHED;
;             G_LDA(At, 0, 1); G_STAGE(G_SB(0, 0), b2, voffB); G_STAGE(G_SB(0, 1), b2 + hstep, voffB); G_STAGE(G_SA(0, 0), a2, voffA);
;             WAIT_V(8); WAIT_L(0); BAR; G_MMA(1, 0, At, B0); G_MMA(1, 1, At, B1); BAR; SCHED;
;             G_LDB(B0, 1, 0); G_LDB(B1, 1, 1); SCHED; G_LDA(At, 1, 0); G_STAGE(G_SA(0, 1), a2 + hstep, voffA);
;             WAIT_V(8); WAIT_L(0); BAR; G_MMA(0, 0, At, B0); G_MMA(0, 1, At, B1); BAR; SCHED;
;             G_LDA(At, 1, 1); G_STAGE(G_SB(1, 0), b3, voffB); G_STAGE(G_SB(1, 1), b3 + hstep, voffB); G_STAGE(G_SA(1, 0), a3, voffA);
;             WAIT_V(8); WAIT_L(0); BAR; G_MMA(1, 0, At, B0); G_MMA(1, 1, At, B1); BAR; SCHED;
	s_mov_b32 m0, s58
	v_lshl_add_u64 v[182:183], v[182:183], 0, s[12:13]
	s_add_u32 s14, s14, 0x20080
	ds_read_b128 v[178:181], v142 offset:49152
	ds_read_b128 v[188:191], v142 offset:50176
	ds_read_b128 v[192:195], v142 offset:51200
	ds_read_b128 v[196:199], v142 offset:52224
	ds_read_b128 v[200:203], v142 offset:53248
	ds_read_b128 v[204:207], v142 offset:54272
	ds_read_b128 v[208:211], v142 offset:55296
	ds_read_b128 v[212:215], v142 offset:56320
	global_load_lds_dwordx4 v[182:183], off
	v_lshl_add_u64 v[182:183], v[184:185], 0, s[12:13]
	s_mov_b32 m0, s59
	s_addc_u32 s15, s15, 0
	global_load_lds_dwordx4 v[182:183], off
	v_lshl_add_u64 v[182:183], s[14:15], 0, v[132:133]
	s_mov_b32 m0, s72
	s_nop 0
	global_load_lds_dwordx4 v[182:183], off
	v_lshl_add_u64 v[182:183], s[14:15], 0, v[128:129]
	s_mov_b32 m0, s73
	s_nop 0
	global_load_lds_dwordx4 v[182:183], off
	v_lshl_add_u64 v[182:183], v[186:187], 0, s[12:13]
	s_mov_b32 m0, s46
	s_nop 0
	global_load_lds_dwordx4 v[182:183], off
	v_lshl_add_u64 v[182:183], v[216:217], 0, s[12:13]
	s_mov_b32 m0, s47
	s_nop 0
	global_load_lds_dwordx4 v[182:183], off
	s_waitcnt vmcnt(8)
	s_waitcnt lgkmcnt(0)
	s_barrier
	s_waitcnt lgkmcnt(0)
	v_mfma_f32_16x16x32_bf16 v[60:63], v[146:149], v[178:181], v[60:63]
	v_mfma_f32_16x16x32_bf16 v[56:59], v[154:157], v[178:181], v[56:59]
	v_mfma_f32_16x16x32_bf16 v[52:55], v[146:149], v[192:195], v[52:55]
	v_mfma_f32_16x16x32_bf16 v[48:51], v[154:157], v[192:195], v[48:51]
	v_mfma_f32_16x16x32_bf16 v[36:39], v[146:149], v[200:203], v[36:39]
	v_mfma_f32_16x16x32_bf16 v[32:35], v[154:157], v[200:203], v[32:35]
	v_mfma_f32_16x16x32_bf16 v[20:23], v[146:149], v[208:211], v[20:23]
	v_mfma_f32_16x16x32_bf16 v[16:19], v[154:157], v[208:211], v[16:19]
	v_mfma_f32_16x16x32_bf16 v[60:63], v[150:153], v[188:191], v[60:63]
	v_mfma_f32_16x16x32_bf16 v[56:59], v[158:161], v[188:191], v[56:59]
	v_mfma_f32_16x16x32_bf16 v[52:55], v[150:153], v[196:199], v[52:55]
	v_mfma_f32_16x16x32_bf16 v[48:51], v[158:161], v[196:199], v[48:51]
	v_mfma_f32_16x16x32_bf16 v[36:39], v[150:153], v[204:207], v[36:39]
	v_mfma_f32_16x16x32_bf16 v[32:35], v[158:161], v[204:207], v[32:35]
	v_mfma_f32_16x16x32_bf16 v[20:23], v[150:153], v[212:215], v[20:23]
	v_mfma_f32_16x16x32_bf16 v[16:19], v[158:161], v[212:215], v[16:19]
	v_mfma_f32_16x16x32_bf16 v[44:47], v[162:165], v[178:181], v[44:47]
	v_mfma_f32_16x16x32_bf16 v[40:43], v[170:173], v[178:181], v[40:43]
	v_mfma_f32_16x16x32_bf16 v[28:31], v[162:165], v[192:195], v[28:31]
	v_mfma_f32_16x16x32_bf16 v[24:27], v[170:173], v[192:195], v[24:27]
	v_mfma_f32_16x16x32_bf16 v[12:15], v[162:165], v[200:203], v[12:15]
	v_mfma_f32_16x16x32_bf16 v[8:11], v[170:173], v[200:203], v[8:11]
	v_mfma_f32_16x16x32_bf16 v[4:7], v[162:165], v[208:211], v[4:7]
	v_mfma_f32_16x16x32_bf16 v[0:3], v[170:173], v[208:211], v[0:3]
	v_mfma_f32_16x16x32_bf16 v[44:47], v[166:169], v[188:191], v[44:47]
	v_mfma_f32_16x16x32_bf16 v[40:43], v[174:177], v[188:191], v[40:43]
	v_mfma_f32_16x16x32_bf16 v[28:31], v[166:169], v[196:199], v[28:31]
	v_mfma_f32_16x16x32_bf16 v[24:27], v[174:177], v[196:199], v[24:27]
	v_mfma_f32_16x16x32_bf16 v[12:15], v[166:169], v[204:207], v[12:15]
	v_mfma_f32_16x16x32_bf16 v[8:11], v[174:177], v[204:207], v[8:11]
	v_mfma_f32_16x16x32_bf16 v[4:7], v[166:169], v[212:215], v[4:7]
	v_mfma_f32_16x16x32_bf16 v[0:3], v[174:177], v[212:215], v[0:3]
	s_barrier
	s_add_i32 s81, s81, 2
	s_add_u32 s36, s36, 0x100
	s_addc_u32 s37, s37, 0
	s_add_u32 s79, s79, 0x100
	s_addc_u32 s80, s80, 0
	s_cmp_gt_u32 s81, 5
	s_cbranch_scc0 .LBB0_445
	s_branch .Lpost_445
.LBB0_445:
	ds_read_b128 v[146:149], v140
	ds_read_b128 v[150:153], v140 offset:1024
	ds_read_b128 v[154:157], v140 offset:2048
	ds_read_b128 v[158:161], v140 offset:3072
	ds_read_b128 v[162:165], v141
	ds_read_b128 v[166:169], v141 offset:1024
	ds_read_b128 v[170:173], v141 offset:2048
	ds_read_b128 v[174:177], v141 offset:3072
	s_add_u32 s14, s36, 0xfffe0080
	s_addc_u32 s15, s37, -1
	s_cmp_eq_u32 s81, 4
	s_cselect_b32 s39, s3, s15
	s_cselect_b32 s38, s2, s14
	s_cselect_b32 s15, s76, s80
	s_cselect_b32 s14, s78, s79
	s_mov_b32 m0, s50
	v_lshl_add_u64 v[182:183], s[36:37], 0, v[136:137]
	ds_read_b128 v[178:181], v142
	ds_read_b128 v[188:191], v142 offset:1024
	ds_read_b128 v[192:195], v142 offset:2048
	ds_read_b128 v[196:199], v142 offset:3072
	ds_read_b128 v[200:203], v142 offset:4096
	ds_read_b128 v[204:207], v142 offset:5120
	ds_read_b128 v[208:211], v142 offset:6144
	ds_read_b128 v[212:215], v142 offset:7168
	global_load_lds_dwordx4 v[182:183], off
	v_lshl_add_u64 v[182:183], s[36:37], 0, v[138:139]
	s_mov_b32 m0, s51
	s_nop 0
	global_load_lds_dwordx4 v[182:183], off
	s_waitcnt vmcnt(8)
	s_waitcnt lgkmcnt(0)
	s_barrier
; #define G_STAGE(bufoff, gbase, voff) do { _Pragma("unroll") for (int _i = 0; _i < 2; ++_i) \
;         __builtin_amdgcn_global_load_lds((const unsigned*)((const char*)(gbase) + voff[_i]), (LAS unsigned*)(lds + (bufoff) + ldsw + _i * 8192), 16, 0, 0); } while (0)
; #define G_LDA(dst, b, h) do { _Pragma("unroll") for (int m = 0; m < 4; ++m) _Pragma("unroll") for (int k = 0; k < 2; ++k) dst[m][k] = *(const LAS bf16x8*)(lds + G_SA(b, h) + aoff + m * 2048 + k * 1024); } while (0)
; #define G_LDB(dst, b, h) do { _Pragma("unroll") for (int n = 0; n < 2; ++n) _Pragma("unroll") for (int k = 0; k < 2; ++k) dst[n][k] = *(const LAS bf16x8*)(lds + G_SB(b, h) + boff + n * 2048 + k * 1024); } while (0)
; #define WAIT_V(n) asm volatile("s_waitcnt vmcnt(" #n ")" ::: "memory")
; #define WAIT_L(n) asm volatile("s_waitcnt lgkmcnt(" #n ")" ::: "memory")
; #define BAR __builtin_amdgcn_s_barrier()
; #define SCHED __builtin_amdgcn_sched_barrier(0)
; template <class Get, class Epi>
; DI void gemm_loop(int ntiles, int ld, char* shm, const Get& get, const Epi& epi) {
;     ...
;         for (int t = 0; t < nt; t += 2) {
;             const bool last = (t == nt - 2);
;             const char* a1 = cA + (size_t)(t + 1) * kstep;
;             const char* a2 = last ? nA : cA + (size_t)(t + 2) * kstep; const char* b2 = last ? nB : cB + (size_t)(t + 2) * kstep;
;             const char* a3 = a2 + kstep; const char* b3 = b2 + kstep;
;             G_LDB(B0, 0, 0); G_LDB(B1, 0, 1); SCHED; G_LDA(At, 0, 0); G_STAGE(G_SA(1, 1), a1 + hstep, voffA);
;             WAIT_V(8); WAIT_L(0); BAR; G_MMA(0, 0, At, B0); G_MMA(0, 1, At, B1); BAR; SCHED;
;             G_LDA(At, 0, 1); G_STAGE(G_SB(0, 0), b2, voffB); G_STAGE(G_SB(0, 1), b2 + hstep, voffB); G_STAGE(G_SA(0, 0), a2, voffA);
;             WAIT_V(8); WAIT_L(0); BAR; G_MMA(1, 0, At, B0); G_MMA(1, 1, At, B1); BAR; SCHED;
;             G_LDB(B0, 1, 0); G_LDB(B1, 1, 1); SCHED; G_LDA(At, 1, 0); G_STAGE(G_SA(0, 1), a2 + hstep, voffA);
;             WAIT_V(8); WAIT_L(0); BAR; G_MMA(0, 0, At, B0); G_MMA(0, 1, At, B1); BAR; SCHED;
;             G_LDA(At, 1, 1); G_STAGE(G_SB(1, 0), b3, voffB); G_STAGE(G_SB(1, 1), b3 + hstep, voffB); G_STAGE(G_SA(1, 0), a3, voffA);
;             WAIT_V(8); WAIT_L(0); BAR; G_MMA(1, 0, At, B0); G_MMA(1, 1, At, B1); BAR; SCHED;
	s_waitcnt lgkmcnt(0)
	v_mfma_f32_16x16x32_bf16 v[124:127], v[146:149], v[178:181], v[124:127]
	v_mfma_f32_16x16x32_bf16 v[120:123], v[154:157], v[178:181], v[120:123]
	v_mfma_f32_16x16x32_bf16 v[116:119], v[146:149], v[192:195], v[116:119]
	v_mfma_f32_16x16x32_bf16 v[112:115], v[154:157], v[192:195], v[112:115]
	v_mfma_f32_16x16x32_bf16 v[100:103], v[146:149], v[200:203], v[100:103]
	v_mfma_f32_16x16x32_bf16 v[96:99], v[154:157], v[200:203], v[96:99]
	v_mfma_f32_16x16x32_bf16 v[84:87], v[146:149], v[208:211], v[84:87]
	v_mfma_f32_16x16x32_bf16 v[80:83], v[154:157], v[208:211], v[80:83]
	v_mfma_f32_16x16x32_bf16 v[124:127], v[150:153], v[188:191], v[124:127]
	v_mfma_f32_16x16x32_bf16 v[120:123], v[158:161], v[188:191], v[120:123]
	v_mfma_f32_16x16x32_bf16 v[116:119], v[150:153], v[196:199], v[116:119]
	v_mfma_f32_16x16x32_bf16 v[112:115], v[158:161], v[196:199], v[112:115]
	v_mfma_f32_16x16x32_bf16 v[100:103], v[150:153], v[204:207], v[100:103]
	v_mfma_f32_16x16x32_bf16 v[96:99], v[158:161], v[204:207], v[96:99]
	v_mfma_f32_16x16x32_bf16 v[84:87], v[150:153], v[212:215], v[84:87]
	v_mfma_f32_16x16x32_bf16 v[80:83], v[158:161], v[212:215], v[80:83]
	v_mfma_f32_16x16x32_bf16 v[108:111], v[162:165], v[178:181], v[108:111]
	v_mfma_f32_16x16x32_bf16 v[104:107], v[170:173], v[178:181], v[104:107]
	v_mfma_f32_16x16x32_bf16 v[92:95], v[162:165], v[192:195], v[92:95]
	v_mfma_f32_16x16x32_bf16 v[88:91], v[170:173], v[192:195], v[88:91]
	v_mfma_f32_16x16x32_bf16 v[76:79], v[162:165], v[200:203], v[76:79]
	v_mfma_f32_16x16x32_bf16 v[72:75], v[170:173], v[200:203], v[72:75]
	v_mfma_f32_16x16x32_bf16 v[68:71], v[162:165], v[208:211], v[68:71]
	v_mfma_f32_16x16x32_bf16 v[64:67], v[170:173], v[208:211], v[64:67]
	v_mfma_f32_16x16x32_bf16 v[108:111], v[166:169], v[188:191], v[108:111]
	v_mfma_f32_16x16x32_bf16 v[104:107], v[174:177], v[188:191], v[104:107]
	v_mfma_f32_16x16x32_bf16 v[92:95], v[166:169], v[196:199], v[92:95]
	v_mfma_f32_16x16x32_bf16 v[88:91], v[174:177], v[196:199], v[88:91]
	v_mfma_f32_16x16x32_bf16 v[76:79], v[166:169], v[204:207], v[76:79]
	v_mfma_f32_16x16x32_bf16 v[72:75], v[174:177], v[204:207], v[72:75]
	v_mfma_f32_16x16x32_bf16 v[68:71], v[166:169], v[212:215], v[68:71]
	v_mfma_f32_16x16x32_bf16 v[64:67], v[174:177], v[212:215], v[64:67]
	s_barrier
	s_mov_b32 m0, s54
	v_lshl_add_u64 v[182:183], s[14:15], 0, v[132:133]
	s_add_u32 s82, s14, 0x20000
	ds_read_b128 v[178:181], v142 offset:16384
	ds_read_b128 v[188:191], v142 offset:17408
	ds_read_b128 v[192:195], v142 offset:18432
	ds_read_b128 v[196:199], v142 offset:19456
	ds_read_b128 v[200:203], v142 offset:20480
	ds_read_b128 v[204:207], v142 offset:21504
	ds_read_b128 v[208:211], v142 offset:22528
	ds_read_b128 v[212:215], v142 offset:23552
	global_load_lds_dwordx4 v[182:183], off
	v_lshl_add_u64 v[184:185], s[14:15], 0, v[128:129]
	s_mov_b32 m0, s55
	s_addc_u32 s83, s15, 0
	global_load_lds_dwordx4 v[184:185], off
	v_lshl_add_u64 v[186:187], s[82:83], 0, v[132:133]
	s_mov_b32 m0, s56
	v_lshl_add_u64 v[216:217], s[38:39], 0, v[130:131]
	global_load_lds_dwordx4 v[186:187], off
	v_lshl_add_u64 v[186:187], s[82:83], 0, v[128:129]
	s_mov_b32 m0, s57
	s_nop 0
	global_load_lds_dwordx4 v[186:187], off
	v_lshl_add_u64 v[186:187], s[38:39], 0, v[134:135]
	s_mov_b32 m0, s41
	s_nop 0
	global_load_lds_dwordx4 v[186:187], off
	s_mov_b32 m0, s43
	s_nop 0
	global_load_lds_dwordx4 v[216:217], off
	s_waitcnt vmcnt(8)
	s_waitcnt lgkmcnt(0)
	s_barrier
	s_waitcnt lgkmcnt(0)
	v_mfma_f32_16x16x32_bf16 v[60:63], v[146:149], v[178:181], v[60:63]
	v_mfma_f32_16x16x32_bf16 v[56:59], v[154:157], v[178:181], v[56:59]
	v_mfma_f32_16x16x32_bf16 v[52:55], v[146:149], v[192:195], v[52:55]
	v_mfma_f32_16x16x32_bf16 v[48:51], v[154:157], v[192:195], v[48:51]
	v_mfma_f32_16x16x32_bf16 v[36:39], v[146:149], v[200:203], v[36:39]
	v_mfma_f32_16x16x32_bf16 v[32:35], v[154:157], v[200:203], v[32:35]
	v_mfma_f32_16x16x32_bf16 v[20:23], v[146:149], v[208:211], v[20:23]
	v_mfma_f32_16x16x32_bf16 v[16:19], v[154:157], v[208:211], v[16:19]
	v_mfma_f32_16x16x32_bf16 v[60:63], v[150:153], v[188:191], v[60:63]
	v_mfma_f32_16x16x32_bf16 v[56:59], v[158:161], v[188:191], v[56:59]
	v_mfma_f32_16x16x32_bf16 v[52:55], v[150:153], v[196:199], v[52:55]
	v_mfma_f32_16x16x32_bf16 v[48:51], v[158:161], v[196:199], v[48:51]
	v_mfma_f32_16x16x32_bf16 v[36:39], v[150:153], v[204:207], v[36:39]
	v_mfma_f32_16x16x32_bf16 v[32:35], v[158:161], v[204:207], v[32:35]
	v_mfma_f32_16x16x32_bf16 v[20:23], v[150:153], v[212:215], v[20:23]
	v_mfma_f32_16x16x32_bf16 v[16:19], v[158:161], v[212:215], v[16:19]
	v_mfma_f32_16x16x32_bf16 v[44:47], v[162:165], v[178:181], v[44:47]
	v_mfma_f32_16x16x32_bf16 v[40:43], v[170:173], v[178:181], v[40:43]
	v_mfma_f32_16x16x32_bf16 v[28:31], v[162:165], v[192:195], v[28:31]
	v_mfma_f32_16x16x32_bf16 v[24:27], v[170:173], v[192:195], v[24:27]
	v_mfma_f32_16x16x32_bf16 v[12:15], v[162:165], v[200:203], v[12:15]
	v_mfma_f32_16x16x32_bf16 v[8:11], v[170:173], v[200:203], v[8:11]
	v_mfma_f32_16x16x32_bf16 v[4:7], v[162:165], v[208:211], v[4:7]
	v_mfma_f32_16x16x32_bf16 v[0:3], v[170:173], v[208:211], v[0:3]
	v_mfma_f32_16x16x32_bf16 v[44:47], v[166:169], v[188:191], v[44:47]
	v_mfma_f32_16x16x32_bf16 v[40:43], v[174:177], v[188:191], v[40:43]
	v_mfma_f32_16x16x32_bf16 v[28:31], v[166:169], v[196:199], v[28:31]
	v_mfma_f32_16x16x32_bf16 v[24:27], v[174:177], v[196:199], v[24:27]
	v_mfma_f32_16x16x32_bf16 v[12:15], v[166:169], v[204:207], v[12:15]
	v_mfma_f32_16x16x32_bf16 v[8:11], v[174:177], v[204:207], v[8:11]
	v_mfma_f32_16x16x32_bf16 v[4:7], v[166:169], v[212:215], v[4:7]
	v_mfma_f32_16x16x32_bf16 v[0:3], v[174:177], v[212:215], v[0:3]
	s_barrier
; #define G_STAGE(bufoff, gbase, voff) do { _Pragma("unroll") for (int _i = 0; _i < 2; ++_i) \
;         __builtin_amdgcn_global_load_lds((const unsigned*)((const char*)(gbase) + voff[_i]), (LAS unsigned*)(lds + (bufoff) + ldsw + _i * 8192), 16, 0, 0); } while (0)
; #define G_LDA(dst, b, h) do { _Pragma("unroll") for (int m = 0; m < 4; ++m) _Pragma("unroll") for (int k = 0; k < 2; ++k) dst[m][k] = *(const LAS bf16x8*)(lds + G_SA(b, h) + aoff + m * 2048 + k * 1024); } while (0)
; #define G_LDB(dst, b, h) do { _Pragma("unroll") for (int n = 0; n < 2; ++n) _Pragma("unroll") for (int k = 0; k < 2; ++k) dst[n][k] = *(const LAS bf16x8*)(lds + G_SB(b, h) + boff + n * 2048 + k * 1024); } while (0)
; #define WAIT_V(n) asm volatile("s_waitcnt vmcnt(" #n ")" ::: "memory")
; #define WAIT_L(n) asm volatile("s_waitcnt lgkmcnt(" #n ")" ::: "memory")
; #define BAR __builtin_amdgcn_s_barrier()
; #define SCHED __builtin_amdgcn_sched_barrier(0)
; template <class Get, class Epi>
; DI void gemm_loop(int ntiles, int ld, char* shm, const Get& get, const Epi& epi) {
;     ...
;         for (int t = 0; t < nt; t += 2) {
;             const bool last = (t == nt - 2);
;             const char* a1 = cA + (size_t)(t + 1) * kstep;
;             const char* a2 = last ? nA : cA + (size_t)(t + 2) * kstep; const char* b2 = last ? nB : cB + (size_t)(t + 2) * kstep;
;             const char* a3 = a2 + kstep; const char* b3 = b2 + kstep;
;             G_LDB(B0, 0, 0); G_LDB(B1, 0, 1); SCHED; G_LDA(At, 0, 0); G_STAGE(G_SA(1, 1), a1 + hstep, voffA);
;             WAIT_V(8); WAIT_L(0); BAR; G_MMA(0, 0, At, B0); G_MMA(0, 1, At, B1); BAR; SCHED;
;             G_LDA(At, 0, 1); G_STAGE(G_SB(0, 0), b2, voffB); G_STAGE(G_SB(0, 1), b2 + hstep, voffB); G_STAGE(G_SA(0, 0), a2, voffA);
;             WAIT_V(8); WAIT_L(0); BAR; G_MMA(1, 0, At, B0); G_MMA(1, 1, At, B1); BAR; SCHED;
;             G_LDB(B0, 1, 0); G_LDB(B1, 1, 1); SCHED; G_LDA(At, 1, 0); G_STAGE(G_SA(0, 1), a2 + hstep, voffA);
;             WAIT_V(8); WAIT_L(0); BAR; G_MMA(0, 0, At, B0); G_MMA(0, 1, At, B1); BAR; SCHED;
;             G_LDA(At, 1, 1); G_STAGE(G_SB(1, 0), b3, voffB); G_STAGE(G_SB(1, 1), b3 + hstep, voffB); G_STAGE(G_SA(1, 0), a3, voffA);
;             WAIT_V(8); WAIT_L(0); BAR; G_MMA(1, 0, At, B0); G_MMA(1, 1, At, B1); BAR; SCHED;
	ds_read_b128 v[146:149], v143
	ds_read_b128 v[150:153], v143 offset:1024
	ds_read_b128 v[154:157], v143 offset:2048
	ds_read_b128 v[158:161], v143 offset:3072
	ds_read_b128 v[162:165], v144
	ds_read_b128 v[166:169], v144 offset:1024
	ds_read_b128 v[170:173], v144 offset:2048
	ds_read_b128 v[174:177], v144 offset:3072
	s_add_u32 s38, s38, 0x20000
	s_addc_u32 s39, s39, 0
	s_mov_b32 m0, s44
	v_lshl_add_u64 v[218:219], s[38:39], 0, v[134:135]
	ds_read_b128 v[178:181], v142 offset:32768
	ds_read_b128 v[188:191], v142 offset:33792
	ds_read_b128 v[192:195], v142 offset:34816
	ds_read_b128 v[196:199], v142 offset:35840
	ds_read_b128 v[200:203], v142 offset:36864
	ds_read_b128 v[204:207], v142 offset:37888
	ds_read_b128 v[208:211], v142 offset:38912
	ds_read_b128 v[212:215], v142 offset:39936
	global_load_lds_dwordx4 v[218:219], off
	v_lshl_add_u64 v[218:219], s[38:39], 0, v[130:131]
	s_mov_b32 m0, s45
	s_nop 0
	global_load_lds_dwordx4 v[218:219], off
	s_waitcnt vmcnt(8)
	s_waitcnt lgkmcnt(0)
	s_barrier
	s_waitcnt lgkmcnt(0)
	v_mfma_f32_16x16x32_bf16 v[124:127], v[146:149], v[178:181], v[124:127]
	v_mfma_f32_16x16x32_bf16 v[120:123], v[154:157], v[178:181], v[120:123]
	v_mfma_f32_16x16x32_bf16 v[116:119], v[146:149], v[192:195], v[116:119]
	v_mfma_f32_16x16x32_bf16 v[112:115], v[154:157], v[192:195], v[112:115]
	v_mfma_f32_16x16x32_bf16 v[100:103], v[146:149], v[200:203], v[100:103]
	v_mfma_f32_16x16x32_bf16 v[96:99], v[154:157], v[200:203], v[96:99]
	v_mfma_f32_16x16x32_bf16 v[84:87], v[146:149], v[208:211], v[84:87]
	v_mfma_f32_16x16x32_bf16 v[80:83], v[154:157], v[208:211], v[80:83]
	v_mfma_f32_16x16x32_bf16 v[124:127], v[150:153], v[188:191], v[124:127]
	v_mfma_f32_16x16x32_bf16 v[120:123], v[158:161], v[188:191], v[120:123]
	v_mfma_f32_16x16x32_bf16 v[116:119], v[150:153], v[196:199], v[116:119]
	v_mfma_f32_16x16x32_bf16 v[112:115], v[158:161], v[196:199], v[112:115]
	v_mfma_f32_16x16x32_bf16 v[100:103], v[150:153], v[204:207], v[100:103]
	v_mfma_f32_16x16x32_bf16 v[96:99], v[158:161], v[204:207], v[96:99]
	v_mfma_f32_16x16x32_bf16 v[84:87], v[150:153], v[212:215], v[84:87]
	v_mfma_f32_16x16x32_bf16 v[80:83], v[158:161], v[212:215], v[80:83]
	v_mfma_f32_16x16x32_bf16 v[108:111], v[162:165], v[178:181], v[108:111]
	v_mfma_f32_16x16x32_bf16 v[104:107], v[170:173], v[178:181], v[104:107]
	v_mfma_f32_16x16x32_bf16 v[92:95], v[162:165], v[192:195], v[92:95]
	v_mfma_f32_16x16x32_bf16 v[88:91], v[170:173], v[192:195], v[88:91]
	v_mfma_f32_16x16x32_bf16 v[76:79], v[162:165], v[200:203], v[76:79]
	v_mfma_f32_16x16x32_bf16 v[72:75], v[170:173], v[200:203], v[72:75]
	v_mfma_f32_16x16x32_bf16 v[68:71], v[162:165], v[208:211], v[68:71]
	v_mfma_f32_16x16x32_bf16 v[64:67], v[170:173], v[208:211], v[64:67]
	v_mfma_f32_16x16x32_bf16 v[108:111], v[166:169], v[188:191], v[108:111]
	v_mfma_f32_16x16x32_bf16 v[104:107], v[174:177], v[188:191], v[104:107]
	v_mfma_f32_16x16x32_bf16 v[92:95], v[166:169], v[196:199], v[92:95]
	v_mfma_f32_16x16x32_bf16 v[88:91], v[174:177], v[196:199], v[88:91]
	v_mfma_f32_16x16x32_bf16 v[76:79], v[166:169], v[204:207], v[76:79]
	v_mfma_f32_16x16x32_bf16 v[72:75], v[174:177], v[204:207], v[72:75]
	v_mfma_f32_16x16x32_bf16 v[68:71], v[166:169], v[212:215], v[68:71]
	v_mfma_f32_16x16x32_bf16 v[64:67], v[174:177], v[212:215], v[64:67]
	s_barrier
	s_mov_b32 m0, s58
	v_lshl_add_u64 v[182:183], v[182:183], 0, s[12:13]
	s_add_u32 s14, s14, 0x20080
	ds_read_b128 v[178:181], v142 offset:49152
	ds_read_b128 v[188:191], v142 offset:50176
	ds_read_b128 v[192:195], v142 offset:51200
	ds_read_b128 v[196:199], v142 offset:52224
	ds_read_b128 v[200:203], v142 offset:53248
	ds_read_b128 v[204:207], v142 offset:54272
	ds_read_b128 v[208:211], v142 offset:55296
	ds_read_b128 v[212:215], v142 offset:56320
	global_load_lds_dwordx4 v[182:183], off
	v_lshl_add_u64 v[182:183], v[184:185], 0, s[12:13]
	s_mov_b32 m0, s59
	s_addc_u32 s15, s15, 0
	global_load_lds_dwordx4 v[182:183], off
	v_lshl_add_u64 v[182:183], s[14:15], 0, v[132:133]
	s_mov_b32 m0, s72
	s_nop 0
	global_load_lds_dwordx4 v[182:183], off
	v_lshl_add_u64 v[182:183], s[14:15], 0, v[128:129]
	s_mov_b32 m0, s73
	s_nop 0
	global_load_lds_dwordx4 v[182:183], off
	v_lshl_add_u64 v[182:183], v[186:187], 0, s[12:13]
	s_mov_b32 m0, s46
	s_nop 0
	global_load_lds_dwordx4 v[182:183], off
	v_lshl_add_u64 v[182:183], v[216:217], 0, s[12:13]
	s_mov_b32 m0, s47
	s_nop 0
	global_load_lds_dwordx4 v[182:183], off
	s_waitcnt vmcnt(8)
	s_waitcnt lgkmcnt(0)
	s_barrier
	s_waitcnt lgkmcnt(0)
	v_mfma_f32_16x16x32_bf16 v[60:63], v[146:149], v[178:181], v[60:63]
	v_mfma_f32_16x16x32_bf16 v[56:59], v[154:157], v[178:181], v[56:59]
	v_mfma_f32_16x16x32_bf16 v[52:55], v[146:149], v[192:195], v[52:55]
	v_mfma_f32_16x16x32_bf16 v[48:51], v[154:157], v[192:195], v[48:51]
	v_mfma_f32_16x16x32_bf16 v[36:39], v[146:149], v[200:203], v[36:39]
	v_mfma_f32_16x16x32_bf16 v[32:35], v[154:157], v[200:203], v[32:35]
	v_mfma_f32_16x16x32_bf16 v[20:23], v[146:149], v[208:211], v[20:23]
	v_mfma_f32_16x16x32_bf16 v[16:19], v[154:157], v[208:211], v[16:19]
	v_mfma_f32_16x16x32_bf16 v[60:63], v[150:153], v[188:191], v[60:63]
	v_mfma_f32_16x16x32_bf16 v[56:59], v[158:161], v[188:191], v[56:59]
	v_mfma_f32_16x16x32_bf16 v[52:55], v[150:153], v[196:199], v[52:55]
	v_mfma_f32_16x16x32_bf16 v[48:51], v[158:161], v[196:199], v[48:51]
	v_mfma_f32_16x16x32_bf16 v[36:39], v[150:153], v[204:207], v[36:39]
	v_mfma_f32_16x16x32_bf16 v[32:35], v[158:161], v[204:207], v[32:35]
	v_mfma_f32_16x16x32_bf16 v[20:23], v[150:153], v[212:215], v[20:23]
	v_mfma_f32_16x16x32_bf16 v[16:19], v[158:161], v[212:215], v[16:19]
	v_mfma_f32_16x16x32_bf16 v[44:47], v[162:165], v[178:181], v[44:47]
	v_mfma_f32_16x16x32_bf16 v[40:43], v[170:173], v[178:181], v[40:43]
	v_mfma_f32_16x16x32_bf16 v[28:31], v[162:165], v[192:195], v[28:31]
	v_mfma_f32_16x16x32_bf16 v[24:27], v[170:173], v[192:195], v[24:27]
	v_mfma_f32_16x16x32_bf16 v[12:15], v[162:165], v[200:203], v[12:15]
	v_mfma_f32_16x16x32_bf16 v[8:11], v[170:173], v[200:203], v[8:11]
	v_mfma_f32_16x16x32_bf16 v[4:7], v[162:165], v[208:211], v[4:7]
	v_mfma_f32_16x16x32_bf16 v[0:3], v[170:173], v[208:211], v[0:3]
	v_mfma_f32_16x16x32_bf16 v[44:47], v[166:169], v[188:191], v[44:47]
	v_mfma_f32_16x16x32_bf16 v[40:43], v[174:177], v[188:191], v[40:43]
	v_mfma_f32_16x16x32_bf16 v[28:31], v[166:169], v[196:199], v[28:31]
	v_mfma_f32_16x16x32_bf16 v[24:27], v[174:177], v[196:199], v[24:27]
	v_mfma_f32_16x16x32_bf16 v[12:15], v[166:169], v[204:207], v[12:15]
	v_mfma_f32_16x16x32_bf16 v[8:11], v[174:177], v[204:207], v[8:11]
	v_mfma_f32_16x16x32_bf16 v[4:7], v[166:169], v[212:215], v[4:7]
	v_mfma_f32_16x16x32_bf16 v[0:3], v[174:177], v[212:215], v[0:3]
	s_barrier
	s_add_i32 s81, s81, 2
	s_add_u32 s36, s36, 0x100
	s_addc_u32 s37, s37, 0
	s_add_u32 s79, s79, 0x100
	s_addc_u32 s80, s80, 0
	s_cmp_gt_u32 s81, 5
	s_cbranch_scc0 .LBB0_445

; #define G_STAGE(bufoff, gbase, voff) do { _Pragma("unroll") for (int _i = 0; _i < 2; ++_i) \
;         __builtin_amdgcn_global_load_lds((const unsigned*)((const char*)(gbase) + voff[_i]), (LAS unsigned*)(lds + (bufoff) + ldsw + _i * 8192), 16, 0, 0); } while (0)
; #define G_LDA(dst, b, h) do { _Pragma("unroll") for (int m = 0; m < 4; ++m) _Pragma("unroll") for (int k = 0; k < 2; ++k) dst[m][k] = *(const LAS bf16x8*)(lds + G_SA(b, h) + aoff + m * 2048 + k * 1024); } while (0)
; #define G_LDB(dst, b, h) do { _Pragma("unroll") for (int n = 0; n < 2; ++n) _Pragma("unroll") for (int k = 0; k < 2; ++k) dst[n][k] = *(const LAS bf16x8*)(lds + G_SB(b, h) + boff + n * 2048 + k * 1024); } while (0)
; template <class Get, class Epi>
; DI void gemm_loop(int ntiles, int ld, char* shm, const Get& get, const Epi& epi) {
;     ...
;     for (;;) {
;         const int Ln = L + gridDim.x; const bool has_next = Ln < ntiles; if (has_next) nxt = get(Ln);
;         const char* nA = has_next ? (const char*)nxt.A + (size_t)nxt.brow * ld * 2 : cA; const char* nB = has_next ? (const char*)nxt.Bt + (size_t)nxt.bcol * ld * 2 : cB;
;         const int nt = cur.K / BK;
;         for (int t = 0; t < nt; t += 2) {
;             const bool last = (t == nt - 2);
;             const char* a1 = cA + (size_t)(t + 1) * kstep;
;             const char* a2 = last ? nA : cA + (size_t)(t + 2) * kstep; const char* b2 = last ? nB : cB + (size_t)(t + 2) * kstep;
;             const char* a3 = a2 + kstep; const char* b3 = b2 + kstep;
;             G_LDB(B0, 0, 0); G_LDB(B1, 0, 1); SCHED; G_LDA(At, 0, 0); G_STAGE(G_SA(1, 1), a1 + hstep, voffA);
;             WAIT_V(8); WAIT_L(0); BAR; G_MMA(0, 0, At, B0); G_MMA(0, 1, At, B1); BAR; SCHED;
;             G_LDA(At, 0, 1); G_STAGE(G_SB(0, 0), b2, voffB); G_STAGE(G_SB(0, 1), b2 + hstep, voffB); G_STAGE(G_SA(0, 0), a2, voffA);
;             WAIT_V(8); WAIT_L(0); BAR; G_MMA(1, 0, At, B0); G_MMA(1, 1, At, B1); BAR; SCHED;
;             G_LDB(B0, 1, 0); G_LDB(B1, 1, 1); SCHED; G_LDA(At, 1, 0); G_STAGE(G_SA(0, 1), a2 + hstep, voffA);
;             WAIT_V(8); WAIT_L(0); BAR; G_MMA(0, 0, At, B0); G_MMA(0, 1, At, B1); BAR; SCHED;
;             G_LDA(At, 1, 1); G_STAGE(G_SB(1, 0), b3, voffB); G_STAGE(G_SB(1, 1), b3 + hstep, voffB); G_STAGE(G_SA(1, 0), a3, voffA);
;             WAIT_V(8); WAIT_L(0); BAR; G_MMA(1, 0, At, B0); G_MMA(1, 1, At, B1); BAR; SCHED;
.Lrj_528_0:
	s_waitcnt lgkmcnt(0)
	s_barrier
	s_waitcnt lgkmcnt(0)
	v_mfma_f32_16x16x32_bf16 v[124:127], v[128:131], v[172:175], 0
	v_mfma_f32_16x16x32_bf16 v[120:123], v[136:139], v[172:175], 0
	v_mfma_f32_16x16x32_bf16 v[116:119], v[128:131], v[188:191], 0
	v_mfma_f32_16x16x32_bf16 v[112:115], v[136:139], v[188:191], 0
	v_mfma_f32_16x16x32_bf16 v[108:111], v[128:131], v[196:199], 0
	v_mfma_f32_16x16x32_bf16 v[104:107], v[136:139], v[196:199], 0
	v_mfma_f32_16x16x32_bf16 v[100:103], v[128:131], v[204:207], 0
	v_mfma_f32_16x16x32_bf16 v[96:99], v[136:139], v[204:207], 0
	v_mfma_f32_16x16x32_bf16 v[124:127], v[132:135], v[180:183], v[124:127]
	v_mfma_f32_16x16x32_bf16 v[120:123], v[140:143], v[180:183], v[120:123]
	v_mfma_f32_16x16x32_bf16 v[116:119], v[132:135], v[192:195], v[116:119]
	v_mfma_f32_16x16x32_bf16 v[112:115], v[140:143], v[192:195], v[112:115]
	v_mfma_f32_16x16x32_bf16 v[108:111], v[132:135], v[200:203], v[108:111]
	v_mfma_f32_16x16x32_bf16 v[104:107], v[140:143], v[200:203], v[104:107]
	v_mfma_f32_16x16x32_bf16 v[100:103], v[132:135], v[208:211], v[100:103]
	v_mfma_f32_16x16x32_bf16 v[96:99], v[140:143], v[208:211], v[96:99]
	v_mfma_f32_16x16x32_bf16 v[60:63], v[144:147], v[172:175], 0
	v_mfma_f32_16x16x32_bf16 v[56:59], v[164:167], v[172:175], 0
	v_mfma_f32_16x16x32_bf16 v[52:55], v[144:147], v[188:191], 0
	v_mfma_f32_16x16x32_bf16 v[48:51], v[164:167], v[188:191], 0
	v_mfma_f32_16x16x32_bf16 v[44:47], v[144:147], v[196:199], 0
	v_mfma_f32_16x16x32_bf16 v[40:43], v[164:167], v[196:199], 0
	v_mfma_f32_16x16x32_bf16 v[36:39], v[144:147], v[204:207], 0
	v_mfma_f32_16x16x32_bf16 v[32:35], v[164:167], v[204:207], 0
	v_mfma_f32_16x16x32_bf16 v[60:63], v[148:151], v[180:183], v[60:63]
	v_mfma_f32_16x16x32_bf16 v[56:59], v[168:171], v[180:183], v[56:59]
	v_mfma_f32_16x16x32_bf16 v[52:55], v[148:151], v[192:195], v[52:55]
	v_mfma_f32_16x16x32_bf16 v[48:51], v[168:171], v[192:195], v[48:51]
	v_mfma_f32_16x16x32_bf16 v[44:47], v[148:151], v[200:203], v[44:47]
	v_mfma_f32_16x16x32_bf16 v[40:43], v[168:171], v[200:203], v[40:43]
	v_mfma_f32_16x16x32_bf16 v[36:39], v[148:151], v[208:211], v[36:39]
	v_mfma_f32_16x16x32_bf16 v[32:35], v[168:171], v[208:211], v[32:35]
	s_barrier
	s_add_i32 s84, s78, s56
	v_lshl_add_u64 v[184:185], s[14:15], 0, v[154:155]
	s_mov_b32 m0, s84
	ds_read_b128 v[172:175], v179 offset:16384
	ds_read_b128 v[180:183], v179 offset:17408
	ds_read_b128 v[188:191], v179 offset:18432
	ds_read_b128 v[192:195], v179 offset:19456
	ds_read_b128 v[196:199], v179 offset:20480
	ds_read_b128 v[200:203], v179 offset:21504
	ds_read_b128 v[204:207], v179 offset:22528
	ds_read_b128 v[208:211], v179 offset:23552
	global_load_lds_dwordx4 v[184:185], off
	s_add_i32 m0, s84, 0x2000
	s_add_u32 s84, s14, 0x40000
	v_lshl_add_u64 v[186:187], s[14:15], 0, v[158:159]
	s_addc_u32 s85, s15, 0
	s_add_i32 s86, s79, s56
	global_load_lds_dwordx4 v[186:187], off
	v_lshl_add_u64 v[212:213], s[84:85], 0, v[154:155]
	s_mov_b32 m0, s86
	v_lshl_add_u64 v[214:215], s[46:47], 0, v[156:157]
	global_load_lds_dwordx4 v[212:213], off
	v_lshl_add_u64 v[212:213], s[84:85], 0, v[158:159]
	s_add_i32 m0, s86, 0x2000
	s_nop 0
	global_load_lds_dwordx4 v[212:213], off
	v_lshl_add_u64 v[212:213], s[46:47], 0, v[152:153]
	s_mov_b32 m0, s57
	s_nop 0
	global_load_lds_dwordx4 v[212:213], off
	s_mov_b32 m0, s58
	s_nop 0
	global_load_lds_dwordx4 v[214:215], off
	s_cmp_lg_u32 s100, 0
	s_cbranch_scc0 .Lrf_528_1
	s_waitcnt vmcnt(16)
	s_branch .Lrj_528_1

; #define G_STAGE(bufoff, gbase, voff) do { _Pragma("unroll") for (int _i = 0; _i < 2; ++_i) \
;         __builtin_amdgcn_global_load_lds((const unsigned*)((const char*)(gbase) + voff[_i]), (LAS unsigned*)(lds + (bufoff) + ldsw + _i * 8192), 16, 0, 0); } while (0)
; #define G_LDA(dst, b, h) do { _Pragma("unroll") for (int m = 0; m < 4; ++m) _Pragma("unroll") for (int k = 0; k < 2; ++k) dst[m][k] = *(const LAS bf16x8*)(lds + G_SA(b, h) + aoff + m * 2048 + k * 1024); } while (0)
; #define G_LDB(dst, b, h) do { _Pragma("unroll") for (int n = 0; n < 2; ++n) _Pragma("unroll") for (int k = 0; k < 2; ++k) dst[n][k] = *(const LAS bf16x8*)(lds + G_SB(b, h) + boff + n * 2048 + k * 1024); } while (0)
; template <class Get, class Epi>
; DI void gemm_loop(int ntiles, int ld, char* shm, const Get& get, const Epi& epi) {
;     ...
;     for (;;) {
;         const int Ln = L + gridDim.x; const bool has_next = Ln < ntiles; if (has_next) nxt = get(Ln);
;         const char* nA = has_next ? (const char*)nxt.A + (size_t)nxt.brow * ld * 2 : cA; const char* nB = has_next ? (const char*)nxt.Bt + (size_t)nxt.bcol * ld * 2 : cB;
;         const int nt = cur.K / BK;
;         for (int t = 0; t < nt; t += 2) {
;             const bool last = (t == nt - 2);
;             const char* a1 = cA + (size_t)(t + 1) * kstep;
;             const char* a2 = last ? nA : cA + (size_t)(t + 2) * kstep; const char* b2 = last ? nB : cB + (size_t)(t + 2) * kstep;
;             const char* a3 = a2 + kstep; const char* b3 = b2 + kstep;
;             G_LDB(B0, 0, 0); G_LDB(B1, 0, 1); SCHED; G_LDA(At, 0, 0); G_STAGE(G_SA(1, 1), a1 + hstep, voffA);
;             WAIT_V(8); WAIT_L(0); BAR; G_MMA(0, 0, At, B0); G_MMA(0, 1, At, B1); BAR; SCHED;
;             G_LDA(At, 0, 1); G_STAGE(G_SB(0, 0), b2, voffB); G_STAGE(G_SB(0, 1), b2 + hstep, voffB); G_STAGE(G_SA(0, 0), a2, voffA);
;             WAIT_V(8); WAIT_L(0); BAR; G_MMA(1, 0, At, B0); G_MMA(1, 1, At, B1); BAR; SCHED;
;             G_LDB(B0, 1, 0); G_LDB(B1, 1, 1); SCHED; G_LDA(At, 1, 0); G_STAGE(G_SA(0, 1), a2 + hstep, voffA);
;             WAIT_V(8); WAIT_L(0); BAR; G_MMA(0, 0, At, B0); G_MMA(0, 1, At, B1); BAR; SCHED;
;             G_LDA(At, 1, 1); G_STAGE(G_SB(1, 0), b3, voffB); G_STAGE(G_SB(1, 1), b3 + hstep, voffB); G_STAGE(G_SA(1, 0), a3, voffA);
;             WAIT_V(8); WAIT_L(0); BAR; G_MMA(1, 0, At, B0); G_MMA(1, 1, At, B1); BAR; SCHED;
.Lrj_528_1:
	s_waitcnt lgkmcnt(0)
	s_barrier
	s_waitcnt lgkmcnt(0)
	v_mfma_f32_16x16x32_bf16 v[92:95], v[128:131], v[172:175], 0
	v_mfma_f32_16x16x32_bf16 v[88:91], v[136:139], v[172:175], 0
	v_mfma_f32_16x16x32_bf16 v[84:87], v[128:131], v[188:191], 0
	v_mfma_f32_16x16x32_bf16 v[80:83], v[136:139], v[188:191], 0
	v_mfma_f32_16x16x32_bf16 v[76:79], v[128:131], v[196:199], 0
	v_mfma_f32_16x16x32_bf16 v[72:75], v[136:139], v[196:199], 0
	v_mfma_f32_16x16x32_bf16 v[68:71], v[128:131], v[204:207], 0
	v_mfma_f32_16x16x32_bf16 v[64:67], v[136:139], v[204:207], 0
	v_mfma_f32_16x16x32_bf16 v[92:95], v[132:135], v[180:183], v[92:95]
	v_mfma_f32_16x16x32_bf16 v[88:91], v[140:143], v[180:183], v[88:91]
	v_mfma_f32_16x16x32_bf16 v[84:87], v[132:135], v[192:195], v[84:87]
	v_mfma_f32_16x16x32_bf16 v[80:83], v[140:143], v[192:195], v[80:83]
	v_mfma_f32_16x16x32_bf16 v[76:79], v[132:135], v[200:203], v[76:79]
	v_mfma_f32_16x16x32_bf16 v[72:75], v[140:143], v[200:203], v[72:75]
	v_mfma_f32_16x16x32_bf16 v[68:71], v[132:135], v[208:211], v[68:71]
	v_mfma_f32_16x16x32_bf16 v[64:67], v[140:143], v[208:211], v[64:67]
	v_mfma_f32_16x16x32_bf16 v[28:31], v[144:147], v[172:175], 0
	v_mfma_f32_16x16x32_bf16 v[24:27], v[164:167], v[172:175], 0
	v_mfma_f32_16x16x32_bf16 v[20:23], v[144:147], v[188:191], 0
	v_mfma_f32_16x16x32_bf16 v[16:19], v[164:167], v[188:191], 0
	v_mfma_f32_16x16x32_bf16 v[12:15], v[144:147], v[196:199], 0
	v_mfma_f32_16x16x32_bf16 v[8:11], v[164:167], v[196:199], 0
	v_mfma_f32_16x16x32_bf16 v[4:7], v[144:147], v[204:207], 0
	v_mfma_f32_16x16x32_bf16 v[0:3], v[164:167], v[204:207], 0
	v_mfma_f32_16x16x32_bf16 v[28:31], v[148:151], v[180:183], v[28:31]
	v_mfma_f32_16x16x32_bf16 v[24:27], v[168:171], v[180:183], v[24:27]
	v_mfma_f32_16x16x32_bf16 v[20:23], v[148:151], v[192:195], v[20:23]
	v_mfma_f32_16x16x32_bf16 v[16:19], v[168:171], v[192:195], v[16:19]
	v_mfma_f32_16x16x32_bf16 v[12:15], v[148:151], v[200:203], v[12:15]
	v_mfma_f32_16x16x32_bf16 v[8:11], v[168:171], v[200:203], v[8:11]
	v_mfma_f32_16x16x32_bf16 v[4:7], v[148:151], v[208:211], v[4:7]
	v_mfma_f32_16x16x32_bf16 v[0:3], v[168:171], v[208:211], v[0:3]
	s_barrier
	s_add_i32 s84, 0, 0x18000
	s_add_i32 s85, 0, 0x1c000
	v_add_u32_e32 v140, s84, v176
	v_add_u32_e32 v168, s85, v176
	ds_read_b128 v[128:131], v140
	ds_read_b128 v[132:135], v140 offset:1024
	ds_read_b128 v[136:139], v140 offset:2048
	ds_read_b128 v[140:143], v140 offset:3072
	ds_read_b128 v[144:147], v168
	ds_read_b128 v[148:151], v168 offset:1024
	ds_read_b128 v[164:167], v168 offset:2048
	ds_read_b128 v[168:171], v168 offset:3072
	s_add_u32 s46, s46, 0x40000
	s_addc_u32 s47, s47, 0
	s_mov_b32 m0, s59
	v_lshl_add_u64 v[216:217], s[46:47], 0, v[152:153]
	ds_read_b128 v[172:175], v179 offset:32768
	ds_read_b128 v[180:183], v179 offset:33792
	ds_read_b128 v[188:191], v179 offset:34816
	ds_read_b128 v[192:195], v179 offset:35840
	ds_read_b128 v[196:199], v179 offset:36864
	ds_read_b128 v[200:203], v179 offset:37888
	ds_read_b128 v[204:207], v179 offset:38912
	ds_read_b128 v[208:211], v179 offset:39936
	global_load_lds_dwordx4 v[216:217], off
	v_lshl_add_u64 v[216:217], s[46:47], 0, v[156:157]
	s_mov_b32 m0, s72
	s_nop 0
	global_load_lds_dwordx4 v[216:217], off
	s_waitcnt vmcnt(8)
	s_waitcnt lgkmcnt(0)
	s_barrier
	s_waitcnt lgkmcnt(0)
	v_mfma_f32_16x16x32_bf16 v[124:127], v[128:131], v[172:175], v[124:127]
	v_mfma_f32_16x16x32_bf16 v[120:123], v[136:139], v[172:175], v[120:123]
	v_mfma_f32_16x16x32_bf16 v[116:119], v[128:131], v[188:191], v[116:119]
	v_mfma_f32_16x16x32_bf16 v[112:115], v[136:139], v[188:191], v[112:115]
	v_mfma_f32_16x16x32_bf16 v[108:111], v[128:131], v[196:199], v[108:111]
	v_mfma_f32_16x16x32_bf16 v[104:107], v[136:139], v[196:199], v[104:107]
	v_mfma_f32_16x16x32_bf16 v[100:103], v[128:131], v[204:207], v[100:103]
	v_mfma_f32_16x16x32_bf16 v[96:99], v[136:139], v[204:207], v[96:99]
	v_mfma_f32_16x16x32_bf16 v[124:127], v[132:135], v[180:183], v[124:127]
	v_mfma_f32_16x16x32_bf16 v[120:123], v[140:143], v[180:183], v[120:123]
	v_mfma_f32_16x16x32_bf16 v[116:119], v[132:135], v[192:195], v[116:119]
	v_mfma_f32_16x16x32_bf16 v[112:115], v[140:143], v[192:195], v[112:115]
	v_mfma_f32_16x16x32_bf16 v[108:111], v[132:135], v[200:203], v[108:111]
	v_mfma_f32_16x16x32_bf16 v[104:107], v[140:143], v[200:203], v[104:107]
	v_mfma_f32_16x16x32_bf16 v[100:103], v[132:135], v[208:211], v[100:103]
	v_mfma_f32_16x16x32_bf16 v[96:99], v[140:143], v[208:211], v[96:99]
	v_mfma_f32_16x16x32_bf16 v[60:63], v[144:147], v[172:175], v[60:63]
	v_mfma_f32_16x16x32_bf16 v[56:59], v[164:167], v[172:175], v[56:59]
	v_mfma_f32_16x16x32_bf16 v[52:55], v[144:147], v[188:191], v[52:55]
	v_mfma_f32_16x16x32_bf16 v[48:51], v[164:167], v[188:191], v[48:51]
	v_mfma_f32_16x16x32_bf16 v[44:47], v[144:147], v[196:199], v[44:47]
	v_mfma_f32_16x16x32_bf16 v[40:43], v[164:167], v[196:199], v[40:43]
	v_mfma_f32_16x16x32_bf16 v[36:39], v[144:147], v[204:207], v[36:39]
	v_mfma_f32_16x16x32_bf16 v[32:35], v[164:167], v[204:207], v[32:35]
	v_mfma_f32_16x16x32_bf16 v[60:63], v[148:151], v[180:183], v[60:63]
	v_mfma_f32_16x16x32_bf16 v[56:59], v[168:171], v[180:183], v[56:59]
	v_mfma_f32_16x16x32_bf16 v[52:55], v[148:151], v[192:195], v[52:55]
	v_mfma_f32_16x16x32_bf16 v[48:51], v[168:171], v[192:195], v[48:51]
	v_mfma_f32_16x16x32_bf16 v[44:47], v[148:151], v[200:203], v[44:47]
	v_mfma_f32_16x16x32_bf16 v[40:43], v[168:171], v[200:203], v[40:43]
	v_mfma_f32_16x16x32_bf16 v[36:39], v[148:151], v[208:211], v[36:39]
	v_mfma_f32_16x16x32_bf16 v[32:35], v[168:171], v[208:211], v[32:35]
	s_barrier
; #define G_STAGE(bufoff, gbase, voff) do { _Pragma("unroll") for (int _i = 0; _i < 2; ++_i) \
;         __builtin_amdgcn_global_load_lds((const unsigned*)((const char*)(gbase) + voff[_i]), (LAS unsigned*)(lds + (bufoff) + ldsw + _i * 8192), 16, 0, 0); } while (0)
; #define G_LDA(dst, b, h) do { _Pragma("unroll") for (int m = 0; m < 4; ++m) _Pragma("unroll") for (int k = 0; k < 2; ++k) dst[m][k] = *(const LAS bf16x8*)(lds + G_SA(b, h) + aoff + m * 2048 + k * 1024); } while (0)
; #define G_LDB(dst, b, h) do { _Pragma("unroll") for (int n = 0; n < 2; ++n) _Pragma("unroll") for (int k = 0; k < 2; ++k) dst[n][k] = *(const LAS bf16x8*)(lds + G_SB(b, h) + boff + n * 2048 + k * 1024); } while (0)
; #define WAIT_V(n) asm volatile("s_waitcnt vmcnt(" #n ")" ::: "memory")
; #define WAIT_L(n) asm volatile("s_waitcnt lgkmcnt(" #n ")" ::: "memory")
; #define BAR __builtin_amdgcn_s_barrier()
; #define SCHED __builtin_amdgcn_sched_barrier(0)
; template <class Get, class Epi>
; DI void gemm_loop(int ntiles, int ld, char* shm, const Get& get, const Epi& epi) {
;     ...
;         for (int t = 0; t < nt; t += 2) {
;             const bool last = (t == nt - 2);
;             const char* a1 = cA + (size_t)(t + 1) * kstep;
;             const char* a2 = last ? nA : cA + (size_t)(t + 2) * kstep; const char* b2 = last ? nB : cB + (size_t)(t + 2) * kstep;
;             const char* a3 = a2 + kstep; const char* b3 = b2 + kstep;
;             G_LDB(B0, 0, 0); G_LDB(B1, 0, 1); SCHED; G_LDA(At, 0, 0); G_STAGE(G_SA(1, 1), a1 + hstep, voffA);
;             WAIT_V(8); WAIT_L(0); BAR; G_MMA(0, 0, At, B0); G_MMA(0, 1, At, B1); BAR; SCHED;
;             G_LDA(At, 0, 1); G_STAGE(G_SB(0, 0), b2, voffB); G_STAGE(G_SB(0, 1), b2 + hstep, voffB); G_STAGE(G_SA(0, 0), a2, voffA);
;             WAIT_V(8); WAIT_L(0); BAR; G_MMA(1, 0, At, B0); G_MMA(1, 1, At, B1); BAR; SCHED;
;             G_LDB(B0, 1, 0); G_LDB(B1, 1, 1); SCHED; G_LDA(At, 1, 0); G_STAGE(G_SA(0, 1), a2 + hstep, voffA);
;             WAIT_V(8); WAIT_L(0); BAR; G_MMA(0, 0, At, B0); G_MMA(0, 1, At, B1); BAR; SCHED;
;             G_LDA(At, 1, 1); G_STAGE(G_SB(1, 0), b3, voffB); G_STAGE(G_SB(1, 1), b3 + hstep, voffB); G_STAGE(G_SA(1, 0), a3, voffA);
;             WAIT_V(8); WAIT_L(0); BAR; G_MMA(1, 0, At, B0); G_MMA(1, 1, At, B1); BAR; SCHED;
	s_add_i32 s46, s84, s56
	v_lshl_add_u64 v[184:185], v[184:185], 0, s[10:11]
	s_mov_b32 m0, s46
	ds_read_b128 v[172:175], v179 offset:49152
	ds_read_b128 v[180:183], v179 offset:50176
	ds_read_b128 v[188:191], v179 offset:51200
	ds_read_b128 v[192:195], v179 offset:52224
	ds_read_b128 v[196:199], v179 offset:53248
	ds_read_b128 v[200:203], v179 offset:54272
	ds_read_b128 v[204:207], v179 offset:55296
	ds_read_b128 v[208:211], v179 offset:56320
	global_load_lds_dwordx4 v[184:185], off
	s_add_i32 m0, s46, 0x2000
	s_add_u32 s14, s14, 0x40080
	v_lshl_add_u64 v[184:185], v[186:187], 0, s[10:11]
	s_addc_u32 s15, s15, 0
	s_add_i32 s46, s85, s56
	global_load_lds_dwordx4 v[184:185], off
	v_lshl_add_u64 v[184:185], s[14:15], 0, v[154:155]
	s_mov_b32 m0, s46
	s_nop 0
	global_load_lds_dwordx4 v[184:185], off
	v_lshl_add_u64 v[184:185], s[14:15], 0, v[158:159]
	s_add_i32 m0, s46, 0x2000
	s_nop 0
	global_load_lds_dwordx4 v[184:185], off
	v_lshl_add_u64 v[184:185], v[212:213], 0, s[10:11]
	s_mov_b32 m0, s75
	s_nop 0
	global_load_lds_dwordx4 v[184:185], off
	v_lshl_add_u64 v[184:185], v[214:215], 0, s[10:11]
	s_mov_b32 m0, s76
	s_nop 0
	global_load_lds_dwordx4 v[184:185], off
	s_waitcnt vmcnt(8)
	s_waitcnt lgkmcnt(0)
	s_barrier
	s_waitcnt lgkmcnt(0)
	v_mfma_f32_16x16x32_bf16 v[92:95], v[128:131], v[172:175], v[92:95]
	v_mfma_f32_16x16x32_bf16 v[88:91], v[136:139], v[172:175], v[88:91]
	v_mfma_f32_16x16x32_bf16 v[84:87], v[128:131], v[188:191], v[84:87]
	v_mfma_f32_16x16x32_bf16 v[80:83], v[136:139], v[188:191], v[80:83]
	v_mfma_f32_16x16x32_bf16 v[76:79], v[128:131], v[196:199], v[76:79]
	v_mfma_f32_16x16x32_bf16 v[72:75], v[136:139], v[196:199], v[72:75]
	v_mfma_f32_16x16x32_bf16 v[68:71], v[128:131], v[204:207], v[68:71]
	v_mfma_f32_16x16x32_bf16 v[64:67], v[136:139], v[204:207], v[64:67]
	v_mfma_f32_16x16x32_bf16 v[92:95], v[132:135], v[180:183], v[92:95]
	v_mfma_f32_16x16x32_bf16 v[88:91], v[140:143], v[180:183], v[88:91]
	v_mfma_f32_16x16x32_bf16 v[84:87], v[132:135], v[192:195], v[84:87]
	v_mfma_f32_16x16x32_bf16 v[80:83], v[140:143], v[192:195], v[80:83]
	v_mfma_f32_16x16x32_bf16 v[76:79], v[132:135], v[200:203], v[76:79]
	v_mfma_f32_16x16x32_bf16 v[72:75], v[140:143], v[200:203], v[72:75]
	v_mfma_f32_16x16x32_bf16 v[68:71], v[132:135], v[208:211], v[68:71]
	v_mfma_f32_16x16x32_bf16 v[64:67], v[140:143], v[208:211], v[64:67]
	v_mfma_f32_16x16x32_bf16 v[28:31], v[144:147], v[172:175], v[28:31]
	v_mfma_f32_16x16x32_bf16 v[24:27], v[164:167], v[172:175], v[24:27]
	v_mfma_f32_16x16x32_bf16 v[20:23], v[144:147], v[188:191], v[20:23]
	v_mfma_f32_16x16x32_bf16 v[16:19], v[164:167], v[188:191], v[16:19]
	v_mfma_f32_16x16x32_bf16 v[12:15], v[144:147], v[196:199], v[12:15]
	v_mfma_f32_16x16x32_bf16 v[8:11], v[164:167], v[196:199], v[8:11]
	v_mfma_f32_16x16x32_bf16 v[4:7], v[144:147], v[204:207], v[4:7]
	v_mfma_f32_16x16x32_bf16 v[0:3], v[164:167], v[204:207], v[0:3]
	v_mfma_f32_16x16x32_bf16 v[28:31], v[148:151], v[180:183], v[28:31]
	v_mfma_f32_16x16x32_bf16 v[24:27], v[168:171], v[180:183], v[24:27]
	v_mfma_f32_16x16x32_bf16 v[20:23], v[148:151], v[192:195], v[20:23]
	v_mfma_f32_16x16x32_bf16 v[16:19], v[168:171], v[192:195], v[16:19]
	v_mfma_f32_16x16x32_bf16 v[12:15], v[148:151], v[200:203], v[12:15]
	v_mfma_f32_16x16x32_bf16 v[8:11], v[168:171], v[200:203], v[8:11]
	v_mfma_f32_16x16x32_bf16 v[4:7], v[148:151], v[208:211], v[4:7]
	v_mfma_f32_16x16x32_bf16 v[0:3], v[168:171], v[208:211], v[0:3]
	s_barrier
	s_add_u32 s44, s44, 0x100
	s_addc_u32 s45, s45, 0
	s_add_u32 s55, s55, 0x100
	s_addc_u32 s82, s82, 0
	s_cmp_ge_u32 s83, s51
	s_mov_b32 s14, s83
	s_cbranch_scc0 .LBB0_528
	s_branch .Lpost_528
.LBB0_528:
	ds_read_b128 v[128:131], v177
	ds_read_b128 v[132:135], v177 offset:1024
	ds_read_b128 v[136:139], v177 offset:2048
	ds_read_b128 v[140:143], v177 offset:3072
	ds_read_b128 v[144:147], v178
	ds_read_b128 v[148:151], v178 offset:1024
	ds_read_b128 v[164:167], v178 offset:2048
	ds_read_b128 v[168:171], v178 offset:3072
	s_add_i32 s83, s14, 2
	s_add_u32 s15, s44, 0xfffc0080
	s_addc_u32 s46, s45, -1
	s_cmp_eq_u32 s54, s14
	s_cselect_b32 s14, s43, s55
	s_cselect_b32 s47, s3, s46
	s_cselect_b32 s46, s35, s15
	s_cselect_b32 s15, s37, s82
	v_lshl_add_u64 v[184:185], s[44:45], 0, v[160:161]
	s_add_i32 m0, s57, 0xc000
	ds_read_b128 v[172:175], v179
	ds_read_b128 v[180:183], v179 offset:1024
	ds_read_b128 v[188:191], v179 offset:2048
	ds_read_b128 v[192:195], v179 offset:3072
	ds_read_b128 v[196:199], v179 offset:4096
	ds_read_b128 v[200:203], v179 offset:5120
	ds_read_b128 v[204:207], v179 offset:6144
	ds_read_b128 v[208:211], v179 offset:7168
	global_load_lds_dwordx4 v[184:185], off
	v_lshl_add_u64 v[184:185], s[44:45], 0, v[162:163]
	s_add_i32 m0, s57, 0xe000
	s_nop 0
	global_load_lds_dwordx4 v[184:185], off
	s_waitcnt vmcnt(8)
	s_waitcnt lgkmcnt(0)
	s_barrier
; #define G_STAGE(bufoff, gbase, voff) do { _Pragma("unroll") for (int _i = 0; _i < 2; ++_i) \
;         __builtin_amdgcn_global_load_lds((const unsigned*)((const char*)(gbase) + voff[_i]), (LAS unsigned*)(lds + (bufoff) + ldsw + _i * 8192), 16, 0, 0); } while (0)
; #define G_LDA(dst, b, h) do { _Pragma("unroll") for (int m = 0; m < 4; ++m) _Pragma("unroll") for (int k = 0; k < 2; ++k) dst[m][k] = *(const LAS bf16x8*)(lds + G_SA(b, h) + aoff + m * 2048 + k * 1024); } while (0)
; #define G_LDB(dst, b, h) do { _Pragma("unroll") for (int n = 0; n < 2; ++n) _Pragma("unroll") for (int k = 0; k < 2; ++k) dst[n][k] = *(const LAS bf16x8*)(lds + G_SB(b, h) + boff + n * 2048 + k * 1024); } while (0)
; #define WAIT_V(n) asm volatile("s_waitcnt vmcnt(" #n ")" ::: "memory")
; #define WAIT_L(n) asm volatile("s_waitcnt lgkmcnt(" #n ")" ::: "memory")
; #define BAR __builtin_amdgcn_s_barrier()
; #define SCHED __builtin_amdgcn_sched_barrier(0)
; template <class Get, class Epi>
; DI void gemm_loop(int ntiles, int ld, char* shm, const Get& get, const Epi& epi) {
;     ...
;         for (int t = 0; t < nt; t += 2) {
;             const bool last = (t == nt - 2);
;             const char* a1 = cA + (size_t)(t + 1) * kstep;
;             const char* a2 = last ? nA : cA + (size_t)(t + 2) * kstep; const char* b2 = last ? nB : cB + (size_t)(t + 2) * kstep;
;             const char* a3 = a2 + kstep; const char* b3 = b2 + kstep;
;             G_LDB(B0, 0, 0); G_LDB(B1, 0, 1); SCHED; G_LDA(At, 0, 0); G_STAGE(G_SA(1, 1), a1 + hstep, voffA);
;             WAIT_V(8); WAIT_L(0); BAR; G_MMA(0, 0, At, B0); G_MMA(0, 1, At, B1); BAR; SCHED;
;             G_LDA(At, 0, 1); G_STAGE(G_SB(0, 0), b2, voffB); G_STAGE(G_SB(0, 1), b2 + hstep, voffB); G_STAGE(G_SA(0, 0), a2, voffA);
;             WAIT_V(8); WAIT_L(0); BAR; G_MMA(1, 0, At, B0); G_MMA(1, 1, At, B1); BAR; SCHED;
;             G_LDB(B0, 1, 0); G_LDB(B1, 1, 1); SCHED; G_LDA(At, 1, 0); G_STAGE(G_SA(0, 1), a2 + hstep, voffA);
;             WAIT_V(8); WAIT_L(0); BAR; G_MMA(0, 0, At, B0); G_MMA(0, 1, At, B1); BAR; SCHED;
;             G_LDA(At, 1, 1); G_STAGE(G_SB(1, 0), b3, voffB); G_STAGE(G_SB(1, 1), b3 + hstep, voffB); G_STAGE(G_SA(1, 0), a3, voffA);
;             WAIT_V(8); WAIT_L(0); BAR; G_MMA(1, 0, At, B0); G_MMA(1, 1, At, B1); BAR; SCHED;
	s_waitcnt lgkmcnt(0)
	v_mfma_f32_16x16x32_bf16 v[124:127], v[128:131], v[172:175], v[124:127]
	v_mfma_f32_16x16x32_bf16 v[120:123], v[136:139], v[172:175], v[120:123]
	v_mfma_f32_16x16x32_bf16 v[116:119], v[128:131], v[188:191], v[116:119]
	v_mfma_f32_16x16x32_bf16 v[112:115], v[136:139], v[188:191], v[112:115]
	v_mfma_f32_16x16x32_bf16 v[108:111], v[128:131], v[196:199], v[108:111]
	v_mfma_f32_16x16x32_bf16 v[104:107], v[136:139], v[196:199], v[104:107]
	v_mfma_f32_16x16x32_bf16 v[100:103], v[128:131], v[204:207], v[100:103]
	v_mfma_f32_16x16x32_bf16 v[96:99], v[136:139], v[204:207], v[96:99]
	v_mfma_f32_16x16x32_bf16 v[124:127], v[132:135], v[180:183], v[124:127]
	v_mfma_f32_16x16x32_bf16 v[120:123], v[140:143], v[180:183], v[120:123]
	v_mfma_f32_16x16x32_bf16 v[116:119], v[132:135], v[192:195], v[116:119]
	v_mfma_f32_16x16x32_bf16 v[112:115], v[140:143], v[192:195], v[112:115]
	v_mfma_f32_16x16x32_bf16 v[108:111], v[132:135], v[200:203], v[108:111]
	v_mfma_f32_16x16x32_bf16 v[104:107], v[140:143], v[200:203], v[104:107]
	v_mfma_f32_16x16x32_bf16 v[100:103], v[132:135], v[208:211], v[100:103]
	v_mfma_f32_16x16x32_bf16 v[96:99], v[140:143], v[208:211], v[96:99]
	v_mfma_f32_16x16x32_bf16 v[60:63], v[144:147], v[172:175], v[60:63]
	v_mfma_f32_16x16x32_bf16 v[56:59], v[164:167], v[172:175], v[56:59]
	v_mfma_f32_16x16x32_bf16 v[52:55], v[144:147], v[188:191], v[52:55]
	v_mfma_f32_16x16x32_bf16 v[48:51], v[164:167], v[188:191], v[48:51]
	v_mfma_f32_16x16x32_bf16 v[44:47], v[144:147], v[196:199], v[44:47]
	v_mfma_f32_16x16x32_bf16 v[40:43], v[164:167], v[196:199], v[40:43]
	v_mfma_f32_16x16x32_bf16 v[36:39], v[144:147], v[204:207], v[36:39]
	v_mfma_f32_16x16x32_bf16 v[32:35], v[164:167], v[204:207], v[32:35]
	v_mfma_f32_16x16x32_bf16 v[60:63], v[148:151], v[180:183], v[60:63]
	v_mfma_f32_16x16x32_bf16 v[56:59], v[168:171], v[180:183], v[56:59]
	v_mfma_f32_16x16x32_bf16 v[52:55], v[148:151], v[192:195], v[52:55]
	v_mfma_f32_16x16x32_bf16 v[48:51], v[168:171], v[192:195], v[48:51]
	v_mfma_f32_16x16x32_bf16 v[44:47], v[148:151], v[200:203], v[44:47]
	v_mfma_f32_16x16x32_bf16 v[40:43], v[168:171], v[200:203], v[40:43]
	v_mfma_f32_16x16x32_bf16 v[36:39], v[148:151], v[208:211], v[36:39]
	v_mfma_f32_16x16x32_bf16 v[32:35], v[168:171], v[208:211], v[32:35]
	s_barrier
	s_add_i32 s84, s78, s56
	v_lshl_add_u64 v[184:185], s[14:15], 0, v[154:155]
	s_mov_b32 m0, s84
	ds_read_b128 v[172:175], v179 offset:16384
	ds_read_b128 v[180:183], v179 offset:17408
	ds_read_b128 v[188:191], v179 offset:18432
	ds_read_b128 v[192:195], v179 offset:19456
	ds_read_b128 v[196:199], v179 offset:20480
	ds_read_b128 v[200:203], v179 offset:21504
	ds_read_b128 v[204:207], v179 offset:22528
	ds_read_b128 v[208:211], v179 offset:23552
	global_load_lds_dwordx4 v[184:185], off
	s_add_i32 m0, s84, 0x2000
	s_add_u32 s84, s14, 0x40000
	v_lshl_add_u64 v[186:187], s[14:15], 0, v[158:159]
	s_addc_u32 s85, s15, 0
	s_add_i32 s86, s79, s56
	global_load_lds_dwordx4 v[186:187], off
	v_lshl_add_u64 v[212:213], s[84:85], 0, v[154:155]
	s_mov_b32 m0, s86
	v_lshl_add_u64 v[214:215], s[46:47], 0, v[156:157]
	global_load_lds_dwordx4 v[212:213], off
	v_lshl_add_u64 v[212:213], s[84:85], 0, v[158:159]
	s_add_i32 m0, s86, 0x2000
	s_nop 0
	global_load_lds_dwordx4 v[212:213], off
	v_lshl_add_u64 v[212:213], s[46:47], 0, v[152:153]
	s_mov_b32 m0, s57
	s_nop 0
	global_load_lds_dwordx4 v[212:213], off
	s_mov_b32 m0, s58
	s_nop 0
	global_load_lds_dwordx4 v[214:215], off
	s_waitcnt vmcnt(8)
	s_waitcnt lgkmcnt(0)
	s_barrier
	s_waitcnt lgkmcnt(0)
	v_mfma_f32_16x16x32_bf16 v[92:95], v[128:131], v[172:175], v[92:95]
	v_mfma_f32_16x16x32_bf16 v[88:91], v[136:139], v[172:175], v[88:91]
	v_mfma_f32_16x16x32_bf16 v[84:87], v[128:131], v[188:191], v[84:87]
	v_mfma_f32_16x16x32_bf16 v[80:83], v[136:139], v[188:191], v[80:83]
	v_mfma_f32_16x16x32_bf16 v[76:79], v[128:131], v[196:199], v[76:79]
	v_mfma_f32_16x16x32_bf16 v[72:75], v[136:139], v[196:199], v[72:75]
	v_mfma_f32_16x16x32_bf16 v[68:71], v[128:131], v[204:207], v[68:71]
	v_mfma_f32_16x16x32_bf16 v[64:67], v[136:139], v[204:207], v[64:67]
	v_mfma_f32_16x16x32_bf16 v[92:95], v[132:135], v[180:183], v[92:95]
	v_mfma_f32_16x16x32_bf16 v[88:91], v[140:143], v[180:183], v[88:91]
	v_mfma_f32_16x16x32_bf16 v[84:87], v[132:135], v[192:195], v[84:87]
	v_mfma_f32_16x16x32_bf16 v[80:83], v[140:143], v[192:195], v[80:83]
	v_mfma_f32_16x16x32_bf16 v[76:79], v[132:135], v[200:203], v[76:79]
	v_mfma_f32_16x16x32_bf16 v[72:75], v[140:143], v[200:203], v[72:75]
	v_mfma_f32_16x16x32_bf16 v[68:71], v[132:135], v[208:211], v[68:71]
	v_mfma_f32_16x16x32_bf16 v[64:67], v[140:143], v[208:211], v[64:67]
	v_mfma_f32_16x16x32_bf16 v[28:31], v[144:147], v[172:175], v[28:31]
	v_mfma_f32_16x16x32_bf16 v[24:27], v[164:167], v[172:175], v[24:27]
	v_mfma_f32_16x16x32_bf16 v[20:23], v[144:147], v[188:191], v[20:23]
	v_mfma_f32_16x16x32_bf16 v[16:19], v[164:167], v[188:191], v[16:19]
	v_mfma_f32_16x16x32_bf16 v[12:15], v[144:147], v[196:199], v[12:15]
	v_mfma_f32_16x16x32_bf16 v[8:11], v[164:167], v[196:199], v[8:11]
	v_mfma_f32_16x16x32_bf16 v[4:7], v[144:147], v[204:207], v[4:7]
	v_mfma_f32_16x16x32_bf16 v[0:3], v[164:167], v[204:207], v[0:3]
	v_mfma_f32_16x16x32_bf16 v[28:31], v[148:151], v[180:183], v[28:31]
	v_mfma_f32_16x16x32_bf16 v[24:27], v[168:171], v[180:183], v[24:27]
	v_mfma_f32_16x16x32_bf16 v[20:23], v[148:151], v[192:195], v[20:23]
	v_mfma_f32_16x16x32_bf16 v[16:19], v[168:171], v[192:195], v[16:19]
	v_mfma_f32_16x16x32_bf16 v[12:15], v[148:151], v[200:203], v[12:15]
	v_mfma_f32_16x16x32_bf16 v[8:11], v[168:171], v[200:203], v[8:11]
	v_mfma_f32_16x16x32_bf16 v[4:7], v[148:151], v[208:211], v[4:7]
	v_mfma_f32_16x16x32_bf16 v[0:3], v[168:171], v[208:211], v[0:3]
	s_barrier
; #define G_STAGE(bufoff, gbase, voff) do { _Pragma("unroll") for (int _i = 0; _i < 2; ++_i) \
;         __builtin_amdgcn_global_load_lds((const unsigned*)((const char*)(gbase) + voff[_i]), (LAS unsigned*)(lds + (bufoff) + ldsw + _i * 8192), 16, 0, 0); } while (0)
; #define G_LDA(dst, b, h) do { _Pragma("unroll") for (int m = 0; m < 4; ++m) _Pragma("unroll") for (int k = 0; k < 2; ++k) dst[m][k] = *(const LAS bf16x8*)(lds + G_SA(b, h) + aoff + m * 2048 + k * 1024); } while (0)
; #define G_LDB(dst, b, h) do { _Pragma("unroll") for (int n = 0; n < 2; ++n) _Pragma("unroll") for (int k = 0; k < 2; ++k) dst[n][k] = *(const LAS bf16x8*)(lds + G_SB(b, h) + boff + n * 2048 + k * 1024); } while (0)
; #define WAIT_V(n) asm volatile("s_waitcnt vmcnt(" #n ")" ::: "memory")
; #define WAIT_L(n) asm volatile("s_waitcnt lgkmcnt(" #n ")" ::: "memory")
; #define BAR __builtin_amdgcn_s_barrier()
; #define SCHED __builtin_amdgcn_sched_barrier(0)
; template <class Get, class Epi>
; DI void gemm_loop(int ntiles, int ld, char* shm, const Get& get, const Epi& epi) {
;     ...
;         for (int t = 0; t < nt; t += 2) {
;             const bool last = (t == nt - 2);
;             const char* a1 = cA + (size_t)(t + 1) * kstep;
;             const char* a2 = last ? nA : cA + (size_t)(t + 2) * kstep; const char* b2 = last ? nB : cB + (size_t)(t + 2) * kstep;
;             const char* a3 = a2 + kstep; const char* b3 = b2 + kstep;
;             G_LDB(B0, 0, 0); G_LDB(B1, 0, 1); SCHED; G_LDA(At, 0, 0); G_STAGE(G_SA(1, 1), a1 + hstep, voffA);
;             WAIT_V(8); WAIT_L(0); BAR; G_MMA(0, 0, At, B0); G_MMA(0, 1, At, B1); BAR; SCHED;
;             G_LDA(At, 0, 1); G_STAGE(G_SB(0, 0), b2, voffB); G_STAGE(G_SB(0, 1), b2 + hstep, voffB); G_STAGE(G_SA(0, 0), a2, voffA);
;             WAIT_V(8); WAIT_L(0); BAR; G_MMA(1, 0, At, B0); G_MMA(1, 1, At, B1); BAR; SCHED;
;             G_LDB(B0, 1, 0); G_LDB(B1, 1, 1); SCHED; G_LDA(At, 1, 0); G_STAGE(G_SA(0, 1), a2 + hstep, voffA);
;             WAIT_V(8); WAIT_L(0); BAR; G_MMA(0, 0, At, B0); G_MMA(0, 1, At, B1); BAR; SCHED;
;             G_LDA(At, 1, 1); G_STAGE(G_SB(1, 0), b3, voffB); G_STAGE(G_SB(1, 1), b3 + hstep, voffB); G_STAGE(G_SA(1, 0), a3, voffA);
;             WAIT_V(8); WAIT_L(0); BAR; G_MMA(1, 0, At, B0); G_MMA(1, 1, At, B1); BAR; SCHED;
	s_add_i32 s84, 0, 0x18000
	s_add_i32 s85, 0, 0x1c000
	v_add_u32_e32 v140, s84, v176
	v_add_u32_e32 v168, s85, v176
	ds_read_b128 v[128:131], v140
	ds_read_b128 v[132:135], v140 offset:1024
	ds_read_b128 v[136:139], v140 offset:2048
	ds_read_b128 v[140:143], v140 offset:3072
	ds_read_b128 v[144:147], v168
	ds_read_b128 v[148:151], v168 offset:1024
	ds_read_b128 v[164:167], v168 offset:2048
	ds_read_b128 v[168:171], v168 offset:3072
	s_add_u32 s46, s46, 0x40000
	s_addc_u32 s47, s47, 0
	s_mov_b32 m0, s59
	v_lshl_add_u64 v[216:217], s[46:47], 0, v[152:153]
	ds_read_b128 v[172:175], v179 offset:32768
	ds_read_b128 v[180:183], v179 offset:33792
	ds_read_b128 v[188:191], v179 offset:34816
	ds_read_b128 v[192:195], v179 offset:35840
	ds_read_b128 v[196:199], v179 offset:36864
	ds_read_b128 v[200:203], v179 offset:37888
	ds_read_b128 v[204:207], v179 offset:38912
	ds_read_b128 v[208:211], v179 offset:39936
	global_load_lds_dwordx4 v[216:217], off
	v_lshl_add_u64 v[216:217], s[46:47], 0, v[156:157]
	s_mov_b32 m0, s72
	s_nop 0
	global_load_lds_dwordx4 v[216:217], off
	s_waitcnt vmcnt(8)
	s_waitcnt lgkmcnt(0)
	s_barrier
	s_waitcnt lgkmcnt(0)
	v_mfma_f32_16x16x32_bf16 v[124:127], v[128:131], v[172:175], v[124:127]
	v_mfma_f32_16x16x32_bf16 v[120:123], v[136:139], v[172:175], v[120:123]
	v_mfma_f32_16x16x32_bf16 v[116:119], v[128:131], v[188:191], v[116:119]
	v_mfma_f32_16x16x32_bf16 v[112:115], v[136:139], v[188:191], v[112:115]
	v_mfma_f32_16x16x32_bf16 v[108:111], v[128:131], v[196:199], v[108:111]
	v_mfma_f32_16x16x32_bf16 v[104:107], v[136:139], v[196:199], v[104:107]
	v_mfma_f32_16x16x32_bf16 v[100:103], v[128:131], v[204:207], v[100:103]
	v_mfma_f32_16x16x32_bf16 v[96:99], v[136:139], v[204:207], v[96:99]
	v_mfma_f32_16x16x32_bf16 v[124:127], v[132:135], v[180:183], v[124:127]
	v_mfma_f32_16x16x32_bf16 v[120:123], v[140:143], v[180:183], v[120:123]
	v_mfma_f32_16x16x32_bf16 v[116:119], v[132:135], v[192:195], v[116:119]
	v_mfma_f32_16x16x32_bf16 v[112:115], v[140:143], v[192:195], v[112:115]
	v_mfma_f32_16x16x32_bf16 v[108:111], v[132:135], v[200:203], v[108:111]
	v_mfma_f32_16x16x32_bf16 v[104:107], v[140:143], v[200:203], v[104:107]
	v_mfma_f32_16x16x32_bf16 v[100:103], v[132:135], v[208:211], v[100:103]
	v_mfma_f32_16x16x32_bf16 v[96:99], v[140:143], v[208:211], v[96:99]
	v_mfma_f32_16x16x32_bf16 v[60:63], v[144:147], v[172:175], v[60:63]
	v_mfma_f32_16x16x32_bf16 v[56:59], v[164:167], v[172:175], v[56:59]
	v_mfma_f32_16x16x32_bf16 v[52:55], v[144:147], v[188:191], v[52:55]
	v_mfma_f32_16x16x32_bf16 v[48:51], v[164:167], v[188:191], v[48:51]
	v_mfma_f32_16x16x32_bf16 v[44:47], v[144:147], v[196:199], v[44:47]
	v_mfma_f32_16x16x32_bf16 v[40:43], v[164:167], v[196:199], v[40:43]
	v_mfma_f32_16x16x32_bf16 v[36:39], v[144:147], v[204:207], v[36:39]
	v_mfma_f32_16x16x32_bf16 v[32:35], v[164:167], v[204:207], v[32:35]
	v_mfma_f32_16x16x32_bf16 v[60:63], v[148:151], v[180:183], v[60:63]
	v_mfma_f32_16x16x32_bf16 v[56:59], v[168:171], v[180:183], v[56:59]
	v_mfma_f32_16x16x32_bf16 v[52:55], v[148:151], v[192:195], v[52:55]
	v_mfma_f32_16x16x32_bf16 v[48:51], v[168:171], v[192:195], v[48:51]
	v_mfma_f32_16x16x32_bf16 v[44:47], v[148:151], v[200:203], v[44:47]
	v_mfma_f32_16x16x32_bf16 v[40:43], v[168:171], v[200:203], v[40:43]
	v_mfma_f32_16x16x32_bf16 v[36:39], v[148:151], v[208:211], v[36:39]
	v_mfma_f32_16x16x32_bf16 v[32:35], v[168:171], v[208:211], v[32:35]
	s_barrier
	s_add_i32 s46, s84, s56
	v_lshl_add_u64 v[184:185], v[184:185], 0, s[10:11]
	s_mov_b32 m0, s46
	ds_read_b128 v[172:175], v179 offset:49152
	ds_read_b128 v[180:183], v179 offset:50176
	ds_read_b128 v[188:191], v179 offset:51200
	ds_read_b128 v[192:195], v179 offset:52224
	ds_read_b128 v[196:199], v179 offset:53248
	ds_read_b128 v[200:203], v179 offset:54272
	ds_read_b128 v[204:207], v179 offset:55296
	ds_read_b128 v[208:211], v179 offset:56320
	global_load_lds_dwordx4 v[184:185], off
	s_add_i32 m0, s46, 0x2000
	s_add_u32 s14, s14, 0x40080
	v_lshl_add_u64 v[184:185], v[186:187], 0, s[10:11]
	s_addc_u32 s15, s15, 0
	s_add_i32 s46, s85, s56
	global_load_lds_dwordx4 v[184:185], off
	v_lshl_add_u64 v[184:185], s[14:15], 0, v[154:155]
	s_mov_b32 m0, s46
	s_nop 0
	global_load_lds_dwordx4 v[184:185], off
	v_lshl_add_u64 v[184:185], s[14:15], 0, v[158:159]
	s_add_i32 m0, s46, 0x2000
	s_nop 0
	global_load_lds_dwordx4 v[184:185], off
	v_lshl_add_u64 v[184:185], v[212:213], 0, s[10:11]
	s_mov_b32 m0, s75
	s_nop 0
	global_load_lds_dwordx4 v[184:185], off
	v_lshl_add_u64 v[184:185], v[214:215], 0, s[10:11]
	s_mov_b32 m0, s76
	s_nop 0
	global_load_lds_dwordx4 v[184:185], off
	s_waitcnt vmcnt(8)
	s_waitcnt lgkmcnt(0)
	s_barrier
	s_waitcnt lgkmcnt(0)
	v_mfma_f32_16x16x32_bf16 v[92:95], v[128:131], v[172:175], v[92:95]
	v_mfma_f32_16x16x32_bf16 v[88:91], v[136:139], v[172:175], v[88:91]
	v_mfma_f32_16x16x32_bf16 v[84:87], v[128:131], v[188:191], v[84:87]
	v_mfma_f32_16x16x32_bf16 v[80:83], v[136:139], v[188:191], v[80:83]
	v_mfma_f32_16x16x32_bf16 v[76:79], v[128:131], v[196:199], v[76:79]
	v_mfma_f32_16x16x32_bf16 v[72:75], v[136:139], v[196:199], v[72:75]
	v_mfma_f32_16x16x32_bf16 v[68:71], v[128:131], v[204:207], v[68:71]
	v_mfma_f32_16x16x32_bf16 v[64:67], v[136:139], v[204:207], v[64:67]
	v_mfma_f32_16x16x32_bf16 v[92:95], v[132:135], v[180:183], v[92:95]
	v_mfma_f32_16x16x32_bf16 v[88:91], v[140:143], v[180:183], v[88:91]
	v_mfma_f32_16x16x32_bf16 v[84:87], v[132:135], v[192:195], v[84:87]
	v_mfma_f32_16x16x32_bf16 v[80:83], v[140:143], v[192:195], v[80:83]
	v_mfma_f32_16x16x32_bf16 v[76:79], v[132:135], v[200:203], v[76:79]
	v_mfma_f32_16x16x32_bf16 v[72:75], v[140:143], v[200:203], v[72:75]
	v_mfma_f32_16x16x32_bf16 v[68:71], v[132:135], v[208:211], v[68:71]
	v_mfma_f32_16x16x32_bf16 v[64:67], v[140:143], v[208:211], v[64:67]
	v_mfma_f32_16x16x32_bf16 v[28:31], v[144:147], v[172:175], v[28:31]
	v_mfma_f32_16x16x32_bf16 v[24:27], v[164:167], v[172:175], v[24:27]
	v_mfma_f32_16x16x32_bf16 v[20:23], v[144:147], v[188:191], v[20:23]
	v_mfma_f32_16x16x32_bf16 v[16:19], v[164:167], v[188:191], v[16:19]
	v_mfma_f32_16x16x32_bf16 v[12:15], v[144:147], v[196:199], v[12:15]
	v_mfma_f32_16x16x32_bf16 v[8:11], v[164:167], v[196:199], v[8:11]
	v_mfma_f32_16x16x32_bf16 v[4:7], v[144:147], v[204:207], v[4:7]
	v_mfma_f32_16x16x32_bf16 v[0:3], v[164:167], v[204:207], v[0:3]
	v_mfma_f32_16x16x32_bf16 v[28:31], v[148:151], v[180:183], v[28:31]
	v_mfma_f32_16x16x32_bf16 v[24:27], v[168:171], v[180:183], v[24:27]
	v_mfma_f32_16x16x32_bf16 v[20:23], v[148:151], v[192:195], v[20:23]
	v_mfma_f32_16x16x32_bf16 v[16:19], v[168:171], v[192:195], v[16:19]
	v_mfma_f32_16x16x32_bf16 v[12:15], v[148:151], v[200:203], v[12:15]
	v_mfma_f32_16x16x32_bf16 v[8:11], v[168:171], v[200:203], v[8:11]
	v_mfma_f32_16x16x32_bf16 v[4:7], v[148:151], v[208:211], v[4:7]
	v_mfma_f32_16x16x32_bf16 v[0:3], v[168:171], v[208:211], v[0:3]
	s_barrier
	s_add_u32 s44, s44, 0x100
	s_addc_u32 s45, s45, 0
	s_add_u32 s55, s55, 0x100
	s_addc_u32 s82, s82, 0
	s_cmp_ge_u32 s83, s51
	s_mov_b32 s14, s83
	s_cbranch_scc0 .LBB0_528

; #define G_STAGE(bufoff, gbase, voff) do { _Pragma("unroll") for (int _i = 0; _i < 2; ++_i) \
;         __builtin_amdgcn_global_load_lds((const unsigned*)((const char*)(gbase) + voff[_i]), (LAS unsigned*)(lds + (bufoff) + ldsw + _i * 8192), 16, 0, 0); } while (0)
; #define G_LDA(dst, b, h) do { _Pragma("unroll") for (int m = 0; m < 4; ++m) _Pragma("unroll") for (int k = 0; k < 2; ++k) dst[m][k] = *(const LAS bf16x8*)(lds + G_SA(b, h) + aoff + m * 2048 + k * 1024); } while (0)
; #define G_LDB(dst, b, h) do { _Pragma("unroll") for (int n = 0; n < 2; ++n) _Pragma("unroll") for (int k = 0; k < 2; ++k) dst[n][k] = *(const LAS bf16x8*)(lds + G_SB(b, h) + boff + n * 2048 + k * 1024); } while (0)
; template <class Get, class Epi>
; DI void gemm_loop(int ntiles, int ld, char* shm, const Get& get, const Epi& epi) {
;     ...
;     for (;;) {
;         const int Ln = L + gridDim.x; const bool has_next = Ln < ntiles; if (has_next) nxt = get(Ln);
;         const char* nA = has_next ? (const char*)nxt.A + (size_t)nxt.brow * ld * 2 : cA; const char* nB = has_next ? (const char*)nxt.Bt + (size_t)nxt.bcol * ld * 2 : cB;
;         const int nt = cur.K / BK;
;         for (int t = 0; t < nt; t += 2) {
;             const bool last = (t == nt - 2);
;             const char* a1 = cA + (size_t)(t + 1) * kstep;
;             const char* a2 = last ? nA : cA + (size_t)(t + 2) * kstep; const char* b2 = last ? nB : cB + (size_t)(t + 2) * kstep;
;             const char* a3 = a2 + kstep; const char* b3 = b2 + kstep;
;             G_LDB(B0, 0, 0); G_LDB(B1, 0, 1); SCHED; G_LDA(At, 0, 0); G_STAGE(G_SA(1, 1), a1 + hstep, voffA);
;             WAIT_V(8); WAIT_L(0); BAR; G_MMA(0, 0, At, B0); G_MMA(0, 1, At, B1); BAR; SCHED;
;             G_LDA(At, 0, 1); G_STAGE(G_SB(0, 0), b2, voffB); G_STAGE(G_SB(0, 1), b2 + hstep, voffB); G_STAGE(G_SA(0, 0), a2, voffA);
;             WAIT_V(8); WAIT_L(0); BAR; G_MMA(1, 0, At, B0); G_MMA(1, 1, At, B1); BAR; SCHED;
;             G_LDB(B0, 1, 0); G_LDB(B1, 1, 1); SCHED; G_LDA(At, 1, 0); G_STAGE(G_SA(0, 1), a2 + hstep, voffA);
;             WAIT_V(8); WAIT_L(0); BAR; G_MMA(0, 0, At, B0); G_MMA(0, 1, At, B1); BAR; SCHED;
;             G_LDA(At, 1, 1); G_STAGE(G_SB(1, 0), b3, voffB); G_STAGE(G_SB(1, 1), b3 + hstep, voffB); G_STAGE(G_SA(1, 0), a3, voffA);
;             WAIT_V(8); WAIT_L(0); BAR; G_MMA(1, 0, At, B0); G_MMA(1, 1, At, B1); BAR; SCHED;
.Lrj_763_0:
	s_waitcnt lgkmcnt(0)
	s_barrier
	s_waitcnt lgkmcnt(0)
	v_mfma_f32_16x16x32_bf16 v[124:127], v[144:147], v[176:179], 0
	v_mfma_f32_16x16x32_bf16 v[120:123], v[152:155], v[176:179], 0
	v_mfma_f32_16x16x32_bf16 v[108:111], v[144:147], v[188:191], 0
	v_mfma_f32_16x16x32_bf16 v[104:107], v[152:155], v[188:191], 0
	v_mfma_f32_16x16x32_bf16 v[92:95], v[144:147], v[196:199], 0
	v_mfma_f32_16x16x32_bf16 v[88:91], v[152:155], v[196:199], 0
	v_mfma_f32_16x16x32_bf16 v[76:79], v[144:147], v[204:207], 0
	v_mfma_f32_16x16x32_bf16 v[72:75], v[152:155], v[204:207], 0
	v_mfma_f32_16x16x32_bf16 v[124:127], v[148:151], v[180:183], v[124:127]
	v_mfma_f32_16x16x32_bf16 v[120:123], v[156:159], v[180:183], v[120:123]
	v_mfma_f32_16x16x32_bf16 v[108:111], v[148:151], v[192:195], v[108:111]
	v_mfma_f32_16x16x32_bf16 v[104:107], v[156:159], v[192:195], v[104:107]
	v_mfma_f32_16x16x32_bf16 v[92:95], v[148:151], v[200:203], v[92:95]
	v_mfma_f32_16x16x32_bf16 v[88:91], v[156:159], v[200:203], v[88:91]
	v_mfma_f32_16x16x32_bf16 v[76:79], v[148:151], v[208:211], v[76:79]
	v_mfma_f32_16x16x32_bf16 v[72:75], v[156:159], v[208:211], v[72:75]
	v_mfma_f32_16x16x32_bf16 v[116:119], v[160:163], v[176:179], 0
	v_mfma_f32_16x16x32_bf16 v[112:115], v[168:171], v[176:179], 0
	v_mfma_f32_16x16x32_bf16 v[100:103], v[160:163], v[188:191], 0
	v_mfma_f32_16x16x32_bf16 v[96:99], v[168:171], v[188:191], 0
	v_mfma_f32_16x16x32_bf16 v[84:87], v[160:163], v[196:199], 0
	v_mfma_f32_16x16x32_bf16 v[80:83], v[168:171], v[196:199], 0
	v_mfma_f32_16x16x32_bf16 v[68:71], v[160:163], v[204:207], 0
	v_mfma_f32_16x16x32_bf16 v[64:67], v[168:171], v[204:207], 0
	v_mfma_f32_16x16x32_bf16 v[116:119], v[164:167], v[180:183], v[116:119]
	v_mfma_f32_16x16x32_bf16 v[112:115], v[172:175], v[180:183], v[112:115]
	v_mfma_f32_16x16x32_bf16 v[100:103], v[164:167], v[192:195], v[100:103]
	v_mfma_f32_16x16x32_bf16 v[96:99], v[172:175], v[192:195], v[96:99]
	v_mfma_f32_16x16x32_bf16 v[84:87], v[164:167], v[200:203], v[84:87]
	v_mfma_f32_16x16x32_bf16 v[80:83], v[172:175], v[200:203], v[80:83]
	v_mfma_f32_16x16x32_bf16 v[68:71], v[164:167], v[208:211], v[68:71]
	v_mfma_f32_16x16x32_bf16 v[64:67], v[172:175], v[208:211], v[64:67]
	s_barrier
	s_add_i32 s55, s45, s26
	v_lshl_add_u64 v[184:185], s[14:15], 0, v[132:133]
	s_mov_b32 m0, s55
	ds_read_b128 v[176:179], v143 offset:16384
	ds_read_b128 v[180:183], v143 offset:17408
	ds_read_b128 v[188:191], v143 offset:18432
	ds_read_b128 v[192:195], v143 offset:19456
	ds_read_b128 v[196:199], v143 offset:20480
	ds_read_b128 v[200:203], v143 offset:21504
	ds_read_b128 v[204:207], v143 offset:22528
	ds_read_b128 v[208:211], v143 offset:23552
	global_load_lds_dwordx4 v[184:185], off
	s_add_i32 m0, s55, 0x2000
	s_add_u32 s56, s14, 0x40000
	v_lshl_add_u64 v[186:187], s[14:15], 0, v[128:129]
	s_addc_u32 s57, s15, 0
	s_add_i32 s55, s46, s26
	global_load_lds_dwordx4 v[186:187], off
	v_lshl_add_u64 v[212:213], s[56:57], 0, v[132:133]
	s_mov_b32 m0, s55
	v_lshl_add_u64 v[214:215], s[38:39], 0, v[130:131]
	global_load_lds_dwordx4 v[212:213], off
	v_lshl_add_u64 v[212:213], s[56:57], 0, v[128:129]
	s_add_i32 m0, s55, 0x2000
	s_nop 0
	global_load_lds_dwordx4 v[212:213], off
	v_lshl_add_u64 v[212:213], s[38:39], 0, v[134:135]
	s_mov_b32 m0, s31
	s_nop 0
	global_load_lds_dwordx4 v[212:213], off
	s_mov_b32 m0, s35
	s_nop 0
	global_load_lds_dwordx4 v[214:215], off
	s_cmp_lg_u32 s100, 0
	s_cbranch_scc0 .Lrf_763_1
	s_waitcnt vmcnt(16)
	s_branch .Lrj_763_1

; #define G_STAGE(bufoff, gbase, voff) do { _Pragma("unroll") for (int _i = 0; _i < 2; ++_i) \
;         __builtin_amdgcn_global_load_lds((const unsigned*)((const char*)(gbase) + voff[_i]), (LAS unsigned*)(lds + (bufoff) + ldsw + _i * 8192), 16, 0, 0); } while (0)
; #define G_LDA(dst, b, h) do { _Pragma("unroll") for (int m = 0; m < 4; ++m) _Pragma("unroll") for (int k = 0; k < 2; ++k) dst[m][k] = *(const LAS bf16x8*)(lds + G_SA(b, h) + aoff + m * 2048 + k * 1024); } while (0)
; #define G_LDB(dst, b, h) do { _Pragma("unroll") for (int n = 0; n < 2; ++n) _Pragma("unroll") for (int k = 0; k < 2; ++k) dst[n][k] = *(const LAS bf16x8*)(lds + G_SB(b, h) + boff + n * 2048 + k * 1024); } while (0)
; template <class Get, class Epi>
; DI void gemm_loop(int ntiles, int ld, char* shm, const Get& get, const Epi& epi) {
;     ...
;     for (;;) {
;         const int Ln = L + gridDim.x; const bool has_next = Ln < ntiles; if (has_next) nxt = get(Ln);
;         const char* nA = has_next ? (const char*)nxt.A + (size_t)nxt.brow * ld * 2 : cA; const char* nB = has_next ? (const char*)nxt.Bt + (size_t)nxt.bcol * ld * 2 : cB;
;         const int nt = cur.K / BK;
;         for (int t = 0; t < nt; t += 2) {
;             const bool last = (t == nt - 2);
;             const char* a1 = cA + (size_t)(t + 1) * kstep;
;             const char* a2 = last ? nA : cA + (size_t)(t + 2) * kstep; const char* b2 = last ? nB : cB + (size_t)(t + 2) * kstep;
;             const char* a3 = a2 + kstep; const char* b3 = b2 + kstep;
;             G_LDB(B0, 0, 0); G_LDB(B1, 0, 1); SCHED; G_LDA(At, 0, 0); G_STAGE(G_SA(1, 1), a1 + hstep, voffA);
;             WAIT_V(8); WAIT_L(0); BAR; G_MMA(0, 0, At, B0); G_MMA(0, 1, At, B1); BAR; SCHED;
;             G_LDA(At, 0, 1); G_STAGE(G_SB(0, 0), b2, voffB); G_STAGE(G_SB(0, 1), b2 + hstep, voffB); G_STAGE(G_SA(0, 0), a2, voffA);
;             WAIT_V(8); WAIT_L(0); BAR; G_MMA(1, 0, At, B0); G_MMA(1, 1, At, B1); BAR; SCHED;
;             G_LDB(B0, 1, 0); G_LDB(B1, 1, 1); SCHED; G_LDA(At, 1, 0); G_STAGE(G_SA(0, 1), a2 + hstep, voffA);
;             WAIT_V(8); WAIT_L(0); BAR; G_MMA(0, 0, At, B0); G_MMA(0, 1, At, B1); BAR; SCHED;
;             G_LDA(At, 1, 1); G_STAGE(G_SB(1, 0), b3, voffB); G_STAGE(G_SB(1, 1), b3 + hstep, voffB); G_STAGE(G_SA(1, 0), a3, voffA);
;             WAIT_V(8); WAIT_L(0); BAR; G_MMA(1, 0, At, B0); G_MMA(1, 1, At, B1); BAR; SCHED;
.Lrj_763_1:
	s_waitcnt lgkmcnt(0)
	s_barrier
	s_waitcnt lgkmcnt(0)
	v_mfma_f32_16x16x32_bf16 v[60:63], v[144:147], v[176:179], 0
	v_mfma_f32_16x16x32_bf16 v[56:59], v[152:155], v[176:179], 0
	v_mfma_f32_16x16x32_bf16 v[44:47], v[144:147], v[188:191], 0
	v_mfma_f32_16x16x32_bf16 v[40:43], v[152:155], v[188:191], 0
	v_mfma_f32_16x16x32_bf16 v[28:31], v[144:147], v[196:199], 0
	v_mfma_f32_16x16x32_bf16 v[24:27], v[152:155], v[196:199], 0
	v_mfma_f32_16x16x32_bf16 v[12:15], v[144:147], v[204:207], 0
	v_mfma_f32_16x16x32_bf16 v[8:11], v[152:155], v[204:207], 0
	v_mfma_f32_16x16x32_bf16 v[60:63], v[148:151], v[180:183], v[60:63]
	v_mfma_f32_16x16x32_bf16 v[56:59], v[156:159], v[180:183], v[56:59]
	v_mfma_f32_16x16x32_bf16 v[44:47], v[148:151], v[192:195], v[44:47]
	v_mfma_f32_16x16x32_bf16 v[40:43], v[156:159], v[192:195], v[40:43]
	v_mfma_f32_16x16x32_bf16 v[28:31], v[148:151], v[200:203], v[28:31]
	v_mfma_f32_16x16x32_bf16 v[24:27], v[156:159], v[200:203], v[24:27]
	v_mfma_f32_16x16x32_bf16 v[12:15], v[148:151], v[208:211], v[12:15]
	v_mfma_f32_16x16x32_bf16 v[8:11], v[156:159], v[208:211], v[8:11]
	v_mfma_f32_16x16x32_bf16 v[52:55], v[160:163], v[176:179], 0
	v_mfma_f32_16x16x32_bf16 v[48:51], v[168:171], v[176:179], 0
	v_mfma_f32_16x16x32_bf16 v[36:39], v[160:163], v[188:191], 0
	v_mfma_f32_16x16x32_bf16 v[32:35], v[168:171], v[188:191], 0
	v_mfma_f32_16x16x32_bf16 v[20:23], v[160:163], v[196:199], 0
	v_mfma_f32_16x16x32_bf16 v[16:19], v[168:171], v[196:199], 0
	v_mfma_f32_16x16x32_bf16 v[4:7], v[160:163], v[204:207], 0
	v_mfma_f32_16x16x32_bf16 v[0:3], v[168:171], v[204:207], 0
	v_mfma_f32_16x16x32_bf16 v[52:55], v[164:167], v[180:183], v[52:55]
	v_mfma_f32_16x16x32_bf16 v[48:51], v[172:175], v[180:183], v[48:51]
	v_mfma_f32_16x16x32_bf16 v[36:39], v[164:167], v[192:195], v[36:39]
	v_mfma_f32_16x16x32_bf16 v[32:35], v[172:175], v[192:195], v[32:35]
	v_mfma_f32_16x16x32_bf16 v[20:23], v[164:167], v[200:203], v[20:23]
	v_mfma_f32_16x16x32_bf16 v[16:19], v[172:175], v[200:203], v[16:19]
	v_mfma_f32_16x16x32_bf16 v[4:7], v[164:167], v[208:211], v[4:7]
	v_mfma_f32_16x16x32_bf16 v[0:3], v[172:175], v[208:211], v[0:3]
	s_barrier
	s_add_i32 s55, 0, 0x18000
	s_add_i32 s56, 0, 0x1c000
	v_add_u32_e32 v156, s55, v140
	v_add_u32_e32 v172, s56, v140
	ds_read_b128 v[144:147], v156
	ds_read_b128 v[148:151], v156 offset:1024
	ds_read_b128 v[152:155], v156 offset:2048
	ds_read_b128 v[156:159], v156 offset:3072
	ds_read_b128 v[160:163], v172
	ds_read_b128 v[164:167], v172 offset:1024
	ds_read_b128 v[168:171], v172 offset:2048
	ds_read_b128 v[172:175], v172 offset:3072
	s_add_u32 s38, s38, 0x40000
	s_addc_u32 s39, s39, 0
	s_mov_b32 m0, s41
	v_lshl_add_u64 v[216:217], s[38:39], 0, v[134:135]
	ds_read_b128 v[176:179], v143 offset:32768
	ds_read_b128 v[180:183], v143 offset:33792
	ds_read_b128 v[188:191], v143 offset:34816
	ds_read_b128 v[192:195], v143 offset:35840
	ds_read_b128 v[196:199], v143 offset:36864
	ds_read_b128 v[200:203], v143 offset:37888
	ds_read_b128 v[204:207], v143 offset:38912
	ds_read_b128 v[208:211], v143 offset:39936
	global_load_lds_dwordx4 v[216:217], off
	v_lshl_add_u64 v[216:217], s[38:39], 0, v[130:131]
	s_mov_b32 m0, s42
	s_nop 0
	global_load_lds_dwordx4 v[216:217], off
	s_waitcnt vmcnt(8)
	s_waitcnt lgkmcnt(0)
	s_barrier
	s_waitcnt lgkmcnt(0)
	v_mfma_f32_16x16x32_bf16 v[124:127], v[144:147], v[176:179], v[124:127]
	v_mfma_f32_16x16x32_bf16 v[120:123], v[152:155], v[176:179], v[120:123]
	v_mfma_f32_16x16x32_bf16 v[108:111], v[144:147], v[188:191], v[108:111]
	v_mfma_f32_16x16x32_bf16 v[104:107], v[152:155], v[188:191], v[104:107]
	v_mfma_f32_16x16x32_bf16 v[92:95], v[144:147], v[196:199], v[92:95]
	v_mfma_f32_16x16x32_bf16 v[88:91], v[152:155], v[196:199], v[88:91]
	v_mfma_f32_16x16x32_bf16 v[76:79], v[144:147], v[204:207], v[76:79]
	v_mfma_f32_16x16x32_bf16 v[72:75], v[152:155], v[204:207], v[72:75]
	v_mfma_f32_16x16x32_bf16 v[124:127], v[148:151], v[180:183], v[124:127]
	v_mfma_f32_16x16x32_bf16 v[120:123], v[156:159], v[180:183], v[120:123]
	v_mfma_f32_16x16x32_bf16 v[108:111], v[148:151], v[192:195], v[108:111]
	v_mfma_f32_16x16x32_bf16 v[104:107], v[156:159], v[192:195], v[104:107]
	v_mfma_f32_16x16x32_bf16 v[92:95], v[148:151], v[200:203], v[92:95]
	v_mfma_f32_16x16x32_bf16 v[88:91], v[156:159], v[200:203], v[88:91]
	v_mfma_f32_16x16x32_bf16 v[76:79], v[148:151], v[208:211], v[76:79]
	v_mfma_f32_16x16x32_bf16 v[72:75], v[156:159], v[208:211], v[72:75]
	v_mfma_f32_16x16x32_bf16 v[116:119], v[160:163], v[176:179], v[116:119]
	v_mfma_f32_16x16x32_bf16 v[112:115], v[168:171], v[176:179], v[112:115]
	v_mfma_f32_16x16x32_bf16 v[100:103], v[160:163], v[188:191], v[100:103]
	v_mfma_f32_16x16x32_bf16 v[96:99], v[168:171], v[188:191], v[96:99]
	v_mfma_f32_16x16x32_bf16 v[84:87], v[160:163], v[196:199], v[84:87]
	v_mfma_f32_16x16x32_bf16 v[80:83], v[168:171], v[196:199], v[80:83]
	v_mfma_f32_16x16x32_bf16 v[68:71], v[160:163], v[204:207], v[68:71]
	v_mfma_f32_16x16x32_bf16 v[64:67], v[168:171], v[204:207], v[64:67]
	v_mfma_f32_16x16x32_bf16 v[116:119], v[164:167], v[180:183], v[116:119]
	v_mfma_f32_16x16x32_bf16 v[112:115], v[172:175], v[180:183], v[112:115]
	v_mfma_f32_16x16x32_bf16 v[100:103], v[164:167], v[192:195], v[100:103]
	v_mfma_f32_16x16x32_bf16 v[96:99], v[172:175], v[192:195], v[96:99]
	v_mfma_f32_16x16x32_bf16 v[84:87], v[164:167], v[200:203], v[84:87]
	v_mfma_f32_16x16x32_bf16 v[80:83], v[172:175], v[200:203], v[80:83]
	v_mfma_f32_16x16x32_bf16 v[68:71], v[164:167], v[208:211], v[68:71]
	v_mfma_f32_16x16x32_bf16 v[64:67], v[172:175], v[208:211], v[64:67]
	s_barrier
; #define G_STAGE(bufoff, gbase, voff) do { _Pragma("unroll") for (int _i = 0; _i < 2; ++_i) \
;         __builtin_amdgcn_global_load_lds((const unsigned*)((const char*)(gbase) + voff[_i]), (LAS unsigned*)(lds + (bufoff) + ldsw + _i * 8192), 16, 0, 0); } while (0)
; #define G_LDA(dst, b, h) do { _Pragma("unroll") for (int m = 0; m < 4; ++m) _Pragma("unroll") for (int k = 0; k < 2; ++k) dst[m][k] = *(const LAS bf16x8*)(lds + G_SA(b, h) + aoff + m * 2048 + k * 1024); } while (0)
; #define G_LDB(dst, b, h) do { _Pragma("unroll") for (int n = 0; n < 2; ++n) _Pragma("unroll") for (int k = 0; k < 2; ++k) dst[n][k] = *(const LAS bf16x8*)(lds + G_SB(b, h) + boff + n * 2048 + k * 1024); } while (0)
; #define WAIT_V(n) asm volatile("s_waitcnt vmcnt(" #n ")" ::: "memory")
; #define WAIT_L(n) asm volatile("s_waitcnt lgkmcnt(" #n ")" ::: "memory")
; #define BAR __builtin_amdgcn_s_barrier()
; #define SCHED __builtin_amdgcn_sched_barrier(0)
; template <class Get, class Epi>
; DI void gemm_loop(int ntiles, int ld, char* shm, const Get& get, const Epi& epi) {
;     ...
;         for (int t = 0; t < nt; t += 2) {
;             const bool last = (t == nt - 2);
;             const char* a1 = cA + (size_t)(t + 1) * kstep;
;             const char* a2 = last ? nA : cA + (size_t)(t + 2) * kstep; const char* b2 = last ? nB : cB + (size_t)(t + 2) * kstep;
;             const char* a3 = a2 + kstep; const char* b3 = b2 + kstep;
;             G_LDB(B0, 0, 0); G_LDB(B1, 0, 1); SCHED; G_LDA(At, 0, 0); G_STAGE(G_SA(1, 1), a1 + hstep, voffA);
;             WAIT_V(8); WAIT_L(0); BAR; G_MMA(0, 0, At, B0); G_MMA(0, 1, At, B1); BAR; SCHED;
;             G_LDA(At, 0, 1); G_STAGE(G_SB(0, 0), b2, voffB); G_STAGE(G_SB(0, 1), b2 + hstep, voffB); G_STAGE(G_SA(0, 0), a2, voffA);
;             WAIT_V(8); WAIT_L(0); BAR; G_MMA(1, 0, At, B0); G_MMA(1, 1, At, B1); BAR; SCHED;
;             G_LDB(B0, 1, 0); G_LDB(B1, 1, 1); SCHED; G_LDA(At, 1, 0); G_STAGE(G_SA(0, 1), a2 + hstep, voffA);
;             WAIT_V(8); WAIT_L(0); BAR; G_MMA(0, 0, At, B0); G_MMA(0, 1, At, B1); BAR; SCHED;
;             G_LDA(At, 1, 1); G_STAGE(G_SB(1, 0), b3, voffB); G_STAGE(G_SB(1, 1), b3 + hstep, voffB); G_STAGE(G_SA(1, 0), a3, voffA);
;             WAIT_V(8); WAIT_L(0); BAR; G_MMA(1, 0, At, B0); G_MMA(1, 1, At, B1); BAR; SCHED;
	s_add_i32 s38, s55, s26
	v_lshl_add_u64 v[184:185], v[184:185], 0, s[2:3]
	s_mov_b32 m0, s38
	ds_read_b128 v[176:179], v143 offset:49152
	ds_read_b128 v[180:183], v143 offset:50176
	ds_read_b128 v[188:191], v143 offset:51200
	ds_read_b128 v[192:195], v143 offset:52224
	ds_read_b128 v[196:199], v143 offset:53248
	ds_read_b128 v[200:203], v143 offset:54272
	ds_read_b128 v[204:207], v143 offset:55296
	ds_read_b128 v[208:211], v143 offset:56320
	global_load_lds_dwordx4 v[184:185], off
	s_add_i32 m0, s38, 0x2000
	s_add_u32 s14, s14, 0x40080
	v_lshl_add_u64 v[184:185], v[186:187], 0, s[2:3]
	s_addc_u32 s15, s15, 0
	s_add_i32 s38, s56, s26
	global_load_lds_dwordx4 v[184:185], off
	v_lshl_add_u64 v[184:185], s[14:15], 0, v[132:133]
	s_mov_b32 m0, s38
	s_nop 0
	global_load_lds_dwordx4 v[184:185], off
	v_lshl_add_u64 v[184:185], s[14:15], 0, v[128:129]
	s_add_i32 m0, s38, 0x2000
	s_nop 0
	global_load_lds_dwordx4 v[184:185], off
	v_lshl_add_u64 v[184:185], v[212:213], 0, s[2:3]
	s_mov_b32 m0, s43
	s_nop 0
	global_load_lds_dwordx4 v[184:185], off
	v_lshl_add_u64 v[184:185], v[214:215], 0, s[2:3]
	s_mov_b32 m0, s44
	s_nop 0
	global_load_lds_dwordx4 v[184:185], off
	s_waitcnt vmcnt(8)
	s_waitcnt lgkmcnt(0)
	s_barrier
	s_waitcnt lgkmcnt(0)
	v_mfma_f32_16x16x32_bf16 v[60:63], v[144:147], v[176:179], v[60:63]
	v_mfma_f32_16x16x32_bf16 v[56:59], v[152:155], v[176:179], v[56:59]
	v_mfma_f32_16x16x32_bf16 v[44:47], v[144:147], v[188:191], v[44:47]
	v_mfma_f32_16x16x32_bf16 v[40:43], v[152:155], v[188:191], v[40:43]
	v_mfma_f32_16x16x32_bf16 v[28:31], v[144:147], v[196:199], v[28:31]
	v_mfma_f32_16x16x32_bf16 v[24:27], v[152:155], v[196:199], v[24:27]
	v_mfma_f32_16x16x32_bf16 v[12:15], v[144:147], v[204:207], v[12:15]
	v_mfma_f32_16x16x32_bf16 v[8:11], v[152:155], v[204:207], v[8:11]
	v_mfma_f32_16x16x32_bf16 v[60:63], v[148:151], v[180:183], v[60:63]
	v_mfma_f32_16x16x32_bf16 v[56:59], v[156:159], v[180:183], v[56:59]
	v_mfma_f32_16x16x32_bf16 v[44:47], v[148:151], v[192:195], v[44:47]
	v_mfma_f32_16x16x32_bf16 v[40:43], v[156:159], v[192:195], v[40:43]
	v_mfma_f32_16x16x32_bf16 v[28:31], v[148:151], v[200:203], v[28:31]
	v_mfma_f32_16x16x32_bf16 v[24:27], v[156:159], v[200:203], v[24:27]
	v_mfma_f32_16x16x32_bf16 v[12:15], v[148:151], v[208:211], v[12:15]
	v_mfma_f32_16x16x32_bf16 v[8:11], v[156:159], v[208:211], v[8:11]
	v_mfma_f32_16x16x32_bf16 v[52:55], v[160:163], v[176:179], v[52:55]
	v_mfma_f32_16x16x32_bf16 v[48:51], v[168:171], v[176:179], v[48:51]
	v_mfma_f32_16x16x32_bf16 v[36:39], v[160:163], v[188:191], v[36:39]
	v_mfma_f32_16x16x32_bf16 v[32:35], v[168:171], v[188:191], v[32:35]
	v_mfma_f32_16x16x32_bf16 v[20:23], v[160:163], v[196:199], v[20:23]
	v_mfma_f32_16x16x32_bf16 v[16:19], v[168:171], v[196:199], v[16:19]
	v_mfma_f32_16x16x32_bf16 v[4:7], v[160:163], v[204:207], v[4:7]
	v_mfma_f32_16x16x32_bf16 v[0:3], v[168:171], v[204:207], v[0:3]
	v_mfma_f32_16x16x32_bf16 v[52:55], v[164:167], v[180:183], v[52:55]
	v_mfma_f32_16x16x32_bf16 v[48:51], v[172:175], v[180:183], v[48:51]
	v_mfma_f32_16x16x32_bf16 v[36:39], v[164:167], v[192:195], v[36:39]
	v_mfma_f32_16x16x32_bf16 v[32:35], v[172:175], v[192:195], v[32:35]
	v_mfma_f32_16x16x32_bf16 v[20:23], v[164:167], v[200:203], v[20:23]
	v_mfma_f32_16x16x32_bf16 v[16:19], v[172:175], v[200:203], v[16:19]
	v_mfma_f32_16x16x32_bf16 v[4:7], v[164:167], v[208:211], v[4:7]
	v_mfma_f32_16x16x32_bf16 v[0:3], v[172:175], v[208:211], v[0:3]
	s_barrier
	s_add_i32 s54, s54, 2
	s_add_u32 s36, s36, 0x100
	s_addc_u32 s37, s37, 0
	s_add_u32 s52, s52, 0x100
	s_addc_u32 s53, s53, 0
	s_cmp_gt_u32 s54, 13
	s_cbranch_scc0 .LBB0_763
	s_branch .Lpost_763
.LBB0_763:
	ds_read_b128 v[144:147], v141
	ds_read_b128 v[148:151], v141 offset:1024
	ds_read_b128 v[152:155], v141 offset:2048
	ds_read_b128 v[156:159], v141 offset:3072
	ds_read_b128 v[160:163], v142
	ds_read_b128 v[164:167], v142 offset:1024
	ds_read_b128 v[168:171], v142 offset:2048
	ds_read_b128 v[172:175], v142 offset:3072
	s_add_u32 s14, s36, 0xfffc0080
	s_addc_u32 s15, s37, -1
	s_cmp_eq_u32 s54, 12
	s_cselect_b32 s39, s9, s15
	s_cselect_b32 s38, s50, s14
	s_cselect_b32 s15, s11, s53
	s_cselect_b32 s14, s51, s52
	v_lshl_add_u64 v[184:185], s[36:37], 0, v[136:137]
	s_add_i32 m0, s31, 0xc000
	ds_read_b128 v[176:179], v143
	ds_read_b128 v[180:183], v143 offset:1024
	ds_read_b128 v[188:191], v143 offset:2048
	ds_read_b128 v[192:195], v143 offset:3072
	ds_read_b128 v[196:199], v143 offset:4096
	ds_read_b128 v[200:203], v143 offset:5120
	ds_read_b128 v[204:207], v143 offset:6144
	ds_read_b128 v[208:211], v143 offset:7168
	global_load_lds_dwordx4 v[184:185], off
	v_lshl_add_u64 v[184:185], s[36:37], 0, v[138:139]
	s_add_i32 m0, s31, 0xe000
	s_nop 0
	global_load_lds_dwordx4 v[184:185], off
	s_waitcnt vmcnt(8)
	s_waitcnt lgkmcnt(0)
	s_barrier
; #define G_STAGE(bufoff, gbase, voff) do { _Pragma("unroll") for (int _i = 0; _i < 2; ++_i) \
;         __builtin_amdgcn_global_load_lds((const unsigned*)((const char*)(gbase) + voff[_i]), (LAS unsigned*)(lds + (bufoff) + ldsw + _i * 8192), 16, 0, 0); } while (0)
; #define G_LDA(dst, b, h) do { _Pragma("unroll") for (int m = 0; m < 4; ++m) _Pragma("unroll") for (int k = 0; k < 2; ++k) dst[m][k] = *(const LAS bf16x8*)(lds + G_SA(b, h) + aoff + m * 2048 + k * 1024); } while (0)
; #define G_LDB(dst, b, h) do { _Pragma("unroll") for (int n = 0; n < 2; ++n) _Pragma("unroll") for (int k = 0; k < 2; ++k) dst[n][k] = *(const LAS bf16x8*)(lds + G_SB(b, h) + boff + n * 2048 + k * 1024); } while (0)
; #define WAIT_V(n) asm volatile("s_waitcnt vmcnt(" #n ")" ::: "memory")
; #define WAIT_L(n) asm volatile("s_waitcnt lgkmcnt(" #n ")" ::: "memory")
; #define BAR __builtin_amdgcn_s_barrier()
; #define SCHED __builtin_amdgcn_sched_barrier(0)
; template <class Get, class Epi>
; DI void gemm_loop(int ntiles, int ld, char* shm, const Get& get, const Epi& epi) {
;     ...
;         for (int t = 0; t < nt; t += 2) {
;             const bool last = (t == nt - 2);
;             const char* a1 = cA + (size_t)(t + 1) * kstep;
;             const char* a2 = last ? nA : cA + (size_t)(t + 2) * kstep; const char* b2 = last ? nB : cB + (size_t)(t + 2) * kstep;
;             const char* a3 = a2 + kstep; const char* b3 = b2 + kstep;
;             G_LDB(B0, 0, 0); G_LDB(B1, 0, 1); SCHED; G_LDA(At, 0, 0); G_STAGE(G_SA(1, 1), a1 + hstep, voffA);
;             WAIT_V(8); WAIT_L(0); BAR; G_MMA(0, 0, At, B0); G_MMA(0, 1, At, B1); BAR; SCHED;
;             G_LDA(At, 0, 1); G_STAGE(G_SB(0, 0), b2, voffB); G_STAGE(G_SB(0, 1), b2 + hstep, voffB); G_STAGE(G_SA(0, 0), a2, voffA);
;             WAIT_V(8); WAIT_L(0); BAR; G_MMA(1, 0, At, B0); G_MMA(1, 1, At, B1); BAR; SCHED;
;             G_LDB(B0, 1, 0); G_LDB(B1, 1, 1); SCHED; G_LDA(At, 1, 0); G_STAGE(G_SA(0, 1), a2 + hstep, voffA);
;             WAIT_V(8); WAIT_L(0); BAR; G_MMA(0, 0, At, B0); G_MMA(0, 1, At, B1); BAR; SCHED;
;             G_LDA(At, 1, 1); G_STAGE(G_SB(1, 0), b3, voffB); G_STAGE(G_SB(1, 1), b3 + hstep, voffB); G_STAGE(G_SA(1, 0), a3, voffA);
;             WAIT_V(8); WAIT_L(0); BAR; G_MMA(1, 0, At, B0); G_MMA(1, 1, At, B1); BAR; SCHED;
	s_waitcnt lgkmcnt(0)
	v_mfma_f32_16x16x32_bf16 v[124:127], v[144:147], v[176:179], v[124:127]
	v_mfma_f32_16x16x32_bf16 v[120:123], v[152:155], v[176:179], v[120:123]
	v_mfma_f32_16x16x32_bf16 v[108:111], v[144:147], v[188:191], v[108:111]
	v_mfma_f32_16x16x32_bf16 v[104:107], v[152:155], v[188:191], v[104:107]
	v_mfma_f32_16x16x32_bf16 v[92:95], v[144:147], v[196:199], v[92:95]
	v_mfma_f32_16x16x32_bf16 v[88:91], v[152:155], v[196:199], v[88:91]
	v_mfma_f32_16x16x32_bf16 v[76:79], v[144:147], v[204:207], v[76:79]
	v_mfma_f32_16x16x32_bf16 v[72:75], v[152:155], v[204:207], v[72:75]
	v_mfma_f32_16x16x32_bf16 v[124:127], v[148:151], v[180:183], v[124:127]
	v_mfma_f32_16x16x32_bf16 v[120:123], v[156:159], v[180:183], v[120:123]
	v_mfma_f32_16x16x32_bf16 v[108:111], v[148:151], v[192:195], v[108:111]
	v_mfma_f32_16x16x32_bf16 v[104:107], v[156:159], v[192:195], v[104:107]
	v_mfma_f32_16x16x32_bf16 v[92:95], v[148:151], v[200:203], v[92:95]
	v_mfma_f32_16x16x32_bf16 v[88:91], v[156:159], v[200:203], v[88:91]
	v_mfma_f32_16x16x32_bf16 v[76:79], v[148:151], v[208:211], v[76:79]
	v_mfma_f32_16x16x32_bf16 v[72:75], v[156:159], v[208:211], v[72:75]
	v_mfma_f32_16x16x32_bf16 v[116:119], v[160:163], v[176:179], v[116:119]
	v_mfma_f32_16x16x32_bf16 v[112:115], v[168:171], v[176:179], v[112:115]
	v_mfma_f32_16x16x32_bf16 v[100:103], v[160:163], v[188:191], v[100:103]
	v_mfma_f32_16x16x32_bf16 v[96:99], v[168:171], v[188:191], v[96:99]
	v_mfma_f32_16x16x32_bf16 v[84:87], v[160:163], v[196:199], v[84:87]
	v_mfma_f32_16x16x32_bf16 v[80:83], v[168:171], v[196:199], v[80:83]
	v_mfma_f32_16x16x32_bf16 v[68:71], v[160:163], v[204:207], v[68:71]
	v_mfma_f32_16x16x32_bf16 v[64:67], v[168:171], v[204:207], v[64:67]
	v_mfma_f32_16x16x32_bf16 v[116:119], v[164:167], v[180:183], v[116:119]
	v_mfma_f32_16x16x32_bf16 v[112:115], v[172:175], v[180:183], v[112:115]
	v_mfma_f32_16x16x32_bf16 v[100:103], v[164:167], v[192:195], v[100:103]
	v_mfma_f32_16x16x32_bf16 v[96:99], v[172:175], v[192:195], v[96:99]
	v_mfma_f32_16x16x32_bf16 v[84:87], v[164:167], v[200:203], v[84:87]
	v_mfma_f32_16x16x32_bf16 v[80:83], v[172:175], v[200:203], v[80:83]
	v_mfma_f32_16x16x32_bf16 v[68:71], v[164:167], v[208:211], v[68:71]
	v_mfma_f32_16x16x32_bf16 v[64:67], v[172:175], v[208:211], v[64:67]
	s_barrier
	s_add_i32 s55, s45, s26
	v_lshl_add_u64 v[184:185], s[14:15], 0, v[132:133]
	s_mov_b32 m0, s55
	ds_read_b128 v[176:179], v143 offset:16384
	ds_read_b128 v[180:183], v143 offset:17408
	ds_read_b128 v[188:191], v143 offset:18432
	ds_read_b128 v[192:195], v143 offset:19456
	ds_read_b128 v[196:199], v143 offset:20480
	ds_read_b128 v[200:203], v143 offset:21504
	ds_read_b128 v[204:207], v143 offset:22528
	ds_read_b128 v[208:211], v143 offset:23552
	global_load_lds_dwordx4 v[184:185], off
	s_add_i32 m0, s55, 0x2000
	s_add_u32 s56, s14, 0x40000
	v_lshl_add_u64 v[186:187], s[14:15], 0, v[128:129]
	s_addc_u32 s57, s15, 0
	s_add_i32 s55, s46, s26
	global_load_lds_dwordx4 v[186:187], off
	v_lshl_add_u64 v[212:213], s[56:57], 0, v[132:133]
	s_mov_b32 m0, s55
	v_lshl_add_u64 v[214:215], s[38:39], 0, v[130:131]
	global_load_lds_dwordx4 v[212:213], off
	v_lshl_add_u64 v[212:213], s[56:57], 0, v[128:129]
	s_add_i32 m0, s55, 0x2000
	s_nop 0
	global_load_lds_dwordx4 v[212:213], off
	v_lshl_add_u64 v[212:213], s[38:39], 0, v[134:135]
	s_mov_b32 m0, s31
	s_nop 0
	global_load_lds_dwordx4 v[212:213], off
	s_mov_b32 m0, s35
	s_nop 0
	global_load_lds_dwordx4 v[214:215], off
	s_waitcnt vmcnt(8)
	s_waitcnt lgkmcnt(0)
	s_barrier
	s_waitcnt lgkmcnt(0)
	v_mfma_f32_16x16x32_bf16 v[60:63], v[144:147], v[176:179], v[60:63]
	v_mfma_f32_16x16x32_bf16 v[56:59], v[152:155], v[176:179], v[56:59]
	v_mfma_f32_16x16x32_bf16 v[44:47], v[144:147], v[188:191], v[44:47]
	v_mfma_f32_16x16x32_bf16 v[40:43], v[152:155], v[188:191], v[40:43]
	v_mfma_f32_16x16x32_bf16 v[28:31], v[144:147], v[196:199], v[28:31]
	v_mfma_f32_16x16x32_bf16 v[24:27], v[152:155], v[196:199], v[24:27]
	v_mfma_f32_16x16x32_bf16 v[12:15], v[144:147], v[204:207], v[12:15]
	v_mfma_f32_16x16x32_bf16 v[8:11], v[152:155], v[204:207], v[8:11]
	v_mfma_f32_16x16x32_bf16 v[60:63], v[148:151], v[180:183], v[60:63]
	v_mfma_f32_16x16x32_bf16 v[56:59], v[156:159], v[180:183], v[56:59]
	v_mfma_f32_16x16x32_bf16 v[44:47], v[148:151], v[192:195], v[44:47]
	v_mfma_f32_16x16x32_bf16 v[40:43], v[156:159], v[192:195], v[40:43]
	v_mfma_f32_16x16x32_bf16 v[28:31], v[148:151], v[200:203], v[28:31]
	v_mfma_f32_16x16x32_bf16 v[24:27], v[156:159], v[200:203], v[24:27]
	v_mfma_f32_16x16x32_bf16 v[12:15], v[148:151], v[208:211], v[12:15]
	v_mfma_f32_16x16x32_bf16 v[8:11], v[156:159], v[208:211], v[8:11]
	v_mfma_f32_16x16x32_bf16 v[52:55], v[160:163], v[176:179], v[52:55]
	v_mfma_f32_16x16x32_bf16 v[48:51], v[168:171], v[176:179], v[48:51]
	v_mfma_f32_16x16x32_bf16 v[36:39], v[160:163], v[188:191], v[36:39]
	v_mfma_f32_16x16x32_bf16 v[32:35], v[168:171], v[188:191], v[32:35]
	v_mfma_f32_16x16x32_bf16 v[20:23], v[160:163], v[196:199], v[20:23]
	v_mfma_f32_16x16x32_bf16 v[16:19], v[168:171], v[196:199], v[16:19]
	v_mfma_f32_16x16x32_bf16 v[4:7], v[160:163], v[204:207], v[4:7]
	v_mfma_f32_16x16x32_bf16 v[0:3], v[168:171], v[204:207], v[0:3]
	v_mfma_f32_16x16x32_bf16 v[52:55], v[164:167], v[180:183], v[52:55]
	v_mfma_f32_16x16x32_bf16 v[48:51], v[172:175], v[180:183], v[48:51]
	v_mfma_f32_16x16x32_bf16 v[36:39], v[164:167], v[192:195], v[36:39]
	v_mfma_f32_16x16x32_bf16 v[32:35], v[172:175], v[192:195], v[32:35]
	v_mfma_f32_16x16x32_bf16 v[20:23], v[164:167], v[200:203], v[20:23]
	v_mfma_f32_16x16x32_bf16 v[16:19], v[172:175], v[200:203], v[16:19]
	v_mfma_f32_16x16x32_bf16 v[4:7], v[164:167], v[208:211], v[4:7]
	v_mfma_f32_16x16x32_bf16 v[0:3], v[172:175], v[208:211], v[0:3]
	s_barrier
; #define G_STAGE(bufoff, gbase, voff) do { _Pragma("unroll") for (int _i = 0; _i < 2; ++_i) \
;         __builtin_amdgcn_global_load_lds((const unsigned*)((const char*)(gbase) + voff[_i]), (LAS unsigned*)(lds + (bufoff) + ldsw + _i * 8192), 16, 0, 0); } while (0)
; #define G_LDA(dst, b, h) do { _Pragma("unroll") for (int m = 0; m < 4; ++m) _Pragma("unroll") for (int k = 0; k < 2; ++k) dst[m][k] = *(const LAS bf16x8*)(lds + G_SA(b, h) + aoff + m * 2048 + k * 1024); } while (0)
; #define G_LDB(dst, b, h) do { _Pragma("unroll") for (int n = 0; n < 2; ++n) _Pragma("unroll") for (int k = 0; k < 2; ++k) dst[n][k] = *(const LAS bf16x8*)(lds + G_SB(b, h) + boff + n * 2048 + k * 1024); } while (0)
; #define G_MMA(ai, bj, At_, Bt_) do { __builtin_amdgcn_s_setprio(1); _Pragma("unroll") for (int m = 0; m < 4; ++m) _Pragma("unroll") for (int n = 0; n < 2; ++n) _Pragma("unroll") for (int k = 0; k < 2; ++k) \
;         acc[ai][bj][m][n] = __builtin_amdgcn_mfma_f32_16x16x32_bf16(Bt_[n][k], At_[m][k], acc[ai][bj][m][n], 0, 0, 0); __builtin_amdgcn_s_setprio(0); } while (0)
; #define WAIT_V(n) asm volatile("s_waitcnt vmcnt(" #n ")" ::: "memory")
; #define WAIT_L(n) asm volatile("s_waitcnt lgkmcnt(" #n ")" ::: "memory")
; #define BAR __builtin_amdgcn_s_barrier()
; #define SCHED __builtin_amdgcn_sched_barrier(0)
; template <class Get, class Epi>
; DI void gemm_loop(int ntiles, int ld, char* shm, const Get& get, const Epi& epi) {
;     ...
;             G_LDB(B0, 1, 0); G_LDB(B1, 1, 1); SCHED; G_LDA(At, 1, 0); G_STAGE(G_SA(0, 1), a2 + hstep, voffA);
;             WAIT_V(8); WAIT_L(0); BAR; G_MMA(0, 0, At, B0); G_MMA(0, 1, At, B1); BAR; SCHED;
;             G_LDA(At, 1, 1); G_STAGE(G_SB(1, 0), b3, voffB); G_STAGE(G_SB(1, 1), b3 + hstep, voffB); G_STAGE(G_SA(1, 0), a3, voffA);
;             WAIT_V(8); WAIT_L(0); BAR; G_MMA(1, 0, At, B0); G_MMA(1, 1, At, B1); BAR; SCHED;
;         }
	s_add_i32 s55, 0, 0x18000
	s_add_i32 s56, 0, 0x1c000
	v_add_u32_e32 v156, s55, v140
	v_add_u32_e32 v172, s56, v140
	ds_read_b128 v[144:147], v156
	ds_read_b128 v[148:151], v156 offset:1024
	ds_read_b128 v[152:155], v156 offset:2048
	ds_read_b128 v[156:159], v156 offset:3072
	ds_read_b128 v[160:163], v172
	ds_read_b128 v[164:167], v172 offset:1024
	ds_read_b128 v[168:171], v172 offset:2048
	ds_read_b128 v[172:175], v172 offset:3072
	s_add_u32 s38, s38, 0x40000
	s_addc_u32 s39, s39, 0
	s_mov_b32 m0, s41
	v_lshl_add_u64 v[216:217], s[38:39], 0, v[134:135]
	ds_read_b128 v[176:179], v143 offset:32768
	ds_read_b128 v[180:183], v143 offset:33792
	ds_read_b128 v[188:191], v143 offset:34816
	ds_read_b128 v[192:195], v143 offset:35840
	ds_read_b128 v[196:199], v143 offset:36864
	ds_read_b128 v[200:203], v143 offset:37888
	ds_read_b128 v[204:207], v143 offset:38912
	ds_read_b128 v[208:211], v143 offset:39936
	global_load_lds_dwordx4 v[216:217], off
	v_lshl_add_u64 v[216:217], s[38:39], 0, v[130:131]
	s_mov_b32 m0, s42
	s_nop 0
	global_load_lds_dwordx4 v[216:217], off
	s_waitcnt vmcnt(8)
	s_waitcnt lgkmcnt(0)
	s_barrier
	s_waitcnt lgkmcnt(0)
	v_mfma_f32_16x16x32_bf16 v[124:127], v[144:147], v[176:179], v[124:127]
	v_mfma_f32_16x16x32_bf16 v[120:123], v[152:155], v[176:179], v[120:123]
	v_mfma_f32_16x16x32_bf16 v[108:111], v[144:147], v[188:191], v[108:111]
	v_mfma_f32_16x16x32_bf16 v[104:107], v[152:155], v[188:191], v[104:107]
	v_mfma_f32_16x16x32_bf16 v[92:95], v[144:147], v[196:199], v[92:95]
	v_mfma_f32_16x16x32_bf16 v[88:91], v[152:155], v[196:199], v[88:91]
	v_mfma_f32_16x16x32_bf16 v[76:79], v[144:147], v[204:207], v[76:79]
	v_mfma_f32_16x16x32_bf16 v[72:75], v[152:155], v[204:207], v[72:75]
	v_mfma_f32_16x16x32_bf16 v[124:127], v[148:151], v[180:183], v[124:127]
	v_mfma_f32_16x16x32_bf16 v[120:123], v[156:159], v[180:183], v[120:123]
	v_mfma_f32_16x16x32_bf16 v[108:111], v[148:151], v[192:195], v[108:111]
	v_mfma_f32_16x16x32_bf16 v[104:107], v[156:159], v[192:195], v[104:107]
	v_mfma_f32_16x16x32_bf16 v[92:95], v[148:151], v[200:203], v[92:95]
	v_mfma_f32_16x16x32_bf16 v[88:91], v[156:159], v[200:203], v[88:91]
	v_mfma_f32_16x16x32_bf16 v[76:79], v[148:151], v[208:211], v[76:79]
	v_mfma_f32_16x16x32_bf16 v[72:75], v[156:159], v[208:211], v[72:75]
	v_mfma_f32_16x16x32_bf16 v[116:119], v[160:163], v[176:179], v[116:119]
	v_mfma_f32_16x16x32_bf16 v[112:115], v[168:171], v[176:179], v[112:115]
	v_mfma_f32_16x16x32_bf16 v[100:103], v[160:163], v[188:191], v[100:103]
	v_mfma_f32_16x16x32_bf16 v[96:99], v[168:171], v[188:191], v[96:99]
	v_mfma_f32_16x16x32_bf16 v[84:87], v[160:163], v[196:199], v[84:87]
	v_mfma_f32_16x16x32_bf16 v[80:83], v[168:171], v[196:199], v[80:83]
	v_mfma_f32_16x16x32_bf16 v[68:71], v[160:163], v[204:207], v[68:71]
	v_mfma_f32_16x16x32_bf16 v[64:67], v[168:171], v[204:207], v[64:67]
	v_mfma_f32_16x16x32_bf16 v[116:119], v[164:167], v[180:183], v[116:119]
	v_mfma_f32_16x16x32_bf16 v[112:115], v[172:175], v[180:183], v[112:115]
	v_mfma_f32_16x16x32_bf16 v[100:103], v[164:167], v[192:195], v[100:103]
	v_mfma_f32_16x16x32_bf16 v[96:99], v[172:175], v[192:195], v[96:99]
	v_mfma_f32_16x16x32_bf16 v[84:87], v[164:167], v[200:203], v[84:87]
	v_mfma_f32_16x16x32_bf16 v[80:83], v[172:175], v[200:203], v[80:83]
	v_mfma_f32_16x16x32_bf16 v[68:71], v[164:167], v[208:211], v[68:71]
	v_mfma_f32_16x16x32_bf16 v[64:67], v[172:175], v[208:211], v[64:67]
	s_barrier
	s_add_i32 s38, s55, s26
	v_lshl_add_u64 v[184:185], v[184:185], 0, s[2:3]
	s_mov_b32 m0, s38
	ds_read_b128 v[176:179], v143 offset:49152
	ds_read_b128 v[180:183], v143 offset:50176
	ds_read_b128 v[188:191], v143 offset:51200
	ds_read_b128 v[192:195], v143 offset:52224
	ds_read_b128 v[196:199], v143 offset:53248
	ds_read_b128 v[200:203], v143 offset:54272
	ds_read_b128 v[204:207], v143 offset:55296
	ds_read_b128 v[208:211], v143 offset:56320
	global_load_lds_dwordx4 v[184:185], off
	s_add_i32 m0, s38, 0x2000
	s_add_u32 s14, s14, 0x40080
	v_lshl_add_u64 v[184:185], v[186:187], 0, s[2:3]
	s_addc_u32 s15, s15, 0
	s_add_i32 s38, s56, s26
	global_load_lds_dwordx4 v[184:185], off
	v_lshl_add_u64 v[184:185], s[14:15], 0, v[132:133]
	s_mov_b32 m0, s38
	s_nop 0
	global_load_lds_dwordx4 v[184:185], off
	v_lshl_add_u64 v[184:185], s[14:15], 0, v[128:129]
	s_add_i32 m0, s38, 0x2000
	s_nop 0
	global_load_lds_dwordx4 v[184:185], off
	v_lshl_add_u64 v[184:185], v[212:213], 0, s[2:3]
	s_mov_b32 m0, s43
	s_nop 0
	global_load_lds_dwordx4 v[184:185], off
	v_lshl_add_u64 v[184:185], v[214:215], 0, s[2:3]
	s_mov_b32 m0, s44
	s_nop 0
	global_load_lds_dwordx4 v[184:185], off
	s_waitcnt vmcnt(8)
	s_waitcnt lgkmcnt(0)
	s_barrier
	s_waitcnt lgkmcnt(0)
	v_mfma_f32_16x16x32_bf16 v[60:63], v[144:147], v[176:179], v[60:63]
	v_mfma_f32_16x16x32_bf16 v[56:59], v[152:155], v[176:179], v[56:59]
	v_mfma_f32_16x16x32_bf16 v[44:47], v[144:147], v[188:191], v[44:47]
	v_mfma_f32_16x16x32_bf16 v[40:43], v[152:155], v[188:191], v[40:43]
	v_mfma_f32_16x16x32_bf16 v[28:31], v[144:147], v[196:199], v[28:31]
	v_mfma_f32_16x16x32_bf16 v[24:27], v[152:155], v[196:199], v[24:27]
	v_mfma_f32_16x16x32_bf16 v[12:15], v[144:147], v[204:207], v[12:15]
	v_mfma_f32_16x16x32_bf16 v[8:11], v[152:155], v[204:207], v[8:11]
	v_mfma_f32_16x16x32_bf16 v[60:63], v[148:151], v[180:183], v[60:63]
	v_mfma_f32_16x16x32_bf16 v[56:59], v[156:159], v[180:183], v[56:59]
	v_mfma_f32_16x16x32_bf16 v[44:47], v[148:151], v[192:195], v[44:47]
	v_mfma_f32_16x16x32_bf16 v[40:43], v[156:159], v[192:195], v[40:43]
	v_mfma_f32_16x16x32_bf16 v[28:31], v[148:151], v[200:203], v[28:31]
	v_mfma_f32_16x16x32_bf16 v[24:27], v[156:159], v[200:203], v[24:27]
	v_mfma_f32_16x16x32_bf16 v[12:15], v[148:151], v[208:211], v[12:15]
	v_mfma_f32_16x16x32_bf16 v[8:11], v[156:159], v[208:211], v[8:11]
	v_mfma_f32_16x16x32_bf16 v[52:55], v[160:163], v[176:179], v[52:55]
	v_mfma_f32_16x16x32_bf16 v[48:51], v[168:171], v[176:179], v[48:51]
	v_mfma_f32_16x16x32_bf16 v[36:39], v[160:163], v[188:191], v[36:39]
	v_mfma_f32_16x16x32_bf16 v[32:35], v[168:171], v[188:191], v[32:35]
	v_mfma_f32_16x16x32_bf16 v[20:23], v[160:163], v[196:199], v[20:23]
	v_mfma_f32_16x16x32_bf16 v[16:19], v[168:171], v[196:199], v[16:19]
	v_mfma_f32_16x16x32_bf16 v[4:7], v[160:163], v[204:207], v[4:7]
	v_mfma_f32_16x16x32_bf16 v[0:3], v[168:171], v[204:207], v[0:3]
	v_mfma_f32_16x16x32_bf16 v[52:55], v[164:167], v[180:183], v[52:55]
	v_mfma_f32_16x16x32_bf16 v[48:51], v[172:175], v[180:183], v[48:51]
	v_mfma_f32_16x16x32_bf16 v[36:39], v[164:167], v[192:195], v[36:39]
	v_mfma_f32_16x16x32_bf16 v[32:35], v[172:175], v[192:195], v[32:35]
	v_mfma_f32_16x16x32_bf16 v[20:23], v[164:167], v[200:203], v[20:23]
	v_mfma_f32_16x16x32_bf16 v[16:19], v[172:175], v[200:203], v[16:19]
	v_mfma_f32_16x16x32_bf16 v[4:7], v[164:167], v[208:211], v[4:7]
	v_mfma_f32_16x16x32_bf16 v[0:3], v[172:175], v[208:211], v[0:3]
	s_barrier
	s_add_i32 s54, s54, 2
	s_add_u32 s36, s36, 0x100
	s_addc_u32 s37, s37, 0
	s_add_u32 s52, s52, 0x100
	s_addc_u32 s53, s53, 0
	s_cmp_gt_u32 s54, 13
	s_cbranch_scc0 .LBB0_763

; #define G_STAGE(bufoff, gbase, voff) do { _Pragma("unroll") for (int _i = 0; _i < 2; ++_i) \
;         __builtin_amdgcn_global_load_lds((const unsigned*)((const char*)(gbase) + voff[_i]), (LAS unsigned*)(lds + (bufoff) + ldsw + _i * 8192), 16, 0, 0); } while (0)
; #define G_LDA(dst, b, h) do { _Pragma("unroll") for (int m = 0; m < 4; ++m) _Pragma("unroll") for (int k = 0; k < 2; ++k) dst[m][k] = *(const LAS bf16x8*)(lds + G_SA(b, h) + aoff + m * 2048 + k * 1024); } while (0)
; #define G_MMA(ai, bj, At_, Bt_) do { __builtin_amdgcn_s_setprio(1); _Pragma("unroll") for (int m = 0; m < 4; ++m) _Pragma("unroll") for (int n = 0; n < 2; ++n) _Pragma("unroll") for (int k = 0; k < 2; ++k) \
;         acc[ai][bj][m][n] = __builtin_amdgcn_mfma_f32_16x16x32_bf16(Bt_[n][k], At_[m][k], acc[ai][bj][m][n], 0, 0, 0); __builtin_amdgcn_s_setprio(0); } while (0)
; #define WAIT_V(n) asm volatile("s_waitcnt vmcnt(" #n ")" ::: "memory")
; #define WAIT_L(n) asm volatile("s_waitcnt lgkmcnt(" #n ")" ::: "memory")
; #define BAR __builtin_amdgcn_s_barrier()
; #define SCHED __builtin_amdgcn_sched_barrier(0)
; template <class Get, class Epi>
; DI void gemm_loop(int ntiles, int ld, char* shm, const Get& get, const Epi& epi) {
;     ...
;             WAIT_V(8); WAIT_L(0); BAR; G_MMA(0, 0, At, B0); G_MMA(0, 1, At, B1); BAR; SCHED;
;             G_LDA(At, 0, 1); G_STAGE(G_SB(0, 0), b2, voffB); G_STAGE(G_SB(0, 1), b2 + hstep, voffB); G_STAGE(G_SA(0, 0), a2, voffA);
;             WAIT_V(8); WAIT_L(0); BAR; G_MMA(1, 0, At, B0); G_MMA(1, 1, At, B1); BAR; SCHED;
;     ...
;         G_ZERO;
.Lrj_850_0:
	s_waitcnt lgkmcnt(0)
	s_barrier
	s_waitcnt lgkmcnt(0)
	v_mfma_f32_16x16x32_bf16 v[124:127], v[128:131], v[180:183], 0
	v_mfma_f32_16x16x32_bf16 v[120:123], v[136:139], v[180:183], 0
	v_mfma_f32_16x16x32_bf16 v[116:119], v[128:131], v[192:195], 0
	v_mfma_f32_16x16x32_bf16 v[112:115], v[136:139], v[192:195], 0
	v_mfma_f32_16x16x32_bf16 v[108:111], v[128:131], v[200:203], 0
	v_mfma_f32_16x16x32_bf16 v[104:107], v[136:139], v[200:203], 0
	v_mfma_f32_16x16x32_bf16 v[100:103], v[128:131], v[208:211], 0
	v_mfma_f32_16x16x32_bf16 v[96:99], v[136:139], v[208:211], 0
	v_mfma_f32_16x16x32_bf16 v[124:127], v[132:135], v[188:191], v[124:127]
	v_mfma_f32_16x16x32_bf16 v[120:123], v[140:143], v[188:191], v[120:123]
	v_mfma_f32_16x16x32_bf16 v[116:119], v[132:135], v[196:199], v[116:119]
	v_mfma_f32_16x16x32_bf16 v[112:115], v[140:143], v[196:199], v[112:115]
	v_mfma_f32_16x16x32_bf16 v[108:111], v[132:135], v[204:207], v[108:111]
	v_mfma_f32_16x16x32_bf16 v[104:107], v[140:143], v[204:207], v[104:107]
	v_mfma_f32_16x16x32_bf16 v[100:103], v[132:135], v[212:215], v[100:103]
	v_mfma_f32_16x16x32_bf16 v[96:99], v[140:143], v[212:215], v[96:99]
	v_mfma_f32_16x16x32_bf16 v[60:63], v[158:161], v[180:183], 0
	v_mfma_f32_16x16x32_bf16 v[56:59], v[172:175], v[180:183], 0
	v_mfma_f32_16x16x32_bf16 v[52:55], v[158:161], v[192:195], 0
	v_mfma_f32_16x16x32_bf16 v[48:51], v[172:175], v[192:195], 0
	v_mfma_f32_16x16x32_bf16 v[44:47], v[158:161], v[200:203], 0
	v_mfma_f32_16x16x32_bf16 v[40:43], v[172:175], v[200:203], 0
	v_mfma_f32_16x16x32_bf16 v[36:39], v[158:161], v[208:211], 0
	v_mfma_f32_16x16x32_bf16 v[32:35], v[172:175], v[208:211], 0
	v_mfma_f32_16x16x32_bf16 v[60:63], v[162:165], v[188:191], v[60:63]
	v_mfma_f32_16x16x32_bf16 v[56:59], v[176:179], v[188:191], v[56:59]
	v_mfma_f32_16x16x32_bf16 v[52:55], v[162:165], v[196:199], v[52:55]
	v_mfma_f32_16x16x32_bf16 v[48:51], v[176:179], v[196:199], v[48:51]
	v_mfma_f32_16x16x32_bf16 v[44:47], v[162:165], v[204:207], v[44:47]
	v_mfma_f32_16x16x32_bf16 v[40:43], v[176:179], v[204:207], v[40:43]
	v_mfma_f32_16x16x32_bf16 v[36:39], v[162:165], v[212:215], v[36:39]
	v_mfma_f32_16x16x32_bf16 v[32:35], v[176:179], v[212:215], v[32:35]
	s_barrier
	s_add_i32 s4, s50, s26
	v_lshl_add_u64 v[144:145], s[38:39], 0, v[148:149]
	s_mov_b32 m0, s4
	ds_read_b128 v[180:183], v171 offset:16384
	ds_read_b128 v[188:191], v171 offset:17408
	ds_read_b128 v[192:195], v171 offset:18432
	ds_read_b128 v[196:199], v171 offset:19456
	ds_read_b128 v[200:203], v171 offset:20480
	ds_read_b128 v[204:207], v171 offset:21504
	ds_read_b128 v[208:211], v171 offset:22528
	ds_read_b128 v[212:215], v171 offset:23552
	global_load_lds_dwordx4 v[144:145], off
	s_add_i32 m0, s4, 0x2000
	s_add_u32 s4, s38, 0xb0000
	v_lshl_add_u64 v[166:167], s[38:39], 0, v[152:153]
	s_addc_u32 s5, s39, 0
	s_add_i32 s76, s51, s26
	global_load_lds_dwordx4 v[166:167], off
	v_lshl_add_u64 v[184:185], s[4:5], 0, v[148:149]
	s_mov_b32 m0, s76
	v_lshl_add_u64 v[186:187], s[40:41], 0, v[150:151]
	global_load_lds_dwordx4 v[184:185], off
	v_lshl_add_u64 v[184:185], s[4:5], 0, v[152:153]
	s_add_i32 m0, s76, 0x2000
	s_nop 0
	global_load_lds_dwordx4 v[184:185], off
	v_lshl_add_u64 v[184:185], s[40:41], 0, v[146:147]
	s_mov_b32 m0, s42
	s_nop 0
	global_load_lds_dwordx4 v[184:185], off
	s_mov_b32 m0, s43
	s_nop 0
	global_load_lds_dwordx4 v[186:187], off
	s_cmp_lg_u32 s100, 0
	s_cbranch_scc0 .Lrf_850_1
	s_waitcnt vmcnt(16)
	s_branch .Lrj_850_1

; #define G_STAGE(bufoff, gbase, voff) do { _Pragma("unroll") for (int _i = 0; _i < 2; ++_i) \
;         __builtin_amdgcn_global_load_lds((const unsigned*)((const char*)(gbase) + voff[_i]), (LAS unsigned*)(lds + (bufoff) + ldsw + _i * 8192), 16, 0, 0); } while (0)
; #define G_LDA(dst, b, h) do { _Pragma("unroll") for (int m = 0; m < 4; ++m) _Pragma("unroll") for (int k = 0; k < 2; ++k) dst[m][k] = *(const LAS bf16x8*)(lds + G_SA(b, h) + aoff + m * 2048 + k * 1024); } while (0)
; #define G_LDB(dst, b, h) do { _Pragma("unroll") for (int n = 0; n < 2; ++n) _Pragma("unroll") for (int k = 0; k < 2; ++k) dst[n][k] = *(const LAS bf16x8*)(lds + G_SB(b, h) + boff + n * 2048 + k * 1024); } while (0)
; #define G_MMA(ai, bj, At_, Bt_) do { __builtin_amdgcn_s_setprio(1); _Pragma("unroll") for (int m = 0; m < 4; ++m) _Pragma("unroll") for (int n = 0; n < 2; ++n) _Pragma("unroll") for (int k = 0; k < 2; ++k) \
;         acc[ai][bj][m][n] = __builtin_amdgcn_mfma_f32_16x16x32_bf16(Bt_[n][k], At_[m][k], acc[ai][bj][m][n], 0, 0, 0); __builtin_amdgcn_s_setprio(0); } while (0)
; #define WAIT_V(n) asm volatile("s_waitcnt vmcnt(" #n ")" ::: "memory")
; #define WAIT_L(n) asm volatile("s_waitcnt lgkmcnt(" #n ")" ::: "memory")
; #define BAR __builtin_amdgcn_s_barrier()
; #define SCHED __builtin_amdgcn_sched_barrier(0)
; template <class Get, class Epi>
; DI void gemm_loop(int ntiles, int ld, char* shm, const Get& get, const Epi& epi) {
;     ...
;             WAIT_V(8); WAIT_L(0); BAR; G_MMA(1, 0, At, B0); G_MMA(1, 1, At, B1); BAR; SCHED;
;             G_LDB(B0, 1, 0); G_LDB(B1, 1, 1); SCHED; G_LDA(At, 1, 0); G_STAGE(G_SA(0, 1), a2 + hstep, voffA);
;             WAIT_V(8); WAIT_L(0); BAR; G_MMA(0, 0, At, B0); G_MMA(0, 1, At, B1); BAR; SCHED;
.Lrj_850_1:
	s_waitcnt lgkmcnt(0)
	s_barrier
	s_waitcnt lgkmcnt(0)
	v_mfma_f32_16x16x32_bf16 v[92:95], v[128:131], v[180:183], 0
	v_mfma_f32_16x16x32_bf16 v[88:91], v[136:139], v[180:183], 0
	v_mfma_f32_16x16x32_bf16 v[84:87], v[128:131], v[192:195], 0
	v_mfma_f32_16x16x32_bf16 v[80:83], v[136:139], v[192:195], 0
	v_mfma_f32_16x16x32_bf16 v[76:79], v[128:131], v[200:203], 0
	v_mfma_f32_16x16x32_bf16 v[72:75], v[136:139], v[200:203], 0
	v_mfma_f32_16x16x32_bf16 v[68:71], v[128:131], v[208:211], 0
	v_mfma_f32_16x16x32_bf16 v[64:67], v[136:139], v[208:211], 0
	v_mfma_f32_16x16x32_bf16 v[92:95], v[132:135], v[188:191], v[92:95]
	v_mfma_f32_16x16x32_bf16 v[88:91], v[140:143], v[188:191], v[88:91]
	v_mfma_f32_16x16x32_bf16 v[84:87], v[132:135], v[196:199], v[84:87]
	v_mfma_f32_16x16x32_bf16 v[80:83], v[140:143], v[196:199], v[80:83]
	v_mfma_f32_16x16x32_bf16 v[76:79], v[132:135], v[204:207], v[76:79]
	v_mfma_f32_16x16x32_bf16 v[72:75], v[140:143], v[204:207], v[72:75]
	v_mfma_f32_16x16x32_bf16 v[68:71], v[132:135], v[212:215], v[68:71]
	v_mfma_f32_16x16x32_bf16 v[64:67], v[140:143], v[212:215], v[64:67]
	v_mfma_f32_16x16x32_bf16 v[28:31], v[158:161], v[180:183], 0
	v_mfma_f32_16x16x32_bf16 v[24:27], v[172:175], v[180:183], 0
	v_mfma_f32_16x16x32_bf16 v[20:23], v[158:161], v[192:195], 0
	v_mfma_f32_16x16x32_bf16 v[16:19], v[172:175], v[192:195], 0
	v_mfma_f32_16x16x32_bf16 v[12:15], v[158:161], v[200:203], 0
	v_mfma_f32_16x16x32_bf16 v[8:11], v[172:175], v[200:203], 0
	v_mfma_f32_16x16x32_bf16 v[4:7], v[158:161], v[208:211], 0
	v_mfma_f32_16x16x32_bf16 v[0:3], v[172:175], v[208:211], 0
	v_mfma_f32_16x16x32_bf16 v[28:31], v[162:165], v[188:191], v[28:31]
	v_mfma_f32_16x16x32_bf16 v[24:27], v[176:179], v[188:191], v[24:27]
	v_mfma_f32_16x16x32_bf16 v[20:23], v[162:165], v[196:199], v[20:23]
	v_mfma_f32_16x16x32_bf16 v[16:19], v[176:179], v[196:199], v[16:19]
	v_mfma_f32_16x16x32_bf16 v[12:15], v[162:165], v[204:207], v[12:15]
	v_mfma_f32_16x16x32_bf16 v[8:11], v[176:179], v[204:207], v[8:11]
	v_mfma_f32_16x16x32_bf16 v[4:7], v[162:165], v[212:215], v[4:7]
	v_mfma_f32_16x16x32_bf16 v[0:3], v[176:179], v[212:215], v[0:3]
	s_barrier
	s_add_i32 s76, 0, 0x18000
	s_add_i32 s78, 0, 0x1c000
	v_add_u32_e32 v140, s76, v168
	v_add_u32_e32 v176, s78, v168
	ds_read_b128 v[128:131], v140
	ds_read_b128 v[132:135], v140 offset:1024
	ds_read_b128 v[136:139], v140 offset:2048
	ds_read_b128 v[140:143], v140 offset:3072
	ds_read_b128 v[158:161], v176
	ds_read_b128 v[162:165], v176 offset:1024
	ds_read_b128 v[172:175], v176 offset:2048
	ds_read_b128 v[176:179], v176 offset:3072
	s_add_u32 s4, s40, 0xb0000
	s_addc_u32 s5, s41, 0
	s_mov_b32 m0, s44
	v_lshl_add_u64 v[216:217], s[4:5], 0, v[146:147]
	ds_read_b128 v[180:183], v171 offset:32768
	ds_read_b128 v[188:191], v171 offset:33792
	ds_read_b128 v[192:195], v171 offset:34816
	ds_read_b128 v[196:199], v171 offset:35840
	ds_read_b128 v[200:203], v171 offset:36864
	ds_read_b128 v[204:207], v171 offset:37888
	ds_read_b128 v[208:211], v171 offset:38912
	ds_read_b128 v[212:215], v171 offset:39936
	global_load_lds_dwordx4 v[216:217], off
	v_lshl_add_u64 v[216:217], s[4:5], 0, v[150:151]
	s_mov_b32 m0, s45
	s_nop 0
	global_load_lds_dwordx4 v[216:217], off
	s_waitcnt vmcnt(8)
	s_waitcnt lgkmcnt(0)
	s_barrier
	s_waitcnt lgkmcnt(0)
	v_mfma_f32_16x16x32_bf16 v[124:127], v[128:131], v[180:183], v[124:127]
	v_mfma_f32_16x16x32_bf16 v[120:123], v[136:139], v[180:183], v[120:123]
	v_mfma_f32_16x16x32_bf16 v[116:119], v[128:131], v[192:195], v[116:119]
	v_mfma_f32_16x16x32_bf16 v[112:115], v[136:139], v[192:195], v[112:115]
	v_mfma_f32_16x16x32_bf16 v[108:111], v[128:131], v[200:203], v[108:111]
	v_mfma_f32_16x16x32_bf16 v[104:107], v[136:139], v[200:203], v[104:107]
	v_mfma_f32_16x16x32_bf16 v[100:103], v[128:131], v[208:211], v[100:103]
	v_mfma_f32_16x16x32_bf16 v[96:99], v[136:139], v[208:211], v[96:99]
	v_mfma_f32_16x16x32_bf16 v[124:127], v[132:135], v[188:191], v[124:127]
	v_mfma_f32_16x16x32_bf16 v[120:123], v[140:143], v[188:191], v[120:123]
	v_mfma_f32_16x16x32_bf16 v[116:119], v[132:135], v[196:199], v[116:119]
	v_mfma_f32_16x16x32_bf16 v[112:115], v[140:143], v[196:199], v[112:115]
	v_mfma_f32_16x16x32_bf16 v[108:111], v[132:135], v[204:207], v[108:111]
	v_mfma_f32_16x16x32_bf16 v[104:107], v[140:143], v[204:207], v[104:107]
	v_mfma_f32_16x16x32_bf16 v[100:103], v[132:135], v[212:215], v[100:103]
	v_mfma_f32_16x16x32_bf16 v[96:99], v[140:143], v[212:215], v[96:99]
	v_mfma_f32_16x16x32_bf16 v[60:63], v[158:161], v[180:183], v[60:63]
	v_mfma_f32_16x16x32_bf16 v[56:59], v[172:175], v[180:183], v[56:59]
	v_mfma_f32_16x16x32_bf16 v[52:55], v[158:161], v[192:195], v[52:55]
	v_mfma_f32_16x16x32_bf16 v[48:51], v[172:175], v[192:195], v[48:51]
	v_mfma_f32_16x16x32_bf16 v[44:47], v[158:161], v[200:203], v[44:47]
	v_mfma_f32_16x16x32_bf16 v[40:43], v[172:175], v[200:203], v[40:43]
	v_mfma_f32_16x16x32_bf16 v[36:39], v[158:161], v[208:211], v[36:39]
	v_mfma_f32_16x16x32_bf16 v[32:35], v[172:175], v[208:211], v[32:35]
	v_mfma_f32_16x16x32_bf16 v[60:63], v[162:165], v[188:191], v[60:63]
	v_mfma_f32_16x16x32_bf16 v[56:59], v[176:179], v[188:191], v[56:59]
	v_mfma_f32_16x16x32_bf16 v[52:55], v[162:165], v[196:199], v[52:55]
	v_mfma_f32_16x16x32_bf16 v[48:51], v[176:179], v[196:199], v[48:51]
	v_mfma_f32_16x16x32_bf16 v[44:47], v[162:165], v[204:207], v[44:47]
	v_mfma_f32_16x16x32_bf16 v[40:43], v[176:179], v[204:207], v[40:43]
	v_mfma_f32_16x16x32_bf16 v[36:39], v[162:165], v[212:215], v[36:39]
	v_mfma_f32_16x16x32_bf16 v[32:35], v[176:179], v[212:215], v[32:35]
	s_barrier
; #define G_STAGE(bufoff, gbase, voff) do { _Pragma("unroll") for (int _i = 0; _i < 2; ++_i) \
;         __builtin_amdgcn_global_load_lds((const unsigned*)((const char*)(gbase) + voff[_i]), (LAS unsigned*)(lds + (bufoff) + ldsw + _i * 8192), 16, 0, 0); } while (0)
; #define G_LDA(dst, b, h) do { _Pragma("unroll") for (int m = 0; m < 4; ++m) _Pragma("unroll") for (int k = 0; k < 2; ++k) dst[m][k] = *(const LAS bf16x8*)(lds + G_SA(b, h) + aoff + m * 2048 + k * 1024); } while (0)
; #define G_LDB(dst, b, h) do { _Pragma("unroll") for (int n = 0; n < 2; ++n) _Pragma("unroll") for (int k = 0; k < 2; ++k) dst[n][k] = *(const LAS bf16x8*)(lds + G_SB(b, h) + boff + n * 2048 + k * 1024); } while (0)
; #define G_MMA(ai, bj, At_, Bt_) do { __builtin_amdgcn_s_setprio(1); _Pragma("unroll") for (int m = 0; m < 4; ++m) _Pragma("unroll") for (int n = 0; n < 2; ++n) _Pragma("unroll") for (int k = 0; k < 2; ++k) \
;         acc[ai][bj][m][n] = __builtin_amdgcn_mfma_f32_16x16x32_bf16(Bt_[n][k], At_[m][k], acc[ai][bj][m][n], 0, 0, 0); __builtin_amdgcn_s_setprio(0); } while (0)
; #define WAIT_V(n) asm volatile("s_waitcnt vmcnt(" #n ")" ::: "memory")
; #define WAIT_L(n) asm volatile("s_waitcnt lgkmcnt(" #n ")" ::: "memory")
; #define BAR __builtin_amdgcn_s_barrier()
; #define SCHED __builtin_amdgcn_sched_barrier(0)
; template <class Get, class Epi>
; DI void gemm_loop(int ntiles, int ld, char* shm, const Get& get, const Epi& epi) {
;     ...
;             G_LDB(B0, 0, 0); G_LDB(B1, 0, 1); SCHED; G_LDA(At, 0, 0); G_STAGE(G_SA(1, 1), a1 + hstep, voffA);
;             WAIT_V(8); WAIT_L(0); BAR; G_MMA(0, 0, At, B0); G_MMA(0, 1, At, B1); BAR; SCHED;
;     ...
;             G_LDA(At, 1, 1); G_STAGE(G_SB(1, 0), b3, voffB); G_STAGE(G_SB(1, 1), b3 + hstep, voffB); G_STAGE(G_SA(1, 0), a3, voffA);
;             WAIT_V(8); WAIT_L(0); BAR; G_MMA(1, 0, At, B0); G_MMA(1, 1, At, B1); BAR; SCHED;
;         }
	s_add_i32 s4, s76, s26
	v_lshl_add_u64 v[144:145], v[144:145], 0, s[10:11]
	s_mov_b32 m0, s4
	ds_read_b128 v[180:183], v171 offset:49152
	ds_read_b128 v[188:191], v171 offset:50176
	ds_read_b128 v[192:195], v171 offset:51200
	ds_read_b128 v[196:199], v171 offset:52224
	ds_read_b128 v[200:203], v171 offset:53248
	ds_read_b128 v[204:207], v171 offset:54272
	ds_read_b128 v[208:211], v171 offset:55296
	ds_read_b128 v[212:215], v171 offset:56320
	global_load_lds_dwordx4 v[144:145], off
	s_add_i32 m0, s4, 0x2000
	s_add_u32 s4, s38, 0xb0080
	v_lshl_add_u64 v[144:145], v[166:167], 0, s[10:11]
	s_addc_u32 s5, s39, 0
	s_add_i32 s38, s78, s26
	global_load_lds_dwordx4 v[144:145], off
	v_lshl_add_u64 v[144:145], s[4:5], 0, v[148:149]
	s_mov_b32 m0, s38
	s_nop 0
	global_load_lds_dwordx4 v[144:145], off
	v_lshl_add_u64 v[144:145], s[4:5], 0, v[152:153]
	s_add_i32 m0, s38, 0x2000
	s_nop 0
	global_load_lds_dwordx4 v[144:145], off
	v_lshl_add_u64 v[144:145], v[184:185], 0, s[10:11]
	s_mov_b32 m0, s48
	s_nop 0
	global_load_lds_dwordx4 v[144:145], off
	v_lshl_add_u64 v[144:145], v[186:187], 0, s[10:11]
	s_mov_b32 m0, s49
	s_nop 0
	global_load_lds_dwordx4 v[144:145], off
	s_waitcnt vmcnt(8)
	s_waitcnt lgkmcnt(0)
	s_barrier
	s_waitcnt lgkmcnt(0)
	v_mfma_f32_16x16x32_bf16 v[92:95], v[128:131], v[180:183], v[92:95]
	v_mfma_f32_16x16x32_bf16 v[88:91], v[136:139], v[180:183], v[88:91]
	v_mfma_f32_16x16x32_bf16 v[84:87], v[128:131], v[192:195], v[84:87]
	v_mfma_f32_16x16x32_bf16 v[80:83], v[136:139], v[192:195], v[80:83]
	v_mfma_f32_16x16x32_bf16 v[76:79], v[128:131], v[200:203], v[76:79]
	v_mfma_f32_16x16x32_bf16 v[72:75], v[136:139], v[200:203], v[72:75]
	v_mfma_f32_16x16x32_bf16 v[68:71], v[128:131], v[208:211], v[68:71]
	v_mfma_f32_16x16x32_bf16 v[64:67], v[136:139], v[208:211], v[64:67]
	v_mfma_f32_16x16x32_bf16 v[92:95], v[132:135], v[188:191], v[92:95]
	v_mfma_f32_16x16x32_bf16 v[88:91], v[140:143], v[188:191], v[88:91]
	v_mfma_f32_16x16x32_bf16 v[84:87], v[132:135], v[196:199], v[84:87]
	v_mfma_f32_16x16x32_bf16 v[80:83], v[140:143], v[196:199], v[80:83]
	v_mfma_f32_16x16x32_bf16 v[76:79], v[132:135], v[204:207], v[76:79]
	v_mfma_f32_16x16x32_bf16 v[72:75], v[140:143], v[204:207], v[72:75]
	v_mfma_f32_16x16x32_bf16 v[68:71], v[132:135], v[212:215], v[68:71]
	v_mfma_f32_16x16x32_bf16 v[64:67], v[140:143], v[212:215], v[64:67]
	v_mfma_f32_16x16x32_bf16 v[28:31], v[158:161], v[180:183], v[28:31]
	v_mfma_f32_16x16x32_bf16 v[24:27], v[172:175], v[180:183], v[24:27]
	v_mfma_f32_16x16x32_bf16 v[20:23], v[158:161], v[192:195], v[20:23]
	v_mfma_f32_16x16x32_bf16 v[16:19], v[172:175], v[192:195], v[16:19]
	v_mfma_f32_16x16x32_bf16 v[12:15], v[158:161], v[200:203], v[12:15]
	v_mfma_f32_16x16x32_bf16 v[8:11], v[172:175], v[200:203], v[8:11]
	v_mfma_f32_16x16x32_bf16 v[4:7], v[158:161], v[208:211], v[4:7]
	v_mfma_f32_16x16x32_bf16 v[0:3], v[172:175], v[208:211], v[0:3]
	v_mfma_f32_16x16x32_bf16 v[28:31], v[162:165], v[188:191], v[28:31]
	v_mfma_f32_16x16x32_bf16 v[24:27], v[176:179], v[188:191], v[24:27]
	v_mfma_f32_16x16x32_bf16 v[20:23], v[162:165], v[196:199], v[20:23]
	v_mfma_f32_16x16x32_bf16 v[16:19], v[176:179], v[196:199], v[16:19]
	v_mfma_f32_16x16x32_bf16 v[12:15], v[162:165], v[204:207], v[12:15]
	v_mfma_f32_16x16x32_bf16 v[8:11], v[176:179], v[204:207], v[8:11]
	v_mfma_f32_16x16x32_bf16 v[4:7], v[162:165], v[212:215], v[4:7]
	v_mfma_f32_16x16x32_bf16 v[0:3], v[176:179], v[212:215], v[0:3]
	s_barrier
	s_add_u32 s73, s73, 0x100
	s_addc_u32 s74, s74, 0
	s_cmp_ge_u32 s75, s59
	s_mov_b64 s[4:5], s[14:15]
	s_mov_b32 s38, s75
	s_cbranch_scc0 .LBB0_850
	s_branch .Lpost_850
.LBB0_850:
	ds_read_b128 v[128:131], v169
	ds_read_b128 v[132:135], v169 offset:1024
	ds_read_b128 v[136:139], v169 offset:2048
	ds_read_b128 v[140:143], v169 offset:3072
	ds_read_b128 v[158:161], v170
	ds_read_b128 v[162:165], v170 offset:1024
	ds_read_b128 v[172:175], v170 offset:2048
	ds_read_b128 v[176:179], v170 offset:3072
	s_add_i32 s75, s38, 2
	s_add_u32 s14, s4, 0x100
	s_addc_u32 s15, s5, 0
	s_cmp_eq_u32 s72, s38
	s_cselect_b32 s38, s36, s73
	s_cselect_b32 s41, s35, s15
	s_cselect_b32 s40, s34, s14
	s_cselect_b32 s39, s37, s74
	v_lshl_add_u64 v[144:145], s[4:5], 0, v[154:155]
	s_add_i32 m0, s42, 0xc000
	ds_read_b128 v[180:183], v171
	ds_read_b128 v[188:191], v171 offset:1024
	ds_read_b128 v[192:195], v171 offset:2048
	ds_read_b128 v[196:199], v171 offset:3072
	ds_read_b128 v[200:203], v171 offset:4096
	ds_read_b128 v[204:207], v171 offset:5120
	ds_read_b128 v[208:211], v171 offset:6144
	ds_read_b128 v[212:215], v171 offset:7168
	global_load_lds_dwordx4 v[144:145], off
	v_lshl_add_u64 v[144:145], s[4:5], 0, v[156:157]
	s_add_i32 m0, s42, 0xe000
	s_nop 0
	global_load_lds_dwordx4 v[144:145], off
	s_waitcnt vmcnt(8)
	s_waitcnt lgkmcnt(0)
	s_barrier
; #define G_STAGE(bufoff, gbase, voff) do { _Pragma("unroll") for (int _i = 0; _i < 2; ++_i) \
;         __builtin_amdgcn_global_load_lds((const unsigned*)((const char*)(gbase) + voff[_i]), (LAS unsigned*)(lds + (bufoff) + ldsw + _i * 8192), 16, 0, 0); } while (0)
; #define G_LDA(dst, b, h) do { _Pragma("unroll") for (int m = 0; m < 4; ++m) _Pragma("unroll") for (int k = 0; k < 2; ++k) dst[m][k] = *(const LAS bf16x8*)(lds + G_SA(b, h) + aoff + m * 2048 + k * 1024); } while (0)
; #define G_MMA(ai, bj, At_, Bt_) do { __builtin_amdgcn_s_setprio(1); _Pragma("unroll") for (int m = 0; m < 4; ++m) _Pragma("unroll") for (int n = 0; n < 2; ++n) _Pragma("unroll") for (int k = 0; k < 2; ++k) \
;         acc[ai][bj][m][n] = __builtin_amdgcn_mfma_f32_16x16x32_bf16(Bt_[n][k], At_[m][k], acc[ai][bj][m][n], 0, 0, 0); __builtin_amdgcn_s_setprio(0); } while (0)
; #define WAIT_V(n) asm volatile("s_waitcnt vmcnt(" #n ")" ::: "memory")
; #define WAIT_L(n) asm volatile("s_waitcnt lgkmcnt(" #n ")" ::: "memory")
; #define BAR __builtin_amdgcn_s_barrier()
; #define SCHED __builtin_amdgcn_sched_barrier(0)
; template <class Get, class Epi>
; DI void gemm_loop(int ntiles, int ld, char* shm, const Get& get, const Epi& epi) {
;     ...
;             WAIT_V(8); WAIT_L(0); BAR; G_MMA(0, 0, At, B0); G_MMA(0, 1, At, B1); BAR; SCHED;
;             G_LDA(At, 0, 1); G_STAGE(G_SB(0, 0), b2, voffB); G_STAGE(G_SB(0, 1), b2 + hstep, voffB); G_STAGE(G_SA(0, 0), a2, voffA);
;             WAIT_V(8); WAIT_L(0); BAR; G_MMA(1, 0, At, B0); G_MMA(1, 1, At, B1); BAR; SCHED;
	s_waitcnt lgkmcnt(0)
	v_mfma_f32_16x16x32_bf16 v[124:127], v[128:131], v[180:183], v[124:127]
	v_mfma_f32_16x16x32_bf16 v[120:123], v[136:139], v[180:183], v[120:123]
	v_mfma_f32_16x16x32_bf16 v[116:119], v[128:131], v[192:195], v[116:119]
	v_mfma_f32_16x16x32_bf16 v[112:115], v[136:139], v[192:195], v[112:115]
	v_mfma_f32_16x16x32_bf16 v[108:111], v[128:131], v[200:203], v[108:111]
	v_mfma_f32_16x16x32_bf16 v[104:107], v[136:139], v[200:203], v[104:107]
	v_mfma_f32_16x16x32_bf16 v[100:103], v[128:131], v[208:211], v[100:103]
	v_mfma_f32_16x16x32_bf16 v[96:99], v[136:139], v[208:211], v[96:99]
	v_mfma_f32_16x16x32_bf16 v[124:127], v[132:135], v[188:191], v[124:127]
	v_mfma_f32_16x16x32_bf16 v[120:123], v[140:143], v[188:191], v[120:123]
	v_mfma_f32_16x16x32_bf16 v[116:119], v[132:135], v[196:199], v[116:119]
	v_mfma_f32_16x16x32_bf16 v[112:115], v[140:143], v[196:199], v[112:115]
	v_mfma_f32_16x16x32_bf16 v[108:111], v[132:135], v[204:207], v[108:111]
	v_mfma_f32_16x16x32_bf16 v[104:107], v[140:143], v[204:207], v[104:107]
	v_mfma_f32_16x16x32_bf16 v[100:103], v[132:135], v[212:215], v[100:103]
	v_mfma_f32_16x16x32_bf16 v[96:99], v[140:143], v[212:215], v[96:99]
	v_mfma_f32_16x16x32_bf16 v[60:63], v[158:161], v[180:183], v[60:63]
	v_mfma_f32_16x16x32_bf16 v[56:59], v[172:175], v[180:183], v[56:59]
	v_mfma_f32_16x16x32_bf16 v[52:55], v[158:161], v[192:195], v[52:55]
	v_mfma_f32_16x16x32_bf16 v[48:51], v[172:175], v[192:195], v[48:51]
	v_mfma_f32_16x16x32_bf16 v[44:47], v[158:161], v[200:203], v[44:47]
	v_mfma_f32_16x16x32_bf16 v[40:43], v[172:175], v[200:203], v[40:43]
	v_mfma_f32_16x16x32_bf16 v[36:39], v[158:161], v[208:211], v[36:39]
	v_mfma_f32_16x16x32_bf16 v[32:35], v[172:175], v[208:211], v[32:35]
	v_mfma_f32_16x16x32_bf16 v[60:63], v[162:165], v[188:191], v[60:63]
	v_mfma_f32_16x16x32_bf16 v[56:59], v[176:179], v[188:191], v[56:59]
	v_mfma_f32_16x16x32_bf16 v[52:55], v[162:165], v[196:199], v[52:55]
	v_mfma_f32_16x16x32_bf16 v[48:51], v[176:179], v[196:199], v[48:51]
	v_mfma_f32_16x16x32_bf16 v[44:47], v[162:165], v[204:207], v[44:47]
	v_mfma_f32_16x16x32_bf16 v[40:43], v[176:179], v[204:207], v[40:43]
	v_mfma_f32_16x16x32_bf16 v[36:39], v[162:165], v[212:215], v[36:39]
	v_mfma_f32_16x16x32_bf16 v[32:35], v[176:179], v[212:215], v[32:35]
	s_barrier
	s_add_i32 s4, s50, s26
	v_lshl_add_u64 v[144:145], s[38:39], 0, v[148:149]
	s_mov_b32 m0, s4
	ds_read_b128 v[180:183], v171 offset:16384
	ds_read_b128 v[188:191], v171 offset:17408
	ds_read_b128 v[192:195], v171 offset:18432
	ds_read_b128 v[196:199], v171 offset:19456
	ds_read_b128 v[200:203], v171 offset:20480
	ds_read_b128 v[204:207], v171 offset:21504
	ds_read_b128 v[208:211], v171 offset:22528
	ds_read_b128 v[212:215], v171 offset:23552
	global_load_lds_dwordx4 v[144:145], off
	s_add_i32 m0, s4, 0x2000
	s_add_u32 s4, s38, 0xb0000
	v_lshl_add_u64 v[166:167], s[38:39], 0, v[152:153]
	s_addc_u32 s5, s39, 0
	s_add_i32 s76, s51, s26
	global_load_lds_dwordx4 v[166:167], off
	v_lshl_add_u64 v[184:185], s[4:5], 0, v[148:149]
	s_mov_b32 m0, s76
	v_lshl_add_u64 v[186:187], s[40:41], 0, v[150:151]
	global_load_lds_dwordx4 v[184:185], off
	v_lshl_add_u64 v[184:185], s[4:5], 0, v[152:153]
	s_add_i32 m0, s76, 0x2000
	s_nop 0
	global_load_lds_dwordx4 v[184:185], off
	v_lshl_add_u64 v[184:185], s[40:41], 0, v[146:147]
	s_mov_b32 m0, s42
	s_nop 0
	global_load_lds_dwordx4 v[184:185], off
	s_mov_b32 m0, s43
	s_nop 0
	global_load_lds_dwordx4 v[186:187], off
	s_waitcnt vmcnt(8)
	s_waitcnt lgkmcnt(0)
	s_barrier
	s_waitcnt lgkmcnt(0)
	v_mfma_f32_16x16x32_bf16 v[92:95], v[128:131], v[180:183], v[92:95]
	v_mfma_f32_16x16x32_bf16 v[88:91], v[136:139], v[180:183], v[88:91]
	v_mfma_f32_16x16x32_bf16 v[84:87], v[128:131], v[192:195], v[84:87]
	v_mfma_f32_16x16x32_bf16 v[80:83], v[136:139], v[192:195], v[80:83]
	v_mfma_f32_16x16x32_bf16 v[76:79], v[128:131], v[200:203], v[76:79]
	v_mfma_f32_16x16x32_bf16 v[72:75], v[136:139], v[200:203], v[72:75]
	v_mfma_f32_16x16x32_bf16 v[68:71], v[128:131], v[208:211], v[68:71]
	v_mfma_f32_16x16x32_bf16 v[64:67], v[136:139], v[208:211], v[64:67]
	v_mfma_f32_16x16x32_bf16 v[92:95], v[132:135], v[188:191], v[92:95]
	v_mfma_f32_16x16x32_bf16 v[88:91], v[140:143], v[188:191], v[88:91]
	v_mfma_f32_16x16x32_bf16 v[84:87], v[132:135], v[196:199], v[84:87]
	v_mfma_f32_16x16x32_bf16 v[80:83], v[140:143], v[196:199], v[80:83]
	v_mfma_f32_16x16x32_bf16 v[76:79], v[132:135], v[204:207], v[76:79]
	v_mfma_f32_16x16x32_bf16 v[72:75], v[140:143], v[204:207], v[72:75]
	v_mfma_f32_16x16x32_bf16 v[68:71], v[132:135], v[212:215], v[68:71]
	v_mfma_f32_16x16x32_bf16 v[64:67], v[140:143], v[212:215], v[64:67]
	v_mfma_f32_16x16x32_bf16 v[28:31], v[158:161], v[180:183], v[28:31]
	v_mfma_f32_16x16x32_bf16 v[24:27], v[172:175], v[180:183], v[24:27]
	v_mfma_f32_16x16x32_bf16 v[20:23], v[158:161], v[192:195], v[20:23]
	v_mfma_f32_16x16x32_bf16 v[16:19], v[172:175], v[192:195], v[16:19]
	v_mfma_f32_16x16x32_bf16 v[12:15], v[158:161], v[200:203], v[12:15]
	v_mfma_f32_16x16x32_bf16 v[8:11], v[172:175], v[200:203], v[8:11]
	v_mfma_f32_16x16x32_bf16 v[4:7], v[158:161], v[208:211], v[4:7]
	v_mfma_f32_16x16x32_bf16 v[0:3], v[172:175], v[208:211], v[0:3]
	v_mfma_f32_16x16x32_bf16 v[28:31], v[162:165], v[188:191], v[28:31]
	v_mfma_f32_16x16x32_bf16 v[24:27], v[176:179], v[188:191], v[24:27]
	v_mfma_f32_16x16x32_bf16 v[20:23], v[162:165], v[196:199], v[20:23]
	v_mfma_f32_16x16x32_bf16 v[16:19], v[176:179], v[196:199], v[16:19]
	v_mfma_f32_16x16x32_bf16 v[12:15], v[162:165], v[204:207], v[12:15]
	v_mfma_f32_16x16x32_bf16 v[8:11], v[176:179], v[204:207], v[8:11]
	v_mfma_f32_16x16x32_bf16 v[4:7], v[162:165], v[212:215], v[4:7]
	v_mfma_f32_16x16x32_bf16 v[0:3], v[176:179], v[212:215], v[0:3]
	s_barrier
; #define G_STAGE(bufoff, gbase, voff) do { _Pragma("unroll") for (int _i = 0; _i < 2; ++_i) \
;         __builtin_amdgcn_global_load_lds((const unsigned*)((const char*)(gbase) + voff[_i]), (LAS unsigned*)(lds + (bufoff) + ldsw + _i * 8192), 16, 0, 0); } while (0)
; #define G_LDA(dst, b, h) do { _Pragma("unroll") for (int m = 0; m < 4; ++m) _Pragma("unroll") for (int k = 0; k < 2; ++k) dst[m][k] = *(const LAS bf16x8*)(lds + G_SA(b, h) + aoff + m * 2048 + k * 1024); } while (0)
; #define G_LDB(dst, b, h) do { _Pragma("unroll") for (int n = 0; n < 2; ++n) _Pragma("unroll") for (int k = 0; k < 2; ++k) dst[n][k] = *(const LAS bf16x8*)(lds + G_SB(b, h) + boff + n * 2048 + k * 1024); } while (0)
; #define G_MMA(ai, bj, At_, Bt_) do { __builtin_amdgcn_s_setprio(1); _Pragma("unroll") for (int m = 0; m < 4; ++m) _Pragma("unroll") for (int n = 0; n < 2; ++n) _Pragma("unroll") for (int k = 0; k < 2; ++k) \
;         acc[ai][bj][m][n] = __builtin_amdgcn_mfma_f32_16x16x32_bf16(Bt_[n][k], At_[m][k], acc[ai][bj][m][n], 0, 0, 0); __builtin_amdgcn_s_setprio(0); } while (0)
; #define WAIT_V(n) asm volatile("s_waitcnt vmcnt(" #n ")" ::: "memory")
; #define WAIT_L(n) asm volatile("s_waitcnt lgkmcnt(" #n ")" ::: "memory")
; #define BAR __builtin_amdgcn_s_barrier()
; #define SCHED __builtin_amdgcn_sched_barrier(0)
; template <class Get, class Epi>
; DI void gemm_loop(int ntiles, int ld, char* shm, const Get& get, const Epi& epi) {
;     ...
;             G_LDB(B0, 1, 0); G_LDB(B1, 1, 1); SCHED; G_LDA(At, 1, 0); G_STAGE(G_SA(0, 1), a2 + hstep, voffA);
;             WAIT_V(8); WAIT_L(0); BAR; G_MMA(0, 0, At, B0); G_MMA(0, 1, At, B1); BAR; SCHED;
;             G_LDA(At, 1, 1); G_STAGE(G_SB(1, 0), b3, voffB); G_STAGE(G_SB(1, 1), b3 + hstep, voffB); G_STAGE(G_SA(1, 0), a3, voffA);
;             WAIT_V(8); WAIT_L(0); BAR; G_MMA(1, 0, At, B0); G_MMA(1, 1, At, B1); BAR; SCHED;
;         }
	s_add_i32 s76, 0, 0x18000
	s_add_i32 s78, 0, 0x1c000
	v_add_u32_e32 v140, s76, v168
	v_add_u32_e32 v176, s78, v168
	ds_read_b128 v[128:131], v140
	ds_read_b128 v[132:135], v140 offset:1024
	ds_read_b128 v[136:139], v140 offset:2048
	ds_read_b128 v[140:143], v140 offset:3072
	ds_read_b128 v[158:161], v176
	ds_read_b128 v[162:165], v176 offset:1024
	ds_read_b128 v[172:175], v176 offset:2048
	ds_read_b128 v[176:179], v176 offset:3072
	s_add_u32 s4, s40, 0xb0000
	s_addc_u32 s5, s41, 0
	s_mov_b32 m0, s44
	v_lshl_add_u64 v[216:217], s[4:5], 0, v[146:147]
	ds_read_b128 v[180:183], v171 offset:32768
	ds_read_b128 v[188:191], v171 offset:33792
	ds_read_b128 v[192:195], v171 offset:34816
	ds_read_b128 v[196:199], v171 offset:35840
	ds_read_b128 v[200:203], v171 offset:36864
	ds_read_b128 v[204:207], v171 offset:37888
	ds_read_b128 v[208:211], v171 offset:38912
	ds_read_b128 v[212:215], v171 offset:39936
	global_load_lds_dwordx4 v[216:217], off
	v_lshl_add_u64 v[216:217], s[4:5], 0, v[150:151]
	s_mov_b32 m0, s45
	s_nop 0
	global_load_lds_dwordx4 v[216:217], off
	s_waitcnt vmcnt(8)
	s_waitcnt lgkmcnt(0)
	s_barrier
	s_waitcnt lgkmcnt(0)
	v_mfma_f32_16x16x32_bf16 v[124:127], v[128:131], v[180:183], v[124:127]
	v_mfma_f32_16x16x32_bf16 v[120:123], v[136:139], v[180:183], v[120:123]
	v_mfma_f32_16x16x32_bf16 v[116:119], v[128:131], v[192:195], v[116:119]
	v_mfma_f32_16x16x32_bf16 v[112:115], v[136:139], v[192:195], v[112:115]
	v_mfma_f32_16x16x32_bf16 v[108:111], v[128:131], v[200:203], v[108:111]
	v_mfma_f32_16x16x32_bf16 v[104:107], v[136:139], v[200:203], v[104:107]
	v_mfma_f32_16x16x32_bf16 v[100:103], v[128:131], v[208:211], v[100:103]
	v_mfma_f32_16x16x32_bf16 v[96:99], v[136:139], v[208:211], v[96:99]
	v_mfma_f32_16x16x32_bf16 v[124:127], v[132:135], v[188:191], v[124:127]
	v_mfma_f32_16x16x32_bf16 v[120:123], v[140:143], v[188:191], v[120:123]
	v_mfma_f32_16x16x32_bf16 v[116:119], v[132:135], v[196:199], v[116:119]
	v_mfma_f32_16x16x32_bf16 v[112:115], v[140:143], v[196:199], v[112:115]
	v_mfma_f32_16x16x32_bf16 v[108:111], v[132:135], v[204:207], v[108:111]
	v_mfma_f32_16x16x32_bf16 v[104:107], v[140:143], v[204:207], v[104:107]
	v_mfma_f32_16x16x32_bf16 v[100:103], v[132:135], v[212:215], v[100:103]
	v_mfma_f32_16x16x32_bf16 v[96:99], v[140:143], v[212:215], v[96:99]
	v_mfma_f32_16x16x32_bf16 v[60:63], v[158:161], v[180:183], v[60:63]
	v_mfma_f32_16x16x32_bf16 v[56:59], v[172:175], v[180:183], v[56:59]
	v_mfma_f32_16x16x32_bf16 v[52:55], v[158:161], v[192:195], v[52:55]
	v_mfma_f32_16x16x32_bf16 v[48:51], v[172:175], v[192:195], v[48:51]
	v_mfma_f32_16x16x32_bf16 v[44:47], v[158:161], v[200:203], v[44:47]
	v_mfma_f32_16x16x32_bf16 v[40:43], v[172:175], v[200:203], v[40:43]
	v_mfma_f32_16x16x32_bf16 v[36:39], v[158:161], v[208:211], v[36:39]
	v_mfma_f32_16x16x32_bf16 v[32:35], v[172:175], v[208:211], v[32:35]
	v_mfma_f32_16x16x32_bf16 v[60:63], v[162:165], v[188:191], v[60:63]
	v_mfma_f32_16x16x32_bf16 v[56:59], v[176:179], v[188:191], v[56:59]
	v_mfma_f32_16x16x32_bf16 v[52:55], v[162:165], v[196:199], v[52:55]
	v_mfma_f32_16x16x32_bf16 v[48:51], v[176:179], v[196:199], v[48:51]
	v_mfma_f32_16x16x32_bf16 v[44:47], v[162:165], v[204:207], v[44:47]
	v_mfma_f32_16x16x32_bf16 v[40:43], v[176:179], v[204:207], v[40:43]
	v_mfma_f32_16x16x32_bf16 v[36:39], v[162:165], v[212:215], v[36:39]
	v_mfma_f32_16x16x32_bf16 v[32:35], v[176:179], v[212:215], v[32:35]
	s_barrier
	s_add_i32 s4, s76, s26
	v_lshl_add_u64 v[144:145], v[144:145], 0, s[10:11]
	s_mov_b32 m0, s4
	ds_read_b128 v[180:183], v171 offset:49152
	ds_read_b128 v[188:191], v171 offset:50176
	ds_read_b128 v[192:195], v171 offset:51200
	ds_read_b128 v[196:199], v171 offset:52224
	ds_read_b128 v[200:203], v171 offset:53248
	ds_read_b128 v[204:207], v171 offset:54272
	ds_read_b128 v[208:211], v171 offset:55296
	ds_read_b128 v[212:215], v171 offset:56320
	global_load_lds_dwordx4 v[144:145], off
	s_add_i32 m0, s4, 0x2000
	s_add_u32 s4, s38, 0xb0080
	v_lshl_add_u64 v[144:145], v[166:167], 0, s[10:11]
	s_addc_u32 s5, s39, 0
	s_add_i32 s38, s78, s26
	global_load_lds_dwordx4 v[144:145], off
	v_lshl_add_u64 v[144:145], s[4:5], 0, v[148:149]
	s_mov_b32 m0, s38
	s_nop 0
	global_load_lds_dwordx4 v[144:145], off
	v_lshl_add_u64 v[144:145], s[4:5], 0, v[152:153]
	s_add_i32 m0, s38, 0x2000
	s_nop 0
	global_load_lds_dwordx4 v[144:145], off
	v_lshl_add_u64 v[144:145], v[184:185], 0, s[10:11]
	s_mov_b32 m0, s48
	s_nop 0
	global_load_lds_dwordx4 v[144:145], off
	v_lshl_add_u64 v[144:145], v[186:187], 0, s[10:11]
	s_mov_b32 m0, s49
	s_nop 0
	global_load_lds_dwordx4 v[144:145], off
	s_waitcnt vmcnt(8)
	s_waitcnt lgkmcnt(0)
	s_barrier
	s_waitcnt lgkmcnt(0)
	v_mfma_f32_16x16x32_bf16 v[92:95], v[128:131], v[180:183], v[92:95]
	v_mfma_f32_16x16x32_bf16 v[88:91], v[136:139], v[180:183], v[88:91]
	v_mfma_f32_16x16x32_bf16 v[84:87], v[128:131], v[192:195], v[84:87]
	v_mfma_f32_16x16x32_bf16 v[80:83], v[136:139], v[192:195], v[80:83]
	v_mfma_f32_16x16x32_bf16 v[76:79], v[128:131], v[200:203], v[76:79]
	v_mfma_f32_16x16x32_bf16 v[72:75], v[136:139], v[200:203], v[72:75]
	v_mfma_f32_16x16x32_bf16 v[68:71], v[128:131], v[208:211], v[68:71]
	v_mfma_f32_16x16x32_bf16 v[64:67], v[136:139], v[208:211], v[64:67]
	v_mfma_f32_16x16x32_bf16 v[92:95], v[132:135], v[188:191], v[92:95]
	v_mfma_f32_16x16x32_bf16 v[88:91], v[140:143], v[188:191], v[88:91]
	v_mfma_f32_16x16x32_bf16 v[84:87], v[132:135], v[196:199], v[84:87]
	v_mfma_f32_16x16x32_bf16 v[80:83], v[140:143], v[196:199], v[80:83]
	v_mfma_f32_16x16x32_bf16 v[76:79], v[132:135], v[204:207], v[76:79]
	v_mfma_f32_16x16x32_bf16 v[72:75], v[140:143], v[204:207], v[72:75]
	v_mfma_f32_16x16x32_bf16 v[68:71], v[132:135], v[212:215], v[68:71]
	v_mfma_f32_16x16x32_bf16 v[64:67], v[140:143], v[212:215], v[64:67]
	v_mfma_f32_16x16x32_bf16 v[28:31], v[158:161], v[180:183], v[28:31]
	v_mfma_f32_16x16x32_bf16 v[24:27], v[172:175], v[180:183], v[24:27]
	v_mfma_f32_16x16x32_bf16 v[20:23], v[158:161], v[192:195], v[20:23]
	v_mfma_f32_16x16x32_bf16 v[16:19], v[172:175], v[192:195], v[16:19]
	v_mfma_f32_16x16x32_bf16 v[12:15], v[158:161], v[200:203], v[12:15]
	v_mfma_f32_16x16x32_bf16 v[8:11], v[172:175], v[200:203], v[8:11]
	v_mfma_f32_16x16x32_bf16 v[4:7], v[158:161], v[208:211], v[4:7]
	v_mfma_f32_16x16x32_bf16 v[0:3], v[172:175], v[208:211], v[0:3]
	v_mfma_f32_16x16x32_bf16 v[28:31], v[162:165], v[188:191], v[28:31]
	v_mfma_f32_16x16x32_bf16 v[24:27], v[176:179], v[188:191], v[24:27]
	v_mfma_f32_16x16x32_bf16 v[20:23], v[162:165], v[196:199], v[20:23]
	v_mfma_f32_16x16x32_bf16 v[16:19], v[176:179], v[196:199], v[16:19]
	v_mfma_f32_16x16x32_bf16 v[12:15], v[162:165], v[204:207], v[12:15]
	v_mfma_f32_16x16x32_bf16 v[8:11], v[176:179], v[204:207], v[8:11]
	v_mfma_f32_16x16x32_bf16 v[4:7], v[162:165], v[212:215], v[4:7]
	v_mfma_f32_16x16x32_bf16 v[0:3], v[176:179], v[212:215], v[0:3]
	s_barrier
	s_add_u32 s73, s73, 0x100
	s_addc_u32 s74, s74, 0
	s_cmp_ge_u32 s75, s59
	s_mov_b64 s[4:5], s[14:15]
	s_mov_b32 s38, s75
	s_cbranch_scc0 .LBB0_850

; #define G_STAGE(bufoff, gbase, voff) do { _Pragma("unroll") for (int _i = 0; _i < 2; ++_i) \
;         __builtin_amdgcn_global_load_lds((const unsigned*)((const char*)(gbase) + voff[_i]), (LAS unsigned*)(lds + (bufoff) + ldsw + _i * 8192), 16, 0, 0); } while (0)
; #define G_LDA(dst, b, h) do { _Pragma("unroll") for (int m = 0; m < 4; ++m) _Pragma("unroll") for (int k = 0; k < 2; ++k) dst[m][k] = *(const LAS bf16x8*)(lds + G_SA(b, h) + aoff + m * 2048 + k * 1024); } while (0)
; #define G_MMA(ai, bj, At_, Bt_) do { __builtin_amdgcn_s_setprio(1); _Pragma("unroll") for (int m = 0; m < 4; ++m) _Pragma("unroll") for (int n = 0; n < 2; ++n) _Pragma("unroll") for (int k = 0; k < 2; ++k) \
;         acc[ai][bj][m][n] = __builtin_amdgcn_mfma_f32_16x16x32_bf16(Bt_[n][k], At_[m][k], acc[ai][bj][m][n], 0, 0, 0); __builtin_amdgcn_s_setprio(0); } while (0)
; #define WAIT_V(n) asm volatile("s_waitcnt vmcnt(" #n ")" ::: "memory")
; #define WAIT_L(n) asm volatile("s_waitcnt lgkmcnt(" #n ")" ::: "memory")
; #define BAR __builtin_amdgcn_s_barrier()
; #define SCHED __builtin_amdgcn_sched_barrier(0)
; template <class Get, class Epi>
; DI void gemm_loop(int ntiles, int ld, char* shm, const Get& get, const Epi& epi) {
;     ...
;             WAIT_V(8); WAIT_L(0); BAR; G_MMA(0, 0, At, B0); G_MMA(0, 1, At, B1); BAR; SCHED;
;             G_LDA(At, 0, 1); G_STAGE(G_SB(0, 0), b2, voffB); G_STAGE(G_SB(0, 1), b2 + hstep, voffB); G_STAGE(G_SA(0, 0), a2, voffA);
;             WAIT_V(8); WAIT_L(0); BAR; G_MMA(1, 0, At, B0); G_MMA(1, 1, At, B1); BAR; SCHED;
;     ...
;         G_ZERO;
.Lrj_1099_0:
	s_waitcnt lgkmcnt(0)
	s_barrier
	s_waitcnt lgkmcnt(0)
	v_mfma_f32_16x16x32_bf16 v[124:127], v[140:143], v[176:179], 0
	v_mfma_f32_16x16x32_bf16 v[120:123], v[152:155], v[176:179], 0
	v_mfma_f32_16x16x32_bf16 v[116:119], v[140:143], v[184:187], 0
	v_mfma_f32_16x16x32_bf16 v[112:115], v[152:155], v[184:187], 0
	v_mfma_f32_16x16x32_bf16 v[108:111], v[140:143], v[192:195], 0
	v_mfma_f32_16x16x32_bf16 v[100:103], v[152:155], v[192:195], 0
	v_mfma_f32_16x16x32_bf16 v[92:95], v[140:143], v[200:203], 0
	v_mfma_f32_16x16x32_bf16 v[84:87], v[152:155], v[200:203], 0
	v_mfma_f32_16x16x32_bf16 v[124:127], v[148:151], v[180:183], v[124:127]
	v_mfma_f32_16x16x32_bf16 v[120:123], v[156:159], v[180:183], v[120:123]
	v_mfma_f32_16x16x32_bf16 v[116:119], v[148:151], v[188:191], v[116:119]
	v_mfma_f32_16x16x32_bf16 v[112:115], v[156:159], v[188:191], v[112:115]
	v_mfma_f32_16x16x32_bf16 v[108:111], v[148:151], v[196:199], v[108:111]
	v_mfma_f32_16x16x32_bf16 v[100:103], v[156:159], v[196:199], v[100:103]
	v_mfma_f32_16x16x32_bf16 v[92:95], v[148:151], v[204:207], v[92:95]
	v_mfma_f32_16x16x32_bf16 v[84:87], v[156:159], v[204:207], v[84:87]
	v_mfma_f32_16x16x32_bf16 v[104:107], v[160:163], v[176:179], 0
	v_mfma_f32_16x16x32_bf16 v[96:99], v[168:171], v[176:179], 0
	v_mfma_f32_16x16x32_bf16 v[88:91], v[160:163], v[184:187], 0
	v_mfma_f32_16x16x32_bf16 v[80:83], v[168:171], v[184:187], 0
	v_mfma_f32_16x16x32_bf16 v[76:79], v[160:163], v[192:195], 0
	v_mfma_f32_16x16x32_bf16 v[72:75], v[168:171], v[192:195], 0
	v_mfma_f32_16x16x32_bf16 v[68:71], v[160:163], v[200:203], 0
	v_mfma_f32_16x16x32_bf16 v[64:67], v[168:171], v[200:203], 0
	v_mfma_f32_16x16x32_bf16 v[104:107], v[164:167], v[180:183], v[104:107]
	v_mfma_f32_16x16x32_bf16 v[96:99], v[172:175], v[180:183], v[96:99]
	v_mfma_f32_16x16x32_bf16 v[88:91], v[164:167], v[188:191], v[88:91]
	v_mfma_f32_16x16x32_bf16 v[80:83], v[172:175], v[188:191], v[80:83]
	v_mfma_f32_16x16x32_bf16 v[76:79], v[164:167], v[196:199], v[76:79]
	v_mfma_f32_16x16x32_bf16 v[72:75], v[172:175], v[196:199], v[72:75]
	v_mfma_f32_16x16x32_bf16 v[68:71], v[164:167], v[204:207], v[68:71]
	v_mfma_f32_16x16x32_bf16 v[64:67], v[172:175], v[204:207], v[64:67]
	s_barrier
	s_add_i32 s77, s57, s7
	v_lshl_add_u64 v[208:209], s[14:15], 0, v[130:131]
	s_mov_b32 m0, s77
	ds_read_b128 v[176:179], v147 offset:16384
	ds_read_b128 v[180:183], v147 offset:17408
	ds_read_b128 v[184:187], v147 offset:18432
	ds_read_b128 v[188:191], v147 offset:19456
	ds_read_b128 v[192:195], v147 offset:20480
	ds_read_b128 v[196:199], v147 offset:21504
	ds_read_b128 v[200:203], v147 offset:22528
	ds_read_b128 v[204:207], v147 offset:23552
	global_load_lds_dwordx4 v[208:209], off
	s_add_i32 m0, s77, 0x2000
	s_add_u32 s78, s14, 0x40000
	v_lshl_add_u64 v[210:211], s[14:15], 0, v[134:135]
	s_addc_u32 s79, s15, 0
	s_add_i32 s77, s58, s7
	global_load_lds_dwordx4 v[210:211], off
	v_lshl_add_u64 v[212:213], s[78:79], 0, v[130:131]
	s_mov_b32 m0, s77
	v_lshl_add_u64 v[214:215], s[46:47], 0, v[132:133]
	global_load_lds_dwordx4 v[212:213], off
	v_lshl_add_u64 v[212:213], s[78:79], 0, v[134:135]
	s_add_i32 m0, s77, 0x2000
	s_nop 0
	global_load_lds_dwordx4 v[212:213], off
	v_lshl_add_u64 v[212:213], s[46:47], 0, v[128:129]
	s_mov_b32 m0, s45
	s_nop 0
	global_load_lds_dwordx4 v[212:213], off
	s_mov_b32 m0, s49
	s_nop 0
	global_load_lds_dwordx4 v[214:215], off
	s_cmp_lg_u32 s100, 0
	s_cbranch_scc0 .Lrf_1099_1
	s_waitcnt vmcnt(16)
	s_branch .Lrj_1099_1

; #define G_STAGE(bufoff, gbase, voff) do { _Pragma("unroll") for (int _i = 0; _i < 2; ++_i) \
;         __builtin_amdgcn_global_load_lds((const unsigned*)((const char*)(gbase) + voff[_i]), (LAS unsigned*)(lds + (bufoff) + ldsw + _i * 8192), 16, 0, 0); } while (0)
; #define G_LDA(dst, b, h) do { _Pragma("unroll") for (int m = 0; m < 4; ++m) _Pragma("unroll") for (int k = 0; k < 2; ++k) dst[m][k] = *(const LAS bf16x8*)(lds + G_SA(b, h) + aoff + m * 2048 + k * 1024); } while (0)
; #define G_LDB(dst, b, h) do { _Pragma("unroll") for (int n = 0; n < 2; ++n) _Pragma("unroll") for (int k = 0; k < 2; ++k) dst[n][k] = *(const LAS bf16x8*)(lds + G_SB(b, h) + boff + n * 2048 + k * 1024); } while (0)
; #define G_MMA(ai, bj, At_, Bt_) do { __builtin_amdgcn_s_setprio(1); _Pragma("unroll") for (int m = 0; m < 4; ++m) _Pragma("unroll") for (int n = 0; n < 2; ++n) _Pragma("unroll") for (int k = 0; k < 2; ++k) \
;         acc[ai][bj][m][n] = __builtin_amdgcn_mfma_f32_16x16x32_bf16(Bt_[n][k], At_[m][k], acc[ai][bj][m][n], 0, 0, 0); __builtin_amdgcn_s_setprio(0); } while (0)
; #define WAIT_V(n) asm volatile("s_waitcnt vmcnt(" #n ")" ::: "memory")
; #define WAIT_L(n) asm volatile("s_waitcnt lgkmcnt(" #n ")" ::: "memory")
; #define BAR __builtin_amdgcn_s_barrier()
; #define SCHED __builtin_amdgcn_sched_barrier(0)
; template <class Get, class Epi>
; DI void gemm_loop(int ntiles, int ld, char* shm, const Get& get, const Epi& epi) {
;     ...
;             WAIT_V(8); WAIT_L(0); BAR; G_MMA(1, 0, At, B0); G_MMA(1, 1, At, B1); BAR; SCHED;
;             G_LDB(B0, 1, 0); G_LDB(B1, 1, 1); SCHED; G_LDA(At, 1, 0); G_STAGE(G_SA(0, 1), a2 + hstep, voffA);
;             WAIT_V(8); WAIT_L(0); BAR; G_MMA(0, 0, At, B0); G_MMA(0, 1, At, B1); BAR; SCHED;
.Lrj_1099_1:
	s_waitcnt lgkmcnt(0)
	s_barrier
	s_waitcnt lgkmcnt(0)
	v_mfma_f32_16x16x32_bf16 v[60:63], v[140:143], v[176:179], 0
	v_mfma_f32_16x16x32_bf16 v[56:59], v[152:155], v[176:179], 0
	v_mfma_f32_16x16x32_bf16 v[52:55], v[140:143], v[184:187], 0
	v_mfma_f32_16x16x32_bf16 v[48:51], v[152:155], v[184:187], 0
	v_mfma_f32_16x16x32_bf16 v[44:47], v[140:143], v[192:195], 0
	v_mfma_f32_16x16x32_bf16 v[36:39], v[152:155], v[192:195], 0
	v_mfma_f32_16x16x32_bf16 v[28:31], v[140:143], v[200:203], 0
	v_mfma_f32_16x16x32_bf16 v[20:23], v[152:155], v[200:203], 0
	v_mfma_f32_16x16x32_bf16 v[60:63], v[148:151], v[180:183], v[60:63]
	v_mfma_f32_16x16x32_bf16 v[56:59], v[156:159], v[180:183], v[56:59]
	v_mfma_f32_16x16x32_bf16 v[52:55], v[148:151], v[188:191], v[52:55]
	v_mfma_f32_16x16x32_bf16 v[48:51], v[156:159], v[188:191], v[48:51]
	v_mfma_f32_16x16x32_bf16 v[44:47], v[148:151], v[196:199], v[44:47]
	v_mfma_f32_16x16x32_bf16 v[36:39], v[156:159], v[196:199], v[36:39]
	v_mfma_f32_16x16x32_bf16 v[28:31], v[148:151], v[204:207], v[28:31]
	v_mfma_f32_16x16x32_bf16 v[20:23], v[156:159], v[204:207], v[20:23]
	v_mfma_f32_16x16x32_bf16 v[40:43], v[160:163], v[176:179], 0
	v_mfma_f32_16x16x32_bf16 v[32:35], v[168:171], v[176:179], 0
	v_mfma_f32_16x16x32_bf16 v[24:27], v[160:163], v[184:187], 0
	v_mfma_f32_16x16x32_bf16 v[16:19], v[168:171], v[184:187], 0
	v_mfma_f32_16x16x32_bf16 v[12:15], v[160:163], v[192:195], 0
	v_mfma_f32_16x16x32_bf16 v[8:11], v[168:171], v[192:195], 0
	v_mfma_f32_16x16x32_bf16 v[4:7], v[160:163], v[200:203], 0
	v_mfma_f32_16x16x32_bf16 v[0:3], v[168:171], v[200:203], 0
	v_mfma_f32_16x16x32_bf16 v[40:43], v[164:167], v[180:183], v[40:43]
	v_mfma_f32_16x16x32_bf16 v[32:35], v[172:175], v[180:183], v[32:35]
	v_mfma_f32_16x16x32_bf16 v[24:27], v[164:167], v[188:191], v[24:27]
	v_mfma_f32_16x16x32_bf16 v[16:19], v[172:175], v[188:191], v[16:19]
	v_mfma_f32_16x16x32_bf16 v[12:15], v[164:167], v[196:199], v[12:15]
	v_mfma_f32_16x16x32_bf16 v[8:11], v[172:175], v[196:199], v[8:11]
	v_mfma_f32_16x16x32_bf16 v[4:7], v[164:167], v[204:207], v[4:7]
	v_mfma_f32_16x16x32_bf16 v[0:3], v[172:175], v[204:207], v[0:3]
	s_barrier
	s_add_i32 s77, 0, 0x18000
	s_add_i32 s78, 0, 0x1c000
	v_add_u32_e32 v156, s77, v144
	v_add_u32_e32 v172, s78, v144
	ds_read_b128 v[140:143], v156
	ds_read_b128 v[148:151], v156 offset:1024
	ds_read_b128 v[152:155], v156 offset:2048
	ds_read_b128 v[156:159], v156 offset:3072
	ds_read_b128 v[160:163], v172
	ds_read_b128 v[164:167], v172 offset:1024
	ds_read_b128 v[168:171], v172 offset:2048
	ds_read_b128 v[172:175], v172 offset:3072
	s_add_u32 s46, s46, 0x40000
	s_addc_u32 s47, s47, 0
	s_mov_b32 m0, s50
	v_lshl_add_u64 v[216:217], s[46:47], 0, v[128:129]
	ds_read_b128 v[176:179], v147 offset:32768
	ds_read_b128 v[180:183], v147 offset:33792
	ds_read_b128 v[184:187], v147 offset:34816
	ds_read_b128 v[188:191], v147 offset:35840
	ds_read_b128 v[192:195], v147 offset:36864
	ds_read_b128 v[196:199], v147 offset:37888
	ds_read_b128 v[200:203], v147 offset:38912
	ds_read_b128 v[204:207], v147 offset:39936
	global_load_lds_dwordx4 v[216:217], off
	v_lshl_add_u64 v[216:217], s[46:47], 0, v[132:133]
	s_mov_b32 m0, s51
	s_nop 0
	global_load_lds_dwordx4 v[216:217], off
	s_waitcnt vmcnt(8)
	s_waitcnt lgkmcnt(0)
	s_barrier
	s_waitcnt lgkmcnt(0)
	v_mfma_f32_16x16x32_bf16 v[124:127], v[140:143], v[176:179], v[124:127]
	v_mfma_f32_16x16x32_bf16 v[120:123], v[152:155], v[176:179], v[120:123]
	v_mfma_f32_16x16x32_bf16 v[116:119], v[140:143], v[184:187], v[116:119]
	v_mfma_f32_16x16x32_bf16 v[112:115], v[152:155], v[184:187], v[112:115]
	v_mfma_f32_16x16x32_bf16 v[108:111], v[140:143], v[192:195], v[108:111]
	v_mfma_f32_16x16x32_bf16 v[100:103], v[152:155], v[192:195], v[100:103]
	v_mfma_f32_16x16x32_bf16 v[92:95], v[140:143], v[200:203], v[92:95]
	v_mfma_f32_16x16x32_bf16 v[84:87], v[152:155], v[200:203], v[84:87]
	v_mfma_f32_16x16x32_bf16 v[124:127], v[148:151], v[180:183], v[124:127]
	v_mfma_f32_16x16x32_bf16 v[120:123], v[156:159], v[180:183], v[120:123]
	v_mfma_f32_16x16x32_bf16 v[116:119], v[148:151], v[188:191], v[116:119]
	v_mfma_f32_16x16x32_bf16 v[112:115], v[156:159], v[188:191], v[112:115]
	v_mfma_f32_16x16x32_bf16 v[108:111], v[148:151], v[196:199], v[108:111]
	v_mfma_f32_16x16x32_bf16 v[100:103], v[156:159], v[196:199], v[100:103]
	v_mfma_f32_16x16x32_bf16 v[92:95], v[148:151], v[204:207], v[92:95]
	v_mfma_f32_16x16x32_bf16 v[84:87], v[156:159], v[204:207], v[84:87]
	v_mfma_f32_16x16x32_bf16 v[104:107], v[160:163], v[176:179], v[104:107]
	v_mfma_f32_16x16x32_bf16 v[96:99], v[168:171], v[176:179], v[96:99]
	v_mfma_f32_16x16x32_bf16 v[88:91], v[160:163], v[184:187], v[88:91]
	v_mfma_f32_16x16x32_bf16 v[80:83], v[168:171], v[184:187], v[80:83]
	v_mfma_f32_16x16x32_bf16 v[76:79], v[160:163], v[192:195], v[76:79]
	v_mfma_f32_16x16x32_bf16 v[72:75], v[168:171], v[192:195], v[72:75]
	v_mfma_f32_16x16x32_bf16 v[68:71], v[160:163], v[200:203], v[68:71]
	v_mfma_f32_16x16x32_bf16 v[64:67], v[168:171], v[200:203], v[64:67]
	v_mfma_f32_16x16x32_bf16 v[104:107], v[164:167], v[180:183], v[104:107]
	v_mfma_f32_16x16x32_bf16 v[96:99], v[172:175], v[180:183], v[96:99]
	v_mfma_f32_16x16x32_bf16 v[88:91], v[164:167], v[188:191], v[88:91]
	v_mfma_f32_16x16x32_bf16 v[80:83], v[172:175], v[188:191], v[80:83]
	v_mfma_f32_16x16x32_bf16 v[76:79], v[164:167], v[196:199], v[76:79]
	v_mfma_f32_16x16x32_bf16 v[72:75], v[172:175], v[196:199], v[72:75]
	v_mfma_f32_16x16x32_bf16 v[68:71], v[164:167], v[204:207], v[68:71]
	v_mfma_f32_16x16x32_bf16 v[64:67], v[172:175], v[204:207], v[64:67]
	s_barrier
; #define G_STAGE(bufoff, gbase, voff) do { _Pragma("unroll") for (int _i = 0; _i < 2; ++_i) \
;         __builtin_amdgcn_global_load_lds((const unsigned*)((const char*)(gbase) + voff[_i]), (LAS unsigned*)(lds + (bufoff) + ldsw + _i * 8192), 16, 0, 0); } while (0)
; #define G_LDA(dst, b, h) do { _Pragma("unroll") for (int m = 0; m < 4; ++m) _Pragma("unroll") for (int k = 0; k < 2; ++k) dst[m][k] = *(const LAS bf16x8*)(lds + G_SA(b, h) + aoff + m * 2048 + k * 1024); } while (0)
; #define G_LDB(dst, b, h) do { _Pragma("unroll") for (int n = 0; n < 2; ++n) _Pragma("unroll") for (int k = 0; k < 2; ++k) dst[n][k] = *(const LAS bf16x8*)(lds + G_SB(b, h) + boff + n * 2048 + k * 1024); } while (0)
; #define G_MMA(ai, bj, At_, Bt_) do { __builtin_amdgcn_s_setprio(1); _Pragma("unroll") for (int m = 0; m < 4; ++m) _Pragma("unroll") for (int n = 0; n < 2; ++n) _Pragma("unroll") for (int k = 0; k < 2; ++k) \
;         acc[ai][bj][m][n] = __builtin_amdgcn_mfma_f32_16x16x32_bf16(Bt_[n][k], At_[m][k], acc[ai][bj][m][n], 0, 0, 0); __builtin_amdgcn_s_setprio(0); } while (0)
; #define WAIT_V(n) asm volatile("s_waitcnt vmcnt(" #n ")" ::: "memory")
; #define WAIT_L(n) asm volatile("s_waitcnt lgkmcnt(" #n ")" ::: "memory")
; #define BAR __builtin_amdgcn_s_barrier()
; #define SCHED __builtin_amdgcn_sched_barrier(0)
; template <class Get, class Epi>
; DI void gemm_loop(int ntiles, int ld, char* shm, const Get& get, const Epi& epi) {
;     ...
;             G_LDB(B0, 0, 0); G_LDB(B1, 0, 1); SCHED; G_LDA(At, 0, 0); G_STAGE(G_SA(1, 1), a1 + hstep, voffA);
;             WAIT_V(8); WAIT_L(0); BAR; G_MMA(0, 0, At, B0); G_MMA(0, 1, At, B1); BAR; SCHED;
;     ...
;             G_LDA(At, 1, 1); G_STAGE(G_SB(1, 0), b3, voffB); G_STAGE(G_SB(1, 1), b3 + hstep, voffB); G_STAGE(G_SA(1, 0), a3, voffA);
;             WAIT_V(8); WAIT_L(0); BAR; G_MMA(1, 0, At, B0); G_MMA(1, 1, At, B1); BAR; SCHED;
;         }
	s_add_i32 s46, s77, s7
	v_lshl_add_u64 v[208:209], v[208:209], 0, s[10:11]
	s_mov_b32 m0, s46
	ds_read_b128 v[176:179], v147 offset:49152
	ds_read_b128 v[180:183], v147 offset:50176
	ds_read_b128 v[184:187], v147 offset:51200
	ds_read_b128 v[188:191], v147 offset:52224
	ds_read_b128 v[192:195], v147 offset:53248
	ds_read_b128 v[196:199], v147 offset:54272
	ds_read_b128 v[200:203], v147 offset:55296
	ds_read_b128 v[204:207], v147 offset:56320
	global_load_lds_dwordx4 v[208:209], off
	s_add_i32 m0, s46, 0x2000
	s_add_u32 s14, s14, 0x40080
	v_lshl_add_u64 v[208:209], v[210:211], 0, s[10:11]
	s_addc_u32 s15, s15, 0
	s_add_i32 s46, s78, s7
	global_load_lds_dwordx4 v[208:209], off
	v_lshl_add_u64 v[208:209], s[14:15], 0, v[130:131]
	s_mov_b32 m0, s46
	s_nop 0
	global_load_lds_dwordx4 v[208:209], off
	v_lshl_add_u64 v[208:209], s[14:15], 0, v[134:135]
	s_add_i32 m0, s46, 0x2000
	s_nop 0
	global_load_lds_dwordx4 v[208:209], off
	v_lshl_add_u64 v[208:209], v[212:213], 0, s[10:11]
	s_mov_b32 m0, s54
	s_nop 0
	global_load_lds_dwordx4 v[208:209], off
	v_lshl_add_u64 v[208:209], v[214:215], 0, s[10:11]
	s_mov_b32 m0, s55
	s_nop 0
	global_load_lds_dwordx4 v[208:209], off
	s_waitcnt vmcnt(8)
	s_waitcnt lgkmcnt(0)
	s_barrier
	s_waitcnt lgkmcnt(0)
	v_mfma_f32_16x16x32_bf16 v[60:63], v[140:143], v[176:179], v[60:63]
	v_mfma_f32_16x16x32_bf16 v[56:59], v[152:155], v[176:179], v[56:59]
	v_mfma_f32_16x16x32_bf16 v[52:55], v[140:143], v[184:187], v[52:55]
	v_mfma_f32_16x16x32_bf16 v[48:51], v[152:155], v[184:187], v[48:51]
	v_mfma_f32_16x16x32_bf16 v[44:47], v[140:143], v[192:195], v[44:47]
	v_mfma_f32_16x16x32_bf16 v[36:39], v[152:155], v[192:195], v[36:39]
	v_mfma_f32_16x16x32_bf16 v[28:31], v[140:143], v[200:203], v[28:31]
	v_mfma_f32_16x16x32_bf16 v[20:23], v[152:155], v[200:203], v[20:23]
	v_mfma_f32_16x16x32_bf16 v[60:63], v[148:151], v[180:183], v[60:63]
	v_mfma_f32_16x16x32_bf16 v[56:59], v[156:159], v[180:183], v[56:59]
	v_mfma_f32_16x16x32_bf16 v[52:55], v[148:151], v[188:191], v[52:55]
	v_mfma_f32_16x16x32_bf16 v[48:51], v[156:159], v[188:191], v[48:51]
	v_mfma_f32_16x16x32_bf16 v[44:47], v[148:151], v[196:199], v[44:47]
	v_mfma_f32_16x16x32_bf16 v[36:39], v[156:159], v[196:199], v[36:39]
	v_mfma_f32_16x16x32_bf16 v[28:31], v[148:151], v[204:207], v[28:31]
	v_mfma_f32_16x16x32_bf16 v[20:23], v[156:159], v[204:207], v[20:23]
	v_mfma_f32_16x16x32_bf16 v[40:43], v[160:163], v[176:179], v[40:43]
	v_mfma_f32_16x16x32_bf16 v[32:35], v[168:171], v[176:179], v[32:35]
	v_mfma_f32_16x16x32_bf16 v[24:27], v[160:163], v[184:187], v[24:27]
	v_mfma_f32_16x16x32_bf16 v[16:19], v[168:171], v[184:187], v[16:19]
	v_mfma_f32_16x16x32_bf16 v[12:15], v[160:163], v[192:195], v[12:15]
	v_mfma_f32_16x16x32_bf16 v[8:11], v[168:171], v[192:195], v[8:11]
	v_mfma_f32_16x16x32_bf16 v[4:7], v[160:163], v[200:203], v[4:7]
	v_mfma_f32_16x16x32_bf16 v[0:3], v[168:171], v[200:203], v[0:3]
	v_mfma_f32_16x16x32_bf16 v[40:43], v[164:167], v[180:183], v[40:43]
	v_mfma_f32_16x16x32_bf16 v[32:35], v[172:175], v[180:183], v[32:35]
	v_mfma_f32_16x16x32_bf16 v[24:27], v[164:167], v[188:191], v[24:27]
	v_mfma_f32_16x16x32_bf16 v[16:19], v[172:175], v[188:191], v[16:19]
	v_mfma_f32_16x16x32_bf16 v[12:15], v[164:167], v[196:199], v[12:15]
	v_mfma_f32_16x16x32_bf16 v[8:11], v[172:175], v[196:199], v[8:11]
	v_mfma_f32_16x16x32_bf16 v[4:7], v[164:167], v[204:207], v[4:7]
	v_mfma_f32_16x16x32_bf16 v[0:3], v[172:175], v[204:207], v[0:3]
	s_barrier
	s_add_i32 s76, s76, 2
	s_add_u32 s52, s52, 0x100
	s_addc_u32 s53, s53, 0
	s_add_u32 s74, s74, 0x100
	s_addc_u32 s75, s75, 0
	s_cmp_gt_u32 s76, 13
	s_cbranch_scc0 .LBB0_1099
	s_branch .Lpost_1099
.LBB0_1099:
	ds_read_b128 v[140:143], v145
	ds_read_b128 v[148:151], v145 offset:1024
	ds_read_b128 v[152:155], v145 offset:2048
	ds_read_b128 v[156:159], v145 offset:3072
	ds_read_b128 v[160:163], v146
	ds_read_b128 v[164:167], v146 offset:1024
	ds_read_b128 v[168:171], v146 offset:2048
	ds_read_b128 v[172:175], v146 offset:3072
	s_add_u32 s14, s52, 0xfffc0080
	s_addc_u32 s15, s53, -1
	s_cmp_eq_u32 s76, 12
	s_cselect_b32 s47, s39, s15
	s_cselect_b32 s46, s72, s14
	s_cselect_b32 s15, s37, s75
	s_cselect_b32 s14, s73, s74
	v_lshl_add_u64 v[208:209], s[52:53], 0, v[136:137]
	s_add_i32 m0, s45, 0xc000
	ds_read_b128 v[176:179], v147
	ds_read_b128 v[180:183], v147 offset:1024
	ds_read_b128 v[184:187], v147 offset:2048
	ds_read_b128 v[188:191], v147 offset:3072
	ds_read_b128 v[192:195], v147 offset:4096
	ds_read_b128 v[196:199], v147 offset:5120
	ds_read_b128 v[200:203], v147 offset:6144
	ds_read_b128 v[204:207], v147 offset:7168
	global_load_lds_dwordx4 v[208:209], off
	v_lshl_add_u64 v[208:209], s[52:53], 0, v[138:139]
	s_add_i32 m0, s45, 0xe000
	s_nop 0
	global_load_lds_dwordx4 v[208:209], off
	s_waitcnt vmcnt(8)
	s_waitcnt lgkmcnt(0)
	s_barrier
; #define G_STAGE(bufoff, gbase, voff) do { _Pragma("unroll") for (int _i = 0; _i < 2; ++_i) \
;         __builtin_amdgcn_global_load_lds((const unsigned*)((const char*)(gbase) + voff[_i]), (LAS unsigned*)(lds + (bufoff) + ldsw + _i * 8192), 16, 0, 0); } while (0)
; #define G_LDA(dst, b, h) do { _Pragma("unroll") for (int m = 0; m < 4; ++m) _Pragma("unroll") for (int k = 0; k < 2; ++k) dst[m][k] = *(const LAS bf16x8*)(lds + G_SA(b, h) + aoff + m * 2048 + k * 1024); } while (0)
; #define G_MMA(ai, bj, At_, Bt_) do { __builtin_amdgcn_s_setprio(1); _Pragma("unroll") for (int m = 0; m < 4; ++m) _Pragma("unroll") for (int n = 0; n < 2; ++n) _Pragma("unroll") for (int k = 0; k < 2; ++k) \
;         acc[ai][bj][m][n] = __builtin_amdgcn_mfma_f32_16x16x32_bf16(Bt_[n][k], At_[m][k], acc[ai][bj][m][n], 0, 0, 0); __builtin_amdgcn_s_setprio(0); } while (0)
; #define WAIT_V(n) asm volatile("s_waitcnt vmcnt(" #n ")" ::: "memory")
; #define WAIT_L(n) asm volatile("s_waitcnt lgkmcnt(" #n ")" ::: "memory")
; #define BAR __builtin_amdgcn_s_barrier()
; #define SCHED __builtin_amdgcn_sched_barrier(0)
; template <class Get, class Epi>
; DI void gemm_loop(int ntiles, int ld, char* shm, const Get& get, const Epi& epi) {
;     ...
;             WAIT_V(8); WAIT_L(0); BAR; G_MMA(0, 0, At, B0); G_MMA(0, 1, At, B1); BAR; SCHED;
;             G_LDA(At, 0, 1); G_STAGE(G_SB(0, 0), b2, voffB); G_STAGE(G_SB(0, 1), b2 + hstep, voffB); G_STAGE(G_SA(0, 0), a2, voffA);
;             WAIT_V(8); WAIT_L(0); BAR; G_MMA(1, 0, At, B0); G_MMA(1, 1, At, B1); BAR; SCHED;
	s_waitcnt lgkmcnt(0)
	v_mfma_f32_16x16x32_bf16 v[124:127], v[140:143], v[176:179], v[124:127]
	v_mfma_f32_16x16x32_bf16 v[120:123], v[152:155], v[176:179], v[120:123]
	v_mfma_f32_16x16x32_bf16 v[116:119], v[140:143], v[184:187], v[116:119]
	v_mfma_f32_16x16x32_bf16 v[112:115], v[152:155], v[184:187], v[112:115]
	v_mfma_f32_16x16x32_bf16 v[108:111], v[140:143], v[192:195], v[108:111]
	v_mfma_f32_16x16x32_bf16 v[100:103], v[152:155], v[192:195], v[100:103]
	v_mfma_f32_16x16x32_bf16 v[92:95], v[140:143], v[200:203], v[92:95]
	v_mfma_f32_16x16x32_bf16 v[84:87], v[152:155], v[200:203], v[84:87]
	v_mfma_f32_16x16x32_bf16 v[124:127], v[148:151], v[180:183], v[124:127]
	v_mfma_f32_16x16x32_bf16 v[120:123], v[156:159], v[180:183], v[120:123]
	v_mfma_f32_16x16x32_bf16 v[116:119], v[148:151], v[188:191], v[116:119]
	v_mfma_f32_16x16x32_bf16 v[112:115], v[156:159], v[188:191], v[112:115]
	v_mfma_f32_16x16x32_bf16 v[108:111], v[148:151], v[196:199], v[108:111]
	v_mfma_f32_16x16x32_bf16 v[100:103], v[156:159], v[196:199], v[100:103]
	v_mfma_f32_16x16x32_bf16 v[92:95], v[148:151], v[204:207], v[92:95]
	v_mfma_f32_16x16x32_bf16 v[84:87], v[156:159], v[204:207], v[84:87]
	v_mfma_f32_16x16x32_bf16 v[104:107], v[160:163], v[176:179], v[104:107]
	v_mfma_f32_16x16x32_bf16 v[96:99], v[168:171], v[176:179], v[96:99]
	v_mfma_f32_16x16x32_bf16 v[88:91], v[160:163], v[184:187], v[88:91]
	v_mfma_f32_16x16x32_bf16 v[80:83], v[168:171], v[184:187], v[80:83]
	v_mfma_f32_16x16x32_bf16 v[76:79], v[160:163], v[192:195], v[76:79]
	v_mfma_f32_16x16x32_bf16 v[72:75], v[168:171], v[192:195], v[72:75]
	v_mfma_f32_16x16x32_bf16 v[68:71], v[160:163], v[200:203], v[68:71]
	v_mfma_f32_16x16x32_bf16 v[64:67], v[168:171], v[200:203], v[64:67]
	v_mfma_f32_16x16x32_bf16 v[104:107], v[164:167], v[180:183], v[104:107]
	v_mfma_f32_16x16x32_bf16 v[96:99], v[172:175], v[180:183], v[96:99]
	v_mfma_f32_16x16x32_bf16 v[88:91], v[164:167], v[188:191], v[88:91]
	v_mfma_f32_16x16x32_bf16 v[80:83], v[172:175], v[188:191], v[80:83]
	v_mfma_f32_16x16x32_bf16 v[76:79], v[164:167], v[196:199], v[76:79]
	v_mfma_f32_16x16x32_bf16 v[72:75], v[172:175], v[196:199], v[72:75]
	v_mfma_f32_16x16x32_bf16 v[68:71], v[164:167], v[204:207], v[68:71]
	v_mfma_f32_16x16x32_bf16 v[64:67], v[172:175], v[204:207], v[64:67]
	s_barrier
	s_add_i32 s77, s57, s7
	v_lshl_add_u64 v[208:209], s[14:15], 0, v[130:131]
	s_mov_b32 m0, s77
	ds_read_b128 v[176:179], v147 offset:16384
	ds_read_b128 v[180:183], v147 offset:17408
	ds_read_b128 v[184:187], v147 offset:18432
	ds_read_b128 v[188:191], v147 offset:19456
	ds_read_b128 v[192:195], v147 offset:20480
	ds_read_b128 v[196:199], v147 offset:21504
	ds_read_b128 v[200:203], v147 offset:22528
	ds_read_b128 v[204:207], v147 offset:23552
	global_load_lds_dwordx4 v[208:209], off
	s_add_i32 m0, s77, 0x2000
	s_add_u32 s78, s14, 0x40000
	v_lshl_add_u64 v[210:211], s[14:15], 0, v[134:135]
	s_addc_u32 s79, s15, 0
	s_add_i32 s77, s58, s7
	global_load_lds_dwordx4 v[210:211], off
	v_lshl_add_u64 v[212:213], s[78:79], 0, v[130:131]
	s_mov_b32 m0, s77
	v_lshl_add_u64 v[214:215], s[46:47], 0, v[132:133]
	global_load_lds_dwordx4 v[212:213], off
	v_lshl_add_u64 v[212:213], s[78:79], 0, v[134:135]
	s_add_i32 m0, s77, 0x2000
	s_nop 0
	global_load_lds_dwordx4 v[212:213], off
	v_lshl_add_u64 v[212:213], s[46:47], 0, v[128:129]
	s_mov_b32 m0, s45
	s_nop 0
	global_load_lds_dwordx4 v[212:213], off
	s_mov_b32 m0, s49
	s_nop 0
	global_load_lds_dwordx4 v[214:215], off
	s_waitcnt vmcnt(8)
	s_waitcnt lgkmcnt(0)
	s_barrier
	s_waitcnt lgkmcnt(0)
	v_mfma_f32_16x16x32_bf16 v[60:63], v[140:143], v[176:179], v[60:63]
	v_mfma_f32_16x16x32_bf16 v[56:59], v[152:155], v[176:179], v[56:59]
	v_mfma_f32_16x16x32_bf16 v[52:55], v[140:143], v[184:187], v[52:55]
	v_mfma_f32_16x16x32_bf16 v[48:51], v[152:155], v[184:187], v[48:51]
	v_mfma_f32_16x16x32_bf16 v[44:47], v[140:143], v[192:195], v[44:47]
	v_mfma_f32_16x16x32_bf16 v[36:39], v[152:155], v[192:195], v[36:39]
	v_mfma_f32_16x16x32_bf16 v[28:31], v[140:143], v[200:203], v[28:31]
	v_mfma_f32_16x16x32_bf16 v[20:23], v[152:155], v[200:203], v[20:23]
	v_mfma_f32_16x16x32_bf16 v[60:63], v[148:151], v[180:183], v[60:63]
	v_mfma_f32_16x16x32_bf16 v[56:59], v[156:159], v[180:183], v[56:59]
	v_mfma_f32_16x16x32_bf16 v[52:55], v[148:151], v[188:191], v[52:55]
	v_mfma_f32_16x16x32_bf16 v[48:51], v[156:159], v[188:191], v[48:51]
	v_mfma_f32_16x16x32_bf16 v[44:47], v[148:151], v[196:199], v[44:47]
	v_mfma_f32_16x16x32_bf16 v[36:39], v[156:159], v[196:199], v[36:39]
	v_mfma_f32_16x16x32_bf16 v[28:31], v[148:151], v[204:207], v[28:31]
	v_mfma_f32_16x16x32_bf16 v[20:23], v[156:159], v[204:207], v[20:23]
	v_mfma_f32_16x16x32_bf16 v[40:43], v[160:163], v[176:179], v[40:43]
	v_mfma_f32_16x16x32_bf16 v[32:35], v[168:171], v[176:179], v[32:35]
	v_mfma_f32_16x16x32_bf16 v[24:27], v[160:163], v[184:187], v[24:27]
	v_mfma_f32_16x16x32_bf16 v[16:19], v[168:171], v[184:187], v[16:19]
	v_mfma_f32_16x16x32_bf16 v[12:15], v[160:163], v[192:195], v[12:15]
	v_mfma_f32_16x16x32_bf16 v[8:11], v[168:171], v[192:195], v[8:11]
	v_mfma_f32_16x16x32_bf16 v[4:7], v[160:163], v[200:203], v[4:7]
	v_mfma_f32_16x16x32_bf16 v[0:3], v[168:171], v[200:203], v[0:3]
	v_mfma_f32_16x16x32_bf16 v[40:43], v[164:167], v[180:183], v[40:43]
	v_mfma_f32_16x16x32_bf16 v[32:35], v[172:175], v[180:183], v[32:35]
	v_mfma_f32_16x16x32_bf16 v[24:27], v[164:167], v[188:191], v[24:27]
	v_mfma_f32_16x16x32_bf16 v[16:19], v[172:175], v[188:191], v[16:19]
	v_mfma_f32_16x16x32_bf16 v[12:15], v[164:167], v[196:199], v[12:15]
	v_mfma_f32_16x16x32_bf16 v[8:11], v[172:175], v[196:199], v[8:11]
	v_mfma_f32_16x16x32_bf16 v[4:7], v[164:167], v[204:207], v[4:7]
	v_mfma_f32_16x16x32_bf16 v[0:3], v[172:175], v[204:207], v[0:3]
	s_barrier
; #define G_STAGE(bufoff, gbase, voff) do { _Pragma("unroll") for (int _i = 0; _i < 2; ++_i) \
;         __builtin_amdgcn_global_load_lds((const unsigned*)((const char*)(gbase) + voff[_i]), (LAS unsigned*)(lds + (bufoff) + ldsw + _i * 8192), 16, 0, 0); } while (0)
; #define G_LDA(dst, b, h) do { _Pragma("unroll") for (int m = 0; m < 4; ++m) _Pragma("unroll") for (int k = 0; k < 2; ++k) dst[m][k] = *(const LAS bf16x8*)(lds + G_SA(b, h) + aoff + m * 2048 + k * 1024); } while (0)
; #define G_LDB(dst, b, h) do { _Pragma("unroll") for (int n = 0; n < 2; ++n) _Pragma("unroll") for (int k = 0; k < 2; ++k) dst[n][k] = *(const LAS bf16x8*)(lds + G_SB(b, h) + boff + n * 2048 + k * 1024); } while (0)
; #define G_MMA(ai, bj, At_, Bt_) do { __builtin_amdgcn_s_setprio(1); _Pragma("unroll") for (int m = 0; m < 4; ++m) _Pragma("unroll") for (int n = 0; n < 2; ++n) _Pragma("unroll") for (int k = 0; k < 2; ++k) \
;         acc[ai][bj][m][n] = __builtin_amdgcn_mfma_f32_16x16x32_bf16(Bt_[n][k], At_[m][k], acc[ai][bj][m][n], 0, 0, 0); __builtin_amdgcn_s_setprio(0); } while (0)
; #define WAIT_V(n) asm volatile("s_waitcnt vmcnt(" #n ")" ::: "memory")
; #define WAIT_L(n) asm volatile("s_waitcnt lgkmcnt(" #n ")" ::: "memory")
; #define BAR __builtin_amdgcn_s_barrier()
; #define SCHED __builtin_amdgcn_sched_barrier(0)
; template <class Get, class Epi>
; DI void gemm_loop(int ntiles, int ld, char* shm, const Get& get, const Epi& epi) {
;     ...
;             G_LDB(B0, 1, 0); G_LDB(B1, 1, 1); SCHED; G_LDA(At, 1, 0); G_STAGE(G_SA(0, 1), a2 + hstep, voffA);
;             WAIT_V(8); WAIT_L(0); BAR; G_MMA(0, 0, At, B0); G_MMA(0, 1, At, B1); BAR; SCHED;
;             G_LDA(At, 1, 1); G_STAGE(G_SB(1, 0), b3, voffB); G_STAGE(G_SB(1, 1), b3 + hstep, voffB); G_STAGE(G_SA(1, 0), a3, voffA);
;             WAIT_V(8); WAIT_L(0); BAR; G_MMA(1, 0, At, B0); G_MMA(1, 1, At, B1); BAR; SCHED;
;         }
	s_add_i32 s77, 0, 0x18000
	s_add_i32 s78, 0, 0x1c000
	v_add_u32_e32 v156, s77, v144
	v_add_u32_e32 v172, s78, v144
	ds_read_b128 v[140:143], v156
	ds_read_b128 v[148:151], v156 offset:1024
	ds_read_b128 v[152:155], v156 offset:2048
	ds_read_b128 v[156:159], v156 offset:3072
	ds_read_b128 v[160:163], v172
	ds_read_b128 v[164:167], v172 offset:1024
	ds_read_b128 v[168:171], v172 offset:2048
	ds_read_b128 v[172:175], v172 offset:3072
	s_add_u32 s46, s46, 0x40000
	s_addc_u32 s47, s47, 0
	s_mov_b32 m0, s50
	v_lshl_add_u64 v[216:217], s[46:47], 0, v[128:129]
	ds_read_b128 v[176:179], v147 offset:32768
	ds_read_b128 v[180:183], v147 offset:33792
	ds_read_b128 v[184:187], v147 offset:34816
	ds_read_b128 v[188:191], v147 offset:35840
	ds_read_b128 v[192:195], v147 offset:36864
	ds_read_b128 v[196:199], v147 offset:37888
	ds_read_b128 v[200:203], v147 offset:38912
	ds_read_b128 v[204:207], v147 offset:39936
	global_load_lds_dwordx4 v[216:217], off
	v_lshl_add_u64 v[216:217], s[46:47], 0, v[132:133]
	s_mov_b32 m0, s51
	s_nop 0
	global_load_lds_dwordx4 v[216:217], off
	s_waitcnt vmcnt(8)
	s_waitcnt lgkmcnt(0)
	s_barrier
	s_waitcnt lgkmcnt(0)
	v_mfma_f32_16x16x32_bf16 v[124:127], v[140:143], v[176:179], v[124:127]
	v_mfma_f32_16x16x32_bf16 v[120:123], v[152:155], v[176:179], v[120:123]
	v_mfma_f32_16x16x32_bf16 v[116:119], v[140:143], v[184:187], v[116:119]
	v_mfma_f32_16x16x32_bf16 v[112:115], v[152:155], v[184:187], v[112:115]
	v_mfma_f32_16x16x32_bf16 v[108:111], v[140:143], v[192:195], v[108:111]
	v_mfma_f32_16x16x32_bf16 v[100:103], v[152:155], v[192:195], v[100:103]
	v_mfma_f32_16x16x32_bf16 v[92:95], v[140:143], v[200:203], v[92:95]
	v_mfma_f32_16x16x32_bf16 v[84:87], v[152:155], v[200:203], v[84:87]
	v_mfma_f32_16x16x32_bf16 v[124:127], v[148:151], v[180:183], v[124:127]
	v_mfma_f32_16x16x32_bf16 v[120:123], v[156:159], v[180:183], v[120:123]
	v_mfma_f32_16x16x32_bf16 v[116:119], v[148:151], v[188:191], v[116:119]
	v_mfma_f32_16x16x32_bf16 v[112:115], v[156:159], v[188:191], v[112:115]
	v_mfma_f32_16x16x32_bf16 v[108:111], v[148:151], v[196:199], v[108:111]
	v_mfma_f32_16x16x32_bf16 v[100:103], v[156:159], v[196:199], v[100:103]
	v_mfma_f32_16x16x32_bf16 v[92:95], v[148:151], v[204:207], v[92:95]
	v_mfma_f32_16x16x32_bf16 v[84:87], v[156:159], v[204:207], v[84:87]
	v_mfma_f32_16x16x32_bf16 v[104:107], v[160:163], v[176:179], v[104:107]
	v_mfma_f32_16x16x32_bf16 v[96:99], v[168:171], v[176:179], v[96:99]
	v_mfma_f32_16x16x32_bf16 v[88:91], v[160:163], v[184:187], v[88:91]
	v_mfma_f32_16x16x32_bf16 v[80:83], v[168:171], v[184:187], v[80:83]
	v_mfma_f32_16x16x32_bf16 v[76:79], v[160:163], v[192:195], v[76:79]
	v_mfma_f32_16x16x32_bf16 v[72:75], v[168:171], v[192:195], v[72:75]
	v_mfma_f32_16x16x32_bf16 v[68:71], v[160:163], v[200:203], v[68:71]
	v_mfma_f32_16x16x32_bf16 v[64:67], v[168:171], v[200:203], v[64:67]
	v_mfma_f32_16x16x32_bf16 v[104:107], v[164:167], v[180:183], v[104:107]
	v_mfma_f32_16x16x32_bf16 v[96:99], v[172:175], v[180:183], v[96:99]
	v_mfma_f32_16x16x32_bf16 v[88:91], v[164:167], v[188:191], v[88:91]
	v_mfma_f32_16x16x32_bf16 v[80:83], v[172:175], v[188:191], v[80:83]
	v_mfma_f32_16x16x32_bf16 v[76:79], v[164:167], v[196:199], v[76:79]
	v_mfma_f32_16x16x32_bf16 v[72:75], v[172:175], v[196:199], v[72:75]
	v_mfma_f32_16x16x32_bf16 v[68:71], v[164:167], v[204:207], v[68:71]
	v_mfma_f32_16x16x32_bf16 v[64:67], v[172:175], v[204:207], v[64:67]
	s_barrier
	s_add_i32 s46, s77, s7
	v_lshl_add_u64 v[208:209], v[208:209], 0, s[10:11]
	s_mov_b32 m0, s46
	ds_read_b128 v[176:179], v147 offset:49152
	ds_read_b128 v[180:183], v147 offset:50176
	ds_read_b128 v[184:187], v147 offset:51200
	ds_read_b128 v[188:191], v147 offset:52224
	ds_read_b128 v[192:195], v147 offset:53248
	ds_read_b128 v[196:199], v147 offset:54272
	ds_read_b128 v[200:203], v147 offset:55296
	ds_read_b128 v[204:207], v147 offset:56320
	global_load_lds_dwordx4 v[208:209], off
	s_add_i32 m0, s46, 0x2000
	s_add_u32 s14, s14, 0x40080
	v_lshl_add_u64 v[208:209], v[210:211], 0, s[10:11]
	s_addc_u32 s15, s15, 0
	s_add_i32 s46, s78, s7
	global_load_lds_dwordx4 v[208:209], off
	v_lshl_add_u64 v[208:209], s[14:15], 0, v[130:131]
	s_mov_b32 m0, s46
	s_nop 0
	global_load_lds_dwordx4 v[208:209], off
	v_lshl_add_u64 v[208:209], s[14:15], 0, v[134:135]
	s_add_i32 m0, s46, 0x2000
	s_nop 0
	global_load_lds_dwordx4 v[208:209], off
	v_lshl_add_u64 v[208:209], v[212:213], 0, s[10:11]
	s_mov_b32 m0, s54
	s_nop 0
	global_load_lds_dwordx4 v[208:209], off
	v_lshl_add_u64 v[208:209], v[214:215], 0, s[10:11]
	s_mov_b32 m0, s55
	s_nop 0
	global_load_lds_dwordx4 v[208:209], off
	s_waitcnt vmcnt(8)
	s_waitcnt lgkmcnt(0)
	s_barrier
	s_waitcnt lgkmcnt(0)
	v_mfma_f32_16x16x32_bf16 v[60:63], v[140:143], v[176:179], v[60:63]
	v_mfma_f32_16x16x32_bf16 v[56:59], v[152:155], v[176:179], v[56:59]
	v_mfma_f32_16x16x32_bf16 v[52:55], v[140:143], v[184:187], v[52:55]
	v_mfma_f32_16x16x32_bf16 v[48:51], v[152:155], v[184:187], v[48:51]
	v_mfma_f32_16x16x32_bf16 v[44:47], v[140:143], v[192:195], v[44:47]
	v_mfma_f32_16x16x32_bf16 v[36:39], v[152:155], v[192:195], v[36:39]
	v_mfma_f32_16x16x32_bf16 v[28:31], v[140:143], v[200:203], v[28:31]
	v_mfma_f32_16x16x32_bf16 v[20:23], v[152:155], v[200:203], v[20:23]
	v_mfma_f32_16x16x32_bf16 v[60:63], v[148:151], v[180:183], v[60:63]
	v_mfma_f32_16x16x32_bf16 v[56:59], v[156:159], v[180:183], v[56:59]
	v_mfma_f32_16x16x32_bf16 v[52:55], v[148:151], v[188:191], v[52:55]
	v_mfma_f32_16x16x32_bf16 v[48:51], v[156:159], v[188:191], v[48:51]
	v_mfma_f32_16x16x32_bf16 v[44:47], v[148:151], v[196:199], v[44:47]
	v_mfma_f32_16x16x32_bf16 v[36:39], v[156:159], v[196:199], v[36:39]
	v_mfma_f32_16x16x32_bf16 v[28:31], v[148:151], v[204:207], v[28:31]
	v_mfma_f32_16x16x32_bf16 v[20:23], v[156:159], v[204:207], v[20:23]
	v_mfma_f32_16x16x32_bf16 v[40:43], v[160:163], v[176:179], v[40:43]
	v_mfma_f32_16x16x32_bf16 v[32:35], v[168:171], v[176:179], v[32:35]
	v_mfma_f32_16x16x32_bf16 v[24:27], v[160:163], v[184:187], v[24:27]
	v_mfma_f32_16x16x32_bf16 v[16:19], v[168:171], v[184:187], v[16:19]
	v_mfma_f32_16x16x32_bf16 v[12:15], v[160:163], v[192:195], v[12:15]
	v_mfma_f32_16x16x32_bf16 v[8:11], v[168:171], v[192:195], v[8:11]
	v_mfma_f32_16x16x32_bf16 v[4:7], v[160:163], v[200:203], v[4:7]
	v_mfma_f32_16x16x32_bf16 v[0:3], v[168:171], v[200:203], v[0:3]
	v_mfma_f32_16x16x32_bf16 v[40:43], v[164:167], v[180:183], v[40:43]
	v_mfma_f32_16x16x32_bf16 v[32:35], v[172:175], v[180:183], v[32:35]
	v_mfma_f32_16x16x32_bf16 v[24:27], v[164:167], v[188:191], v[24:27]
	v_mfma_f32_16x16x32_bf16 v[16:19], v[172:175], v[188:191], v[16:19]
	v_mfma_f32_16x16x32_bf16 v[12:15], v[164:167], v[196:199], v[12:15]
	v_mfma_f32_16x16x32_bf16 v[8:11], v[172:175], v[196:199], v[8:11]
	v_mfma_f32_16x16x32_bf16 v[4:7], v[164:167], v[204:207], v[4:7]
	v_mfma_f32_16x16x32_bf16 v[0:3], v[172:175], v[204:207], v[0:3]
	s_barrier
	s_add_i32 s76, s76, 2
	s_add_u32 s52, s52, 0x100
	s_addc_u32 s53, s53, 0
	s_add_u32 s74, s74, 0x100
	s_addc_u32 s75, s75, 0
	s_cmp_gt_u32 s76, 13
	s_cbranch_scc0 .LBB0_1099

; #define G_STAGE(bufoff, gbase, voff) do { _Pragma("unroll") for (int _i = 0; _i < 2; ++_i) \
;         __builtin_amdgcn_global_load_lds((const unsigned*)((const char*)(gbase) + voff[_i]), (LAS unsigned*)(lds + (bufoff) + ldsw + _i * 8192), 16, 0, 0); } while (0)
; #define G_LDA(dst, b, h) do { _Pragma("unroll") for (int m = 0; m < 4; ++m) _Pragma("unroll") for (int k = 0; k < 2; ++k) dst[m][k] = *(const LAS bf16x8*)(lds + G_SA(b, h) + aoff + m * 2048 + k * 1024); } while (0)
; #define G_MMA(ai, bj, At_, Bt_) do { __builtin_amdgcn_s_setprio(1); _Pragma("unroll") for (int m = 0; m < 4; ++m) _Pragma("unroll") for (int n = 0; n < 2; ++n) _Pragma("unroll") for (int k = 0; k < 2; ++k) \
;         acc[ai][bj][m][n] = __builtin_amdgcn_mfma_f32_16x16x32_bf16(Bt_[n][k], At_[m][k], acc[ai][bj][m][n], 0, 0, 0); __builtin_amdgcn_s_setprio(0); } while (0)
; #define WAIT_V(n) asm volatile("s_waitcnt vmcnt(" #n ")" ::: "memory")
; #define WAIT_L(n) asm volatile("s_waitcnt lgkmcnt(" #n ")" ::: "memory")
; #define BAR __builtin_amdgcn_s_barrier()
; #define SCHED __builtin_amdgcn_sched_barrier(0)
; template <class Get, class Epi>
; DI void gemm_loop(int ntiles, int ld, char* shm, const Get& get, const Epi& epi) {
;     ...
;             WAIT_V(8); WAIT_L(0); BAR; G_MMA(0, 0, At, B0); G_MMA(0, 1, At, B1); BAR; SCHED;
;             G_LDA(At, 0, 1); G_STAGE(G_SB(0, 0), b2, voffB); G_STAGE(G_SB(0, 1), b2 + hstep, voffB); G_STAGE(G_SA(0, 0), a2, voffA);
;             WAIT_V(8); WAIT_L(0); BAR; G_MMA(1, 0, At, B0); G_MMA(1, 1, At, B1); BAR; SCHED;
;     ...
;         G_ZERO;
.Lrj_1463_0:
	s_waitcnt lgkmcnt(0)
	s_barrier
	s_waitcnt lgkmcnt(0)
	v_mfma_f32_16x16x32_bf16 v[124:127], v[128:131], v[180:183], 0
	v_mfma_f32_16x16x32_bf16 v[120:123], v[136:139], v[180:183], 0
	v_mfma_f32_16x16x32_bf16 v[116:119], v[128:131], v[188:191], 0
	v_mfma_f32_16x16x32_bf16 v[112:115], v[136:139], v[188:191], 0
	v_mfma_f32_16x16x32_bf16 v[108:111], v[128:131], v[196:199], 0
	v_mfma_f32_16x16x32_bf16 v[104:107], v[136:139], v[196:199], 0
	v_mfma_f32_16x16x32_bf16 v[100:103], v[128:131], v[204:207], 0
	v_mfma_f32_16x16x32_bf16 v[96:99], v[136:139], v[204:207], 0
	v_mfma_f32_16x16x32_bf16 v[124:127], v[132:135], v[184:187], v[124:127]
	v_mfma_f32_16x16x32_bf16 v[120:123], v[140:143], v[184:187], v[120:123]
	v_mfma_f32_16x16x32_bf16 v[116:119], v[132:135], v[192:195], v[116:119]
	v_mfma_f32_16x16x32_bf16 v[112:115], v[140:143], v[192:195], v[112:115]
	v_mfma_f32_16x16x32_bf16 v[108:111], v[132:135], v[200:203], v[108:111]
	v_mfma_f32_16x16x32_bf16 v[104:107], v[140:143], v[200:203], v[104:107]
	v_mfma_f32_16x16x32_bf16 v[100:103], v[132:135], v[208:211], v[100:103]
	v_mfma_f32_16x16x32_bf16 v[96:99], v[140:143], v[208:211], v[96:99]
	v_mfma_f32_16x16x32_bf16 v[60:63], v[158:161], v[180:183], 0
	v_mfma_f32_16x16x32_bf16 v[56:59], v[172:175], v[180:183], 0
	v_mfma_f32_16x16x32_bf16 v[52:55], v[158:161], v[188:191], 0
	v_mfma_f32_16x16x32_bf16 v[48:51], v[172:175], v[188:191], 0
	v_mfma_f32_16x16x32_bf16 v[44:47], v[158:161], v[196:199], 0
	v_mfma_f32_16x16x32_bf16 v[40:43], v[172:175], v[196:199], 0
	v_mfma_f32_16x16x32_bf16 v[36:39], v[158:161], v[204:207], 0
	v_mfma_f32_16x16x32_bf16 v[32:35], v[172:175], v[204:207], 0
	v_mfma_f32_16x16x32_bf16 v[60:63], v[162:165], v[184:187], v[60:63]
	v_mfma_f32_16x16x32_bf16 v[56:59], v[176:179], v[184:187], v[56:59]
	v_mfma_f32_16x16x32_bf16 v[52:55], v[162:165], v[192:195], v[52:55]
	v_mfma_f32_16x16x32_bf16 v[48:51], v[176:179], v[192:195], v[48:51]
	v_mfma_f32_16x16x32_bf16 v[44:47], v[162:165], v[200:203], v[44:47]
	v_mfma_f32_16x16x32_bf16 v[40:43], v[176:179], v[200:203], v[40:43]
	v_mfma_f32_16x16x32_bf16 v[36:39], v[162:165], v[208:211], v[36:39]
	v_mfma_f32_16x16x32_bf16 v[32:35], v[176:179], v[208:211], v[32:35]
	s_barrier
	s_add_i32 s79, s57, s7
	v_lshl_add_u64 v[144:145], s[14:15], 0, v[148:149]
	s_mov_b32 m0, s79
	ds_read_b128 v[180:183], v171 offset:16384
	ds_read_b128 v[184:187], v171 offset:17408
	ds_read_b128 v[188:191], v171 offset:18432
	ds_read_b128 v[192:195], v171 offset:19456
	ds_read_b128 v[196:199], v171 offset:20480
	ds_read_b128 v[200:203], v171 offset:21504
	ds_read_b128 v[204:207], v171 offset:22528
	ds_read_b128 v[208:211], v171 offset:23552
	global_load_lds_dwordx4 v[144:145], off
	s_add_i32 m0, s79, 0x2000
	s_add_u32 s80, s14, 0x40000
	v_lshl_add_u64 v[166:167], s[14:15], 0, v[152:153]
	s_addc_u32 s81, s15, 0
	s_add_i32 s79, s58, s7
	global_load_lds_dwordx4 v[166:167], off
	v_lshl_add_u64 v[212:213], s[80:81], 0, v[148:149]
	s_mov_b32 m0, s79
	v_lshl_add_u64 v[214:215], s[46:47], 0, v[150:151]
	global_load_lds_dwordx4 v[212:213], off
	v_lshl_add_u64 v[212:213], s[80:81], 0, v[152:153]
	s_add_i32 m0, s79, 0x2000
	s_nop 0
	global_load_lds_dwordx4 v[212:213], off
	v_lshl_add_u64 v[212:213], s[46:47], 0, v[146:147]
	s_mov_b32 m0, s45
	s_nop 0
	global_load_lds_dwordx4 v[212:213], off
	s_mov_b32 m0, s50
	s_nop 0
	global_load_lds_dwordx4 v[214:215], off
	s_cmp_lg_u32 s100, 0
	s_cbranch_scc0 .Lrf_1463_1
	s_waitcnt vmcnt(16)
	s_branch .Lrj_1463_1

; #define G_STAGE(bufoff, gbase, voff) do { _Pragma("unroll") for (int _i = 0; _i < 2; ++_i) \
;         __builtin_amdgcn_global_load_lds((const unsigned*)((const char*)(gbase) + voff[_i]), (LAS unsigned*)(lds + (bufoff) + ldsw + _i * 8192), 16, 0, 0); } while (0)
; #define G_LDA(dst, b, h) do { _Pragma("unroll") for (int m = 0; m < 4; ++m) _Pragma("unroll") for (int k = 0; k < 2; ++k) dst[m][k] = *(const LAS bf16x8*)(lds + G_SA(b, h) + aoff + m * 2048 + k * 1024); } while (0)
; #define G_LDB(dst, b, h) do { _Pragma("unroll") for (int n = 0; n < 2; ++n) _Pragma("unroll") for (int k = 0; k < 2; ++k) dst[n][k] = *(const LAS bf16x8*)(lds + G_SB(b, h) + boff + n * 2048 + k * 1024); } while (0)
; #define G_MMA(ai, bj, At_, Bt_) do { __builtin_amdgcn_s_setprio(1); _Pragma("unroll") for (int m = 0; m < 4; ++m) _Pragma("unroll") for (int n = 0; n < 2; ++n) _Pragma("unroll") for (int k = 0; k < 2; ++k) \
;         acc[ai][bj][m][n] = __builtin_amdgcn_mfma_f32_16x16x32_bf16(Bt_[n][k], At_[m][k], acc[ai][bj][m][n], 0, 0, 0); __builtin_amdgcn_s_setprio(0); } while (0)
; #define WAIT_V(n) asm volatile("s_waitcnt vmcnt(" #n ")" ::: "memory")
; #define WAIT_L(n) asm volatile("s_waitcnt lgkmcnt(" #n ")" ::: "memory")
; #define BAR __builtin_amdgcn_s_barrier()
; #define SCHED __builtin_amdgcn_sched_barrier(0)
; template <class Get, class Epi>
; DI void gemm_loop(int ntiles, int ld, char* shm, const Get& get, const Epi& epi) {
;     ...
;             WAIT_V(8); WAIT_L(0); BAR; G_MMA(1, 0, At, B0); G_MMA(1, 1, At, B1); BAR; SCHED;
;             G_LDB(B0, 1, 0); G_LDB(B1, 1, 1); SCHED; G_LDA(At, 1, 0); G_STAGE(G_SA(0, 1), a2 + hstep, voffA);
;             WAIT_V(8); WAIT_L(0); BAR; G_MMA(0, 0, At, B0); G_MMA(0, 1, At, B1); BAR; SCHED;
.Lrj_1463_1:
	s_waitcnt lgkmcnt(0)
	s_barrier
	s_waitcnt lgkmcnt(0)
	v_mfma_f32_16x16x32_bf16 v[92:95], v[128:131], v[180:183], 0
	v_mfma_f32_16x16x32_bf16 v[88:91], v[136:139], v[180:183], 0
	v_mfma_f32_16x16x32_bf16 v[84:87], v[128:131], v[188:191], 0
	v_mfma_f32_16x16x32_bf16 v[80:83], v[136:139], v[188:191], 0
	v_mfma_f32_16x16x32_bf16 v[76:79], v[128:131], v[196:199], 0
	v_mfma_f32_16x16x32_bf16 v[72:75], v[136:139], v[196:199], 0
	v_mfma_f32_16x16x32_bf16 v[68:71], v[128:131], v[204:207], 0
	v_mfma_f32_16x16x32_bf16 v[64:67], v[136:139], v[204:207], 0
	v_mfma_f32_16x16x32_bf16 v[92:95], v[132:135], v[184:187], v[92:95]
	v_mfma_f32_16x16x32_bf16 v[88:91], v[140:143], v[184:187], v[88:91]
	v_mfma_f32_16x16x32_bf16 v[84:87], v[132:135], v[192:195], v[84:87]
	v_mfma_f32_16x16x32_bf16 v[80:83], v[140:143], v[192:195], v[80:83]
	v_mfma_f32_16x16x32_bf16 v[76:79], v[132:135], v[200:203], v[76:79]
	v_mfma_f32_16x16x32_bf16 v[72:75], v[140:143], v[200:203], v[72:75]
	v_mfma_f32_16x16x32_bf16 v[68:71], v[132:135], v[208:211], v[68:71]
	v_mfma_f32_16x16x32_bf16 v[64:67], v[140:143], v[208:211], v[64:67]
	v_mfma_f32_16x16x32_bf16 v[28:31], v[158:161], v[180:183], 0
	v_mfma_f32_16x16x32_bf16 v[24:27], v[172:175], v[180:183], 0
	v_mfma_f32_16x16x32_bf16 v[20:23], v[158:161], v[188:191], 0
	v_mfma_f32_16x16x32_bf16 v[16:19], v[172:175], v[188:191], 0
	v_mfma_f32_16x16x32_bf16 v[12:15], v[158:161], v[196:199], 0
	v_mfma_f32_16x16x32_bf16 v[8:11], v[172:175], v[196:199], 0
	v_mfma_f32_16x16x32_bf16 v[4:7], v[158:161], v[204:207], 0
	v_mfma_f32_16x16x32_bf16 v[0:3], v[172:175], v[204:207], 0
	v_mfma_f32_16x16x32_bf16 v[28:31], v[162:165], v[184:187], v[28:31]
	v_mfma_f32_16x16x32_bf16 v[24:27], v[176:179], v[184:187], v[24:27]
	v_mfma_f32_16x16x32_bf16 v[20:23], v[162:165], v[192:195], v[20:23]
	v_mfma_f32_16x16x32_bf16 v[16:19], v[176:179], v[192:195], v[16:19]
	v_mfma_f32_16x16x32_bf16 v[12:15], v[162:165], v[200:203], v[12:15]
	v_mfma_f32_16x16x32_bf16 v[8:11], v[176:179], v[200:203], v[8:11]
	v_mfma_f32_16x16x32_bf16 v[4:7], v[162:165], v[208:211], v[4:7]
	v_mfma_f32_16x16x32_bf16 v[0:3], v[176:179], v[208:211], v[0:3]
	s_barrier
	s_add_i32 s79, 0, 0x18000
	s_add_i32 s80, 0, 0x1c000
	v_add_u32_e32 v140, s79, v168
	v_add_u32_e32 v176, s80, v168
	ds_read_b128 v[128:131], v140
	ds_read_b128 v[132:135], v140 offset:1024
	ds_read_b128 v[136:139], v140 offset:2048
	ds_read_b128 v[140:143], v140 offset:3072
	ds_read_b128 v[158:161], v176
	ds_read_b128 v[162:165], v176 offset:1024
	ds_read_b128 v[172:175], v176 offset:2048
	ds_read_b128 v[176:179], v176 offset:3072
	s_add_u32 s46, s46, 0x40000
	s_addc_u32 s47, s47, 0
	s_mov_b32 m0, s51
	v_lshl_add_u64 v[216:217], s[46:47], 0, v[146:147]
	ds_read_b128 v[180:183], v171 offset:32768
	ds_read_b128 v[184:187], v171 offset:33792
	ds_read_b128 v[188:191], v171 offset:34816
	ds_read_b128 v[192:195], v171 offset:35840
	ds_read_b128 v[196:199], v171 offset:36864
	ds_read_b128 v[200:203], v171 offset:37888
	ds_read_b128 v[204:207], v171 offset:38912
	ds_read_b128 v[208:211], v171 offset:39936
	global_load_lds_dwordx4 v[216:217], off
	v_lshl_add_u64 v[216:217], s[46:47], 0, v[150:151]
	s_mov_b32 m0, s52
	s_nop 0
	global_load_lds_dwordx4 v[216:217], off
	s_waitcnt vmcnt(8)
	s_waitcnt lgkmcnt(0)
	s_barrier
	s_waitcnt lgkmcnt(0)
	v_mfma_f32_16x16x32_bf16 v[124:127], v[128:131], v[180:183], v[124:127]
	v_mfma_f32_16x16x32_bf16 v[120:123], v[136:139], v[180:183], v[120:123]
	v_mfma_f32_16x16x32_bf16 v[116:119], v[128:131], v[188:191], v[116:119]
	v_mfma_f32_16x16x32_bf16 v[112:115], v[136:139], v[188:191], v[112:115]
	v_mfma_f32_16x16x32_bf16 v[108:111], v[128:131], v[196:199], v[108:111]
	v_mfma_f32_16x16x32_bf16 v[104:107], v[136:139], v[196:199], v[104:107]
	v_mfma_f32_16x16x32_bf16 v[100:103], v[128:131], v[204:207], v[100:103]
	v_mfma_f32_16x16x32_bf16 v[96:99], v[136:139], v[204:207], v[96:99]
	v_mfma_f32_16x16x32_bf16 v[124:127], v[132:135], v[184:187], v[124:127]
	v_mfma_f32_16x16x32_bf16 v[120:123], v[140:143], v[184:187], v[120:123]
	v_mfma_f32_16x16x32_bf16 v[116:119], v[132:135], v[192:195], v[116:119]
	v_mfma_f32_16x16x32_bf16 v[112:115], v[140:143], v[192:195], v[112:115]
	v_mfma_f32_16x16x32_bf16 v[108:111], v[132:135], v[200:203], v[108:111]
	v_mfma_f32_16x16x32_bf16 v[104:107], v[140:143], v[200:203], v[104:107]
	v_mfma_f32_16x16x32_bf16 v[100:103], v[132:135], v[208:211], v[100:103]
	v_mfma_f32_16x16x32_bf16 v[96:99], v[140:143], v[208:211], v[96:99]
	v_mfma_f32_16x16x32_bf16 v[60:63], v[158:161], v[180:183], v[60:63]
	v_mfma_f32_16x16x32_bf16 v[56:59], v[172:175], v[180:183], v[56:59]
	v_mfma_f32_16x16x32_bf16 v[52:55], v[158:161], v[188:191], v[52:55]
	v_mfma_f32_16x16x32_bf16 v[48:51], v[172:175], v[188:191], v[48:51]
	v_mfma_f32_16x16x32_bf16 v[44:47], v[158:161], v[196:199], v[44:47]
	v_mfma_f32_16x16x32_bf16 v[40:43], v[172:175], v[196:199], v[40:43]
	v_mfma_f32_16x16x32_bf16 v[36:39], v[158:161], v[204:207], v[36:39]
	v_mfma_f32_16x16x32_bf16 v[32:35], v[172:175], v[204:207], v[32:35]
	v_mfma_f32_16x16x32_bf16 v[60:63], v[162:165], v[184:187], v[60:63]
	v_mfma_f32_16x16x32_bf16 v[56:59], v[176:179], v[184:187], v[56:59]
	v_mfma_f32_16x16x32_bf16 v[52:55], v[162:165], v[192:195], v[52:55]
	v_mfma_f32_16x16x32_bf16 v[48:51], v[176:179], v[192:195], v[48:51]
	v_mfma_f32_16x16x32_bf16 v[44:47], v[162:165], v[200:203], v[44:47]
	v_mfma_f32_16x16x32_bf16 v[40:43], v[176:179], v[200:203], v[40:43]
	v_mfma_f32_16x16x32_bf16 v[36:39], v[162:165], v[208:211], v[36:39]
	v_mfma_f32_16x16x32_bf16 v[32:35], v[176:179], v[208:211], v[32:35]
	s_barrier
; #define G_STAGE(bufoff, gbase, voff) do { _Pragma("unroll") for (int _i = 0; _i < 2; ++_i) \
;         __builtin_amdgcn_global_load_lds((const unsigned*)((const char*)(gbase) + voff[_i]), (LAS unsigned*)(lds + (bufoff) + ldsw + _i * 8192), 16, 0, 0); } while (0)
; #define G_LDA(dst, b, h) do { _Pragma("unroll") for (int m = 0; m < 4; ++m) _Pragma("unroll") for (int k = 0; k < 2; ++k) dst[m][k] = *(const LAS bf16x8*)(lds + G_SA(b, h) + aoff + m * 2048 + k * 1024); } while (0)
; #define G_LDB(dst, b, h) do { _Pragma("unroll") for (int n = 0; n < 2; ++n) _Pragma("unroll") for (int k = 0; k < 2; ++k) dst[n][k] = *(const LAS bf16x8*)(lds + G_SB(b, h) + boff + n * 2048 + k * 1024); } while (0)
; #define G_MMA(ai, bj, At_, Bt_) do { __builtin_amdgcn_s_setprio(1); _Pragma("unroll") for (int m = 0; m < 4; ++m) _Pragma("unroll") for (int n = 0; n < 2; ++n) _Pragma("unroll") for (int k = 0; k < 2; ++k) \
;         acc[ai][bj][m][n] = __builtin_amdgcn_mfma_f32_16x16x32_bf16(Bt_[n][k], At_[m][k], acc[ai][bj][m][n], 0, 0, 0); __builtin_amdgcn_s_setprio(0); } while (0)
; #define WAIT_V(n) asm volatile("s_waitcnt vmcnt(" #n ")" ::: "memory")
; #define WAIT_L(n) asm volatile("s_waitcnt lgkmcnt(" #n ")" ::: "memory")
; #define BAR __builtin_amdgcn_s_barrier()
; #define SCHED __builtin_amdgcn_sched_barrier(0)
; template <class Get, class Epi>
; DI void gemm_loop(int ntiles, int ld, char* shm, const Get& get, const Epi& epi) {
;     ...
;             G_LDB(B0, 0, 0); G_LDB(B1, 0, 1); SCHED; G_LDA(At, 0, 0); G_STAGE(G_SA(1, 1), a1 + hstep, voffA);
;             WAIT_V(8); WAIT_L(0); BAR; G_MMA(0, 0, At, B0); G_MMA(0, 1, At, B1); BAR; SCHED;
;     ...
;             G_LDA(At, 1, 1); G_STAGE(G_SB(1, 0), b3, voffB); G_STAGE(G_SB(1, 1), b3 + hstep, voffB); G_STAGE(G_SA(1, 0), a3, voffA);
;             WAIT_V(8); WAIT_L(0); BAR; G_MMA(1, 0, At, B0); G_MMA(1, 1, At, B1); BAR; SCHED;
;         }
	s_add_i32 s46, s79, s7
	v_lshl_add_u64 v[144:145], v[144:145], 0, s[10:11]
	s_mov_b32 m0, s46
	ds_read_b128 v[180:183], v171 offset:49152
	ds_read_b128 v[184:187], v171 offset:50176
	ds_read_b128 v[188:191], v171 offset:51200
	ds_read_b128 v[192:195], v171 offset:52224
	ds_read_b128 v[196:199], v171 offset:53248
	ds_read_b128 v[200:203], v171 offset:54272
	ds_read_b128 v[204:207], v171 offset:55296
	ds_read_b128 v[208:211], v171 offset:56320
	global_load_lds_dwordx4 v[144:145], off
	s_add_i32 m0, s46, 0x2000
	s_add_u32 s14, s14, 0x40080
	v_lshl_add_u64 v[144:145], v[166:167], 0, s[10:11]
	s_addc_u32 s15, s15, 0
	s_add_i32 s46, s80, s7
	global_load_lds_dwordx4 v[144:145], off
	v_lshl_add_u64 v[144:145], s[14:15], 0, v[148:149]
	s_mov_b32 m0, s46
	s_nop 0
	global_load_lds_dwordx4 v[144:145], off
	v_lshl_add_u64 v[144:145], s[14:15], 0, v[152:153]
	s_add_i32 m0, s46, 0x2000
	s_nop 0
	global_load_lds_dwordx4 v[144:145], off
	v_lshl_add_u64 v[144:145], v[212:213], 0, s[10:11]
	s_mov_b32 m0, s55
	s_nop 0
	global_load_lds_dwordx4 v[144:145], off
	v_lshl_add_u64 v[144:145], v[214:215], 0, s[10:11]
	s_mov_b32 m0, s56
	s_nop 0
	global_load_lds_dwordx4 v[144:145], off
	s_waitcnt vmcnt(8)
	s_waitcnt lgkmcnt(0)
	s_barrier
	s_waitcnt lgkmcnt(0)
	v_mfma_f32_16x16x32_bf16 v[92:95], v[128:131], v[180:183], v[92:95]
	v_mfma_f32_16x16x32_bf16 v[88:91], v[136:139], v[180:183], v[88:91]
	v_mfma_f32_16x16x32_bf16 v[84:87], v[128:131], v[188:191], v[84:87]
	v_mfma_f32_16x16x32_bf16 v[80:83], v[136:139], v[188:191], v[80:83]
	v_mfma_f32_16x16x32_bf16 v[76:79], v[128:131], v[196:199], v[76:79]
	v_mfma_f32_16x16x32_bf16 v[72:75], v[136:139], v[196:199], v[72:75]
	v_mfma_f32_16x16x32_bf16 v[68:71], v[128:131], v[204:207], v[68:71]
	v_mfma_f32_16x16x32_bf16 v[64:67], v[136:139], v[204:207], v[64:67]
	v_mfma_f32_16x16x32_bf16 v[92:95], v[132:135], v[184:187], v[92:95]
	v_mfma_f32_16x16x32_bf16 v[88:91], v[140:143], v[184:187], v[88:91]
	v_mfma_f32_16x16x32_bf16 v[84:87], v[132:135], v[192:195], v[84:87]
	v_mfma_f32_16x16x32_bf16 v[80:83], v[140:143], v[192:195], v[80:83]
	v_mfma_f32_16x16x32_bf16 v[76:79], v[132:135], v[200:203], v[76:79]
	v_mfma_f32_16x16x32_bf16 v[72:75], v[140:143], v[200:203], v[72:75]
	v_mfma_f32_16x16x32_bf16 v[68:71], v[132:135], v[208:211], v[68:71]
	v_mfma_f32_16x16x32_bf16 v[64:67], v[140:143], v[208:211], v[64:67]
	v_mfma_f32_16x16x32_bf16 v[28:31], v[158:161], v[180:183], v[28:31]
	v_mfma_f32_16x16x32_bf16 v[24:27], v[172:175], v[180:183], v[24:27]
	v_mfma_f32_16x16x32_bf16 v[20:23], v[158:161], v[188:191], v[20:23]
	v_mfma_f32_16x16x32_bf16 v[16:19], v[172:175], v[188:191], v[16:19]
	v_mfma_f32_16x16x32_bf16 v[12:15], v[158:161], v[196:199], v[12:15]
	v_mfma_f32_16x16x32_bf16 v[8:11], v[172:175], v[196:199], v[8:11]
	v_mfma_f32_16x16x32_bf16 v[4:7], v[158:161], v[204:207], v[4:7]
	v_mfma_f32_16x16x32_bf16 v[0:3], v[172:175], v[204:207], v[0:3]
	v_mfma_f32_16x16x32_bf16 v[28:31], v[162:165], v[184:187], v[28:31]
	v_mfma_f32_16x16x32_bf16 v[24:27], v[176:179], v[184:187], v[24:27]
	v_mfma_f32_16x16x32_bf16 v[20:23], v[162:165], v[192:195], v[20:23]
	v_mfma_f32_16x16x32_bf16 v[16:19], v[176:179], v[192:195], v[16:19]
	v_mfma_f32_16x16x32_bf16 v[12:15], v[162:165], v[200:203], v[12:15]
	v_mfma_f32_16x16x32_bf16 v[8:11], v[176:179], v[200:203], v[8:11]
	v_mfma_f32_16x16x32_bf16 v[4:7], v[162:165], v[208:211], v[4:7]
	v_mfma_f32_16x16x32_bf16 v[0:3], v[176:179], v[208:211], v[0:3]
	s_barrier
	s_add_u32 s48, s48, 0x100
	s_addc_u32 s49, s49, 0
	s_add_u32 s76, s76, 0x100
	s_addc_u32 s77, s77, 0
	s_cmp_ge_u32 s78, s74
	s_mov_b32 s14, s78
	s_cbranch_scc0 .LBB0_1463
	s_branch .Lpost_1463
.LBB0_1463:
	ds_read_b128 v[128:131], v169
	ds_read_b128 v[132:135], v169 offset:1024
	ds_read_b128 v[136:139], v169 offset:2048
	ds_read_b128 v[140:143], v169 offset:3072
	ds_read_b128 v[158:161], v170
	ds_read_b128 v[162:165], v170 offset:1024
	ds_read_b128 v[172:175], v170 offset:2048
	ds_read_b128 v[176:179], v170 offset:3072
	s_add_i32 s78, s14, 2
	s_add_u32 s15, s48, 0xfffc0080
	s_addc_u32 s46, s49, -1
	s_cmp_eq_u32 s75, s14
	s_cselect_b32 s14, s73, s76
	s_cselect_b32 s47, s3, s46
	s_cselect_b32 s46, s37, s15
	s_cselect_b32 s15, s39, s77
	v_lshl_add_u64 v[144:145], s[48:49], 0, v[154:155]
	s_add_i32 m0, s45, 0xc000
	ds_read_b128 v[180:183], v171
	ds_read_b128 v[184:187], v171 offset:1024
	ds_read_b128 v[188:191], v171 offset:2048
	ds_read_b128 v[192:195], v171 offset:3072
	ds_read_b128 v[196:199], v171 offset:4096
	ds_read_b128 v[200:203], v171 offset:5120
	ds_read_b128 v[204:207], v171 offset:6144
	ds_read_b128 v[208:211], v171 offset:7168
	global_load_lds_dwordx4 v[144:145], off
	v_lshl_add_u64 v[144:145], s[48:49], 0, v[156:157]
	s_add_i32 m0, s45, 0xe000
	s_nop 0
	global_load_lds_dwordx4 v[144:145], off
	s_waitcnt vmcnt(8)
	s_waitcnt lgkmcnt(0)
	s_barrier
; #define G_STAGE(bufoff, gbase, voff) do { _Pragma("unroll") for (int _i = 0; _i < 2; ++_i) \
;         __builtin_amdgcn_global_load_lds((const unsigned*)((const char*)(gbase) + voff[_i]), (LAS unsigned*)(lds + (bufoff) + ldsw + _i * 8192), 16, 0, 0); } while (0)
; #define G_LDA(dst, b, h) do { _Pragma("unroll") for (int m = 0; m < 4; ++m) _Pragma("unroll") for (int k = 0; k < 2; ++k) dst[m][k] = *(const LAS bf16x8*)(lds + G_SA(b, h) + aoff + m * 2048 + k * 1024); } while (0)
; #define G_MMA(ai, bj, At_, Bt_) do { __builtin_amdgcn_s_setprio(1); _Pragma("unroll") for (int m = 0; m < 4; ++m) _Pragma("unroll") for (int n = 0; n < 2; ++n) _Pragma("unroll") for (int k = 0; k < 2; ++k) \
;         acc[ai][bj][m][n] = __builtin_amdgcn_mfma_f32_16x16x32_bf16(Bt_[n][k], At_[m][k], acc[ai][bj][m][n], 0, 0, 0); __builtin_amdgcn_s_setprio(0); } while (0)
; #define WAIT_V(n) asm volatile("s_waitcnt vmcnt(" #n ")" ::: "memory")
; #define WAIT_L(n) asm volatile("s_waitcnt lgkmcnt(" #n ")" ::: "memory")
; #define BAR __builtin_amdgcn_s_barrier()
; #define SCHED __builtin_amdgcn_sched_barrier(0)
; template <class Get, class Epi>
; DI void gemm_loop(int ntiles, int ld, char* shm, const Get& get, const Epi& epi) {
;     ...
;             WAIT_V(8); WAIT_L(0); BAR; G_MMA(0, 0, At, B0); G_MMA(0, 1, At, B1); BAR; SCHED;
;             G_LDA(At, 0, 1); G_STAGE(G_SB(0, 0), b2, voffB); G_STAGE(G_SB(0, 1), b2 + hstep, voffB); G_STAGE(G_SA(0, 0), a2, voffA);
;             WAIT_V(8); WAIT_L(0); BAR; G_MMA(1, 0, At, B0); G_MMA(1, 1, At, B1); BAR; SCHED;
	s_waitcnt lgkmcnt(0)
	v_mfma_f32_16x16x32_bf16 v[124:127], v[128:131], v[180:183], v[124:127]
	v_mfma_f32_16x16x32_bf16 v[120:123], v[136:139], v[180:183], v[120:123]
	v_mfma_f32_16x16x32_bf16 v[116:119], v[128:131], v[188:191], v[116:119]
	v_mfma_f32_16x16x32_bf16 v[112:115], v[136:139], v[188:191], v[112:115]
	v_mfma_f32_16x16x32_bf16 v[108:111], v[128:131], v[196:199], v[108:111]
	v_mfma_f32_16x16x32_bf16 v[104:107], v[136:139], v[196:199], v[104:107]
	v_mfma_f32_16x16x32_bf16 v[100:103], v[128:131], v[204:207], v[100:103]
	v_mfma_f32_16x16x32_bf16 v[96:99], v[136:139], v[204:207], v[96:99]
	v_mfma_f32_16x16x32_bf16 v[124:127], v[132:135], v[184:187], v[124:127]
	v_mfma_f32_16x16x32_bf16 v[120:123], v[140:143], v[184:187], v[120:123]
	v_mfma_f32_16x16x32_bf16 v[116:119], v[132:135], v[192:195], v[116:119]
	v_mfma_f32_16x16x32_bf16 v[112:115], v[140:143], v[192:195], v[112:115]
	v_mfma_f32_16x16x32_bf16 v[108:111], v[132:135], v[200:203], v[108:111]
	v_mfma_f32_16x16x32_bf16 v[104:107], v[140:143], v[200:203], v[104:107]
	v_mfma_f32_16x16x32_bf16 v[100:103], v[132:135], v[208:211], v[100:103]
	v_mfma_f32_16x16x32_bf16 v[96:99], v[140:143], v[208:211], v[96:99]
	v_mfma_f32_16x16x32_bf16 v[60:63], v[158:161], v[180:183], v[60:63]
	v_mfma_f32_16x16x32_bf16 v[56:59], v[172:175], v[180:183], v[56:59]
	v_mfma_f32_16x16x32_bf16 v[52:55], v[158:161], v[188:191], v[52:55]
	v_mfma_f32_16x16x32_bf16 v[48:51], v[172:175], v[188:191], v[48:51]
	v_mfma_f32_16x16x32_bf16 v[44:47], v[158:161], v[196:199], v[44:47]
	v_mfma_f32_16x16x32_bf16 v[40:43], v[172:175], v[196:199], v[40:43]
	v_mfma_f32_16x16x32_bf16 v[36:39], v[158:161], v[204:207], v[36:39]
	v_mfma_f32_16x16x32_bf16 v[32:35], v[172:175], v[204:207], v[32:35]
	v_mfma_f32_16x16x32_bf16 v[60:63], v[162:165], v[184:187], v[60:63]
	v_mfma_f32_16x16x32_bf16 v[56:59], v[176:179], v[184:187], v[56:59]
	v_mfma_f32_16x16x32_bf16 v[52:55], v[162:165], v[192:195], v[52:55]
	v_mfma_f32_16x16x32_bf16 v[48:51], v[176:179], v[192:195], v[48:51]
	v_mfma_f32_16x16x32_bf16 v[44:47], v[162:165], v[200:203], v[44:47]
	v_mfma_f32_16x16x32_bf16 v[40:43], v[176:179], v[200:203], v[40:43]
	v_mfma_f32_16x16x32_bf16 v[36:39], v[162:165], v[208:211], v[36:39]
	v_mfma_f32_16x16x32_bf16 v[32:35], v[176:179], v[208:211], v[32:35]
	s_barrier
	s_add_i32 s79, s57, s7
	v_lshl_add_u64 v[144:145], s[14:15], 0, v[148:149]
	s_mov_b32 m0, s79
	ds_read_b128 v[180:183], v171 offset:16384
	ds_read_b128 v[184:187], v171 offset:17408
	ds_read_b128 v[188:191], v171 offset:18432
	ds_read_b128 v[192:195], v171 offset:19456
	ds_read_b128 v[196:199], v171 offset:20480
	ds_read_b128 v[200:203], v171 offset:21504
	ds_read_b128 v[204:207], v171 offset:22528
	ds_read_b128 v[208:211], v171 offset:23552
	global_load_lds_dwordx4 v[144:145], off
	s_add_i32 m0, s79, 0x2000
	s_add_u32 s80, s14, 0x40000
	v_lshl_add_u64 v[166:167], s[14:15], 0, v[152:153]
	s_addc_u32 s81, s15, 0
	s_add_i32 s79, s58, s7
	global_load_lds_dwordx4 v[166:167], off
	v_lshl_add_u64 v[212:213], s[80:81], 0, v[148:149]
	s_mov_b32 m0, s79
	v_lshl_add_u64 v[214:215], s[46:47], 0, v[150:151]
	global_load_lds_dwordx4 v[212:213], off
	v_lshl_add_u64 v[212:213], s[80:81], 0, v[152:153]
	s_add_i32 m0, s79, 0x2000
	s_nop 0
	global_load_lds_dwordx4 v[212:213], off
	v_lshl_add_u64 v[212:213], s[46:47], 0, v[146:147]
	s_mov_b32 m0, s45
	s_nop 0
	global_load_lds_dwordx4 v[212:213], off
	s_mov_b32 m0, s50
	s_nop 0
	global_load_lds_dwordx4 v[214:215], off
	s_waitcnt vmcnt(8)
	s_waitcnt lgkmcnt(0)
	s_barrier
	s_waitcnt lgkmcnt(0)
	v_mfma_f32_16x16x32_bf16 v[92:95], v[128:131], v[180:183], v[92:95]
	v_mfma_f32_16x16x32_bf16 v[88:91], v[136:139], v[180:183], v[88:91]
	v_mfma_f32_16x16x32_bf16 v[84:87], v[128:131], v[188:191], v[84:87]
	v_mfma_f32_16x16x32_bf16 v[80:83], v[136:139], v[188:191], v[80:83]
	v_mfma_f32_16x16x32_bf16 v[76:79], v[128:131], v[196:199], v[76:79]
	v_mfma_f32_16x16x32_bf16 v[72:75], v[136:139], v[196:199], v[72:75]
	v_mfma_f32_16x16x32_bf16 v[68:71], v[128:131], v[204:207], v[68:71]
	v_mfma_f32_16x16x32_bf16 v[64:67], v[136:139], v[204:207], v[64:67]
	v_mfma_f32_16x16x32_bf16 v[92:95], v[132:135], v[184:187], v[92:95]
	v_mfma_f32_16x16x32_bf16 v[88:91], v[140:143], v[184:187], v[88:91]
	v_mfma_f32_16x16x32_bf16 v[84:87], v[132:135], v[192:195], v[84:87]
	v_mfma_f32_16x16x32_bf16 v[80:83], v[140:143], v[192:195], v[80:83]
	v_mfma_f32_16x16x32_bf16 v[76:79], v[132:135], v[200:203], v[76:79]
	v_mfma_f32_16x16x32_bf16 v[72:75], v[140:143], v[200:203], v[72:75]
	v_mfma_f32_16x16x32_bf16 v[68:71], v[132:135], v[208:211], v[68:71]
	v_mfma_f32_16x16x32_bf16 v[64:67], v[140:143], v[208:211], v[64:67]
	v_mfma_f32_16x16x32_bf16 v[28:31], v[158:161], v[180:183], v[28:31]
	v_mfma_f32_16x16x32_bf16 v[24:27], v[172:175], v[180:183], v[24:27]
	v_mfma_f32_16x16x32_bf16 v[20:23], v[158:161], v[188:191], v[20:23]
	v_mfma_f32_16x16x32_bf16 v[16:19], v[172:175], v[188:191], v[16:19]
	v_mfma_f32_16x16x32_bf16 v[12:15], v[158:161], v[196:199], v[12:15]
	v_mfma_f32_16x16x32_bf16 v[8:11], v[172:175], v[196:199], v[8:11]
	v_mfma_f32_16x16x32_bf16 v[4:7], v[158:161], v[204:207], v[4:7]
	v_mfma_f32_16x16x32_bf16 v[0:3], v[172:175], v[204:207], v[0:3]
	v_mfma_f32_16x16x32_bf16 v[28:31], v[162:165], v[184:187], v[28:31]
	v_mfma_f32_16x16x32_bf16 v[24:27], v[176:179], v[184:187], v[24:27]
	v_mfma_f32_16x16x32_bf16 v[20:23], v[162:165], v[192:195], v[20:23]
	v_mfma_f32_16x16x32_bf16 v[16:19], v[176:179], v[192:195], v[16:19]
	v_mfma_f32_16x16x32_bf16 v[12:15], v[162:165], v[200:203], v[12:15]
	v_mfma_f32_16x16x32_bf16 v[8:11], v[176:179], v[200:203], v[8:11]
	v_mfma_f32_16x16x32_bf16 v[4:7], v[162:165], v[208:211], v[4:7]
	v_mfma_f32_16x16x32_bf16 v[0:3], v[176:179], v[208:211], v[0:3]
	s_barrier
; #define G_STAGE(bufoff, gbase, voff) do { _Pragma("unroll") for (int _i = 0; _i < 2; ++_i) \
;         __builtin_amdgcn_global_load_lds((const unsigned*)((const char*)(gbase) + voff[_i]), (LAS unsigned*)(lds + (bufoff) + ldsw + _i * 8192), 16, 0, 0); } while (0)
; #define G_LDA(dst, b, h) do { _Pragma("unroll") for (int m = 0; m < 4; ++m) _Pragma("unroll") for (int k = 0; k < 2; ++k) dst[m][k] = *(const LAS bf16x8*)(lds + G_SA(b, h) + aoff + m * 2048 + k * 1024); } while (0)
; #define G_LDB(dst, b, h) do { _Pragma("unroll") for (int n = 0; n < 2; ++n) _Pragma("unroll") for (int k = 0; k < 2; ++k) dst[n][k] = *(const LAS bf16x8*)(lds + G_SB(b, h) + boff + n * 2048 + k * 1024); } while (0)
; #define G_MMA(ai, bj, At_, Bt_) do { __builtin_amdgcn_s_setprio(1); _Pragma("unroll") for (int m = 0; m < 4; ++m) _Pragma("unroll") for (int n = 0; n < 2; ++n) _Pragma("unroll") for (int k = 0; k < 2; ++k) \
;         acc[ai][bj][m][n] = __builtin_amdgcn_mfma_f32_16x16x32_bf16(Bt_[n][k], At_[m][k], acc[ai][bj][m][n], 0, 0, 0); __builtin_amdgcn_s_setprio(0); } while (0)
; #define WAIT_V(n) asm volatile("s_waitcnt vmcnt(" #n ")" ::: "memory")
; #define WAIT_L(n) asm volatile("s_waitcnt lgkmcnt(" #n ")" ::: "memory")
; #define BAR __builtin_amdgcn_s_barrier()
; #define SCHED __builtin_amdgcn_sched_barrier(0)
; template <class Get, class Epi>
; DI void gemm_loop(int ntiles, int ld, char* shm, const Get& get, const Epi& epi) {
;     ...
;             G_LDB(B0, 1, 0); G_LDB(B1, 1, 1); SCHED; G_LDA(At, 1, 0); G_STAGE(G_SA(0, 1), a2 + hstep, voffA);
;             WAIT_V(8); WAIT_L(0); BAR; G_MMA(0, 0, At, B0); G_MMA(0, 1, At, B1); BAR; SCHED;
;             G_LDA(At, 1, 1); G_STAGE(G_SB(1, 0), b3, voffB); G_STAGE(G_SB(1, 1), b3 + hstep, voffB); G_STAGE(G_SA(1, 0), a3, voffA);
;             WAIT_V(8); WAIT_L(0); BAR; G_MMA(1, 0, At, B0); G_MMA(1, 1, At, B1); BAR; SCHED;
;         }
	s_add_i32 s79, 0, 0x18000
	s_add_i32 s80, 0, 0x1c000
	v_add_u32_e32 v140, s79, v168
	v_add_u32_e32 v176, s80, v168
	ds_read_b128 v[128:131], v140
	ds_read_b128 v[132:135], v140 offset:1024
	ds_read_b128 v[136:139], v140 offset:2048
	ds_read_b128 v[140:143], v140 offset:3072
	ds_read_b128 v[158:161], v176
	ds_read_b128 v[162:165], v176 offset:1024
	ds_read_b128 v[172:175], v176 offset:2048
	ds_read_b128 v[176:179], v176 offset:3072
	s_add_u32 s46, s46, 0x40000
	s_addc_u32 s47, s47, 0
	s_mov_b32 m0, s51
	v_lshl_add_u64 v[216:217], s[46:47], 0, v[146:147]
	ds_read_b128 v[180:183], v171 offset:32768
	ds_read_b128 v[184:187], v171 offset:33792
	ds_read_b128 v[188:191], v171 offset:34816
	ds_read_b128 v[192:195], v171 offset:35840
	ds_read_b128 v[196:199], v171 offset:36864
	ds_read_b128 v[200:203], v171 offset:37888
	ds_read_b128 v[204:207], v171 offset:38912
	ds_read_b128 v[208:211], v171 offset:39936
	global_load_lds_dwordx4 v[216:217], off
	v_lshl_add_u64 v[216:217], s[46:47], 0, v[150:151]
	s_mov_b32 m0, s52
	s_nop 0
	global_load_lds_dwordx4 v[216:217], off
	s_waitcnt vmcnt(8)
	s_waitcnt lgkmcnt(0)
	s_barrier
	s_waitcnt lgkmcnt(0)
	v_mfma_f32_16x16x32_bf16 v[124:127], v[128:131], v[180:183], v[124:127]
	v_mfma_f32_16x16x32_bf16 v[120:123], v[136:139], v[180:183], v[120:123]
	v_mfma_f32_16x16x32_bf16 v[116:119], v[128:131], v[188:191], v[116:119]
	v_mfma_f32_16x16x32_bf16 v[112:115], v[136:139], v[188:191], v[112:115]
	v_mfma_f32_16x16x32_bf16 v[108:111], v[128:131], v[196:199], v[108:111]
	v_mfma_f32_16x16x32_bf16 v[104:107], v[136:139], v[196:199], v[104:107]
	v_mfma_f32_16x16x32_bf16 v[100:103], v[128:131], v[204:207], v[100:103]
	v_mfma_f32_16x16x32_bf16 v[96:99], v[136:139], v[204:207], v[96:99]
	v_mfma_f32_16x16x32_bf16 v[124:127], v[132:135], v[184:187], v[124:127]
	v_mfma_f32_16x16x32_bf16 v[120:123], v[140:143], v[184:187], v[120:123]
	v_mfma_f32_16x16x32_bf16 v[116:119], v[132:135], v[192:195], v[116:119]
	v_mfma_f32_16x16x32_bf16 v[112:115], v[140:143], v[192:195], v[112:115]
	v_mfma_f32_16x16x32_bf16 v[108:111], v[132:135], v[200:203], v[108:111]
	v_mfma_f32_16x16x32_bf16 v[104:107], v[140:143], v[200:203], v[104:107]
	v_mfma_f32_16x16x32_bf16 v[100:103], v[132:135], v[208:211], v[100:103]
	v_mfma_f32_16x16x32_bf16 v[96:99], v[140:143], v[208:211], v[96:99]
	v_mfma_f32_16x16x32_bf16 v[60:63], v[158:161], v[180:183], v[60:63]
	v_mfma_f32_16x16x32_bf16 v[56:59], v[172:175], v[180:183], v[56:59]
	v_mfma_f32_16x16x32_bf16 v[52:55], v[158:161], v[188:191], v[52:55]
	v_mfma_f32_16x16x32_bf16 v[48:51], v[172:175], v[188:191], v[48:51]
	v_mfma_f32_16x16x32_bf16 v[44:47], v[158:161], v[196:199], v[44:47]
	v_mfma_f32_16x16x32_bf16 v[40:43], v[172:175], v[196:199], v[40:43]
	v_mfma_f32_16x16x32_bf16 v[36:39], v[158:161], v[204:207], v[36:39]
	v_mfma_f32_16x16x32_bf16 v[32:35], v[172:175], v[204:207], v[32:35]
	v_mfma_f32_16x16x32_bf16 v[60:63], v[162:165], v[184:187], v[60:63]
	v_mfma_f32_16x16x32_bf16 v[56:59], v[176:179], v[184:187], v[56:59]
	v_mfma_f32_16x16x32_bf16 v[52:55], v[162:165], v[192:195], v[52:55]
	v_mfma_f32_16x16x32_bf16 v[48:51], v[176:179], v[192:195], v[48:51]
	v_mfma_f32_16x16x32_bf16 v[44:47], v[162:165], v[200:203], v[44:47]
	v_mfma_f32_16x16x32_bf16 v[40:43], v[176:179], v[200:203], v[40:43]
	v_mfma_f32_16x16x32_bf16 v[36:39], v[162:165], v[208:211], v[36:39]
	v_mfma_f32_16x16x32_bf16 v[32:35], v[176:179], v[208:211], v[32:35]
	s_barrier
	s_add_i32 s46, s79, s7
	v_lshl_add_u64 v[144:145], v[144:145], 0, s[10:11]
	s_mov_b32 m0, s46
	ds_read_b128 v[180:183], v171 offset:49152
	ds_read_b128 v[184:187], v171 offset:50176
	ds_read_b128 v[188:191], v171 offset:51200
	ds_read_b128 v[192:195], v171 offset:52224
	ds_read_b128 v[196:199], v171 offset:53248
	ds_read_b128 v[200:203], v171 offset:54272
	ds_read_b128 v[204:207], v171 offset:55296
	ds_read_b128 v[208:211], v171 offset:56320
	global_load_lds_dwordx4 v[144:145], off
	s_add_i32 m0, s46, 0x2000
	s_add_u32 s14, s14, 0x40080
	v_lshl_add_u64 v[144:145], v[166:167], 0, s[10:11]
	s_addc_u32 s15, s15, 0
	s_add_i32 s46, s80, s7
	global_load_lds_dwordx4 v[144:145], off
	v_lshl_add_u64 v[144:145], s[14:15], 0, v[148:149]
	s_mov_b32 m0, s46
	s_nop 0
	global_load_lds_dwordx4 v[144:145], off
	v_lshl_add_u64 v[144:145], s[14:15], 0, v[152:153]
	s_add_i32 m0, s46, 0x2000
	s_nop 0
	global_load_lds_dwordx4 v[144:145], off
	v_lshl_add_u64 v[144:145], v[212:213], 0, s[10:11]
	s_mov_b32 m0, s55
	s_nop 0
	global_load_lds_dwordx4 v[144:145], off
	v_lshl_add_u64 v[144:145], v[214:215], 0, s[10:11]
	s_mov_b32 m0, s56
	s_nop 0
	global_load_lds_dwordx4 v[144:145], off
	s_waitcnt vmcnt(8)
	s_waitcnt lgkmcnt(0)
	s_barrier
	s_waitcnt lgkmcnt(0)
	v_mfma_f32_16x16x32_bf16 v[92:95], v[128:131], v[180:183], v[92:95]
	v_mfma_f32_16x16x32_bf16 v[88:91], v[136:139], v[180:183], v[88:91]
	v_mfma_f32_16x16x32_bf16 v[84:87], v[128:131], v[188:191], v[84:87]
	v_mfma_f32_16x16x32_bf16 v[80:83], v[136:139], v[188:191], v[80:83]
	v_mfma_f32_16x16x32_bf16 v[76:79], v[128:131], v[196:199], v[76:79]
	v_mfma_f32_16x16x32_bf16 v[72:75], v[136:139], v[196:199], v[72:75]
	v_mfma_f32_16x16x32_bf16 v[68:71], v[128:131], v[204:207], v[68:71]
	v_mfma_f32_16x16x32_bf16 v[64:67], v[136:139], v[204:207], v[64:67]
	v_mfma_f32_16x16x32_bf16 v[92:95], v[132:135], v[184:187], v[92:95]
	v_mfma_f32_16x16x32_bf16 v[88:91], v[140:143], v[184:187], v[88:91]
	v_mfma_f32_16x16x32_bf16 v[84:87], v[132:135], v[192:195], v[84:87]
	v_mfma_f32_16x16x32_bf16 v[80:83], v[140:143], v[192:195], v[80:83]
	v_mfma_f32_16x16x32_bf16 v[76:79], v[132:135], v[200:203], v[76:79]
	v_mfma_f32_16x16x32_bf16 v[72:75], v[140:143], v[200:203], v[72:75]
	v_mfma_f32_16x16x32_bf16 v[68:71], v[132:135], v[208:211], v[68:71]
	v_mfma_f32_16x16x32_bf16 v[64:67], v[140:143], v[208:211], v[64:67]
	v_mfma_f32_16x16x32_bf16 v[28:31], v[158:161], v[180:183], v[28:31]
	v_mfma_f32_16x16x32_bf16 v[24:27], v[172:175], v[180:183], v[24:27]
	v_mfma_f32_16x16x32_bf16 v[20:23], v[158:161], v[188:191], v[20:23]
	v_mfma_f32_16x16x32_bf16 v[16:19], v[172:175], v[188:191], v[16:19]
	v_mfma_f32_16x16x32_bf16 v[12:15], v[158:161], v[196:199], v[12:15]
	v_mfma_f32_16x16x32_bf16 v[8:11], v[172:175], v[196:199], v[8:11]
	v_mfma_f32_16x16x32_bf16 v[4:7], v[158:161], v[204:207], v[4:7]
	v_mfma_f32_16x16x32_bf16 v[0:3], v[172:175], v[204:207], v[0:3]
	v_mfma_f32_16x16x32_bf16 v[28:31], v[162:165], v[184:187], v[28:31]
	v_mfma_f32_16x16x32_bf16 v[24:27], v[176:179], v[184:187], v[24:27]
	v_mfma_f32_16x16x32_bf16 v[20:23], v[162:165], v[192:195], v[20:23]
	v_mfma_f32_16x16x32_bf16 v[16:19], v[176:179], v[192:195], v[16:19]
	v_mfma_f32_16x16x32_bf16 v[12:15], v[162:165], v[200:203], v[12:15]
	v_mfma_f32_16x16x32_bf16 v[8:11], v[176:179], v[200:203], v[8:11]
	v_mfma_f32_16x16x32_bf16 v[4:7], v[162:165], v[208:211], v[4:7]
	v_mfma_f32_16x16x32_bf16 v[0:3], v[176:179], v[208:211], v[0:3]
	s_barrier
	s_add_u32 s48, s48, 0x100
	s_addc_u32 s49, s49, 0
	s_add_u32 s76, s76, 0x100
	s_addc_u32 s77, s77, 0
	s_cmp_ge_u32 s78, s74
	s_mov_b32 s14, s78
	s_cbranch_scc0 .LBB0_1463

; #define G_STAGE(bufoff, gbase, voff) do { _Pragma("unroll") for (int _i = 0; _i < 2; ++_i) \
;         __builtin_amdgcn_global_load_lds((const unsigned*)((const char*)(gbase) + voff[_i]), (LAS unsigned*)(lds + (bufoff) + ldsw + _i * 8192), 16, 0, 0); } while (0)
; #define G_LDA(dst, b, h) do { _Pragma("unroll") for (int m = 0; m < 4; ++m) _Pragma("unroll") for (int k = 0; k < 2; ++k) dst[m][k] = *(const LAS bf16x8*)(lds + G_SA(b, h) + aoff + m * 2048 + k * 1024); } while (0)
; #define G_MMA(ai, bj, At_, Bt_) do { __builtin_amdgcn_s_setprio(1); _Pragma("unroll") for (int m = 0; m < 4; ++m) _Pragma("unroll") for (int n = 0; n < 2; ++n) _Pragma("unroll") for (int k = 0; k < 2; ++k) \
;         acc[ai][bj][m][n] = __builtin_amdgcn_mfma_f32_16x16x32_bf16(Bt_[n][k], At_[m][k], acc[ai][bj][m][n], 0, 0, 0); __builtin_amdgcn_s_setprio(0); } while (0)
; #define WAIT_V(n) asm volatile("s_waitcnt vmcnt(" #n ")" ::: "memory")
; #define WAIT_L(n) asm volatile("s_waitcnt lgkmcnt(" #n ")" ::: "memory")
; #define BAR __builtin_amdgcn_s_barrier()
; #define SCHED __builtin_amdgcn_sched_barrier(0)
; template <class Get, class Epi>
; DI void gemm_loop(int ntiles, int ld, char* shm, const Get& get, const Epi& epi) {
;     ...
;             WAIT_V(8); WAIT_L(0); BAR; G_MMA(0, 0, At, B0); G_MMA(0, 1, At, B1); BAR; SCHED;
;             G_LDA(At, 0, 1); G_STAGE(G_SB(0, 0), b2, voffB); G_STAGE(G_SB(0, 1), b2 + hstep, voffB); G_STAGE(G_SA(0, 0), a2, voffA);
;             WAIT_V(8); WAIT_L(0); BAR; G_MMA(1, 0, At, B0); G_MMA(1, 1, At, B1); BAR; SCHED;
;     ...
;         G_ZERO;
.Lrj_1694_0:
	s_waitcnt lgkmcnt(0)
	s_barrier
	s_waitcnt lgkmcnt(0)
	v_mfma_f32_16x16x32_bf16 v[124:127], v[144:147], v[176:179], 0
	v_mfma_f32_16x16x32_bf16 v[120:123], v[152:155], v[176:179], 0
	v_mfma_f32_16x16x32_bf16 v[108:111], v[144:147], v[184:187], 0
	v_mfma_f32_16x16x32_bf16 v[104:107], v[152:155], v[184:187], 0
	v_mfma_f32_16x16x32_bf16 v[92:95], v[144:147], v[192:195], 0
	v_mfma_f32_16x16x32_bf16 v[88:91], v[152:155], v[192:195], 0
	v_mfma_f32_16x16x32_bf16 v[76:79], v[144:147], v[200:203], 0
	v_mfma_f32_16x16x32_bf16 v[72:75], v[152:155], v[200:203], 0
	v_mfma_f32_16x16x32_bf16 v[124:127], v[148:151], v[180:183], v[124:127]
	v_mfma_f32_16x16x32_bf16 v[120:123], v[156:159], v[180:183], v[120:123]
	v_mfma_f32_16x16x32_bf16 v[108:111], v[148:151], v[188:191], v[108:111]
	v_mfma_f32_16x16x32_bf16 v[104:107], v[156:159], v[188:191], v[104:107]
	v_mfma_f32_16x16x32_bf16 v[92:95], v[148:151], v[196:199], v[92:95]
	v_mfma_f32_16x16x32_bf16 v[88:91], v[156:159], v[196:199], v[88:91]
	v_mfma_f32_16x16x32_bf16 v[76:79], v[148:151], v[204:207], v[76:79]
	v_mfma_f32_16x16x32_bf16 v[72:75], v[156:159], v[204:207], v[72:75]
	v_mfma_f32_16x16x32_bf16 v[116:119], v[160:163], v[176:179], 0
	v_mfma_f32_16x16x32_bf16 v[112:115], v[168:171], v[176:179], 0
	v_mfma_f32_16x16x32_bf16 v[100:103], v[160:163], v[184:187], 0
	v_mfma_f32_16x16x32_bf16 v[96:99], v[168:171], v[184:187], 0
	v_mfma_f32_16x16x32_bf16 v[84:87], v[160:163], v[192:195], 0
	v_mfma_f32_16x16x32_bf16 v[80:83], v[168:171], v[192:195], 0
	v_mfma_f32_16x16x32_bf16 v[68:71], v[160:163], v[200:203], 0
	v_mfma_f32_16x16x32_bf16 v[64:67], v[168:171], v[200:203], 0
	v_mfma_f32_16x16x32_bf16 v[116:119], v[164:167], v[180:183], v[116:119]
	v_mfma_f32_16x16x32_bf16 v[112:115], v[172:175], v[180:183], v[112:115]
	v_mfma_f32_16x16x32_bf16 v[100:103], v[164:167], v[188:191], v[100:103]
	v_mfma_f32_16x16x32_bf16 v[96:99], v[172:175], v[188:191], v[96:99]
	v_mfma_f32_16x16x32_bf16 v[84:87], v[164:167], v[196:199], v[84:87]
	v_mfma_f32_16x16x32_bf16 v[80:83], v[172:175], v[196:199], v[80:83]
	v_mfma_f32_16x16x32_bf16 v[68:71], v[164:167], v[204:207], v[68:71]
	v_mfma_f32_16x16x32_bf16 v[64:67], v[172:175], v[204:207], v[64:67]
	s_barrier
	s_add_i32 s58, s48, s42
	v_lshl_add_u64 v[208:209], s[14:15], 0, v[132:133]
	s_mov_b32 m0, s58
	ds_read_b128 v[176:179], v143 offset:16384
	ds_read_b128 v[180:183], v143 offset:17408
	ds_read_b128 v[184:187], v143 offset:18432
	ds_read_b128 v[188:191], v143 offset:19456
	ds_read_b128 v[192:195], v143 offset:20480
	ds_read_b128 v[196:199], v143 offset:21504
	ds_read_b128 v[200:203], v143 offset:22528
	ds_read_b128 v[204:207], v143 offset:23552
	global_load_lds_dwordx4 v[208:209], off
	s_add_i32 m0, s58, 0x2000
	s_add_u32 s58, s14, 0x40000
	v_lshl_add_u64 v[210:211], s[14:15], 0, v[128:129]
	s_addc_u32 s59, s15, 0
	s_add_i32 s71, s49, s42
	global_load_lds_dwordx4 v[210:211], off
	v_lshl_add_u64 v[212:213], s[58:59], 0, v[132:133]
	s_mov_b32 m0, s71
	v_lshl_add_u64 v[214:215], s[40:41], 0, v[130:131]
	global_load_lds_dwordx4 v[212:213], off
	v_lshl_add_u64 v[212:213], s[58:59], 0, v[128:129]
	s_add_i32 m0, s71, 0x2000
	s_nop 0
	global_load_lds_dwordx4 v[212:213], off
	v_lshl_add_u64 v[212:213], s[40:41], 0, v[134:135]
	s_mov_b32 m0, s35
	s_nop 0
	global_load_lds_dwordx4 v[212:213], off
	s_mov_b32 m0, s37
	s_nop 0
	global_load_lds_dwordx4 v[214:215], off
	s_cmp_lg_u32 s100, 0
	s_cbranch_scc0 .Lrf_1694_1
	s_waitcnt vmcnt(16)
	s_branch .Lrj_1694_1

; #define G_STAGE(bufoff, gbase, voff) do { _Pragma("unroll") for (int _i = 0; _i < 2; ++_i) \
;         __builtin_amdgcn_global_load_lds((const unsigned*)((const char*)(gbase) + voff[_i]), (LAS unsigned*)(lds + (bufoff) + ldsw + _i * 8192), 16, 0, 0); } while (0)
; #define G_LDA(dst, b, h) do { _Pragma("unroll") for (int m = 0; m < 4; ++m) _Pragma("unroll") for (int k = 0; k < 2; ++k) dst[m][k] = *(const LAS bf16x8*)(lds + G_SA(b, h) + aoff + m * 2048 + k * 1024); } while (0)
; #define G_LDB(dst, b, h) do { _Pragma("unroll") for (int n = 0; n < 2; ++n) _Pragma("unroll") for (int k = 0; k < 2; ++k) dst[n][k] = *(const LAS bf16x8*)(lds + G_SB(b, h) + boff + n * 2048 + k * 1024); } while (0)
; #define G_MMA(ai, bj, At_, Bt_) do { __builtin_amdgcn_s_setprio(1); _Pragma("unroll") for (int m = 0; m < 4; ++m) _Pragma("unroll") for (int n = 0; n < 2; ++n) _Pragma("unroll") for (int k = 0; k < 2; ++k) \
;         acc[ai][bj][m][n] = __builtin_amdgcn_mfma_f32_16x16x32_bf16(Bt_[n][k], At_[m][k], acc[ai][bj][m][n], 0, 0, 0); __builtin_amdgcn_s_setprio(0); } while (0)
; #define WAIT_V(n) asm volatile("s_waitcnt vmcnt(" #n ")" ::: "memory")
; #define WAIT_L(n) asm volatile("s_waitcnt lgkmcnt(" #n ")" ::: "memory")
; #define BAR __builtin_amdgcn_s_barrier()
; #define SCHED __builtin_amdgcn_sched_barrier(0)
; template <class Get, class Epi>
; DI void gemm_loop(int ntiles, int ld, char* shm, const Get& get, const Epi& epi) {
;     ...
;             WAIT_V(8); WAIT_L(0); BAR; G_MMA(1, 0, At, B0); G_MMA(1, 1, At, B1); BAR; SCHED;
;             G_LDB(B0, 1, 0); G_LDB(B1, 1, 1); SCHED; G_LDA(At, 1, 0); G_STAGE(G_SA(0, 1), a2 + hstep, voffA);
;             WAIT_V(8); WAIT_L(0); BAR; G_MMA(0, 0, At, B0); G_MMA(0, 1, At, B1); BAR; SCHED;
.Lrj_1694_1:
	s_waitcnt lgkmcnt(0)
	s_barrier
	s_waitcnt lgkmcnt(0)
	v_mfma_f32_16x16x32_bf16 v[60:63], v[144:147], v[176:179], 0
	v_mfma_f32_16x16x32_bf16 v[56:59], v[152:155], v[176:179], 0
	v_mfma_f32_16x16x32_bf16 v[44:47], v[144:147], v[184:187], 0
	v_mfma_f32_16x16x32_bf16 v[40:43], v[152:155], v[184:187], 0
	v_mfma_f32_16x16x32_bf16 v[28:31], v[144:147], v[192:195], 0
	v_mfma_f32_16x16x32_bf16 v[24:27], v[152:155], v[192:195], 0
	v_mfma_f32_16x16x32_bf16 v[12:15], v[144:147], v[200:203], 0
	v_mfma_f32_16x16x32_bf16 v[8:11], v[152:155], v[200:203], 0
	v_mfma_f32_16x16x32_bf16 v[60:63], v[148:151], v[180:183], v[60:63]
	v_mfma_f32_16x16x32_bf16 v[56:59], v[156:159], v[180:183], v[56:59]
	v_mfma_f32_16x16x32_bf16 v[44:47], v[148:151], v[188:191], v[44:47]
	v_mfma_f32_16x16x32_bf16 v[40:43], v[156:159], v[188:191], v[40:43]
	v_mfma_f32_16x16x32_bf16 v[28:31], v[148:151], v[196:199], v[28:31]
	v_mfma_f32_16x16x32_bf16 v[24:27], v[156:159], v[196:199], v[24:27]
	v_mfma_f32_16x16x32_bf16 v[12:15], v[148:151], v[204:207], v[12:15]
	v_mfma_f32_16x16x32_bf16 v[8:11], v[156:159], v[204:207], v[8:11]
	v_mfma_f32_16x16x32_bf16 v[52:55], v[160:163], v[176:179], 0
	v_mfma_f32_16x16x32_bf16 v[48:51], v[168:171], v[176:179], 0
	v_mfma_f32_16x16x32_bf16 v[36:39], v[160:163], v[184:187], 0
	v_mfma_f32_16x16x32_bf16 v[32:35], v[168:171], v[184:187], 0
	v_mfma_f32_16x16x32_bf16 v[20:23], v[160:163], v[192:195], 0
	v_mfma_f32_16x16x32_bf16 v[16:19], v[168:171], v[192:195], 0
	v_mfma_f32_16x16x32_bf16 v[4:7], v[160:163], v[200:203], 0
	v_mfma_f32_16x16x32_bf16 v[0:3], v[168:171], v[200:203], 0
	v_mfma_f32_16x16x32_bf16 v[52:55], v[164:167], v[180:183], v[52:55]
	v_mfma_f32_16x16x32_bf16 v[48:51], v[172:175], v[180:183], v[48:51]
	v_mfma_f32_16x16x32_bf16 v[36:39], v[164:167], v[188:191], v[36:39]
	v_mfma_f32_16x16x32_bf16 v[32:35], v[172:175], v[188:191], v[32:35]
	v_mfma_f32_16x16x32_bf16 v[20:23], v[164:167], v[196:199], v[20:23]
	v_mfma_f32_16x16x32_bf16 v[16:19], v[172:175], v[196:199], v[16:19]
	v_mfma_f32_16x16x32_bf16 v[4:7], v[164:167], v[204:207], v[4:7]
	v_mfma_f32_16x16x32_bf16 v[0:3], v[172:175], v[204:207], v[0:3]
	s_barrier
	s_add_i32 s58, 0, 0x18000
	s_add_i32 s59, 0, 0x1c000
	v_add_u32_e32 v156, s58, v140
	v_add_u32_e32 v172, s59, v140
	ds_read_b128 v[144:147], v156
	ds_read_b128 v[148:151], v156 offset:1024
	ds_read_b128 v[152:155], v156 offset:2048
	ds_read_b128 v[156:159], v156 offset:3072
	ds_read_b128 v[160:163], v172
	ds_read_b128 v[164:167], v172 offset:1024
	ds_read_b128 v[168:171], v172 offset:2048
	ds_read_b128 v[172:175], v172 offset:3072
	s_add_u32 s40, s40, 0x40000
	s_addc_u32 s41, s41, 0
	s_mov_b32 m0, s44
	v_lshl_add_u64 v[216:217], s[40:41], 0, v[134:135]
	ds_read_b128 v[176:179], v143 offset:32768
	ds_read_b128 v[180:183], v143 offset:33792
	ds_read_b128 v[184:187], v143 offset:34816
	ds_read_b128 v[188:191], v143 offset:35840
	ds_read_b128 v[192:195], v143 offset:36864
	ds_read_b128 v[196:199], v143 offset:37888
	ds_read_b128 v[200:203], v143 offset:38912
	ds_read_b128 v[204:207], v143 offset:39936
	global_load_lds_dwordx4 v[216:217], off
	v_lshl_add_u64 v[216:217], s[40:41], 0, v[130:131]
	s_mov_b32 m0, s45
	s_nop 0
	global_load_lds_dwordx4 v[216:217], off
	s_waitcnt vmcnt(8)
	s_waitcnt lgkmcnt(0)
	s_barrier
	s_waitcnt lgkmcnt(0)
	v_mfma_f32_16x16x32_bf16 v[124:127], v[144:147], v[176:179], v[124:127]
	v_mfma_f32_16x16x32_bf16 v[120:123], v[152:155], v[176:179], v[120:123]
	v_mfma_f32_16x16x32_bf16 v[108:111], v[144:147], v[184:187], v[108:111]
	v_mfma_f32_16x16x32_bf16 v[104:107], v[152:155], v[184:187], v[104:107]
	v_mfma_f32_16x16x32_bf16 v[92:95], v[144:147], v[192:195], v[92:95]
	v_mfma_f32_16x16x32_bf16 v[88:91], v[152:155], v[192:195], v[88:91]
	v_mfma_f32_16x16x32_bf16 v[76:79], v[144:147], v[200:203], v[76:79]
	v_mfma_f32_16x16x32_bf16 v[72:75], v[152:155], v[200:203], v[72:75]
	v_mfma_f32_16x16x32_bf16 v[124:127], v[148:151], v[180:183], v[124:127]
	v_mfma_f32_16x16x32_bf16 v[120:123], v[156:159], v[180:183], v[120:123]
	v_mfma_f32_16x16x32_bf16 v[108:111], v[148:151], v[188:191], v[108:111]
	v_mfma_f32_16x16x32_bf16 v[104:107], v[156:159], v[188:191], v[104:107]
	v_mfma_f32_16x16x32_bf16 v[92:95], v[148:151], v[196:199], v[92:95]
	v_mfma_f32_16x16x32_bf16 v[88:91], v[156:159], v[196:199], v[88:91]
	v_mfma_f32_16x16x32_bf16 v[76:79], v[148:151], v[204:207], v[76:79]
	v_mfma_f32_16x16x32_bf16 v[72:75], v[156:159], v[204:207], v[72:75]
	v_mfma_f32_16x16x32_bf16 v[116:119], v[160:163], v[176:179], v[116:119]
	v_mfma_f32_16x16x32_bf16 v[112:115], v[168:171], v[176:179], v[112:115]
	v_mfma_f32_16x16x32_bf16 v[100:103], v[160:163], v[184:187], v[100:103]
	v_mfma_f32_16x16x32_bf16 v[96:99], v[168:171], v[184:187], v[96:99]
	v_mfma_f32_16x16x32_bf16 v[84:87], v[160:163], v[192:195], v[84:87]
	v_mfma_f32_16x16x32_bf16 v[80:83], v[168:171], v[192:195], v[80:83]
	v_mfma_f32_16x16x32_bf16 v[68:71], v[160:163], v[200:203], v[68:71]
	v_mfma_f32_16x16x32_bf16 v[64:67], v[168:171], v[200:203], v[64:67]
	v_mfma_f32_16x16x32_bf16 v[116:119], v[164:167], v[180:183], v[116:119]
	v_mfma_f32_16x16x32_bf16 v[112:115], v[172:175], v[180:183], v[112:115]
	v_mfma_f32_16x16x32_bf16 v[100:103], v[164:167], v[188:191], v[100:103]
	v_mfma_f32_16x16x32_bf16 v[96:99], v[172:175], v[188:191], v[96:99]
	v_mfma_f32_16x16x32_bf16 v[84:87], v[164:167], v[196:199], v[84:87]
	v_mfma_f32_16x16x32_bf16 v[80:83], v[172:175], v[196:199], v[80:83]
	v_mfma_f32_16x16x32_bf16 v[68:71], v[164:167], v[204:207], v[68:71]
	v_mfma_f32_16x16x32_bf16 v[64:67], v[172:175], v[204:207], v[64:67]
	s_barrier
; #define G_STAGE(bufoff, gbase, voff) do { _Pragma("unroll") for (int _i = 0; _i < 2; ++_i) \
;         __builtin_amdgcn_global_load_lds((const unsigned*)((const char*)(gbase) + voff[_i]), (LAS unsigned*)(lds + (bufoff) + ldsw + _i * 8192), 16, 0, 0); } while (0)
; #define G_LDA(dst, b, h) do { _Pragma("unroll") for (int m = 0; m < 4; ++m) _Pragma("unroll") for (int k = 0; k < 2; ++k) dst[m][k] = *(const LAS bf16x8*)(lds + G_SA(b, h) + aoff + m * 2048 + k * 1024); } while (0)
; #define G_LDB(dst, b, h) do { _Pragma("unroll") for (int n = 0; n < 2; ++n) _Pragma("unroll") for (int k = 0; k < 2; ++k) dst[n][k] = *(const LAS bf16x8*)(lds + G_SB(b, h) + boff + n * 2048 + k * 1024); } while (0)
; #define G_MMA(ai, bj, At_, Bt_) do { __builtin_amdgcn_s_setprio(1); _Pragma("unroll") for (int m = 0; m < 4; ++m) _Pragma("unroll") for (int n = 0; n < 2; ++n) _Pragma("unroll") for (int k = 0; k < 2; ++k) \
;         acc[ai][bj][m][n] = __builtin_amdgcn_mfma_f32_16x16x32_bf16(Bt_[n][k], At_[m][k], acc[ai][bj][m][n], 0, 0, 0); __builtin_amdgcn_s_setprio(0); } while (0)
; #define WAIT_V(n) asm volatile("s_waitcnt vmcnt(" #n ")" ::: "memory")
; #define WAIT_L(n) asm volatile("s_waitcnt lgkmcnt(" #n ")" ::: "memory")
; #define BAR __builtin_amdgcn_s_barrier()
; #define SCHED __builtin_amdgcn_sched_barrier(0)
; template <class Get, class Epi>
; DI void gemm_loop(int ntiles, int ld, char* shm, const Get& get, const Epi& epi) {
;     ...
;             G_LDB(B0, 0, 0); G_LDB(B1, 0, 1); SCHED; G_LDA(At, 0, 0); G_STAGE(G_SA(1, 1), a1 + hstep, voffA);
;             WAIT_V(8); WAIT_L(0); BAR; G_MMA(0, 0, At, B0); G_MMA(0, 1, At, B1); BAR; SCHED;
;     ...
;             G_LDA(At, 1, 1); G_STAGE(G_SB(1, 0), b3, voffB); G_STAGE(G_SB(1, 1), b3 + hstep, voffB); G_STAGE(G_SA(1, 0), a3, voffA);
;             WAIT_V(8); WAIT_L(0); BAR; G_MMA(1, 0, At, B0); G_MMA(1, 1, At, B1); BAR; SCHED;
;         }
	s_add_i32 s40, s58, s42
	v_lshl_add_u64 v[208:209], v[208:209], 0, s[2:3]
	s_mov_b32 m0, s40
	ds_read_b128 v[176:179], v143 offset:49152
	ds_read_b128 v[180:183], v143 offset:50176
	ds_read_b128 v[184:187], v143 offset:51200
	ds_read_b128 v[188:191], v143 offset:52224
	ds_read_b128 v[192:195], v143 offset:53248
	ds_read_b128 v[196:199], v143 offset:54272
	ds_read_b128 v[200:203], v143 offset:55296
	ds_read_b128 v[204:207], v143 offset:56320
	global_load_lds_dwordx4 v[208:209], off
	s_add_i32 m0, s40, 0x2000
	s_add_u32 s14, s14, 0x40080
	v_lshl_add_u64 v[208:209], v[210:211], 0, s[2:3]
	s_addc_u32 s15, s15, 0
	s_add_i32 s40, s59, s42
	global_load_lds_dwordx4 v[208:209], off
	v_lshl_add_u64 v[208:209], s[14:15], 0, v[132:133]
	s_mov_b32 m0, s40
	s_nop 0
	global_load_lds_dwordx4 v[208:209], off
	v_lshl_add_u64 v[208:209], s[14:15], 0, v[128:129]
	s_add_i32 m0, s40, 0x2000
	s_nop 0
	global_load_lds_dwordx4 v[208:209], off
	v_lshl_add_u64 v[208:209], v[212:213], 0, s[2:3]
	s_mov_b32 m0, s46
	s_nop 0
	global_load_lds_dwordx4 v[208:209], off
	v_lshl_add_u64 v[208:209], v[214:215], 0, s[2:3]
	s_mov_b32 m0, s47
	s_nop 0
	global_load_lds_dwordx4 v[208:209], off
	s_waitcnt vmcnt(8)
	s_waitcnt lgkmcnt(0)
	s_barrier
	s_waitcnt lgkmcnt(0)
	v_mfma_f32_16x16x32_bf16 v[60:63], v[144:147], v[176:179], v[60:63]
	v_mfma_f32_16x16x32_bf16 v[56:59], v[152:155], v[176:179], v[56:59]
	v_mfma_f32_16x16x32_bf16 v[44:47], v[144:147], v[184:187], v[44:47]
	v_mfma_f32_16x16x32_bf16 v[40:43], v[152:155], v[184:187], v[40:43]
	v_mfma_f32_16x16x32_bf16 v[28:31], v[144:147], v[192:195], v[28:31]
	v_mfma_f32_16x16x32_bf16 v[24:27], v[152:155], v[192:195], v[24:27]
	v_mfma_f32_16x16x32_bf16 v[12:15], v[144:147], v[200:203], v[12:15]
	v_mfma_f32_16x16x32_bf16 v[8:11], v[152:155], v[200:203], v[8:11]
	v_mfma_f32_16x16x32_bf16 v[60:63], v[148:151], v[180:183], v[60:63]
	v_mfma_f32_16x16x32_bf16 v[56:59], v[156:159], v[180:183], v[56:59]
	v_mfma_f32_16x16x32_bf16 v[44:47], v[148:151], v[188:191], v[44:47]
	v_mfma_f32_16x16x32_bf16 v[40:43], v[156:159], v[188:191], v[40:43]
	v_mfma_f32_16x16x32_bf16 v[28:31], v[148:151], v[196:199], v[28:31]
	v_mfma_f32_16x16x32_bf16 v[24:27], v[156:159], v[196:199], v[24:27]
	v_mfma_f32_16x16x32_bf16 v[12:15], v[148:151], v[204:207], v[12:15]
	v_mfma_f32_16x16x32_bf16 v[8:11], v[156:159], v[204:207], v[8:11]
	v_mfma_f32_16x16x32_bf16 v[52:55], v[160:163], v[176:179], v[52:55]
	v_mfma_f32_16x16x32_bf16 v[48:51], v[168:171], v[176:179], v[48:51]
	v_mfma_f32_16x16x32_bf16 v[36:39], v[160:163], v[184:187], v[36:39]
	v_mfma_f32_16x16x32_bf16 v[32:35], v[168:171], v[184:187], v[32:35]
	v_mfma_f32_16x16x32_bf16 v[20:23], v[160:163], v[192:195], v[20:23]
	v_mfma_f32_16x16x32_bf16 v[16:19], v[168:171], v[192:195], v[16:19]
	v_mfma_f32_16x16x32_bf16 v[4:7], v[160:163], v[200:203], v[4:7]
	v_mfma_f32_16x16x32_bf16 v[0:3], v[168:171], v[200:203], v[0:3]
	v_mfma_f32_16x16x32_bf16 v[52:55], v[164:167], v[180:183], v[52:55]
	v_mfma_f32_16x16x32_bf16 v[48:51], v[172:175], v[180:183], v[48:51]
	v_mfma_f32_16x16x32_bf16 v[36:39], v[164:167], v[188:191], v[36:39]
	v_mfma_f32_16x16x32_bf16 v[32:35], v[172:175], v[188:191], v[32:35]
	v_mfma_f32_16x16x32_bf16 v[20:23], v[164:167], v[196:199], v[20:23]
	v_mfma_f32_16x16x32_bf16 v[16:19], v[172:175], v[196:199], v[16:19]
	v_mfma_f32_16x16x32_bf16 v[4:7], v[164:167], v[204:207], v[4:7]
	v_mfma_f32_16x16x32_bf16 v[0:3], v[172:175], v[204:207], v[0:3]
	s_barrier
	s_add_i32 s57, s57, 2
	s_add_u32 s38, s38, 0x100
	s_addc_u32 s39, s39, 0
	s_add_u32 s55, s55, 0x100
	s_addc_u32 s56, s56, 0
	s_cmp_gt_u32 s57, 13
	s_cbranch_scc0 .LBB0_1694
	s_branch .Lpost_1694
.LBB0_1694:
	ds_read_b128 v[144:147], v141
	ds_read_b128 v[148:151], v141 offset:1024
	ds_read_b128 v[152:155], v141 offset:2048
	ds_read_b128 v[156:159], v141 offset:3072
	ds_read_b128 v[160:163], v142
	ds_read_b128 v[164:167], v142 offset:1024
	ds_read_b128 v[168:171], v142 offset:2048
	ds_read_b128 v[172:175], v142 offset:3072
	s_add_u32 s14, s38, 0xfffc0080
	s_addc_u32 s15, s39, -1
	s_cmp_eq_u32 s57, 12
	s_cselect_b32 s41, s9, s15
	s_cselect_b32 s40, s53, s14
	s_cselect_b32 s15, s11, s56
	s_cselect_b32 s14, s54, s55
	v_lshl_add_u64 v[208:209], s[38:39], 0, v[136:137]
	s_add_i32 m0, s35, 0xc000
	ds_read_b128 v[176:179], v143
	ds_read_b128 v[180:183], v143 offset:1024
	ds_read_b128 v[184:187], v143 offset:2048
	ds_read_b128 v[188:191], v143 offset:3072
	ds_read_b128 v[192:195], v143 offset:4096
	ds_read_b128 v[196:199], v143 offset:5120
	ds_read_b128 v[200:203], v143 offset:6144
	ds_read_b128 v[204:207], v143 offset:7168
	global_load_lds_dwordx4 v[208:209], off
	v_lshl_add_u64 v[208:209], s[38:39], 0, v[138:139]
	s_add_i32 m0, s35, 0xe000
	s_nop 0
	global_load_lds_dwordx4 v[208:209], off
	s_waitcnt vmcnt(8)
	s_waitcnt lgkmcnt(0)
	s_barrier
; #define G_STAGE(bufoff, gbase, voff) do { _Pragma("unroll") for (int _i = 0; _i < 2; ++_i) \
;         __builtin_amdgcn_global_load_lds((const unsigned*)((const char*)(gbase) + voff[_i]), (LAS unsigned*)(lds + (bufoff) + ldsw + _i * 8192), 16, 0, 0); } while (0)
; #define G_LDA(dst, b, h) do { _Pragma("unroll") for (int m = 0; m < 4; ++m) _Pragma("unroll") for (int k = 0; k < 2; ++k) dst[m][k] = *(const LAS bf16x8*)(lds + G_SA(b, h) + aoff + m * 2048 + k * 1024); } while (0)
; #define G_MMA(ai, bj, At_, Bt_) do { __builtin_amdgcn_s_setprio(1); _Pragma("unroll") for (int m = 0; m < 4; ++m) _Pragma("unroll") for (int n = 0; n < 2; ++n) _Pragma("unroll") for (int k = 0; k < 2; ++k) \
;         acc[ai][bj][m][n] = __builtin_amdgcn_mfma_f32_16x16x32_bf16(Bt_[n][k], At_[m][k], acc[ai][bj][m][n], 0, 0, 0); __builtin_amdgcn_s_setprio(0); } while (0)
; #define WAIT_V(n) asm volatile("s_waitcnt vmcnt(" #n ")" ::: "memory")
; #define WAIT_L(n) asm volatile("s_waitcnt lgkmcnt(" #n ")" ::: "memory")
; #define BAR __builtin_amdgcn_s_barrier()
; #define SCHED __builtin_amdgcn_sched_barrier(0)
; template <class Get, class Epi>
; DI void gemm_loop(int ntiles, int ld, char* shm, const Get& get, const Epi& epi) {
;     ...
;             WAIT_V(8); WAIT_L(0); BAR; G_MMA(0, 0, At, B0); G_MMA(0, 1, At, B1); BAR; SCHED;
;             G_LDA(At, 0, 1); G_STAGE(G_SB(0, 0), b2, voffB); G_STAGE(G_SB(0, 1), b2 + hstep, voffB); G_STAGE(G_SA(0, 0), a2, voffA);
;             WAIT_V(8); WAIT_L(0); BAR; G_MMA(1, 0, At, B0); G_MMA(1, 1, At, B1); BAR; SCHED;
	s_waitcnt lgkmcnt(0)
	v_mfma_f32_16x16x32_bf16 v[124:127], v[144:147], v[176:179], v[124:127]
	v_mfma_f32_16x16x32_bf16 v[120:123], v[152:155], v[176:179], v[120:123]
	v_mfma_f32_16x16x32_bf16 v[108:111], v[144:147], v[184:187], v[108:111]
	v_mfma_f32_16x16x32_bf16 v[104:107], v[152:155], v[184:187], v[104:107]
	v_mfma_f32_16x16x32_bf16 v[92:95], v[144:147], v[192:195], v[92:95]
	v_mfma_f32_16x16x32_bf16 v[88:91], v[152:155], v[192:195], v[88:91]
	v_mfma_f32_16x16x32_bf16 v[76:79], v[144:147], v[200:203], v[76:79]
	v_mfma_f32_16x16x32_bf16 v[72:75], v[152:155], v[200:203], v[72:75]
	v_mfma_f32_16x16x32_bf16 v[124:127], v[148:151], v[180:183], v[124:127]
	v_mfma_f32_16x16x32_bf16 v[120:123], v[156:159], v[180:183], v[120:123]
	v_mfma_f32_16x16x32_bf16 v[108:111], v[148:151], v[188:191], v[108:111]
	v_mfma_f32_16x16x32_bf16 v[104:107], v[156:159], v[188:191], v[104:107]
	v_mfma_f32_16x16x32_bf16 v[92:95], v[148:151], v[196:199], v[92:95]
	v_mfma_f32_16x16x32_bf16 v[88:91], v[156:159], v[196:199], v[88:91]
	v_mfma_f32_16x16x32_bf16 v[76:79], v[148:151], v[204:207], v[76:79]
	v_mfma_f32_16x16x32_bf16 v[72:75], v[156:159], v[204:207], v[72:75]
	v_mfma_f32_16x16x32_bf16 v[116:119], v[160:163], v[176:179], v[116:119]
	v_mfma_f32_16x16x32_bf16 v[112:115], v[168:171], v[176:179], v[112:115]
	v_mfma_f32_16x16x32_bf16 v[100:103], v[160:163], v[184:187], v[100:103]
	v_mfma_f32_16x16x32_bf16 v[96:99], v[168:171], v[184:187], v[96:99]
	v_mfma_f32_16x16x32_bf16 v[84:87], v[160:163], v[192:195], v[84:87]
	v_mfma_f32_16x16x32_bf16 v[80:83], v[168:171], v[192:195], v[80:83]
	v_mfma_f32_16x16x32_bf16 v[68:71], v[160:163], v[200:203], v[68:71]
	v_mfma_f32_16x16x32_bf16 v[64:67], v[168:171], v[200:203], v[64:67]
	v_mfma_f32_16x16x32_bf16 v[116:119], v[164:167], v[180:183], v[116:119]
	v_mfma_f32_16x16x32_bf16 v[112:115], v[172:175], v[180:183], v[112:115]
	v_mfma_f32_16x16x32_bf16 v[100:103], v[164:167], v[188:191], v[100:103]
	v_mfma_f32_16x16x32_bf16 v[96:99], v[172:175], v[188:191], v[96:99]
	v_mfma_f32_16x16x32_bf16 v[84:87], v[164:167], v[196:199], v[84:87]
	v_mfma_f32_16x16x32_bf16 v[80:83], v[172:175], v[196:199], v[80:83]
	v_mfma_f32_16x16x32_bf16 v[68:71], v[164:167], v[204:207], v[68:71]
	v_mfma_f32_16x16x32_bf16 v[64:67], v[172:175], v[204:207], v[64:67]
	s_barrier
	s_add_i32 s58, s48, s42
	v_lshl_add_u64 v[208:209], s[14:15], 0, v[132:133]
	s_mov_b32 m0, s58
	ds_read_b128 v[176:179], v143 offset:16384
	ds_read_b128 v[180:183], v143 offset:17408
	ds_read_b128 v[184:187], v143 offset:18432
	ds_read_b128 v[188:191], v143 offset:19456
	ds_read_b128 v[192:195], v143 offset:20480
	ds_read_b128 v[196:199], v143 offset:21504
	ds_read_b128 v[200:203], v143 offset:22528
	ds_read_b128 v[204:207], v143 offset:23552
	global_load_lds_dwordx4 v[208:209], off
	s_add_i32 m0, s58, 0x2000
	s_add_u32 s58, s14, 0x40000
	v_lshl_add_u64 v[210:211], s[14:15], 0, v[128:129]
	s_addc_u32 s59, s15, 0
	s_add_i32 s71, s49, s42
	global_load_lds_dwordx4 v[210:211], off
	v_lshl_add_u64 v[212:213], s[58:59], 0, v[132:133]
	s_mov_b32 m0, s71
	v_lshl_add_u64 v[214:215], s[40:41], 0, v[130:131]
	global_load_lds_dwordx4 v[212:213], off
	v_lshl_add_u64 v[212:213], s[58:59], 0, v[128:129]
	s_add_i32 m0, s71, 0x2000
	s_nop 0
	global_load_lds_dwordx4 v[212:213], off
	v_lshl_add_u64 v[212:213], s[40:41], 0, v[134:135]
	s_mov_b32 m0, s35
	s_nop 0
	global_load_lds_dwordx4 v[212:213], off
	s_mov_b32 m0, s37
	s_nop 0
	global_load_lds_dwordx4 v[214:215], off
	s_waitcnt vmcnt(8)
	s_waitcnt lgkmcnt(0)
	s_barrier
	s_waitcnt lgkmcnt(0)
	v_mfma_f32_16x16x32_bf16 v[60:63], v[144:147], v[176:179], v[60:63]
	v_mfma_f32_16x16x32_bf16 v[56:59], v[152:155], v[176:179], v[56:59]
	v_mfma_f32_16x16x32_bf16 v[44:47], v[144:147], v[184:187], v[44:47]
	v_mfma_f32_16x16x32_bf16 v[40:43], v[152:155], v[184:187], v[40:43]
	v_mfma_f32_16x16x32_bf16 v[28:31], v[144:147], v[192:195], v[28:31]
	v_mfma_f32_16x16x32_bf16 v[24:27], v[152:155], v[192:195], v[24:27]
	v_mfma_f32_16x16x32_bf16 v[12:15], v[144:147], v[200:203], v[12:15]
	v_mfma_f32_16x16x32_bf16 v[8:11], v[152:155], v[200:203], v[8:11]
	v_mfma_f32_16x16x32_bf16 v[60:63], v[148:151], v[180:183], v[60:63]
	v_mfma_f32_16x16x32_bf16 v[56:59], v[156:159], v[180:183], v[56:59]
	v_mfma_f32_16x16x32_bf16 v[44:47], v[148:151], v[188:191], v[44:47]
	v_mfma_f32_16x16x32_bf16 v[40:43], v[156:159], v[188:191], v[40:43]
	v_mfma_f32_16x16x32_bf16 v[28:31], v[148:151], v[196:199], v[28:31]
	v_mfma_f32_16x16x32_bf16 v[24:27], v[156:159], v[196:199], v[24:27]
	v_mfma_f32_16x16x32_bf16 v[12:15], v[148:151], v[204:207], v[12:15]
	v_mfma_f32_16x16x32_bf16 v[8:11], v[156:159], v[204:207], v[8:11]
	v_mfma_f32_16x16x32_bf16 v[52:55], v[160:163], v[176:179], v[52:55]
	v_mfma_f32_16x16x32_bf16 v[48:51], v[168:171], v[176:179], v[48:51]
	v_mfma_f32_16x16x32_bf16 v[36:39], v[160:163], v[184:187], v[36:39]
	v_mfma_f32_16x16x32_bf16 v[32:35], v[168:171], v[184:187], v[32:35]
	v_mfma_f32_16x16x32_bf16 v[20:23], v[160:163], v[192:195], v[20:23]
	v_mfma_f32_16x16x32_bf16 v[16:19], v[168:171], v[192:195], v[16:19]
	v_mfma_f32_16x16x32_bf16 v[4:7], v[160:163], v[200:203], v[4:7]
	v_mfma_f32_16x16x32_bf16 v[0:3], v[168:171], v[200:203], v[0:3]
	v_mfma_f32_16x16x32_bf16 v[52:55], v[164:167], v[180:183], v[52:55]
	v_mfma_f32_16x16x32_bf16 v[48:51], v[172:175], v[180:183], v[48:51]
	v_mfma_f32_16x16x32_bf16 v[36:39], v[164:167], v[188:191], v[36:39]
	v_mfma_f32_16x16x32_bf16 v[32:35], v[172:175], v[188:191], v[32:35]
	v_mfma_f32_16x16x32_bf16 v[20:23], v[164:167], v[196:199], v[20:23]
	v_mfma_f32_16x16x32_bf16 v[16:19], v[172:175], v[196:199], v[16:19]
	v_mfma_f32_16x16x32_bf16 v[4:7], v[164:167], v[204:207], v[4:7]
	v_mfma_f32_16x16x32_bf16 v[0:3], v[172:175], v[204:207], v[0:3]
	s_barrier
; #define G_STAGE(bufoff, gbase, voff) do { _Pragma("unroll") for (int _i = 0; _i < 2; ++_i) \
;         __builtin_amdgcn_global_load_lds((const unsigned*)((const char*)(gbase) + voff[_i]), (LAS unsigned*)(lds + (bufoff) + ldsw + _i * 8192), 16, 0, 0); } while (0)
; #define G_LDA(dst, b, h) do { _Pragma("unroll") for (int m = 0; m < 4; ++m) _Pragma("unroll") for (int k = 0; k < 2; ++k) dst[m][k] = *(const LAS bf16x8*)(lds + G_SA(b, h) + aoff + m * 2048 + k * 1024); } while (0)
; #define G_LDB(dst, b, h) do { _Pragma("unroll") for (int n = 0; n < 2; ++n) _Pragma("unroll") for (int k = 0; k < 2; ++k) dst[n][k] = *(const LAS bf16x8*)(lds + G_SB(b, h) + boff + n * 2048 + k * 1024); } while (0)
; #define G_MMA(ai, bj, At_, Bt_) do { __builtin_amdgcn_s_setprio(1); _Pragma("unroll") for (int m = 0; m < 4; ++m) _Pragma("unroll") for (int n = 0; n < 2; ++n) _Pragma("unroll") for (int k = 0; k < 2; ++k) \
;         acc[ai][bj][m][n] = __builtin_amdgcn_mfma_f32_16x16x32_bf16(Bt_[n][k], At_[m][k], acc[ai][bj][m][n], 0, 0, 0); __builtin_amdgcn_s_setprio(0); } while (0)
; #define WAIT_V(n) asm volatile("s_waitcnt vmcnt(" #n ")" ::: "memory")
; #define WAIT_L(n) asm volatile("s_waitcnt lgkmcnt(" #n ")" ::: "memory")
; #define BAR __builtin_amdgcn_s_barrier()
; #define SCHED __builtin_amdgcn_sched_barrier(0)
; template <class Get, class Epi>
; DI void gemm_loop(int ntiles, int ld, char* shm, const Get& get, const Epi& epi) {
;     ...
;             G_LDB(B0, 1, 0); G_LDB(B1, 1, 1); SCHED; G_LDA(At, 1, 0); G_STAGE(G_SA(0, 1), a2 + hstep, voffA);
;             WAIT_V(8); WAIT_L(0); BAR; G_MMA(0, 0, At, B0); G_MMA(0, 1, At, B1); BAR; SCHED;
;             G_LDA(At, 1, 1); G_STAGE(G_SB(1, 0), b3, voffB); G_STAGE(G_SB(1, 1), b3 + hstep, voffB); G_STAGE(G_SA(1, 0), a3, voffA);
;             WAIT_V(8); WAIT_L(0); BAR; G_MMA(1, 0, At, B0); G_MMA(1, 1, At, B1); BAR; SCHED;
;         }
	s_add_i32 s58, 0, 0x18000
	s_add_i32 s59, 0, 0x1c000
	v_add_u32_e32 v156, s58, v140
	v_add_u32_e32 v172, s59, v140
	ds_read_b128 v[144:147], v156
	ds_read_b128 v[148:151], v156 offset:1024
	ds_read_b128 v[152:155], v156 offset:2048
	ds_read_b128 v[156:159], v156 offset:3072
	ds_read_b128 v[160:163], v172
	ds_read_b128 v[164:167], v172 offset:1024
	ds_read_b128 v[168:171], v172 offset:2048
	ds_read_b128 v[172:175], v172 offset:3072
	s_add_u32 s40, s40, 0x40000
	s_addc_u32 s41, s41, 0
	s_mov_b32 m0, s44
	v_lshl_add_u64 v[216:217], s[40:41], 0, v[134:135]
	ds_read_b128 v[176:179], v143 offset:32768
	ds_read_b128 v[180:183], v143 offset:33792
	ds_read_b128 v[184:187], v143 offset:34816
	ds_read_b128 v[188:191], v143 offset:35840
	ds_read_b128 v[192:195], v143 offset:36864
	ds_read_b128 v[196:199], v143 offset:37888
	ds_read_b128 v[200:203], v143 offset:38912
	ds_read_b128 v[204:207], v143 offset:39936
	global_load_lds_dwordx4 v[216:217], off
	v_lshl_add_u64 v[216:217], s[40:41], 0, v[130:131]
	s_mov_b32 m0, s45
	s_nop 0
	global_load_lds_dwordx4 v[216:217], off
	s_waitcnt vmcnt(8)
	s_waitcnt lgkmcnt(0)
	s_barrier
	s_waitcnt lgkmcnt(0)
	v_mfma_f32_16x16x32_bf16 v[124:127], v[144:147], v[176:179], v[124:127]
	v_mfma_f32_16x16x32_bf16 v[120:123], v[152:155], v[176:179], v[120:123]
	v_mfma_f32_16x16x32_bf16 v[108:111], v[144:147], v[184:187], v[108:111]
	v_mfma_f32_16x16x32_bf16 v[104:107], v[152:155], v[184:187], v[104:107]
	v_mfma_f32_16x16x32_bf16 v[92:95], v[144:147], v[192:195], v[92:95]
	v_mfma_f32_16x16x32_bf16 v[88:91], v[152:155], v[192:195], v[88:91]
	v_mfma_f32_16x16x32_bf16 v[76:79], v[144:147], v[200:203], v[76:79]
	v_mfma_f32_16x16x32_bf16 v[72:75], v[152:155], v[200:203], v[72:75]
	v_mfma_f32_16x16x32_bf16 v[124:127], v[148:151], v[180:183], v[124:127]
	v_mfma_f32_16x16x32_bf16 v[120:123], v[156:159], v[180:183], v[120:123]
	v_mfma_f32_16x16x32_bf16 v[108:111], v[148:151], v[188:191], v[108:111]
	v_mfma_f32_16x16x32_bf16 v[104:107], v[156:159], v[188:191], v[104:107]
	v_mfma_f32_16x16x32_bf16 v[92:95], v[148:151], v[196:199], v[92:95]
	v_mfma_f32_16x16x32_bf16 v[88:91], v[156:159], v[196:199], v[88:91]
	v_mfma_f32_16x16x32_bf16 v[76:79], v[148:151], v[204:207], v[76:79]
	v_mfma_f32_16x16x32_bf16 v[72:75], v[156:159], v[204:207], v[72:75]
	v_mfma_f32_16x16x32_bf16 v[116:119], v[160:163], v[176:179], v[116:119]
	v_mfma_f32_16x16x32_bf16 v[112:115], v[168:171], v[176:179], v[112:115]
	v_mfma_f32_16x16x32_bf16 v[100:103], v[160:163], v[184:187], v[100:103]
	v_mfma_f32_16x16x32_bf16 v[96:99], v[168:171], v[184:187], v[96:99]
	v_mfma_f32_16x16x32_bf16 v[84:87], v[160:163], v[192:195], v[84:87]
	v_mfma_f32_16x16x32_bf16 v[80:83], v[168:171], v[192:195], v[80:83]
	v_mfma_f32_16x16x32_bf16 v[68:71], v[160:163], v[200:203], v[68:71]
	v_mfma_f32_16x16x32_bf16 v[64:67], v[168:171], v[200:203], v[64:67]
	v_mfma_f32_16x16x32_bf16 v[116:119], v[164:167], v[180:183], v[116:119]
	v_mfma_f32_16x16x32_bf16 v[112:115], v[172:175], v[180:183], v[112:115]
	v_mfma_f32_16x16x32_bf16 v[100:103], v[164:167], v[188:191], v[100:103]
	v_mfma_f32_16x16x32_bf16 v[96:99], v[172:175], v[188:191], v[96:99]
	v_mfma_f32_16x16x32_bf16 v[84:87], v[164:167], v[196:199], v[84:87]
	v_mfma_f32_16x16x32_bf16 v[80:83], v[172:175], v[196:199], v[80:83]
	v_mfma_f32_16x16x32_bf16 v[68:71], v[164:167], v[204:207], v[68:71]
	v_mfma_f32_16x16x32_bf16 v[64:67], v[172:175], v[204:207], v[64:67]
	s_barrier
	s_add_i32 s40, s58, s42
	v_lshl_add_u64 v[208:209], v[208:209], 0, s[2:3]
	s_mov_b32 m0, s40
	ds_read_b128 v[176:179], v143 offset:49152
	ds_read_b128 v[180:183], v143 offset:50176
	ds_read_b128 v[184:187], v143 offset:51200
	ds_read_b128 v[188:191], v143 offset:52224
	ds_read_b128 v[192:195], v143 offset:53248
	ds_read_b128 v[196:199], v143 offset:54272
	ds_read_b128 v[200:203], v143 offset:55296
	ds_read_b128 v[204:207], v143 offset:56320
	global_load_lds_dwordx4 v[208:209], off
	s_add_i32 m0, s40, 0x2000
	s_add_u32 s14, s14, 0x40080
	v_lshl_add_u64 v[208:209], v[210:211], 0, s[2:3]
	s_addc_u32 s15, s15, 0
	s_add_i32 s40, s59, s42
	global_load_lds_dwordx4 v[208:209], off
	v_lshl_add_u64 v[208:209], s[14:15], 0, v[132:133]
	s_mov_b32 m0, s40
	s_nop 0
	global_load_lds_dwordx4 v[208:209], off
	v_lshl_add_u64 v[208:209], s[14:15], 0, v[128:129]
	s_add_i32 m0, s40, 0x2000
	s_nop 0
	global_load_lds_dwordx4 v[208:209], off
	v_lshl_add_u64 v[208:209], v[212:213], 0, s[2:3]
	s_mov_b32 m0, s46
	s_nop 0
	global_load_lds_dwordx4 v[208:209], off
	v_lshl_add_u64 v[208:209], v[214:215], 0, s[2:3]
	s_mov_b32 m0, s47
	s_nop 0
	global_load_lds_dwordx4 v[208:209], off
	s_waitcnt vmcnt(8)
	s_waitcnt lgkmcnt(0)
	s_barrier
	s_waitcnt lgkmcnt(0)
	v_mfma_f32_16x16x32_bf16 v[60:63], v[144:147], v[176:179], v[60:63]
	v_mfma_f32_16x16x32_bf16 v[56:59], v[152:155], v[176:179], v[56:59]
	v_mfma_f32_16x16x32_bf16 v[44:47], v[144:147], v[184:187], v[44:47]
	v_mfma_f32_16x16x32_bf16 v[40:43], v[152:155], v[184:187], v[40:43]
	v_mfma_f32_16x16x32_bf16 v[28:31], v[144:147], v[192:195], v[28:31]
	v_mfma_f32_16x16x32_bf16 v[24:27], v[152:155], v[192:195], v[24:27]
	v_mfma_f32_16x16x32_bf16 v[12:15], v[144:147], v[200:203], v[12:15]
	v_mfma_f32_16x16x32_bf16 v[8:11], v[152:155], v[200:203], v[8:11]
	v_mfma_f32_16x16x32_bf16 v[60:63], v[148:151], v[180:183], v[60:63]
	v_mfma_f32_16x16x32_bf16 v[56:59], v[156:159], v[180:183], v[56:59]
	v_mfma_f32_16x16x32_bf16 v[44:47], v[148:151], v[188:191], v[44:47]
	v_mfma_f32_16x16x32_bf16 v[40:43], v[156:159], v[188:191], v[40:43]
	v_mfma_f32_16x16x32_bf16 v[28:31], v[148:151], v[196:199], v[28:31]
	v_mfma_f32_16x16x32_bf16 v[24:27], v[156:159], v[196:199], v[24:27]
	v_mfma_f32_16x16x32_bf16 v[12:15], v[148:151], v[204:207], v[12:15]
	v_mfma_f32_16x16x32_bf16 v[8:11], v[156:159], v[204:207], v[8:11]
	v_mfma_f32_16x16x32_bf16 v[52:55], v[160:163], v[176:179], v[52:55]
	v_mfma_f32_16x16x32_bf16 v[48:51], v[168:171], v[176:179], v[48:51]
	v_mfma_f32_16x16x32_bf16 v[36:39], v[160:163], v[184:187], v[36:39]
	v_mfma_f32_16x16x32_bf16 v[32:35], v[168:171], v[184:187], v[32:35]
	v_mfma_f32_16x16x32_bf16 v[20:23], v[160:163], v[192:195], v[20:23]
	v_mfma_f32_16x16x32_bf16 v[16:19], v[168:171], v[192:195], v[16:19]
	v_mfma_f32_16x16x32_bf16 v[4:7], v[160:163], v[200:203], v[4:7]
	v_mfma_f32_16x16x32_bf16 v[0:3], v[168:171], v[200:203], v[0:3]
	v_mfma_f32_16x16x32_bf16 v[52:55], v[164:167], v[180:183], v[52:55]
	v_mfma_f32_16x16x32_bf16 v[48:51], v[172:175], v[180:183], v[48:51]
	v_mfma_f32_16x16x32_bf16 v[36:39], v[164:167], v[188:191], v[36:39]
	v_mfma_f32_16x16x32_bf16 v[32:35], v[172:175], v[188:191], v[32:35]
	v_mfma_f32_16x16x32_bf16 v[20:23], v[164:167], v[196:199], v[20:23]
	v_mfma_f32_16x16x32_bf16 v[16:19], v[172:175], v[196:199], v[16:19]
	v_mfma_f32_16x16x32_bf16 v[4:7], v[164:167], v[204:207], v[4:7]
	v_mfma_f32_16x16x32_bf16 v[0:3], v[172:175], v[204:207], v[0:3]
	s_barrier
	s_add_i32 s57, s57, 2
	s_add_u32 s38, s38, 0x100
	s_addc_u32 s39, s39, 0
	s_add_u32 s55, s55, 0x100
	s_addc_u32 s56, s56, 0
	s_cmp_gt_u32 s57, 13
	s_cbranch_scc0 .LBB0_1694

; #define G_STAGE(bufoff, gbase, voff) do { _Pragma("unroll") for (int _i = 0; _i < 2; ++_i) \
;         __builtin_amdgcn_global_load_lds((const unsigned*)((const char*)(gbase) + voff[_i]), (LAS unsigned*)(lds + (bufoff) + ldsw + _i * 8192), 16, 0, 0); } while (0)
; #define G_LDA(dst, b, h) do { _Pragma("unroll") for (int m = 0; m < 4; ++m) _Pragma("unroll") for (int k = 0; k < 2; ++k) dst[m][k] = *(const LAS bf16x8*)(lds + G_SA(b, h) + aoff + m * 2048 + k * 1024); } while (0)
; #define G_MMA(ai, bj, At_, Bt_) do { __builtin_amdgcn_s_setprio(1); _Pragma("unroll") for (int m = 0; m < 4; ++m) _Pragma("unroll") for (int n = 0; n < 2; ++n) _Pragma("unroll") for (int k = 0; k < 2; ++k) \
;         acc[ai][bj][m][n] = __builtin_amdgcn_mfma_f32_16x16x32_bf16(Bt_[n][k], At_[m][k], acc[ai][bj][m][n], 0, 0, 0); __builtin_amdgcn_s_setprio(0); } while (0)
; #define WAIT_V(n) asm volatile("s_waitcnt vmcnt(" #n ")" ::: "memory")
; #define WAIT_L(n) asm volatile("s_waitcnt lgkmcnt(" #n ")" ::: "memory")
; #define BAR __builtin_amdgcn_s_barrier()
; #define SCHED __builtin_amdgcn_sched_barrier(0)
; template <class Get, class Epi>
; DI void gemm_loop(int ntiles, int ld, char* shm, const Get& get, const Epi& epi) {
;     ...
;             WAIT_V(8); WAIT_L(0); BAR; G_MMA(0, 0, At, B0); G_MMA(0, 1, At, B1); BAR; SCHED;
;             G_LDA(At, 0, 1); G_STAGE(G_SB(0, 0), b2, voffB); G_STAGE(G_SB(0, 1), b2 + hstep, voffB); G_STAGE(G_SA(0, 0), a2, voffA);
;             WAIT_V(8); WAIT_L(0); BAR; G_MMA(1, 0, At, B0); G_MMA(1, 1, At, B1); BAR; SCHED;
;     ...
;         G_ZERO;
.Lrj_1781_0:
	s_waitcnt lgkmcnt(0)
	s_barrier
	s_waitcnt lgkmcnt(0)
	v_mfma_f32_16x16x32_bf16 v[124:127], v[128:131], v[180:183], 0
	v_mfma_f32_16x16x32_bf16 v[120:123], v[136:139], v[180:183], 0
	v_mfma_f32_16x16x32_bf16 v[116:119], v[128:131], v[188:191], 0
	v_mfma_f32_16x16x32_bf16 v[112:115], v[136:139], v[188:191], 0
	v_mfma_f32_16x16x32_bf16 v[108:111], v[128:131], v[196:199], 0
	v_mfma_f32_16x16x32_bf16 v[104:107], v[136:139], v[196:199], 0
	v_mfma_f32_16x16x32_bf16 v[100:103], v[128:131], v[204:207], 0
	v_mfma_f32_16x16x32_bf16 v[96:99], v[136:139], v[204:207], 0
	v_mfma_f32_16x16x32_bf16 v[124:127], v[132:135], v[184:187], v[124:127]
	v_mfma_f32_16x16x32_bf16 v[120:123], v[140:143], v[184:187], v[120:123]
	v_mfma_f32_16x16x32_bf16 v[116:119], v[132:135], v[192:195], v[116:119]
	v_mfma_f32_16x16x32_bf16 v[112:115], v[140:143], v[192:195], v[112:115]
	v_mfma_f32_16x16x32_bf16 v[108:111], v[132:135], v[200:203], v[108:111]
	v_mfma_f32_16x16x32_bf16 v[104:107], v[140:143], v[200:203], v[104:107]
	v_mfma_f32_16x16x32_bf16 v[100:103], v[132:135], v[208:211], v[100:103]
	v_mfma_f32_16x16x32_bf16 v[96:99], v[140:143], v[208:211], v[96:99]
	v_mfma_f32_16x16x32_bf16 v[60:63], v[158:161], v[180:183], 0
	v_mfma_f32_16x16x32_bf16 v[56:59], v[172:175], v[180:183], 0
	v_mfma_f32_16x16x32_bf16 v[52:55], v[158:161], v[188:191], 0
	v_mfma_f32_16x16x32_bf16 v[48:51], v[172:175], v[188:191], 0
	v_mfma_f32_16x16x32_bf16 v[44:47], v[158:161], v[196:199], 0
	v_mfma_f32_16x16x32_bf16 v[40:43], v[172:175], v[196:199], 0
	v_mfma_f32_16x16x32_bf16 v[36:39], v[158:161], v[204:207], 0
	v_mfma_f32_16x16x32_bf16 v[32:35], v[172:175], v[204:207], 0
	v_mfma_f32_16x16x32_bf16 v[60:63], v[162:165], v[184:187], v[60:63]
	v_mfma_f32_16x16x32_bf16 v[56:59], v[176:179], v[184:187], v[56:59]
	v_mfma_f32_16x16x32_bf16 v[52:55], v[162:165], v[192:195], v[52:55]
	v_mfma_f32_16x16x32_bf16 v[48:51], v[176:179], v[192:195], v[48:51]
	v_mfma_f32_16x16x32_bf16 v[44:47], v[162:165], v[200:203], v[44:47]
	v_mfma_f32_16x16x32_bf16 v[40:43], v[176:179], v[200:203], v[40:43]
	v_mfma_f32_16x16x32_bf16 v[36:39], v[162:165], v[208:211], v[36:39]
	v_mfma_f32_16x16x32_bf16 v[32:35], v[176:179], v[208:211], v[32:35]
	s_barrier
	s_add_i32 s4, s53, s44
	v_lshl_add_u64 v[144:145], s[40:41], 0, v[148:149]
	s_mov_b32 m0, s4
	ds_read_b128 v[180:183], v171 offset:16384
	ds_read_b128 v[184:187], v171 offset:17408
	ds_read_b128 v[188:191], v171 offset:18432
	ds_read_b128 v[192:195], v171 offset:19456
	ds_read_b128 v[196:199], v171 offset:20480
	ds_read_b128 v[200:203], v171 offset:21504
	ds_read_b128 v[204:207], v171 offset:22528
	ds_read_b128 v[208:211], v171 offset:23552
	global_load_lds_dwordx4 v[144:145], off
	s_add_i32 m0, s4, 0x2000
	s_add_u32 s4, s40, 0xb0000
	v_lshl_add_u64 v[166:167], s[40:41], 0, v[152:153]
	s_addc_u32 s5, s41, 0
	s_add_i32 s78, s54, s44
	global_load_lds_dwordx4 v[166:167], off
	v_lshl_add_u64 v[212:213], s[4:5], 0, v[148:149]
	s_mov_b32 m0, s78
	v_lshl_add_u64 v[214:215], s[42:43], 0, v[150:151]
	global_load_lds_dwordx4 v[212:213], off
	v_lshl_add_u64 v[212:213], s[4:5], 0, v[152:153]
	s_add_i32 m0, s78, 0x2000
	s_nop 0
	global_load_lds_dwordx4 v[212:213], off
	v_lshl_add_u64 v[212:213], s[42:43], 0, v[146:147]
	s_mov_b32 m0, s45
	s_nop 0
	global_load_lds_dwordx4 v[212:213], off
	s_mov_b32 m0, s46
	s_nop 0
	global_load_lds_dwordx4 v[214:215], off
	s_cmp_lg_u32 s100, 0
	s_cbranch_scc0 .Lrf_1781_1
	s_waitcnt vmcnt(16)
	s_branch .Lrj_1781_1

; #define G_STAGE(bufoff, gbase, voff) do { _Pragma("unroll") for (int _i = 0; _i < 2; ++_i) \
;         __builtin_amdgcn_global_load_lds((const unsigned*)((const char*)(gbase) + voff[_i]), (LAS unsigned*)(lds + (bufoff) + ldsw + _i * 8192), 16, 0, 0); } while (0)
; #define G_LDA(dst, b, h) do { _Pragma("unroll") for (int m = 0; m < 4; ++m) _Pragma("unroll") for (int k = 0; k < 2; ++k) dst[m][k] = *(const LAS bf16x8*)(lds + G_SA(b, h) + aoff + m * 2048 + k * 1024); } while (0)
; #define G_LDB(dst, b, h) do { _Pragma("unroll") for (int n = 0; n < 2; ++n) _Pragma("unroll") for (int k = 0; k < 2; ++k) dst[n][k] = *(const LAS bf16x8*)(lds + G_SB(b, h) + boff + n * 2048 + k * 1024); } while (0)
; #define G_MMA(ai, bj, At_, Bt_) do { __builtin_amdgcn_s_setprio(1); _Pragma("unroll") for (int m = 0; m < 4; ++m) _Pragma("unroll") for (int n = 0; n < 2; ++n) _Pragma("unroll") for (int k = 0; k < 2; ++k) \
;         acc[ai][bj][m][n] = __builtin_amdgcn_mfma_f32_16x16x32_bf16(Bt_[n][k], At_[m][k], acc[ai][bj][m][n], 0, 0, 0); __builtin_amdgcn_s_setprio(0); } while (0)
; #define WAIT_V(n) asm volatile("s_waitcnt vmcnt(" #n ")" ::: "memory")
; #define WAIT_L(n) asm volatile("s_waitcnt lgkmcnt(" #n ")" ::: "memory")
; #define BAR __builtin_amdgcn_s_barrier()
; #define SCHED __builtin_amdgcn_sched_barrier(0)
; template <class Get, class Epi>
; DI void gemm_loop(int ntiles, int ld, char* shm, const Get& get, const Epi& epi) {
;     ...
;             G_LDB(B0, 0, 0); G_LDB(B1, 0, 1); SCHED; G_LDA(At, 0, 0); G_STAGE(G_SA(1, 1), a1 + hstep, voffA);
;             WAIT_V(8); WAIT_L(0); BAR; G_MMA(0, 0, At, B0); G_MMA(0, 1, At, B1); BAR; SCHED;
;             G_LDA(At, 0, 1); G_STAGE(G_SB(0, 0), b2, voffB); G_STAGE(G_SB(0, 1), b2 + hstep, voffB); G_STAGE(G_SA(0, 0), a2, voffA);
;             WAIT_V(8); WAIT_L(0); BAR; G_MMA(1, 0, At, B0); G_MMA(1, 1, At, B1); BAR; SCHED;
;             G_LDB(B0, 1, 0); G_LDB(B1, 1, 1); SCHED; G_LDA(At, 1, 0); G_STAGE(G_SA(0, 1), a2 + hstep, voffA);
;             WAIT_V(8); WAIT_L(0); BAR; G_MMA(0, 0, At, B0); G_MMA(0, 1, At, B1); BAR; SCHED;
;             G_LDA(At, 1, 1); G_STAGE(G_SB(1, 0), b3, voffB); G_STAGE(G_SB(1, 1), b3 + hstep, voffB); G_STAGE(G_SA(1, 0), a3, voffA);
;             WAIT_V(8); WAIT_L(0); BAR; G_MMA(1, 0, At, B0); G_MMA(1, 1, At, B1); BAR; SCHED;
.Lrj_1781_1:
	s_waitcnt lgkmcnt(0)
	s_barrier
	s_waitcnt lgkmcnt(0)
	v_mfma_f32_16x16x32_bf16 v[92:95], v[128:131], v[180:183], 0
	v_mfma_f32_16x16x32_bf16 v[88:91], v[136:139], v[180:183], 0
	v_mfma_f32_16x16x32_bf16 v[84:87], v[128:131], v[188:191], 0
	v_mfma_f32_16x16x32_bf16 v[80:83], v[136:139], v[188:191], 0
	v_mfma_f32_16x16x32_bf16 v[76:79], v[128:131], v[196:199], 0
	v_mfma_f32_16x16x32_bf16 v[72:75], v[136:139], v[196:199], 0
	v_mfma_f32_16x16x32_bf16 v[68:71], v[128:131], v[204:207], 0
	v_mfma_f32_16x16x32_bf16 v[64:67], v[136:139], v[204:207], 0
	v_mfma_f32_16x16x32_bf16 v[92:95], v[132:135], v[184:187], v[92:95]
	v_mfma_f32_16x16x32_bf16 v[88:91], v[140:143], v[184:187], v[88:91]
	v_mfma_f32_16x16x32_bf16 v[84:87], v[132:135], v[192:195], v[84:87]
	v_mfma_f32_16x16x32_bf16 v[80:83], v[140:143], v[192:195], v[80:83]
	v_mfma_f32_16x16x32_bf16 v[76:79], v[132:135], v[200:203], v[76:79]
	v_mfma_f32_16x16x32_bf16 v[72:75], v[140:143], v[200:203], v[72:75]
	v_mfma_f32_16x16x32_bf16 v[68:71], v[132:135], v[208:211], v[68:71]
	v_mfma_f32_16x16x32_bf16 v[64:67], v[140:143], v[208:211], v[64:67]
	v_mfma_f32_16x16x32_bf16 v[28:31], v[158:161], v[180:183], 0
	v_mfma_f32_16x16x32_bf16 v[24:27], v[172:175], v[180:183], 0
	v_mfma_f32_16x16x32_bf16 v[20:23], v[158:161], v[188:191], 0
	v_mfma_f32_16x16x32_bf16 v[16:19], v[172:175], v[188:191], 0
	v_mfma_f32_16x16x32_bf16 v[12:15], v[158:161], v[196:199], 0
	v_mfma_f32_16x16x32_bf16 v[8:11], v[172:175], v[196:199], 0
	v_mfma_f32_16x16x32_bf16 v[4:7], v[158:161], v[204:207], 0
	v_mfma_f32_16x16x32_bf16 v[0:3], v[172:175], v[204:207], 0
	v_mfma_f32_16x16x32_bf16 v[28:31], v[162:165], v[184:187], v[28:31]
	v_mfma_f32_16x16x32_bf16 v[24:27], v[176:179], v[184:187], v[24:27]
	v_mfma_f32_16x16x32_bf16 v[20:23], v[162:165], v[192:195], v[20:23]
	v_mfma_f32_16x16x32_bf16 v[16:19], v[176:179], v[192:195], v[16:19]
	v_mfma_f32_16x16x32_bf16 v[12:15], v[162:165], v[200:203], v[12:15]
	v_mfma_f32_16x16x32_bf16 v[8:11], v[176:179], v[200:203], v[8:11]
	v_mfma_f32_16x16x32_bf16 v[4:7], v[162:165], v[208:211], v[4:7]
	v_mfma_f32_16x16x32_bf16 v[0:3], v[176:179], v[208:211], v[0:3]
	s_barrier
	s_add_i32 s78, 0, 0x18000
	s_add_i32 s79, 0, 0x1c000
	v_add_u32_e32 v140, s78, v168
	v_add_u32_e32 v176, s79, v168
	ds_read_b128 v[128:131], v140
	ds_read_b128 v[132:135], v140 offset:1024
	ds_read_b128 v[136:139], v140 offset:2048
	ds_read_b128 v[140:143], v140 offset:3072
	ds_read_b128 v[158:161], v176
	ds_read_b128 v[162:165], v176 offset:1024
	ds_read_b128 v[172:175], v176 offset:2048
	ds_read_b128 v[176:179], v176 offset:3072
	s_add_u32 s4, s42, 0xb0000
	s_addc_u32 s5, s43, 0
	s_mov_b32 m0, s47
	v_lshl_add_u64 v[216:217], s[4:5], 0, v[146:147]
	ds_read_b128 v[180:183], v171 offset:32768
	ds_read_b128 v[184:187], v171 offset:33792
	ds_read_b128 v[188:191], v171 offset:34816
	ds_read_b128 v[192:195], v171 offset:35840
	ds_read_b128 v[196:199], v171 offset:36864
	ds_read_b128 v[200:203], v171 offset:37888
	ds_read_b128 v[204:207], v171 offset:38912
	ds_read_b128 v[208:211], v171 offset:39936
	global_load_lds_dwordx4 v[216:217], off
	v_lshl_add_u64 v[216:217], s[4:5], 0, v[150:151]
	s_mov_b32 m0, s48
	s_nop 0
	global_load_lds_dwordx4 v[216:217], off
	s_waitcnt vmcnt(8)
	s_waitcnt lgkmcnt(0)
	s_barrier
	s_waitcnt lgkmcnt(0)
	v_mfma_f32_16x16x32_bf16 v[124:127], v[128:131], v[180:183], v[124:127]
	v_mfma_f32_16x16x32_bf16 v[120:123], v[136:139], v[180:183], v[120:123]
	v_mfma_f32_16x16x32_bf16 v[116:119], v[128:131], v[188:191], v[116:119]
	v_mfma_f32_16x16x32_bf16 v[112:115], v[136:139], v[188:191], v[112:115]
	v_mfma_f32_16x16x32_bf16 v[108:111], v[128:131], v[196:199], v[108:111]
	v_mfma_f32_16x16x32_bf16 v[104:107], v[136:139], v[196:199], v[104:107]
	v_mfma_f32_16x16x32_bf16 v[100:103], v[128:131], v[204:207], v[100:103]
	v_mfma_f32_16x16x32_bf16 v[96:99], v[136:139], v[204:207], v[96:99]
	v_mfma_f32_16x16x32_bf16 v[124:127], v[132:135], v[184:187], v[124:127]
	v_mfma_f32_16x16x32_bf16 v[120:123], v[140:143], v[184:187], v[120:123]
	v_mfma_f32_16x16x32_bf16 v[116:119], v[132:135], v[192:195], v[116:119]
	v_mfma_f32_16x16x32_bf16 v[112:115], v[140:143], v[192:195], v[112:115]
	v_mfma_f32_16x16x32_bf16 v[108:111], v[132:135], v[200:203], v[108:111]
	v_mfma_f32_16x16x32_bf16 v[104:107], v[140:143], v[200:203], v[104:107]
	v_mfma_f32_16x16x32_bf16 v[100:103], v[132:135], v[208:211], v[100:103]
	v_mfma_f32_16x16x32_bf16 v[96:99], v[140:143], v[208:211], v[96:99]
	v_mfma_f32_16x16x32_bf16 v[60:63], v[158:161], v[180:183], v[60:63]
	v_mfma_f32_16x16x32_bf16 v[56:59], v[172:175], v[180:183], v[56:59]
	v_mfma_f32_16x16x32_bf16 v[52:55], v[158:161], v[188:191], v[52:55]
	v_mfma_f32_16x16x32_bf16 v[48:51], v[172:175], v[188:191], v[48:51]
	v_mfma_f32_16x16x32_bf16 v[44:47], v[158:161], v[196:199], v[44:47]
	v_mfma_f32_16x16x32_bf16 v[40:43], v[172:175], v[196:199], v[40:43]
	v_mfma_f32_16x16x32_bf16 v[36:39], v[158:161], v[204:207], v[36:39]
	v_mfma_f32_16x16x32_bf16 v[32:35], v[172:175], v[204:207], v[32:35]
	v_mfma_f32_16x16x32_bf16 v[60:63], v[162:165], v[184:187], v[60:63]
	v_mfma_f32_16x16x32_bf16 v[56:59], v[176:179], v[184:187], v[56:59]
	v_mfma_f32_16x16x32_bf16 v[52:55], v[162:165], v[192:195], v[52:55]
	v_mfma_f32_16x16x32_bf16 v[48:51], v[176:179], v[192:195], v[48:51]
	v_mfma_f32_16x16x32_bf16 v[44:47], v[162:165], v[200:203], v[44:47]
	v_mfma_f32_16x16x32_bf16 v[40:43], v[176:179], v[200:203], v[40:43]
	v_mfma_f32_16x16x32_bf16 v[36:39], v[162:165], v[208:211], v[36:39]
	v_mfma_f32_16x16x32_bf16 v[32:35], v[176:179], v[208:211], v[32:35]
	s_barrier
; #define G_STAGE(bufoff, gbase, voff) do { _Pragma("unroll") for (int _i = 0; _i < 2; ++_i) \
;         __builtin_amdgcn_global_load_lds((const unsigned*)((const char*)(gbase) + voff[_i]), (LAS unsigned*)(lds + (bufoff) + ldsw + _i * 8192), 16, 0, 0); } while (0)
; #define G_LDA(dst, b, h) do { _Pragma("unroll") for (int m = 0; m < 4; ++m) _Pragma("unroll") for (int k = 0; k < 2; ++k) dst[m][k] = *(const LAS bf16x8*)(lds + G_SA(b, h) + aoff + m * 2048 + k * 1024); } while (0)
; #define G_LDB(dst, b, h) do { _Pragma("unroll") for (int n = 0; n < 2; ++n) _Pragma("unroll") for (int k = 0; k < 2; ++k) dst[n][k] = *(const LAS bf16x8*)(lds + G_SB(b, h) + boff + n * 2048 + k * 1024); } while (0)
; #define WAIT_V(n) asm volatile("s_waitcnt vmcnt(" #n ")" ::: "memory")
; #define WAIT_L(n) asm volatile("s_waitcnt lgkmcnt(" #n ")" ::: "memory")
; #define BAR __builtin_amdgcn_s_barrier()
; #define SCHED __builtin_amdgcn_sched_barrier(0)
; template <class Get, class Epi>
; DI void gemm_loop(int ntiles, int ld, char* shm, const Get& get, const Epi& epi) {
;     ...
;         for (int t = 0; t < nt; t += 2) {
;             const bool last = (t == nt - 2);
;             const char* a1 = cA + (size_t)(t + 1) * kstep;
;             const char* a2 = last ? nA : cA + (size_t)(t + 2) * kstep; const char* b2 = last ? nB : cB + (size_t)(t + 2) * kstep;
;             const char* a3 = a2 + kstep; const char* b3 = b2 + kstep;
;             G_LDB(B0, 0, 0); G_LDB(B1, 0, 1); SCHED; G_LDA(At, 0, 0); G_STAGE(G_SA(1, 1), a1 + hstep, voffA);
;             WAIT_V(8); WAIT_L(0); BAR; G_MMA(0, 0, At, B0); G_MMA(0, 1, At, B1); BAR; SCHED;
;             G_LDA(At, 0, 1); G_STAGE(G_SB(0, 0), b2, voffB); G_STAGE(G_SB(0, 1), b2 + hstep, voffB); G_STAGE(G_SA(0, 0), a2, voffA);
;             WAIT_V(8); WAIT_L(0); BAR; G_MMA(1, 0, At, B0); G_MMA(1, 1, At, B1); BAR; SCHED;
;             G_LDB(B0, 1, 0); G_LDB(B1, 1, 1); SCHED; G_LDA(At, 1, 0); G_STAGE(G_SA(0, 1), a2 + hstep, voffA);
;             WAIT_V(8); WAIT_L(0); BAR; G_MMA(0, 0, At, B0); G_MMA(0, 1, At, B1); BAR; SCHED;
;             G_LDA(At, 1, 1); G_STAGE(G_SB(1, 0), b3, voffB); G_STAGE(G_SB(1, 1), b3 + hstep, voffB); G_STAGE(G_SA(1, 0), a3, voffA);
;             WAIT_V(8); WAIT_L(0); BAR; G_MMA(1, 0, At, B0); G_MMA(1, 1, At, B1); BAR; SCHED;
	s_add_i32 s4, s78, s44
	v_lshl_add_u64 v[144:145], v[144:145], 0, s[10:11]
	s_mov_b32 m0, s4
	ds_read_b128 v[180:183], v171 offset:49152
	ds_read_b128 v[184:187], v171 offset:50176
	ds_read_b128 v[188:191], v171 offset:51200
	ds_read_b128 v[192:195], v171 offset:52224
	ds_read_b128 v[196:199], v171 offset:53248
	ds_read_b128 v[200:203], v171 offset:54272
	ds_read_b128 v[204:207], v171 offset:55296
	ds_read_b128 v[208:211], v171 offset:56320
	global_load_lds_dwordx4 v[144:145], off
	s_add_i32 m0, s4, 0x2000
	s_add_u32 s4, s40, 0xb0080
	v_lshl_add_u64 v[144:145], v[166:167], 0, s[10:11]
	s_addc_u32 s5, s41, 0
	s_add_i32 s40, s79, s44
	global_load_lds_dwordx4 v[144:145], off
	v_lshl_add_u64 v[144:145], s[4:5], 0, v[148:149]
	s_mov_b32 m0, s40
	s_nop 0
	global_load_lds_dwordx4 v[144:145], off
	v_lshl_add_u64 v[144:145], s[4:5], 0, v[152:153]
	s_add_i32 m0, s40, 0x2000
	s_nop 0
	global_load_lds_dwordx4 v[144:145], off
	v_lshl_add_u64 v[144:145], v[212:213], 0, s[10:11]
	s_mov_b32 m0, s51
	s_nop 0
	global_load_lds_dwordx4 v[144:145], off
	v_lshl_add_u64 v[144:145], v[214:215], 0, s[10:11]
	s_mov_b32 m0, s52
	s_nop 0
	global_load_lds_dwordx4 v[144:145], off
	s_waitcnt vmcnt(8)
	s_waitcnt lgkmcnt(0)
	s_barrier
	s_waitcnt lgkmcnt(0)
	v_mfma_f32_16x16x32_bf16 v[92:95], v[128:131], v[180:183], v[92:95]
	v_mfma_f32_16x16x32_bf16 v[88:91], v[136:139], v[180:183], v[88:91]
	v_mfma_f32_16x16x32_bf16 v[84:87], v[128:131], v[188:191], v[84:87]
	v_mfma_f32_16x16x32_bf16 v[80:83], v[136:139], v[188:191], v[80:83]
	v_mfma_f32_16x16x32_bf16 v[76:79], v[128:131], v[196:199], v[76:79]
	v_mfma_f32_16x16x32_bf16 v[72:75], v[136:139], v[196:199], v[72:75]
	v_mfma_f32_16x16x32_bf16 v[68:71], v[128:131], v[204:207], v[68:71]
	v_mfma_f32_16x16x32_bf16 v[64:67], v[136:139], v[204:207], v[64:67]
	v_mfma_f32_16x16x32_bf16 v[92:95], v[132:135], v[184:187], v[92:95]
	v_mfma_f32_16x16x32_bf16 v[88:91], v[140:143], v[184:187], v[88:91]
	v_mfma_f32_16x16x32_bf16 v[84:87], v[132:135], v[192:195], v[84:87]
	v_mfma_f32_16x16x32_bf16 v[80:83], v[140:143], v[192:195], v[80:83]
	v_mfma_f32_16x16x32_bf16 v[76:79], v[132:135], v[200:203], v[76:79]
	v_mfma_f32_16x16x32_bf16 v[72:75], v[140:143], v[200:203], v[72:75]
	v_mfma_f32_16x16x32_bf16 v[68:71], v[132:135], v[208:211], v[68:71]
	v_mfma_f32_16x16x32_bf16 v[64:67], v[140:143], v[208:211], v[64:67]
	v_mfma_f32_16x16x32_bf16 v[28:31], v[158:161], v[180:183], v[28:31]
	v_mfma_f32_16x16x32_bf16 v[24:27], v[172:175], v[180:183], v[24:27]
	v_mfma_f32_16x16x32_bf16 v[20:23], v[158:161], v[188:191], v[20:23]
	v_mfma_f32_16x16x32_bf16 v[16:19], v[172:175], v[188:191], v[16:19]
	v_mfma_f32_16x16x32_bf16 v[12:15], v[158:161], v[196:199], v[12:15]
	v_mfma_f32_16x16x32_bf16 v[8:11], v[172:175], v[196:199], v[8:11]
	v_mfma_f32_16x16x32_bf16 v[4:7], v[158:161], v[204:207], v[4:7]
	v_mfma_f32_16x16x32_bf16 v[0:3], v[172:175], v[204:207], v[0:3]
	v_mfma_f32_16x16x32_bf16 v[28:31], v[162:165], v[184:187], v[28:31]
	v_mfma_f32_16x16x32_bf16 v[24:27], v[176:179], v[184:187], v[24:27]
	v_mfma_f32_16x16x32_bf16 v[20:23], v[162:165], v[192:195], v[20:23]
	v_mfma_f32_16x16x32_bf16 v[16:19], v[176:179], v[192:195], v[16:19]
	v_mfma_f32_16x16x32_bf16 v[12:15], v[162:165], v[200:203], v[12:15]
	v_mfma_f32_16x16x32_bf16 v[8:11], v[176:179], v[200:203], v[8:11]
	v_mfma_f32_16x16x32_bf16 v[4:7], v[162:165], v[208:211], v[4:7]
	v_mfma_f32_16x16x32_bf16 v[0:3], v[176:179], v[208:211], v[0:3]
	s_barrier
	s_add_u32 s75, s75, 0x100
	s_addc_u32 s76, s76, 0
	s_cmp_ge_u32 s77, s73
	s_mov_b64 s[4:5], s[14:15]
	s_mov_b32 s40, s77
	s_cbranch_scc0 .LBB0_1781
	s_branch .Lpost_1781
.LBB0_1781:
	ds_read_b128 v[128:131], v169
	ds_read_b128 v[132:135], v169 offset:1024
	ds_read_b128 v[136:139], v169 offset:2048
	ds_read_b128 v[140:143], v169 offset:3072
	ds_read_b128 v[158:161], v170
	ds_read_b128 v[162:165], v170 offset:1024
	ds_read_b128 v[172:175], v170 offset:2048
	ds_read_b128 v[176:179], v170 offset:3072
	s_add_i32 s77, s40, 2
	s_add_u32 s14, s4, 0x100
	s_addc_u32 s15, s5, 0
	s_cmp_eq_u32 s74, s40
	s_cselect_b32 s40, s38, s75
	s_cselect_b32 s43, s37, s15
	s_cselect_b32 s42, s36, s14
	s_cselect_b32 s41, s39, s76
	v_lshl_add_u64 v[144:145], s[4:5], 0, v[154:155]
	s_add_i32 m0, s45, 0xc000
	ds_read_b128 v[180:183], v171
	ds_read_b128 v[184:187], v171 offset:1024
	ds_read_b128 v[188:191], v171 offset:2048
	ds_read_b128 v[192:195], v171 offset:3072
	ds_read_b128 v[196:199], v171 offset:4096
	ds_read_b128 v[200:203], v171 offset:5120
	ds_read_b128 v[204:207], v171 offset:6144
	ds_read_b128 v[208:211], v171 offset:7168
	global_load_lds_dwordx4 v[144:145], off
	v_lshl_add_u64 v[144:145], s[4:5], 0, v[156:157]
	s_add_i32 m0, s45, 0xe000
	s_nop 0
	global_load_lds_dwordx4 v[144:145], off
	s_waitcnt vmcnt(8)
	s_waitcnt lgkmcnt(0)
	s_barrier
; #define G_STAGE(bufoff, gbase, voff) do { _Pragma("unroll") for (int _i = 0; _i < 2; ++_i) \
;         __builtin_amdgcn_global_load_lds((const unsigned*)((const char*)(gbase) + voff[_i]), (LAS unsigned*)(lds + (bufoff) + ldsw + _i * 8192), 16, 0, 0); } while (0)
; #define G_LDA(dst, b, h) do { _Pragma("unroll") for (int m = 0; m < 4; ++m) _Pragma("unroll") for (int k = 0; k < 2; ++k) dst[m][k] = *(const LAS bf16x8*)(lds + G_SA(b, h) + aoff + m * 2048 + k * 1024); } while (0)
; #define G_LDB(dst, b, h) do { _Pragma("unroll") for (int n = 0; n < 2; ++n) _Pragma("unroll") for (int k = 0; k < 2; ++k) dst[n][k] = *(const LAS bf16x8*)(lds + G_SB(b, h) + boff + n * 2048 + k * 1024); } while (0)
; #define G_MMA(ai, bj, At_, Bt_) do { __builtin_amdgcn_s_setprio(1); _Pragma("unroll") for (int m = 0; m < 4; ++m) _Pragma("unroll") for (int n = 0; n < 2; ++n) _Pragma("unroll") for (int k = 0; k < 2; ++k) \
;         acc[ai][bj][m][n] = __builtin_amdgcn_mfma_f32_16x16x32_bf16(Bt_[n][k], At_[m][k], acc[ai][bj][m][n], 0, 0, 0); __builtin_amdgcn_s_setprio(0); } while (0)
; #define WAIT_V(n) asm volatile("s_waitcnt vmcnt(" #n ")" ::: "memory")
; #define WAIT_L(n) asm volatile("s_waitcnt lgkmcnt(" #n ")" ::: "memory")
; #define BAR __builtin_amdgcn_s_barrier()
; #define SCHED __builtin_amdgcn_sched_barrier(0)
; template <class Get, class Epi>
; DI void gemm_loop(int ntiles, int ld, char* shm, const Get& get, const Epi& epi) {
;     ...
;             G_LDB(B0, 0, 0); G_LDB(B1, 0, 1); SCHED; G_LDA(At, 0, 0); G_STAGE(G_SA(1, 1), a1 + hstep, voffA);
;             WAIT_V(8); WAIT_L(0); BAR; G_MMA(0, 0, At, B0); G_MMA(0, 1, At, B1); BAR; SCHED;
;             G_LDA(At, 0, 1); G_STAGE(G_SB(0, 0), b2, voffB); G_STAGE(G_SB(0, 1), b2 + hstep, voffB); G_STAGE(G_SA(0, 0), a2, voffA);
;             WAIT_V(8); WAIT_L(0); BAR; G_MMA(1, 0, At, B0); G_MMA(1, 1, At, B1); BAR; SCHED;
	s_waitcnt lgkmcnt(0)
	v_mfma_f32_16x16x32_bf16 v[124:127], v[128:131], v[180:183], v[124:127]
	v_mfma_f32_16x16x32_bf16 v[120:123], v[136:139], v[180:183], v[120:123]
	v_mfma_f32_16x16x32_bf16 v[116:119], v[128:131], v[188:191], v[116:119]
	v_mfma_f32_16x16x32_bf16 v[112:115], v[136:139], v[188:191], v[112:115]
	v_mfma_f32_16x16x32_bf16 v[108:111], v[128:131], v[196:199], v[108:111]
	v_mfma_f32_16x16x32_bf16 v[104:107], v[136:139], v[196:199], v[104:107]
	v_mfma_f32_16x16x32_bf16 v[100:103], v[128:131], v[204:207], v[100:103]
	v_mfma_f32_16x16x32_bf16 v[96:99], v[136:139], v[204:207], v[96:99]
	v_mfma_f32_16x16x32_bf16 v[124:127], v[132:135], v[184:187], v[124:127]
	v_mfma_f32_16x16x32_bf16 v[120:123], v[140:143], v[184:187], v[120:123]
	v_mfma_f32_16x16x32_bf16 v[116:119], v[132:135], v[192:195], v[116:119]
	v_mfma_f32_16x16x32_bf16 v[112:115], v[140:143], v[192:195], v[112:115]
	v_mfma_f32_16x16x32_bf16 v[108:111], v[132:135], v[200:203], v[108:111]
	v_mfma_f32_16x16x32_bf16 v[104:107], v[140:143], v[200:203], v[104:107]
	v_mfma_f32_16x16x32_bf16 v[100:103], v[132:135], v[208:211], v[100:103]
	v_mfma_f32_16x16x32_bf16 v[96:99], v[140:143], v[208:211], v[96:99]
	v_mfma_f32_16x16x32_bf16 v[60:63], v[158:161], v[180:183], v[60:63]
	v_mfma_f32_16x16x32_bf16 v[56:59], v[172:175], v[180:183], v[56:59]
	v_mfma_f32_16x16x32_bf16 v[52:55], v[158:161], v[188:191], v[52:55]
	v_mfma_f32_16x16x32_bf16 v[48:51], v[172:175], v[188:191], v[48:51]
	v_mfma_f32_16x16x32_bf16 v[44:47], v[158:161], v[196:199], v[44:47]
	v_mfma_f32_16x16x32_bf16 v[40:43], v[172:175], v[196:199], v[40:43]
	v_mfma_f32_16x16x32_bf16 v[36:39], v[158:161], v[204:207], v[36:39]
	v_mfma_f32_16x16x32_bf16 v[32:35], v[172:175], v[204:207], v[32:35]
	v_mfma_f32_16x16x32_bf16 v[60:63], v[162:165], v[184:187], v[60:63]
	v_mfma_f32_16x16x32_bf16 v[56:59], v[176:179], v[184:187], v[56:59]
	v_mfma_f32_16x16x32_bf16 v[52:55], v[162:165], v[192:195], v[52:55]
	v_mfma_f32_16x16x32_bf16 v[48:51], v[176:179], v[192:195], v[48:51]
	v_mfma_f32_16x16x32_bf16 v[44:47], v[162:165], v[200:203], v[44:47]
	v_mfma_f32_16x16x32_bf16 v[40:43], v[176:179], v[200:203], v[40:43]
	v_mfma_f32_16x16x32_bf16 v[36:39], v[162:165], v[208:211], v[36:39]
	v_mfma_f32_16x16x32_bf16 v[32:35], v[176:179], v[208:211], v[32:35]
	s_barrier
	s_add_i32 s4, s53, s44
	v_lshl_add_u64 v[144:145], s[40:41], 0, v[148:149]
	s_mov_b32 m0, s4
	ds_read_b128 v[180:183], v171 offset:16384
	ds_read_b128 v[184:187], v171 offset:17408
	ds_read_b128 v[188:191], v171 offset:18432
	ds_read_b128 v[192:195], v171 offset:19456
	ds_read_b128 v[196:199], v171 offset:20480
	ds_read_b128 v[200:203], v171 offset:21504
	ds_read_b128 v[204:207], v171 offset:22528
	ds_read_b128 v[208:211], v171 offset:23552
	global_load_lds_dwordx4 v[144:145], off
	s_add_i32 m0, s4, 0x2000
	s_add_u32 s4, s40, 0xb0000
	v_lshl_add_u64 v[166:167], s[40:41], 0, v[152:153]
	s_addc_u32 s5, s41, 0
	s_add_i32 s78, s54, s44
	global_load_lds_dwordx4 v[166:167], off
	v_lshl_add_u64 v[212:213], s[4:5], 0, v[148:149]
	s_mov_b32 m0, s78
	v_lshl_add_u64 v[214:215], s[42:43], 0, v[150:151]
	global_load_lds_dwordx4 v[212:213], off
	v_lshl_add_u64 v[212:213], s[4:5], 0, v[152:153]
	s_add_i32 m0, s78, 0x2000
	s_nop 0
	global_load_lds_dwordx4 v[212:213], off
	v_lshl_add_u64 v[212:213], s[42:43], 0, v[146:147]
	s_mov_b32 m0, s45
	s_nop 0
	global_load_lds_dwordx4 v[212:213], off
	s_mov_b32 m0, s46
	s_nop 0
	global_load_lds_dwordx4 v[214:215], off
	s_waitcnt vmcnt(8)
	s_waitcnt lgkmcnt(0)
	s_barrier
	s_waitcnt lgkmcnt(0)
	v_mfma_f32_16x16x32_bf16 v[92:95], v[128:131], v[180:183], v[92:95]
	v_mfma_f32_16x16x32_bf16 v[88:91], v[136:139], v[180:183], v[88:91]
	v_mfma_f32_16x16x32_bf16 v[84:87], v[128:131], v[188:191], v[84:87]
	v_mfma_f32_16x16x32_bf16 v[80:83], v[136:139], v[188:191], v[80:83]
	v_mfma_f32_16x16x32_bf16 v[76:79], v[128:131], v[196:199], v[76:79]
	v_mfma_f32_16x16x32_bf16 v[72:75], v[136:139], v[196:199], v[72:75]
	v_mfma_f32_16x16x32_bf16 v[68:71], v[128:131], v[204:207], v[68:71]
	v_mfma_f32_16x16x32_bf16 v[64:67], v[136:139], v[204:207], v[64:67]
	v_mfma_f32_16x16x32_bf16 v[92:95], v[132:135], v[184:187], v[92:95]
	v_mfma_f32_16x16x32_bf16 v[88:91], v[140:143], v[184:187], v[88:91]
	v_mfma_f32_16x16x32_bf16 v[84:87], v[132:135], v[192:195], v[84:87]
	v_mfma_f32_16x16x32_bf16 v[80:83], v[140:143], v[192:195], v[80:83]
	v_mfma_f32_16x16x32_bf16 v[76:79], v[132:135], v[200:203], v[76:79]
	v_mfma_f32_16x16x32_bf16 v[72:75], v[140:143], v[200:203], v[72:75]
	v_mfma_f32_16x16x32_bf16 v[68:71], v[132:135], v[208:211], v[68:71]
	v_mfma_f32_16x16x32_bf16 v[64:67], v[140:143], v[208:211], v[64:67]
	v_mfma_f32_16x16x32_bf16 v[28:31], v[158:161], v[180:183], v[28:31]
	v_mfma_f32_16x16x32_bf16 v[24:27], v[172:175], v[180:183], v[24:27]
	v_mfma_f32_16x16x32_bf16 v[20:23], v[158:161], v[188:191], v[20:23]
	v_mfma_f32_16x16x32_bf16 v[16:19], v[172:175], v[188:191], v[16:19]
	v_mfma_f32_16x16x32_bf16 v[12:15], v[158:161], v[196:199], v[12:15]
	v_mfma_f32_16x16x32_bf16 v[8:11], v[172:175], v[196:199], v[8:11]
	v_mfma_f32_16x16x32_bf16 v[4:7], v[158:161], v[204:207], v[4:7]
	v_mfma_f32_16x16x32_bf16 v[0:3], v[172:175], v[204:207], v[0:3]
	v_mfma_f32_16x16x32_bf16 v[28:31], v[162:165], v[184:187], v[28:31]
	v_mfma_f32_16x16x32_bf16 v[24:27], v[176:179], v[184:187], v[24:27]
	v_mfma_f32_16x16x32_bf16 v[20:23], v[162:165], v[192:195], v[20:23]
	v_mfma_f32_16x16x32_bf16 v[16:19], v[176:179], v[192:195], v[16:19]
	v_mfma_f32_16x16x32_bf16 v[12:15], v[162:165], v[200:203], v[12:15]
	v_mfma_f32_16x16x32_bf16 v[8:11], v[176:179], v[200:203], v[8:11]
	v_mfma_f32_16x16x32_bf16 v[4:7], v[162:165], v[208:211], v[4:7]
	v_mfma_f32_16x16x32_bf16 v[0:3], v[176:179], v[208:211], v[0:3]
	s_barrier
; #define G_STAGE(bufoff, gbase, voff) do { _Pragma("unroll") for (int _i = 0; _i < 2; ++_i) \
;         __builtin_amdgcn_global_load_lds((const unsigned*)((const char*)(gbase) + voff[_i]), (LAS unsigned*)(lds + (bufoff) + ldsw + _i * 8192), 16, 0, 0); } while (0)
; #define G_LDA(dst, b, h) do { _Pragma("unroll") for (int m = 0; m < 4; ++m) _Pragma("unroll") for (int k = 0; k < 2; ++k) dst[m][k] = *(const LAS bf16x8*)(lds + G_SA(b, h) + aoff + m * 2048 + k * 1024); } while (0)
; #define G_LDB(dst, b, h) do { _Pragma("unroll") for (int n = 0; n < 2; ++n) _Pragma("unroll") for (int k = 0; k < 2; ++k) dst[n][k] = *(const LAS bf16x8*)(lds + G_SB(b, h) + boff + n * 2048 + k * 1024); } while (0)
; #define G_MMA(ai, bj, At_, Bt_) do { __builtin_amdgcn_s_setprio(1); _Pragma("unroll") for (int m = 0; m < 4; ++m) _Pragma("unroll") for (int n = 0; n < 2; ++n) _Pragma("unroll") for (int k = 0; k < 2; ++k) \
;         acc[ai][bj][m][n] = __builtin_amdgcn_mfma_f32_16x16x32_bf16(Bt_[n][k], At_[m][k], acc[ai][bj][m][n], 0, 0, 0); __builtin_amdgcn_s_setprio(0); } while (0)
; #define WAIT_V(n) asm volatile("s_waitcnt vmcnt(" #n ")" ::: "memory")
; #define WAIT_L(n) asm volatile("s_waitcnt lgkmcnt(" #n ")" ::: "memory")
; #define BAR __builtin_amdgcn_s_barrier()
; #define SCHED __builtin_amdgcn_sched_barrier(0)
; template <class Get, class Epi>
; DI void gemm_loop(int ntiles, int ld, char* shm, const Get& get, const Epi& epi) {
;     ...
;             G_LDB(B0, 1, 0); G_LDB(B1, 1, 1); SCHED; G_LDA(At, 1, 0); G_STAGE(G_SA(0, 1), a2 + hstep, voffA);
;             WAIT_V(8); WAIT_L(0); BAR; G_MMA(0, 0, At, B0); G_MMA(0, 1, At, B1); BAR; SCHED;
;             G_LDA(At, 1, 1); G_STAGE(G_SB(1, 0), b3, voffB); G_STAGE(G_SB(1, 1), b3 + hstep, voffB); G_STAGE(G_SA(1, 0), a3, voffA);
;             WAIT_V(8); WAIT_L(0); BAR; G_MMA(1, 0, At, B0); G_MMA(1, 1, At, B1); BAR; SCHED;
	s_add_i32 s78, 0, 0x18000
	s_add_i32 s79, 0, 0x1c000
	v_add_u32_e32 v140, s78, v168
	v_add_u32_e32 v176, s79, v168
	ds_read_b128 v[128:131], v140
	ds_read_b128 v[132:135], v140 offset:1024
	ds_read_b128 v[136:139], v140 offset:2048
	ds_read_b128 v[140:143], v140 offset:3072
	ds_read_b128 v[158:161], v176
	ds_read_b128 v[162:165], v176 offset:1024
	ds_read_b128 v[172:175], v176 offset:2048
	ds_read_b128 v[176:179], v176 offset:3072
	s_add_u32 s4, s42, 0xb0000
	s_addc_u32 s5, s43, 0
	s_mov_b32 m0, s47
	v_lshl_add_u64 v[216:217], s[4:5], 0, v[146:147]
	ds_read_b128 v[180:183], v171 offset:32768
	ds_read_b128 v[184:187], v171 offset:33792
	ds_read_b128 v[188:191], v171 offset:34816
	ds_read_b128 v[192:195], v171 offset:35840
	ds_read_b128 v[196:199], v171 offset:36864
	ds_read_b128 v[200:203], v171 offset:37888
	ds_read_b128 v[204:207], v171 offset:38912
	ds_read_b128 v[208:211], v171 offset:39936
	global_load_lds_dwordx4 v[216:217], off
	v_lshl_add_u64 v[216:217], s[4:5], 0, v[150:151]
	s_mov_b32 m0, s48
	s_nop 0
	global_load_lds_dwordx4 v[216:217], off
	s_waitcnt vmcnt(8)
	s_waitcnt lgkmcnt(0)
	s_barrier
	s_waitcnt lgkmcnt(0)
	v_mfma_f32_16x16x32_bf16 v[124:127], v[128:131], v[180:183], v[124:127]
	v_mfma_f32_16x16x32_bf16 v[120:123], v[136:139], v[180:183], v[120:123]
	v_mfma_f32_16x16x32_bf16 v[116:119], v[128:131], v[188:191], v[116:119]
	v_mfma_f32_16x16x32_bf16 v[112:115], v[136:139], v[188:191], v[112:115]
	v_mfma_f32_16x16x32_bf16 v[108:111], v[128:131], v[196:199], v[108:111]
	v_mfma_f32_16x16x32_bf16 v[104:107], v[136:139], v[196:199], v[104:107]
	v_mfma_f32_16x16x32_bf16 v[100:103], v[128:131], v[204:207], v[100:103]
	v_mfma_f32_16x16x32_bf16 v[96:99], v[136:139], v[204:207], v[96:99]
	v_mfma_f32_16x16x32_bf16 v[124:127], v[132:135], v[184:187], v[124:127]
	v_mfma_f32_16x16x32_bf16 v[120:123], v[140:143], v[184:187], v[120:123]
	v_mfma_f32_16x16x32_bf16 v[116:119], v[132:135], v[192:195], v[116:119]
	v_mfma_f32_16x16x32_bf16 v[112:115], v[140:143], v[192:195], v[112:115]
	v_mfma_f32_16x16x32_bf16 v[108:111], v[132:135], v[200:203], v[108:111]
	v_mfma_f32_16x16x32_bf16 v[104:107], v[140:143], v[200:203], v[104:107]
	v_mfma_f32_16x16x32_bf16 v[100:103], v[132:135], v[208:211], v[100:103]
	v_mfma_f32_16x16x32_bf16 v[96:99], v[140:143], v[208:211], v[96:99]
	v_mfma_f32_16x16x32_bf16 v[60:63], v[158:161], v[180:183], v[60:63]
	v_mfma_f32_16x16x32_bf16 v[56:59], v[172:175], v[180:183], v[56:59]
	v_mfma_f32_16x16x32_bf16 v[52:55], v[158:161], v[188:191], v[52:55]
	v_mfma_f32_16x16x32_bf16 v[48:51], v[172:175], v[188:191], v[48:51]
	v_mfma_f32_16x16x32_bf16 v[44:47], v[158:161], v[196:199], v[44:47]
	v_mfma_f32_16x16x32_bf16 v[40:43], v[172:175], v[196:199], v[40:43]
	v_mfma_f32_16x16x32_bf16 v[36:39], v[158:161], v[204:207], v[36:39]
	v_mfma_f32_16x16x32_bf16 v[32:35], v[172:175], v[204:207], v[32:35]
	v_mfma_f32_16x16x32_bf16 v[60:63], v[162:165], v[184:187], v[60:63]
	v_mfma_f32_16x16x32_bf16 v[56:59], v[176:179], v[184:187], v[56:59]
	v_mfma_f32_16x16x32_bf16 v[52:55], v[162:165], v[192:195], v[52:55]
	v_mfma_f32_16x16x32_bf16 v[48:51], v[176:179], v[192:195], v[48:51]
	v_mfma_f32_16x16x32_bf16 v[44:47], v[162:165], v[200:203], v[44:47]
	v_mfma_f32_16x16x32_bf16 v[40:43], v[176:179], v[200:203], v[40:43]
	v_mfma_f32_16x16x32_bf16 v[36:39], v[162:165], v[208:211], v[36:39]
	v_mfma_f32_16x16x32_bf16 v[32:35], v[176:179], v[208:211], v[32:35]
	s_barrier
	s_add_i32 s4, s78, s44
	v_lshl_add_u64 v[144:145], v[144:145], 0, s[10:11]
	s_mov_b32 m0, s4
	ds_read_b128 v[180:183], v171 offset:49152
	ds_read_b128 v[184:187], v171 offset:50176
	ds_read_b128 v[188:191], v171 offset:51200
	ds_read_b128 v[192:195], v171 offset:52224
	ds_read_b128 v[196:199], v171 offset:53248
	ds_read_b128 v[200:203], v171 offset:54272
	ds_read_b128 v[204:207], v171 offset:55296
	ds_read_b128 v[208:211], v171 offset:56320
	global_load_lds_dwordx4 v[144:145], off
	s_add_i32 m0, s4, 0x2000
	s_add_u32 s4, s40, 0xb0080
	v_lshl_add_u64 v[144:145], v[166:167], 0, s[10:11]
	s_addc_u32 s5, s41, 0
	s_add_i32 s40, s79, s44
	global_load_lds_dwordx4 v[144:145], off
	v_lshl_add_u64 v[144:145], s[4:5], 0, v[148:149]
	s_mov_b32 m0, s40
	s_nop 0
	global_load_lds_dwordx4 v[144:145], off
	v_lshl_add_u64 v[144:145], s[4:5], 0, v[152:153]
	s_add_i32 m0, s40, 0x2000
	s_nop 0
	global_load_lds_dwordx4 v[144:145], off
	v_lshl_add_u64 v[144:145], v[212:213], 0, s[10:11]
	s_mov_b32 m0, s51
	s_nop 0
	global_load_lds_dwordx4 v[144:145], off
	v_lshl_add_u64 v[144:145], v[214:215], 0, s[10:11]
	s_mov_b32 m0, s52
	s_nop 0
	global_load_lds_dwordx4 v[144:145], off
	s_waitcnt vmcnt(8)
	s_waitcnt lgkmcnt(0)
	s_barrier
	s_waitcnt lgkmcnt(0)
	v_mfma_f32_16x16x32_bf16 v[92:95], v[128:131], v[180:183], v[92:95]
	v_mfma_f32_16x16x32_bf16 v[88:91], v[136:139], v[180:183], v[88:91]
	v_mfma_f32_16x16x32_bf16 v[84:87], v[128:131], v[188:191], v[84:87]
	v_mfma_f32_16x16x32_bf16 v[80:83], v[136:139], v[188:191], v[80:83]
	v_mfma_f32_16x16x32_bf16 v[76:79], v[128:131], v[196:199], v[76:79]
	v_mfma_f32_16x16x32_bf16 v[72:75], v[136:139], v[196:199], v[72:75]
	v_mfma_f32_16x16x32_bf16 v[68:71], v[128:131], v[204:207], v[68:71]
	v_mfma_f32_16x16x32_bf16 v[64:67], v[136:139], v[204:207], v[64:67]
	v_mfma_f32_16x16x32_bf16 v[92:95], v[132:135], v[184:187], v[92:95]
	v_mfma_f32_16x16x32_bf16 v[88:91], v[140:143], v[184:187], v[88:91]
	v_mfma_f32_16x16x32_bf16 v[84:87], v[132:135], v[192:195], v[84:87]
	v_mfma_f32_16x16x32_bf16 v[80:83], v[140:143], v[192:195], v[80:83]
	v_mfma_f32_16x16x32_bf16 v[76:79], v[132:135], v[200:203], v[76:79]
	v_mfma_f32_16x16x32_bf16 v[72:75], v[140:143], v[200:203], v[72:75]
	v_mfma_f32_16x16x32_bf16 v[68:71], v[132:135], v[208:211], v[68:71]
	v_mfma_f32_16x16x32_bf16 v[64:67], v[140:143], v[208:211], v[64:67]
	v_mfma_f32_16x16x32_bf16 v[28:31], v[158:161], v[180:183], v[28:31]
	v_mfma_f32_16x16x32_bf16 v[24:27], v[172:175], v[180:183], v[24:27]
	v_mfma_f32_16x16x32_bf16 v[20:23], v[158:161], v[188:191], v[20:23]
	v_mfma_f32_16x16x32_bf16 v[16:19], v[172:175], v[188:191], v[16:19]
	v_mfma_f32_16x16x32_bf16 v[12:15], v[158:161], v[196:199], v[12:15]
	v_mfma_f32_16x16x32_bf16 v[8:11], v[172:175], v[196:199], v[8:11]
	v_mfma_f32_16x16x32_bf16 v[4:7], v[158:161], v[204:207], v[4:7]
	v_mfma_f32_16x16x32_bf16 v[0:3], v[172:175], v[204:207], v[0:3]
	v_mfma_f32_16x16x32_bf16 v[28:31], v[162:165], v[184:187], v[28:31]
	v_mfma_f32_16x16x32_bf16 v[24:27], v[176:179], v[184:187], v[24:27]
	v_mfma_f32_16x16x32_bf16 v[20:23], v[162:165], v[192:195], v[20:23]
	v_mfma_f32_16x16x32_bf16 v[16:19], v[176:179], v[192:195], v[16:19]
	v_mfma_f32_16x16x32_bf16 v[12:15], v[162:165], v[200:203], v[12:15]
	v_mfma_f32_16x16x32_bf16 v[8:11], v[176:179], v[200:203], v[8:11]
	v_mfma_f32_16x16x32_bf16 v[4:7], v[162:165], v[208:211], v[4:7]
	v_mfma_f32_16x16x32_bf16 v[0:3], v[176:179], v[208:211], v[0:3]
	s_barrier
	s_add_u32 s75, s75, 0x100
	s_addc_u32 s76, s76, 0
	s_cmp_ge_u32 s77, s73
	s_mov_b64 s[4:5], s[14:15]
	s_mov_b32 s40, s77
	s_cbranch_scc0 .LBB0_1781

; #define G_STAGE(bufoff, gbase, voff) do { _Pragma("unroll") for (int _i = 0; _i < 2; ++_i) \
;         __builtin_amdgcn_global_load_lds((const unsigned*)((const char*)(gbase) + voff[_i]), (LAS unsigned*)(lds + (bufoff) + ldsw + _i * 8192), 16, 0, 0); } while (0)
; #define G_LDA(dst, b, h) do { _Pragma("unroll") for (int m = 0; m < 4; ++m) _Pragma("unroll") for (int k = 0; k < 2; ++k) dst[m][k] = *(const LAS bf16x8*)(lds + G_SA(b, h) + aoff + m * 2048 + k * 1024); } while (0)
; #define G_LDB(dst, b, h) do { _Pragma("unroll") for (int n = 0; n < 2; ++n) _Pragma("unroll") for (int k = 0; k < 2; ++k) dst[n][k] = *(const LAS bf16x8*)(lds + G_SB(b, h) + boff + n * 2048 + k * 1024); } while (0)
; #define G_MMA(ai, bj, At_, Bt_) do { __builtin_amdgcn_s_setprio(1); _Pragma("unroll") for (int m = 0; m < 4; ++m) _Pragma("unroll") for (int n = 0; n < 2; ++n) _Pragma("unroll") for (int k = 0; k < 2; ++k) \
;         acc[ai][bj][m][n] = __builtin_amdgcn_mfma_f32_16x16x32_bf16(Bt_[n][k], At_[m][k], acc[ai][bj][m][n], 0, 0, 0); __builtin_amdgcn_s_setprio(0); } while (0)
; #define WAIT_V(n) asm volatile("s_waitcnt vmcnt(" #n ")" ::: "memory")
; #define WAIT_L(n) asm volatile("s_waitcnt lgkmcnt(" #n ")" ::: "memory")
; #define BAR __builtin_amdgcn_s_barrier()
; #define SCHED __builtin_amdgcn_sched_barrier(0)
; template <class Get, class Epi>
; DI void gemm_loop(int ntiles, int ld, char* shm, const Get& get, const Epi& epi) {
;     ...
;             G_LDB(B0, 0, 0); G_LDB(B1, 0, 1); SCHED; G_LDA(At, 0, 0); G_STAGE(G_SA(1, 1), a1 + hstep, voffA);
;             WAIT_V(8); WAIT_L(0); BAR; G_MMA(0, 0, At, B0); G_MMA(0, 1, At, B1); BAR; SCHED;
;             G_LDA(At, 0, 1); G_STAGE(G_SB(0, 0), b2, voffB); G_STAGE(G_SB(0, 1), b2 + hstep, voffB); G_STAGE(G_SA(0, 0), a2, voffA);
.Lrj_2022_0:
	s_waitcnt lgkmcnt(0)
	s_barrier
	s_waitcnt lgkmcnt(0)
	v_mfma_f32_16x16x32_bf16 v[132:135], v[96:99], v[184:187], 0
	v_mfma_f32_16x16x32_bf16 v[124:127], v[150:153], v[184:187], 0
	v_mfma_f32_16x16x32_bf16 v[128:131], v[96:99], v[192:195], 0
	v_mfma_f32_16x16x32_bf16 v[120:123], v[150:153], v[192:195], 0
	v_mfma_f32_16x16x32_bf16 v[116:119], v[96:99], v[200:203], 0
	v_mfma_f32_16x16x32_bf16 v[104:107], v[150:153], v[200:203], 0
	v_mfma_f32_16x16x32_bf16 v[112:115], v[96:99], v[208:211], 0
	v_mfma_f32_16x16x32_bf16 v[100:103], v[150:153], v[208:211], 0
	v_mfma_f32_16x16x32_bf16 v[132:135], v[108:111], v[188:191], v[132:135]
	v_mfma_f32_16x16x32_bf16 v[124:127], v[154:157], v[188:191], v[124:127]
	v_mfma_f32_16x16x32_bf16 v[128:131], v[108:111], v[196:199], v[128:131]
	v_mfma_f32_16x16x32_bf16 v[120:123], v[154:157], v[196:199], v[120:123]
	v_mfma_f32_16x16x32_bf16 v[116:119], v[108:111], v[204:207], v[116:119]
	v_mfma_f32_16x16x32_bf16 v[104:107], v[154:157], v[204:207], v[104:107]
	v_mfma_f32_16x16x32_bf16 v[112:115], v[108:111], v[212:215], v[112:115]
	v_mfma_f32_16x16x32_bf16 v[100:103], v[154:157], v[212:215], v[100:103]
	v_mfma_f32_16x16x32_bf16 v[60:63], v[158:161], v[184:187], 0
	v_mfma_f32_16x16x32_bf16 v[52:55], v[166:169], v[184:187], 0
	v_mfma_f32_16x16x32_bf16 v[56:59], v[158:161], v[192:195], 0
	v_mfma_f32_16x16x32_bf16 v[48:51], v[166:169], v[192:195], 0
	v_mfma_f32_16x16x32_bf16 v[44:47], v[158:161], v[200:203], 0
	v_mfma_f32_16x16x32_bf16 v[36:39], v[166:169], v[200:203], 0
	v_mfma_f32_16x16x32_bf16 v[40:43], v[158:161], v[208:211], 0
	v_mfma_f32_16x16x32_bf16 v[32:35], v[166:169], v[208:211], 0
	v_mfma_f32_16x16x32_bf16 v[60:63], v[162:165], v[188:191], v[60:63]
	v_mfma_f32_16x16x32_bf16 v[52:55], v[180:183], v[188:191], v[52:55]
	v_mfma_f32_16x16x32_bf16 v[56:59], v[162:165], v[196:199], v[56:59]
	v_mfma_f32_16x16x32_bf16 v[48:51], v[180:183], v[196:199], v[48:51]
	v_mfma_f32_16x16x32_bf16 v[44:47], v[162:165], v[204:207], v[44:47]
	v_mfma_f32_16x16x32_bf16 v[36:39], v[180:183], v[204:207], v[36:39]
	v_mfma_f32_16x16x32_bf16 v[40:43], v[162:165], v[212:215], v[40:43]
	v_mfma_f32_16x16x32_bf16 v[32:35], v[180:183], v[212:215], v[32:35]
	s_barrier
	s_add_i32 s57, s75, s46
	v_lshl_add_u64 v[170:171], s[6:7], 0, v[140:141]
	s_mov_b32 m0, s57
	ds_read_b128 v[184:187], v175 offset:16384
	ds_read_b128 v[188:191], v175 offset:17408
	ds_read_b128 v[192:195], v175 offset:18432
	ds_read_b128 v[196:199], v175 offset:19456
	ds_read_b128 v[200:203], v175 offset:20480
	ds_read_b128 v[204:207], v175 offset:21504
	ds_read_b128 v[208:211], v175 offset:22528
	ds_read_b128 v[212:215], v175 offset:23552
	global_load_lds_dwordx4 v[170:171], off
	s_add_i32 m0, s57, 0x2000
	s_add_u32 s58, s6, 0x40000
	v_lshl_add_u64 v[216:217], s[6:7], 0, v[136:137]
	s_addc_u32 s59, s7, 0
	s_add_i32 s57, s76, s46
	global_load_lds_dwordx4 v[216:217], off
	v_lshl_add_u64 v[218:219], s[58:59], 0, v[140:141]
	s_mov_b32 m0, s57
	v_lshl_add_u64 v[220:221], s[14:15], 0, v[138:139]
	global_load_lds_dwordx4 v[218:219], off
	v_lshl_add_u64 v[218:219], s[58:59], 0, v[136:137]
	s_add_i32 m0, s57, 0x2000
	s_nop 0
	global_load_lds_dwordx4 v[218:219], off
	v_lshl_add_u64 v[218:219], s[14:15], 0, v[142:143]
	s_mov_b32 m0, s50
	s_nop 0
	global_load_lds_dwordx4 v[218:219], off
	s_mov_b32 m0, s51
	s_nop 0
	global_load_lds_dwordx4 v[220:221], off
	s_cmp_lg_u32 s100, 0
	s_cbranch_scc0 .Lrf_2022_1
	s_waitcnt vmcnt(16)
	s_branch .Lrj_2022_1

; #define G_STAGE(bufoff, gbase, voff) do { _Pragma("unroll") for (int _i = 0; _i < 2; ++_i) \
;         __builtin_amdgcn_global_load_lds((const unsigned*)((const char*)(gbase) + voff[_i]), (LAS unsigned*)(lds + (bufoff) + ldsw + _i * 8192), 16, 0, 0); } while (0)
; #define G_LDA(dst, b, h) do { _Pragma("unroll") for (int m = 0; m < 4; ++m) _Pragma("unroll") for (int k = 0; k < 2; ++k) dst[m][k] = *(const LAS bf16x8*)(lds + G_SA(b, h) + aoff + m * 2048 + k * 1024); } while (0)
; #define G_LDB(dst, b, h) do { _Pragma("unroll") for (int n = 0; n < 2; ++n) _Pragma("unroll") for (int k = 0; k < 2; ++k) dst[n][k] = *(const LAS bf16x8*)(lds + G_SB(b, h) + boff + n * 2048 + k * 1024); } while (0)
; #define G_MMA(ai, bj, At_, Bt_) do { __builtin_amdgcn_s_setprio(1); _Pragma("unroll") for (int m = 0; m < 4; ++m) _Pragma("unroll") for (int n = 0; n < 2; ++n) _Pragma("unroll") for (int k = 0; k < 2; ++k) \
;         acc[ai][bj][m][n] = __builtin_amdgcn_mfma_f32_16x16x32_bf16(Bt_[n][k], At_[m][k], acc[ai][bj][m][n], 0, 0, 0); __builtin_amdgcn_s_setprio(0); } while (0)
; #define WAIT_V(n) asm volatile("s_waitcnt vmcnt(" #n ")" ::: "memory")
; #define WAIT_L(n) asm volatile("s_waitcnt lgkmcnt(" #n ")" ::: "memory")
; #define BAR __builtin_amdgcn_s_barrier()
; #define SCHED __builtin_amdgcn_sched_barrier(0)
; template <class Get, class Epi>
; DI void gemm_loop(int ntiles, int ld, char* shm, const Get& get, const Epi& epi) {
;     ...
;             WAIT_V(8); WAIT_L(0); BAR; G_MMA(1, 0, At, B0); G_MMA(1, 1, At, B1); BAR; SCHED;
;             G_LDB(B0, 1, 0); G_LDB(B1, 1, 1); SCHED; G_LDA(At, 1, 0); G_STAGE(G_SA(0, 1), a2 + hstep, voffA);
;             WAIT_V(8); WAIT_L(0); BAR; G_MMA(0, 0, At, B0); G_MMA(0, 1, At, B1); BAR; SCHED;
;             G_LDA(At, 1, 1); G_STAGE(G_SB(1, 0), b3, voffB); G_STAGE(G_SB(1, 1), b3 + hstep, voffB); G_STAGE(G_SA(1, 0), a3, voffA);
;             WAIT_V(8); WAIT_L(0); BAR; G_MMA(1, 0, At, B0); G_MMA(1, 1, At, B1); BAR; SCHED;
.Lrj_2022_1:
	s_waitcnt lgkmcnt(0)
	s_barrier
	s_waitcnt lgkmcnt(0)
	v_mfma_f32_16x16x32_bf16 v[92:95], v[96:99], v[184:187], 0
	v_mfma_f32_16x16x32_bf16 v[84:87], v[150:153], v[184:187], 0
	v_mfma_f32_16x16x32_bf16 v[88:91], v[96:99], v[192:195], 0
	v_mfma_f32_16x16x32_bf16 v[80:83], v[150:153], v[192:195], 0
	v_mfma_f32_16x16x32_bf16 v[76:79], v[96:99], v[200:203], 0
	v_mfma_f32_16x16x32_bf16 v[68:71], v[150:153], v[200:203], 0
	v_mfma_f32_16x16x32_bf16 v[72:75], v[96:99], v[208:211], 0
	v_mfma_f32_16x16x32_bf16 v[64:67], v[150:153], v[208:211], 0
	v_mfma_f32_16x16x32_bf16 v[92:95], v[108:111], v[188:191], v[92:95]
	v_mfma_f32_16x16x32_bf16 v[84:87], v[154:157], v[188:191], v[84:87]
	v_mfma_f32_16x16x32_bf16 v[88:91], v[108:111], v[196:199], v[88:91]
	v_mfma_f32_16x16x32_bf16 v[80:83], v[154:157], v[196:199], v[80:83]
	v_mfma_f32_16x16x32_bf16 v[76:79], v[108:111], v[204:207], v[76:79]
	v_mfma_f32_16x16x32_bf16 v[68:71], v[154:157], v[204:207], v[68:71]
	v_mfma_f32_16x16x32_bf16 v[72:75], v[108:111], v[212:215], v[72:75]
	v_mfma_f32_16x16x32_bf16 v[64:67], v[154:157], v[212:215], v[64:67]
	v_mfma_f32_16x16x32_bf16 v[28:31], v[158:161], v[184:187], 0
	v_mfma_f32_16x16x32_bf16 v[20:23], v[166:169], v[184:187], 0
	v_mfma_f32_16x16x32_bf16 v[24:27], v[158:161], v[192:195], 0
	v_mfma_f32_16x16x32_bf16 v[16:19], v[166:169], v[192:195], 0
	v_mfma_f32_16x16x32_bf16 v[12:15], v[158:161], v[200:203], 0
	v_mfma_f32_16x16x32_bf16 v[4:7], v[166:169], v[200:203], 0
	v_mfma_f32_16x16x32_bf16 v[8:11], v[158:161], v[208:211], 0
	v_mfma_f32_16x16x32_bf16 v[0:3], v[166:169], v[208:211], 0
	v_mfma_f32_16x16x32_bf16 v[28:31], v[162:165], v[188:191], v[28:31]
	v_mfma_f32_16x16x32_bf16 v[20:23], v[180:183], v[188:191], v[20:23]
	v_mfma_f32_16x16x32_bf16 v[24:27], v[162:165], v[196:199], v[24:27]
	v_mfma_f32_16x16x32_bf16 v[16:19], v[180:183], v[196:199], v[16:19]
	v_mfma_f32_16x16x32_bf16 v[12:15], v[162:165], v[204:207], v[12:15]
	v_mfma_f32_16x16x32_bf16 v[4:7], v[180:183], v[204:207], v[4:7]
	v_mfma_f32_16x16x32_bf16 v[8:11], v[162:165], v[212:215], v[8:11]
	v_mfma_f32_16x16x32_bf16 v[0:3], v[180:183], v[212:215], v[0:3]
	s_barrier
	s_add_i32 s57, 0, 0x18000
	v_add_u32_e32 v144, s57, v172
	s_add_i32 s58, 0, 0x1c000
	ds_read_b128 v[96:99], v144
	ds_read_b128 v[108:111], v144 offset:1024
	ds_read_b128 v[150:153], v144 offset:2048
	ds_read_b128 v[154:157], v144 offset:3072
	v_add_u32_e32 v144, s58, v172
	ds_read_b128 v[158:161], v144
	ds_read_b128 v[162:165], v144 offset:1024
	ds_read_b128 v[166:169], v144 offset:2048
	ds_read_b128 v[180:183], v144 offset:3072
	s_add_u32 s14, s14, 0x40000
	s_addc_u32 s15, s15, 0
	s_mov_b32 m0, s71
	v_lshl_add_u64 v[222:223], s[14:15], 0, v[142:143]
	ds_read_b128 v[184:187], v175 offset:32768
	ds_read_b128 v[188:191], v175 offset:33792
	ds_read_b128 v[192:195], v175 offset:34816
	ds_read_b128 v[196:199], v175 offset:35840
	ds_read_b128 v[200:203], v175 offset:36864
	ds_read_b128 v[204:207], v175 offset:37888
	ds_read_b128 v[208:211], v175 offset:38912
	ds_read_b128 v[212:215], v175 offset:39936
	global_load_lds_dwordx4 v[222:223], off
	v_lshl_add_u64 v[222:223], s[14:15], 0, v[138:139]
	s_mov_b32 m0, s72
	s_nop 0
	global_load_lds_dwordx4 v[222:223], off
	s_waitcnt vmcnt(8)
	s_waitcnt lgkmcnt(0)
	s_barrier
	s_waitcnt lgkmcnt(0)
	v_mfma_f32_16x16x32_bf16 v[132:135], v[96:99], v[184:187], v[132:135]
	v_mfma_f32_16x16x32_bf16 v[124:127], v[150:153], v[184:187], v[124:127]
	v_mfma_f32_16x16x32_bf16 v[128:131], v[96:99], v[192:195], v[128:131]
	v_mfma_f32_16x16x32_bf16 v[120:123], v[150:153], v[192:195], v[120:123]
	v_mfma_f32_16x16x32_bf16 v[116:119], v[96:99], v[200:203], v[116:119]
	v_mfma_f32_16x16x32_bf16 v[104:107], v[150:153], v[200:203], v[104:107]
	v_mfma_f32_16x16x32_bf16 v[112:115], v[96:99], v[208:211], v[112:115]
	v_mfma_f32_16x16x32_bf16 v[100:103], v[150:153], v[208:211], v[100:103]
	v_mfma_f32_16x16x32_bf16 v[132:135], v[108:111], v[188:191], v[132:135]
	v_mfma_f32_16x16x32_bf16 v[124:127], v[154:157], v[188:191], v[124:127]
	v_mfma_f32_16x16x32_bf16 v[128:131], v[108:111], v[196:199], v[128:131]
	v_mfma_f32_16x16x32_bf16 v[120:123], v[154:157], v[196:199], v[120:123]
	v_mfma_f32_16x16x32_bf16 v[116:119], v[108:111], v[204:207], v[116:119]
	v_mfma_f32_16x16x32_bf16 v[104:107], v[154:157], v[204:207], v[104:107]
	v_mfma_f32_16x16x32_bf16 v[112:115], v[108:111], v[212:215], v[112:115]
	v_mfma_f32_16x16x32_bf16 v[100:103], v[154:157], v[212:215], v[100:103]
	v_mfma_f32_16x16x32_bf16 v[60:63], v[158:161], v[184:187], v[60:63]
	v_mfma_f32_16x16x32_bf16 v[52:55], v[166:169], v[184:187], v[52:55]
	v_mfma_f32_16x16x32_bf16 v[56:59], v[158:161], v[192:195], v[56:59]
	v_mfma_f32_16x16x32_bf16 v[48:51], v[166:169], v[192:195], v[48:51]
	v_mfma_f32_16x16x32_bf16 v[44:47], v[158:161], v[200:203], v[44:47]
	v_mfma_f32_16x16x32_bf16 v[36:39], v[166:169], v[200:203], v[36:39]
	v_mfma_f32_16x16x32_bf16 v[40:43], v[158:161], v[208:211], v[40:43]
	v_mfma_f32_16x16x32_bf16 v[32:35], v[166:169], v[208:211], v[32:35]
	v_mfma_f32_16x16x32_bf16 v[60:63], v[162:165], v[188:191], v[60:63]
	v_mfma_f32_16x16x32_bf16 v[52:55], v[180:183], v[188:191], v[52:55]
	v_mfma_f32_16x16x32_bf16 v[56:59], v[162:165], v[196:199], v[56:59]
	v_mfma_f32_16x16x32_bf16 v[48:51], v[180:183], v[196:199], v[48:51]
	v_mfma_f32_16x16x32_bf16 v[44:47], v[162:165], v[204:207], v[44:47]
	v_mfma_f32_16x16x32_bf16 v[36:39], v[180:183], v[204:207], v[36:39]
	v_mfma_f32_16x16x32_bf16 v[40:43], v[162:165], v[212:215], v[40:43]
	v_mfma_f32_16x16x32_bf16 v[32:35], v[180:183], v[212:215], v[32:35]
	s_barrier
; #define G_STAGE(bufoff, gbase, voff) do { _Pragma("unroll") for (int _i = 0; _i < 2; ++_i) \
;         __builtin_amdgcn_global_load_lds((const unsigned*)((const char*)(gbase) + voff[_i]), (LAS unsigned*)(lds + (bufoff) + ldsw + _i * 8192), 16, 0, 0); } while (0)
; #define G_LDA(dst, b, h) do { _Pragma("unroll") for (int m = 0; m < 4; ++m) _Pragma("unroll") for (int k = 0; k < 2; ++k) dst[m][k] = *(const LAS bf16x8*)(lds + G_SA(b, h) + aoff + m * 2048 + k * 1024); } while (0)
; #define G_LDB(dst, b, h) do { _Pragma("unroll") for (int n = 0; n < 2; ++n) _Pragma("unroll") for (int k = 0; k < 2; ++k) dst[n][k] = *(const LAS bf16x8*)(lds + G_SB(b, h) + boff + n * 2048 + k * 1024); } while (0)
; #define WAIT_V(n) asm volatile("s_waitcnt vmcnt(" #n ")" ::: "memory")
; #define WAIT_L(n) asm volatile("s_waitcnt lgkmcnt(" #n ")" ::: "memory")
; #define BAR __builtin_amdgcn_s_barrier()
; #define SCHED __builtin_amdgcn_sched_barrier(0)
; template <class Get, class Epi>
; DI void gemm_loop(int ntiles, int ld, char* shm, const Get& get, const Epi& epi) {
;     ...
;         for (int t = 0; t < nt; t += 2) {
;             const bool last = (t == nt - 2);
;             const char* a1 = cA + (size_t)(t + 1) * kstep;
;             const char* a2 = last ? nA : cA + (size_t)(t + 2) * kstep; const char* b2 = last ? nB : cB + (size_t)(t + 2) * kstep;
;             const char* a3 = a2 + kstep; const char* b3 = b2 + kstep;
;             G_LDB(B0, 0, 0); G_LDB(B1, 0, 1); SCHED; G_LDA(At, 0, 0); G_STAGE(G_SA(1, 1), a1 + hstep, voffA);
;             WAIT_V(8); WAIT_L(0); BAR; G_MMA(0, 0, At, B0); G_MMA(0, 1, At, B1); BAR; SCHED;
;             G_LDA(At, 0, 1); G_STAGE(G_SB(0, 0), b2, voffB); G_STAGE(G_SB(0, 1), b2 + hstep, voffB); G_STAGE(G_SA(0, 0), a2, voffA);
;             WAIT_V(8); WAIT_L(0); BAR; G_MMA(1, 0, At, B0); G_MMA(1, 1, At, B1); BAR; SCHED;
;             G_LDB(B0, 1, 0); G_LDB(B1, 1, 1); SCHED; G_LDA(At, 1, 0); G_STAGE(G_SA(0, 1), a2 + hstep, voffA);
;             WAIT_V(8); WAIT_L(0); BAR; G_MMA(0, 0, At, B0); G_MMA(0, 1, At, B1); BAR; SCHED;
;             G_LDA(At, 1, 1); G_STAGE(G_SB(1, 0), b3, voffB); G_STAGE(G_SB(1, 1), b3 + hstep, voffB); G_STAGE(G_SA(1, 0), a3, voffA);
;             WAIT_V(8); WAIT_L(0); BAR; G_MMA(1, 0, At, B0); G_MMA(1, 1, At, B1); BAR; SCHED;
	s_add_i32 s14, s57, s46
	v_lshl_add_u64 v[170:171], v[170:171], 0, s[10:11]
	s_mov_b32 m0, s14
	ds_read_b128 v[184:187], v175 offset:49152
	ds_read_b128 v[188:191], v175 offset:50176
	ds_read_b128 v[192:195], v175 offset:51200
	ds_read_b128 v[196:199], v175 offset:52224
	ds_read_b128 v[200:203], v175 offset:53248
	ds_read_b128 v[204:207], v175 offset:54272
	ds_read_b128 v[208:211], v175 offset:55296
	ds_read_b128 v[212:215], v175 offset:56320
	global_load_lds_dwordx4 v[170:171], off
	s_add_i32 m0, s14, 0x2000
	s_add_u32 s6, s6, 0x40080
	v_lshl_add_u64 v[170:171], v[216:217], 0, s[10:11]
	s_addc_u32 s7, s7, 0
	s_add_i32 s14, s58, s46
	global_load_lds_dwordx4 v[170:171], off
	v_lshl_add_u64 v[170:171], s[6:7], 0, v[140:141]
	s_mov_b32 m0, s14
	s_nop 0
	global_load_lds_dwordx4 v[170:171], off
	v_lshl_add_u64 v[170:171], s[6:7], 0, v[136:137]
	s_add_i32 m0, s14, 0x2000
	s_nop 0
	global_load_lds_dwordx4 v[170:171], off
	v_lshl_add_u64 v[170:171], v[218:219], 0, s[10:11]
	s_mov_b32 m0, s73
	s_nop 0
	global_load_lds_dwordx4 v[170:171], off
	v_lshl_add_u64 v[170:171], v[220:221], 0, s[10:11]
	s_mov_b32 m0, s74
	s_nop 0
	global_load_lds_dwordx4 v[170:171], off
	s_waitcnt vmcnt(8)
	s_waitcnt lgkmcnt(0)
	s_barrier
	s_waitcnt lgkmcnt(0)
	v_mfma_f32_16x16x32_bf16 v[92:95], v[96:99], v[184:187], v[92:95]
	v_mfma_f32_16x16x32_bf16 v[84:87], v[150:153], v[184:187], v[84:87]
	v_mfma_f32_16x16x32_bf16 v[88:91], v[96:99], v[192:195], v[88:91]
	v_mfma_f32_16x16x32_bf16 v[80:83], v[150:153], v[192:195], v[80:83]
	v_mfma_f32_16x16x32_bf16 v[76:79], v[96:99], v[200:203], v[76:79]
	v_mfma_f32_16x16x32_bf16 v[68:71], v[150:153], v[200:203], v[68:71]
	v_mfma_f32_16x16x32_bf16 v[72:75], v[96:99], v[208:211], v[72:75]
	v_mfma_f32_16x16x32_bf16 v[64:67], v[150:153], v[208:211], v[64:67]
	v_mfma_f32_16x16x32_bf16 v[92:95], v[108:111], v[188:191], v[92:95]
	v_mfma_f32_16x16x32_bf16 v[84:87], v[154:157], v[188:191], v[84:87]
	v_mfma_f32_16x16x32_bf16 v[88:91], v[108:111], v[196:199], v[88:91]
	v_mfma_f32_16x16x32_bf16 v[80:83], v[154:157], v[196:199], v[80:83]
	v_mfma_f32_16x16x32_bf16 v[76:79], v[108:111], v[204:207], v[76:79]
	v_mfma_f32_16x16x32_bf16 v[68:71], v[154:157], v[204:207], v[68:71]
	v_mfma_f32_16x16x32_bf16 v[72:75], v[108:111], v[212:215], v[72:75]
	v_mfma_f32_16x16x32_bf16 v[64:67], v[154:157], v[212:215], v[64:67]
	v_mfma_f32_16x16x32_bf16 v[28:31], v[158:161], v[184:187], v[28:31]
	v_mfma_f32_16x16x32_bf16 v[20:23], v[166:169], v[184:187], v[20:23]
	v_mfma_f32_16x16x32_bf16 v[24:27], v[158:161], v[192:195], v[24:27]
	v_mfma_f32_16x16x32_bf16 v[16:19], v[166:169], v[192:195], v[16:19]
	v_mfma_f32_16x16x32_bf16 v[12:15], v[158:161], v[200:203], v[12:15]
	v_mfma_f32_16x16x32_bf16 v[4:7], v[166:169], v[200:203], v[4:7]
	v_mfma_f32_16x16x32_bf16 v[8:11], v[158:161], v[208:211], v[8:11]
	v_mfma_f32_16x16x32_bf16 v[0:3], v[166:169], v[208:211], v[0:3]
	v_mfma_f32_16x16x32_bf16 v[28:31], v[162:165], v[188:191], v[28:31]
	v_mfma_f32_16x16x32_bf16 v[20:23], v[180:183], v[188:191], v[20:23]
	v_mfma_f32_16x16x32_bf16 v[24:27], v[162:165], v[196:199], v[24:27]
	v_mfma_f32_16x16x32_bf16 v[16:19], v[180:183], v[196:199], v[16:19]
	v_mfma_f32_16x16x32_bf16 v[12:15], v[162:165], v[204:207], v[12:15]
	v_mfma_f32_16x16x32_bf16 v[4:7], v[180:183], v[204:207], v[4:7]
	v_mfma_f32_16x16x32_bf16 v[8:11], v[162:165], v[212:215], v[8:11]
	v_mfma_f32_16x16x32_bf16 v[0:3], v[180:183], v[212:215], v[0:3]
	s_barrier
	s_add_i32 s56, s56, 2
	s_add_u32 s4, s4, 0x100
	s_addc_u32 s5, s5, 0
	s_add_u32 s54, s54, 0x100
	s_addc_u32 s55, s55, 0
	s_cmp_gt_u32 s56, 13
	s_cbranch_scc0 .LBB0_2022
	s_branch .Lpost_2022
.LBB0_2022:
	ds_read_b128 v[96:99], v173
	ds_read_b128 v[108:111], v173 offset:1024
	ds_read_b128 v[150:153], v173 offset:2048
	ds_read_b128 v[154:157], v173 offset:3072
	ds_read_b128 v[158:161], v174
	ds_read_b128 v[162:165], v174 offset:1024
	ds_read_b128 v[166:169], v174 offset:2048
	ds_read_b128 v[180:183], v174 offset:3072
	s_add_u32 s6, s4, 0xfffc0080
	s_addc_u32 s7, s5, -1
	s_cmp_eq_u32 s56, 12
	s_cselect_b32 s15, s3, s7
	s_cselect_b32 s14, s41, s6
	s_cselect_b32 s7, s43, s55
	s_cselect_b32 s6, s53, s54
	v_lshl_add_u64 v[170:171], s[4:5], 0, v[146:147]
	s_add_i32 m0, s50, 0xc000
	ds_read_b128 v[184:187], v175
	ds_read_b128 v[188:191], v175 offset:1024
	ds_read_b128 v[192:195], v175 offset:2048
	ds_read_b128 v[196:199], v175 offset:3072
	ds_read_b128 v[200:203], v175 offset:4096
	ds_read_b128 v[204:207], v175 offset:5120
	ds_read_b128 v[208:211], v175 offset:6144
	ds_read_b128 v[212:215], v175 offset:7168
	global_load_lds_dwordx4 v[170:171], off
	v_lshl_add_u64 v[170:171], s[4:5], 0, v[148:149]
	s_add_i32 m0, s50, 0xe000
	s_nop 0
	global_load_lds_dwordx4 v[170:171], off
	s_waitcnt vmcnt(8)
	s_waitcnt lgkmcnt(0)
	s_barrier
; #define G_STAGE(bufoff, gbase, voff) do { _Pragma("unroll") for (int _i = 0; _i < 2; ++_i) \
;         __builtin_amdgcn_global_load_lds((const unsigned*)((const char*)(gbase) + voff[_i]), (LAS unsigned*)(lds + (bufoff) + ldsw + _i * 8192), 16, 0, 0); } while (0)
; #define G_LDA(dst, b, h) do { _Pragma("unroll") for (int m = 0; m < 4; ++m) _Pragma("unroll") for (int k = 0; k < 2; ++k) dst[m][k] = *(const LAS bf16x8*)(lds + G_SA(b, h) + aoff + m * 2048 + k * 1024); } while (0)
; #define G_LDB(dst, b, h) do { _Pragma("unroll") for (int n = 0; n < 2; ++n) _Pragma("unroll") for (int k = 0; k < 2; ++k) dst[n][k] = *(const LAS bf16x8*)(lds + G_SB(b, h) + boff + n * 2048 + k * 1024); } while (0)
; #define G_MMA(ai, bj, At_, Bt_) do { __builtin_amdgcn_s_setprio(1); _Pragma("unroll") for (int m = 0; m < 4; ++m) _Pragma("unroll") for (int n = 0; n < 2; ++n) _Pragma("unroll") for (int k = 0; k < 2; ++k) \
;         acc[ai][bj][m][n] = __builtin_amdgcn_mfma_f32_16x16x32_bf16(Bt_[n][k], At_[m][k], acc[ai][bj][m][n], 0, 0, 0); __builtin_amdgcn_s_setprio(0); } while (0)
; #define WAIT_V(n) asm volatile("s_waitcnt vmcnt(" #n ")" ::: "memory")
; #define WAIT_L(n) asm volatile("s_waitcnt lgkmcnt(" #n ")" ::: "memory")
; #define BAR __builtin_amdgcn_s_barrier()
; #define SCHED __builtin_amdgcn_sched_barrier(0)
; template <class Get, class Epi>
; DI void gemm_loop(int ntiles, int ld, char* shm, const Get& get, const Epi& epi) {
;     ...
;             G_LDB(B0, 0, 0); G_LDB(B1, 0, 1); SCHED; G_LDA(At, 0, 0); G_STAGE(G_SA(1, 1), a1 + hstep, voffA);
;             WAIT_V(8); WAIT_L(0); BAR; G_MMA(0, 0, At, B0); G_MMA(0, 1, At, B1); BAR; SCHED;
;             G_LDA(At, 0, 1); G_STAGE(G_SB(0, 0), b2, voffB); G_STAGE(G_SB(0, 1), b2 + hstep, voffB); G_STAGE(G_SA(0, 0), a2, voffA);
;             WAIT_V(8); WAIT_L(0); BAR; G_MMA(1, 0, At, B0); G_MMA(1, 1, At, B1); BAR; SCHED;
	s_waitcnt lgkmcnt(0)
	v_mfma_f32_16x16x32_bf16 v[132:135], v[96:99], v[184:187], v[132:135]
	v_mfma_f32_16x16x32_bf16 v[124:127], v[150:153], v[184:187], v[124:127]
	v_mfma_f32_16x16x32_bf16 v[128:131], v[96:99], v[192:195], v[128:131]
	v_mfma_f32_16x16x32_bf16 v[120:123], v[150:153], v[192:195], v[120:123]
	v_mfma_f32_16x16x32_bf16 v[116:119], v[96:99], v[200:203], v[116:119]
	v_mfma_f32_16x16x32_bf16 v[104:107], v[150:153], v[200:203], v[104:107]
	v_mfma_f32_16x16x32_bf16 v[112:115], v[96:99], v[208:211], v[112:115]
	v_mfma_f32_16x16x32_bf16 v[100:103], v[150:153], v[208:211], v[100:103]
	v_mfma_f32_16x16x32_bf16 v[132:135], v[108:111], v[188:191], v[132:135]
	v_mfma_f32_16x16x32_bf16 v[124:127], v[154:157], v[188:191], v[124:127]
	v_mfma_f32_16x16x32_bf16 v[128:131], v[108:111], v[196:199], v[128:131]
	v_mfma_f32_16x16x32_bf16 v[120:123], v[154:157], v[196:199], v[120:123]
	v_mfma_f32_16x16x32_bf16 v[116:119], v[108:111], v[204:207], v[116:119]
	v_mfma_f32_16x16x32_bf16 v[104:107], v[154:157], v[204:207], v[104:107]
	v_mfma_f32_16x16x32_bf16 v[112:115], v[108:111], v[212:215], v[112:115]
	v_mfma_f32_16x16x32_bf16 v[100:103], v[154:157], v[212:215], v[100:103]
	v_mfma_f32_16x16x32_bf16 v[60:63], v[158:161], v[184:187], v[60:63]
	v_mfma_f32_16x16x32_bf16 v[52:55], v[166:169], v[184:187], v[52:55]
	v_mfma_f32_16x16x32_bf16 v[56:59], v[158:161], v[192:195], v[56:59]
	v_mfma_f32_16x16x32_bf16 v[48:51], v[166:169], v[192:195], v[48:51]
	v_mfma_f32_16x16x32_bf16 v[44:47], v[158:161], v[200:203], v[44:47]
	v_mfma_f32_16x16x32_bf16 v[36:39], v[166:169], v[200:203], v[36:39]
	v_mfma_f32_16x16x32_bf16 v[40:43], v[158:161], v[208:211], v[40:43]
	v_mfma_f32_16x16x32_bf16 v[32:35], v[166:169], v[208:211], v[32:35]
	v_mfma_f32_16x16x32_bf16 v[60:63], v[162:165], v[188:191], v[60:63]
	v_mfma_f32_16x16x32_bf16 v[52:55], v[180:183], v[188:191], v[52:55]
	v_mfma_f32_16x16x32_bf16 v[56:59], v[162:165], v[196:199], v[56:59]
	v_mfma_f32_16x16x32_bf16 v[48:51], v[180:183], v[196:199], v[48:51]
	v_mfma_f32_16x16x32_bf16 v[44:47], v[162:165], v[204:207], v[44:47]
	v_mfma_f32_16x16x32_bf16 v[36:39], v[180:183], v[204:207], v[36:39]
	v_mfma_f32_16x16x32_bf16 v[40:43], v[162:165], v[212:215], v[40:43]
	v_mfma_f32_16x16x32_bf16 v[32:35], v[180:183], v[212:215], v[32:35]
	s_barrier
	s_add_i32 s57, s75, s46
	v_lshl_add_u64 v[170:171], s[6:7], 0, v[140:141]
	s_mov_b32 m0, s57
	ds_read_b128 v[184:187], v175 offset:16384
	ds_read_b128 v[188:191], v175 offset:17408
	ds_read_b128 v[192:195], v175 offset:18432
	ds_read_b128 v[196:199], v175 offset:19456
	ds_read_b128 v[200:203], v175 offset:20480
	ds_read_b128 v[204:207], v175 offset:21504
	ds_read_b128 v[208:211], v175 offset:22528
	ds_read_b128 v[212:215], v175 offset:23552
	global_load_lds_dwordx4 v[170:171], off
	s_add_i32 m0, s57, 0x2000
	s_add_u32 s58, s6, 0x40000
	v_lshl_add_u64 v[216:217], s[6:7], 0, v[136:137]
	s_addc_u32 s59, s7, 0
	s_add_i32 s57, s76, s46
	global_load_lds_dwordx4 v[216:217], off
	v_lshl_add_u64 v[218:219], s[58:59], 0, v[140:141]
	s_mov_b32 m0, s57
	v_lshl_add_u64 v[220:221], s[14:15], 0, v[138:139]
	global_load_lds_dwordx4 v[218:219], off
	v_lshl_add_u64 v[218:219], s[58:59], 0, v[136:137]
	s_add_i32 m0, s57, 0x2000
	s_nop 0
	global_load_lds_dwordx4 v[218:219], off
	v_lshl_add_u64 v[218:219], s[14:15], 0, v[142:143]
	s_mov_b32 m0, s50
	s_nop 0
	global_load_lds_dwordx4 v[218:219], off
	s_mov_b32 m0, s51
	s_nop 0
	global_load_lds_dwordx4 v[220:221], off
	s_waitcnt vmcnt(8)
	s_waitcnt lgkmcnt(0)
	s_barrier
	s_waitcnt lgkmcnt(0)
	v_mfma_f32_16x16x32_bf16 v[92:95], v[96:99], v[184:187], v[92:95]
	v_mfma_f32_16x16x32_bf16 v[84:87], v[150:153], v[184:187], v[84:87]
	v_mfma_f32_16x16x32_bf16 v[88:91], v[96:99], v[192:195], v[88:91]
	v_mfma_f32_16x16x32_bf16 v[80:83], v[150:153], v[192:195], v[80:83]
	v_mfma_f32_16x16x32_bf16 v[76:79], v[96:99], v[200:203], v[76:79]
	v_mfma_f32_16x16x32_bf16 v[68:71], v[150:153], v[200:203], v[68:71]
	v_mfma_f32_16x16x32_bf16 v[72:75], v[96:99], v[208:211], v[72:75]
	v_mfma_f32_16x16x32_bf16 v[64:67], v[150:153], v[208:211], v[64:67]
	v_mfma_f32_16x16x32_bf16 v[92:95], v[108:111], v[188:191], v[92:95]
	v_mfma_f32_16x16x32_bf16 v[84:87], v[154:157], v[188:191], v[84:87]
	v_mfma_f32_16x16x32_bf16 v[88:91], v[108:111], v[196:199], v[88:91]
	v_mfma_f32_16x16x32_bf16 v[80:83], v[154:157], v[196:199], v[80:83]
	v_mfma_f32_16x16x32_bf16 v[76:79], v[108:111], v[204:207], v[76:79]
	v_mfma_f32_16x16x32_bf16 v[68:71], v[154:157], v[204:207], v[68:71]
	v_mfma_f32_16x16x32_bf16 v[72:75], v[108:111], v[212:215], v[72:75]
	v_mfma_f32_16x16x32_bf16 v[64:67], v[154:157], v[212:215], v[64:67]
	v_mfma_f32_16x16x32_bf16 v[28:31], v[158:161], v[184:187], v[28:31]
	v_mfma_f32_16x16x32_bf16 v[20:23], v[166:169], v[184:187], v[20:23]
	v_mfma_f32_16x16x32_bf16 v[24:27], v[158:161], v[192:195], v[24:27]
	v_mfma_f32_16x16x32_bf16 v[16:19], v[166:169], v[192:195], v[16:19]
	v_mfma_f32_16x16x32_bf16 v[12:15], v[158:161], v[200:203], v[12:15]
	v_mfma_f32_16x16x32_bf16 v[4:7], v[166:169], v[200:203], v[4:7]
	v_mfma_f32_16x16x32_bf16 v[8:11], v[158:161], v[208:211], v[8:11]
	v_mfma_f32_16x16x32_bf16 v[0:3], v[166:169], v[208:211], v[0:3]
	v_mfma_f32_16x16x32_bf16 v[28:31], v[162:165], v[188:191], v[28:31]
	v_mfma_f32_16x16x32_bf16 v[20:23], v[180:183], v[188:191], v[20:23]
	v_mfma_f32_16x16x32_bf16 v[24:27], v[162:165], v[196:199], v[24:27]
	v_mfma_f32_16x16x32_bf16 v[16:19], v[180:183], v[196:199], v[16:19]
	v_mfma_f32_16x16x32_bf16 v[12:15], v[162:165], v[204:207], v[12:15]
	v_mfma_f32_16x16x32_bf16 v[4:7], v[180:183], v[204:207], v[4:7]
	v_mfma_f32_16x16x32_bf16 v[8:11], v[162:165], v[212:215], v[8:11]
	v_mfma_f32_16x16x32_bf16 v[0:3], v[180:183], v[212:215], v[0:3]
	s_barrier
; #define G_STAGE(bufoff, gbase, voff) do { _Pragma("unroll") for (int _i = 0; _i < 2; ++_i) \
;         __builtin_amdgcn_global_load_lds((const unsigned*)((const char*)(gbase) + voff[_i]), (LAS unsigned*)(lds + (bufoff) + ldsw + _i * 8192), 16, 0, 0); } while (0)
; #define G_LDA(dst, b, h) do { _Pragma("unroll") for (int m = 0; m < 4; ++m) _Pragma("unroll") for (int k = 0; k < 2; ++k) dst[m][k] = *(const LAS bf16x8*)(lds + G_SA(b, h) + aoff + m * 2048 + k * 1024); } while (0)
; #define G_LDB(dst, b, h) do { _Pragma("unroll") for (int n = 0; n < 2; ++n) _Pragma("unroll") for (int k = 0; k < 2; ++k) dst[n][k] = *(const LAS bf16x8*)(lds + G_SB(b, h) + boff + n * 2048 + k * 1024); } while (0)
; #define G_MMA(ai, bj, At_, Bt_) do { __builtin_amdgcn_s_setprio(1); _Pragma("unroll") for (int m = 0; m < 4; ++m) _Pragma("unroll") for (int n = 0; n < 2; ++n) _Pragma("unroll") for (int k = 0; k < 2; ++k) \
;         acc[ai][bj][m][n] = __builtin_amdgcn_mfma_f32_16x16x32_bf16(Bt_[n][k], At_[m][k], acc[ai][bj][m][n], 0, 0, 0); __builtin_amdgcn_s_setprio(0); } while (0)
; #define WAIT_V(n) asm volatile("s_waitcnt vmcnt(" #n ")" ::: "memory")
; #define WAIT_L(n) asm volatile("s_waitcnt lgkmcnt(" #n ")" ::: "memory")
; #define BAR __builtin_amdgcn_s_barrier()
; #define SCHED __builtin_amdgcn_sched_barrier(0)
; template <class Get, class Epi>
; DI void gemm_loop(int ntiles, int ld, char* shm, const Get& get, const Epi& epi) {
;     ...
;             G_LDB(B0, 1, 0); G_LDB(B1, 1, 1); SCHED; G_LDA(At, 1, 0); G_STAGE(G_SA(0, 1), a2 + hstep, voffA);
;             WAIT_V(8); WAIT_L(0); BAR; G_MMA(0, 0, At, B0); G_MMA(0, 1, At, B1); BAR; SCHED;
;             G_LDA(At, 1, 1); G_STAGE(G_SB(1, 0), b3, voffB); G_STAGE(G_SB(1, 1), b3 + hstep, voffB); G_STAGE(G_SA(1, 0), a3, voffA);
;             WAIT_V(8); WAIT_L(0); BAR; G_MMA(1, 0, At, B0); G_MMA(1, 1, At, B1); BAR; SCHED;
	s_add_i32 s57, 0, 0x18000
	v_add_u32_e32 v144, s57, v172
	s_add_i32 s58, 0, 0x1c000
	ds_read_b128 v[96:99], v144
	ds_read_b128 v[108:111], v144 offset:1024
	ds_read_b128 v[150:153], v144 offset:2048
	ds_read_b128 v[154:157], v144 offset:3072
	v_add_u32_e32 v144, s58, v172
	ds_read_b128 v[158:161], v144
	ds_read_b128 v[162:165], v144 offset:1024
	ds_read_b128 v[166:169], v144 offset:2048
	ds_read_b128 v[180:183], v144 offset:3072
	s_add_u32 s14, s14, 0x40000
	s_addc_u32 s15, s15, 0
	s_mov_b32 m0, s71
	v_lshl_add_u64 v[222:223], s[14:15], 0, v[142:143]
	ds_read_b128 v[184:187], v175 offset:32768
	ds_read_b128 v[188:191], v175 offset:33792
	ds_read_b128 v[192:195], v175 offset:34816
	ds_read_b128 v[196:199], v175 offset:35840
	ds_read_b128 v[200:203], v175 offset:36864
	ds_read_b128 v[204:207], v175 offset:37888
	ds_read_b128 v[208:211], v175 offset:38912
	ds_read_b128 v[212:215], v175 offset:39936
	global_load_lds_dwordx4 v[222:223], off
	v_lshl_add_u64 v[222:223], s[14:15], 0, v[138:139]
	s_mov_b32 m0, s72
	s_nop 0
	global_load_lds_dwordx4 v[222:223], off
	s_waitcnt vmcnt(8)
	s_waitcnt lgkmcnt(0)
	s_barrier
	s_waitcnt lgkmcnt(0)
	v_mfma_f32_16x16x32_bf16 v[132:135], v[96:99], v[184:187], v[132:135]
	v_mfma_f32_16x16x32_bf16 v[124:127], v[150:153], v[184:187], v[124:127]
	v_mfma_f32_16x16x32_bf16 v[128:131], v[96:99], v[192:195], v[128:131]
	v_mfma_f32_16x16x32_bf16 v[120:123], v[150:153], v[192:195], v[120:123]
	v_mfma_f32_16x16x32_bf16 v[116:119], v[96:99], v[200:203], v[116:119]
	v_mfma_f32_16x16x32_bf16 v[104:107], v[150:153], v[200:203], v[104:107]
	v_mfma_f32_16x16x32_bf16 v[112:115], v[96:99], v[208:211], v[112:115]
	v_mfma_f32_16x16x32_bf16 v[100:103], v[150:153], v[208:211], v[100:103]
	v_mfma_f32_16x16x32_bf16 v[132:135], v[108:111], v[188:191], v[132:135]
	v_mfma_f32_16x16x32_bf16 v[124:127], v[154:157], v[188:191], v[124:127]
	v_mfma_f32_16x16x32_bf16 v[128:131], v[108:111], v[196:199], v[128:131]
	v_mfma_f32_16x16x32_bf16 v[120:123], v[154:157], v[196:199], v[120:123]
	v_mfma_f32_16x16x32_bf16 v[116:119], v[108:111], v[204:207], v[116:119]
	v_mfma_f32_16x16x32_bf16 v[104:107], v[154:157], v[204:207], v[104:107]
	v_mfma_f32_16x16x32_bf16 v[112:115], v[108:111], v[212:215], v[112:115]
	v_mfma_f32_16x16x32_bf16 v[100:103], v[154:157], v[212:215], v[100:103]
	v_mfma_f32_16x16x32_bf16 v[60:63], v[158:161], v[184:187], v[60:63]
	v_mfma_f32_16x16x32_bf16 v[52:55], v[166:169], v[184:187], v[52:55]
	v_mfma_f32_16x16x32_bf16 v[56:59], v[158:161], v[192:195], v[56:59]
	v_mfma_f32_16x16x32_bf16 v[48:51], v[166:169], v[192:195], v[48:51]
	v_mfma_f32_16x16x32_bf16 v[44:47], v[158:161], v[200:203], v[44:47]
	v_mfma_f32_16x16x32_bf16 v[36:39], v[166:169], v[200:203], v[36:39]
	v_mfma_f32_16x16x32_bf16 v[40:43], v[158:161], v[208:211], v[40:43]
	v_mfma_f32_16x16x32_bf16 v[32:35], v[166:169], v[208:211], v[32:35]
	v_mfma_f32_16x16x32_bf16 v[60:63], v[162:165], v[188:191], v[60:63]
	v_mfma_f32_16x16x32_bf16 v[52:55], v[180:183], v[188:191], v[52:55]
	v_mfma_f32_16x16x32_bf16 v[56:59], v[162:165], v[196:199], v[56:59]
	v_mfma_f32_16x16x32_bf16 v[48:51], v[180:183], v[196:199], v[48:51]
	v_mfma_f32_16x16x32_bf16 v[44:47], v[162:165], v[204:207], v[44:47]
	v_mfma_f32_16x16x32_bf16 v[36:39], v[180:183], v[204:207], v[36:39]
	v_mfma_f32_16x16x32_bf16 v[40:43], v[162:165], v[212:215], v[40:43]
	v_mfma_f32_16x16x32_bf16 v[32:35], v[180:183], v[212:215], v[32:35]
	s_barrier
	s_add_i32 s14, s57, s46
	v_lshl_add_u64 v[170:171], v[170:171], 0, s[10:11]
	s_mov_b32 m0, s14
	ds_read_b128 v[184:187], v175 offset:49152
	ds_read_b128 v[188:191], v175 offset:50176
	ds_read_b128 v[192:195], v175 offset:51200
	ds_read_b128 v[196:199], v175 offset:52224
	ds_read_b128 v[200:203], v175 offset:53248
	ds_read_b128 v[204:207], v175 offset:54272
	ds_read_b128 v[208:211], v175 offset:55296
	ds_read_b128 v[212:215], v175 offset:56320
	global_load_lds_dwordx4 v[170:171], off
	s_add_i32 m0, s14, 0x2000
	s_add_u32 s6, s6, 0x40080
	v_lshl_add_u64 v[170:171], v[216:217], 0, s[10:11]
	s_addc_u32 s7, s7, 0
	s_add_i32 s14, s58, s46
	global_load_lds_dwordx4 v[170:171], off
	v_lshl_add_u64 v[170:171], s[6:7], 0, v[140:141]
	s_mov_b32 m0, s14
	s_nop 0
	global_load_lds_dwordx4 v[170:171], off
	v_lshl_add_u64 v[170:171], s[6:7], 0, v[136:137]
	s_add_i32 m0, s14, 0x2000
	s_nop 0
	global_load_lds_dwordx4 v[170:171], off
	v_lshl_add_u64 v[170:171], v[218:219], 0, s[10:11]
	s_mov_b32 m0, s73
	s_nop 0
	global_load_lds_dwordx4 v[170:171], off
	v_lshl_add_u64 v[170:171], v[220:221], 0, s[10:11]
	s_mov_b32 m0, s74
	s_nop 0
	global_load_lds_dwordx4 v[170:171], off
	s_waitcnt vmcnt(8)
	s_waitcnt lgkmcnt(0)
	s_barrier
	s_waitcnt lgkmcnt(0)
	v_mfma_f32_16x16x32_bf16 v[92:95], v[96:99], v[184:187], v[92:95]
	v_mfma_f32_16x16x32_bf16 v[84:87], v[150:153], v[184:187], v[84:87]
	v_mfma_f32_16x16x32_bf16 v[88:91], v[96:99], v[192:195], v[88:91]
	v_mfma_f32_16x16x32_bf16 v[80:83], v[150:153], v[192:195], v[80:83]
	v_mfma_f32_16x16x32_bf16 v[76:79], v[96:99], v[200:203], v[76:79]
	v_mfma_f32_16x16x32_bf16 v[68:71], v[150:153], v[200:203], v[68:71]
	v_mfma_f32_16x16x32_bf16 v[72:75], v[96:99], v[208:211], v[72:75]
	v_mfma_f32_16x16x32_bf16 v[64:67], v[150:153], v[208:211], v[64:67]
	v_mfma_f32_16x16x32_bf16 v[92:95], v[108:111], v[188:191], v[92:95]
	v_mfma_f32_16x16x32_bf16 v[84:87], v[154:157], v[188:191], v[84:87]
	v_mfma_f32_16x16x32_bf16 v[88:91], v[108:111], v[196:199], v[88:91]
	v_mfma_f32_16x16x32_bf16 v[80:83], v[154:157], v[196:199], v[80:83]
	v_mfma_f32_16x16x32_bf16 v[76:79], v[108:111], v[204:207], v[76:79]
	v_mfma_f32_16x16x32_bf16 v[68:71], v[154:157], v[204:207], v[68:71]
	v_mfma_f32_16x16x32_bf16 v[72:75], v[108:111], v[212:215], v[72:75]
	v_mfma_f32_16x16x32_bf16 v[64:67], v[154:157], v[212:215], v[64:67]
	v_mfma_f32_16x16x32_bf16 v[28:31], v[158:161], v[184:187], v[28:31]
	v_mfma_f32_16x16x32_bf16 v[20:23], v[166:169], v[184:187], v[20:23]
	v_mfma_f32_16x16x32_bf16 v[24:27], v[158:161], v[192:195], v[24:27]
	v_mfma_f32_16x16x32_bf16 v[16:19], v[166:169], v[192:195], v[16:19]
	v_mfma_f32_16x16x32_bf16 v[12:15], v[158:161], v[200:203], v[12:15]
	v_mfma_f32_16x16x32_bf16 v[4:7], v[166:169], v[200:203], v[4:7]
	v_mfma_f32_16x16x32_bf16 v[8:11], v[158:161], v[208:211], v[8:11]
	v_mfma_f32_16x16x32_bf16 v[0:3], v[166:169], v[208:211], v[0:3]
	v_mfma_f32_16x16x32_bf16 v[28:31], v[162:165], v[188:191], v[28:31]
	v_mfma_f32_16x16x32_bf16 v[20:23], v[180:183], v[188:191], v[20:23]
	v_mfma_f32_16x16x32_bf16 v[24:27], v[162:165], v[196:199], v[24:27]
	v_mfma_f32_16x16x32_bf16 v[16:19], v[180:183], v[196:199], v[16:19]
	v_mfma_f32_16x16x32_bf16 v[12:15], v[162:165], v[204:207], v[12:15]
	v_mfma_f32_16x16x32_bf16 v[4:7], v[180:183], v[204:207], v[4:7]
	v_mfma_f32_16x16x32_bf16 v[8:11], v[162:165], v[212:215], v[8:11]
	v_mfma_f32_16x16x32_bf16 v[0:3], v[180:183], v[212:215], v[0:3]
	s_barrier
	s_add_i32 s56, s56, 2
	s_add_u32 s4, s4, 0x100
	s_addc_u32 s5, s5, 0
	s_add_u32 s54, s54, 0x100
	s_addc_u32 s55, s55, 0
	s_cmp_gt_u32 s56, 13
	s_cbranch_scc0 .LBB0_2022

; #define G_STAGE(bufoff, gbase, voff) do { _Pragma("unroll") for (int _i = 0; _i < 2; ++_i) \
;         __builtin_amdgcn_global_load_lds((const unsigned*)((const char*)(gbase) + voff[_i]), (LAS unsigned*)(lds + (bufoff) + ldsw + _i * 8192), 16, 0, 0); } while (0)
; #define G_LDA(dst, b, h) do { _Pragma("unroll") for (int m = 0; m < 4; ++m) _Pragma("unroll") for (int k = 0; k < 2; ++k) dst[m][k] = *(const LAS bf16x8*)(lds + G_SA(b, h) + aoff + m * 2048 + k * 1024); } while (0)
; #define G_LDB(dst, b, h) do { _Pragma("unroll") for (int n = 0; n < 2; ++n) _Pragma("unroll") for (int k = 0; k < 2; ++k) dst[n][k] = *(const LAS bf16x8*)(lds + G_SB(b, h) + boff + n * 2048 + k * 1024); } while (0)
; #define G_MMA(ai, bj, At_, Bt_) do { __builtin_amdgcn_s_setprio(1); _Pragma("unroll") for (int m = 0; m < 4; ++m) _Pragma("unroll") for (int n = 0; n < 2; ++n) _Pragma("unroll") for (int k = 0; k < 2; ++k) \
;         acc[ai][bj][m][n] = __builtin_amdgcn_mfma_f32_16x16x32_bf16(Bt_[n][k], At_[m][k], acc[ai][bj][m][n], 0, 0, 0); __builtin_amdgcn_s_setprio(0); } while (0)
; #define WAIT_V(n) asm volatile("s_waitcnt vmcnt(" #n ")" ::: "memory")
; #define WAIT_L(n) asm volatile("s_waitcnt lgkmcnt(" #n ")" ::: "memory")
; #define BAR __builtin_amdgcn_s_barrier()
; #define SCHED __builtin_amdgcn_sched_barrier(0)
; template <class Get, class Epi>
; DI void gemm_loop(int ntiles, int ld, char* shm, const Get& get, const Epi& epi) {
;     ...
;             G_LDB(B0, 0, 0); G_LDB(B1, 0, 1); SCHED; G_LDA(At, 0, 0); G_STAGE(G_SA(1, 1), a1 + hstep, voffA);
;             WAIT_V(8); WAIT_L(0); BAR; G_MMA(0, 0, At, B0); G_MMA(0, 1, At, B1); BAR; SCHED;
;             G_LDA(At, 0, 1); G_STAGE(G_SB(0, 0), b2, voffB); G_STAGE(G_SB(0, 1), b2 + hstep, voffB); G_STAGE(G_SA(0, 0), a2, voffA);
.Lrj_2574_0:
	s_waitcnt lgkmcnt(0)
	s_barrier
	s_waitcnt lgkmcnt(0)
	v_mfma_f32_16x16x32_bf16 v[124:127], v[128:131], v[180:183], 0
	v_mfma_f32_16x16x32_bf16 v[120:123], v[136:139], v[180:183], 0
	v_mfma_f32_16x16x32_bf16 v[116:119], v[128:131], v[188:191], 0
	v_mfma_f32_16x16x32_bf16 v[112:115], v[136:139], v[188:191], 0
	v_mfma_f32_16x16x32_bf16 v[108:111], v[128:131], v[196:199], 0
	v_mfma_f32_16x16x32_bf16 v[104:107], v[136:139], v[196:199], 0
	v_mfma_f32_16x16x32_bf16 v[100:103], v[128:131], v[204:207], 0
	v_mfma_f32_16x16x32_bf16 v[96:99], v[136:139], v[204:207], 0
	v_mfma_f32_16x16x32_bf16 v[124:127], v[132:135], v[184:187], v[124:127]
	v_mfma_f32_16x16x32_bf16 v[120:123], v[140:143], v[184:187], v[120:123]
	v_mfma_f32_16x16x32_bf16 v[116:119], v[132:135], v[192:195], v[116:119]
	v_mfma_f32_16x16x32_bf16 v[112:115], v[140:143], v[192:195], v[112:115]
	v_mfma_f32_16x16x32_bf16 v[108:111], v[132:135], v[200:203], v[108:111]
	v_mfma_f32_16x16x32_bf16 v[104:107], v[140:143], v[200:203], v[104:107]
	v_mfma_f32_16x16x32_bf16 v[100:103], v[132:135], v[208:211], v[100:103]
	v_mfma_f32_16x16x32_bf16 v[96:99], v[140:143], v[208:211], v[96:99]
	v_mfma_f32_16x16x32_bf16 v[60:63], v[158:161], v[180:183], 0
	v_mfma_f32_16x16x32_bf16 v[56:59], v[172:175], v[180:183], 0
	v_mfma_f32_16x16x32_bf16 v[52:55], v[158:161], v[188:191], 0
	v_mfma_f32_16x16x32_bf16 v[48:51], v[172:175], v[188:191], 0
	v_mfma_f32_16x16x32_bf16 v[44:47], v[158:161], v[196:199], 0
	v_mfma_f32_16x16x32_bf16 v[40:43], v[172:175], v[196:199], 0
	v_mfma_f32_16x16x32_bf16 v[36:39], v[158:161], v[204:207], 0
	v_mfma_f32_16x16x32_bf16 v[32:35], v[172:175], v[204:207], 0
	v_mfma_f32_16x16x32_bf16 v[60:63], v[162:165], v[184:187], v[60:63]
	v_mfma_f32_16x16x32_bf16 v[56:59], v[176:179], v[184:187], v[56:59]
	v_mfma_f32_16x16x32_bf16 v[52:55], v[162:165], v[192:195], v[52:55]
	v_mfma_f32_16x16x32_bf16 v[48:51], v[176:179], v[192:195], v[48:51]
	v_mfma_f32_16x16x32_bf16 v[44:47], v[162:165], v[200:203], v[44:47]
	v_mfma_f32_16x16x32_bf16 v[40:43], v[176:179], v[200:203], v[40:43]
	v_mfma_f32_16x16x32_bf16 v[36:39], v[162:165], v[208:211], v[36:39]
	v_mfma_f32_16x16x32_bf16 v[32:35], v[176:179], v[208:211], v[32:35]
	s_barrier
	s_add_i32 s83, s72, s31
	v_lshl_add_u64 v[144:145], s[14:15], 0, v[148:149]
	s_mov_b32 m0, s83
	ds_read_b128 v[180:183], v171 offset:16384
	ds_read_b128 v[184:187], v171 offset:17408
	ds_read_b128 v[188:191], v171 offset:18432
	ds_read_b128 v[192:195], v171 offset:19456
	ds_read_b128 v[196:199], v171 offset:20480
	ds_read_b128 v[200:203], v171 offset:21504
	ds_read_b128 v[204:207], v171 offset:22528
	ds_read_b128 v[208:211], v171 offset:23552
	global_load_lds_dwordx4 v[144:145], off
	s_add_i32 m0, s83, 0x2000
	s_add_u32 s84, s14, 0x40000
	v_lshl_add_u64 v[166:167], s[14:15], 0, v[152:153]
	s_addc_u32 s85, s15, 0
	s_add_i32 s83, s73, s31
	global_load_lds_dwordx4 v[166:167], off
	v_lshl_add_u64 v[212:213], s[84:85], 0, v[148:149]
	s_mov_b32 m0, s83
	v_lshl_add_u64 v[214:215], s[46:47], 0, v[150:151]
	global_load_lds_dwordx4 v[212:213], off
	v_lshl_add_u64 v[212:213], s[84:85], 0, v[152:153]
	s_add_i32 m0, s83, 0x2000
	s_nop 0
	global_load_lds_dwordx4 v[212:213], off
	v_lshl_add_u64 v[212:213], s[46:47], 0, v[146:147]
	s_mov_b32 m0, s51
	s_nop 0
	global_load_lds_dwordx4 v[212:213], off
	s_mov_b32 m0, s54
	s_nop 0
	global_load_lds_dwordx4 v[214:215], off
	s_cmp_lg_u32 s100, 0
	s_cbranch_scc0 .Lrf_2574_1
	s_waitcnt vmcnt(16)
	s_branch .Lrj_2574_1

; #define G_STAGE(bufoff, gbase, voff) do { _Pragma("unroll") for (int _i = 0; _i < 2; ++_i) \
;         __builtin_amdgcn_global_load_lds((const unsigned*)((const char*)(gbase) + voff[_i]), (LAS unsigned*)(lds + (bufoff) + ldsw + _i * 8192), 16, 0, 0); } while (0)
; #define G_LDA(dst, b, h) do { _Pragma("unroll") for (int m = 0; m < 4; ++m) _Pragma("unroll") for (int k = 0; k < 2; ++k) dst[m][k] = *(const LAS bf16x8*)(lds + G_SA(b, h) + aoff + m * 2048 + k * 1024); } while (0)
; #define G_LDB(dst, b, h) do { _Pragma("unroll") for (int n = 0; n < 2; ++n) _Pragma("unroll") for (int k = 0; k < 2; ++k) dst[n][k] = *(const LAS bf16x8*)(lds + G_SB(b, h) + boff + n * 2048 + k * 1024); } while (0)
; #define G_MMA(ai, bj, At_, Bt_) do { __builtin_amdgcn_s_setprio(1); _Pragma("unroll") for (int m = 0; m < 4; ++m) _Pragma("unroll") for (int n = 0; n < 2; ++n) _Pragma("unroll") for (int k = 0; k < 2; ++k) \
;         acc[ai][bj][m][n] = __builtin_amdgcn_mfma_f32_16x16x32_bf16(Bt_[n][k], At_[m][k], acc[ai][bj][m][n], 0, 0, 0); __builtin_amdgcn_s_setprio(0); } while (0)
; #define WAIT_V(n) asm volatile("s_waitcnt vmcnt(" #n ")" ::: "memory")
; #define WAIT_L(n) asm volatile("s_waitcnt lgkmcnt(" #n ")" ::: "memory")
; #define BAR __builtin_amdgcn_s_barrier()
; #define SCHED __builtin_amdgcn_sched_barrier(0)
; template <class Get, class Epi>
; DI void gemm_loop(int ntiles, int ld, char* shm, const Get& get, const Epi& epi) {
;     ...
;             WAIT_V(8); WAIT_L(0); BAR; G_MMA(1, 0, At, B0); G_MMA(1, 1, At, B1); BAR; SCHED;
;             G_LDB(B0, 1, 0); G_LDB(B1, 1, 1); SCHED; G_LDA(At, 1, 0); G_STAGE(G_SA(0, 1), a2 + hstep, voffA);
;             WAIT_V(8); WAIT_L(0); BAR; G_MMA(0, 0, At, B0); G_MMA(0, 1, At, B1); BAR; SCHED;
;             G_LDA(At, 1, 1); G_STAGE(G_SB(1, 0), b3, voffB); G_STAGE(G_SB(1, 1), b3 + hstep, voffB); G_STAGE(G_SA(1, 0), a3, voffA);
;             WAIT_V(8); WAIT_L(0); BAR; G_MMA(1, 0, At, B0); G_MMA(1, 1, At, B1); BAR; SCHED;
.Lrj_2574_1:
	s_waitcnt lgkmcnt(0)
	s_barrier
	s_waitcnt lgkmcnt(0)
	v_mfma_f32_16x16x32_bf16 v[92:95], v[128:131], v[180:183], 0
	v_mfma_f32_16x16x32_bf16 v[88:91], v[136:139], v[180:183], 0
	v_mfma_f32_16x16x32_bf16 v[84:87], v[128:131], v[188:191], 0
	v_mfma_f32_16x16x32_bf16 v[80:83], v[136:139], v[188:191], 0
	v_mfma_f32_16x16x32_bf16 v[76:79], v[128:131], v[196:199], 0
	v_mfma_f32_16x16x32_bf16 v[72:75], v[136:139], v[196:199], 0
	v_mfma_f32_16x16x32_bf16 v[68:71], v[128:131], v[204:207], 0
	v_mfma_f32_16x16x32_bf16 v[64:67], v[136:139], v[204:207], 0
	v_mfma_f32_16x16x32_bf16 v[92:95], v[132:135], v[184:187], v[92:95]
	v_mfma_f32_16x16x32_bf16 v[88:91], v[140:143], v[184:187], v[88:91]
	v_mfma_f32_16x16x32_bf16 v[84:87], v[132:135], v[192:195], v[84:87]
	v_mfma_f32_16x16x32_bf16 v[80:83], v[140:143], v[192:195], v[80:83]
	v_mfma_f32_16x16x32_bf16 v[76:79], v[132:135], v[200:203], v[76:79]
	v_mfma_f32_16x16x32_bf16 v[72:75], v[140:143], v[200:203], v[72:75]
	v_mfma_f32_16x16x32_bf16 v[68:71], v[132:135], v[208:211], v[68:71]
	v_mfma_f32_16x16x32_bf16 v[64:67], v[140:143], v[208:211], v[64:67]
	v_mfma_f32_16x16x32_bf16 v[28:31], v[158:161], v[180:183], 0
	v_mfma_f32_16x16x32_bf16 v[24:27], v[172:175], v[180:183], 0
	v_mfma_f32_16x16x32_bf16 v[20:23], v[158:161], v[188:191], 0
	v_mfma_f32_16x16x32_bf16 v[16:19], v[172:175], v[188:191], 0
	v_mfma_f32_16x16x32_bf16 v[12:15], v[158:161], v[196:199], 0
	v_mfma_f32_16x16x32_bf16 v[8:11], v[172:175], v[196:199], 0
	v_mfma_f32_16x16x32_bf16 v[4:7], v[158:161], v[204:207], 0
	v_mfma_f32_16x16x32_bf16 v[0:3], v[172:175], v[204:207], 0
	v_mfma_f32_16x16x32_bf16 v[28:31], v[162:165], v[184:187], v[28:31]
	v_mfma_f32_16x16x32_bf16 v[24:27], v[176:179], v[184:187], v[24:27]
	v_mfma_f32_16x16x32_bf16 v[20:23], v[162:165], v[192:195], v[20:23]
	v_mfma_f32_16x16x32_bf16 v[16:19], v[176:179], v[192:195], v[16:19]
	v_mfma_f32_16x16x32_bf16 v[12:15], v[162:165], v[200:203], v[12:15]
	v_mfma_f32_16x16x32_bf16 v[8:11], v[176:179], v[200:203], v[8:11]
	v_mfma_f32_16x16x32_bf16 v[4:7], v[162:165], v[208:211], v[4:7]
	v_mfma_f32_16x16x32_bf16 v[0:3], v[176:179], v[208:211], v[0:3]
	s_barrier
	s_add_i32 s83, 0, 0x18000
	s_add_i32 s84, 0, 0x1c000
	v_add_u32_e32 v140, s83, v168
	v_add_u32_e32 v176, s84, v168
	ds_read_b128 v[128:131], v140
	ds_read_b128 v[132:135], v140 offset:1024
	ds_read_b128 v[136:139], v140 offset:2048
	ds_read_b128 v[140:143], v140 offset:3072
	ds_read_b128 v[158:161], v176
	ds_read_b128 v[162:165], v176 offset:1024
	ds_read_b128 v[172:175], v176 offset:2048
	ds_read_b128 v[176:179], v176 offset:3072
	s_add_u32 s46, s46, 0x40000
	s_addc_u32 s47, s47, 0
	s_mov_b32 m0, s55
	v_lshl_add_u64 v[216:217], s[46:47], 0, v[146:147]
	ds_read_b128 v[180:183], v171 offset:32768
	ds_read_b128 v[184:187], v171 offset:33792
	ds_read_b128 v[188:191], v171 offset:34816
	ds_read_b128 v[192:195], v171 offset:35840
	ds_read_b128 v[196:199], v171 offset:36864
	ds_read_b128 v[200:203], v171 offset:37888
	ds_read_b128 v[204:207], v171 offset:38912
	ds_read_b128 v[208:211], v171 offset:39936
	global_load_lds_dwordx4 v[216:217], off
	v_lshl_add_u64 v[216:217], s[46:47], 0, v[150:151]
	s_mov_b32 m0, s56
	s_nop 0
	global_load_lds_dwordx4 v[216:217], off
	s_waitcnt vmcnt(8)
	s_waitcnt lgkmcnt(0)
	s_barrier
	s_waitcnt lgkmcnt(0)
	v_mfma_f32_16x16x32_bf16 v[124:127], v[128:131], v[180:183], v[124:127]
	v_mfma_f32_16x16x32_bf16 v[120:123], v[136:139], v[180:183], v[120:123]
	v_mfma_f32_16x16x32_bf16 v[116:119], v[128:131], v[188:191], v[116:119]
	v_mfma_f32_16x16x32_bf16 v[112:115], v[136:139], v[188:191], v[112:115]
	v_mfma_f32_16x16x32_bf16 v[108:111], v[128:131], v[196:199], v[108:111]
	v_mfma_f32_16x16x32_bf16 v[104:107], v[136:139], v[196:199], v[104:107]
	v_mfma_f32_16x16x32_bf16 v[100:103], v[128:131], v[204:207], v[100:103]
	v_mfma_f32_16x16x32_bf16 v[96:99], v[136:139], v[204:207], v[96:99]
	v_mfma_f32_16x16x32_bf16 v[124:127], v[132:135], v[184:187], v[124:127]
	v_mfma_f32_16x16x32_bf16 v[120:123], v[140:143], v[184:187], v[120:123]
	v_mfma_f32_16x16x32_bf16 v[116:119], v[132:135], v[192:195], v[116:119]
	v_mfma_f32_16x16x32_bf16 v[112:115], v[140:143], v[192:195], v[112:115]
	v_mfma_f32_16x16x32_bf16 v[108:111], v[132:135], v[200:203], v[108:111]
	v_mfma_f32_16x16x32_bf16 v[104:107], v[140:143], v[200:203], v[104:107]
	v_mfma_f32_16x16x32_bf16 v[100:103], v[132:135], v[208:211], v[100:103]
	v_mfma_f32_16x16x32_bf16 v[96:99], v[140:143], v[208:211], v[96:99]
	v_mfma_f32_16x16x32_bf16 v[60:63], v[158:161], v[180:183], v[60:63]
	v_mfma_f32_16x16x32_bf16 v[56:59], v[172:175], v[180:183], v[56:59]
	v_mfma_f32_16x16x32_bf16 v[52:55], v[158:161], v[188:191], v[52:55]
	v_mfma_f32_16x16x32_bf16 v[48:51], v[172:175], v[188:191], v[48:51]
	v_mfma_f32_16x16x32_bf16 v[44:47], v[158:161], v[196:199], v[44:47]
	v_mfma_f32_16x16x32_bf16 v[40:43], v[172:175], v[196:199], v[40:43]
	v_mfma_f32_16x16x32_bf16 v[36:39], v[158:161], v[204:207], v[36:39]
	v_mfma_f32_16x16x32_bf16 v[32:35], v[172:175], v[204:207], v[32:35]
	v_mfma_f32_16x16x32_bf16 v[60:63], v[162:165], v[184:187], v[60:63]
	v_mfma_f32_16x16x32_bf16 v[56:59], v[176:179], v[184:187], v[56:59]
	v_mfma_f32_16x16x32_bf16 v[52:55], v[162:165], v[192:195], v[52:55]
	v_mfma_f32_16x16x32_bf16 v[48:51], v[176:179], v[192:195], v[48:51]
	v_mfma_f32_16x16x32_bf16 v[44:47], v[162:165], v[200:203], v[44:47]
	v_mfma_f32_16x16x32_bf16 v[40:43], v[176:179], v[200:203], v[40:43]
	v_mfma_f32_16x16x32_bf16 v[36:39], v[162:165], v[208:211], v[36:39]
	v_mfma_f32_16x16x32_bf16 v[32:35], v[176:179], v[208:211], v[32:35]
	s_barrier
; #define G_STAGE(bufoff, gbase, voff) do { _Pragma("unroll") for (int _i = 0; _i < 2; ++_i) \
;         __builtin_amdgcn_global_load_lds((const unsigned*)((const char*)(gbase) + voff[_i]), (LAS unsigned*)(lds + (bufoff) + ldsw + _i * 8192), 16, 0, 0); } while (0)
; #define G_LDA(dst, b, h) do { _Pragma("unroll") for (int m = 0; m < 4; ++m) _Pragma("unroll") for (int k = 0; k < 2; ++k) dst[m][k] = *(const LAS bf16x8*)(lds + G_SA(b, h) + aoff + m * 2048 + k * 1024); } while (0)
; #define G_LDB(dst, b, h) do { _Pragma("unroll") for (int n = 0; n < 2; ++n) _Pragma("unroll") for (int k = 0; k < 2; ++k) dst[n][k] = *(const LAS bf16x8*)(lds + G_SB(b, h) + boff + n * 2048 + k * 1024); } while (0)
; #define WAIT_V(n) asm volatile("s_waitcnt vmcnt(" #n ")" ::: "memory")
; #define WAIT_L(n) asm volatile("s_waitcnt lgkmcnt(" #n ")" ::: "memory")
; #define BAR __builtin_amdgcn_s_barrier()
; #define SCHED __builtin_amdgcn_sched_barrier(0)
; template <class Get, class Epi>
; DI void gemm_loop(int ntiles, int ld, char* shm, const Get& get, const Epi& epi) {
;     ...
;         for (int t = 0; t < nt; t += 2) {
;             const bool last = (t == nt - 2);
;             const char* a1 = cA + (size_t)(t + 1) * kstep;
;             const char* a2 = last ? nA : cA + (size_t)(t + 2) * kstep; const char* b2 = last ? nB : cB + (size_t)(t + 2) * kstep;
;             const char* a3 = a2 + kstep; const char* b3 = b2 + kstep;
;             G_LDB(B0, 0, 0); G_LDB(B1, 0, 1); SCHED; G_LDA(At, 0, 0); G_STAGE(G_SA(1, 1), a1 + hstep, voffA);
;             WAIT_V(8); WAIT_L(0); BAR; G_MMA(0, 0, At, B0); G_MMA(0, 1, At, B1); BAR; SCHED;
;             G_LDA(At, 0, 1); G_STAGE(G_SB(0, 0), b2, voffB); G_STAGE(G_SB(0, 1), b2 + hstep, voffB); G_STAGE(G_SA(0, 0), a2, voffA);
;             WAIT_V(8); WAIT_L(0); BAR; G_MMA(1, 0, At, B0); G_MMA(1, 1, At, B1); BAR; SCHED;
;             G_LDB(B0, 1, 0); G_LDB(B1, 1, 1); SCHED; G_LDA(At, 1, 0); G_STAGE(G_SA(0, 1), a2 + hstep, voffA);
;             WAIT_V(8); WAIT_L(0); BAR; G_MMA(0, 0, At, B0); G_MMA(0, 1, At, B1); BAR; SCHED;
;             G_LDA(At, 1, 1); G_STAGE(G_SB(1, 0), b3, voffB); G_STAGE(G_SB(1, 1), b3 + hstep, voffB); G_STAGE(G_SA(1, 0), a3, voffA);
;             WAIT_V(8); WAIT_L(0); BAR; G_MMA(1, 0, At, B0); G_MMA(1, 1, At, B1); BAR; SCHED;
	s_add_i32 s46, s83, s31
	v_lshl_add_u64 v[144:145], v[144:145], 0, s[8:9]
	s_mov_b32 m0, s46
	ds_read_b128 v[180:183], v171 offset:49152
	ds_read_b128 v[184:187], v171 offset:50176
	ds_read_b128 v[188:191], v171 offset:51200
	ds_read_b128 v[192:195], v171 offset:52224
	ds_read_b128 v[196:199], v171 offset:53248
	ds_read_b128 v[200:203], v171 offset:54272
	ds_read_b128 v[204:207], v171 offset:55296
	ds_read_b128 v[208:211], v171 offset:56320
	global_load_lds_dwordx4 v[144:145], off
	s_add_i32 m0, s46, 0x2000
	s_add_u32 s14, s14, 0x40080
	v_lshl_add_u64 v[144:145], v[166:167], 0, s[8:9]
	s_addc_u32 s15, s15, 0
	s_add_i32 s46, s84, s31
	global_load_lds_dwordx4 v[144:145], off
	v_lshl_add_u64 v[144:145], s[14:15], 0, v[148:149]
	s_mov_b32 m0, s46
	s_nop 0
	global_load_lds_dwordx4 v[144:145], off
	v_lshl_add_u64 v[144:145], s[14:15], 0, v[152:153]
	s_add_i32 m0, s46, 0x2000
	s_nop 0
	global_load_lds_dwordx4 v[144:145], off
	v_lshl_add_u64 v[144:145], v[212:213], 0, s[8:9]
	s_mov_b32 m0, s59
	s_nop 0
	global_load_lds_dwordx4 v[144:145], off
	v_lshl_add_u64 v[144:145], v[214:215], 0, s[8:9]
	s_mov_b32 m0, s71
	s_nop 0
	global_load_lds_dwordx4 v[144:145], off
	s_waitcnt vmcnt(8)
	s_waitcnt lgkmcnt(0)
	s_barrier
	s_waitcnt lgkmcnt(0)
	v_mfma_f32_16x16x32_bf16 v[92:95], v[128:131], v[180:183], v[92:95]
	v_mfma_f32_16x16x32_bf16 v[88:91], v[136:139], v[180:183], v[88:91]
	v_mfma_f32_16x16x32_bf16 v[84:87], v[128:131], v[188:191], v[84:87]
	v_mfma_f32_16x16x32_bf16 v[80:83], v[136:139], v[188:191], v[80:83]
	v_mfma_f32_16x16x32_bf16 v[76:79], v[128:131], v[196:199], v[76:79]
	v_mfma_f32_16x16x32_bf16 v[72:75], v[136:139], v[196:199], v[72:75]
	v_mfma_f32_16x16x32_bf16 v[68:71], v[128:131], v[204:207], v[68:71]
	v_mfma_f32_16x16x32_bf16 v[64:67], v[136:139], v[204:207], v[64:67]
	v_mfma_f32_16x16x32_bf16 v[92:95], v[132:135], v[184:187], v[92:95]
	v_mfma_f32_16x16x32_bf16 v[88:91], v[140:143], v[184:187], v[88:91]
	v_mfma_f32_16x16x32_bf16 v[84:87], v[132:135], v[192:195], v[84:87]
	v_mfma_f32_16x16x32_bf16 v[80:83], v[140:143], v[192:195], v[80:83]
	v_mfma_f32_16x16x32_bf16 v[76:79], v[132:135], v[200:203], v[76:79]
	v_mfma_f32_16x16x32_bf16 v[72:75], v[140:143], v[200:203], v[72:75]
	v_mfma_f32_16x16x32_bf16 v[68:71], v[132:135], v[208:211], v[68:71]
	v_mfma_f32_16x16x32_bf16 v[64:67], v[140:143], v[208:211], v[64:67]
	v_mfma_f32_16x16x32_bf16 v[28:31], v[158:161], v[180:183], v[28:31]
	v_mfma_f32_16x16x32_bf16 v[24:27], v[172:175], v[180:183], v[24:27]
	v_mfma_f32_16x16x32_bf16 v[20:23], v[158:161], v[188:191], v[20:23]
	v_mfma_f32_16x16x32_bf16 v[16:19], v[172:175], v[188:191], v[16:19]
	v_mfma_f32_16x16x32_bf16 v[12:15], v[158:161], v[196:199], v[12:15]
	v_mfma_f32_16x16x32_bf16 v[8:11], v[172:175], v[196:199], v[8:11]
	v_mfma_f32_16x16x32_bf16 v[4:7], v[158:161], v[204:207], v[4:7]
	v_mfma_f32_16x16x32_bf16 v[0:3], v[172:175], v[204:207], v[0:3]
	v_mfma_f32_16x16x32_bf16 v[28:31], v[162:165], v[184:187], v[28:31]
	v_mfma_f32_16x16x32_bf16 v[24:27], v[176:179], v[184:187], v[24:27]
	v_mfma_f32_16x16x32_bf16 v[20:23], v[162:165], v[192:195], v[20:23]
	v_mfma_f32_16x16x32_bf16 v[16:19], v[176:179], v[192:195], v[16:19]
	v_mfma_f32_16x16x32_bf16 v[12:15], v[162:165], v[200:203], v[12:15]
	v_mfma_f32_16x16x32_bf16 v[8:11], v[176:179], v[200:203], v[8:11]
	v_mfma_f32_16x16x32_bf16 v[4:7], v[162:165], v[208:211], v[4:7]
	v_mfma_f32_16x16x32_bf16 v[0:3], v[176:179], v[208:211], v[0:3]
	s_barrier
	s_add_u32 s52, s52, 0x100
	s_addc_u32 s53, s53, 0
	s_add_u32 s80, s80, 0x100
	s_addc_u32 s81, s81, 0
	s_cmp_ge_u32 s82, s78
	s_mov_b32 s14, s82
	s_cbranch_scc0 .LBB0_2574
	s_branch .Lpost_2574
.LBB0_2574:
	ds_read_b128 v[128:131], v169
	ds_read_b128 v[132:135], v169 offset:1024
	ds_read_b128 v[136:139], v169 offset:2048
	ds_read_b128 v[140:143], v169 offset:3072
	ds_read_b128 v[158:161], v170
	ds_read_b128 v[162:165], v170 offset:1024
	ds_read_b128 v[172:175], v170 offset:2048
	ds_read_b128 v[176:179], v170 offset:3072
	s_add_i32 s82, s14, 2
	s_add_u32 s15, s52, 0xfffc0080
	s_addc_u32 s46, s53, -1
	s_cmp_eq_u32 s79, s14
	s_cselect_b32 s14, s77, s80
	s_cselect_b32 s47, s3, s46
	s_cselect_b32 s46, s41, s15
	s_cselect_b32 s15, s43, s81
	v_lshl_add_u64 v[144:145], s[52:53], 0, v[154:155]
	s_add_i32 m0, s51, 0xc000
	ds_read_b128 v[180:183], v171
	ds_read_b128 v[184:187], v171 offset:1024
	ds_read_b128 v[188:191], v171 offset:2048
	ds_read_b128 v[192:195], v171 offset:3072
	ds_read_b128 v[196:199], v171 offset:4096
	ds_read_b128 v[200:203], v171 offset:5120
	ds_read_b128 v[204:207], v171 offset:6144
	ds_read_b128 v[208:211], v171 offset:7168
	global_load_lds_dwordx4 v[144:145], off
	v_lshl_add_u64 v[144:145], s[52:53], 0, v[156:157]
	s_add_i32 m0, s51, 0xe000
	s_nop 0
	global_load_lds_dwordx4 v[144:145], off
	s_waitcnt vmcnt(8)
	s_waitcnt lgkmcnt(0)
	s_barrier
; #define G_STAGE(bufoff, gbase, voff) do { _Pragma("unroll") for (int _i = 0; _i < 2; ++_i) \
;         __builtin_amdgcn_global_load_lds((const unsigned*)((const char*)(gbase) + voff[_i]), (LAS unsigned*)(lds + (bufoff) + ldsw + _i * 8192), 16, 0, 0); } while (0)
; #define G_LDA(dst, b, h) do { _Pragma("unroll") for (int m = 0; m < 4; ++m) _Pragma("unroll") for (int k = 0; k < 2; ++k) dst[m][k] = *(const LAS bf16x8*)(lds + G_SA(b, h) + aoff + m * 2048 + k * 1024); } while (0)
; #define G_LDB(dst, b, h) do { _Pragma("unroll") for (int n = 0; n < 2; ++n) _Pragma("unroll") for (int k = 0; k < 2; ++k) dst[n][k] = *(const LAS bf16x8*)(lds + G_SB(b, h) + boff + n * 2048 + k * 1024); } while (0)
; #define G_MMA(ai, bj, At_, Bt_) do { __builtin_amdgcn_s_setprio(1); _Pragma("unroll") for (int m = 0; m < 4; ++m) _Pragma("unroll") for (int n = 0; n < 2; ++n) _Pragma("unroll") for (int k = 0; k < 2; ++k) \
;         acc[ai][bj][m][n] = __builtin_amdgcn_mfma_f32_16x16x32_bf16(Bt_[n][k], At_[m][k], acc[ai][bj][m][n], 0, 0, 0); __builtin_amdgcn_s_setprio(0); } while (0)
; #define WAIT_V(n) asm volatile("s_waitcnt vmcnt(" #n ")" ::: "memory")
; #define WAIT_L(n) asm volatile("s_waitcnt lgkmcnt(" #n ")" ::: "memory")
; #define BAR __builtin_amdgcn_s_barrier()
; #define SCHED __builtin_amdgcn_sched_barrier(0)
; template <class Get, class Epi>
; DI void gemm_loop(int ntiles, int ld, char* shm, const Get& get, const Epi& epi) {
;     ...
;             G_LDB(B0, 0, 0); G_LDB(B1, 0, 1); SCHED; G_LDA(At, 0, 0); G_STAGE(G_SA(1, 1), a1 + hstep, voffA);
;             WAIT_V(8); WAIT_L(0); BAR; G_MMA(0, 0, At, B0); G_MMA(0, 1, At, B1); BAR; SCHED;
;             G_LDA(At, 0, 1); G_STAGE(G_SB(0, 0), b2, voffB); G_STAGE(G_SB(0, 1), b2 + hstep, voffB); G_STAGE(G_SA(0, 0), a2, voffA);
;             WAIT_V(8); WAIT_L(0); BAR; G_MMA(1, 0, At, B0); G_MMA(1, 1, At, B1); BAR; SCHED;
	s_waitcnt lgkmcnt(0)
	v_mfma_f32_16x16x32_bf16 v[124:127], v[128:131], v[180:183], v[124:127]
	v_mfma_f32_16x16x32_bf16 v[120:123], v[136:139], v[180:183], v[120:123]
	v_mfma_f32_16x16x32_bf16 v[116:119], v[128:131], v[188:191], v[116:119]
	v_mfma_f32_16x16x32_bf16 v[112:115], v[136:139], v[188:191], v[112:115]
	v_mfma_f32_16x16x32_bf16 v[108:111], v[128:131], v[196:199], v[108:111]
	v_mfma_f32_16x16x32_bf16 v[104:107], v[136:139], v[196:199], v[104:107]
	v_mfma_f32_16x16x32_bf16 v[100:103], v[128:131], v[204:207], v[100:103]
	v_mfma_f32_16x16x32_bf16 v[96:99], v[136:139], v[204:207], v[96:99]
	v_mfma_f32_16x16x32_bf16 v[124:127], v[132:135], v[184:187], v[124:127]
	v_mfma_f32_16x16x32_bf16 v[120:123], v[140:143], v[184:187], v[120:123]
	v_mfma_f32_16x16x32_bf16 v[116:119], v[132:135], v[192:195], v[116:119]
	v_mfma_f32_16x16x32_bf16 v[112:115], v[140:143], v[192:195], v[112:115]
	v_mfma_f32_16x16x32_bf16 v[108:111], v[132:135], v[200:203], v[108:111]
	v_mfma_f32_16x16x32_bf16 v[104:107], v[140:143], v[200:203], v[104:107]
	v_mfma_f32_16x16x32_bf16 v[100:103], v[132:135], v[208:211], v[100:103]
	v_mfma_f32_16x16x32_bf16 v[96:99], v[140:143], v[208:211], v[96:99]
	v_mfma_f32_16x16x32_bf16 v[60:63], v[158:161], v[180:183], v[60:63]
	v_mfma_f32_16x16x32_bf16 v[56:59], v[172:175], v[180:183], v[56:59]
	v_mfma_f32_16x16x32_bf16 v[52:55], v[158:161], v[188:191], v[52:55]
	v_mfma_f32_16x16x32_bf16 v[48:51], v[172:175], v[188:191], v[48:51]
	v_mfma_f32_16x16x32_bf16 v[44:47], v[158:161], v[196:199], v[44:47]
	v_mfma_f32_16x16x32_bf16 v[40:43], v[172:175], v[196:199], v[40:43]
	v_mfma_f32_16x16x32_bf16 v[36:39], v[158:161], v[204:207], v[36:39]
	v_mfma_f32_16x16x32_bf16 v[32:35], v[172:175], v[204:207], v[32:35]
	v_mfma_f32_16x16x32_bf16 v[60:63], v[162:165], v[184:187], v[60:63]
	v_mfma_f32_16x16x32_bf16 v[56:59], v[176:179], v[184:187], v[56:59]
	v_mfma_f32_16x16x32_bf16 v[52:55], v[162:165], v[192:195], v[52:55]
	v_mfma_f32_16x16x32_bf16 v[48:51], v[176:179], v[192:195], v[48:51]
	v_mfma_f32_16x16x32_bf16 v[44:47], v[162:165], v[200:203], v[44:47]
	v_mfma_f32_16x16x32_bf16 v[40:43], v[176:179], v[200:203], v[40:43]
	v_mfma_f32_16x16x32_bf16 v[36:39], v[162:165], v[208:211], v[36:39]
	v_mfma_f32_16x16x32_bf16 v[32:35], v[176:179], v[208:211], v[32:35]
	s_barrier
	s_add_i32 s83, s72, s31
	v_lshl_add_u64 v[144:145], s[14:15], 0, v[148:149]
	s_mov_b32 m0, s83
	ds_read_b128 v[180:183], v171 offset:16384
	ds_read_b128 v[184:187], v171 offset:17408
	ds_read_b128 v[188:191], v171 offset:18432
	ds_read_b128 v[192:195], v171 offset:19456
	ds_read_b128 v[196:199], v171 offset:20480
	ds_read_b128 v[200:203], v171 offset:21504
	ds_read_b128 v[204:207], v171 offset:22528
	ds_read_b128 v[208:211], v171 offset:23552
	global_load_lds_dwordx4 v[144:145], off
	s_add_i32 m0, s83, 0x2000
	s_add_u32 s84, s14, 0x40000
	v_lshl_add_u64 v[166:167], s[14:15], 0, v[152:153]
	s_addc_u32 s85, s15, 0
	s_add_i32 s83, s73, s31
	global_load_lds_dwordx4 v[166:167], off
	v_lshl_add_u64 v[212:213], s[84:85], 0, v[148:149]
	s_mov_b32 m0, s83
	v_lshl_add_u64 v[214:215], s[46:47], 0, v[150:151]
	global_load_lds_dwordx4 v[212:213], off
	v_lshl_add_u64 v[212:213], s[84:85], 0, v[152:153]
	s_add_i32 m0, s83, 0x2000
	s_nop 0
	global_load_lds_dwordx4 v[212:213], off
	v_lshl_add_u64 v[212:213], s[46:47], 0, v[146:147]
	s_mov_b32 m0, s51
	s_nop 0
	global_load_lds_dwordx4 v[212:213], off
	s_mov_b32 m0, s54
	s_nop 0
	global_load_lds_dwordx4 v[214:215], off
	s_waitcnt vmcnt(8)
	s_waitcnt lgkmcnt(0)
	s_barrier
	s_waitcnt lgkmcnt(0)
	v_mfma_f32_16x16x32_bf16 v[92:95], v[128:131], v[180:183], v[92:95]
	v_mfma_f32_16x16x32_bf16 v[88:91], v[136:139], v[180:183], v[88:91]
	v_mfma_f32_16x16x32_bf16 v[84:87], v[128:131], v[188:191], v[84:87]
	v_mfma_f32_16x16x32_bf16 v[80:83], v[136:139], v[188:191], v[80:83]
	v_mfma_f32_16x16x32_bf16 v[76:79], v[128:131], v[196:199], v[76:79]
	v_mfma_f32_16x16x32_bf16 v[72:75], v[136:139], v[196:199], v[72:75]
	v_mfma_f32_16x16x32_bf16 v[68:71], v[128:131], v[204:207], v[68:71]
	v_mfma_f32_16x16x32_bf16 v[64:67], v[136:139], v[204:207], v[64:67]
	v_mfma_f32_16x16x32_bf16 v[92:95], v[132:135], v[184:187], v[92:95]
	v_mfma_f32_16x16x32_bf16 v[88:91], v[140:143], v[184:187], v[88:91]
	v_mfma_f32_16x16x32_bf16 v[84:87], v[132:135], v[192:195], v[84:87]
	v_mfma_f32_16x16x32_bf16 v[80:83], v[140:143], v[192:195], v[80:83]
	v_mfma_f32_16x16x32_bf16 v[76:79], v[132:135], v[200:203], v[76:79]
	v_mfma_f32_16x16x32_bf16 v[72:75], v[140:143], v[200:203], v[72:75]
	v_mfma_f32_16x16x32_bf16 v[68:71], v[132:135], v[208:211], v[68:71]
	v_mfma_f32_16x16x32_bf16 v[64:67], v[140:143], v[208:211], v[64:67]
	v_mfma_f32_16x16x32_bf16 v[28:31], v[158:161], v[180:183], v[28:31]
	v_mfma_f32_16x16x32_bf16 v[24:27], v[172:175], v[180:183], v[24:27]
	v_mfma_f32_16x16x32_bf16 v[20:23], v[158:161], v[188:191], v[20:23]
	v_mfma_f32_16x16x32_bf16 v[16:19], v[172:175], v[188:191], v[16:19]
	v_mfma_f32_16x16x32_bf16 v[12:15], v[158:161], v[196:199], v[12:15]
	v_mfma_f32_16x16x32_bf16 v[8:11], v[172:175], v[196:199], v[8:11]
	v_mfma_f32_16x16x32_bf16 v[4:7], v[158:161], v[204:207], v[4:7]
	v_mfma_f32_16x16x32_bf16 v[0:3], v[172:175], v[204:207], v[0:3]
	v_mfma_f32_16x16x32_bf16 v[28:31], v[162:165], v[184:187], v[28:31]
	v_mfma_f32_16x16x32_bf16 v[24:27], v[176:179], v[184:187], v[24:27]
	v_mfma_f32_16x16x32_bf16 v[20:23], v[162:165], v[192:195], v[20:23]
	v_mfma_f32_16x16x32_bf16 v[16:19], v[176:179], v[192:195], v[16:19]
	v_mfma_f32_16x16x32_bf16 v[12:15], v[162:165], v[200:203], v[12:15]
	v_mfma_f32_16x16x32_bf16 v[8:11], v[176:179], v[200:203], v[8:11]
	v_mfma_f32_16x16x32_bf16 v[4:7], v[162:165], v[208:211], v[4:7]
	v_mfma_f32_16x16x32_bf16 v[0:3], v[176:179], v[208:211], v[0:3]
	s_barrier
; #define G_STAGE(bufoff, gbase, voff) do { _Pragma("unroll") for (int _i = 0; _i < 2; ++_i) \
;         __builtin_amdgcn_global_load_lds((const unsigned*)((const char*)(gbase) + voff[_i]), (LAS unsigned*)(lds + (bufoff) + ldsw + _i * 8192), 16, 0, 0); } while (0)
; #define G_LDA(dst, b, h) do { _Pragma("unroll") for (int m = 0; m < 4; ++m) _Pragma("unroll") for (int k = 0; k < 2; ++k) dst[m][k] = *(const LAS bf16x8*)(lds + G_SA(b, h) + aoff + m * 2048 + k * 1024); } while (0)
; #define G_LDB(dst, b, h) do { _Pragma("unroll") for (int n = 0; n < 2; ++n) _Pragma("unroll") for (int k = 0; k < 2; ++k) dst[n][k] = *(const LAS bf16x8*)(lds + G_SB(b, h) + boff + n * 2048 + k * 1024); } while (0)
; #define G_MMA(ai, bj, At_, Bt_) do { __builtin_amdgcn_s_setprio(1); _Pragma("unroll") for (int m = 0; m < 4; ++m) _Pragma("unroll") for (int n = 0; n < 2; ++n) _Pragma("unroll") for (int k = 0; k < 2; ++k) \
;         acc[ai][bj][m][n] = __builtin_amdgcn_mfma_f32_16x16x32_bf16(Bt_[n][k], At_[m][k], acc[ai][bj][m][n], 0, 0, 0); __builtin_amdgcn_s_setprio(0); } while (0)
; #define WAIT_V(n) asm volatile("s_waitcnt vmcnt(" #n ")" ::: "memory")
; #define WAIT_L(n) asm volatile("s_waitcnt lgkmcnt(" #n ")" ::: "memory")
; #define BAR __builtin_amdgcn_s_barrier()
; #define SCHED __builtin_amdgcn_sched_barrier(0)
; template <class Get, class Epi>
; DI void gemm_loop(int ntiles, int ld, char* shm, const Get& get, const Epi& epi) {
;     ...
;             G_LDB(B0, 1, 0); G_LDB(B1, 1, 1); SCHED; G_LDA(At, 1, 0); G_STAGE(G_SA(0, 1), a2 + hstep, voffA);
;             WAIT_V(8); WAIT_L(0); BAR; G_MMA(0, 0, At, B0); G_MMA(0, 1, At, B1); BAR; SCHED;
;             G_LDA(At, 1, 1); G_STAGE(G_SB(1, 0), b3, voffB); G_STAGE(G_SB(1, 1), b3 + hstep, voffB); G_STAGE(G_SA(1, 0), a3, voffA);
;             WAIT_V(8); WAIT_L(0); BAR; G_MMA(1, 0, At, B0); G_MMA(1, 1, At, B1); BAR; SCHED;
	s_add_i32 s83, 0, 0x18000
	s_add_i32 s84, 0, 0x1c000
	v_add_u32_e32 v140, s83, v168
	v_add_u32_e32 v176, s84, v168
	ds_read_b128 v[128:131], v140
	ds_read_b128 v[132:135], v140 offset:1024
	ds_read_b128 v[136:139], v140 offset:2048
	ds_read_b128 v[140:143], v140 offset:3072
	ds_read_b128 v[158:161], v176
	ds_read_b128 v[162:165], v176 offset:1024
	ds_read_b128 v[172:175], v176 offset:2048
	ds_read_b128 v[176:179], v176 offset:3072
	s_add_u32 s46, s46, 0x40000
	s_addc_u32 s47, s47, 0
	s_mov_b32 m0, s55
	v_lshl_add_u64 v[216:217], s[46:47], 0, v[146:147]
	ds_read_b128 v[180:183], v171 offset:32768
	ds_read_b128 v[184:187], v171 offset:33792
	ds_read_b128 v[188:191], v171 offset:34816
	ds_read_b128 v[192:195], v171 offset:35840
	ds_read_b128 v[196:199], v171 offset:36864
	ds_read_b128 v[200:203], v171 offset:37888
	ds_read_b128 v[204:207], v171 offset:38912
	ds_read_b128 v[208:211], v171 offset:39936
	global_load_lds_dwordx4 v[216:217], off
	v_lshl_add_u64 v[216:217], s[46:47], 0, v[150:151]
	s_mov_b32 m0, s56
	s_nop 0
	global_load_lds_dwordx4 v[216:217], off
	s_waitcnt vmcnt(8)
	s_waitcnt lgkmcnt(0)
	s_barrier
	s_waitcnt lgkmcnt(0)
	v_mfma_f32_16x16x32_bf16 v[124:127], v[128:131], v[180:183], v[124:127]
	v_mfma_f32_16x16x32_bf16 v[120:123], v[136:139], v[180:183], v[120:123]
	v_mfma_f32_16x16x32_bf16 v[116:119], v[128:131], v[188:191], v[116:119]
	v_mfma_f32_16x16x32_bf16 v[112:115], v[136:139], v[188:191], v[112:115]
	v_mfma_f32_16x16x32_bf16 v[108:111], v[128:131], v[196:199], v[108:111]
	v_mfma_f32_16x16x32_bf16 v[104:107], v[136:139], v[196:199], v[104:107]
	v_mfma_f32_16x16x32_bf16 v[100:103], v[128:131], v[204:207], v[100:103]
	v_mfma_f32_16x16x32_bf16 v[96:99], v[136:139], v[204:207], v[96:99]
	v_mfma_f32_16x16x32_bf16 v[124:127], v[132:135], v[184:187], v[124:127]
	v_mfma_f32_16x16x32_bf16 v[120:123], v[140:143], v[184:187], v[120:123]
	v_mfma_f32_16x16x32_bf16 v[116:119], v[132:135], v[192:195], v[116:119]
	v_mfma_f32_16x16x32_bf16 v[112:115], v[140:143], v[192:195], v[112:115]
	v_mfma_f32_16x16x32_bf16 v[108:111], v[132:135], v[200:203], v[108:111]
	v_mfma_f32_16x16x32_bf16 v[104:107], v[140:143], v[200:203], v[104:107]
	v_mfma_f32_16x16x32_bf16 v[100:103], v[132:135], v[208:211], v[100:103]
	v_mfma_f32_16x16x32_bf16 v[96:99], v[140:143], v[208:211], v[96:99]
	v_mfma_f32_16x16x32_bf16 v[60:63], v[158:161], v[180:183], v[60:63]
	v_mfma_f32_16x16x32_bf16 v[56:59], v[172:175], v[180:183], v[56:59]
	v_mfma_f32_16x16x32_bf16 v[52:55], v[158:161], v[188:191], v[52:55]
	v_mfma_f32_16x16x32_bf16 v[48:51], v[172:175], v[188:191], v[48:51]
	v_mfma_f32_16x16x32_bf16 v[44:47], v[158:161], v[196:199], v[44:47]
	v_mfma_f32_16x16x32_bf16 v[40:43], v[172:175], v[196:199], v[40:43]
	v_mfma_f32_16x16x32_bf16 v[36:39], v[158:161], v[204:207], v[36:39]
	v_mfma_f32_16x16x32_bf16 v[32:35], v[172:175], v[204:207], v[32:35]
	v_mfma_f32_16x16x32_bf16 v[60:63], v[162:165], v[184:187], v[60:63]
	v_mfma_f32_16x16x32_bf16 v[56:59], v[176:179], v[184:187], v[56:59]
	v_mfma_f32_16x16x32_bf16 v[52:55], v[162:165], v[192:195], v[52:55]
	v_mfma_f32_16x16x32_bf16 v[48:51], v[176:179], v[192:195], v[48:51]
	v_mfma_f32_16x16x32_bf16 v[44:47], v[162:165], v[200:203], v[44:47]
	v_mfma_f32_16x16x32_bf16 v[40:43], v[176:179], v[200:203], v[40:43]
	v_mfma_f32_16x16x32_bf16 v[36:39], v[162:165], v[208:211], v[36:39]
	v_mfma_f32_16x16x32_bf16 v[32:35], v[176:179], v[208:211], v[32:35]
	s_barrier
	s_add_i32 s46, s83, s31
	v_lshl_add_u64 v[144:145], v[144:145], 0, s[8:9]
	s_mov_b32 m0, s46
	ds_read_b128 v[180:183], v171 offset:49152
	ds_read_b128 v[184:187], v171 offset:50176
	ds_read_b128 v[188:191], v171 offset:51200
	ds_read_b128 v[192:195], v171 offset:52224
	ds_read_b128 v[196:199], v171 offset:53248
	ds_read_b128 v[200:203], v171 offset:54272
	ds_read_b128 v[204:207], v171 offset:55296
	ds_read_b128 v[208:211], v171 offset:56320
	global_load_lds_dwordx4 v[144:145], off
	s_add_i32 m0, s46, 0x2000
	s_add_u32 s14, s14, 0x40080
	v_lshl_add_u64 v[144:145], v[166:167], 0, s[8:9]
	s_addc_u32 s15, s15, 0
	s_add_i32 s46, s84, s31
	global_load_lds_dwordx4 v[144:145], off
	v_lshl_add_u64 v[144:145], s[14:15], 0, v[148:149]
	s_mov_b32 m0, s46
	s_nop 0
	global_load_lds_dwordx4 v[144:145], off
	v_lshl_add_u64 v[144:145], s[14:15], 0, v[152:153]
	s_add_i32 m0, s46, 0x2000
	s_nop 0
	global_load_lds_dwordx4 v[144:145], off
	v_lshl_add_u64 v[144:145], v[212:213], 0, s[8:9]
	s_mov_b32 m0, s59
	s_nop 0
	global_load_lds_dwordx4 v[144:145], off
	v_lshl_add_u64 v[144:145], v[214:215], 0, s[8:9]
	s_mov_b32 m0, s71
	s_nop 0
	global_load_lds_dwordx4 v[144:145], off
	s_waitcnt vmcnt(8)
	s_waitcnt lgkmcnt(0)
	s_barrier
	s_waitcnt lgkmcnt(0)
	v_mfma_f32_16x16x32_bf16 v[92:95], v[128:131], v[180:183], v[92:95]
	v_mfma_f32_16x16x32_bf16 v[88:91], v[136:139], v[180:183], v[88:91]
	v_mfma_f32_16x16x32_bf16 v[84:87], v[128:131], v[188:191], v[84:87]
	v_mfma_f32_16x16x32_bf16 v[80:83], v[136:139], v[188:191], v[80:83]
	v_mfma_f32_16x16x32_bf16 v[76:79], v[128:131], v[196:199], v[76:79]
	v_mfma_f32_16x16x32_bf16 v[72:75], v[136:139], v[196:199], v[72:75]
	v_mfma_f32_16x16x32_bf16 v[68:71], v[128:131], v[204:207], v[68:71]
	v_mfma_f32_16x16x32_bf16 v[64:67], v[136:139], v[204:207], v[64:67]
	v_mfma_f32_16x16x32_bf16 v[92:95], v[132:135], v[184:187], v[92:95]
	v_mfma_f32_16x16x32_bf16 v[88:91], v[140:143], v[184:187], v[88:91]
	v_mfma_f32_16x16x32_bf16 v[84:87], v[132:135], v[192:195], v[84:87]
	v_mfma_f32_16x16x32_bf16 v[80:83], v[140:143], v[192:195], v[80:83]
	v_mfma_f32_16x16x32_bf16 v[76:79], v[132:135], v[200:203], v[76:79]
	v_mfma_f32_16x16x32_bf16 v[72:75], v[140:143], v[200:203], v[72:75]
	v_mfma_f32_16x16x32_bf16 v[68:71], v[132:135], v[208:211], v[68:71]
	v_mfma_f32_16x16x32_bf16 v[64:67], v[140:143], v[208:211], v[64:67]
	v_mfma_f32_16x16x32_bf16 v[28:31], v[158:161], v[180:183], v[28:31]
	v_mfma_f32_16x16x32_bf16 v[24:27], v[172:175], v[180:183], v[24:27]
	v_mfma_f32_16x16x32_bf16 v[20:23], v[158:161], v[188:191], v[20:23]
	v_mfma_f32_16x16x32_bf16 v[16:19], v[172:175], v[188:191], v[16:19]
	v_mfma_f32_16x16x32_bf16 v[12:15], v[158:161], v[196:199], v[12:15]
	v_mfma_f32_16x16x32_bf16 v[8:11], v[172:175], v[196:199], v[8:11]
	v_mfma_f32_16x16x32_bf16 v[4:7], v[158:161], v[204:207], v[4:7]
	v_mfma_f32_16x16x32_bf16 v[0:3], v[172:175], v[204:207], v[0:3]
	v_mfma_f32_16x16x32_bf16 v[28:31], v[162:165], v[184:187], v[28:31]
	v_mfma_f32_16x16x32_bf16 v[24:27], v[176:179], v[184:187], v[24:27]
	v_mfma_f32_16x16x32_bf16 v[20:23], v[162:165], v[192:195], v[20:23]
	v_mfma_f32_16x16x32_bf16 v[16:19], v[176:179], v[192:195], v[16:19]
	v_mfma_f32_16x16x32_bf16 v[12:15], v[162:165], v[200:203], v[12:15]
	v_mfma_f32_16x16x32_bf16 v[8:11], v[176:179], v[200:203], v[8:11]
	v_mfma_f32_16x16x32_bf16 v[4:7], v[162:165], v[208:211], v[4:7]
	v_mfma_f32_16x16x32_bf16 v[0:3], v[176:179], v[208:211], v[0:3]
	s_barrier
	s_add_u32 s52, s52, 0x100
	s_addc_u32 s53, s53, 0
	s_add_u32 s80, s80, 0x100
	s_addc_u32 s81, s81, 0
	s_cmp_ge_u32 s82, s78
	s_mov_b32 s14, s82
	s_cbranch_scc0 .LBB0_2574

; #define G_STAGE(bufoff, gbase, voff) do { _Pragma("unroll") for (int _i = 0; _i < 2; ++_i) \
;         __builtin_amdgcn_global_load_lds((const unsigned*)((const char*)(gbase) + voff[_i]), (LAS unsigned*)(lds + (bufoff) + ldsw + _i * 8192), 16, 0, 0); } while (0)
; #define G_LDA(dst, b, h) do { _Pragma("unroll") for (int m = 0; m < 4; ++m) _Pragma("unroll") for (int k = 0; k < 2; ++k) dst[m][k] = *(const LAS bf16x8*)(lds + G_SA(b, h) + aoff + m * 2048 + k * 1024); } while (0)
; #define G_LDB(dst, b, h) do { _Pragma("unroll") for (int n = 0; n < 2; ++n) _Pragma("unroll") for (int k = 0; k < 2; ++k) dst[n][k] = *(const LAS bf16x8*)(lds + G_SB(b, h) + boff + n * 2048 + k * 1024); } while (0)
; #define G_MMA(ai, bj, At_, Bt_) do { __builtin_amdgcn_s_setprio(1); _Pragma("unroll") for (int m = 0; m < 4; ++m) _Pragma("unroll") for (int n = 0; n < 2; ++n) _Pragma("unroll") for (int k = 0; k < 2; ++k) \
;         acc[ai][bj][m][n] = __builtin_amdgcn_mfma_f32_16x16x32_bf16(Bt_[n][k], At_[m][k], acc[ai][bj][m][n], 0, 0, 0); __builtin_amdgcn_s_setprio(0); } while (0)
; #define WAIT_V(n) asm volatile("s_waitcnt vmcnt(" #n ")" ::: "memory")
; #define WAIT_L(n) asm volatile("s_waitcnt lgkmcnt(" #n ")" ::: "memory")
; #define BAR __builtin_amdgcn_s_barrier()
; #define SCHED __builtin_amdgcn_sched_barrier(0)
; template <class Get, class Epi>
; DI void gemm_loop(int ntiles, int ld, char* shm, const Get& get, const Epi& epi) {
;     ...
;             G_LDB(B0, 0, 0); G_LDB(B1, 0, 1); SCHED; G_LDA(At, 0, 0); G_STAGE(G_SA(1, 1), a1 + hstep, voffA);
;             WAIT_V(8); WAIT_L(0); BAR; G_MMA(0, 0, At, B0); G_MMA(0, 1, At, B1); BAR; SCHED;
;             G_LDA(At, 0, 1); G_STAGE(G_SB(0, 0), b2, voffB); G_STAGE(G_SB(0, 1), b2 + hstep, voffB); G_STAGE(G_SA(0, 0), a2, voffA);
.Lrj_2892_0:
	s_waitcnt lgkmcnt(0)
	s_barrier
	s_waitcnt lgkmcnt(0)
	v_mfma_f32_16x16x32_bf16 v[124:127], v[128:131], v[180:183], 0
	v_mfma_f32_16x16x32_bf16 v[120:123], v[136:139], v[180:183], 0
	v_mfma_f32_16x16x32_bf16 v[116:119], v[128:131], v[188:191], 0
	v_mfma_f32_16x16x32_bf16 v[112:115], v[136:139], v[188:191], 0
	v_mfma_f32_16x16x32_bf16 v[108:111], v[128:131], v[196:199], 0
	v_mfma_f32_16x16x32_bf16 v[104:107], v[136:139], v[196:199], 0
	v_mfma_f32_16x16x32_bf16 v[100:103], v[128:131], v[204:207], 0
	v_mfma_f32_16x16x32_bf16 v[96:99], v[136:139], v[204:207], 0
	v_mfma_f32_16x16x32_bf16 v[124:127], v[132:135], v[184:187], v[124:127]
	v_mfma_f32_16x16x32_bf16 v[120:123], v[140:143], v[184:187], v[120:123]
	v_mfma_f32_16x16x32_bf16 v[116:119], v[132:135], v[192:195], v[116:119]
	v_mfma_f32_16x16x32_bf16 v[112:115], v[140:143], v[192:195], v[112:115]
	v_mfma_f32_16x16x32_bf16 v[108:111], v[132:135], v[200:203], v[108:111]
	v_mfma_f32_16x16x32_bf16 v[104:107], v[140:143], v[200:203], v[104:107]
	v_mfma_f32_16x16x32_bf16 v[100:103], v[132:135], v[208:211], v[100:103]
	v_mfma_f32_16x16x32_bf16 v[96:99], v[140:143], v[208:211], v[96:99]
	v_mfma_f32_16x16x32_bf16 v[60:63], v[158:161], v[180:183], 0
	v_mfma_f32_16x16x32_bf16 v[56:59], v[172:175], v[180:183], 0
	v_mfma_f32_16x16x32_bf16 v[52:55], v[158:161], v[188:191], 0
	v_mfma_f32_16x16x32_bf16 v[48:51], v[172:175], v[188:191], 0
	v_mfma_f32_16x16x32_bf16 v[44:47], v[158:161], v[196:199], 0
	v_mfma_f32_16x16x32_bf16 v[40:43], v[172:175], v[196:199], 0
	v_mfma_f32_16x16x32_bf16 v[36:39], v[158:161], v[204:207], 0
	v_mfma_f32_16x16x32_bf16 v[32:35], v[172:175], v[204:207], 0
	v_mfma_f32_16x16x32_bf16 v[60:63], v[162:165], v[184:187], v[60:63]
	v_mfma_f32_16x16x32_bf16 v[56:59], v[176:179], v[184:187], v[56:59]
	v_mfma_f32_16x16x32_bf16 v[52:55], v[162:165], v[192:195], v[52:55]
	v_mfma_f32_16x16x32_bf16 v[48:51], v[176:179], v[192:195], v[48:51]
	v_mfma_f32_16x16x32_bf16 v[44:47], v[162:165], v[200:203], v[44:47]
	v_mfma_f32_16x16x32_bf16 v[40:43], v[176:179], v[200:203], v[40:43]
	v_mfma_f32_16x16x32_bf16 v[36:39], v[162:165], v[208:211], v[36:39]
	v_mfma_f32_16x16x32_bf16 v[32:35], v[176:179], v[208:211], v[32:35]
	s_barrier
	s_add_i32 s4, s58, s48
	v_lshl_add_u64 v[144:145], s[44:45], 0, v[148:149]
	s_mov_b32 m0, s4
	ds_read_b128 v[180:183], v171 offset:16384
	ds_read_b128 v[184:187], v171 offset:17408
	ds_read_b128 v[188:191], v171 offset:18432
	ds_read_b128 v[192:195], v171 offset:19456
	ds_read_b128 v[196:199], v171 offset:20480
	ds_read_b128 v[200:203], v171 offset:21504
	ds_read_b128 v[204:207], v171 offset:22528
	ds_read_b128 v[208:211], v171 offset:23552
	global_load_lds_dwordx4 v[144:145], off
	s_add_i32 m0, s4, 0x2000
	s_add_u32 s4, s44, 0xb0000
	v_lshl_add_u64 v[166:167], s[44:45], 0, v[152:153]
	s_addc_u32 s5, s45, 0
	s_add_i32 s84, s59, s48
	global_load_lds_dwordx4 v[166:167], off
	v_lshl_add_u64 v[212:213], s[4:5], 0, v[148:149]
	s_mov_b32 m0, s84
	v_lshl_add_u64 v[214:215], s[46:47], 0, v[150:151]
	global_load_lds_dwordx4 v[212:213], off
	v_lshl_add_u64 v[212:213], s[4:5], 0, v[152:153]
	s_add_i32 m0, s84, 0x2000
	s_nop 0
	global_load_lds_dwordx4 v[212:213], off
	v_lshl_add_u64 v[212:213], s[46:47], 0, v[146:147]
	s_mov_b32 m0, s49
	s_nop 0
	global_load_lds_dwordx4 v[212:213], off
	s_mov_b32 m0, s50
	s_nop 0
	global_load_lds_dwordx4 v[214:215], off
	s_cmp_lg_u32 s100, 0
	s_cbranch_scc0 .Lrf_2892_1
	s_waitcnt vmcnt(16)
	s_branch .Lrj_2892_1

; #define G_STAGE(bufoff, gbase, voff) do { _Pragma("unroll") for (int _i = 0; _i < 2; ++_i) \
;         __builtin_amdgcn_global_load_lds((const unsigned*)((const char*)(gbase) + voff[_i]), (LAS unsigned*)(lds + (bufoff) + ldsw + _i * 8192), 16, 0, 0); } while (0)
; #define G_LDA(dst, b, h) do { _Pragma("unroll") for (int m = 0; m < 4; ++m) _Pragma("unroll") for (int k = 0; k < 2; ++k) dst[m][k] = *(const LAS bf16x8*)(lds + G_SA(b, h) + aoff + m * 2048 + k * 1024); } while (0)
; #define G_LDB(dst, b, h) do { _Pragma("unroll") for (int n = 0; n < 2; ++n) _Pragma("unroll") for (int k = 0; k < 2; ++k) dst[n][k] = *(const LAS bf16x8*)(lds + G_SB(b, h) + boff + n * 2048 + k * 1024); } while (0)
; #define G_MMA(ai, bj, At_, Bt_) do { __builtin_amdgcn_s_setprio(1); _Pragma("unroll") for (int m = 0; m < 4; ++m) _Pragma("unroll") for (int n = 0; n < 2; ++n) _Pragma("unroll") for (int k = 0; k < 2; ++k) \
;         acc[ai][bj][m][n] = __builtin_amdgcn_mfma_f32_16x16x32_bf16(Bt_[n][k], At_[m][k], acc[ai][bj][m][n], 0, 0, 0); __builtin_amdgcn_s_setprio(0); } while (0)
; #define WAIT_V(n) asm volatile("s_waitcnt vmcnt(" #n ")" ::: "memory")
; #define WAIT_L(n) asm volatile("s_waitcnt lgkmcnt(" #n ")" ::: "memory")
; #define BAR __builtin_amdgcn_s_barrier()
; #define SCHED __builtin_amdgcn_sched_barrier(0)
; template <class Get, class Epi>
; DI void gemm_loop(int ntiles, int ld, char* shm, const Get& get, const Epi& epi) {
;     ...
;             WAIT_V(8); WAIT_L(0); BAR; G_MMA(1, 0, At, B0); G_MMA(1, 1, At, B1); BAR; SCHED;
;             G_LDB(B0, 1, 0); G_LDB(B1, 1, 1); SCHED; G_LDA(At, 1, 0); G_STAGE(G_SA(0, 1), a2 + hstep, voffA);
;             WAIT_V(8); WAIT_L(0); BAR; G_MMA(0, 0, At, B0); G_MMA(0, 1, At, B1); BAR; SCHED;
;             G_LDA(At, 1, 1); G_STAGE(G_SB(1, 0), b3, voffB); G_STAGE(G_SB(1, 1), b3 + hstep, voffB); G_STAGE(G_SA(1, 0), a3, voffA);
;             WAIT_V(8); WAIT_L(0); BAR; G_MMA(1, 0, At, B0); G_MMA(1, 1, At, B1); BAR; SCHED;
.Lrj_2892_1:
	s_waitcnt lgkmcnt(0)
	s_barrier
	s_waitcnt lgkmcnt(0)
	v_mfma_f32_16x16x32_bf16 v[92:95], v[128:131], v[180:183], 0
	v_mfma_f32_16x16x32_bf16 v[88:91], v[136:139], v[180:183], 0
	v_mfma_f32_16x16x32_bf16 v[84:87], v[128:131], v[188:191], 0
	v_mfma_f32_16x16x32_bf16 v[80:83], v[136:139], v[188:191], 0
	v_mfma_f32_16x16x32_bf16 v[76:79], v[128:131], v[196:199], 0
	v_mfma_f32_16x16x32_bf16 v[72:75], v[136:139], v[196:199], 0
	v_mfma_f32_16x16x32_bf16 v[68:71], v[128:131], v[204:207], 0
	v_mfma_f32_16x16x32_bf16 v[64:67], v[136:139], v[204:207], 0
	v_mfma_f32_16x16x32_bf16 v[92:95], v[132:135], v[184:187], v[92:95]
	v_mfma_f32_16x16x32_bf16 v[88:91], v[140:143], v[184:187], v[88:91]
	v_mfma_f32_16x16x32_bf16 v[84:87], v[132:135], v[192:195], v[84:87]
	v_mfma_f32_16x16x32_bf16 v[80:83], v[140:143], v[192:195], v[80:83]
	v_mfma_f32_16x16x32_bf16 v[76:79], v[132:135], v[200:203], v[76:79]
	v_mfma_f32_16x16x32_bf16 v[72:75], v[140:143], v[200:203], v[72:75]
	v_mfma_f32_16x16x32_bf16 v[68:71], v[132:135], v[208:211], v[68:71]
	v_mfma_f32_16x16x32_bf16 v[64:67], v[140:143], v[208:211], v[64:67]
	v_mfma_f32_16x16x32_bf16 v[28:31], v[158:161], v[180:183], 0
	v_mfma_f32_16x16x32_bf16 v[24:27], v[172:175], v[180:183], 0
	v_mfma_f32_16x16x32_bf16 v[20:23], v[158:161], v[188:191], 0
	v_mfma_f32_16x16x32_bf16 v[16:19], v[172:175], v[188:191], 0
	v_mfma_f32_16x16x32_bf16 v[12:15], v[158:161], v[196:199], 0
	v_mfma_f32_16x16x32_bf16 v[8:11], v[172:175], v[196:199], 0
	v_mfma_f32_16x16x32_bf16 v[4:7], v[158:161], v[204:207], 0
	v_mfma_f32_16x16x32_bf16 v[0:3], v[172:175], v[204:207], 0
	v_mfma_f32_16x16x32_bf16 v[28:31], v[162:165], v[184:187], v[28:31]
	v_mfma_f32_16x16x32_bf16 v[24:27], v[176:179], v[184:187], v[24:27]
	v_mfma_f32_16x16x32_bf16 v[20:23], v[162:165], v[192:195], v[20:23]
	v_mfma_f32_16x16x32_bf16 v[16:19], v[176:179], v[192:195], v[16:19]
	v_mfma_f32_16x16x32_bf16 v[12:15], v[162:165], v[200:203], v[12:15]
	v_mfma_f32_16x16x32_bf16 v[8:11], v[176:179], v[200:203], v[8:11]
	v_mfma_f32_16x16x32_bf16 v[4:7], v[162:165], v[208:211], v[4:7]
	v_mfma_f32_16x16x32_bf16 v[0:3], v[176:179], v[208:211], v[0:3]
	s_barrier
	s_add_i32 s84, 0, 0x18000
	s_add_i32 s85, 0, 0x1c000
	v_add_u32_e32 v140, s84, v168
	v_add_u32_e32 v176, s85, v168
	ds_read_b128 v[128:131], v140
	ds_read_b128 v[132:135], v140 offset:1024
	ds_read_b128 v[136:139], v140 offset:2048
	ds_read_b128 v[140:143], v140 offset:3072
	ds_read_b128 v[158:161], v176
	ds_read_b128 v[162:165], v176 offset:1024
	ds_read_b128 v[172:175], v176 offset:2048
	ds_read_b128 v[176:179], v176 offset:3072
	s_add_u32 s4, s46, 0xb0000
	s_addc_u32 s5, s47, 0
	s_mov_b32 m0, s51
	v_lshl_add_u64 v[216:217], s[4:5], 0, v[146:147]
	ds_read_b128 v[180:183], v171 offset:32768
	ds_read_b128 v[184:187], v171 offset:33792
	ds_read_b128 v[188:191], v171 offset:34816
	ds_read_b128 v[192:195], v171 offset:35840
	ds_read_b128 v[196:199], v171 offset:36864
	ds_read_b128 v[200:203], v171 offset:37888
	ds_read_b128 v[204:207], v171 offset:38912
	ds_read_b128 v[208:211], v171 offset:39936
	global_load_lds_dwordx4 v[216:217], off
	v_lshl_add_u64 v[216:217], s[4:5], 0, v[150:151]
	s_mov_b32 m0, s52
	s_nop 0
	global_load_lds_dwordx4 v[216:217], off
	s_waitcnt vmcnt(8)
	s_waitcnt lgkmcnt(0)
	s_barrier
	s_waitcnt lgkmcnt(0)
	v_mfma_f32_16x16x32_bf16 v[124:127], v[128:131], v[180:183], v[124:127]
	v_mfma_f32_16x16x32_bf16 v[120:123], v[136:139], v[180:183], v[120:123]
	v_mfma_f32_16x16x32_bf16 v[116:119], v[128:131], v[188:191], v[116:119]
	v_mfma_f32_16x16x32_bf16 v[112:115], v[136:139], v[188:191], v[112:115]
	v_mfma_f32_16x16x32_bf16 v[108:111], v[128:131], v[196:199], v[108:111]
	v_mfma_f32_16x16x32_bf16 v[104:107], v[136:139], v[196:199], v[104:107]
	v_mfma_f32_16x16x32_bf16 v[100:103], v[128:131], v[204:207], v[100:103]
	v_mfma_f32_16x16x32_bf16 v[96:99], v[136:139], v[204:207], v[96:99]
	v_mfma_f32_16x16x32_bf16 v[124:127], v[132:135], v[184:187], v[124:127]
	v_mfma_f32_16x16x32_bf16 v[120:123], v[140:143], v[184:187], v[120:123]
	v_mfma_f32_16x16x32_bf16 v[116:119], v[132:135], v[192:195], v[116:119]
	v_mfma_f32_16x16x32_bf16 v[112:115], v[140:143], v[192:195], v[112:115]
	v_mfma_f32_16x16x32_bf16 v[108:111], v[132:135], v[200:203], v[108:111]
	v_mfma_f32_16x16x32_bf16 v[104:107], v[140:143], v[200:203], v[104:107]
	v_mfma_f32_16x16x32_bf16 v[100:103], v[132:135], v[208:211], v[100:103]
	v_mfma_f32_16x16x32_bf16 v[96:99], v[140:143], v[208:211], v[96:99]
	v_mfma_f32_16x16x32_bf16 v[60:63], v[158:161], v[180:183], v[60:63]
	v_mfma_f32_16x16x32_bf16 v[56:59], v[172:175], v[180:183], v[56:59]
	v_mfma_f32_16x16x32_bf16 v[52:55], v[158:161], v[188:191], v[52:55]
	v_mfma_f32_16x16x32_bf16 v[48:51], v[172:175], v[188:191], v[48:51]
	v_mfma_f32_16x16x32_bf16 v[44:47], v[158:161], v[196:199], v[44:47]
	v_mfma_f32_16x16x32_bf16 v[40:43], v[172:175], v[196:199], v[40:43]
	v_mfma_f32_16x16x32_bf16 v[36:39], v[158:161], v[204:207], v[36:39]
	v_mfma_f32_16x16x32_bf16 v[32:35], v[172:175], v[204:207], v[32:35]
	v_mfma_f32_16x16x32_bf16 v[60:63], v[162:165], v[184:187], v[60:63]
	v_mfma_f32_16x16x32_bf16 v[56:59], v[176:179], v[184:187], v[56:59]
	v_mfma_f32_16x16x32_bf16 v[52:55], v[162:165], v[192:195], v[52:55]
	v_mfma_f32_16x16x32_bf16 v[48:51], v[176:179], v[192:195], v[48:51]
	v_mfma_f32_16x16x32_bf16 v[44:47], v[162:165], v[200:203], v[44:47]
	v_mfma_f32_16x16x32_bf16 v[40:43], v[176:179], v[200:203], v[40:43]
	v_mfma_f32_16x16x32_bf16 v[36:39], v[162:165], v[208:211], v[36:39]
	v_mfma_f32_16x16x32_bf16 v[32:35], v[176:179], v[208:211], v[32:35]
	s_barrier
; #define G_STAGE(bufoff, gbase, voff) do { _Pragma("unroll") for (int _i = 0; _i < 2; ++_i) \
;         __builtin_amdgcn_global_load_lds((const unsigned*)((const char*)(gbase) + voff[_i]), (LAS unsigned*)(lds + (bufoff) + ldsw + _i * 8192), 16, 0, 0); } while (0)
; #define G_LDA(dst, b, h) do { _Pragma("unroll") for (int m = 0; m < 4; ++m) _Pragma("unroll") for (int k = 0; k < 2; ++k) dst[m][k] = *(const LAS bf16x8*)(lds + G_SA(b, h) + aoff + m * 2048 + k * 1024); } while (0)
; #define G_LDB(dst, b, h) do { _Pragma("unroll") for (int n = 0; n < 2; ++n) _Pragma("unroll") for (int k = 0; k < 2; ++k) dst[n][k] = *(const LAS bf16x8*)(lds + G_SB(b, h) + boff + n * 2048 + k * 1024); } while (0)
; #define WAIT_V(n) asm volatile("s_waitcnt vmcnt(" #n ")" ::: "memory")
; #define WAIT_L(n) asm volatile("s_waitcnt lgkmcnt(" #n ")" ::: "memory")
; #define BAR __builtin_amdgcn_s_barrier()
; #define SCHED __builtin_amdgcn_sched_barrier(0)
; template <class Get, class Epi>
; DI void gemm_loop(int ntiles, int ld, char* shm, const Get& get, const Epi& epi) {
;     ...
;         for (int t = 0; t < nt; t += 2) {
;             const bool last = (t == nt - 2);
;             const char* a1 = cA + (size_t)(t + 1) * kstep;
;             const char* a2 = last ? nA : cA + (size_t)(t + 2) * kstep; const char* b2 = last ? nB : cB + (size_t)(t + 2) * kstep;
;             const char* a3 = a2 + kstep; const char* b3 = b2 + kstep;
;             G_LDB(B0, 0, 0); G_LDB(B1, 0, 1); SCHED; G_LDA(At, 0, 0); G_STAGE(G_SA(1, 1), a1 + hstep, voffA);
;             WAIT_V(8); WAIT_L(0); BAR; G_MMA(0, 0, At, B0); G_MMA(0, 1, At, B1); BAR; SCHED;
;             G_LDA(At, 0, 1); G_STAGE(G_SB(0, 0), b2, voffB); G_STAGE(G_SB(0, 1), b2 + hstep, voffB); G_STAGE(G_SA(0, 0), a2, voffA);
;             WAIT_V(8); WAIT_L(0); BAR; G_MMA(1, 0, At, B0); G_MMA(1, 1, At, B1); BAR; SCHED;
;             G_LDB(B0, 1, 0); G_LDB(B1, 1, 1); SCHED; G_LDA(At, 1, 0); G_STAGE(G_SA(0, 1), a2 + hstep, voffA);
;             WAIT_V(8); WAIT_L(0); BAR; G_MMA(0, 0, At, B0); G_MMA(0, 1, At, B1); BAR; SCHED;
;             G_LDA(At, 1, 1); G_STAGE(G_SB(1, 0), b3, voffB); G_STAGE(G_SB(1, 1), b3 + hstep, voffB); G_STAGE(G_SA(1, 0), a3, voffA);
;             WAIT_V(8); WAIT_L(0); BAR; G_MMA(1, 0, At, B0); G_MMA(1, 1, At, B1); BAR; SCHED;
	s_add_i32 s4, s84, s48
	v_lshl_add_u64 v[144:145], v[144:145], 0, s[10:11]
	s_mov_b32 m0, s4
	ds_read_b128 v[180:183], v171 offset:49152
	ds_read_b128 v[184:187], v171 offset:50176
	ds_read_b128 v[188:191], v171 offset:51200
	ds_read_b128 v[192:195], v171 offset:52224
	ds_read_b128 v[196:199], v171 offset:53248
	ds_read_b128 v[200:203], v171 offset:54272
	ds_read_b128 v[204:207], v171 offset:55296
	ds_read_b128 v[208:211], v171 offset:56320
	global_load_lds_dwordx4 v[144:145], off
	s_add_i32 m0, s4, 0x2000
	s_add_u32 s4, s44, 0xb0080
	v_lshl_add_u64 v[144:145], v[166:167], 0, s[10:11]
	s_addc_u32 s5, s45, 0
	s_add_i32 s44, s85, s48
	global_load_lds_dwordx4 v[144:145], off
	v_lshl_add_u64 v[144:145], s[4:5], 0, v[148:149]
	s_mov_b32 m0, s44
	s_nop 0
	global_load_lds_dwordx4 v[144:145], off
	v_lshl_add_u64 v[144:145], s[4:5], 0, v[152:153]
	s_add_i32 m0, s44, 0x2000
	s_nop 0
	global_load_lds_dwordx4 v[144:145], off
	v_lshl_add_u64 v[144:145], v[212:213], 0, s[10:11]
	s_mov_b32 m0, s55
	s_nop 0
	global_load_lds_dwordx4 v[144:145], off
	v_lshl_add_u64 v[144:145], v[214:215], 0, s[10:11]
	s_mov_b32 m0, s56
	s_nop 0
	global_load_lds_dwordx4 v[144:145], off
	s_waitcnt vmcnt(8)
	s_waitcnt lgkmcnt(0)
	s_barrier
	s_waitcnt lgkmcnt(0)
	v_mfma_f32_16x16x32_bf16 v[92:95], v[128:131], v[180:183], v[92:95]
	v_mfma_f32_16x16x32_bf16 v[88:91], v[136:139], v[180:183], v[88:91]
	v_mfma_f32_16x16x32_bf16 v[84:87], v[128:131], v[188:191], v[84:87]
	v_mfma_f32_16x16x32_bf16 v[80:83], v[136:139], v[188:191], v[80:83]
	v_mfma_f32_16x16x32_bf16 v[76:79], v[128:131], v[196:199], v[76:79]
	v_mfma_f32_16x16x32_bf16 v[72:75], v[136:139], v[196:199], v[72:75]
	v_mfma_f32_16x16x32_bf16 v[68:71], v[128:131], v[204:207], v[68:71]
	v_mfma_f32_16x16x32_bf16 v[64:67], v[136:139], v[204:207], v[64:67]
	v_mfma_f32_16x16x32_bf16 v[92:95], v[132:135], v[184:187], v[92:95]
	v_mfma_f32_16x16x32_bf16 v[88:91], v[140:143], v[184:187], v[88:91]
	v_mfma_f32_16x16x32_bf16 v[84:87], v[132:135], v[192:195], v[84:87]
	v_mfma_f32_16x16x32_bf16 v[80:83], v[140:143], v[192:195], v[80:83]
	v_mfma_f32_16x16x32_bf16 v[76:79], v[132:135], v[200:203], v[76:79]
	v_mfma_f32_16x16x32_bf16 v[72:75], v[140:143], v[200:203], v[72:75]
	v_mfma_f32_16x16x32_bf16 v[68:71], v[132:135], v[208:211], v[68:71]
	v_mfma_f32_16x16x32_bf16 v[64:67], v[140:143], v[208:211], v[64:67]
	v_mfma_f32_16x16x32_bf16 v[28:31], v[158:161], v[180:183], v[28:31]
	v_mfma_f32_16x16x32_bf16 v[24:27], v[172:175], v[180:183], v[24:27]
	v_mfma_f32_16x16x32_bf16 v[20:23], v[158:161], v[188:191], v[20:23]
	v_mfma_f32_16x16x32_bf16 v[16:19], v[172:175], v[188:191], v[16:19]
	v_mfma_f32_16x16x32_bf16 v[12:15], v[158:161], v[196:199], v[12:15]
	v_mfma_f32_16x16x32_bf16 v[8:11], v[172:175], v[196:199], v[8:11]
	v_mfma_f32_16x16x32_bf16 v[4:7], v[158:161], v[204:207], v[4:7]
	v_mfma_f32_16x16x32_bf16 v[0:3], v[172:175], v[204:207], v[0:3]
	v_mfma_f32_16x16x32_bf16 v[28:31], v[162:165], v[184:187], v[28:31]
	v_mfma_f32_16x16x32_bf16 v[24:27], v[176:179], v[184:187], v[24:27]
	v_mfma_f32_16x16x32_bf16 v[20:23], v[162:165], v[192:195], v[20:23]
	v_mfma_f32_16x16x32_bf16 v[16:19], v[176:179], v[192:195], v[16:19]
	v_mfma_f32_16x16x32_bf16 v[12:15], v[162:165], v[200:203], v[12:15]
	v_mfma_f32_16x16x32_bf16 v[8:11], v[176:179], v[200:203], v[8:11]
	v_mfma_f32_16x16x32_bf16 v[4:7], v[162:165], v[208:211], v[4:7]
	v_mfma_f32_16x16x32_bf16 v[0:3], v[176:179], v[208:211], v[0:3]
	s_barrier
	s_add_u32 s81, s81, 0x100
	s_addc_u32 s82, s82, 0
	s_cmp_ge_u32 s83, s79
	s_mov_b64 s[4:5], s[14:15]
	s_mov_b32 s44, s83
	s_cbranch_scc0 .LBB0_2892
	s_branch .Lpost_2892
.LBB0_2892:
	ds_read_b128 v[128:131], v169
	ds_read_b128 v[132:135], v169 offset:1024
	ds_read_b128 v[136:139], v169 offset:2048
	ds_read_b128 v[140:143], v169 offset:3072
	ds_read_b128 v[158:161], v170
	ds_read_b128 v[162:165], v170 offset:1024
	ds_read_b128 v[172:175], v170 offset:2048
	ds_read_b128 v[176:179], v170 offset:3072
	s_add_i32 s83, s44, 2
	s_add_u32 s14, s4, 0x100
	s_addc_u32 s15, s5, 0
	s_cmp_eq_u32 s80, s44
	s_cselect_b32 s44, s42, s81
	s_cselect_b32 s47, s41, s15
	s_cselect_b32 s46, s40, s14
	s_cselect_b32 s45, s43, s82
	v_lshl_add_u64 v[144:145], s[4:5], 0, v[154:155]
	s_add_i32 m0, s49, 0xc000
	ds_read_b128 v[180:183], v171
	ds_read_b128 v[184:187], v171 offset:1024
	ds_read_b128 v[188:191], v171 offset:2048
	ds_read_b128 v[192:195], v171 offset:3072
	ds_read_b128 v[196:199], v171 offset:4096
	ds_read_b128 v[200:203], v171 offset:5120
	ds_read_b128 v[204:207], v171 offset:6144
	ds_read_b128 v[208:211], v171 offset:7168
	global_load_lds_dwordx4 v[144:145], off
	v_lshl_add_u64 v[144:145], s[4:5], 0, v[156:157]
	s_add_i32 m0, s49, 0xe000
	s_nop 0
	global_load_lds_dwordx4 v[144:145], off
	s_waitcnt vmcnt(8)
	s_waitcnt lgkmcnt(0)
	s_barrier
; #define G_STAGE(bufoff, gbase, voff) do { _Pragma("unroll") for (int _i = 0; _i < 2; ++_i) \
;         __builtin_amdgcn_global_load_lds((const unsigned*)((const char*)(gbase) + voff[_i]), (LAS unsigned*)(lds + (bufoff) + ldsw + _i * 8192), 16, 0, 0); } while (0)
; #define G_LDA(dst, b, h) do { _Pragma("unroll") for (int m = 0; m < 4; ++m) _Pragma("unroll") for (int k = 0; k < 2; ++k) dst[m][k] = *(const LAS bf16x8*)(lds + G_SA(b, h) + aoff + m * 2048 + k * 1024); } while (0)
; #define G_LDB(dst, b, h) do { _Pragma("unroll") for (int n = 0; n < 2; ++n) _Pragma("unroll") for (int k = 0; k < 2; ++k) dst[n][k] = *(const LAS bf16x8*)(lds + G_SB(b, h) + boff + n * 2048 + k * 1024); } while (0)
; #define G_MMA(ai, bj, At_, Bt_) do { __builtin_amdgcn_s_setprio(1); _Pragma("unroll") for (int m = 0; m < 4; ++m) _Pragma("unroll") for (int n = 0; n < 2; ++n) _Pragma("unroll") for (int k = 0; k < 2; ++k) \
;         acc[ai][bj][m][n] = __builtin_amdgcn_mfma_f32_16x16x32_bf16(Bt_[n][k], At_[m][k], acc[ai][bj][m][n], 0, 0, 0); __builtin_amdgcn_s_setprio(0); } while (0)
; #define WAIT_V(n) asm volatile("s_waitcnt vmcnt(" #n ")" ::: "memory")
; #define WAIT_L(n) asm volatile("s_waitcnt lgkmcnt(" #n ")" ::: "memory")
; #define BAR __builtin_amdgcn_s_barrier()
; #define SCHED __builtin_amdgcn_sched_barrier(0)
; template <class Get, class Epi>
; DI void gemm_loop(int ntiles, int ld, char* shm, const Get& get, const Epi& epi) {
;     ...
;             G_LDB(B0, 0, 0); G_LDB(B1, 0, 1); SCHED; G_LDA(At, 0, 0); G_STAGE(G_SA(1, 1), a1 + hstep, voffA);
;             WAIT_V(8); WAIT_L(0); BAR; G_MMA(0, 0, At, B0); G_MMA(0, 1, At, B1); BAR; SCHED;
;             G_LDA(At, 0, 1); G_STAGE(G_SB(0, 0), b2, voffB); G_STAGE(G_SB(0, 1), b2 + hstep, voffB); G_STAGE(G_SA(0, 0), a2, voffA);
;             WAIT_V(8); WAIT_L(0); BAR; G_MMA(1, 0, At, B0); G_MMA(1, 1, At, B1); BAR; SCHED;
	s_waitcnt lgkmcnt(0)
	v_mfma_f32_16x16x32_bf16 v[124:127], v[128:131], v[180:183], v[124:127]
	v_mfma_f32_16x16x32_bf16 v[120:123], v[136:139], v[180:183], v[120:123]
	v_mfma_f32_16x16x32_bf16 v[116:119], v[128:131], v[188:191], v[116:119]
	v_mfma_f32_16x16x32_bf16 v[112:115], v[136:139], v[188:191], v[112:115]
	v_mfma_f32_16x16x32_bf16 v[108:111], v[128:131], v[196:199], v[108:111]
	v_mfma_f32_16x16x32_bf16 v[104:107], v[136:139], v[196:199], v[104:107]
	v_mfma_f32_16x16x32_bf16 v[100:103], v[128:131], v[204:207], v[100:103]
	v_mfma_f32_16x16x32_bf16 v[96:99], v[136:139], v[204:207], v[96:99]
	v_mfma_f32_16x16x32_bf16 v[124:127], v[132:135], v[184:187], v[124:127]
	v_mfma_f32_16x16x32_bf16 v[120:123], v[140:143], v[184:187], v[120:123]
	v_mfma_f32_16x16x32_bf16 v[116:119], v[132:135], v[192:195], v[116:119]
	v_mfma_f32_16x16x32_bf16 v[112:115], v[140:143], v[192:195], v[112:115]
	v_mfma_f32_16x16x32_bf16 v[108:111], v[132:135], v[200:203], v[108:111]
	v_mfma_f32_16x16x32_bf16 v[104:107], v[140:143], v[200:203], v[104:107]
	v_mfma_f32_16x16x32_bf16 v[100:103], v[132:135], v[208:211], v[100:103]
	v_mfma_f32_16x16x32_bf16 v[96:99], v[140:143], v[208:211], v[96:99]
	v_mfma_f32_16x16x32_bf16 v[60:63], v[158:161], v[180:183], v[60:63]
	v_mfma_f32_16x16x32_bf16 v[56:59], v[172:175], v[180:183], v[56:59]
	v_mfma_f32_16x16x32_bf16 v[52:55], v[158:161], v[188:191], v[52:55]
	v_mfma_f32_16x16x32_bf16 v[48:51], v[172:175], v[188:191], v[48:51]
	v_mfma_f32_16x16x32_bf16 v[44:47], v[158:161], v[196:199], v[44:47]
	v_mfma_f32_16x16x32_bf16 v[40:43], v[172:175], v[196:199], v[40:43]
	v_mfma_f32_16x16x32_bf16 v[36:39], v[158:161], v[204:207], v[36:39]
	v_mfma_f32_16x16x32_bf16 v[32:35], v[172:175], v[204:207], v[32:35]
	v_mfma_f32_16x16x32_bf16 v[60:63], v[162:165], v[184:187], v[60:63]
	v_mfma_f32_16x16x32_bf16 v[56:59], v[176:179], v[184:187], v[56:59]
	v_mfma_f32_16x16x32_bf16 v[52:55], v[162:165], v[192:195], v[52:55]
	v_mfma_f32_16x16x32_bf16 v[48:51], v[176:179], v[192:195], v[48:51]
	v_mfma_f32_16x16x32_bf16 v[44:47], v[162:165], v[200:203], v[44:47]
	v_mfma_f32_16x16x32_bf16 v[40:43], v[176:179], v[200:203], v[40:43]
	v_mfma_f32_16x16x32_bf16 v[36:39], v[162:165], v[208:211], v[36:39]
	v_mfma_f32_16x16x32_bf16 v[32:35], v[176:179], v[208:211], v[32:35]
	s_barrier
	s_add_i32 s4, s58, s48
	v_lshl_add_u64 v[144:145], s[44:45], 0, v[148:149]
	s_mov_b32 m0, s4
	ds_read_b128 v[180:183], v171 offset:16384
	ds_read_b128 v[184:187], v171 offset:17408
	ds_read_b128 v[188:191], v171 offset:18432
	ds_read_b128 v[192:195], v171 offset:19456
	ds_read_b128 v[196:199], v171 offset:20480
	ds_read_b128 v[200:203], v171 offset:21504
	ds_read_b128 v[204:207], v171 offset:22528
	ds_read_b128 v[208:211], v171 offset:23552
	global_load_lds_dwordx4 v[144:145], off
	s_add_i32 m0, s4, 0x2000
	s_add_u32 s4, s44, 0xb0000
	v_lshl_add_u64 v[166:167], s[44:45], 0, v[152:153]
	s_addc_u32 s5, s45, 0
	s_add_i32 s84, s59, s48
	global_load_lds_dwordx4 v[166:167], off
	v_lshl_add_u64 v[212:213], s[4:5], 0, v[148:149]
	s_mov_b32 m0, s84
	v_lshl_add_u64 v[214:215], s[46:47], 0, v[150:151]
	global_load_lds_dwordx4 v[212:213], off
	v_lshl_add_u64 v[212:213], s[4:5], 0, v[152:153]
	s_add_i32 m0, s84, 0x2000
	s_nop 0
	global_load_lds_dwordx4 v[212:213], off
	v_lshl_add_u64 v[212:213], s[46:47], 0, v[146:147]
	s_mov_b32 m0, s49
	s_nop 0
	global_load_lds_dwordx4 v[212:213], off
	s_mov_b32 m0, s50
	s_nop 0
	global_load_lds_dwordx4 v[214:215], off
	s_waitcnt vmcnt(8)
	s_waitcnt lgkmcnt(0)
	s_barrier
	s_waitcnt lgkmcnt(0)
	v_mfma_f32_16x16x32_bf16 v[92:95], v[128:131], v[180:183], v[92:95]
	v_mfma_f32_16x16x32_bf16 v[88:91], v[136:139], v[180:183], v[88:91]
	v_mfma_f32_16x16x32_bf16 v[84:87], v[128:131], v[188:191], v[84:87]
	v_mfma_f32_16x16x32_bf16 v[80:83], v[136:139], v[188:191], v[80:83]
	v_mfma_f32_16x16x32_bf16 v[76:79], v[128:131], v[196:199], v[76:79]
	v_mfma_f32_16x16x32_bf16 v[72:75], v[136:139], v[196:199], v[72:75]
	v_mfma_f32_16x16x32_bf16 v[68:71], v[128:131], v[204:207], v[68:71]
	v_mfma_f32_16x16x32_bf16 v[64:67], v[136:139], v[204:207], v[64:67]
	v_mfma_f32_16x16x32_bf16 v[92:95], v[132:135], v[184:187], v[92:95]
	v_mfma_f32_16x16x32_bf16 v[88:91], v[140:143], v[184:187], v[88:91]
	v_mfma_f32_16x16x32_bf16 v[84:87], v[132:135], v[192:195], v[84:87]
	v_mfma_f32_16x16x32_bf16 v[80:83], v[140:143], v[192:195], v[80:83]
	v_mfma_f32_16x16x32_bf16 v[76:79], v[132:135], v[200:203], v[76:79]
	v_mfma_f32_16x16x32_bf16 v[72:75], v[140:143], v[200:203], v[72:75]
	v_mfma_f32_16x16x32_bf16 v[68:71], v[132:135], v[208:211], v[68:71]
	v_mfma_f32_16x16x32_bf16 v[64:67], v[140:143], v[208:211], v[64:67]
	v_mfma_f32_16x16x32_bf16 v[28:31], v[158:161], v[180:183], v[28:31]
	v_mfma_f32_16x16x32_bf16 v[24:27], v[172:175], v[180:183], v[24:27]
	v_mfma_f32_16x16x32_bf16 v[20:23], v[158:161], v[188:191], v[20:23]
	v_mfma_f32_16x16x32_bf16 v[16:19], v[172:175], v[188:191], v[16:19]
	v_mfma_f32_16x16x32_bf16 v[12:15], v[158:161], v[196:199], v[12:15]
	v_mfma_f32_16x16x32_bf16 v[8:11], v[172:175], v[196:199], v[8:11]
	v_mfma_f32_16x16x32_bf16 v[4:7], v[158:161], v[204:207], v[4:7]
	v_mfma_f32_16x16x32_bf16 v[0:3], v[172:175], v[204:207], v[0:3]
	v_mfma_f32_16x16x32_bf16 v[28:31], v[162:165], v[184:187], v[28:31]
	v_mfma_f32_16x16x32_bf16 v[24:27], v[176:179], v[184:187], v[24:27]
	v_mfma_f32_16x16x32_bf16 v[20:23], v[162:165], v[192:195], v[20:23]
	v_mfma_f32_16x16x32_bf16 v[16:19], v[176:179], v[192:195], v[16:19]
	v_mfma_f32_16x16x32_bf16 v[12:15], v[162:165], v[200:203], v[12:15]
	v_mfma_f32_16x16x32_bf16 v[8:11], v[176:179], v[200:203], v[8:11]
	v_mfma_f32_16x16x32_bf16 v[4:7], v[162:165], v[208:211], v[4:7]
	v_mfma_f32_16x16x32_bf16 v[0:3], v[176:179], v[208:211], v[0:3]
	s_barrier
; #define G_STAGE(bufoff, gbase, voff) do { _Pragma("unroll") for (int _i = 0; _i < 2; ++_i) \
;         __builtin_amdgcn_global_load_lds((const unsigned*)((const char*)(gbase) + voff[_i]), (LAS unsigned*)(lds + (bufoff) + ldsw + _i * 8192), 16, 0, 0); } while (0)
; #define G_LDA(dst, b, h) do { _Pragma("unroll") for (int m = 0; m < 4; ++m) _Pragma("unroll") for (int k = 0; k < 2; ++k) dst[m][k] = *(const LAS bf16x8*)(lds + G_SA(b, h) + aoff + m * 2048 + k * 1024); } while (0)
; #define G_LDB(dst, b, h) do { _Pragma("unroll") for (int n = 0; n < 2; ++n) _Pragma("unroll") for (int k = 0; k < 2; ++k) dst[n][k] = *(const LAS bf16x8*)(lds + G_SB(b, h) + boff + n * 2048 + k * 1024); } while (0)
; #define G_MMA(ai, bj, At_, Bt_) do { __builtin_amdgcn_s_setprio(1); _Pragma("unroll") for (int m = 0; m < 4; ++m) _Pragma("unroll") for (int n = 0; n < 2; ++n) _Pragma("unroll") for (int k = 0; k < 2; ++k) \
;         acc[ai][bj][m][n] = __builtin_amdgcn_mfma_f32_16x16x32_bf16(Bt_[n][k], At_[m][k], acc[ai][bj][m][n], 0, 0, 0); __builtin_amdgcn_s_setprio(0); } while (0)
; #define WAIT_V(n) asm volatile("s_waitcnt vmcnt(" #n ")" ::: "memory")
; #define WAIT_L(n) asm volatile("s_waitcnt lgkmcnt(" #n ")" ::: "memory")
; #define BAR __builtin_amdgcn_s_barrier()
; #define SCHED __builtin_amdgcn_sched_barrier(0)
; template <class Get, class Epi>
; DI void gemm_loop(int ntiles, int ld, char* shm, const Get& get, const Epi& epi) {
;     ...
;             G_LDB(B0, 1, 0); G_LDB(B1, 1, 1); SCHED; G_LDA(At, 1, 0); G_STAGE(G_SA(0, 1), a2 + hstep, voffA);
;             WAIT_V(8); WAIT_L(0); BAR; G_MMA(0, 0, At, B0); G_MMA(0, 1, At, B1); BAR; SCHED;
;             G_LDA(At, 1, 1); G_STAGE(G_SB(1, 0), b3, voffB); G_STAGE(G_SB(1, 1), b3 + hstep, voffB); G_STAGE(G_SA(1, 0), a3, voffA);
;             WAIT_V(8); WAIT_L(0); BAR; G_MMA(1, 0, At, B0); G_MMA(1, 1, At, B1); BAR; SCHED;
	s_add_i32 s84, 0, 0x18000
	s_add_i32 s85, 0, 0x1c000
	v_add_u32_e32 v140, s84, v168
	v_add_u32_e32 v176, s85, v168
	ds_read_b128 v[128:131], v140
	ds_read_b128 v[132:135], v140 offset:1024
	ds_read_b128 v[136:139], v140 offset:2048
	ds_read_b128 v[140:143], v140 offset:3072
	ds_read_b128 v[158:161], v176
	ds_read_b128 v[162:165], v176 offset:1024
	ds_read_b128 v[172:175], v176 offset:2048
	ds_read_b128 v[176:179], v176 offset:3072
	s_add_u32 s4, s46, 0xb0000
	s_addc_u32 s5, s47, 0
	s_mov_b32 m0, s51
	v_lshl_add_u64 v[216:217], s[4:5], 0, v[146:147]
	ds_read_b128 v[180:183], v171 offset:32768
	ds_read_b128 v[184:187], v171 offset:33792
	ds_read_b128 v[188:191], v171 offset:34816
	ds_read_b128 v[192:195], v171 offset:35840
	ds_read_b128 v[196:199], v171 offset:36864
	ds_read_b128 v[200:203], v171 offset:37888
	ds_read_b128 v[204:207], v171 offset:38912
	ds_read_b128 v[208:211], v171 offset:39936
	global_load_lds_dwordx4 v[216:217], off
	v_lshl_add_u64 v[216:217], s[4:5], 0, v[150:151]
	s_mov_b32 m0, s52
	s_nop 0
	global_load_lds_dwordx4 v[216:217], off
	s_waitcnt vmcnt(8)
	s_waitcnt lgkmcnt(0)
	s_barrier
	s_waitcnt lgkmcnt(0)
	v_mfma_f32_16x16x32_bf16 v[124:127], v[128:131], v[180:183], v[124:127]
	v_mfma_f32_16x16x32_bf16 v[120:123], v[136:139], v[180:183], v[120:123]
	v_mfma_f32_16x16x32_bf16 v[116:119], v[128:131], v[188:191], v[116:119]
	v_mfma_f32_16x16x32_bf16 v[112:115], v[136:139], v[188:191], v[112:115]
	v_mfma_f32_16x16x32_bf16 v[108:111], v[128:131], v[196:199], v[108:111]
	v_mfma_f32_16x16x32_bf16 v[104:107], v[136:139], v[196:199], v[104:107]
	v_mfma_f32_16x16x32_bf16 v[100:103], v[128:131], v[204:207], v[100:103]
	v_mfma_f32_16x16x32_bf16 v[96:99], v[136:139], v[204:207], v[96:99]
	v_mfma_f32_16x16x32_bf16 v[124:127], v[132:135], v[184:187], v[124:127]
	v_mfma_f32_16x16x32_bf16 v[120:123], v[140:143], v[184:187], v[120:123]
	v_mfma_f32_16x16x32_bf16 v[116:119], v[132:135], v[192:195], v[116:119]
	v_mfma_f32_16x16x32_bf16 v[112:115], v[140:143], v[192:195], v[112:115]
	v_mfma_f32_16x16x32_bf16 v[108:111], v[132:135], v[200:203], v[108:111]
	v_mfma_f32_16x16x32_bf16 v[104:107], v[140:143], v[200:203], v[104:107]
	v_mfma_f32_16x16x32_bf16 v[100:103], v[132:135], v[208:211], v[100:103]
	v_mfma_f32_16x16x32_bf16 v[96:99], v[140:143], v[208:211], v[96:99]
	v_mfma_f32_16x16x32_bf16 v[60:63], v[158:161], v[180:183], v[60:63]
	v_mfma_f32_16x16x32_bf16 v[56:59], v[172:175], v[180:183], v[56:59]
	v_mfma_f32_16x16x32_bf16 v[52:55], v[158:161], v[188:191], v[52:55]
	v_mfma_f32_16x16x32_bf16 v[48:51], v[172:175], v[188:191], v[48:51]
	v_mfma_f32_16x16x32_bf16 v[44:47], v[158:161], v[196:199], v[44:47]
	v_mfma_f32_16x16x32_bf16 v[40:43], v[172:175], v[196:199], v[40:43]
	v_mfma_f32_16x16x32_bf16 v[36:39], v[158:161], v[204:207], v[36:39]
	v_mfma_f32_16x16x32_bf16 v[32:35], v[172:175], v[204:207], v[32:35]
	v_mfma_f32_16x16x32_bf16 v[60:63], v[162:165], v[184:187], v[60:63]
	v_mfma_f32_16x16x32_bf16 v[56:59], v[176:179], v[184:187], v[56:59]
	v_mfma_f32_16x16x32_bf16 v[52:55], v[162:165], v[192:195], v[52:55]
	v_mfma_f32_16x16x32_bf16 v[48:51], v[176:179], v[192:195], v[48:51]
	v_mfma_f32_16x16x32_bf16 v[44:47], v[162:165], v[200:203], v[44:47]
	v_mfma_f32_16x16x32_bf16 v[40:43], v[176:179], v[200:203], v[40:43]
	v_mfma_f32_16x16x32_bf16 v[36:39], v[162:165], v[208:211], v[36:39]
	v_mfma_f32_16x16x32_bf16 v[32:35], v[176:179], v[208:211], v[32:35]
	s_barrier
	s_add_i32 s4, s84, s48
	v_lshl_add_u64 v[144:145], v[144:145], 0, s[10:11]
	s_mov_b32 m0, s4
	ds_read_b128 v[180:183], v171 offset:49152
	ds_read_b128 v[184:187], v171 offset:50176
	ds_read_b128 v[188:191], v171 offset:51200
	ds_read_b128 v[192:195], v171 offset:52224
	ds_read_b128 v[196:199], v171 offset:53248
	ds_read_b128 v[200:203], v171 offset:54272
	ds_read_b128 v[204:207], v171 offset:55296
	ds_read_b128 v[208:211], v171 offset:56320
	global_load_lds_dwordx4 v[144:145], off
	s_add_i32 m0, s4, 0x2000
	s_add_u32 s4, s44, 0xb0080
	v_lshl_add_u64 v[144:145], v[166:167], 0, s[10:11]
	s_addc_u32 s5, s45, 0
	s_add_i32 s44, s85, s48
	global_load_lds_dwordx4 v[144:145], off
	v_lshl_add_u64 v[144:145], s[4:5], 0, v[148:149]
	s_mov_b32 m0, s44
	s_nop 0
	global_load_lds_dwordx4 v[144:145], off
	v_lshl_add_u64 v[144:145], s[4:5], 0, v[152:153]
	s_add_i32 m0, s44, 0x2000
	s_nop 0
	global_load_lds_dwordx4 v[144:145], off
	v_lshl_add_u64 v[144:145], v[212:213], 0, s[10:11]
	s_mov_b32 m0, s55
	s_nop 0
	global_load_lds_dwordx4 v[144:145], off
	v_lshl_add_u64 v[144:145], v[214:215], 0, s[10:11]
	s_mov_b32 m0, s56
	s_nop 0
	global_load_lds_dwordx4 v[144:145], off
	s_waitcnt vmcnt(8)
	s_waitcnt lgkmcnt(0)
	s_barrier
	s_waitcnt lgkmcnt(0)
	v_mfma_f32_16x16x32_bf16 v[92:95], v[128:131], v[180:183], v[92:95]
	v_mfma_f32_16x16x32_bf16 v[88:91], v[136:139], v[180:183], v[88:91]
	v_mfma_f32_16x16x32_bf16 v[84:87], v[128:131], v[188:191], v[84:87]
	v_mfma_f32_16x16x32_bf16 v[80:83], v[136:139], v[188:191], v[80:83]
	v_mfma_f32_16x16x32_bf16 v[76:79], v[128:131], v[196:199], v[76:79]
	v_mfma_f32_16x16x32_bf16 v[72:75], v[136:139], v[196:199], v[72:75]
	v_mfma_f32_16x16x32_bf16 v[68:71], v[128:131], v[204:207], v[68:71]
	v_mfma_f32_16x16x32_bf16 v[64:67], v[136:139], v[204:207], v[64:67]
	v_mfma_f32_16x16x32_bf16 v[92:95], v[132:135], v[184:187], v[92:95]
	v_mfma_f32_16x16x32_bf16 v[88:91], v[140:143], v[184:187], v[88:91]
	v_mfma_f32_16x16x32_bf16 v[84:87], v[132:135], v[192:195], v[84:87]
	v_mfma_f32_16x16x32_bf16 v[80:83], v[140:143], v[192:195], v[80:83]
	v_mfma_f32_16x16x32_bf16 v[76:79], v[132:135], v[200:203], v[76:79]
	v_mfma_f32_16x16x32_bf16 v[72:75], v[140:143], v[200:203], v[72:75]
	v_mfma_f32_16x16x32_bf16 v[68:71], v[132:135], v[208:211], v[68:71]
	v_mfma_f32_16x16x32_bf16 v[64:67], v[140:143], v[208:211], v[64:67]
	v_mfma_f32_16x16x32_bf16 v[28:31], v[158:161], v[180:183], v[28:31]
	v_mfma_f32_16x16x32_bf16 v[24:27], v[172:175], v[180:183], v[24:27]
	v_mfma_f32_16x16x32_bf16 v[20:23], v[158:161], v[188:191], v[20:23]
	v_mfma_f32_16x16x32_bf16 v[16:19], v[172:175], v[188:191], v[16:19]
	v_mfma_f32_16x16x32_bf16 v[12:15], v[158:161], v[196:199], v[12:15]
	v_mfma_f32_16x16x32_bf16 v[8:11], v[172:175], v[196:199], v[8:11]
	v_mfma_f32_16x16x32_bf16 v[4:7], v[158:161], v[204:207], v[4:7]
	v_mfma_f32_16x16x32_bf16 v[0:3], v[172:175], v[204:207], v[0:3]
	v_mfma_f32_16x16x32_bf16 v[28:31], v[162:165], v[184:187], v[28:31]
	v_mfma_f32_16x16x32_bf16 v[24:27], v[176:179], v[184:187], v[24:27]
	v_mfma_f32_16x16x32_bf16 v[20:23], v[162:165], v[192:195], v[20:23]
	v_mfma_f32_16x16x32_bf16 v[16:19], v[176:179], v[192:195], v[16:19]
	v_mfma_f32_16x16x32_bf16 v[12:15], v[162:165], v[200:203], v[12:15]
	v_mfma_f32_16x16x32_bf16 v[8:11], v[176:179], v[200:203], v[8:11]
	v_mfma_f32_16x16x32_bf16 v[4:7], v[162:165], v[208:211], v[4:7]
	v_mfma_f32_16x16x32_bf16 v[0:3], v[176:179], v[208:211], v[0:3]
	s_barrier
	s_add_u32 s81, s81, 0x100
	s_addc_u32 s82, s82, 0
	s_cmp_ge_u32 s83, s79
	s_mov_b64 s[4:5], s[14:15]
	s_mov_b32 s44, s83
	s_cbranch_scc0 .LBB0_2892

; #define G_STAGE(bufoff, gbase, voff) do { _Pragma("unroll") for (int _i = 0; _i < 2; ++_i) \
;         __builtin_amdgcn_global_load_lds((const unsigned*)((const char*)(gbase) + voff[_i]), (LAS unsigned*)(lds + (bufoff) + ldsw + _i * 8192), 16, 0, 0); } while (0)
; #define G_LDA(dst, b, h) do { _Pragma("unroll") for (int m = 0; m < 4; ++m) _Pragma("unroll") for (int k = 0; k < 2; ++k) dst[m][k] = *(const LAS bf16x8*)(lds + G_SA(b, h) + aoff + m * 2048 + k * 1024); } while (0)
; #define G_LDB(dst, b, h) do { _Pragma("unroll") for (int n = 0; n < 2; ++n) _Pragma("unroll") for (int k = 0; k < 2; ++k) dst[n][k] = *(const LAS bf16x8*)(lds + G_SB(b, h) + boff + n * 2048 + k * 1024); } while (0)
; #define G_MMA(ai, bj, At_, Bt_) do { __builtin_amdgcn_s_setprio(1); _Pragma("unroll") for (int m = 0; m < 4; ++m) _Pragma("unroll") for (int n = 0; n < 2; ++n) _Pragma("unroll") for (int k = 0; k < 2; ++k) \
;         acc[ai][bj][m][n] = __builtin_amdgcn_mfma_f32_16x16x32_bf16(Bt_[n][k], At_[m][k], acc[ai][bj][m][n], 0, 0, 0); __builtin_amdgcn_s_setprio(0); } while (0)
; #define WAIT_V(n) asm volatile("s_waitcnt vmcnt(" #n ")" ::: "memory")
; #define WAIT_L(n) asm volatile("s_waitcnt lgkmcnt(" #n ")" ::: "memory")
; #define BAR __builtin_amdgcn_s_barrier()
; #define SCHED __builtin_amdgcn_sched_barrier(0)
; template <class Get, class Epi>
; DI void gemm_loop(int ntiles, int ld, char* shm, const Get& get, const Epi& epi) {
;     ...
;             G_LDB(B0, 0, 0); G_LDB(B1, 0, 1); SCHED; G_LDA(At, 0, 0); G_STAGE(G_SA(1, 1), a1 + hstep, voffA);
;             WAIT_V(8); WAIT_L(0); BAR; G_MMA(0, 0, At, B0); G_MMA(0, 1, At, B1); BAR; SCHED;
;             G_LDA(At, 0, 1); G_STAGE(G_SB(0, 0), b2, voffB); G_STAGE(G_SB(0, 1), b2 + hstep, voffB); G_STAGE(G_SA(0, 0), a2, voffA);
.Lrj_3141_0:
	s_waitcnt lgkmcnt(0)
	s_barrier
	s_waitcnt lgkmcnt(0)
	v_mfma_f32_16x16x32_bf16 v[124:127], v[144:147], v[176:179], 0
	v_mfma_f32_16x16x32_bf16 v[120:123], v[152:155], v[176:179], 0
	v_mfma_f32_16x16x32_bf16 v[116:119], v[144:147], v[184:187], 0
	v_mfma_f32_16x16x32_bf16 v[112:115], v[152:155], v[184:187], 0
	v_mfma_f32_16x16x32_bf16 v[100:103], v[144:147], v[192:195], 0
	v_mfma_f32_16x16x32_bf16 v[96:99], v[152:155], v[192:195], 0
	v_mfma_f32_16x16x32_bf16 v[84:87], v[144:147], v[200:203], 0
	v_mfma_f32_16x16x32_bf16 v[80:83], v[152:155], v[200:203], 0
	v_mfma_f32_16x16x32_bf16 v[124:127], v[148:151], v[180:183], v[124:127]
	v_mfma_f32_16x16x32_bf16 v[120:123], v[156:159], v[180:183], v[120:123]
	v_mfma_f32_16x16x32_bf16 v[116:119], v[148:151], v[188:191], v[116:119]
	v_mfma_f32_16x16x32_bf16 v[112:115], v[156:159], v[188:191], v[112:115]
	v_mfma_f32_16x16x32_bf16 v[100:103], v[148:151], v[196:199], v[100:103]
	v_mfma_f32_16x16x32_bf16 v[96:99], v[156:159], v[196:199], v[96:99]
	v_mfma_f32_16x16x32_bf16 v[84:87], v[148:151], v[204:207], v[84:87]
	v_mfma_f32_16x16x32_bf16 v[80:83], v[156:159], v[204:207], v[80:83]
	v_mfma_f32_16x16x32_bf16 v[108:111], v[160:163], v[176:179], 0
	v_mfma_f32_16x16x32_bf16 v[104:107], v[168:171], v[176:179], 0
	v_mfma_f32_16x16x32_bf16 v[92:95], v[160:163], v[184:187], 0
	v_mfma_f32_16x16x32_bf16 v[88:91], v[168:171], v[184:187], 0
	v_mfma_f32_16x16x32_bf16 v[76:79], v[160:163], v[192:195], 0
	v_mfma_f32_16x16x32_bf16 v[72:75], v[168:171], v[192:195], 0
	v_mfma_f32_16x16x32_bf16 v[68:71], v[160:163], v[200:203], 0
	v_mfma_f32_16x16x32_bf16 v[64:67], v[168:171], v[200:203], 0
	v_mfma_f32_16x16x32_bf16 v[108:111], v[164:167], v[180:183], v[108:111]
	v_mfma_f32_16x16x32_bf16 v[104:107], v[172:175], v[180:183], v[104:107]
	v_mfma_f32_16x16x32_bf16 v[92:95], v[164:167], v[188:191], v[92:95]
	v_mfma_f32_16x16x32_bf16 v[88:91], v[172:175], v[188:191], v[88:91]
	v_mfma_f32_16x16x32_bf16 v[76:79], v[164:167], v[196:199], v[76:79]
	v_mfma_f32_16x16x32_bf16 v[72:75], v[172:175], v[196:199], v[72:75]
	v_mfma_f32_16x16x32_bf16 v[68:71], v[164:167], v[204:207], v[68:71]
	v_mfma_f32_16x16x32_bf16 v[64:67], v[172:175], v[204:207], v[64:67]
	s_barrier
	s_add_i32 s71, s57, s50
	v_lshl_add_u64 v[208:209], s[14:15], 0, v[130:131]
	s_mov_b32 m0, s71
	ds_read_b128 v[176:179], v143 offset:16384
	ds_read_b128 v[180:183], v143 offset:17408
	ds_read_b128 v[184:187], v143 offset:18432
	ds_read_b128 v[188:191], v143 offset:19456
	ds_read_b128 v[192:195], v143 offset:20480
	ds_read_b128 v[196:199], v143 offset:21504
	ds_read_b128 v[200:203], v143 offset:22528
	ds_read_b128 v[204:207], v143 offset:23552
	global_load_lds_dwordx4 v[208:209], off
	s_add_i32 m0, s71, 0x2000
	s_add_u32 s72, s14, 0x40000
	v_lshl_add_u64 v[210:211], s[14:15], 0, v[134:135]
	s_addc_u32 s73, s15, 0
	s_add_i32 s71, s58, s50
	global_load_lds_dwordx4 v[210:211], off
	v_lshl_add_u64 v[212:213], s[72:73], 0, v[130:131]
	s_mov_b32 m0, s71
	v_lshl_add_u64 v[214:215], s[46:47], 0, v[132:133]
	global_load_lds_dwordx4 v[212:213], off
	v_lshl_add_u64 v[212:213], s[72:73], 0, v[134:135]
	s_add_i32 m0, s71, 0x2000
	s_nop 0
	global_load_lds_dwordx4 v[212:213], off
	v_lshl_add_u64 v[212:213], s[46:47], 0, v[128:129]
	s_mov_b32 m0, s35
	s_nop 0
	global_load_lds_dwordx4 v[212:213], off
	s_mov_b32 m0, s51
	s_nop 0
	global_load_lds_dwordx4 v[214:215], off
	s_cmp_lg_u32 s100, 0
	s_cbranch_scc0 .Lrf_3141_1
	s_waitcnt vmcnt(16)
	s_branch .Lrj_3141_1

; #define G_STAGE(bufoff, gbase, voff) do { _Pragma("unroll") for (int _i = 0; _i < 2; ++_i) \
;         __builtin_amdgcn_global_load_lds((const unsigned*)((const char*)(gbase) + voff[_i]), (LAS unsigned*)(lds + (bufoff) + ldsw + _i * 8192), 16, 0, 0); } while (0)
; #define G_LDA(dst, b, h) do { _Pragma("unroll") for (int m = 0; m < 4; ++m) _Pragma("unroll") for (int k = 0; k < 2; ++k) dst[m][k] = *(const LAS bf16x8*)(lds + G_SA(b, h) + aoff + m * 2048 + k * 1024); } while (0)
; #define G_LDB(dst, b, h) do { _Pragma("unroll") for (int n = 0; n < 2; ++n) _Pragma("unroll") for (int k = 0; k < 2; ++k) dst[n][k] = *(const LAS bf16x8*)(lds + G_SB(b, h) + boff + n * 2048 + k * 1024); } while (0)
; #define G_MMA(ai, bj, At_, Bt_) do { __builtin_amdgcn_s_setprio(1); _Pragma("unroll") for (int m = 0; m < 4; ++m) _Pragma("unroll") for (int n = 0; n < 2; ++n) _Pragma("unroll") for (int k = 0; k < 2; ++k) \
;         acc[ai][bj][m][n] = __builtin_amdgcn_mfma_f32_16x16x32_bf16(Bt_[n][k], At_[m][k], acc[ai][bj][m][n], 0, 0, 0); __builtin_amdgcn_s_setprio(0); } while (0)
; #define WAIT_V(n) asm volatile("s_waitcnt vmcnt(" #n ")" ::: "memory")
; #define WAIT_L(n) asm volatile("s_waitcnt lgkmcnt(" #n ")" ::: "memory")
; #define BAR __builtin_amdgcn_s_barrier()
; #define SCHED __builtin_amdgcn_sched_barrier(0)
; template <class Get, class Epi>
; DI void gemm_loop(int ntiles, int ld, char* shm, const Get& get, const Epi& epi) {
;     ...
;             WAIT_V(8); WAIT_L(0); BAR; G_MMA(1, 0, At, B0); G_MMA(1, 1, At, B1); BAR; SCHED;
;             G_LDB(B0, 1, 0); G_LDB(B1, 1, 1); SCHED; G_LDA(At, 1, 0); G_STAGE(G_SA(0, 1), a2 + hstep, voffA);
;             WAIT_V(8); WAIT_L(0); BAR; G_MMA(0, 0, At, B0); G_MMA(0, 1, At, B1); BAR; SCHED;
;             G_LDA(At, 1, 1); G_STAGE(G_SB(1, 0), b3, voffB); G_STAGE(G_SB(1, 1), b3 + hstep, voffB); G_STAGE(G_SA(1, 0), a3, voffA);
;             WAIT_V(8); WAIT_L(0); BAR; G_MMA(1, 0, At, B0); G_MMA(1, 1, At, B1); BAR; SCHED;
.Lrj_3141_1:
	s_waitcnt lgkmcnt(0)
	s_barrier
	s_waitcnt lgkmcnt(0)
	v_mfma_f32_16x16x32_bf16 v[60:63], v[144:147], v[176:179], 0
	v_mfma_f32_16x16x32_bf16 v[56:59], v[152:155], v[176:179], 0
	v_mfma_f32_16x16x32_bf16 v[52:55], v[144:147], v[184:187], 0
	v_mfma_f32_16x16x32_bf16 v[48:51], v[152:155], v[184:187], 0
	v_mfma_f32_16x16x32_bf16 v[36:39], v[144:147], v[192:195], 0
	v_mfma_f32_16x16x32_bf16 v[32:35], v[152:155], v[192:195], 0
	v_mfma_f32_16x16x32_bf16 v[20:23], v[144:147], v[200:203], 0
	v_mfma_f32_16x16x32_bf16 v[16:19], v[152:155], v[200:203], 0
	v_mfma_f32_16x16x32_bf16 v[60:63], v[148:151], v[180:183], v[60:63]
	v_mfma_f32_16x16x32_bf16 v[56:59], v[156:159], v[180:183], v[56:59]
	v_mfma_f32_16x16x32_bf16 v[52:55], v[148:151], v[188:191], v[52:55]
	v_mfma_f32_16x16x32_bf16 v[48:51], v[156:159], v[188:191], v[48:51]
	v_mfma_f32_16x16x32_bf16 v[36:39], v[148:151], v[196:199], v[36:39]
	v_mfma_f32_16x16x32_bf16 v[32:35], v[156:159], v[196:199], v[32:35]
	v_mfma_f32_16x16x32_bf16 v[20:23], v[148:151], v[204:207], v[20:23]
	v_mfma_f32_16x16x32_bf16 v[16:19], v[156:159], v[204:207], v[16:19]
	v_mfma_f32_16x16x32_bf16 v[44:47], v[160:163], v[176:179], 0
	v_mfma_f32_16x16x32_bf16 v[40:43], v[168:171], v[176:179], 0
	v_mfma_f32_16x16x32_bf16 v[28:31], v[160:163], v[184:187], 0
	v_mfma_f32_16x16x32_bf16 v[24:27], v[168:171], v[184:187], 0
	v_mfma_f32_16x16x32_bf16 v[12:15], v[160:163], v[192:195], 0
	v_mfma_f32_16x16x32_bf16 v[8:11], v[168:171], v[192:195], 0
	v_mfma_f32_16x16x32_bf16 v[4:7], v[160:163], v[200:203], 0
	v_mfma_f32_16x16x32_bf16 v[0:3], v[168:171], v[200:203], 0
	v_mfma_f32_16x16x32_bf16 v[44:47], v[164:167], v[180:183], v[44:47]
	v_mfma_f32_16x16x32_bf16 v[40:43], v[172:175], v[180:183], v[40:43]
	v_mfma_f32_16x16x32_bf16 v[28:31], v[164:167], v[188:191], v[28:31]
	v_mfma_f32_16x16x32_bf16 v[24:27], v[172:175], v[188:191], v[24:27]
	v_mfma_f32_16x16x32_bf16 v[12:15], v[164:167], v[196:199], v[12:15]
	v_mfma_f32_16x16x32_bf16 v[8:11], v[172:175], v[196:199], v[8:11]
	v_mfma_f32_16x16x32_bf16 v[4:7], v[164:167], v[204:207], v[4:7]
	v_mfma_f32_16x16x32_bf16 v[0:3], v[172:175], v[204:207], v[0:3]
	s_barrier
	s_add_i32 s71, 0, 0x18000
	s_add_i32 s72, 0, 0x1c000
	v_add_u32_e32 v156, s71, v140
	v_add_u32_e32 v172, s72, v140
	ds_read_b128 v[144:147], v156
	ds_read_b128 v[148:151], v156 offset:1024
	ds_read_b128 v[152:155], v156 offset:2048
	ds_read_b128 v[156:159], v156 offset:3072
	ds_read_b128 v[160:163], v172
	ds_read_b128 v[164:167], v172 offset:1024
	ds_read_b128 v[168:171], v172 offset:2048
	ds_read_b128 v[172:175], v172 offset:3072
	s_add_u32 s46, s46, 0x40000
	s_addc_u32 s47, s47, 0
	s_mov_b32 m0, s52
	v_lshl_add_u64 v[216:217], s[46:47], 0, v[128:129]
	ds_read_b128 v[176:179], v143 offset:32768
	ds_read_b128 v[180:183], v143 offset:33792
	ds_read_b128 v[184:187], v143 offset:34816
	ds_read_b128 v[188:191], v143 offset:35840
	ds_read_b128 v[192:195], v143 offset:36864
	ds_read_b128 v[196:199], v143 offset:37888
	ds_read_b128 v[200:203], v143 offset:38912
	ds_read_b128 v[204:207], v143 offset:39936
	global_load_lds_dwordx4 v[216:217], off
	v_lshl_add_u64 v[216:217], s[46:47], 0, v[132:133]
	s_mov_b32 m0, s53
	s_nop 0
	global_load_lds_dwordx4 v[216:217], off
	s_waitcnt vmcnt(8)
	s_waitcnt lgkmcnt(0)
	s_barrier
	s_waitcnt lgkmcnt(0)
	v_mfma_f32_16x16x32_bf16 v[124:127], v[144:147], v[176:179], v[124:127]
	v_mfma_f32_16x16x32_bf16 v[120:123], v[152:155], v[176:179], v[120:123]
	v_mfma_f32_16x16x32_bf16 v[116:119], v[144:147], v[184:187], v[116:119]
	v_mfma_f32_16x16x32_bf16 v[112:115], v[152:155], v[184:187], v[112:115]
	v_mfma_f32_16x16x32_bf16 v[100:103], v[144:147], v[192:195], v[100:103]
	v_mfma_f32_16x16x32_bf16 v[96:99], v[152:155], v[192:195], v[96:99]
	v_mfma_f32_16x16x32_bf16 v[84:87], v[144:147], v[200:203], v[84:87]
	v_mfma_f32_16x16x32_bf16 v[80:83], v[152:155], v[200:203], v[80:83]
	v_mfma_f32_16x16x32_bf16 v[124:127], v[148:151], v[180:183], v[124:127]
	v_mfma_f32_16x16x32_bf16 v[120:123], v[156:159], v[180:183], v[120:123]
	v_mfma_f32_16x16x32_bf16 v[116:119], v[148:151], v[188:191], v[116:119]
	v_mfma_f32_16x16x32_bf16 v[112:115], v[156:159], v[188:191], v[112:115]
	v_mfma_f32_16x16x32_bf16 v[100:103], v[148:151], v[196:199], v[100:103]
	v_mfma_f32_16x16x32_bf16 v[96:99], v[156:159], v[196:199], v[96:99]
	v_mfma_f32_16x16x32_bf16 v[84:87], v[148:151], v[204:207], v[84:87]
	v_mfma_f32_16x16x32_bf16 v[80:83], v[156:159], v[204:207], v[80:83]
	v_mfma_f32_16x16x32_bf16 v[108:111], v[160:163], v[176:179], v[108:111]
	v_mfma_f32_16x16x32_bf16 v[104:107], v[168:171], v[176:179], v[104:107]
	v_mfma_f32_16x16x32_bf16 v[92:95], v[160:163], v[184:187], v[92:95]
	v_mfma_f32_16x16x32_bf16 v[88:91], v[168:171], v[184:187], v[88:91]
	v_mfma_f32_16x16x32_bf16 v[76:79], v[160:163], v[192:195], v[76:79]
	v_mfma_f32_16x16x32_bf16 v[72:75], v[168:171], v[192:195], v[72:75]
	v_mfma_f32_16x16x32_bf16 v[68:71], v[160:163], v[200:203], v[68:71]
	v_mfma_f32_16x16x32_bf16 v[64:67], v[168:171], v[200:203], v[64:67]
	v_mfma_f32_16x16x32_bf16 v[108:111], v[164:167], v[180:183], v[108:111]
	v_mfma_f32_16x16x32_bf16 v[104:107], v[172:175], v[180:183], v[104:107]
	v_mfma_f32_16x16x32_bf16 v[92:95], v[164:167], v[188:191], v[92:95]
	v_mfma_f32_16x16x32_bf16 v[88:91], v[172:175], v[188:191], v[88:91]
	v_mfma_f32_16x16x32_bf16 v[76:79], v[164:167], v[196:199], v[76:79]
	v_mfma_f32_16x16x32_bf16 v[72:75], v[172:175], v[196:199], v[72:75]
	v_mfma_f32_16x16x32_bf16 v[68:71], v[164:167], v[204:207], v[68:71]
	v_mfma_f32_16x16x32_bf16 v[64:67], v[172:175], v[204:207], v[64:67]
	s_barrier
; #define G_STAGE(bufoff, gbase, voff) do { _Pragma("unroll") for (int _i = 0; _i < 2; ++_i) \
;         __builtin_amdgcn_global_load_lds((const unsigned*)((const char*)(gbase) + voff[_i]), (LAS unsigned*)(lds + (bufoff) + ldsw + _i * 8192), 16, 0, 0); } while (0)
; #define G_LDA(dst, b, h) do { _Pragma("unroll") for (int m = 0; m < 4; ++m) _Pragma("unroll") for (int k = 0; k < 2; ++k) dst[m][k] = *(const LAS bf16x8*)(lds + G_SA(b, h) + aoff + m * 2048 + k * 1024); } while (0)
; #define G_LDB(dst, b, h) do { _Pragma("unroll") for (int n = 0; n < 2; ++n) _Pragma("unroll") for (int k = 0; k < 2; ++k) dst[n][k] = *(const LAS bf16x8*)(lds + G_SB(b, h) + boff + n * 2048 + k * 1024); } while (0)
; #define WAIT_V(n) asm volatile("s_waitcnt vmcnt(" #n ")" ::: "memory")
; #define WAIT_L(n) asm volatile("s_waitcnt lgkmcnt(" #n ")" ::: "memory")
; #define BAR __builtin_amdgcn_s_barrier()
; #define SCHED __builtin_amdgcn_sched_barrier(0)
; template <class Get, class Epi>
; DI void gemm_loop(int ntiles, int ld, char* shm, const Get& get, const Epi& epi) {
;     ...
;         for (int t = 0; t < nt; t += 2) {
;             const bool last = (t == nt - 2);
;             const char* a1 = cA + (size_t)(t + 1) * kstep;
;             const char* a2 = last ? nA : cA + (size_t)(t + 2) * kstep; const char* b2 = last ? nB : cB + (size_t)(t + 2) * kstep;
;             const char* a3 = a2 + kstep; const char* b3 = b2 + kstep;
;             G_LDB(B0, 0, 0); G_LDB(B1, 0, 1); SCHED; G_LDA(At, 0, 0); G_STAGE(G_SA(1, 1), a1 + hstep, voffA);
;             WAIT_V(8); WAIT_L(0); BAR; G_MMA(0, 0, At, B0); G_MMA(0, 1, At, B1); BAR; SCHED;
;             G_LDA(At, 0, 1); G_STAGE(G_SB(0, 0), b2, voffB); G_STAGE(G_SB(0, 1), b2 + hstep, voffB); G_STAGE(G_SA(0, 0), a2, voffA);
;             WAIT_V(8); WAIT_L(0); BAR; G_MMA(1, 0, At, B0); G_MMA(1, 1, At, B1); BAR; SCHED;
;             G_LDB(B0, 1, 0); G_LDB(B1, 1, 1); SCHED; G_LDA(At, 1, 0); G_STAGE(G_SA(0, 1), a2 + hstep, voffA);
;             WAIT_V(8); WAIT_L(0); BAR; G_MMA(0, 0, At, B0); G_MMA(0, 1, At, B1); BAR; SCHED;
;             G_LDA(At, 1, 1); G_STAGE(G_SB(1, 0), b3, voffB); G_STAGE(G_SB(1, 1), b3 + hstep, voffB); G_STAGE(G_SA(1, 0), a3, voffA);
;             WAIT_V(8); WAIT_L(0); BAR; G_MMA(1, 0, At, B0); G_MMA(1, 1, At, B1); BAR; SCHED;
	s_add_i32 s46, s71, s50
	v_lshl_add_u64 v[208:209], v[208:209], 0, s[8:9]
	s_mov_b32 m0, s46
	ds_read_b128 v[176:179], v143 offset:49152
	ds_read_b128 v[180:183], v143 offset:50176
	ds_read_b128 v[184:187], v143 offset:51200
	ds_read_b128 v[188:191], v143 offset:52224
	ds_read_b128 v[192:195], v143 offset:53248
	ds_read_b128 v[196:199], v143 offset:54272
	ds_read_b128 v[200:203], v143 offset:55296
	ds_read_b128 v[204:207], v143 offset:56320
	global_load_lds_dwordx4 v[208:209], off
	s_add_i32 m0, s46, 0x2000
	s_add_u32 s14, s14, 0x40080
	v_lshl_add_u64 v[208:209], v[210:211], 0, s[8:9]
	s_addc_u32 s15, s15, 0
	s_add_i32 s46, s72, s50
	global_load_lds_dwordx4 v[208:209], off
	v_lshl_add_u64 v[208:209], s[14:15], 0, v[130:131]
	s_mov_b32 m0, s46
	s_nop 0
	global_load_lds_dwordx4 v[208:209], off
	v_lshl_add_u64 v[208:209], s[14:15], 0, v[134:135]
	s_add_i32 m0, s46, 0x2000
	s_nop 0
	global_load_lds_dwordx4 v[208:209], off
	v_lshl_add_u64 v[208:209], v[212:213], 0, s[8:9]
	s_mov_b32 m0, s55
	s_nop 0
	global_load_lds_dwordx4 v[208:209], off
	v_lshl_add_u64 v[208:209], v[214:215], 0, s[8:9]
	s_mov_b32 m0, s56
	s_nop 0
	global_load_lds_dwordx4 v[208:209], off
	s_waitcnt vmcnt(8)
	s_waitcnt lgkmcnt(0)
	s_barrier
	s_waitcnt lgkmcnt(0)
	v_mfma_f32_16x16x32_bf16 v[60:63], v[144:147], v[176:179], v[60:63]
	v_mfma_f32_16x16x32_bf16 v[56:59], v[152:155], v[176:179], v[56:59]
	v_mfma_f32_16x16x32_bf16 v[52:55], v[144:147], v[184:187], v[52:55]
	v_mfma_f32_16x16x32_bf16 v[48:51], v[152:155], v[184:187], v[48:51]
	v_mfma_f32_16x16x32_bf16 v[36:39], v[144:147], v[192:195], v[36:39]
	v_mfma_f32_16x16x32_bf16 v[32:35], v[152:155], v[192:195], v[32:35]
	v_mfma_f32_16x16x32_bf16 v[20:23], v[144:147], v[200:203], v[20:23]
	v_mfma_f32_16x16x32_bf16 v[16:19], v[152:155], v[200:203], v[16:19]
	v_mfma_f32_16x16x32_bf16 v[60:63], v[148:151], v[180:183], v[60:63]
	v_mfma_f32_16x16x32_bf16 v[56:59], v[156:159], v[180:183], v[56:59]
	v_mfma_f32_16x16x32_bf16 v[52:55], v[148:151], v[188:191], v[52:55]
	v_mfma_f32_16x16x32_bf16 v[48:51], v[156:159], v[188:191], v[48:51]
	v_mfma_f32_16x16x32_bf16 v[36:39], v[148:151], v[196:199], v[36:39]
	v_mfma_f32_16x16x32_bf16 v[32:35], v[156:159], v[196:199], v[32:35]
	v_mfma_f32_16x16x32_bf16 v[20:23], v[148:151], v[204:207], v[20:23]
	v_mfma_f32_16x16x32_bf16 v[16:19], v[156:159], v[204:207], v[16:19]
	v_mfma_f32_16x16x32_bf16 v[44:47], v[160:163], v[176:179], v[44:47]
	v_mfma_f32_16x16x32_bf16 v[40:43], v[168:171], v[176:179], v[40:43]
	v_mfma_f32_16x16x32_bf16 v[28:31], v[160:163], v[184:187], v[28:31]
	v_mfma_f32_16x16x32_bf16 v[24:27], v[168:171], v[184:187], v[24:27]
	v_mfma_f32_16x16x32_bf16 v[12:15], v[160:163], v[192:195], v[12:15]
	v_mfma_f32_16x16x32_bf16 v[8:11], v[168:171], v[192:195], v[8:11]
	v_mfma_f32_16x16x32_bf16 v[4:7], v[160:163], v[200:203], v[4:7]
	v_mfma_f32_16x16x32_bf16 v[0:3], v[168:171], v[200:203], v[0:3]
	v_mfma_f32_16x16x32_bf16 v[44:47], v[164:167], v[180:183], v[44:47]
	v_mfma_f32_16x16x32_bf16 v[40:43], v[172:175], v[180:183], v[40:43]
	v_mfma_f32_16x16x32_bf16 v[28:31], v[164:167], v[188:191], v[28:31]
	v_mfma_f32_16x16x32_bf16 v[24:27], v[172:175], v[188:191], v[24:27]
	v_mfma_f32_16x16x32_bf16 v[12:15], v[164:167], v[196:199], v[12:15]
	v_mfma_f32_16x16x32_bf16 v[8:11], v[172:175], v[196:199], v[8:11]
	v_mfma_f32_16x16x32_bf16 v[4:7], v[164:167], v[204:207], v[4:7]
	v_mfma_f32_16x16x32_bf16 v[0:3], v[172:175], v[204:207], v[0:3]
	s_barrier
	s_add_i32 s70, s70, 2
	s_add_u32 s48, s48, 0x100
	s_addc_u32 s49, s49, 0
	s_add_u32 s64, s64, 0x100
	s_addc_u32 s65, s65, 0
	s_cmp_gt_u32 s70, 13
	s_cbranch_scc0 .LBB0_3141
	s_branch .Lpost_3141
.LBB0_3141:
	ds_read_b128 v[144:147], v141
	ds_read_b128 v[148:151], v141 offset:1024
	ds_read_b128 v[152:155], v141 offset:2048
	ds_read_b128 v[156:159], v141 offset:3072
	ds_read_b128 v[160:163], v142
	ds_read_b128 v[164:167], v142 offset:1024
	ds_read_b128 v[168:171], v142 offset:2048
	ds_read_b128 v[172:175], v142 offset:3072
	s_add_u32 s14, s48, 0xfffc0080
	s_addc_u32 s15, s49, -1
	s_cmp_eq_u32 s70, 12
	s_cselect_b32 s47, s11, s15
	s_cselect_b32 s46, s39, s14
	s_cselect_b32 s15, s41, s65
	s_cselect_b32 s14, s63, s64
	v_lshl_add_u64 v[208:209], s[48:49], 0, v[136:137]
	s_add_i32 m0, s35, 0xc000
	ds_read_b128 v[176:179], v143
	ds_read_b128 v[180:183], v143 offset:1024
	ds_read_b128 v[184:187], v143 offset:2048
	ds_read_b128 v[188:191], v143 offset:3072
	ds_read_b128 v[192:195], v143 offset:4096
	ds_read_b128 v[196:199], v143 offset:5120
	ds_read_b128 v[200:203], v143 offset:6144
	ds_read_b128 v[204:207], v143 offset:7168
	global_load_lds_dwordx4 v[208:209], off
	v_lshl_add_u64 v[208:209], s[48:49], 0, v[138:139]
	s_add_i32 m0, s35, 0xe000
	s_nop 0
	global_load_lds_dwordx4 v[208:209], off
	s_waitcnt vmcnt(8)
	s_waitcnt lgkmcnt(0)
	s_barrier
; #define G_STAGE(bufoff, gbase, voff) do { _Pragma("unroll") for (int _i = 0; _i < 2; ++_i) \
;         __builtin_amdgcn_global_load_lds((const unsigned*)((const char*)(gbase) + voff[_i]), (LAS unsigned*)(lds + (bufoff) + ldsw + _i * 8192), 16, 0, 0); } while (0)
; #define G_LDA(dst, b, h) do { _Pragma("unroll") for (int m = 0; m < 4; ++m) _Pragma("unroll") for (int k = 0; k < 2; ++k) dst[m][k] = *(const LAS bf16x8*)(lds + G_SA(b, h) + aoff + m * 2048 + k * 1024); } while (0)
; #define G_LDB(dst, b, h) do { _Pragma("unroll") for (int n = 0; n < 2; ++n) _Pragma("unroll") for (int k = 0; k < 2; ++k) dst[n][k] = *(const LAS bf16x8*)(lds + G_SB(b, h) + boff + n * 2048 + k * 1024); } while (0)
; #define G_MMA(ai, bj, At_, Bt_) do { __builtin_amdgcn_s_setprio(1); _Pragma("unroll") for (int m = 0; m < 4; ++m) _Pragma("unroll") for (int n = 0; n < 2; ++n) _Pragma("unroll") for (int k = 0; k < 2; ++k) \
;         acc[ai][bj][m][n] = __builtin_amdgcn_mfma_f32_16x16x32_bf16(Bt_[n][k], At_[m][k], acc[ai][bj][m][n], 0, 0, 0); __builtin_amdgcn_s_setprio(0); } while (0)
; #define WAIT_V(n) asm volatile("s_waitcnt vmcnt(" #n ")" ::: "memory")
; #define WAIT_L(n) asm volatile("s_waitcnt lgkmcnt(" #n ")" ::: "memory")
; #define BAR __builtin_amdgcn_s_barrier()
; #define SCHED __builtin_amdgcn_sched_barrier(0)
; template <class Get, class Epi>
; DI void gemm_loop(int ntiles, int ld, char* shm, const Get& get, const Epi& epi) {
;     ...
;             G_LDB(B0, 0, 0); G_LDB(B1, 0, 1); SCHED; G_LDA(At, 0, 0); G_STAGE(G_SA(1, 1), a1 + hstep, voffA);
;             WAIT_V(8); WAIT_L(0); BAR; G_MMA(0, 0, At, B0); G_MMA(0, 1, At, B1); BAR; SCHED;
;             G_LDA(At, 0, 1); G_STAGE(G_SB(0, 0), b2, voffB); G_STAGE(G_SB(0, 1), b2 + hstep, voffB); G_STAGE(G_SA(0, 0), a2, voffA);
;             WAIT_V(8); WAIT_L(0); BAR; G_MMA(1, 0, At, B0); G_MMA(1, 1, At, B1); BAR; SCHED;
;             G_LDB(B0, 1, 0); G_LDB(B1, 1, 1); SCHED; G_LDA(At, 1, 0); G_STAGE(G_SA(0, 1), a2 + hstep, voffA);
;             WAIT_V(8); WAIT_L(0); BAR; G_MMA(0, 0, At, B0); G_MMA(0, 1, At, B1); BAR; SCHED;
;             G_LDA(At, 1, 1); G_STAGE(G_SB(1, 0), b3, voffB); G_STAGE(G_SB(1, 1), b3 + hstep, voffB); G_STAGE(G_SA(1, 0), a3, voffA);
;             WAIT_V(8); WAIT_L(0); BAR; G_MMA(1, 0, At, B0); G_MMA(1, 1, At, B1); BAR; SCHED;
	s_waitcnt lgkmcnt(0)
	v_mfma_f32_16x16x32_bf16 v[124:127], v[144:147], v[176:179], v[124:127]
	v_mfma_f32_16x16x32_bf16 v[120:123], v[152:155], v[176:179], v[120:123]
	v_mfma_f32_16x16x32_bf16 v[116:119], v[144:147], v[184:187], v[116:119]
	v_mfma_f32_16x16x32_bf16 v[112:115], v[152:155], v[184:187], v[112:115]
	v_mfma_f32_16x16x32_bf16 v[100:103], v[144:147], v[192:195], v[100:103]
	v_mfma_f32_16x16x32_bf16 v[96:99], v[152:155], v[192:195], v[96:99]
	v_mfma_f32_16x16x32_bf16 v[84:87], v[144:147], v[200:203], v[84:87]
	v_mfma_f32_16x16x32_bf16 v[80:83], v[152:155], v[200:203], v[80:83]
	v_mfma_f32_16x16x32_bf16 v[124:127], v[148:151], v[180:183], v[124:127]
	v_mfma_f32_16x16x32_bf16 v[120:123], v[156:159], v[180:183], v[120:123]
	v_mfma_f32_16x16x32_bf16 v[116:119], v[148:151], v[188:191], v[116:119]
	v_mfma_f32_16x16x32_bf16 v[112:115], v[156:159], v[188:191], v[112:115]
	v_mfma_f32_16x16x32_bf16 v[100:103], v[148:151], v[196:199], v[100:103]
	v_mfma_f32_16x16x32_bf16 v[96:99], v[156:159], v[196:199], v[96:99]
	v_mfma_f32_16x16x32_bf16 v[84:87], v[148:151], v[204:207], v[84:87]
	v_mfma_f32_16x16x32_bf16 v[80:83], v[156:159], v[204:207], v[80:83]
	v_mfma_f32_16x16x32_bf16 v[108:111], v[160:163], v[176:179], v[108:111]
	v_mfma_f32_16x16x32_bf16 v[104:107], v[168:171], v[176:179], v[104:107]
	v_mfma_f32_16x16x32_bf16 v[92:95], v[160:163], v[184:187], v[92:95]
	v_mfma_f32_16x16x32_bf16 v[88:91], v[168:171], v[184:187], v[88:91]
	v_mfma_f32_16x16x32_bf16 v[76:79], v[160:163], v[192:195], v[76:79]
	v_mfma_f32_16x16x32_bf16 v[72:75], v[168:171], v[192:195], v[72:75]
	v_mfma_f32_16x16x32_bf16 v[68:71], v[160:163], v[200:203], v[68:71]
	v_mfma_f32_16x16x32_bf16 v[64:67], v[168:171], v[200:203], v[64:67]
	v_mfma_f32_16x16x32_bf16 v[108:111], v[164:167], v[180:183], v[108:111]
	v_mfma_f32_16x16x32_bf16 v[104:107], v[172:175], v[180:183], v[104:107]
	v_mfma_f32_16x16x32_bf16 v[92:95], v[164:167], v[188:191], v[92:95]
	v_mfma_f32_16x16x32_bf16 v[88:91], v[172:175], v[188:191], v[88:91]
	v_mfma_f32_16x16x32_bf16 v[76:79], v[164:167], v[196:199], v[76:79]
	v_mfma_f32_16x16x32_bf16 v[72:75], v[172:175], v[196:199], v[72:75]
	v_mfma_f32_16x16x32_bf16 v[68:71], v[164:167], v[204:207], v[68:71]
	v_mfma_f32_16x16x32_bf16 v[64:67], v[172:175], v[204:207], v[64:67]
	s_barrier
	s_add_i32 s71, s57, s50
	v_lshl_add_u64 v[208:209], s[14:15], 0, v[130:131]
	s_mov_b32 m0, s71
	ds_read_b128 v[176:179], v143 offset:16384
	ds_read_b128 v[180:183], v143 offset:17408
	ds_read_b128 v[184:187], v143 offset:18432
	ds_read_b128 v[188:191], v143 offset:19456
	ds_read_b128 v[192:195], v143 offset:20480
	ds_read_b128 v[196:199], v143 offset:21504
	ds_read_b128 v[200:203], v143 offset:22528
	ds_read_b128 v[204:207], v143 offset:23552
	global_load_lds_dwordx4 v[208:209], off
	s_add_i32 m0, s71, 0x2000
	s_add_u32 s72, s14, 0x40000
	v_lshl_add_u64 v[210:211], s[14:15], 0, v[134:135]
	s_addc_u32 s73, s15, 0
	s_add_i32 s71, s58, s50
	global_load_lds_dwordx4 v[210:211], off
	v_lshl_add_u64 v[212:213], s[72:73], 0, v[130:131]
	s_mov_b32 m0, s71
	v_lshl_add_u64 v[214:215], s[46:47], 0, v[132:133]
	global_load_lds_dwordx4 v[212:213], off
	v_lshl_add_u64 v[212:213], s[72:73], 0, v[134:135]
	s_add_i32 m0, s71, 0x2000
	s_nop 0
	global_load_lds_dwordx4 v[212:213], off
	v_lshl_add_u64 v[212:213], s[46:47], 0, v[128:129]
	s_mov_b32 m0, s35
	s_nop 0
	global_load_lds_dwordx4 v[212:213], off
	s_mov_b32 m0, s51
	s_nop 0
	global_load_lds_dwordx4 v[214:215], off
	s_waitcnt vmcnt(8)
	s_waitcnt lgkmcnt(0)
	s_barrier
	s_waitcnt lgkmcnt(0)
	v_mfma_f32_16x16x32_bf16 v[60:63], v[144:147], v[176:179], v[60:63]
	v_mfma_f32_16x16x32_bf16 v[56:59], v[152:155], v[176:179], v[56:59]
	v_mfma_f32_16x16x32_bf16 v[52:55], v[144:147], v[184:187], v[52:55]
	v_mfma_f32_16x16x32_bf16 v[48:51], v[152:155], v[184:187], v[48:51]
	v_mfma_f32_16x16x32_bf16 v[36:39], v[144:147], v[192:195], v[36:39]
	v_mfma_f32_16x16x32_bf16 v[32:35], v[152:155], v[192:195], v[32:35]
	v_mfma_f32_16x16x32_bf16 v[20:23], v[144:147], v[200:203], v[20:23]
	v_mfma_f32_16x16x32_bf16 v[16:19], v[152:155], v[200:203], v[16:19]
	v_mfma_f32_16x16x32_bf16 v[60:63], v[148:151], v[180:183], v[60:63]
	v_mfma_f32_16x16x32_bf16 v[56:59], v[156:159], v[180:183], v[56:59]
	v_mfma_f32_16x16x32_bf16 v[52:55], v[148:151], v[188:191], v[52:55]
	v_mfma_f32_16x16x32_bf16 v[48:51], v[156:159], v[188:191], v[48:51]
	v_mfma_f32_16x16x32_bf16 v[36:39], v[148:151], v[196:199], v[36:39]
	v_mfma_f32_16x16x32_bf16 v[32:35], v[156:159], v[196:199], v[32:35]
	v_mfma_f32_16x16x32_bf16 v[20:23], v[148:151], v[204:207], v[20:23]
	v_mfma_f32_16x16x32_bf16 v[16:19], v[156:159], v[204:207], v[16:19]
	v_mfma_f32_16x16x32_bf16 v[44:47], v[160:163], v[176:179], v[44:47]
	v_mfma_f32_16x16x32_bf16 v[40:43], v[168:171], v[176:179], v[40:43]
	v_mfma_f32_16x16x32_bf16 v[28:31], v[160:163], v[184:187], v[28:31]
	v_mfma_f32_16x16x32_bf16 v[24:27], v[168:171], v[184:187], v[24:27]
	v_mfma_f32_16x16x32_bf16 v[12:15], v[160:163], v[192:195], v[12:15]
	v_mfma_f32_16x16x32_bf16 v[8:11], v[168:171], v[192:195], v[8:11]
	v_mfma_f32_16x16x32_bf16 v[4:7], v[160:163], v[200:203], v[4:7]
	v_mfma_f32_16x16x32_bf16 v[0:3], v[168:171], v[200:203], v[0:3]
	v_mfma_f32_16x16x32_bf16 v[44:47], v[164:167], v[180:183], v[44:47]
	v_mfma_f32_16x16x32_bf16 v[40:43], v[172:175], v[180:183], v[40:43]
	v_mfma_f32_16x16x32_bf16 v[28:31], v[164:167], v[188:191], v[28:31]
	v_mfma_f32_16x16x32_bf16 v[24:27], v[172:175], v[188:191], v[24:27]
	v_mfma_f32_16x16x32_bf16 v[12:15], v[164:167], v[196:199], v[12:15]
	v_mfma_f32_16x16x32_bf16 v[8:11], v[172:175], v[196:199], v[8:11]
	v_mfma_f32_16x16x32_bf16 v[4:7], v[164:167], v[204:207], v[4:7]
	v_mfma_f32_16x16x32_bf16 v[0:3], v[172:175], v[204:207], v[0:3]
	s_barrier
; #define G_STAGE(bufoff, gbase, voff) do { _Pragma("unroll") for (int _i = 0; _i < 2; ++_i) \
;         __builtin_amdgcn_global_load_lds((const unsigned*)((const char*)(gbase) + voff[_i]), (LAS unsigned*)(lds + (bufoff) + ldsw + _i * 8192), 16, 0, 0); } while (0)
; #define G_LDA(dst, b, h) do { _Pragma("unroll") for (int m = 0; m < 4; ++m) _Pragma("unroll") for (int k = 0; k < 2; ++k) dst[m][k] = *(const LAS bf16x8*)(lds + G_SA(b, h) + aoff + m * 2048 + k * 1024); } while (0)
; #define G_LDB(dst, b, h) do { _Pragma("unroll") for (int n = 0; n < 2; ++n) _Pragma("unroll") for (int k = 0; k < 2; ++k) dst[n][k] = *(const LAS bf16x8*)(lds + G_SB(b, h) + boff + n * 2048 + k * 1024); } while (0)
; #define G_MMA(ai, bj, At_, Bt_) do { __builtin_amdgcn_s_setprio(1); _Pragma("unroll") for (int m = 0; m < 4; ++m) _Pragma("unroll") for (int n = 0; n < 2; ++n) _Pragma("unroll") for (int k = 0; k < 2; ++k) \
;         acc[ai][bj][m][n] = __builtin_amdgcn_mfma_f32_16x16x32_bf16(Bt_[n][k], At_[m][k], acc[ai][bj][m][n], 0, 0, 0); __builtin_amdgcn_s_setprio(0); } while (0)
; #define WAIT_V(n) asm volatile("s_waitcnt vmcnt(" #n ")" ::: "memory")
; #define WAIT_L(n) asm volatile("s_waitcnt lgkmcnt(" #n ")" ::: "memory")
; #define BAR __builtin_amdgcn_s_barrier()
; #define SCHED __builtin_amdgcn_sched_barrier(0)
; template <class Get, class Epi>
; DI void gemm_loop(int ntiles, int ld, char* shm, const Get& get, const Epi& epi) {
;     ...
;             G_LDB(B0, 1, 0); G_LDB(B1, 1, 1); SCHED; G_LDA(At, 1, 0); G_STAGE(G_SA(0, 1), a2 + hstep, voffA);
;             WAIT_V(8); WAIT_L(0); BAR; G_MMA(0, 0, At, B0); G_MMA(0, 1, At, B1); BAR; SCHED;
;             G_LDA(At, 1, 1); G_STAGE(G_SB(1, 0), b3, voffB); G_STAGE(G_SB(1, 1), b3 + hstep, voffB); G_STAGE(G_SA(1, 0), a3, voffA);
;             WAIT_V(8); WAIT_L(0); BAR; G_MMA(1, 0, At, B0); G_MMA(1, 1, At, B1); BAR; SCHED;
;         }
	s_add_i32 s71, 0, 0x18000
	s_add_i32 s72, 0, 0x1c000
	v_add_u32_e32 v156, s71, v140
	v_add_u32_e32 v172, s72, v140
	ds_read_b128 v[144:147], v156
	ds_read_b128 v[148:151], v156 offset:1024
	ds_read_b128 v[152:155], v156 offset:2048
	ds_read_b128 v[156:159], v156 offset:3072
	ds_read_b128 v[160:163], v172
	ds_read_b128 v[164:167], v172 offset:1024
	ds_read_b128 v[168:171], v172 offset:2048
	ds_read_b128 v[172:175], v172 offset:3072
	s_add_u32 s46, s46, 0x40000
	s_addc_u32 s47, s47, 0
	s_mov_b32 m0, s52
	v_lshl_add_u64 v[216:217], s[46:47], 0, v[128:129]
	ds_read_b128 v[176:179], v143 offset:32768
	ds_read_b128 v[180:183], v143 offset:33792
	ds_read_b128 v[184:187], v143 offset:34816
	ds_read_b128 v[188:191], v143 offset:35840
	ds_read_b128 v[192:195], v143 offset:36864
	ds_read_b128 v[196:199], v143 offset:37888
	ds_read_b128 v[200:203], v143 offset:38912
	ds_read_b128 v[204:207], v143 offset:39936
	global_load_lds_dwordx4 v[216:217], off
	v_lshl_add_u64 v[216:217], s[46:47], 0, v[132:133]
	s_mov_b32 m0, s53
	s_nop 0
	global_load_lds_dwordx4 v[216:217], off
	s_waitcnt vmcnt(8)
	s_waitcnt lgkmcnt(0)
	s_barrier
	s_waitcnt lgkmcnt(0)
	v_mfma_f32_16x16x32_bf16 v[124:127], v[144:147], v[176:179], v[124:127]
	v_mfma_f32_16x16x32_bf16 v[120:123], v[152:155], v[176:179], v[120:123]
	v_mfma_f32_16x16x32_bf16 v[116:119], v[144:147], v[184:187], v[116:119]
	v_mfma_f32_16x16x32_bf16 v[112:115], v[152:155], v[184:187], v[112:115]
	v_mfma_f32_16x16x32_bf16 v[100:103], v[144:147], v[192:195], v[100:103]
	v_mfma_f32_16x16x32_bf16 v[96:99], v[152:155], v[192:195], v[96:99]
	v_mfma_f32_16x16x32_bf16 v[84:87], v[144:147], v[200:203], v[84:87]
	v_mfma_f32_16x16x32_bf16 v[80:83], v[152:155], v[200:203], v[80:83]
	v_mfma_f32_16x16x32_bf16 v[124:127], v[148:151], v[180:183], v[124:127]
	v_mfma_f32_16x16x32_bf16 v[120:123], v[156:159], v[180:183], v[120:123]
	v_mfma_f32_16x16x32_bf16 v[116:119], v[148:151], v[188:191], v[116:119]
	v_mfma_f32_16x16x32_bf16 v[112:115], v[156:159], v[188:191], v[112:115]
	v_mfma_f32_16x16x32_bf16 v[100:103], v[148:151], v[196:199], v[100:103]
	v_mfma_f32_16x16x32_bf16 v[96:99], v[156:159], v[196:199], v[96:99]
	v_mfma_f32_16x16x32_bf16 v[84:87], v[148:151], v[204:207], v[84:87]
	v_mfma_f32_16x16x32_bf16 v[80:83], v[156:159], v[204:207], v[80:83]
	v_mfma_f32_16x16x32_bf16 v[108:111], v[160:163], v[176:179], v[108:111]
	v_mfma_f32_16x16x32_bf16 v[104:107], v[168:171], v[176:179], v[104:107]
	v_mfma_f32_16x16x32_bf16 v[92:95], v[160:163], v[184:187], v[92:95]
	v_mfma_f32_16x16x32_bf16 v[88:91], v[168:171], v[184:187], v[88:91]
	v_mfma_f32_16x16x32_bf16 v[76:79], v[160:163], v[192:195], v[76:79]
	v_mfma_f32_16x16x32_bf16 v[72:75], v[168:171], v[192:195], v[72:75]
	v_mfma_f32_16x16x32_bf16 v[68:71], v[160:163], v[200:203], v[68:71]
	v_mfma_f32_16x16x32_bf16 v[64:67], v[168:171], v[200:203], v[64:67]
	v_mfma_f32_16x16x32_bf16 v[108:111], v[164:167], v[180:183], v[108:111]
	v_mfma_f32_16x16x32_bf16 v[104:107], v[172:175], v[180:183], v[104:107]
	v_mfma_f32_16x16x32_bf16 v[92:95], v[164:167], v[188:191], v[92:95]
	v_mfma_f32_16x16x32_bf16 v[88:91], v[172:175], v[188:191], v[88:91]
	v_mfma_f32_16x16x32_bf16 v[76:79], v[164:167], v[196:199], v[76:79]
	v_mfma_f32_16x16x32_bf16 v[72:75], v[172:175], v[196:199], v[72:75]
	v_mfma_f32_16x16x32_bf16 v[68:71], v[164:167], v[204:207], v[68:71]
	v_mfma_f32_16x16x32_bf16 v[64:67], v[172:175], v[204:207], v[64:67]
	s_barrier
	s_add_i32 s46, s71, s50
	v_lshl_add_u64 v[208:209], v[208:209], 0, s[8:9]
	s_mov_b32 m0, s46
	ds_read_b128 v[176:179], v143 offset:49152
	ds_read_b128 v[180:183], v143 offset:50176
	ds_read_b128 v[184:187], v143 offset:51200
	ds_read_b128 v[188:191], v143 offset:52224
	ds_read_b128 v[192:195], v143 offset:53248
	ds_read_b128 v[196:199], v143 offset:54272
	ds_read_b128 v[200:203], v143 offset:55296
	ds_read_b128 v[204:207], v143 offset:56320
	global_load_lds_dwordx4 v[208:209], off
	s_add_i32 m0, s46, 0x2000
	s_add_u32 s14, s14, 0x40080
	v_lshl_add_u64 v[208:209], v[210:211], 0, s[8:9]
	s_addc_u32 s15, s15, 0
	s_add_i32 s46, s72, s50
	global_load_lds_dwordx4 v[208:209], off
	v_lshl_add_u64 v[208:209], s[14:15], 0, v[130:131]
	s_mov_b32 m0, s46
	s_nop 0
	global_load_lds_dwordx4 v[208:209], off
	v_lshl_add_u64 v[208:209], s[14:15], 0, v[134:135]
	s_add_i32 m0, s46, 0x2000
	s_nop 0
	global_load_lds_dwordx4 v[208:209], off
	v_lshl_add_u64 v[208:209], v[212:213], 0, s[8:9]
	s_mov_b32 m0, s55
	s_nop 0
	global_load_lds_dwordx4 v[208:209], off
	v_lshl_add_u64 v[208:209], v[214:215], 0, s[8:9]
	s_mov_b32 m0, s56
	s_nop 0
	global_load_lds_dwordx4 v[208:209], off
	s_waitcnt vmcnt(8)
	s_waitcnt lgkmcnt(0)
	s_barrier
	s_waitcnt lgkmcnt(0)
	v_mfma_f32_16x16x32_bf16 v[60:63], v[144:147], v[176:179], v[60:63]
	v_mfma_f32_16x16x32_bf16 v[56:59], v[152:155], v[176:179], v[56:59]
	v_mfma_f32_16x16x32_bf16 v[52:55], v[144:147], v[184:187], v[52:55]
	v_mfma_f32_16x16x32_bf16 v[48:51], v[152:155], v[184:187], v[48:51]
	v_mfma_f32_16x16x32_bf16 v[36:39], v[144:147], v[192:195], v[36:39]
	v_mfma_f32_16x16x32_bf16 v[32:35], v[152:155], v[192:195], v[32:35]
	v_mfma_f32_16x16x32_bf16 v[20:23], v[144:147], v[200:203], v[20:23]
	v_mfma_f32_16x16x32_bf16 v[16:19], v[152:155], v[200:203], v[16:19]
	v_mfma_f32_16x16x32_bf16 v[60:63], v[148:151], v[180:183], v[60:63]
	v_mfma_f32_16x16x32_bf16 v[56:59], v[156:159], v[180:183], v[56:59]
	v_mfma_f32_16x16x32_bf16 v[52:55], v[148:151], v[188:191], v[52:55]
	v_mfma_f32_16x16x32_bf16 v[48:51], v[156:159], v[188:191], v[48:51]
	v_mfma_f32_16x16x32_bf16 v[36:39], v[148:151], v[196:199], v[36:39]
	v_mfma_f32_16x16x32_bf16 v[32:35], v[156:159], v[196:199], v[32:35]
	v_mfma_f32_16x16x32_bf16 v[20:23], v[148:151], v[204:207], v[20:23]
	v_mfma_f32_16x16x32_bf16 v[16:19], v[156:159], v[204:207], v[16:19]
	v_mfma_f32_16x16x32_bf16 v[44:47], v[160:163], v[176:179], v[44:47]
	v_mfma_f32_16x16x32_bf16 v[40:43], v[168:171], v[176:179], v[40:43]
	v_mfma_f32_16x16x32_bf16 v[28:31], v[160:163], v[184:187], v[28:31]
	v_mfma_f32_16x16x32_bf16 v[24:27], v[168:171], v[184:187], v[24:27]
	v_mfma_f32_16x16x32_bf16 v[12:15], v[160:163], v[192:195], v[12:15]
	v_mfma_f32_16x16x32_bf16 v[8:11], v[168:171], v[192:195], v[8:11]
	v_mfma_f32_16x16x32_bf16 v[4:7], v[160:163], v[200:203], v[4:7]
	v_mfma_f32_16x16x32_bf16 v[0:3], v[168:171], v[200:203], v[0:3]
	v_mfma_f32_16x16x32_bf16 v[44:47], v[164:167], v[180:183], v[44:47]
	v_mfma_f32_16x16x32_bf16 v[40:43], v[172:175], v[180:183], v[40:43]
	v_mfma_f32_16x16x32_bf16 v[28:31], v[164:167], v[188:191], v[28:31]
	v_mfma_f32_16x16x32_bf16 v[24:27], v[172:175], v[188:191], v[24:27]
	v_mfma_f32_16x16x32_bf16 v[12:15], v[164:167], v[196:199], v[12:15]
	v_mfma_f32_16x16x32_bf16 v[8:11], v[172:175], v[196:199], v[8:11]
	v_mfma_f32_16x16x32_bf16 v[4:7], v[164:167], v[204:207], v[4:7]
	v_mfma_f32_16x16x32_bf16 v[0:3], v[172:175], v[204:207], v[0:3]
	s_barrier
	s_add_i32 s70, s70, 2
	s_add_u32 s48, s48, 0x100
	s_addc_u32 s49, s49, 0
	s_add_u32 s64, s64, 0x100
	s_addc_u32 s65, s65, 0
	s_cmp_gt_u32 s70, 13
	s_cbranch_scc0 .LBB0_3141

; #define G_STAGE(bufoff, gbase, voff) do { _Pragma("unroll") for (int _i = 0; _i < 2; ++_i) \
;         __builtin_amdgcn_global_load_lds((const unsigned*)((const char*)(gbase) + voff[_i]), (LAS unsigned*)(lds + (bufoff) + ldsw + _i * 8192), 16, 0, 0); } while (0)
; #define G_LDA(dst, b, h) do { _Pragma("unroll") for (int m = 0; m < 4; ++m) _Pragma("unroll") for (int k = 0; k < 2; ++k) dst[m][k] = *(const LAS bf16x8*)(lds + G_SA(b, h) + aoff + m * 2048 + k * 1024); } while (0)
; #define G_LDB(dst, b, h) do { _Pragma("unroll") for (int n = 0; n < 2; ++n) _Pragma("unroll") for (int k = 0; k < 2; ++k) dst[n][k] = *(const LAS bf16x8*)(lds + G_SB(b, h) + boff + n * 2048 + k * 1024); } while (0)
; #define G_MMA(ai, bj, At_, Bt_) do { __builtin_amdgcn_s_setprio(1); _Pragma("unroll") for (int m = 0; m < 4; ++m) _Pragma("unroll") for (int n = 0; n < 2; ++n) _Pragma("unroll") for (int k = 0; k < 2; ++k) \
;         acc[ai][bj][m][n] = __builtin_amdgcn_mfma_f32_16x16x32_bf16(Bt_[n][k], At_[m][k], acc[ai][bj][m][n], 0, 0, 0); __builtin_amdgcn_s_setprio(0); } while (0)
; #define WAIT_V(n) asm volatile("s_waitcnt vmcnt(" #n ")" ::: "memory")
; #define WAIT_L(n) asm volatile("s_waitcnt lgkmcnt(" #n ")" ::: "memory")
; #define BAR __builtin_amdgcn_s_barrier()
; #define SCHED __builtin_amdgcn_sched_barrier(0)
; template <class Get, class Epi>
; DI void gemm_loop(int ntiles, int ld, char* shm, const Get& get, const Epi& epi) {
;     ...
;             G_LDB(B0, 0, 0); G_LDB(B1, 0, 1); SCHED; G_LDA(At, 0, 0); G_STAGE(G_SA(1, 1), a1 + hstep, voffA);
;             WAIT_V(8); WAIT_L(0); BAR; G_MMA(0, 0, At, B0); G_MMA(0, 1, At, B1); BAR; SCHED;
;             G_LDA(At, 0, 1); G_STAGE(G_SB(0, 0), b2, voffB); G_STAGE(G_SB(0, 1), b2 + hstep, voffB); G_STAGE(G_SA(0, 0), a2, voffA);
;             WAIT_V(8); WAIT_L(0); BAR; G_MMA(1, 0, At, B0); G_MMA(1, 1, At, B1); BAR; SCHED;
.Lrj_3466_0:
	s_waitcnt lgkmcnt(0)
	s_barrier
	s_waitcnt lgkmcnt(0)
	v_mfma_f32_16x16x32_bf16 v[124:127], v[128:131], v[180:183], 0
	v_mfma_f32_16x16x32_bf16 v[120:123], v[136:139], v[180:183], 0
	v_mfma_f32_16x16x32_bf16 v[116:119], v[128:131], v[188:191], 0
	v_mfma_f32_16x16x32_bf16 v[112:115], v[136:139], v[188:191], 0
	v_mfma_f32_16x16x32_bf16 v[108:111], v[128:131], v[196:199], 0
	v_mfma_f32_16x16x32_bf16 v[104:107], v[136:139], v[196:199], 0
	v_mfma_f32_16x16x32_bf16 v[100:103], v[128:131], v[204:207], 0
	v_mfma_f32_16x16x32_bf16 v[96:99], v[136:139], v[204:207], 0
	v_mfma_f32_16x16x32_bf16 v[124:127], v[132:135], v[184:187], v[124:127]
	v_mfma_f32_16x16x32_bf16 v[120:123], v[140:143], v[184:187], v[120:123]
	v_mfma_f32_16x16x32_bf16 v[116:119], v[132:135], v[192:195], v[116:119]
	v_mfma_f32_16x16x32_bf16 v[112:115], v[140:143], v[192:195], v[112:115]
	v_mfma_f32_16x16x32_bf16 v[108:111], v[132:135], v[200:203], v[108:111]
	v_mfma_f32_16x16x32_bf16 v[104:107], v[140:143], v[200:203], v[104:107]
	v_mfma_f32_16x16x32_bf16 v[100:103], v[132:135], v[208:211], v[100:103]
	v_mfma_f32_16x16x32_bf16 v[96:99], v[140:143], v[208:211], v[96:99]
	v_mfma_f32_16x16x32_bf16 v[60:63], v[158:161], v[180:183], 0
	v_mfma_f32_16x16x32_bf16 v[56:59], v[172:175], v[180:183], 0
	v_mfma_f32_16x16x32_bf16 v[52:55], v[158:161], v[188:191], 0
	v_mfma_f32_16x16x32_bf16 v[48:51], v[172:175], v[188:191], 0
	v_mfma_f32_16x16x32_bf16 v[44:47], v[158:161], v[196:199], 0
	v_mfma_f32_16x16x32_bf16 v[40:43], v[172:175], v[196:199], 0
	v_mfma_f32_16x16x32_bf16 v[36:39], v[158:161], v[204:207], 0
	v_mfma_f32_16x16x32_bf16 v[32:35], v[172:175], v[204:207], 0
	v_mfma_f32_16x16x32_bf16 v[60:63], v[162:165], v[184:187], v[60:63]
	v_mfma_f32_16x16x32_bf16 v[56:59], v[176:179], v[184:187], v[56:59]
	v_mfma_f32_16x16x32_bf16 v[52:55], v[162:165], v[192:195], v[52:55]
	v_mfma_f32_16x16x32_bf16 v[48:51], v[176:179], v[192:195], v[48:51]
	v_mfma_f32_16x16x32_bf16 v[44:47], v[162:165], v[200:203], v[44:47]
	v_mfma_f32_16x16x32_bf16 v[40:43], v[176:179], v[200:203], v[40:43]
	v_mfma_f32_16x16x32_bf16 v[36:39], v[162:165], v[208:211], v[36:39]
	v_mfma_f32_16x16x32_bf16 v[32:35], v[176:179], v[208:211], v[32:35]
	s_barrier
	s_add_i32 s72, s56, s48
	v_lshl_add_u64 v[144:145], s[14:15], 0, v[148:149]
	s_mov_b32 m0, s72
	ds_read_b128 v[180:183], v171 offset:16384
	ds_read_b128 v[184:187], v171 offset:17408
	ds_read_b128 v[188:191], v171 offset:18432
	ds_read_b128 v[192:195], v171 offset:19456
	ds_read_b128 v[196:199], v171 offset:20480
	ds_read_b128 v[200:203], v171 offset:21504
	ds_read_b128 v[204:207], v171 offset:22528
	ds_read_b128 v[208:211], v171 offset:23552
	global_load_lds_dwordx4 v[144:145], off
	s_add_i32 m0, s72, 0x2000
	s_add_u32 s72, s14, 0x40000
	v_lshl_add_u64 v[166:167], s[14:15], 0, v[152:153]
	s_addc_u32 s73, s15, 0
	s_add_i32 s74, s57, s48
	global_load_lds_dwordx4 v[166:167], off
	v_lshl_add_u64 v[212:213], s[72:73], 0, v[148:149]
	s_mov_b32 m0, s74
	v_lshl_add_u64 v[214:215], s[46:47], 0, v[150:151]
	global_load_lds_dwordx4 v[212:213], off
	v_lshl_add_u64 v[212:213], s[72:73], 0, v[152:153]
	s_add_i32 m0, s74, 0x2000
	s_nop 0
	global_load_lds_dwordx4 v[212:213], off
	v_lshl_add_u64 v[212:213], s[46:47], 0, v[146:147]
	s_mov_b32 m0, s43
	s_nop 0
	global_load_lds_dwordx4 v[212:213], off
	s_mov_b32 m0, s49
	s_nop 0
	global_load_lds_dwordx4 v[214:215], off
	s_cmp_lg_u32 s100, 0
	s_cbranch_scc0 .Lrf_3466_1
	s_waitcnt vmcnt(16)
	s_branch .Lrj_3466_1

; #define G_STAGE(bufoff, gbase, voff) do { _Pragma("unroll") for (int _i = 0; _i < 2; ++_i) \
;         __builtin_amdgcn_global_load_lds((const unsigned*)((const char*)(gbase) + voff[_i]), (LAS unsigned*)(lds + (bufoff) + ldsw + _i * 8192), 16, 0, 0); } while (0)
; #define G_LDA(dst, b, h) do { _Pragma("unroll") for (int m = 0; m < 4; ++m) _Pragma("unroll") for (int k = 0; k < 2; ++k) dst[m][k] = *(const LAS bf16x8*)(lds + G_SA(b, h) + aoff + m * 2048 + k * 1024); } while (0)
; #define G_LDB(dst, b, h) do { _Pragma("unroll") for (int n = 0; n < 2; ++n) _Pragma("unroll") for (int k = 0; k < 2; ++k) dst[n][k] = *(const LAS bf16x8*)(lds + G_SB(b, h) + boff + n * 2048 + k * 1024); } while (0)
; #define G_MMA(ai, bj, At_, Bt_) do { __builtin_amdgcn_s_setprio(1); _Pragma("unroll") for (int m = 0; m < 4; ++m) _Pragma("unroll") for (int n = 0; n < 2; ++n) _Pragma("unroll") for (int k = 0; k < 2; ++k) \
;         acc[ai][bj][m][n] = __builtin_amdgcn_mfma_f32_16x16x32_bf16(Bt_[n][k], At_[m][k], acc[ai][bj][m][n], 0, 0, 0); __builtin_amdgcn_s_setprio(0); } while (0)
; #define WAIT_V(n) asm volatile("s_waitcnt vmcnt(" #n ")" ::: "memory")
; #define WAIT_L(n) asm volatile("s_waitcnt lgkmcnt(" #n ")" ::: "memory")
; #define BAR __builtin_amdgcn_s_barrier()
; #define SCHED __builtin_amdgcn_sched_barrier(0)
; template <class Get, class Epi>
; DI void gemm_loop(int ntiles, int ld, char* shm, const Get& get, const Epi& epi) {
;     ...
;             WAIT_V(8); WAIT_L(0); BAR; G_MMA(1, 0, At, B0); G_MMA(1, 1, At, B1); BAR; SCHED;
;             G_LDB(B0, 1, 0); G_LDB(B1, 1, 1); SCHED; G_LDA(At, 1, 0); G_STAGE(G_SA(0, 1), a2 + hstep, voffA);
;             WAIT_V(8); WAIT_L(0); BAR; G_MMA(0, 0, At, B0); G_MMA(0, 1, At, B1); BAR; SCHED;
;             G_LDA(At, 1, 1); G_STAGE(G_SB(1, 0), b3, voffB); G_STAGE(G_SB(1, 1), b3 + hstep, voffB); G_STAGE(G_SA(1, 0), a3, voffA);
.Lrj_3466_1:
	s_waitcnt lgkmcnt(0)
	s_barrier
	s_waitcnt lgkmcnt(0)
	v_mfma_f32_16x16x32_bf16 v[92:95], v[128:131], v[180:183], 0
	v_mfma_f32_16x16x32_bf16 v[88:91], v[136:139], v[180:183], 0
	v_mfma_f32_16x16x32_bf16 v[84:87], v[128:131], v[188:191], 0
	v_mfma_f32_16x16x32_bf16 v[80:83], v[136:139], v[188:191], 0
	v_mfma_f32_16x16x32_bf16 v[76:79], v[128:131], v[196:199], 0
	v_mfma_f32_16x16x32_bf16 v[72:75], v[136:139], v[196:199], 0
	v_mfma_f32_16x16x32_bf16 v[68:71], v[128:131], v[204:207], 0
	v_mfma_f32_16x16x32_bf16 v[64:67], v[136:139], v[204:207], 0
	v_mfma_f32_16x16x32_bf16 v[92:95], v[132:135], v[184:187], v[92:95]
	v_mfma_f32_16x16x32_bf16 v[88:91], v[140:143], v[184:187], v[88:91]
	v_mfma_f32_16x16x32_bf16 v[84:87], v[132:135], v[192:195], v[84:87]
	v_mfma_f32_16x16x32_bf16 v[80:83], v[140:143], v[192:195], v[80:83]
	v_mfma_f32_16x16x32_bf16 v[76:79], v[132:135], v[200:203], v[76:79]
	v_mfma_f32_16x16x32_bf16 v[72:75], v[140:143], v[200:203], v[72:75]
	v_mfma_f32_16x16x32_bf16 v[68:71], v[132:135], v[208:211], v[68:71]
	v_mfma_f32_16x16x32_bf16 v[64:67], v[140:143], v[208:211], v[64:67]
	v_mfma_f32_16x16x32_bf16 v[28:31], v[158:161], v[180:183], 0
	v_mfma_f32_16x16x32_bf16 v[24:27], v[172:175], v[180:183], 0
	v_mfma_f32_16x16x32_bf16 v[20:23], v[158:161], v[188:191], 0
	v_mfma_f32_16x16x32_bf16 v[16:19], v[172:175], v[188:191], 0
	v_mfma_f32_16x16x32_bf16 v[12:15], v[158:161], v[196:199], 0
	v_mfma_f32_16x16x32_bf16 v[8:11], v[172:175], v[196:199], 0
	v_mfma_f32_16x16x32_bf16 v[4:7], v[158:161], v[204:207], 0
	v_mfma_f32_16x16x32_bf16 v[0:3], v[172:175], v[204:207], 0
	v_mfma_f32_16x16x32_bf16 v[28:31], v[162:165], v[184:187], v[28:31]
	v_mfma_f32_16x16x32_bf16 v[24:27], v[176:179], v[184:187], v[24:27]
	v_mfma_f32_16x16x32_bf16 v[20:23], v[162:165], v[192:195], v[20:23]
	v_mfma_f32_16x16x32_bf16 v[16:19], v[176:179], v[192:195], v[16:19]
	v_mfma_f32_16x16x32_bf16 v[12:15], v[162:165], v[200:203], v[12:15]
	v_mfma_f32_16x16x32_bf16 v[8:11], v[176:179], v[200:203], v[8:11]
	v_mfma_f32_16x16x32_bf16 v[4:7], v[162:165], v[208:211], v[4:7]
	v_mfma_f32_16x16x32_bf16 v[0:3], v[176:179], v[208:211], v[0:3]
	s_barrier
	s_add_i32 s72, 0, 0x18000
	s_add_i32 s73, 0, 0x1c000
	v_add_u32_e32 v140, s72, v168
	v_add_u32_e32 v176, s73, v168
	ds_read_b128 v[128:131], v140
	ds_read_b128 v[132:135], v140 offset:1024
	ds_read_b128 v[136:139], v140 offset:2048
	ds_read_b128 v[140:143], v140 offset:3072
	ds_read_b128 v[158:161], v176
	ds_read_b128 v[162:165], v176 offset:1024
	ds_read_b128 v[172:175], v176 offset:2048
	ds_read_b128 v[176:179], v176 offset:3072
	s_add_u32 s46, s46, 0x40000
	s_addc_u32 s47, s47, 0
	s_mov_b32 m0, s50
	v_lshl_add_u64 v[216:217], s[46:47], 0, v[146:147]
	ds_read_b128 v[180:183], v171 offset:32768
	ds_read_b128 v[184:187], v171 offset:33792
	ds_read_b128 v[188:191], v171 offset:34816
	ds_read_b128 v[192:195], v171 offset:35840
	ds_read_b128 v[196:199], v171 offset:36864
	ds_read_b128 v[200:203], v171 offset:37888
	ds_read_b128 v[204:207], v171 offset:38912
	ds_read_b128 v[208:211], v171 offset:39936
	global_load_lds_dwordx4 v[216:217], off
	v_lshl_add_u64 v[216:217], s[46:47], 0, v[150:151]
	s_mov_b32 m0, s51
	s_nop 0
	global_load_lds_dwordx4 v[216:217], off
	s_waitcnt vmcnt(8)
	s_waitcnt lgkmcnt(0)
	s_barrier
	s_waitcnt lgkmcnt(0)
	v_mfma_f32_16x16x32_bf16 v[124:127], v[128:131], v[180:183], v[124:127]
	v_mfma_f32_16x16x32_bf16 v[120:123], v[136:139], v[180:183], v[120:123]
	v_mfma_f32_16x16x32_bf16 v[116:119], v[128:131], v[188:191], v[116:119]
	v_mfma_f32_16x16x32_bf16 v[112:115], v[136:139], v[188:191], v[112:115]
	v_mfma_f32_16x16x32_bf16 v[108:111], v[128:131], v[196:199], v[108:111]
	v_mfma_f32_16x16x32_bf16 v[104:107], v[136:139], v[196:199], v[104:107]
	v_mfma_f32_16x16x32_bf16 v[100:103], v[128:131], v[204:207], v[100:103]
	v_mfma_f32_16x16x32_bf16 v[96:99], v[136:139], v[204:207], v[96:99]
	v_mfma_f32_16x16x32_bf16 v[124:127], v[132:135], v[184:187], v[124:127]
	v_mfma_f32_16x16x32_bf16 v[120:123], v[140:143], v[184:187], v[120:123]
	v_mfma_f32_16x16x32_bf16 v[116:119], v[132:135], v[192:195], v[116:119]
	v_mfma_f32_16x16x32_bf16 v[112:115], v[140:143], v[192:195], v[112:115]
	v_mfma_f32_16x16x32_bf16 v[108:111], v[132:135], v[200:203], v[108:111]
	v_mfma_f32_16x16x32_bf16 v[104:107], v[140:143], v[200:203], v[104:107]
	v_mfma_f32_16x16x32_bf16 v[100:103], v[132:135], v[208:211], v[100:103]
	v_mfma_f32_16x16x32_bf16 v[96:99], v[140:143], v[208:211], v[96:99]
	v_mfma_f32_16x16x32_bf16 v[60:63], v[158:161], v[180:183], v[60:63]
	v_mfma_f32_16x16x32_bf16 v[56:59], v[172:175], v[180:183], v[56:59]
	v_mfma_f32_16x16x32_bf16 v[52:55], v[158:161], v[188:191], v[52:55]
	v_mfma_f32_16x16x32_bf16 v[48:51], v[172:175], v[188:191], v[48:51]
	v_mfma_f32_16x16x32_bf16 v[44:47], v[158:161], v[196:199], v[44:47]
	v_mfma_f32_16x16x32_bf16 v[40:43], v[172:175], v[196:199], v[40:43]
	v_mfma_f32_16x16x32_bf16 v[36:39], v[158:161], v[204:207], v[36:39]
	v_mfma_f32_16x16x32_bf16 v[32:35], v[172:175], v[204:207], v[32:35]
	v_mfma_f32_16x16x32_bf16 v[60:63], v[162:165], v[184:187], v[60:63]
	v_mfma_f32_16x16x32_bf16 v[56:59], v[176:179], v[184:187], v[56:59]
	v_mfma_f32_16x16x32_bf16 v[52:55], v[162:165], v[192:195], v[52:55]
	v_mfma_f32_16x16x32_bf16 v[48:51], v[176:179], v[192:195], v[48:51]
	v_mfma_f32_16x16x32_bf16 v[44:47], v[162:165], v[200:203], v[44:47]
	v_mfma_f32_16x16x32_bf16 v[40:43], v[176:179], v[200:203], v[40:43]
	v_mfma_f32_16x16x32_bf16 v[36:39], v[162:165], v[208:211], v[36:39]
	v_mfma_f32_16x16x32_bf16 v[32:35], v[176:179], v[208:211], v[32:35]
	s_barrier
; #define G_STAGE(bufoff, gbase, voff) do { _Pragma("unroll") for (int _i = 0; _i < 2; ++_i) \
;         __builtin_amdgcn_global_load_lds((const unsigned*)((const char*)(gbase) + voff[_i]), (LAS unsigned*)(lds + (bufoff) + ldsw + _i * 8192), 16, 0, 0); } while (0)
; #define G_LDA(dst, b, h) do { _Pragma("unroll") for (int m = 0; m < 4; ++m) _Pragma("unroll") for (int k = 0; k < 2; ++k) dst[m][k] = *(const LAS bf16x8*)(lds + G_SA(b, h) + aoff + m * 2048 + k * 1024); } while (0)
; #define G_LDB(dst, b, h) do { _Pragma("unroll") for (int n = 0; n < 2; ++n) _Pragma("unroll") for (int k = 0; k < 2; ++k) dst[n][k] = *(const LAS bf16x8*)(lds + G_SB(b, h) + boff + n * 2048 + k * 1024); } while (0)
; #define G_MMA(ai, bj, At_, Bt_) do { __builtin_amdgcn_s_setprio(1); _Pragma("unroll") for (int m = 0; m < 4; ++m) _Pragma("unroll") for (int n = 0; n < 2; ++n) _Pragma("unroll") for (int k = 0; k < 2; ++k) \
;         acc[ai][bj][m][n] = __builtin_amdgcn_mfma_f32_16x16x32_bf16(Bt_[n][k], At_[m][k], acc[ai][bj][m][n], 0, 0, 0); __builtin_amdgcn_s_setprio(0); } while (0)
; #define WAIT_V(n) asm volatile("s_waitcnt vmcnt(" #n ")" ::: "memory")
; #define WAIT_L(n) asm volatile("s_waitcnt lgkmcnt(" #n ")" ::: "memory")
; #define BAR __builtin_amdgcn_s_barrier()
; #define SCHED __builtin_amdgcn_sched_barrier(0)
; template <class Get, class Epi>
; DI void gemm_loop(int ntiles, int ld, char* shm, const Get& get, const Epi& epi) {
;     ...
;             G_LDB(B0, 0, 0); G_LDB(B1, 0, 1); SCHED; G_LDA(At, 0, 0); G_STAGE(G_SA(1, 1), a1 + hstep, voffA);
;             WAIT_V(8); WAIT_L(0); BAR; G_MMA(0, 0, At, B0); G_MMA(0, 1, At, B1); BAR; SCHED;
;     ...
;             G_LDA(At, 1, 1); G_STAGE(G_SB(1, 0), b3, voffB); G_STAGE(G_SB(1, 1), b3 + hstep, voffB); G_STAGE(G_SA(1, 0), a3, voffA);
;             WAIT_V(8); WAIT_L(0); BAR; G_MMA(1, 0, At, B0); G_MMA(1, 1, At, B1); BAR; SCHED;
;         }
	s_add_i32 s46, s72, s48
	v_lshl_add_u64 v[144:145], v[144:145], 0, s[4:5]
	s_mov_b32 m0, s46
	ds_read_b128 v[180:183], v171 offset:49152
	ds_read_b128 v[184:187], v171 offset:50176
	ds_read_b128 v[188:191], v171 offset:51200
	ds_read_b128 v[192:195], v171 offset:52224
	ds_read_b128 v[196:199], v171 offset:53248
	ds_read_b128 v[200:203], v171 offset:54272
	ds_read_b128 v[204:207], v171 offset:55296
	ds_read_b128 v[208:211], v171 offset:56320
	global_load_lds_dwordx4 v[144:145], off
	s_add_i32 m0, s46, 0x2000
	s_add_u32 s14, s14, 0x40080
	v_lshl_add_u64 v[144:145], v[166:167], 0, s[4:5]
	s_addc_u32 s15, s15, 0
	s_add_i32 s46, s73, s48
	global_load_lds_dwordx4 v[144:145], off
	v_lshl_add_u64 v[144:145], s[14:15], 0, v[148:149]
	s_mov_b32 m0, s46
	s_nop 0
	global_load_lds_dwordx4 v[144:145], off
	v_lshl_add_u64 v[144:145], s[14:15], 0, v[152:153]
	s_add_i32 m0, s46, 0x2000
	s_nop 0
	global_load_lds_dwordx4 v[144:145], off
	v_lshl_add_u64 v[144:145], v[212:213], 0, s[4:5]
	s_mov_b32 m0, s54
	s_nop 0
	global_load_lds_dwordx4 v[144:145], off
	v_lshl_add_u64 v[144:145], v[214:215], 0, s[4:5]
	s_mov_b32 m0, s55
	s_nop 0
	global_load_lds_dwordx4 v[144:145], off
	s_waitcnt vmcnt(8)
	s_waitcnt lgkmcnt(0)
	s_barrier
	s_waitcnt lgkmcnt(0)
	v_mfma_f32_16x16x32_bf16 v[92:95], v[128:131], v[180:183], v[92:95]
	v_mfma_f32_16x16x32_bf16 v[88:91], v[136:139], v[180:183], v[88:91]
	v_mfma_f32_16x16x32_bf16 v[84:87], v[128:131], v[188:191], v[84:87]
	v_mfma_f32_16x16x32_bf16 v[80:83], v[136:139], v[188:191], v[80:83]
	v_mfma_f32_16x16x32_bf16 v[76:79], v[128:131], v[196:199], v[76:79]
	v_mfma_f32_16x16x32_bf16 v[72:75], v[136:139], v[196:199], v[72:75]
	v_mfma_f32_16x16x32_bf16 v[68:71], v[128:131], v[204:207], v[68:71]
	v_mfma_f32_16x16x32_bf16 v[64:67], v[136:139], v[204:207], v[64:67]
	v_mfma_f32_16x16x32_bf16 v[92:95], v[132:135], v[184:187], v[92:95]
	v_mfma_f32_16x16x32_bf16 v[88:91], v[140:143], v[184:187], v[88:91]
	v_mfma_f32_16x16x32_bf16 v[84:87], v[132:135], v[192:195], v[84:87]
	v_mfma_f32_16x16x32_bf16 v[80:83], v[140:143], v[192:195], v[80:83]
	v_mfma_f32_16x16x32_bf16 v[76:79], v[132:135], v[200:203], v[76:79]
	v_mfma_f32_16x16x32_bf16 v[72:75], v[140:143], v[200:203], v[72:75]
	v_mfma_f32_16x16x32_bf16 v[68:71], v[132:135], v[208:211], v[68:71]
	v_mfma_f32_16x16x32_bf16 v[64:67], v[140:143], v[208:211], v[64:67]
	v_mfma_f32_16x16x32_bf16 v[28:31], v[158:161], v[180:183], v[28:31]
	v_mfma_f32_16x16x32_bf16 v[24:27], v[172:175], v[180:183], v[24:27]
	v_mfma_f32_16x16x32_bf16 v[20:23], v[158:161], v[188:191], v[20:23]
	v_mfma_f32_16x16x32_bf16 v[16:19], v[172:175], v[188:191], v[16:19]
	v_mfma_f32_16x16x32_bf16 v[12:15], v[158:161], v[196:199], v[12:15]
	v_mfma_f32_16x16x32_bf16 v[8:11], v[172:175], v[196:199], v[8:11]
	v_mfma_f32_16x16x32_bf16 v[4:7], v[158:161], v[204:207], v[4:7]
	v_mfma_f32_16x16x32_bf16 v[0:3], v[172:175], v[204:207], v[0:3]
	v_mfma_f32_16x16x32_bf16 v[28:31], v[162:165], v[184:187], v[28:31]
	v_mfma_f32_16x16x32_bf16 v[24:27], v[176:179], v[184:187], v[24:27]
	v_mfma_f32_16x16x32_bf16 v[20:23], v[162:165], v[192:195], v[20:23]
	v_mfma_f32_16x16x32_bf16 v[16:19], v[176:179], v[192:195], v[16:19]
	v_mfma_f32_16x16x32_bf16 v[12:15], v[162:165], v[200:203], v[12:15]
	v_mfma_f32_16x16x32_bf16 v[8:11], v[176:179], v[200:203], v[8:11]
	v_mfma_f32_16x16x32_bf16 v[4:7], v[162:165], v[208:211], v[4:7]
	v_mfma_f32_16x16x32_bf16 v[0:3], v[176:179], v[208:211], v[0:3]
	s_barrier
	s_add_i32 s71, s71, 2
	s_add_u32 s44, s44, 0x100
	s_addc_u32 s45, s45, 0
	s_add_u32 s65, s65, 0x100
	s_addc_u32 s70, s70, 0
	s_cmp_gt_u32 s71, 13
	s_cbranch_scc0 .LBB0_3466
	s_branch .Lpost_3466
.LBB0_3466:
	ds_read_b128 v[128:131], v169
	ds_read_b128 v[132:135], v169 offset:1024
	ds_read_b128 v[136:139], v169 offset:2048
	ds_read_b128 v[140:143], v169 offset:3072
	ds_read_b128 v[158:161], v170
	ds_read_b128 v[162:165], v170 offset:1024
	ds_read_b128 v[172:175], v170 offset:2048
	ds_read_b128 v[176:179], v170 offset:3072
	s_add_u32 s14, s44, 0xfffc0080
	s_addc_u32 s15, s45, -1
	s_cmp_eq_u32 s71, 12
	s_cselect_b32 s47, s3, s15
	s_cselect_b32 s46, s35, s14
	s_cselect_b32 s15, s37, s70
	s_cselect_b32 s14, s64, s65
	v_lshl_add_u64 v[144:145], s[44:45], 0, v[154:155]
	s_add_i32 m0, s43, 0xc000
	ds_read_b128 v[180:183], v171
	ds_read_b128 v[184:187], v171 offset:1024
	ds_read_b128 v[188:191], v171 offset:2048
	ds_read_b128 v[192:195], v171 offset:3072
	ds_read_b128 v[196:199], v171 offset:4096
	ds_read_b128 v[200:203], v171 offset:5120
	ds_read_b128 v[204:207], v171 offset:6144
	ds_read_b128 v[208:211], v171 offset:7168
	global_load_lds_dwordx4 v[144:145], off
	v_lshl_add_u64 v[144:145], s[44:45], 0, v[156:157]
	s_add_i32 m0, s43, 0xe000
	s_nop 0
	global_load_lds_dwordx4 v[144:145], off
	s_waitcnt vmcnt(8)
	s_waitcnt lgkmcnt(0)
	s_barrier
; #define G_STAGE(bufoff, gbase, voff) do { _Pragma("unroll") for (int _i = 0; _i < 2; ++_i) \
;         __builtin_amdgcn_global_load_lds((const unsigned*)((const char*)(gbase) + voff[_i]), (LAS unsigned*)(lds + (bufoff) + ldsw + _i * 8192), 16, 0, 0); } while (0)
; #define G_LDA(dst, b, h) do { _Pragma("unroll") for (int m = 0; m < 4; ++m) _Pragma("unroll") for (int k = 0; k < 2; ++k) dst[m][k] = *(const LAS bf16x8*)(lds + G_SA(b, h) + aoff + m * 2048 + k * 1024); } while (0)
; #define G_LDB(dst, b, h) do { _Pragma("unroll") for (int n = 0; n < 2; ++n) _Pragma("unroll") for (int k = 0; k < 2; ++k) dst[n][k] = *(const LAS bf16x8*)(lds + G_SB(b, h) + boff + n * 2048 + k * 1024); } while (0)
; #define G_MMA(ai, bj, At_, Bt_) do { __builtin_amdgcn_s_setprio(1); _Pragma("unroll") for (int m = 0; m < 4; ++m) _Pragma("unroll") for (int n = 0; n < 2; ++n) _Pragma("unroll") for (int k = 0; k < 2; ++k) \
;         acc[ai][bj][m][n] = __builtin_amdgcn_mfma_f32_16x16x32_bf16(Bt_[n][k], At_[m][k], acc[ai][bj][m][n], 0, 0, 0); __builtin_amdgcn_s_setprio(0); } while (0)
; #define WAIT_V(n) asm volatile("s_waitcnt vmcnt(" #n ")" ::: "memory")
; #define WAIT_L(n) asm volatile("s_waitcnt lgkmcnt(" #n ")" ::: "memory")
; #define BAR __builtin_amdgcn_s_barrier()
; #define SCHED __builtin_amdgcn_sched_barrier(0)
; template <class Get, class Epi>
; DI void gemm_loop(int ntiles, int ld, char* shm, const Get& get, const Epi& epi) {
;     ...
;             WAIT_V(8); WAIT_L(0); BAR; G_MMA(0, 0, At, B0); G_MMA(0, 1, At, B1); BAR; SCHED;
;             G_LDA(At, 0, 1); G_STAGE(G_SB(0, 0), b2, voffB); G_STAGE(G_SB(0, 1), b2 + hstep, voffB); G_STAGE(G_SA(0, 0), a2, voffA);
;             WAIT_V(8); WAIT_L(0); BAR; G_MMA(1, 0, At, B0); G_MMA(1, 1, At, B1); BAR; SCHED;
;             G_LDB(B0, 1, 0); G_LDB(B1, 1, 1); SCHED; G_LDA(At, 1, 0); G_STAGE(G_SA(0, 1), a2 + hstep, voffA);
;             WAIT_V(8); WAIT_L(0); BAR; G_MMA(0, 0, At, B0); G_MMA(0, 1, At, B1); BAR; SCHED;
	s_waitcnt lgkmcnt(0)
	v_mfma_f32_16x16x32_bf16 v[124:127], v[128:131], v[180:183], v[124:127]
	v_mfma_f32_16x16x32_bf16 v[120:123], v[136:139], v[180:183], v[120:123]
	v_mfma_f32_16x16x32_bf16 v[116:119], v[128:131], v[188:191], v[116:119]
	v_mfma_f32_16x16x32_bf16 v[112:115], v[136:139], v[188:191], v[112:115]
	v_mfma_f32_16x16x32_bf16 v[108:111], v[128:131], v[196:199], v[108:111]
	v_mfma_f32_16x16x32_bf16 v[104:107], v[136:139], v[196:199], v[104:107]
	v_mfma_f32_16x16x32_bf16 v[100:103], v[128:131], v[204:207], v[100:103]
	v_mfma_f32_16x16x32_bf16 v[96:99], v[136:139], v[204:207], v[96:99]
	v_mfma_f32_16x16x32_bf16 v[124:127], v[132:135], v[184:187], v[124:127]
	v_mfma_f32_16x16x32_bf16 v[120:123], v[140:143], v[184:187], v[120:123]
	v_mfma_f32_16x16x32_bf16 v[116:119], v[132:135], v[192:195], v[116:119]
	v_mfma_f32_16x16x32_bf16 v[112:115], v[140:143], v[192:195], v[112:115]
	v_mfma_f32_16x16x32_bf16 v[108:111], v[132:135], v[200:203], v[108:111]
	v_mfma_f32_16x16x32_bf16 v[104:107], v[140:143], v[200:203], v[104:107]
	v_mfma_f32_16x16x32_bf16 v[100:103], v[132:135], v[208:211], v[100:103]
	v_mfma_f32_16x16x32_bf16 v[96:99], v[140:143], v[208:211], v[96:99]
	v_mfma_f32_16x16x32_bf16 v[60:63], v[158:161], v[180:183], v[60:63]
	v_mfma_f32_16x16x32_bf16 v[56:59], v[172:175], v[180:183], v[56:59]
	v_mfma_f32_16x16x32_bf16 v[52:55], v[158:161], v[188:191], v[52:55]
	v_mfma_f32_16x16x32_bf16 v[48:51], v[172:175], v[188:191], v[48:51]
	v_mfma_f32_16x16x32_bf16 v[44:47], v[158:161], v[196:199], v[44:47]
	v_mfma_f32_16x16x32_bf16 v[40:43], v[172:175], v[196:199], v[40:43]
	v_mfma_f32_16x16x32_bf16 v[36:39], v[158:161], v[204:207], v[36:39]
	v_mfma_f32_16x16x32_bf16 v[32:35], v[172:175], v[204:207], v[32:35]
	v_mfma_f32_16x16x32_bf16 v[60:63], v[162:165], v[184:187], v[60:63]
	v_mfma_f32_16x16x32_bf16 v[56:59], v[176:179], v[184:187], v[56:59]
	v_mfma_f32_16x16x32_bf16 v[52:55], v[162:165], v[192:195], v[52:55]
	v_mfma_f32_16x16x32_bf16 v[48:51], v[176:179], v[192:195], v[48:51]
	v_mfma_f32_16x16x32_bf16 v[44:47], v[162:165], v[200:203], v[44:47]
	v_mfma_f32_16x16x32_bf16 v[40:43], v[176:179], v[200:203], v[40:43]
	v_mfma_f32_16x16x32_bf16 v[36:39], v[162:165], v[208:211], v[36:39]
	v_mfma_f32_16x16x32_bf16 v[32:35], v[176:179], v[208:211], v[32:35]
	s_barrier
	s_add_i32 s72, s56, s48
	v_lshl_add_u64 v[144:145], s[14:15], 0, v[148:149]
	s_mov_b32 m0, s72
	ds_read_b128 v[180:183], v171 offset:16384
	ds_read_b128 v[184:187], v171 offset:17408
	ds_read_b128 v[188:191], v171 offset:18432
	ds_read_b128 v[192:195], v171 offset:19456
	ds_read_b128 v[196:199], v171 offset:20480
	ds_read_b128 v[200:203], v171 offset:21504
	ds_read_b128 v[204:207], v171 offset:22528
	ds_read_b128 v[208:211], v171 offset:23552
	global_load_lds_dwordx4 v[144:145], off
	s_add_i32 m0, s72, 0x2000
	s_add_u32 s72, s14, 0x40000
	v_lshl_add_u64 v[166:167], s[14:15], 0, v[152:153]
	s_addc_u32 s73, s15, 0
	s_add_i32 s74, s57, s48
	global_load_lds_dwordx4 v[166:167], off
	v_lshl_add_u64 v[212:213], s[72:73], 0, v[148:149]
	s_mov_b32 m0, s74
	v_lshl_add_u64 v[214:215], s[46:47], 0, v[150:151]
	global_load_lds_dwordx4 v[212:213], off
	v_lshl_add_u64 v[212:213], s[72:73], 0, v[152:153]
	s_add_i32 m0, s74, 0x2000
	s_nop 0
	global_load_lds_dwordx4 v[212:213], off
	v_lshl_add_u64 v[212:213], s[46:47], 0, v[146:147]
	s_mov_b32 m0, s43
	s_nop 0
	global_load_lds_dwordx4 v[212:213], off
	s_mov_b32 m0, s49
	s_nop 0
	global_load_lds_dwordx4 v[214:215], off
	s_waitcnt vmcnt(8)
	s_waitcnt lgkmcnt(0)
	s_barrier
	s_waitcnt lgkmcnt(0)
	v_mfma_f32_16x16x32_bf16 v[92:95], v[128:131], v[180:183], v[92:95]
	v_mfma_f32_16x16x32_bf16 v[88:91], v[136:139], v[180:183], v[88:91]
	v_mfma_f32_16x16x32_bf16 v[84:87], v[128:131], v[188:191], v[84:87]
	v_mfma_f32_16x16x32_bf16 v[80:83], v[136:139], v[188:191], v[80:83]
	v_mfma_f32_16x16x32_bf16 v[76:79], v[128:131], v[196:199], v[76:79]
	v_mfma_f32_16x16x32_bf16 v[72:75], v[136:139], v[196:199], v[72:75]
	v_mfma_f32_16x16x32_bf16 v[68:71], v[128:131], v[204:207], v[68:71]
	v_mfma_f32_16x16x32_bf16 v[64:67], v[136:139], v[204:207], v[64:67]
	v_mfma_f32_16x16x32_bf16 v[92:95], v[132:135], v[184:187], v[92:95]
	v_mfma_f32_16x16x32_bf16 v[88:91], v[140:143], v[184:187], v[88:91]
	v_mfma_f32_16x16x32_bf16 v[84:87], v[132:135], v[192:195], v[84:87]
	v_mfma_f32_16x16x32_bf16 v[80:83], v[140:143], v[192:195], v[80:83]
	v_mfma_f32_16x16x32_bf16 v[76:79], v[132:135], v[200:203], v[76:79]
	v_mfma_f32_16x16x32_bf16 v[72:75], v[140:143], v[200:203], v[72:75]
	v_mfma_f32_16x16x32_bf16 v[68:71], v[132:135], v[208:211], v[68:71]
	v_mfma_f32_16x16x32_bf16 v[64:67], v[140:143], v[208:211], v[64:67]
	v_mfma_f32_16x16x32_bf16 v[28:31], v[158:161], v[180:183], v[28:31]
	v_mfma_f32_16x16x32_bf16 v[24:27], v[172:175], v[180:183], v[24:27]
	v_mfma_f32_16x16x32_bf16 v[20:23], v[158:161], v[188:191], v[20:23]
	v_mfma_f32_16x16x32_bf16 v[16:19], v[172:175], v[188:191], v[16:19]
	v_mfma_f32_16x16x32_bf16 v[12:15], v[158:161], v[196:199], v[12:15]
	v_mfma_f32_16x16x32_bf16 v[8:11], v[172:175], v[196:199], v[8:11]
	v_mfma_f32_16x16x32_bf16 v[4:7], v[158:161], v[204:207], v[4:7]
	v_mfma_f32_16x16x32_bf16 v[0:3], v[172:175], v[204:207], v[0:3]
	v_mfma_f32_16x16x32_bf16 v[28:31], v[162:165], v[184:187], v[28:31]
	v_mfma_f32_16x16x32_bf16 v[24:27], v[176:179], v[184:187], v[24:27]
	v_mfma_f32_16x16x32_bf16 v[20:23], v[162:165], v[192:195], v[20:23]
	v_mfma_f32_16x16x32_bf16 v[16:19], v[176:179], v[192:195], v[16:19]
	v_mfma_f32_16x16x32_bf16 v[12:15], v[162:165], v[200:203], v[12:15]
	v_mfma_f32_16x16x32_bf16 v[8:11], v[176:179], v[200:203], v[8:11]
	v_mfma_f32_16x16x32_bf16 v[4:7], v[162:165], v[208:211], v[4:7]
	v_mfma_f32_16x16x32_bf16 v[0:3], v[176:179], v[208:211], v[0:3]
	s_barrier
; #define G_STAGE(bufoff, gbase, voff) do { _Pragma("unroll") for (int _i = 0; _i < 2; ++_i) \
;         __builtin_amdgcn_global_load_lds((const unsigned*)((const char*)(gbase) + voff[_i]), (LAS unsigned*)(lds + (bufoff) + ldsw + _i * 8192), 16, 0, 0); } while (0)
; #define G_LDA(dst, b, h) do { _Pragma("unroll") for (int m = 0; m < 4; ++m) _Pragma("unroll") for (int k = 0; k < 2; ++k) dst[m][k] = *(const LAS bf16x8*)(lds + G_SA(b, h) + aoff + m * 2048 + k * 1024); } while (0)
; #define G_LDB(dst, b, h) do { _Pragma("unroll") for (int n = 0; n < 2; ++n) _Pragma("unroll") for (int k = 0; k < 2; ++k) dst[n][k] = *(const LAS bf16x8*)(lds + G_SB(b, h) + boff + n * 2048 + k * 1024); } while (0)
; #define G_MMA(ai, bj, At_, Bt_) do { __builtin_amdgcn_s_setprio(1); _Pragma("unroll") for (int m = 0; m < 4; ++m) _Pragma("unroll") for (int n = 0; n < 2; ++n) _Pragma("unroll") for (int k = 0; k < 2; ++k) \
;         acc[ai][bj][m][n] = __builtin_amdgcn_mfma_f32_16x16x32_bf16(Bt_[n][k], At_[m][k], acc[ai][bj][m][n], 0, 0, 0); __builtin_amdgcn_s_setprio(0); } while (0)
; #define WAIT_V(n) asm volatile("s_waitcnt vmcnt(" #n ")" ::: "memory")
; #define WAIT_L(n) asm volatile("s_waitcnt lgkmcnt(" #n ")" ::: "memory")
; #define BAR __builtin_amdgcn_s_barrier()
; #define SCHED __builtin_amdgcn_sched_barrier(0)
; template <class Get, class Epi>
; DI void gemm_loop(int ntiles, int ld, char* shm, const Get& get, const Epi& epi) {
;     ...
;             G_LDB(B0, 1, 0); G_LDB(B1, 1, 1); SCHED; G_LDA(At, 1, 0); G_STAGE(G_SA(0, 1), a2 + hstep, voffA);
;             WAIT_V(8); WAIT_L(0); BAR; G_MMA(0, 0, At, B0); G_MMA(0, 1, At, B1); BAR; SCHED;
;             G_LDA(At, 1, 1); G_STAGE(G_SB(1, 0), b3, voffB); G_STAGE(G_SB(1, 1), b3 + hstep, voffB); G_STAGE(G_SA(1, 0), a3, voffA);
;             WAIT_V(8); WAIT_L(0); BAR; G_MMA(1, 0, At, B0); G_MMA(1, 1, At, B1); BAR; SCHED;
;         }
	s_add_i32 s72, 0, 0x18000
	s_add_i32 s73, 0, 0x1c000
	v_add_u32_e32 v140, s72, v168
	v_add_u32_e32 v176, s73, v168
	ds_read_b128 v[128:131], v140
	ds_read_b128 v[132:135], v140 offset:1024
	ds_read_b128 v[136:139], v140 offset:2048
	ds_read_b128 v[140:143], v140 offset:3072
	ds_read_b128 v[158:161], v176
	ds_read_b128 v[162:165], v176 offset:1024
	ds_read_b128 v[172:175], v176 offset:2048
	ds_read_b128 v[176:179], v176 offset:3072
	s_add_u32 s46, s46, 0x40000
	s_addc_u32 s47, s47, 0
	s_mov_b32 m0, s50
	v_lshl_add_u64 v[216:217], s[46:47], 0, v[146:147]
	ds_read_b128 v[180:183], v171 offset:32768
	ds_read_b128 v[184:187], v171 offset:33792
	ds_read_b128 v[188:191], v171 offset:34816
	ds_read_b128 v[192:195], v171 offset:35840
	ds_read_b128 v[196:199], v171 offset:36864
	ds_read_b128 v[200:203], v171 offset:37888
	ds_read_b128 v[204:207], v171 offset:38912
	ds_read_b128 v[208:211], v171 offset:39936
	global_load_lds_dwordx4 v[216:217], off
	v_lshl_add_u64 v[216:217], s[46:47], 0, v[150:151]
	s_mov_b32 m0, s51
	s_nop 0
	global_load_lds_dwordx4 v[216:217], off
	s_waitcnt vmcnt(8)
	s_waitcnt lgkmcnt(0)
	s_barrier
	s_waitcnt lgkmcnt(0)
	v_mfma_f32_16x16x32_bf16 v[124:127], v[128:131], v[180:183], v[124:127]
	v_mfma_f32_16x16x32_bf16 v[120:123], v[136:139], v[180:183], v[120:123]
	v_mfma_f32_16x16x32_bf16 v[116:119], v[128:131], v[188:191], v[116:119]
	v_mfma_f32_16x16x32_bf16 v[112:115], v[136:139], v[188:191], v[112:115]
	v_mfma_f32_16x16x32_bf16 v[108:111], v[128:131], v[196:199], v[108:111]
	v_mfma_f32_16x16x32_bf16 v[104:107], v[136:139], v[196:199], v[104:107]
	v_mfma_f32_16x16x32_bf16 v[100:103], v[128:131], v[204:207], v[100:103]
	v_mfma_f32_16x16x32_bf16 v[96:99], v[136:139], v[204:207], v[96:99]
	v_mfma_f32_16x16x32_bf16 v[124:127], v[132:135], v[184:187], v[124:127]
	v_mfma_f32_16x16x32_bf16 v[120:123], v[140:143], v[184:187], v[120:123]
	v_mfma_f32_16x16x32_bf16 v[116:119], v[132:135], v[192:195], v[116:119]
	v_mfma_f32_16x16x32_bf16 v[112:115], v[140:143], v[192:195], v[112:115]
	v_mfma_f32_16x16x32_bf16 v[108:111], v[132:135], v[200:203], v[108:111]
	v_mfma_f32_16x16x32_bf16 v[104:107], v[140:143], v[200:203], v[104:107]
	v_mfma_f32_16x16x32_bf16 v[100:103], v[132:135], v[208:211], v[100:103]
	v_mfma_f32_16x16x32_bf16 v[96:99], v[140:143], v[208:211], v[96:99]
	v_mfma_f32_16x16x32_bf16 v[60:63], v[158:161], v[180:183], v[60:63]
	v_mfma_f32_16x16x32_bf16 v[56:59], v[172:175], v[180:183], v[56:59]
	v_mfma_f32_16x16x32_bf16 v[52:55], v[158:161], v[188:191], v[52:55]
	v_mfma_f32_16x16x32_bf16 v[48:51], v[172:175], v[188:191], v[48:51]
	v_mfma_f32_16x16x32_bf16 v[44:47], v[158:161], v[196:199], v[44:47]
	v_mfma_f32_16x16x32_bf16 v[40:43], v[172:175], v[196:199], v[40:43]
	v_mfma_f32_16x16x32_bf16 v[36:39], v[158:161], v[204:207], v[36:39]
	v_mfma_f32_16x16x32_bf16 v[32:35], v[172:175], v[204:207], v[32:35]
	v_mfma_f32_16x16x32_bf16 v[60:63], v[162:165], v[184:187], v[60:63]
	v_mfma_f32_16x16x32_bf16 v[56:59], v[176:179], v[184:187], v[56:59]
	v_mfma_f32_16x16x32_bf16 v[52:55], v[162:165], v[192:195], v[52:55]
	v_mfma_f32_16x16x32_bf16 v[48:51], v[176:179], v[192:195], v[48:51]
	v_mfma_f32_16x16x32_bf16 v[44:47], v[162:165], v[200:203], v[44:47]
	v_mfma_f32_16x16x32_bf16 v[40:43], v[176:179], v[200:203], v[40:43]
	v_mfma_f32_16x16x32_bf16 v[36:39], v[162:165], v[208:211], v[36:39]
	v_mfma_f32_16x16x32_bf16 v[32:35], v[176:179], v[208:211], v[32:35]
	s_barrier
	s_add_i32 s46, s72, s48
	v_lshl_add_u64 v[144:145], v[144:145], 0, s[4:5]
	s_mov_b32 m0, s46
	ds_read_b128 v[180:183], v171 offset:49152
	ds_read_b128 v[184:187], v171 offset:50176
	ds_read_b128 v[188:191], v171 offset:51200
	ds_read_b128 v[192:195], v171 offset:52224
	ds_read_b128 v[196:199], v171 offset:53248
	ds_read_b128 v[200:203], v171 offset:54272
	ds_read_b128 v[204:207], v171 offset:55296
	ds_read_b128 v[208:211], v171 offset:56320
	global_load_lds_dwordx4 v[144:145], off
	s_add_i32 m0, s46, 0x2000
	s_add_u32 s14, s14, 0x40080
	v_lshl_add_u64 v[144:145], v[166:167], 0, s[4:5]
	s_addc_u32 s15, s15, 0
	s_add_i32 s46, s73, s48
	global_load_lds_dwordx4 v[144:145], off
	v_lshl_add_u64 v[144:145], s[14:15], 0, v[148:149]
	s_mov_b32 m0, s46
	s_nop 0
	global_load_lds_dwordx4 v[144:145], off
	v_lshl_add_u64 v[144:145], s[14:15], 0, v[152:153]
	s_add_i32 m0, s46, 0x2000
	s_nop 0
	global_load_lds_dwordx4 v[144:145], off
	v_lshl_add_u64 v[144:145], v[212:213], 0, s[4:5]
	s_mov_b32 m0, s54
	s_nop 0
	global_load_lds_dwordx4 v[144:145], off
	v_lshl_add_u64 v[144:145], v[214:215], 0, s[4:5]
	s_mov_b32 m0, s55
	s_nop 0
	global_load_lds_dwordx4 v[144:145], off
	s_waitcnt vmcnt(8)
	s_waitcnt lgkmcnt(0)
	s_barrier
	s_waitcnt lgkmcnt(0)
	v_mfma_f32_16x16x32_bf16 v[92:95], v[128:131], v[180:183], v[92:95]
	v_mfma_f32_16x16x32_bf16 v[88:91], v[136:139], v[180:183], v[88:91]
	v_mfma_f32_16x16x32_bf16 v[84:87], v[128:131], v[188:191], v[84:87]
	v_mfma_f32_16x16x32_bf16 v[80:83], v[136:139], v[188:191], v[80:83]
	v_mfma_f32_16x16x32_bf16 v[76:79], v[128:131], v[196:199], v[76:79]
	v_mfma_f32_16x16x32_bf16 v[72:75], v[136:139], v[196:199], v[72:75]
	v_mfma_f32_16x16x32_bf16 v[68:71], v[128:131], v[204:207], v[68:71]
	v_mfma_f32_16x16x32_bf16 v[64:67], v[136:139], v[204:207], v[64:67]
	v_mfma_f32_16x16x32_bf16 v[92:95], v[132:135], v[184:187], v[92:95]
	v_mfma_f32_16x16x32_bf16 v[88:91], v[140:143], v[184:187], v[88:91]
	v_mfma_f32_16x16x32_bf16 v[84:87], v[132:135], v[192:195], v[84:87]
	v_mfma_f32_16x16x32_bf16 v[80:83], v[140:143], v[192:195], v[80:83]
	v_mfma_f32_16x16x32_bf16 v[76:79], v[132:135], v[200:203], v[76:79]
	v_mfma_f32_16x16x32_bf16 v[72:75], v[140:143], v[200:203], v[72:75]
	v_mfma_f32_16x16x32_bf16 v[68:71], v[132:135], v[208:211], v[68:71]
	v_mfma_f32_16x16x32_bf16 v[64:67], v[140:143], v[208:211], v[64:67]
	v_mfma_f32_16x16x32_bf16 v[28:31], v[158:161], v[180:183], v[28:31]
	v_mfma_f32_16x16x32_bf16 v[24:27], v[172:175], v[180:183], v[24:27]
	v_mfma_f32_16x16x32_bf16 v[20:23], v[158:161], v[188:191], v[20:23]
	v_mfma_f32_16x16x32_bf16 v[16:19], v[172:175], v[188:191], v[16:19]
	v_mfma_f32_16x16x32_bf16 v[12:15], v[158:161], v[196:199], v[12:15]
	v_mfma_f32_16x16x32_bf16 v[8:11], v[172:175], v[196:199], v[8:11]
	v_mfma_f32_16x16x32_bf16 v[4:7], v[158:161], v[204:207], v[4:7]
	v_mfma_f32_16x16x32_bf16 v[0:3], v[172:175], v[204:207], v[0:3]
	v_mfma_f32_16x16x32_bf16 v[28:31], v[162:165], v[184:187], v[28:31]
	v_mfma_f32_16x16x32_bf16 v[24:27], v[176:179], v[184:187], v[24:27]
	v_mfma_f32_16x16x32_bf16 v[20:23], v[162:165], v[192:195], v[20:23]
	v_mfma_f32_16x16x32_bf16 v[16:19], v[176:179], v[192:195], v[16:19]
	v_mfma_f32_16x16x32_bf16 v[12:15], v[162:165], v[200:203], v[12:15]
	v_mfma_f32_16x16x32_bf16 v[8:11], v[176:179], v[200:203], v[8:11]
	v_mfma_f32_16x16x32_bf16 v[4:7], v[162:165], v[208:211], v[4:7]
	v_mfma_f32_16x16x32_bf16 v[0:3], v[176:179], v[208:211], v[0:3]
	s_barrier
	s_add_i32 s71, s71, 2
	s_add_u32 s44, s44, 0x100
	s_addc_u32 s45, s45, 0
	s_add_u32 s65, s65, 0x100
	s_addc_u32 s70, s70, 0
	s_cmp_gt_u32 s71, 13
	s_cbranch_scc0 .LBB0_3466

; #define G_STAGE(bufoff, gbase, voff) do { _Pragma("unroll") for (int _i = 0; _i < 2; ++_i) \
;         __builtin_amdgcn_global_load_lds((const unsigned*)((const char*)(gbase) + voff[_i]), (LAS unsigned*)(lds + (bufoff) + ldsw + _i * 8192), 16, 0, 0); } while (0)
; #define G_LDA(dst, b, h) do { _Pragma("unroll") for (int m = 0; m < 4; ++m) _Pragma("unroll") for (int k = 0; k < 2; ++k) dst[m][k] = *(const LAS bf16x8*)(lds + G_SA(b, h) + aoff + m * 2048 + k * 1024); } while (0)
; #define G_LDB(dst, b, h) do { _Pragma("unroll") for (int n = 0; n < 2; ++n) _Pragma("unroll") for (int k = 0; k < 2; ++k) dst[n][k] = *(const LAS bf16x8*)(lds + G_SB(b, h) + boff + n * 2048 + k * 1024); } while (0)
; #define G_MMA(ai, bj, At_, Bt_) do { __builtin_amdgcn_s_setprio(1); _Pragma("unroll") for (int m = 0; m < 4; ++m) _Pragma("unroll") for (int n = 0; n < 2; ++n) _Pragma("unroll") for (int k = 0; k < 2; ++k) \
;         acc[ai][bj][m][n] = __builtin_amdgcn_mfma_f32_16x16x32_bf16(Bt_[n][k], At_[m][k], acc[ai][bj][m][n], 0, 0, 0); __builtin_amdgcn_s_setprio(0); } while (0)
; #define WAIT_V(n) asm volatile("s_waitcnt vmcnt(" #n ")" ::: "memory")
; #define WAIT_L(n) asm volatile("s_waitcnt lgkmcnt(" #n ")" ::: "memory")
; #define BAR __builtin_amdgcn_s_barrier()
; #define SCHED __builtin_amdgcn_sched_barrier(0)
; template <class Get, class Epi>
; DI void gemm_loop(int ntiles, int ld, char* shm, const Get& get, const Epi& epi) {
;     ...
;             G_LDB(B0, 0, 0); G_LDB(B1, 0, 1); SCHED; G_LDA(At, 0, 0); G_STAGE(G_SA(1, 1), a1 + hstep, voffA);
;             WAIT_V(8); WAIT_L(0); BAR; G_MMA(0, 0, At, B0); G_MMA(0, 1, At, B1); BAR; SCHED;
;             G_LDA(At, 0, 1); G_STAGE(G_SB(0, 0), b2, voffB); G_STAGE(G_SB(0, 1), b2 + hstep, voffB); G_STAGE(G_SA(0, 0), a2, voffA);
;             WAIT_V(8); WAIT_L(0); BAR; G_MMA(1, 0, At, B0); G_MMA(1, 1, At, B1); BAR; SCHED;
.Lrj_3679_0:
	s_waitcnt lgkmcnt(0)
	s_barrier
	s_waitcnt lgkmcnt(0)
	v_mfma_f32_16x16x32_bf16 v[124:127], v[144:147], v[176:179], 0
	v_mfma_f32_16x16x32_bf16 v[120:123], v[152:155], v[176:179], 0
	v_mfma_f32_16x16x32_bf16 v[108:111], v[144:147], v[184:187], 0
	v_mfma_f32_16x16x32_bf16 v[104:107], v[152:155], v[184:187], 0
	v_mfma_f32_16x16x32_bf16 v[92:95], v[144:147], v[192:195], 0
	v_mfma_f32_16x16x32_bf16 v[88:91], v[152:155], v[192:195], 0
	v_mfma_f32_16x16x32_bf16 v[76:79], v[144:147], v[200:203], 0
	v_mfma_f32_16x16x32_bf16 v[72:75], v[152:155], v[200:203], 0
	v_mfma_f32_16x16x32_bf16 v[124:127], v[148:151], v[180:183], v[124:127]
	v_mfma_f32_16x16x32_bf16 v[120:123], v[156:159], v[180:183], v[120:123]
	v_mfma_f32_16x16x32_bf16 v[108:111], v[148:151], v[188:191], v[108:111]
	v_mfma_f32_16x16x32_bf16 v[104:107], v[156:159], v[188:191], v[104:107]
	v_mfma_f32_16x16x32_bf16 v[92:95], v[148:151], v[196:199], v[92:95]
	v_mfma_f32_16x16x32_bf16 v[88:91], v[156:159], v[196:199], v[88:91]
	v_mfma_f32_16x16x32_bf16 v[76:79], v[148:151], v[204:207], v[76:79]
	v_mfma_f32_16x16x32_bf16 v[72:75], v[156:159], v[204:207], v[72:75]
	v_mfma_f32_16x16x32_bf16 v[116:119], v[160:163], v[176:179], 0
	v_mfma_f32_16x16x32_bf16 v[112:115], v[168:171], v[176:179], 0
	v_mfma_f32_16x16x32_bf16 v[100:103], v[160:163], v[184:187], 0
	v_mfma_f32_16x16x32_bf16 v[96:99], v[168:171], v[184:187], 0
	v_mfma_f32_16x16x32_bf16 v[84:87], v[160:163], v[192:195], 0
	v_mfma_f32_16x16x32_bf16 v[80:83], v[168:171], v[192:195], 0
	v_mfma_f32_16x16x32_bf16 v[68:71], v[160:163], v[200:203], 0
	v_mfma_f32_16x16x32_bf16 v[64:67], v[168:171], v[200:203], 0
	v_mfma_f32_16x16x32_bf16 v[116:119], v[164:167], v[180:183], v[116:119]
	v_mfma_f32_16x16x32_bf16 v[112:115], v[172:175], v[180:183], v[112:115]
	v_mfma_f32_16x16x32_bf16 v[100:103], v[164:167], v[188:191], v[100:103]
	v_mfma_f32_16x16x32_bf16 v[96:99], v[172:175], v[188:191], v[96:99]
	v_mfma_f32_16x16x32_bf16 v[84:87], v[164:167], v[196:199], v[84:87]
	v_mfma_f32_16x16x32_bf16 v[80:83], v[172:175], v[196:199], v[80:83]
	v_mfma_f32_16x16x32_bf16 v[68:71], v[164:167], v[204:207], v[68:71]
	v_mfma_f32_16x16x32_bf16 v[64:67], v[172:175], v[204:207], v[64:67]
	s_barrier
	s_add_i32 s54, s44, s38
	v_lshl_add_u64 v[208:209], s[14:15], 0, v[132:133]
	s_mov_b32 m0, s54
	ds_read_b128 v[176:179], v143 offset:16384
	ds_read_b128 v[180:183], v143 offset:17408
	ds_read_b128 v[184:187], v143 offset:18432
	ds_read_b128 v[188:191], v143 offset:19456
	ds_read_b128 v[192:195], v143 offset:20480
	ds_read_b128 v[196:199], v143 offset:21504
	ds_read_b128 v[200:203], v143 offset:22528
	ds_read_b128 v[204:207], v143 offset:23552
	global_load_lds_dwordx4 v[208:209], off
	s_add_i32 m0, s54, 0x2000
	s_add_u32 s54, s14, 0x40000
	v_lshl_add_u64 v[210:211], s[14:15], 0, v[128:129]
	s_addc_u32 s55, s15, 0
	s_add_i32 s56, s45, s38
	global_load_lds_dwordx4 v[210:211], off
	v_lshl_add_u64 v[212:213], s[54:55], 0, v[132:133]
	s_mov_b32 m0, s56
	v_lshl_add_u64 v[214:215], s[36:37], 0, v[130:131]
	global_load_lds_dwordx4 v[212:213], off
	v_lshl_add_u64 v[212:213], s[54:55], 0, v[128:129]
	s_add_i32 m0, s56, 0x2000
	s_nop 0
	global_load_lds_dwordx4 v[212:213], off
	v_lshl_add_u64 v[212:213], s[36:37], 0, v[134:135]
	s_mov_b32 m0, s25
	s_nop 0
	global_load_lds_dwordx4 v[212:213], off
	s_mov_b32 m0, s31
	s_nop 0
	global_load_lds_dwordx4 v[214:215], off
	s_cmp_lg_u32 s100, 0
	s_cbranch_scc0 .Lrf_3679_1
	s_waitcnt vmcnt(16)
	s_branch .Lrj_3679_1

; #define G_STAGE(bufoff, gbase, voff) do { _Pragma("unroll") for (int _i = 0; _i < 2; ++_i) \
;         __builtin_amdgcn_global_load_lds((const unsigned*)((const char*)(gbase) + voff[_i]), (LAS unsigned*)(lds + (bufoff) + ldsw + _i * 8192), 16, 0, 0); } while (0)
; #define G_LDA(dst, b, h) do { _Pragma("unroll") for (int m = 0; m < 4; ++m) _Pragma("unroll") for (int k = 0; k < 2; ++k) dst[m][k] = *(const LAS bf16x8*)(lds + G_SA(b, h) + aoff + m * 2048 + k * 1024); } while (0)
; #define G_LDB(dst, b, h) do { _Pragma("unroll") for (int n = 0; n < 2; ++n) _Pragma("unroll") for (int k = 0; k < 2; ++k) dst[n][k] = *(const LAS bf16x8*)(lds + G_SB(b, h) + boff + n * 2048 + k * 1024); } while (0)
; #define G_MMA(ai, bj, At_, Bt_) do { __builtin_amdgcn_s_setprio(1); _Pragma("unroll") for (int m = 0; m < 4; ++m) _Pragma("unroll") for (int n = 0; n < 2; ++n) _Pragma("unroll") for (int k = 0; k < 2; ++k) \
;         acc[ai][bj][m][n] = __builtin_amdgcn_mfma_f32_16x16x32_bf16(Bt_[n][k], At_[m][k], acc[ai][bj][m][n], 0, 0, 0); __builtin_amdgcn_s_setprio(0); } while (0)
; #define WAIT_V(n) asm volatile("s_waitcnt vmcnt(" #n ")" ::: "memory")
; #define WAIT_L(n) asm volatile("s_waitcnt lgkmcnt(" #n ")" ::: "memory")
; #define BAR __builtin_amdgcn_s_barrier()
; #define SCHED __builtin_amdgcn_sched_barrier(0)
; template <class Get, class Epi>
; DI void gemm_loop(int ntiles, int ld, char* shm, const Get& get, const Epi& epi) {
;     ...
;             WAIT_V(8); WAIT_L(0); BAR; G_MMA(1, 0, At, B0); G_MMA(1, 1, At, B1); BAR; SCHED;
;             G_LDB(B0, 1, 0); G_LDB(B1, 1, 1); SCHED; G_LDA(At, 1, 0); G_STAGE(G_SA(0, 1), a2 + hstep, voffA);
;             WAIT_V(8); WAIT_L(0); BAR; G_MMA(0, 0, At, B0); G_MMA(0, 1, At, B1); BAR; SCHED;
;             G_LDA(At, 1, 1); G_STAGE(G_SB(1, 0), b3, voffB); G_STAGE(G_SB(1, 1), b3 + hstep, voffB); G_STAGE(G_SA(1, 0), a3, voffA);
.Lrj_3679_1:
	s_waitcnt lgkmcnt(0)
	s_barrier
	s_waitcnt lgkmcnt(0)
	v_mfma_f32_16x16x32_bf16 v[60:63], v[144:147], v[176:179], 0
	v_mfma_f32_16x16x32_bf16 v[56:59], v[152:155], v[176:179], 0
	v_mfma_f32_16x16x32_bf16 v[44:47], v[144:147], v[184:187], 0
	v_mfma_f32_16x16x32_bf16 v[40:43], v[152:155], v[184:187], 0
	v_mfma_f32_16x16x32_bf16 v[28:31], v[144:147], v[192:195], 0
	v_mfma_f32_16x16x32_bf16 v[24:27], v[152:155], v[192:195], 0
	v_mfma_f32_16x16x32_bf16 v[12:15], v[144:147], v[200:203], 0
	v_mfma_f32_16x16x32_bf16 v[8:11], v[152:155], v[200:203], 0
	v_mfma_f32_16x16x32_bf16 v[60:63], v[148:151], v[180:183], v[60:63]
	v_mfma_f32_16x16x32_bf16 v[56:59], v[156:159], v[180:183], v[56:59]
	v_mfma_f32_16x16x32_bf16 v[44:47], v[148:151], v[188:191], v[44:47]
	v_mfma_f32_16x16x32_bf16 v[40:43], v[156:159], v[188:191], v[40:43]
	v_mfma_f32_16x16x32_bf16 v[28:31], v[148:151], v[196:199], v[28:31]
	v_mfma_f32_16x16x32_bf16 v[24:27], v[156:159], v[196:199], v[24:27]
	v_mfma_f32_16x16x32_bf16 v[12:15], v[148:151], v[204:207], v[12:15]
	v_mfma_f32_16x16x32_bf16 v[8:11], v[156:159], v[204:207], v[8:11]
	v_mfma_f32_16x16x32_bf16 v[52:55], v[160:163], v[176:179], 0
	v_mfma_f32_16x16x32_bf16 v[48:51], v[168:171], v[176:179], 0
	v_mfma_f32_16x16x32_bf16 v[36:39], v[160:163], v[184:187], 0
	v_mfma_f32_16x16x32_bf16 v[32:35], v[168:171], v[184:187], 0
	v_mfma_f32_16x16x32_bf16 v[20:23], v[160:163], v[192:195], 0
	v_mfma_f32_16x16x32_bf16 v[16:19], v[168:171], v[192:195], 0
	v_mfma_f32_16x16x32_bf16 v[4:7], v[160:163], v[200:203], 0
	v_mfma_f32_16x16x32_bf16 v[0:3], v[168:171], v[200:203], 0
	v_mfma_f32_16x16x32_bf16 v[52:55], v[164:167], v[180:183], v[52:55]
	v_mfma_f32_16x16x32_bf16 v[48:51], v[172:175], v[180:183], v[48:51]
	v_mfma_f32_16x16x32_bf16 v[36:39], v[164:167], v[188:191], v[36:39]
	v_mfma_f32_16x16x32_bf16 v[32:35], v[172:175], v[188:191], v[32:35]
	v_mfma_f32_16x16x32_bf16 v[20:23], v[164:167], v[196:199], v[20:23]
	v_mfma_f32_16x16x32_bf16 v[16:19], v[172:175], v[196:199], v[16:19]
	v_mfma_f32_16x16x32_bf16 v[4:7], v[164:167], v[204:207], v[4:7]
	v_mfma_f32_16x16x32_bf16 v[0:3], v[172:175], v[204:207], v[0:3]
	s_barrier
	s_add_i32 s54, 0, 0x18000
	s_add_i32 s55, 0, 0x1c000
	v_add_u32_e32 v156, s54, v140
	v_add_u32_e32 v172, s55, v140
	ds_read_b128 v[144:147], v156
	ds_read_b128 v[148:151], v156 offset:1024
	ds_read_b128 v[152:155], v156 offset:2048
	ds_read_b128 v[156:159], v156 offset:3072
	ds_read_b128 v[160:163], v172
	ds_read_b128 v[164:167], v172 offset:1024
	ds_read_b128 v[168:171], v172 offset:2048
	ds_read_b128 v[172:175], v172 offset:3072
	s_add_u32 s36, s36, 0x40000
	s_addc_u32 s37, s37, 0
	s_mov_b32 m0, s40
	v_lshl_add_u64 v[216:217], s[36:37], 0, v[134:135]
	ds_read_b128 v[176:179], v143 offset:32768
	ds_read_b128 v[180:183], v143 offset:33792
	ds_read_b128 v[184:187], v143 offset:34816
	ds_read_b128 v[188:191], v143 offset:35840
	ds_read_b128 v[192:195], v143 offset:36864
	ds_read_b128 v[196:199], v143 offset:37888
	ds_read_b128 v[200:203], v143 offset:38912
	ds_read_b128 v[204:207], v143 offset:39936
	global_load_lds_dwordx4 v[216:217], off
	v_lshl_add_u64 v[216:217], s[36:37], 0, v[130:131]
	s_mov_b32 m0, s41
	s_nop 0
	global_load_lds_dwordx4 v[216:217], off
	s_waitcnt vmcnt(8)
	s_waitcnt lgkmcnt(0)
	s_barrier
	s_waitcnt lgkmcnt(0)
	v_mfma_f32_16x16x32_bf16 v[124:127], v[144:147], v[176:179], v[124:127]
	v_mfma_f32_16x16x32_bf16 v[120:123], v[152:155], v[176:179], v[120:123]
	v_mfma_f32_16x16x32_bf16 v[108:111], v[144:147], v[184:187], v[108:111]
	v_mfma_f32_16x16x32_bf16 v[104:107], v[152:155], v[184:187], v[104:107]
	v_mfma_f32_16x16x32_bf16 v[92:95], v[144:147], v[192:195], v[92:95]
	v_mfma_f32_16x16x32_bf16 v[88:91], v[152:155], v[192:195], v[88:91]
	v_mfma_f32_16x16x32_bf16 v[76:79], v[144:147], v[200:203], v[76:79]
	v_mfma_f32_16x16x32_bf16 v[72:75], v[152:155], v[200:203], v[72:75]
	v_mfma_f32_16x16x32_bf16 v[124:127], v[148:151], v[180:183], v[124:127]
	v_mfma_f32_16x16x32_bf16 v[120:123], v[156:159], v[180:183], v[120:123]
	v_mfma_f32_16x16x32_bf16 v[108:111], v[148:151], v[188:191], v[108:111]
	v_mfma_f32_16x16x32_bf16 v[104:107], v[156:159], v[188:191], v[104:107]
	v_mfma_f32_16x16x32_bf16 v[92:95], v[148:151], v[196:199], v[92:95]
	v_mfma_f32_16x16x32_bf16 v[88:91], v[156:159], v[196:199], v[88:91]
	v_mfma_f32_16x16x32_bf16 v[76:79], v[148:151], v[204:207], v[76:79]
	v_mfma_f32_16x16x32_bf16 v[72:75], v[156:159], v[204:207], v[72:75]
	v_mfma_f32_16x16x32_bf16 v[116:119], v[160:163], v[176:179], v[116:119]
	v_mfma_f32_16x16x32_bf16 v[112:115], v[168:171], v[176:179], v[112:115]
	v_mfma_f32_16x16x32_bf16 v[100:103], v[160:163], v[184:187], v[100:103]
	v_mfma_f32_16x16x32_bf16 v[96:99], v[168:171], v[184:187], v[96:99]
	v_mfma_f32_16x16x32_bf16 v[84:87], v[160:163], v[192:195], v[84:87]
	v_mfma_f32_16x16x32_bf16 v[80:83], v[168:171], v[192:195], v[80:83]
	v_mfma_f32_16x16x32_bf16 v[68:71], v[160:163], v[200:203], v[68:71]
	v_mfma_f32_16x16x32_bf16 v[64:67], v[168:171], v[200:203], v[64:67]
	v_mfma_f32_16x16x32_bf16 v[116:119], v[164:167], v[180:183], v[116:119]
	v_mfma_f32_16x16x32_bf16 v[112:115], v[172:175], v[180:183], v[112:115]
	v_mfma_f32_16x16x32_bf16 v[100:103], v[164:167], v[188:191], v[100:103]
	v_mfma_f32_16x16x32_bf16 v[96:99], v[172:175], v[188:191], v[96:99]
	v_mfma_f32_16x16x32_bf16 v[84:87], v[164:167], v[196:199], v[84:87]
	v_mfma_f32_16x16x32_bf16 v[80:83], v[172:175], v[196:199], v[80:83]
	v_mfma_f32_16x16x32_bf16 v[68:71], v[164:167], v[204:207], v[68:71]
	v_mfma_f32_16x16x32_bf16 v[64:67], v[172:175], v[204:207], v[64:67]
	s_barrier
; #define G_STAGE(bufoff, gbase, voff) do { _Pragma("unroll") for (int _i = 0; _i < 2; ++_i) \
;         __builtin_amdgcn_global_load_lds((const unsigned*)((const char*)(gbase) + voff[_i]), (LAS unsigned*)(lds + (bufoff) + ldsw + _i * 8192), 16, 0, 0); } while (0)
; #define G_LDA(dst, b, h) do { _Pragma("unroll") for (int m = 0; m < 4; ++m) _Pragma("unroll") for (int k = 0; k < 2; ++k) dst[m][k] = *(const LAS bf16x8*)(lds + G_SA(b, h) + aoff + m * 2048 + k * 1024); } while (0)
; #define G_LDB(dst, b, h) do { _Pragma("unroll") for (int n = 0; n < 2; ++n) _Pragma("unroll") for (int k = 0; k < 2; ++k) dst[n][k] = *(const LAS bf16x8*)(lds + G_SB(b, h) + boff + n * 2048 + k * 1024); } while (0)
; #define G_MMA(ai, bj, At_, Bt_) do { __builtin_amdgcn_s_setprio(1); _Pragma("unroll") for (int m = 0; m < 4; ++m) _Pragma("unroll") for (int n = 0; n < 2; ++n) _Pragma("unroll") for (int k = 0; k < 2; ++k) \
;         acc[ai][bj][m][n] = __builtin_amdgcn_mfma_f32_16x16x32_bf16(Bt_[n][k], At_[m][k], acc[ai][bj][m][n], 0, 0, 0); __builtin_amdgcn_s_setprio(0); } while (0)
; #define WAIT_V(n) asm volatile("s_waitcnt vmcnt(" #n ")" ::: "memory")
; #define WAIT_L(n) asm volatile("s_waitcnt lgkmcnt(" #n ")" ::: "memory")
; #define BAR __builtin_amdgcn_s_barrier()
; #define SCHED __builtin_amdgcn_sched_barrier(0)
; template <class Get, class Epi>
; DI void gemm_loop(int ntiles, int ld, char* shm, const Get& get, const Epi& epi) {
;     ...
;             G_LDB(B0, 0, 0); G_LDB(B1, 0, 1); SCHED; G_LDA(At, 0, 0); G_STAGE(G_SA(1, 1), a1 + hstep, voffA);
;             WAIT_V(8); WAIT_L(0); BAR; G_MMA(0, 0, At, B0); G_MMA(0, 1, At, B1); BAR; SCHED;
;     ...
;             G_LDA(At, 1, 1); G_STAGE(G_SB(1, 0), b3, voffB); G_STAGE(G_SB(1, 1), b3 + hstep, voffB); G_STAGE(G_SA(1, 0), a3, voffA);
;             WAIT_V(8); WAIT_L(0); BAR; G_MMA(1, 0, At, B0); G_MMA(1, 1, At, B1); BAR; SCHED;
;         }
	s_add_i32 s36, s54, s38
	v_lshl_add_u64 v[208:209], v[208:209], 0, s[2:3]
	s_mov_b32 m0, s36
	ds_read_b128 v[176:179], v143 offset:49152
	ds_read_b128 v[180:183], v143 offset:50176
	ds_read_b128 v[184:187], v143 offset:51200
	ds_read_b128 v[188:191], v143 offset:52224
	ds_read_b128 v[192:195], v143 offset:53248
	ds_read_b128 v[196:199], v143 offset:54272
	ds_read_b128 v[200:203], v143 offset:55296
	ds_read_b128 v[204:207], v143 offset:56320
	global_load_lds_dwordx4 v[208:209], off
	s_add_i32 m0, s36, 0x2000
	s_add_u32 s14, s14, 0x40080
	v_lshl_add_u64 v[208:209], v[210:211], 0, s[2:3]
	s_addc_u32 s15, s15, 0
	s_add_i32 s36, s55, s38
	global_load_lds_dwordx4 v[208:209], off
	v_lshl_add_u64 v[208:209], s[14:15], 0, v[132:133]
	s_mov_b32 m0, s36
	s_nop 0
	global_load_lds_dwordx4 v[208:209], off
	v_lshl_add_u64 v[208:209], s[14:15], 0, v[128:129]
	s_add_i32 m0, s36, 0x2000
	s_nop 0
	global_load_lds_dwordx4 v[208:209], off
	v_lshl_add_u64 v[208:209], v[212:213], 0, s[2:3]
	s_mov_b32 m0, s42
	s_nop 0
	global_load_lds_dwordx4 v[208:209], off
	v_lshl_add_u64 v[208:209], v[214:215], 0, s[2:3]
	s_mov_b32 m0, s43
	s_nop 0
	global_load_lds_dwordx4 v[208:209], off
	s_waitcnt vmcnt(8)
	s_waitcnt lgkmcnt(0)
	s_barrier
	s_waitcnt lgkmcnt(0)
	v_mfma_f32_16x16x32_bf16 v[60:63], v[144:147], v[176:179], v[60:63]
	v_mfma_f32_16x16x32_bf16 v[56:59], v[152:155], v[176:179], v[56:59]
	v_mfma_f32_16x16x32_bf16 v[44:47], v[144:147], v[184:187], v[44:47]
	v_mfma_f32_16x16x32_bf16 v[40:43], v[152:155], v[184:187], v[40:43]
	v_mfma_f32_16x16x32_bf16 v[28:31], v[144:147], v[192:195], v[28:31]
	v_mfma_f32_16x16x32_bf16 v[24:27], v[152:155], v[192:195], v[24:27]
	v_mfma_f32_16x16x32_bf16 v[12:15], v[144:147], v[200:203], v[12:15]
	v_mfma_f32_16x16x32_bf16 v[8:11], v[152:155], v[200:203], v[8:11]
	v_mfma_f32_16x16x32_bf16 v[60:63], v[148:151], v[180:183], v[60:63]
	v_mfma_f32_16x16x32_bf16 v[56:59], v[156:159], v[180:183], v[56:59]
	v_mfma_f32_16x16x32_bf16 v[44:47], v[148:151], v[188:191], v[44:47]
	v_mfma_f32_16x16x32_bf16 v[40:43], v[156:159], v[188:191], v[40:43]
	v_mfma_f32_16x16x32_bf16 v[28:31], v[148:151], v[196:199], v[28:31]
	v_mfma_f32_16x16x32_bf16 v[24:27], v[156:159], v[196:199], v[24:27]
	v_mfma_f32_16x16x32_bf16 v[12:15], v[148:151], v[204:207], v[12:15]
	v_mfma_f32_16x16x32_bf16 v[8:11], v[156:159], v[204:207], v[8:11]
	v_mfma_f32_16x16x32_bf16 v[52:55], v[160:163], v[176:179], v[52:55]
	v_mfma_f32_16x16x32_bf16 v[48:51], v[168:171], v[176:179], v[48:51]
	v_mfma_f32_16x16x32_bf16 v[36:39], v[160:163], v[184:187], v[36:39]
	v_mfma_f32_16x16x32_bf16 v[32:35], v[168:171], v[184:187], v[32:35]
	v_mfma_f32_16x16x32_bf16 v[20:23], v[160:163], v[192:195], v[20:23]
	v_mfma_f32_16x16x32_bf16 v[16:19], v[168:171], v[192:195], v[16:19]
	v_mfma_f32_16x16x32_bf16 v[4:7], v[160:163], v[200:203], v[4:7]
	v_mfma_f32_16x16x32_bf16 v[0:3], v[168:171], v[200:203], v[0:3]
	v_mfma_f32_16x16x32_bf16 v[52:55], v[164:167], v[180:183], v[52:55]
	v_mfma_f32_16x16x32_bf16 v[48:51], v[172:175], v[180:183], v[48:51]
	v_mfma_f32_16x16x32_bf16 v[36:39], v[164:167], v[188:191], v[36:39]
	v_mfma_f32_16x16x32_bf16 v[32:35], v[172:175], v[188:191], v[32:35]
	v_mfma_f32_16x16x32_bf16 v[20:23], v[164:167], v[196:199], v[20:23]
	v_mfma_f32_16x16x32_bf16 v[16:19], v[172:175], v[196:199], v[16:19]
	v_mfma_f32_16x16x32_bf16 v[4:7], v[164:167], v[204:207], v[4:7]
	v_mfma_f32_16x16x32_bf16 v[0:3], v[172:175], v[204:207], v[0:3]
	s_barrier
	s_add_i32 s53, s53, 2
	s_add_u32 s34, s34, 0x100
	s_addc_u32 s35, s35, 0
	s_add_u32 s51, s51, 0x100
	s_addc_u32 s52, s52, 0
	s_cmp_gt_u32 s53, 13
	s_cbranch_scc0 .LBB0_3679
	s_branch .Lpost_3679
.LBB0_3679:
	ds_read_b128 v[144:147], v141
	ds_read_b128 v[148:151], v141 offset:1024
	ds_read_b128 v[152:155], v141 offset:2048
	ds_read_b128 v[156:159], v141 offset:3072
	ds_read_b128 v[160:163], v142
	ds_read_b128 v[164:167], v142 offset:1024
	ds_read_b128 v[168:171], v142 offset:2048
	ds_read_b128 v[172:175], v142 offset:3072
	s_add_u32 s14, s34, 0xfffc0080
	s_addc_u32 s15, s35, -1
	s_cmp_eq_u32 s53, 12
	s_cselect_b32 s37, s9, s15
	s_cselect_b32 s36, s49, s14
	s_cselect_b32 s15, s11, s52
	s_cselect_b32 s14, s50, s51
	v_lshl_add_u64 v[208:209], s[34:35], 0, v[136:137]
	s_add_i32 m0, s25, 0xc000
	ds_read_b128 v[176:179], v143
	ds_read_b128 v[180:183], v143 offset:1024
	ds_read_b128 v[184:187], v143 offset:2048
	ds_read_b128 v[188:191], v143 offset:3072
	ds_read_b128 v[192:195], v143 offset:4096
	ds_read_b128 v[196:199], v143 offset:5120
	ds_read_b128 v[200:203], v143 offset:6144
	ds_read_b128 v[204:207], v143 offset:7168
	global_load_lds_dwordx4 v[208:209], off
	v_lshl_add_u64 v[208:209], s[34:35], 0, v[138:139]
	s_add_i32 m0, s25, 0xe000
	s_nop 0
	global_load_lds_dwordx4 v[208:209], off
	s_waitcnt vmcnt(8)
	s_waitcnt lgkmcnt(0)
	s_barrier
; #define G_STAGE(bufoff, gbase, voff) do { _Pragma("unroll") for (int _i = 0; _i < 2; ++_i) \
;         __builtin_amdgcn_global_load_lds((const unsigned*)((const char*)(gbase) + voff[_i]), (LAS unsigned*)(lds + (bufoff) + ldsw + _i * 8192), 16, 0, 0); } while (0)
; #define G_LDA(dst, b, h) do { _Pragma("unroll") for (int m = 0; m < 4; ++m) _Pragma("unroll") for (int k = 0; k < 2; ++k) dst[m][k] = *(const LAS bf16x8*)(lds + G_SA(b, h) + aoff + m * 2048 + k * 1024); } while (0)
; #define G_LDB(dst, b, h) do { _Pragma("unroll") for (int n = 0; n < 2; ++n) _Pragma("unroll") for (int k = 0; k < 2; ++k) dst[n][k] = *(const LAS bf16x8*)(lds + G_SB(b, h) + boff + n * 2048 + k * 1024); } while (0)
; #define G_MMA(ai, bj, At_, Bt_) do { __builtin_amdgcn_s_setprio(1); _Pragma("unroll") for (int m = 0; m < 4; ++m) _Pragma("unroll") for (int n = 0; n < 2; ++n) _Pragma("unroll") for (int k = 0; k < 2; ++k) \
;         acc[ai][bj][m][n] = __builtin_amdgcn_mfma_f32_16x16x32_bf16(Bt_[n][k], At_[m][k], acc[ai][bj][m][n], 0, 0, 0); __builtin_amdgcn_s_setprio(0); } while (0)
; #define WAIT_V(n) asm volatile("s_waitcnt vmcnt(" #n ")" ::: "memory")
; #define WAIT_L(n) asm volatile("s_waitcnt lgkmcnt(" #n ")" ::: "memory")
; #define BAR __builtin_amdgcn_s_barrier()
; #define SCHED __builtin_amdgcn_sched_barrier(0)
; template <class Get, class Epi>
; DI void gemm_loop(int ntiles, int ld, char* shm, const Get& get, const Epi& epi) {
;     ...
;             WAIT_V(8); WAIT_L(0); BAR; G_MMA(0, 0, At, B0); G_MMA(0, 1, At, B1); BAR; SCHED;
;             G_LDA(At, 0, 1); G_STAGE(G_SB(0, 0), b2, voffB); G_STAGE(G_SB(0, 1), b2 + hstep, voffB); G_STAGE(G_SA(0, 0), a2, voffA);
;             WAIT_V(8); WAIT_L(0); BAR; G_MMA(1, 0, At, B0); G_MMA(1, 1, At, B1); BAR; SCHED;
;             G_LDB(B0, 1, 0); G_LDB(B1, 1, 1); SCHED; G_LDA(At, 1, 0); G_STAGE(G_SA(0, 1), a2 + hstep, voffA);
;             WAIT_V(8); WAIT_L(0); BAR; G_MMA(0, 0, At, B0); G_MMA(0, 1, At, B1); BAR; SCHED;
	s_waitcnt lgkmcnt(0)
	v_mfma_f32_16x16x32_bf16 v[124:127], v[144:147], v[176:179], v[124:127]
	v_mfma_f32_16x16x32_bf16 v[120:123], v[152:155], v[176:179], v[120:123]
	v_mfma_f32_16x16x32_bf16 v[108:111], v[144:147], v[184:187], v[108:111]
	v_mfma_f32_16x16x32_bf16 v[104:107], v[152:155], v[184:187], v[104:107]
	v_mfma_f32_16x16x32_bf16 v[92:95], v[144:147], v[192:195], v[92:95]
	v_mfma_f32_16x16x32_bf16 v[88:91], v[152:155], v[192:195], v[88:91]
	v_mfma_f32_16x16x32_bf16 v[76:79], v[144:147], v[200:203], v[76:79]
	v_mfma_f32_16x16x32_bf16 v[72:75], v[152:155], v[200:203], v[72:75]
	v_mfma_f32_16x16x32_bf16 v[124:127], v[148:151], v[180:183], v[124:127]
	v_mfma_f32_16x16x32_bf16 v[120:123], v[156:159], v[180:183], v[120:123]
	v_mfma_f32_16x16x32_bf16 v[108:111], v[148:151], v[188:191], v[108:111]
	v_mfma_f32_16x16x32_bf16 v[104:107], v[156:159], v[188:191], v[104:107]
	v_mfma_f32_16x16x32_bf16 v[92:95], v[148:151], v[196:199], v[92:95]
	v_mfma_f32_16x16x32_bf16 v[88:91], v[156:159], v[196:199], v[88:91]
	v_mfma_f32_16x16x32_bf16 v[76:79], v[148:151], v[204:207], v[76:79]
	v_mfma_f32_16x16x32_bf16 v[72:75], v[156:159], v[204:207], v[72:75]
	v_mfma_f32_16x16x32_bf16 v[116:119], v[160:163], v[176:179], v[116:119]
	v_mfma_f32_16x16x32_bf16 v[112:115], v[168:171], v[176:179], v[112:115]
	v_mfma_f32_16x16x32_bf16 v[100:103], v[160:163], v[184:187], v[100:103]
	v_mfma_f32_16x16x32_bf16 v[96:99], v[168:171], v[184:187], v[96:99]
	v_mfma_f32_16x16x32_bf16 v[84:87], v[160:163], v[192:195], v[84:87]
	v_mfma_f32_16x16x32_bf16 v[80:83], v[168:171], v[192:195], v[80:83]
	v_mfma_f32_16x16x32_bf16 v[68:71], v[160:163], v[200:203], v[68:71]
	v_mfma_f32_16x16x32_bf16 v[64:67], v[168:171], v[200:203], v[64:67]
	v_mfma_f32_16x16x32_bf16 v[116:119], v[164:167], v[180:183], v[116:119]
	v_mfma_f32_16x16x32_bf16 v[112:115], v[172:175], v[180:183], v[112:115]
	v_mfma_f32_16x16x32_bf16 v[100:103], v[164:167], v[188:191], v[100:103]
	v_mfma_f32_16x16x32_bf16 v[96:99], v[172:175], v[188:191], v[96:99]
	v_mfma_f32_16x16x32_bf16 v[84:87], v[164:167], v[196:199], v[84:87]
	v_mfma_f32_16x16x32_bf16 v[80:83], v[172:175], v[196:199], v[80:83]
	v_mfma_f32_16x16x32_bf16 v[68:71], v[164:167], v[204:207], v[68:71]
	v_mfma_f32_16x16x32_bf16 v[64:67], v[172:175], v[204:207], v[64:67]
	s_barrier
	s_add_i32 s54, s44, s38
	v_lshl_add_u64 v[208:209], s[14:15], 0, v[132:133]
	s_mov_b32 m0, s54
	ds_read_b128 v[176:179], v143 offset:16384
	ds_read_b128 v[180:183], v143 offset:17408
	ds_read_b128 v[184:187], v143 offset:18432
	ds_read_b128 v[188:191], v143 offset:19456
	ds_read_b128 v[192:195], v143 offset:20480
	ds_read_b128 v[196:199], v143 offset:21504
	ds_read_b128 v[200:203], v143 offset:22528
	ds_read_b128 v[204:207], v143 offset:23552
	global_load_lds_dwordx4 v[208:209], off
	s_add_i32 m0, s54, 0x2000
	s_add_u32 s54, s14, 0x40000
	v_lshl_add_u64 v[210:211], s[14:15], 0, v[128:129]
	s_addc_u32 s55, s15, 0
	s_add_i32 s56, s45, s38
	global_load_lds_dwordx4 v[210:211], off
	v_lshl_add_u64 v[212:213], s[54:55], 0, v[132:133]
	s_mov_b32 m0, s56
	v_lshl_add_u64 v[214:215], s[36:37], 0, v[130:131]
	global_load_lds_dwordx4 v[212:213], off
	v_lshl_add_u64 v[212:213], s[54:55], 0, v[128:129]
	s_add_i32 m0, s56, 0x2000
	s_nop 0
	global_load_lds_dwordx4 v[212:213], off
	v_lshl_add_u64 v[212:213], s[36:37], 0, v[134:135]
	s_mov_b32 m0, s25
	s_nop 0
	global_load_lds_dwordx4 v[212:213], off
	s_mov_b32 m0, s31
	s_nop 0
	global_load_lds_dwordx4 v[214:215], off
	s_waitcnt vmcnt(8)
	s_waitcnt lgkmcnt(0)
	s_barrier
	s_waitcnt lgkmcnt(0)
	v_mfma_f32_16x16x32_bf16 v[60:63], v[144:147], v[176:179], v[60:63]
	v_mfma_f32_16x16x32_bf16 v[56:59], v[152:155], v[176:179], v[56:59]
	v_mfma_f32_16x16x32_bf16 v[44:47], v[144:147], v[184:187], v[44:47]
	v_mfma_f32_16x16x32_bf16 v[40:43], v[152:155], v[184:187], v[40:43]
	v_mfma_f32_16x16x32_bf16 v[28:31], v[144:147], v[192:195], v[28:31]
	v_mfma_f32_16x16x32_bf16 v[24:27], v[152:155], v[192:195], v[24:27]
	v_mfma_f32_16x16x32_bf16 v[12:15], v[144:147], v[200:203], v[12:15]
	v_mfma_f32_16x16x32_bf16 v[8:11], v[152:155], v[200:203], v[8:11]
	v_mfma_f32_16x16x32_bf16 v[60:63], v[148:151], v[180:183], v[60:63]
	v_mfma_f32_16x16x32_bf16 v[56:59], v[156:159], v[180:183], v[56:59]
	v_mfma_f32_16x16x32_bf16 v[44:47], v[148:151], v[188:191], v[44:47]
	v_mfma_f32_16x16x32_bf16 v[40:43], v[156:159], v[188:191], v[40:43]
	v_mfma_f32_16x16x32_bf16 v[28:31], v[148:151], v[196:199], v[28:31]
	v_mfma_f32_16x16x32_bf16 v[24:27], v[156:159], v[196:199], v[24:27]
	v_mfma_f32_16x16x32_bf16 v[12:15], v[148:151], v[204:207], v[12:15]
	v_mfma_f32_16x16x32_bf16 v[8:11], v[156:159], v[204:207], v[8:11]
	v_mfma_f32_16x16x32_bf16 v[52:55], v[160:163], v[176:179], v[52:55]
	v_mfma_f32_16x16x32_bf16 v[48:51], v[168:171], v[176:179], v[48:51]
	v_mfma_f32_16x16x32_bf16 v[36:39], v[160:163], v[184:187], v[36:39]
	v_mfma_f32_16x16x32_bf16 v[32:35], v[168:171], v[184:187], v[32:35]
	v_mfma_f32_16x16x32_bf16 v[20:23], v[160:163], v[192:195], v[20:23]
	v_mfma_f32_16x16x32_bf16 v[16:19], v[168:171], v[192:195], v[16:19]
	v_mfma_f32_16x16x32_bf16 v[4:7], v[160:163], v[200:203], v[4:7]
	v_mfma_f32_16x16x32_bf16 v[0:3], v[168:171], v[200:203], v[0:3]
	v_mfma_f32_16x16x32_bf16 v[52:55], v[164:167], v[180:183], v[52:55]
	v_mfma_f32_16x16x32_bf16 v[48:51], v[172:175], v[180:183], v[48:51]
	v_mfma_f32_16x16x32_bf16 v[36:39], v[164:167], v[188:191], v[36:39]
	v_mfma_f32_16x16x32_bf16 v[32:35], v[172:175], v[188:191], v[32:35]
	v_mfma_f32_16x16x32_bf16 v[20:23], v[164:167], v[196:199], v[20:23]
	v_mfma_f32_16x16x32_bf16 v[16:19], v[172:175], v[196:199], v[16:19]
	v_mfma_f32_16x16x32_bf16 v[4:7], v[164:167], v[204:207], v[4:7]
	v_mfma_f32_16x16x32_bf16 v[0:3], v[172:175], v[204:207], v[0:3]
	s_barrier
; #define G_STAGE(bufoff, gbase, voff) do { _Pragma("unroll") for (int _i = 0; _i < 2; ++_i) \
;         __builtin_amdgcn_global_load_lds((const unsigned*)((const char*)(gbase) + voff[_i]), (LAS unsigned*)(lds + (bufoff) + ldsw + _i * 8192), 16, 0, 0); } while (0)
; #define G_LDA(dst, b, h) do { _Pragma("unroll") for (int m = 0; m < 4; ++m) _Pragma("unroll") for (int k = 0; k < 2; ++k) dst[m][k] = *(const LAS bf16x8*)(lds + G_SA(b, h) + aoff + m * 2048 + k * 1024); } while (0)
; #define G_LDB(dst, b, h) do { _Pragma("unroll") for (int n = 0; n < 2; ++n) _Pragma("unroll") for (int k = 0; k < 2; ++k) dst[n][k] = *(const LAS bf16x8*)(lds + G_SB(b, h) + boff + n * 2048 + k * 1024); } while (0)
; #define G_MMA(ai, bj, At_, Bt_) do { __builtin_amdgcn_s_setprio(1); _Pragma("unroll") for (int m = 0; m < 4; ++m) _Pragma("unroll") for (int n = 0; n < 2; ++n) _Pragma("unroll") for (int k = 0; k < 2; ++k) \
;         acc[ai][bj][m][n] = __builtin_amdgcn_mfma_f32_16x16x32_bf16(Bt_[n][k], At_[m][k], acc[ai][bj][m][n], 0, 0, 0); __builtin_amdgcn_s_setprio(0); } while (0)
; #define WAIT_V(n) asm volatile("s_waitcnt vmcnt(" #n ")" ::: "memory")
; #define WAIT_L(n) asm volatile("s_waitcnt lgkmcnt(" #n ")" ::: "memory")
; #define BAR __builtin_amdgcn_s_barrier()
; #define SCHED __builtin_amdgcn_sched_barrier(0)
; template <class Get, class Epi>
; DI void gemm_loop(int ntiles, int ld, char* shm, const Get& get, const Epi& epi) {
;     ...
;             G_LDB(B0, 1, 0); G_LDB(B1, 1, 1); SCHED; G_LDA(At, 1, 0); G_STAGE(G_SA(0, 1), a2 + hstep, voffA);
;             WAIT_V(8); WAIT_L(0); BAR; G_MMA(0, 0, At, B0); G_MMA(0, 1, At, B1); BAR; SCHED;
;             G_LDA(At, 1, 1); G_STAGE(G_SB(1, 0), b3, voffB); G_STAGE(G_SB(1, 1), b3 + hstep, voffB); G_STAGE(G_SA(1, 0), a3, voffA);
;             WAIT_V(8); WAIT_L(0); BAR; G_MMA(1, 0, At, B0); G_MMA(1, 1, At, B1); BAR; SCHED;
;         }
	s_add_i32 s54, 0, 0x18000
	s_add_i32 s55, 0, 0x1c000
	v_add_u32_e32 v156, s54, v140
	v_add_u32_e32 v172, s55, v140
	ds_read_b128 v[144:147], v156
	ds_read_b128 v[148:151], v156 offset:1024
	ds_read_b128 v[152:155], v156 offset:2048
	ds_read_b128 v[156:159], v156 offset:3072
	ds_read_b128 v[160:163], v172
	ds_read_b128 v[164:167], v172 offset:1024
	ds_read_b128 v[168:171], v172 offset:2048
	ds_read_b128 v[172:175], v172 offset:3072
	s_add_u32 s36, s36, 0x40000
	s_addc_u32 s37, s37, 0
	s_mov_b32 m0, s40
	v_lshl_add_u64 v[216:217], s[36:37], 0, v[134:135]
	ds_read_b128 v[176:179], v143 offset:32768
	ds_read_b128 v[180:183], v143 offset:33792
	ds_read_b128 v[184:187], v143 offset:34816
	ds_read_b128 v[188:191], v143 offset:35840
	ds_read_b128 v[192:195], v143 offset:36864
	ds_read_b128 v[196:199], v143 offset:37888
	ds_read_b128 v[200:203], v143 offset:38912
	ds_read_b128 v[204:207], v143 offset:39936
	global_load_lds_dwordx4 v[216:217], off
	v_lshl_add_u64 v[216:217], s[36:37], 0, v[130:131]
	s_mov_b32 m0, s41
	s_nop 0
	global_load_lds_dwordx4 v[216:217], off
	s_waitcnt vmcnt(8)
	s_waitcnt lgkmcnt(0)
	s_barrier
	s_waitcnt lgkmcnt(0)
	v_mfma_f32_16x16x32_bf16 v[124:127], v[144:147], v[176:179], v[124:127]
	v_mfma_f32_16x16x32_bf16 v[120:123], v[152:155], v[176:179], v[120:123]
	v_mfma_f32_16x16x32_bf16 v[108:111], v[144:147], v[184:187], v[108:111]
	v_mfma_f32_16x16x32_bf16 v[104:107], v[152:155], v[184:187], v[104:107]
	v_mfma_f32_16x16x32_bf16 v[92:95], v[144:147], v[192:195], v[92:95]
	v_mfma_f32_16x16x32_bf16 v[88:91], v[152:155], v[192:195], v[88:91]
	v_mfma_f32_16x16x32_bf16 v[76:79], v[144:147], v[200:203], v[76:79]
	v_mfma_f32_16x16x32_bf16 v[72:75], v[152:155], v[200:203], v[72:75]
	v_mfma_f32_16x16x32_bf16 v[124:127], v[148:151], v[180:183], v[124:127]
	v_mfma_f32_16x16x32_bf16 v[120:123], v[156:159], v[180:183], v[120:123]
	v_mfma_f32_16x16x32_bf16 v[108:111], v[148:151], v[188:191], v[108:111]
	v_mfma_f32_16x16x32_bf16 v[104:107], v[156:159], v[188:191], v[104:107]
	v_mfma_f32_16x16x32_bf16 v[92:95], v[148:151], v[196:199], v[92:95]
	v_mfma_f32_16x16x32_bf16 v[88:91], v[156:159], v[196:199], v[88:91]
	v_mfma_f32_16x16x32_bf16 v[76:79], v[148:151], v[204:207], v[76:79]
	v_mfma_f32_16x16x32_bf16 v[72:75], v[156:159], v[204:207], v[72:75]
	v_mfma_f32_16x16x32_bf16 v[116:119], v[160:163], v[176:179], v[116:119]
	v_mfma_f32_16x16x32_bf16 v[112:115], v[168:171], v[176:179], v[112:115]
	v_mfma_f32_16x16x32_bf16 v[100:103], v[160:163], v[184:187], v[100:103]
	v_mfma_f32_16x16x32_bf16 v[96:99], v[168:171], v[184:187], v[96:99]
	v_mfma_f32_16x16x32_bf16 v[84:87], v[160:163], v[192:195], v[84:87]
	v_mfma_f32_16x16x32_bf16 v[80:83], v[168:171], v[192:195], v[80:83]
	v_mfma_f32_16x16x32_bf16 v[68:71], v[160:163], v[200:203], v[68:71]
	v_mfma_f32_16x16x32_bf16 v[64:67], v[168:171], v[200:203], v[64:67]
	v_mfma_f32_16x16x32_bf16 v[116:119], v[164:167], v[180:183], v[116:119]
	v_mfma_f32_16x16x32_bf16 v[112:115], v[172:175], v[180:183], v[112:115]
	v_mfma_f32_16x16x32_bf16 v[100:103], v[164:167], v[188:191], v[100:103]
	v_mfma_f32_16x16x32_bf16 v[96:99], v[172:175], v[188:191], v[96:99]
	v_mfma_f32_16x16x32_bf16 v[84:87], v[164:167], v[196:199], v[84:87]
	v_mfma_f32_16x16x32_bf16 v[80:83], v[172:175], v[196:199], v[80:83]
	v_mfma_f32_16x16x32_bf16 v[68:71], v[164:167], v[204:207], v[68:71]
	v_mfma_f32_16x16x32_bf16 v[64:67], v[172:175], v[204:207], v[64:67]
	s_barrier
	s_add_i32 s36, s54, s38
	v_lshl_add_u64 v[208:209], v[208:209], 0, s[2:3]
	s_mov_b32 m0, s36
	ds_read_b128 v[176:179], v143 offset:49152
	ds_read_b128 v[180:183], v143 offset:50176
	ds_read_b128 v[184:187], v143 offset:51200
	ds_read_b128 v[188:191], v143 offset:52224
	ds_read_b128 v[192:195], v143 offset:53248
	ds_read_b128 v[196:199], v143 offset:54272
	ds_read_b128 v[200:203], v143 offset:55296
	ds_read_b128 v[204:207], v143 offset:56320
	global_load_lds_dwordx4 v[208:209], off
	s_add_i32 m0, s36, 0x2000
	s_add_u32 s14, s14, 0x40080
	v_lshl_add_u64 v[208:209], v[210:211], 0, s[2:3]
	s_addc_u32 s15, s15, 0
	s_add_i32 s36, s55, s38
	global_load_lds_dwordx4 v[208:209], off
	v_lshl_add_u64 v[208:209], s[14:15], 0, v[132:133]
	s_mov_b32 m0, s36
	s_nop 0
	global_load_lds_dwordx4 v[208:209], off
	v_lshl_add_u64 v[208:209], s[14:15], 0, v[128:129]
	s_add_i32 m0, s36, 0x2000
	s_nop 0
	global_load_lds_dwordx4 v[208:209], off
	v_lshl_add_u64 v[208:209], v[212:213], 0, s[2:3]
	s_mov_b32 m0, s42
	s_nop 0
	global_load_lds_dwordx4 v[208:209], off
	v_lshl_add_u64 v[208:209], v[214:215], 0, s[2:3]
	s_mov_b32 m0, s43
	s_nop 0
	global_load_lds_dwordx4 v[208:209], off
	s_waitcnt vmcnt(8)
	s_waitcnt lgkmcnt(0)
	s_barrier
	s_waitcnt lgkmcnt(0)
	v_mfma_f32_16x16x32_bf16 v[60:63], v[144:147], v[176:179], v[60:63]
	v_mfma_f32_16x16x32_bf16 v[56:59], v[152:155], v[176:179], v[56:59]
	v_mfma_f32_16x16x32_bf16 v[44:47], v[144:147], v[184:187], v[44:47]
	v_mfma_f32_16x16x32_bf16 v[40:43], v[152:155], v[184:187], v[40:43]
	v_mfma_f32_16x16x32_bf16 v[28:31], v[144:147], v[192:195], v[28:31]
	v_mfma_f32_16x16x32_bf16 v[24:27], v[152:155], v[192:195], v[24:27]
	v_mfma_f32_16x16x32_bf16 v[12:15], v[144:147], v[200:203], v[12:15]
	v_mfma_f32_16x16x32_bf16 v[8:11], v[152:155], v[200:203], v[8:11]
	v_mfma_f32_16x16x32_bf16 v[60:63], v[148:151], v[180:183], v[60:63]
	v_mfma_f32_16x16x32_bf16 v[56:59], v[156:159], v[180:183], v[56:59]
	v_mfma_f32_16x16x32_bf16 v[44:47], v[148:151], v[188:191], v[44:47]
	v_mfma_f32_16x16x32_bf16 v[40:43], v[156:159], v[188:191], v[40:43]
	v_mfma_f32_16x16x32_bf16 v[28:31], v[148:151], v[196:199], v[28:31]
	v_mfma_f32_16x16x32_bf16 v[24:27], v[156:159], v[196:199], v[24:27]
	v_mfma_f32_16x16x32_bf16 v[12:15], v[148:151], v[204:207], v[12:15]
	v_mfma_f32_16x16x32_bf16 v[8:11], v[156:159], v[204:207], v[8:11]
	v_mfma_f32_16x16x32_bf16 v[52:55], v[160:163], v[176:179], v[52:55]
	v_mfma_f32_16x16x32_bf16 v[48:51], v[168:171], v[176:179], v[48:51]
	v_mfma_f32_16x16x32_bf16 v[36:39], v[160:163], v[184:187], v[36:39]
	v_mfma_f32_16x16x32_bf16 v[32:35], v[168:171], v[184:187], v[32:35]
	v_mfma_f32_16x16x32_bf16 v[20:23], v[160:163], v[192:195], v[20:23]
	v_mfma_f32_16x16x32_bf16 v[16:19], v[168:171], v[192:195], v[16:19]
	v_mfma_f32_16x16x32_bf16 v[4:7], v[160:163], v[200:203], v[4:7]
	v_mfma_f32_16x16x32_bf16 v[0:3], v[168:171], v[200:203], v[0:3]
	v_mfma_f32_16x16x32_bf16 v[52:55], v[164:167], v[180:183], v[52:55]
	v_mfma_f32_16x16x32_bf16 v[48:51], v[172:175], v[180:183], v[48:51]
	v_mfma_f32_16x16x32_bf16 v[36:39], v[164:167], v[188:191], v[36:39]
	v_mfma_f32_16x16x32_bf16 v[32:35], v[172:175], v[188:191], v[32:35]
	v_mfma_f32_16x16x32_bf16 v[20:23], v[164:167], v[196:199], v[20:23]
	v_mfma_f32_16x16x32_bf16 v[16:19], v[172:175], v[196:199], v[16:19]
	v_mfma_f32_16x16x32_bf16 v[4:7], v[164:167], v[204:207], v[4:7]
	v_mfma_f32_16x16x32_bf16 v[0:3], v[172:175], v[204:207], v[0:3]
	s_barrier
	s_add_i32 s53, s53, 2
	s_add_u32 s34, s34, 0x100
	s_addc_u32 s35, s35, 0
	s_add_u32 s51, s51, 0x100
	s_addc_u32 s52, s52, 0
	s_cmp_gt_u32 s53, 13
	s_cbranch_scc0 .LBB0_3679

; #define G_STAGE(bufoff, gbase, voff) do { _Pragma("unroll") for (int _i = 0; _i < 2; ++_i) \
;         __builtin_amdgcn_global_load_lds((const unsigned*)((const char*)(gbase) + voff[_i]), (LAS unsigned*)(lds + (bufoff) + ldsw + _i * 8192), 16, 0, 0); } while (0)
; #define G_LDA(dst, b, h) do { _Pragma("unroll") for (int m = 0; m < 4; ++m) _Pragma("unroll") for (int k = 0; k < 2; ++k) dst[m][k] = *(const LAS bf16x8*)(lds + G_SA(b, h) + aoff + m * 2048 + k * 1024); } while (0)
; #define G_LDB(dst, b, h) do { _Pragma("unroll") for (int n = 0; n < 2; ++n) _Pragma("unroll") for (int k = 0; k < 2; ++k) dst[n][k] = *(const LAS bf16x8*)(lds + G_SB(b, h) + boff + n * 2048 + k * 1024); } while (0)
; #define G_MMA(ai, bj, At_, Bt_) do { __builtin_amdgcn_s_setprio(1); _Pragma("unroll") for (int m = 0; m < 4; ++m) _Pragma("unroll") for (int n = 0; n < 2; ++n) _Pragma("unroll") for (int k = 0; k < 2; ++k) \
;         acc[ai][bj][m][n] = __builtin_amdgcn_mfma_f32_16x16x32_bf16(Bt_[n][k], At_[m][k], acc[ai][bj][m][n], 0, 0, 0); __builtin_amdgcn_s_setprio(0); } while (0)
; #define WAIT_V(n) asm volatile("s_waitcnt vmcnt(" #n ")" ::: "memory")
; #define WAIT_L(n) asm volatile("s_waitcnt lgkmcnt(" #n ")" ::: "memory")
; #define BAR __builtin_amdgcn_s_barrier()
; #define SCHED __builtin_amdgcn_sched_barrier(0)
; template <class Get, class Epi>
; DI void gemm_loop(int ntiles, int ld, char* shm, const Get& get, const Epi& epi) {
;     ...
;             G_LDB(B0, 0, 0); G_LDB(B1, 0, 1); SCHED; G_LDA(At, 0, 0); G_STAGE(G_SA(1, 1), a1 + hstep, voffA);
;             WAIT_V(8); WAIT_L(0); BAR; G_MMA(0, 0, At, B0); G_MMA(0, 1, At, B1); BAR; SCHED;
;             G_LDA(At, 0, 1); G_STAGE(G_SB(0, 0), b2, voffB); G_STAGE(G_SB(0, 1), b2 + hstep, voffB); G_STAGE(G_SA(0, 0), a2, voffA);
;             WAIT_V(8); WAIT_L(0); BAR; G_MMA(1, 0, At, B0); G_MMA(1, 1, At, B1); BAR; SCHED;
.Lrj_3759_0:
	s_waitcnt lgkmcnt(0)
	s_barrier
	s_waitcnt lgkmcnt(0)
	v_mfma_f32_16x16x32_bf16 v[124:127], v[128:131], v[180:183], 0
	v_mfma_f32_16x16x32_bf16 v[120:123], v[136:139], v[180:183], 0
	v_mfma_f32_16x16x32_bf16 v[116:119], v[128:131], v[188:191], 0
	v_mfma_f32_16x16x32_bf16 v[112:115], v[136:139], v[188:191], 0
	v_mfma_f32_16x16x32_bf16 v[108:111], v[128:131], v[196:199], 0
	v_mfma_f32_16x16x32_bf16 v[104:107], v[136:139], v[196:199], 0
	v_mfma_f32_16x16x32_bf16 v[100:103], v[128:131], v[204:207], 0
	v_mfma_f32_16x16x32_bf16 v[96:99], v[136:139], v[204:207], 0
	v_mfma_f32_16x16x32_bf16 v[124:127], v[132:135], v[184:187], v[124:127]
	v_mfma_f32_16x16x32_bf16 v[120:123], v[140:143], v[184:187], v[120:123]
	v_mfma_f32_16x16x32_bf16 v[116:119], v[132:135], v[192:195], v[116:119]
	v_mfma_f32_16x16x32_bf16 v[112:115], v[140:143], v[192:195], v[112:115]
	v_mfma_f32_16x16x32_bf16 v[108:111], v[132:135], v[200:203], v[108:111]
	v_mfma_f32_16x16x32_bf16 v[104:107], v[140:143], v[200:203], v[104:107]
	v_mfma_f32_16x16x32_bf16 v[100:103], v[132:135], v[208:211], v[100:103]
	v_mfma_f32_16x16x32_bf16 v[96:99], v[140:143], v[208:211], v[96:99]
	v_mfma_f32_16x16x32_bf16 v[60:63], v[158:161], v[180:183], 0
	v_mfma_f32_16x16x32_bf16 v[56:59], v[172:175], v[180:183], 0
	v_mfma_f32_16x16x32_bf16 v[52:55], v[158:161], v[188:191], 0
	v_mfma_f32_16x16x32_bf16 v[48:51], v[172:175], v[188:191], 0
	v_mfma_f32_16x16x32_bf16 v[44:47], v[158:161], v[196:199], 0
	v_mfma_f32_16x16x32_bf16 v[40:43], v[172:175], v[196:199], 0
	v_mfma_f32_16x16x32_bf16 v[36:39], v[158:161], v[204:207], 0
	v_mfma_f32_16x16x32_bf16 v[32:35], v[172:175], v[204:207], 0
	v_mfma_f32_16x16x32_bf16 v[60:63], v[162:165], v[184:187], v[60:63]
	v_mfma_f32_16x16x32_bf16 v[56:59], v[176:179], v[184:187], v[56:59]
	v_mfma_f32_16x16x32_bf16 v[52:55], v[162:165], v[192:195], v[52:55]
	v_mfma_f32_16x16x32_bf16 v[48:51], v[176:179], v[192:195], v[48:51]
	v_mfma_f32_16x16x32_bf16 v[44:47], v[162:165], v[200:203], v[44:47]
	v_mfma_f32_16x16x32_bf16 v[40:43], v[176:179], v[200:203], v[40:43]
	v_mfma_f32_16x16x32_bf16 v[36:39], v[162:165], v[208:211], v[36:39]
	v_mfma_f32_16x16x32_bf16 v[32:35], v[176:179], v[208:211], v[32:35]
	s_barrier
	s_add_i32 s2, s44, s33
	v_lshl_add_u64 v[144:145], s[30:31], 0, v[148:149]
	s_mov_b32 m0, s2
	ds_read_b128 v[180:183], v171 offset:16384
	ds_read_b128 v[184:187], v171 offset:17408
	ds_read_b128 v[188:191], v171 offset:18432
	ds_read_b128 v[192:195], v171 offset:19456
	ds_read_b128 v[196:199], v171 offset:20480
	ds_read_b128 v[200:203], v171 offset:21504
	ds_read_b128 v[204:207], v171 offset:22528
	ds_read_b128 v[208:211], v171 offset:23552
	global_load_lds_dwordx4 v[144:145], off
	s_add_i32 m0, s2, 0x2000
	s_add_u32 s2, s30, 0xb0000
	v_lshl_add_u64 v[166:167], s[30:31], 0, v[152:153]
	s_addc_u32 s3, s31, 0
	s_add_i32 s55, s45, s33
	global_load_lds_dwordx4 v[166:167], off
	v_lshl_add_u64 v[212:213], s[2:3], 0, v[148:149]
	s_mov_b32 m0, s55
	v_lshl_add_u64 v[214:215], s[34:35], 0, v[150:151]
	global_load_lds_dwordx4 v[212:213], off
	v_lshl_add_u64 v[212:213], s[2:3], 0, v[152:153]
	s_add_i32 m0, s55, 0x2000
	s_nop 0
	global_load_lds_dwordx4 v[212:213], off
	v_lshl_add_u64 v[212:213], s[34:35], 0, v[146:147]
	s_mov_b32 m0, s36
	s_nop 0
	global_load_lds_dwordx4 v[212:213], off
	s_mov_b32 m0, s37
	s_nop 0
	global_load_lds_dwordx4 v[214:215], off
	s_cmp_lg_u32 s100, 0
	s_cbranch_scc0 .Lrf_3759_1
	s_waitcnt vmcnt(16)
	s_branch .Lrj_3759_1

; #define G_STAGE(bufoff, gbase, voff) do { _Pragma("unroll") for (int _i = 0; _i < 2; ++_i) \
;         __builtin_amdgcn_global_load_lds((const unsigned*)((const char*)(gbase) + voff[_i]), (LAS unsigned*)(lds + (bufoff) + ldsw + _i * 8192), 16, 0, 0); } while (0)
; #define G_LDA(dst, b, h) do { _Pragma("unroll") for (int m = 0; m < 4; ++m) _Pragma("unroll") for (int k = 0; k < 2; ++k) dst[m][k] = *(const LAS bf16x8*)(lds + G_SA(b, h) + aoff + m * 2048 + k * 1024); } while (0)
; #define G_LDB(dst, b, h) do { _Pragma("unroll") for (int n = 0; n < 2; ++n) _Pragma("unroll") for (int k = 0; k < 2; ++k) dst[n][k] = *(const LAS bf16x8*)(lds + G_SB(b, h) + boff + n * 2048 + k * 1024); } while (0)
; #define G_MMA(ai, bj, At_, Bt_) do { __builtin_amdgcn_s_setprio(1); _Pragma("unroll") for (int m = 0; m < 4; ++m) _Pragma("unroll") for (int n = 0; n < 2; ++n) _Pragma("unroll") for (int k = 0; k < 2; ++k) \
;         acc[ai][bj][m][n] = __builtin_amdgcn_mfma_f32_16x16x32_bf16(Bt_[n][k], At_[m][k], acc[ai][bj][m][n], 0, 0, 0); __builtin_amdgcn_s_setprio(0); } while (0)
; #define WAIT_V(n) asm volatile("s_waitcnt vmcnt(" #n ")" ::: "memory")
; #define WAIT_L(n) asm volatile("s_waitcnt lgkmcnt(" #n ")" ::: "memory")
; #define BAR __builtin_amdgcn_s_barrier()
; #define SCHED __builtin_amdgcn_sched_barrier(0)
; template <class Get, class Epi>
; DI void gemm_loop(int ntiles, int ld, char* shm, const Get& get, const Epi& epi) {
;     ...
;             WAIT_V(8); WAIT_L(0); BAR; G_MMA(1, 0, At, B0); G_MMA(1, 1, At, B1); BAR; SCHED;
;             G_LDB(B0, 1, 0); G_LDB(B1, 1, 1); SCHED; G_LDA(At, 1, 0); G_STAGE(G_SA(0, 1), a2 + hstep, voffA);
;             WAIT_V(8); WAIT_L(0); BAR; G_MMA(0, 0, At, B0); G_MMA(0, 1, At, B1); BAR; SCHED;
;             G_LDA(At, 1, 1); G_STAGE(G_SB(1, 0), b3, voffB); G_STAGE(G_SB(1, 1), b3 + hstep, voffB); G_STAGE(G_SA(1, 0), a3, voffA);
.Lrj_3759_1:
	s_waitcnt lgkmcnt(0)
	s_barrier
	s_waitcnt lgkmcnt(0)
	v_mfma_f32_16x16x32_bf16 v[92:95], v[128:131], v[180:183], 0
	v_mfma_f32_16x16x32_bf16 v[88:91], v[136:139], v[180:183], 0
	v_mfma_f32_16x16x32_bf16 v[84:87], v[128:131], v[188:191], 0
	v_mfma_f32_16x16x32_bf16 v[80:83], v[136:139], v[188:191], 0
	v_mfma_f32_16x16x32_bf16 v[76:79], v[128:131], v[196:199], 0
	v_mfma_f32_16x16x32_bf16 v[72:75], v[136:139], v[196:199], 0
	v_mfma_f32_16x16x32_bf16 v[68:71], v[128:131], v[204:207], 0
	v_mfma_f32_16x16x32_bf16 v[64:67], v[136:139], v[204:207], 0
	v_mfma_f32_16x16x32_bf16 v[92:95], v[132:135], v[184:187], v[92:95]
	v_mfma_f32_16x16x32_bf16 v[88:91], v[140:143], v[184:187], v[88:91]
	v_mfma_f32_16x16x32_bf16 v[84:87], v[132:135], v[192:195], v[84:87]
	v_mfma_f32_16x16x32_bf16 v[80:83], v[140:143], v[192:195], v[80:83]
	v_mfma_f32_16x16x32_bf16 v[76:79], v[132:135], v[200:203], v[76:79]
	v_mfma_f32_16x16x32_bf16 v[72:75], v[140:143], v[200:203], v[72:75]
	v_mfma_f32_16x16x32_bf16 v[68:71], v[132:135], v[208:211], v[68:71]
	v_mfma_f32_16x16x32_bf16 v[64:67], v[140:143], v[208:211], v[64:67]
	v_mfma_f32_16x16x32_bf16 v[28:31], v[158:161], v[180:183], 0
	v_mfma_f32_16x16x32_bf16 v[24:27], v[172:175], v[180:183], 0
	v_mfma_f32_16x16x32_bf16 v[20:23], v[158:161], v[188:191], 0
	v_mfma_f32_16x16x32_bf16 v[16:19], v[172:175], v[188:191], 0
	v_mfma_f32_16x16x32_bf16 v[12:15], v[158:161], v[196:199], 0
	v_mfma_f32_16x16x32_bf16 v[8:11], v[172:175], v[196:199], 0
	v_mfma_f32_16x16x32_bf16 v[4:7], v[158:161], v[204:207], 0
	v_mfma_f32_16x16x32_bf16 v[0:3], v[172:175], v[204:207], 0
	v_mfma_f32_16x16x32_bf16 v[28:31], v[162:165], v[184:187], v[28:31]
	v_mfma_f32_16x16x32_bf16 v[24:27], v[176:179], v[184:187], v[24:27]
	v_mfma_f32_16x16x32_bf16 v[20:23], v[162:165], v[192:195], v[20:23]
	v_mfma_f32_16x16x32_bf16 v[16:19], v[176:179], v[192:195], v[16:19]
	v_mfma_f32_16x16x32_bf16 v[12:15], v[162:165], v[200:203], v[12:15]
	v_mfma_f32_16x16x32_bf16 v[8:11], v[176:179], v[200:203], v[8:11]
	v_mfma_f32_16x16x32_bf16 v[4:7], v[162:165], v[208:211], v[4:7]
	v_mfma_f32_16x16x32_bf16 v[0:3], v[176:179], v[208:211], v[0:3]
	s_barrier
	s_add_i32 s55, 0, 0x18000
	s_add_i32 s56, 0, 0x1c000
	v_add_u32_e32 v140, s55, v168
	v_add_u32_e32 v176, s56, v168
	ds_read_b128 v[128:131], v140
	ds_read_b128 v[132:135], v140 offset:1024
	ds_read_b128 v[136:139], v140 offset:2048
	ds_read_b128 v[140:143], v140 offset:3072
	ds_read_b128 v[158:161], v176
	ds_read_b128 v[162:165], v176 offset:1024
	ds_read_b128 v[172:175], v176 offset:2048
	ds_read_b128 v[176:179], v176 offset:3072
	s_add_u32 s2, s34, 0xb0000
	s_addc_u32 s3, s35, 0
	s_mov_b32 m0, s38
	v_lshl_add_u64 v[216:217], s[2:3], 0, v[146:147]
	ds_read_b128 v[180:183], v171 offset:32768
	ds_read_b128 v[184:187], v171 offset:33792
	ds_read_b128 v[188:191], v171 offset:34816
	ds_read_b128 v[192:195], v171 offset:35840
	ds_read_b128 v[196:199], v171 offset:36864
	ds_read_b128 v[200:203], v171 offset:37888
	ds_read_b128 v[204:207], v171 offset:38912
	ds_read_b128 v[208:211], v171 offset:39936
	global_load_lds_dwordx4 v[216:217], off
	v_lshl_add_u64 v[216:217], s[2:3], 0, v[150:151]
	s_mov_b32 m0, s39
	s_nop 0
	global_load_lds_dwordx4 v[216:217], off
	s_waitcnt vmcnt(8)
	s_waitcnt lgkmcnt(0)
	s_barrier
	s_waitcnt lgkmcnt(0)
	v_mfma_f32_16x16x32_bf16 v[124:127], v[128:131], v[180:183], v[124:127]
	v_mfma_f32_16x16x32_bf16 v[120:123], v[136:139], v[180:183], v[120:123]
	v_mfma_f32_16x16x32_bf16 v[116:119], v[128:131], v[188:191], v[116:119]
	v_mfma_f32_16x16x32_bf16 v[112:115], v[136:139], v[188:191], v[112:115]
	v_mfma_f32_16x16x32_bf16 v[108:111], v[128:131], v[196:199], v[108:111]
	v_mfma_f32_16x16x32_bf16 v[104:107], v[136:139], v[196:199], v[104:107]
	v_mfma_f32_16x16x32_bf16 v[100:103], v[128:131], v[204:207], v[100:103]
	v_mfma_f32_16x16x32_bf16 v[96:99], v[136:139], v[204:207], v[96:99]
	v_mfma_f32_16x16x32_bf16 v[124:127], v[132:135], v[184:187], v[124:127]
	v_mfma_f32_16x16x32_bf16 v[120:123], v[140:143], v[184:187], v[120:123]
	v_mfma_f32_16x16x32_bf16 v[116:119], v[132:135], v[192:195], v[116:119]
	v_mfma_f32_16x16x32_bf16 v[112:115], v[140:143], v[192:195], v[112:115]
	v_mfma_f32_16x16x32_bf16 v[108:111], v[132:135], v[200:203], v[108:111]
	v_mfma_f32_16x16x32_bf16 v[104:107], v[140:143], v[200:203], v[104:107]
	v_mfma_f32_16x16x32_bf16 v[100:103], v[132:135], v[208:211], v[100:103]
	v_mfma_f32_16x16x32_bf16 v[96:99], v[140:143], v[208:211], v[96:99]
	v_mfma_f32_16x16x32_bf16 v[60:63], v[158:161], v[180:183], v[60:63]
	v_mfma_f32_16x16x32_bf16 v[56:59], v[172:175], v[180:183], v[56:59]
	v_mfma_f32_16x16x32_bf16 v[52:55], v[158:161], v[188:191], v[52:55]
	v_mfma_f32_16x16x32_bf16 v[48:51], v[172:175], v[188:191], v[48:51]
	v_mfma_f32_16x16x32_bf16 v[44:47], v[158:161], v[196:199], v[44:47]
	v_mfma_f32_16x16x32_bf16 v[40:43], v[172:175], v[196:199], v[40:43]
	v_mfma_f32_16x16x32_bf16 v[36:39], v[158:161], v[204:207], v[36:39]
	v_mfma_f32_16x16x32_bf16 v[32:35], v[172:175], v[204:207], v[32:35]
	v_mfma_f32_16x16x32_bf16 v[60:63], v[162:165], v[184:187], v[60:63]
	v_mfma_f32_16x16x32_bf16 v[56:59], v[176:179], v[184:187], v[56:59]
	v_mfma_f32_16x16x32_bf16 v[52:55], v[162:165], v[192:195], v[52:55]
	v_mfma_f32_16x16x32_bf16 v[48:51], v[176:179], v[192:195], v[48:51]
	v_mfma_f32_16x16x32_bf16 v[44:47], v[162:165], v[200:203], v[44:47]
	v_mfma_f32_16x16x32_bf16 v[40:43], v[176:179], v[200:203], v[40:43]
	v_mfma_f32_16x16x32_bf16 v[36:39], v[162:165], v[208:211], v[36:39]
	v_mfma_f32_16x16x32_bf16 v[32:35], v[176:179], v[208:211], v[32:35]
	s_barrier
; #define G_STAGE(bufoff, gbase, voff) do { _Pragma("unroll") for (int _i = 0; _i < 2; ++_i) \
;         __builtin_amdgcn_global_load_lds((const unsigned*)((const char*)(gbase) + voff[_i]), (LAS unsigned*)(lds + (bufoff) + ldsw + _i * 8192), 16, 0, 0); } while (0)
; #define G_LDA(dst, b, h) do { _Pragma("unroll") for (int m = 0; m < 4; ++m) _Pragma("unroll") for (int k = 0; k < 2; ++k) dst[m][k] = *(const LAS bf16x8*)(lds + G_SA(b, h) + aoff + m * 2048 + k * 1024); } while (0)
; #define G_LDB(dst, b, h) do { _Pragma("unroll") for (int n = 0; n < 2; ++n) _Pragma("unroll") for (int k = 0; k < 2; ++k) dst[n][k] = *(const LAS bf16x8*)(lds + G_SB(b, h) + boff + n * 2048 + k * 1024); } while (0)
; #define G_MMA(ai, bj, At_, Bt_) do { __builtin_amdgcn_s_setprio(1); _Pragma("unroll") for (int m = 0; m < 4; ++m) _Pragma("unroll") for (int n = 0; n < 2; ++n) _Pragma("unroll") for (int k = 0; k < 2; ++k) \
;         acc[ai][bj][m][n] = __builtin_amdgcn_mfma_f32_16x16x32_bf16(Bt_[n][k], At_[m][k], acc[ai][bj][m][n], 0, 0, 0); __builtin_amdgcn_s_setprio(0); } while (0)
; #define WAIT_V(n) asm volatile("s_waitcnt vmcnt(" #n ")" ::: "memory")
; #define WAIT_L(n) asm volatile("s_waitcnt lgkmcnt(" #n ")" ::: "memory")
; #define BAR __builtin_amdgcn_s_barrier()
; #define SCHED __builtin_amdgcn_sched_barrier(0)
; template <class Get, class Epi>
; DI void gemm_loop(int ntiles, int ld, char* shm, const Get& get, const Epi& epi) {
;     ...
;             G_LDB(B0, 0, 0); G_LDB(B1, 0, 1); SCHED; G_LDA(At, 0, 0); G_STAGE(G_SA(1, 1), a1 + hstep, voffA);
;             WAIT_V(8); WAIT_L(0); BAR; G_MMA(0, 0, At, B0); G_MMA(0, 1, At, B1); BAR; SCHED;
;     ...
;             G_LDA(At, 1, 1); G_STAGE(G_SB(1, 0), b3, voffB); G_STAGE(G_SB(1, 1), b3 + hstep, voffB); G_STAGE(G_SA(1, 0), a3, voffA);
;             WAIT_V(8); WAIT_L(0); BAR; G_MMA(1, 0, At, B0); G_MMA(1, 1, At, B1); BAR; SCHED;
;         }
	s_add_i32 s2, s55, s33
	v_lshl_add_u64 v[144:145], v[144:145], 0, s[6:7]
	s_mov_b32 m0, s2
	ds_read_b128 v[180:183], v171 offset:49152
	ds_read_b128 v[184:187], v171 offset:50176
	ds_read_b128 v[188:191], v171 offset:51200
	ds_read_b128 v[192:195], v171 offset:52224
	ds_read_b128 v[196:199], v171 offset:53248
	ds_read_b128 v[200:203], v171 offset:54272
	ds_read_b128 v[204:207], v171 offset:55296
	ds_read_b128 v[208:211], v171 offset:56320
	global_load_lds_dwordx4 v[144:145], off
	s_add_i32 m0, s2, 0x2000
	s_add_u32 s2, s30, 0xb0080
	v_lshl_add_u64 v[144:145], v[166:167], 0, s[6:7]
	s_addc_u32 s3, s31, 0
	s_add_i32 s30, s56, s33
	global_load_lds_dwordx4 v[144:145], off
	v_lshl_add_u64 v[144:145], s[2:3], 0, v[148:149]
	s_mov_b32 m0, s30
	s_nop 0
	global_load_lds_dwordx4 v[144:145], off
	v_lshl_add_u64 v[144:145], s[2:3], 0, v[152:153]
	s_add_i32 m0, s30, 0x2000
	s_nop 0
	global_load_lds_dwordx4 v[144:145], off
	v_lshl_add_u64 v[144:145], v[212:213], 0, s[6:7]
	s_mov_b32 m0, s42
	s_nop 0
	global_load_lds_dwordx4 v[144:145], off
	v_lshl_add_u64 v[144:145], v[214:215], 0, s[6:7]
	s_mov_b32 m0, s43
	s_nop 0
	global_load_lds_dwordx4 v[144:145], off
	s_waitcnt vmcnt(8)
	s_waitcnt lgkmcnt(0)
	s_barrier
	s_waitcnt lgkmcnt(0)
	v_mfma_f32_16x16x32_bf16 v[92:95], v[128:131], v[180:183], v[92:95]
	v_mfma_f32_16x16x32_bf16 v[88:91], v[136:139], v[180:183], v[88:91]
	v_mfma_f32_16x16x32_bf16 v[84:87], v[128:131], v[188:191], v[84:87]
	v_mfma_f32_16x16x32_bf16 v[80:83], v[136:139], v[188:191], v[80:83]
	v_mfma_f32_16x16x32_bf16 v[76:79], v[128:131], v[196:199], v[76:79]
	v_mfma_f32_16x16x32_bf16 v[72:75], v[136:139], v[196:199], v[72:75]
	v_mfma_f32_16x16x32_bf16 v[68:71], v[128:131], v[204:207], v[68:71]
	v_mfma_f32_16x16x32_bf16 v[64:67], v[136:139], v[204:207], v[64:67]
	v_mfma_f32_16x16x32_bf16 v[92:95], v[132:135], v[184:187], v[92:95]
	v_mfma_f32_16x16x32_bf16 v[88:91], v[140:143], v[184:187], v[88:91]
	v_mfma_f32_16x16x32_bf16 v[84:87], v[132:135], v[192:195], v[84:87]
	v_mfma_f32_16x16x32_bf16 v[80:83], v[140:143], v[192:195], v[80:83]
	v_mfma_f32_16x16x32_bf16 v[76:79], v[132:135], v[200:203], v[76:79]
	v_mfma_f32_16x16x32_bf16 v[72:75], v[140:143], v[200:203], v[72:75]
	v_mfma_f32_16x16x32_bf16 v[68:71], v[132:135], v[208:211], v[68:71]
	v_mfma_f32_16x16x32_bf16 v[64:67], v[140:143], v[208:211], v[64:67]
	v_mfma_f32_16x16x32_bf16 v[28:31], v[158:161], v[180:183], v[28:31]
	v_mfma_f32_16x16x32_bf16 v[24:27], v[172:175], v[180:183], v[24:27]
	v_mfma_f32_16x16x32_bf16 v[20:23], v[158:161], v[188:191], v[20:23]
	v_mfma_f32_16x16x32_bf16 v[16:19], v[172:175], v[188:191], v[16:19]
	v_mfma_f32_16x16x32_bf16 v[12:15], v[158:161], v[196:199], v[12:15]
	v_mfma_f32_16x16x32_bf16 v[8:11], v[172:175], v[196:199], v[8:11]
	v_mfma_f32_16x16x32_bf16 v[4:7], v[158:161], v[204:207], v[4:7]
	v_mfma_f32_16x16x32_bf16 v[0:3], v[172:175], v[204:207], v[0:3]
	v_mfma_f32_16x16x32_bf16 v[28:31], v[162:165], v[184:187], v[28:31]
	v_mfma_f32_16x16x32_bf16 v[24:27], v[176:179], v[184:187], v[24:27]
	v_mfma_f32_16x16x32_bf16 v[20:23], v[162:165], v[192:195], v[20:23]
	v_mfma_f32_16x16x32_bf16 v[16:19], v[176:179], v[192:195], v[16:19]
	v_mfma_f32_16x16x32_bf16 v[12:15], v[162:165], v[200:203], v[12:15]
	v_mfma_f32_16x16x32_bf16 v[8:11], v[176:179], v[200:203], v[8:11]
	v_mfma_f32_16x16x32_bf16 v[4:7], v[162:165], v[208:211], v[4:7]
	v_mfma_f32_16x16x32_bf16 v[0:3], v[176:179], v[208:211], v[0:3]
	s_barrier
	s_add_i32 s54, s54, 2
	s_add_u32 s52, s52, 0x100
	s_addc_u32 s53, s53, 0
	s_cmp_gt_u32 s54, 41
	s_mov_b64 s[2:3], s[24:25]
	s_cbranch_scc0 .LBB0_3759
	s_branch .Lpost_3759
.LBB0_3759:
	ds_read_b128 v[128:131], v169
	ds_read_b128 v[132:135], v169 offset:1024
	ds_read_b128 v[136:139], v169 offset:2048
	ds_read_b128 v[140:143], v169 offset:3072
	ds_read_b128 v[158:161], v170
	ds_read_b128 v[162:165], v170 offset:1024
	ds_read_b128 v[172:175], v170 offset:2048
	ds_read_b128 v[176:179], v170 offset:3072
	s_add_u32 s24, s2, 0x100
	s_addc_u32 s25, s3, 0
	s_cmp_eq_u32 s54, 40
	s_cselect_b32 s35, s21, s25
	s_cselect_b32 s34, s20, s24
	s_cselect_b32 s31, s23, s53
	s_cselect_b32 s30, s22, s52
	v_lshl_add_u64 v[144:145], s[2:3], 0, v[154:155]
	s_add_i32 m0, s36, 0xc000
	ds_read_b128 v[180:183], v171
	ds_read_b128 v[184:187], v171 offset:1024
	ds_read_b128 v[188:191], v171 offset:2048
	ds_read_b128 v[192:195], v171 offset:3072
	ds_read_b128 v[196:199], v171 offset:4096
	ds_read_b128 v[200:203], v171 offset:5120
	ds_read_b128 v[204:207], v171 offset:6144
	ds_read_b128 v[208:211], v171 offset:7168
	global_load_lds_dwordx4 v[144:145], off
	v_lshl_add_u64 v[144:145], s[2:3], 0, v[156:157]
	s_add_i32 m0, s36, 0xe000
	s_nop 0
	global_load_lds_dwordx4 v[144:145], off
	s_waitcnt vmcnt(8)
	s_waitcnt lgkmcnt(0)
	s_barrier
; #define G_STAGE(bufoff, gbase, voff) do { _Pragma("unroll") for (int _i = 0; _i < 2; ++_i) \
;         __builtin_amdgcn_global_load_lds((const unsigned*)((const char*)(gbase) + voff[_i]), (LAS unsigned*)(lds + (bufoff) + ldsw + _i * 8192), 16, 0, 0); } while (0)
; #define G_LDA(dst, b, h) do { _Pragma("unroll") for (int m = 0; m < 4; ++m) _Pragma("unroll") for (int k = 0; k < 2; ++k) dst[m][k] = *(const LAS bf16x8*)(lds + G_SA(b, h) + aoff + m * 2048 + k * 1024); } while (0)
; #define G_LDB(dst, b, h) do { _Pragma("unroll") for (int n = 0; n < 2; ++n) _Pragma("unroll") for (int k = 0; k < 2; ++k) dst[n][k] = *(const LAS bf16x8*)(lds + G_SB(b, h) + boff + n * 2048 + k * 1024); } while (0)
; #define G_MMA(ai, bj, At_, Bt_) do { __builtin_amdgcn_s_setprio(1); _Pragma("unroll") for (int m = 0; m < 4; ++m) _Pragma("unroll") for (int n = 0; n < 2; ++n) _Pragma("unroll") for (int k = 0; k < 2; ++k) \
;         acc[ai][bj][m][n] = __builtin_amdgcn_mfma_f32_16x16x32_bf16(Bt_[n][k], At_[m][k], acc[ai][bj][m][n], 0, 0, 0); __builtin_amdgcn_s_setprio(0); } while (0)
; #define WAIT_V(n) asm volatile("s_waitcnt vmcnt(" #n ")" ::: "memory")
; #define WAIT_L(n) asm volatile("s_waitcnt lgkmcnt(" #n ")" ::: "memory")
; #define BAR __builtin_amdgcn_s_barrier()
; #define SCHED __builtin_amdgcn_sched_barrier(0)
; template <class Get, class Epi>
; DI void gemm_loop(int ntiles, int ld, char* shm, const Get& get, const Epi& epi) {
;     ...
;             WAIT_V(8); WAIT_L(0); BAR; G_MMA(0, 0, At, B0); G_MMA(0, 1, At, B1); BAR; SCHED;
;             G_LDA(At, 0, 1); G_STAGE(G_SB(0, 0), b2, voffB); G_STAGE(G_SB(0, 1), b2 + hstep, voffB); G_STAGE(G_SA(0, 0), a2, voffA);
;             WAIT_V(8); WAIT_L(0); BAR; G_MMA(1, 0, At, B0); G_MMA(1, 1, At, B1); BAR; SCHED;
;             G_LDB(B0, 1, 0); G_LDB(B1, 1, 1); SCHED; G_LDA(At, 1, 0); G_STAGE(G_SA(0, 1), a2 + hstep, voffA);
;             WAIT_V(8); WAIT_L(0); BAR; G_MMA(0, 0, At, B0); G_MMA(0, 1, At, B1); BAR; SCHED;
	s_waitcnt lgkmcnt(0)
	v_mfma_f32_16x16x32_bf16 v[124:127], v[128:131], v[180:183], v[124:127]
	v_mfma_f32_16x16x32_bf16 v[120:123], v[136:139], v[180:183], v[120:123]
	v_mfma_f32_16x16x32_bf16 v[116:119], v[128:131], v[188:191], v[116:119]
	v_mfma_f32_16x16x32_bf16 v[112:115], v[136:139], v[188:191], v[112:115]
	v_mfma_f32_16x16x32_bf16 v[108:111], v[128:131], v[196:199], v[108:111]
	v_mfma_f32_16x16x32_bf16 v[104:107], v[136:139], v[196:199], v[104:107]
	v_mfma_f32_16x16x32_bf16 v[100:103], v[128:131], v[204:207], v[100:103]
	v_mfma_f32_16x16x32_bf16 v[96:99], v[136:139], v[204:207], v[96:99]
	v_mfma_f32_16x16x32_bf16 v[124:127], v[132:135], v[184:187], v[124:127]
	v_mfma_f32_16x16x32_bf16 v[120:123], v[140:143], v[184:187], v[120:123]
	v_mfma_f32_16x16x32_bf16 v[116:119], v[132:135], v[192:195], v[116:119]
	v_mfma_f32_16x16x32_bf16 v[112:115], v[140:143], v[192:195], v[112:115]
	v_mfma_f32_16x16x32_bf16 v[108:111], v[132:135], v[200:203], v[108:111]
	v_mfma_f32_16x16x32_bf16 v[104:107], v[140:143], v[200:203], v[104:107]
	v_mfma_f32_16x16x32_bf16 v[100:103], v[132:135], v[208:211], v[100:103]
	v_mfma_f32_16x16x32_bf16 v[96:99], v[140:143], v[208:211], v[96:99]
	v_mfma_f32_16x16x32_bf16 v[60:63], v[158:161], v[180:183], v[60:63]
	v_mfma_f32_16x16x32_bf16 v[56:59], v[172:175], v[180:183], v[56:59]
	v_mfma_f32_16x16x32_bf16 v[52:55], v[158:161], v[188:191], v[52:55]
	v_mfma_f32_16x16x32_bf16 v[48:51], v[172:175], v[188:191], v[48:51]
	v_mfma_f32_16x16x32_bf16 v[44:47], v[158:161], v[196:199], v[44:47]
	v_mfma_f32_16x16x32_bf16 v[40:43], v[172:175], v[196:199], v[40:43]
	v_mfma_f32_16x16x32_bf16 v[36:39], v[158:161], v[204:207], v[36:39]
	v_mfma_f32_16x16x32_bf16 v[32:35], v[172:175], v[204:207], v[32:35]
	v_mfma_f32_16x16x32_bf16 v[60:63], v[162:165], v[184:187], v[60:63]
	v_mfma_f32_16x16x32_bf16 v[56:59], v[176:179], v[184:187], v[56:59]
	v_mfma_f32_16x16x32_bf16 v[52:55], v[162:165], v[192:195], v[52:55]
	v_mfma_f32_16x16x32_bf16 v[48:51], v[176:179], v[192:195], v[48:51]
	v_mfma_f32_16x16x32_bf16 v[44:47], v[162:165], v[200:203], v[44:47]
	v_mfma_f32_16x16x32_bf16 v[40:43], v[176:179], v[200:203], v[40:43]
	v_mfma_f32_16x16x32_bf16 v[36:39], v[162:165], v[208:211], v[36:39]
	v_mfma_f32_16x16x32_bf16 v[32:35], v[176:179], v[208:211], v[32:35]
	s_barrier
	s_add_i32 s2, s44, s33
	v_lshl_add_u64 v[144:145], s[30:31], 0, v[148:149]
	s_mov_b32 m0, s2
	ds_read_b128 v[180:183], v171 offset:16384
	ds_read_b128 v[184:187], v171 offset:17408
	ds_read_b128 v[188:191], v171 offset:18432
	ds_read_b128 v[192:195], v171 offset:19456
	ds_read_b128 v[196:199], v171 offset:20480
	ds_read_b128 v[200:203], v171 offset:21504
	ds_read_b128 v[204:207], v171 offset:22528
	ds_read_b128 v[208:211], v171 offset:23552
	global_load_lds_dwordx4 v[144:145], off
	s_add_i32 m0, s2, 0x2000
	s_add_u32 s2, s30, 0xb0000
	v_lshl_add_u64 v[166:167], s[30:31], 0, v[152:153]
	s_addc_u32 s3, s31, 0
	s_add_i32 s55, s45, s33
	global_load_lds_dwordx4 v[166:167], off
	v_lshl_add_u64 v[212:213], s[2:3], 0, v[148:149]
	s_mov_b32 m0, s55
	v_lshl_add_u64 v[214:215], s[34:35], 0, v[150:151]
	global_load_lds_dwordx4 v[212:213], off
	v_lshl_add_u64 v[212:213], s[2:3], 0, v[152:153]
	s_add_i32 m0, s55, 0x2000
	s_nop 0
	global_load_lds_dwordx4 v[212:213], off
	v_lshl_add_u64 v[212:213], s[34:35], 0, v[146:147]
	s_mov_b32 m0, s36
	s_nop 0
	global_load_lds_dwordx4 v[212:213], off
	s_mov_b32 m0, s37
	s_nop 0
	global_load_lds_dwordx4 v[214:215], off
	s_waitcnt vmcnt(8)
	s_waitcnt lgkmcnt(0)
	s_barrier
	s_waitcnt lgkmcnt(0)
	v_mfma_f32_16x16x32_bf16 v[92:95], v[128:131], v[180:183], v[92:95]
	v_mfma_f32_16x16x32_bf16 v[88:91], v[136:139], v[180:183], v[88:91]
	v_mfma_f32_16x16x32_bf16 v[84:87], v[128:131], v[188:191], v[84:87]
	v_mfma_f32_16x16x32_bf16 v[80:83], v[136:139], v[188:191], v[80:83]
	v_mfma_f32_16x16x32_bf16 v[76:79], v[128:131], v[196:199], v[76:79]
	v_mfma_f32_16x16x32_bf16 v[72:75], v[136:139], v[196:199], v[72:75]
	v_mfma_f32_16x16x32_bf16 v[68:71], v[128:131], v[204:207], v[68:71]
	v_mfma_f32_16x16x32_bf16 v[64:67], v[136:139], v[204:207], v[64:67]
	v_mfma_f32_16x16x32_bf16 v[92:95], v[132:135], v[184:187], v[92:95]
	v_mfma_f32_16x16x32_bf16 v[88:91], v[140:143], v[184:187], v[88:91]
	v_mfma_f32_16x16x32_bf16 v[84:87], v[132:135], v[192:195], v[84:87]
	v_mfma_f32_16x16x32_bf16 v[80:83], v[140:143], v[192:195], v[80:83]
	v_mfma_f32_16x16x32_bf16 v[76:79], v[132:135], v[200:203], v[76:79]
	v_mfma_f32_16x16x32_bf16 v[72:75], v[140:143], v[200:203], v[72:75]
	v_mfma_f32_16x16x32_bf16 v[68:71], v[132:135], v[208:211], v[68:71]
	v_mfma_f32_16x16x32_bf16 v[64:67], v[140:143], v[208:211], v[64:67]
	v_mfma_f32_16x16x32_bf16 v[28:31], v[158:161], v[180:183], v[28:31]
	v_mfma_f32_16x16x32_bf16 v[24:27], v[172:175], v[180:183], v[24:27]
	v_mfma_f32_16x16x32_bf16 v[20:23], v[158:161], v[188:191], v[20:23]
	v_mfma_f32_16x16x32_bf16 v[16:19], v[172:175], v[188:191], v[16:19]
	v_mfma_f32_16x16x32_bf16 v[12:15], v[158:161], v[196:199], v[12:15]
	v_mfma_f32_16x16x32_bf16 v[8:11], v[172:175], v[196:199], v[8:11]
	v_mfma_f32_16x16x32_bf16 v[4:7], v[158:161], v[204:207], v[4:7]
	v_mfma_f32_16x16x32_bf16 v[0:3], v[172:175], v[204:207], v[0:3]
	v_mfma_f32_16x16x32_bf16 v[28:31], v[162:165], v[184:187], v[28:31]
	v_mfma_f32_16x16x32_bf16 v[24:27], v[176:179], v[184:187], v[24:27]
	v_mfma_f32_16x16x32_bf16 v[20:23], v[162:165], v[192:195], v[20:23]
	v_mfma_f32_16x16x32_bf16 v[16:19], v[176:179], v[192:195], v[16:19]
	v_mfma_f32_16x16x32_bf16 v[12:15], v[162:165], v[200:203], v[12:15]
	v_mfma_f32_16x16x32_bf16 v[8:11], v[176:179], v[200:203], v[8:11]
	v_mfma_f32_16x16x32_bf16 v[4:7], v[162:165], v[208:211], v[4:7]
	v_mfma_f32_16x16x32_bf16 v[0:3], v[176:179], v[208:211], v[0:3]
	s_barrier
; #define G_STAGE(bufoff, gbase, voff) do { _Pragma("unroll") for (int _i = 0; _i < 2; ++_i) \
;         __builtin_amdgcn_global_load_lds((const unsigned*)((const char*)(gbase) + voff[_i]), (LAS unsigned*)(lds + (bufoff) + ldsw + _i * 8192), 16, 0, 0); } while (0)
; #define G_LDA(dst, b, h) do { _Pragma("unroll") for (int m = 0; m < 4; ++m) _Pragma("unroll") for (int k = 0; k < 2; ++k) dst[m][k] = *(const LAS bf16x8*)(lds + G_SA(b, h) + aoff + m * 2048 + k * 1024); } while (0)
; #define G_LDB(dst, b, h) do { _Pragma("unroll") for (int n = 0; n < 2; ++n) _Pragma("unroll") for (int k = 0; k < 2; ++k) dst[n][k] = *(const LAS bf16x8*)(lds + G_SB(b, h) + boff + n * 2048 + k * 1024); } while (0)
; #define G_MMA(ai, bj, At_, Bt_) do { __builtin_amdgcn_s_setprio(1); _Pragma("unroll") for (int m = 0; m < 4; ++m) _Pragma("unroll") for (int n = 0; n < 2; ++n) _Pragma("unroll") for (int k = 0; k < 2; ++k) \
;         acc[ai][bj][m][n] = __builtin_amdgcn_mfma_f32_16x16x32_bf16(Bt_[n][k], At_[m][k], acc[ai][bj][m][n], 0, 0, 0); __builtin_amdgcn_s_setprio(0); } while (0)
; #define WAIT_V(n) asm volatile("s_waitcnt vmcnt(" #n ")" ::: "memory")
; #define WAIT_L(n) asm volatile("s_waitcnt lgkmcnt(" #n ")" ::: "memory")
; #define BAR __builtin_amdgcn_s_barrier()
; #define SCHED __builtin_amdgcn_sched_barrier(0)
; template <class Get, class Epi>
; DI void gemm_loop(int ntiles, int ld, char* shm, const Get& get, const Epi& epi) {
;     ...
;             G_LDB(B0, 1, 0); G_LDB(B1, 1, 1); SCHED; G_LDA(At, 1, 0); G_STAGE(G_SA(0, 1), a2 + hstep, voffA);
;             WAIT_V(8); WAIT_L(0); BAR; G_MMA(0, 0, At, B0); G_MMA(0, 1, At, B1); BAR; SCHED;
;             G_LDA(At, 1, 1); G_STAGE(G_SB(1, 0), b3, voffB); G_STAGE(G_SB(1, 1), b3 + hstep, voffB); G_STAGE(G_SA(1, 0), a3, voffA);
;             WAIT_V(8); WAIT_L(0); BAR; G_MMA(1, 0, At, B0); G_MMA(1, 1, At, B1); BAR; SCHED;
;         }
	s_add_i32 s55, 0, 0x18000
	s_add_i32 s56, 0, 0x1c000
	v_add_u32_e32 v140, s55, v168
	v_add_u32_e32 v176, s56, v168
	ds_read_b128 v[128:131], v140
	ds_read_b128 v[132:135], v140 offset:1024
	ds_read_b128 v[136:139], v140 offset:2048
	ds_read_b128 v[140:143], v140 offset:3072
	ds_read_b128 v[158:161], v176
	ds_read_b128 v[162:165], v176 offset:1024
	ds_read_b128 v[172:175], v176 offset:2048
	ds_read_b128 v[176:179], v176 offset:3072
	s_add_u32 s2, s34, 0xb0000
	s_addc_u32 s3, s35, 0
	s_mov_b32 m0, s38
	v_lshl_add_u64 v[216:217], s[2:3], 0, v[146:147]
	ds_read_b128 v[180:183], v171 offset:32768
	ds_read_b128 v[184:187], v171 offset:33792
	ds_read_b128 v[188:191], v171 offset:34816
	ds_read_b128 v[192:195], v171 offset:35840
	ds_read_b128 v[196:199], v171 offset:36864
	ds_read_b128 v[200:203], v171 offset:37888
	ds_read_b128 v[204:207], v171 offset:38912
	ds_read_b128 v[208:211], v171 offset:39936
	global_load_lds_dwordx4 v[216:217], off
	v_lshl_add_u64 v[216:217], s[2:3], 0, v[150:151]
	s_mov_b32 m0, s39
	s_nop 0
	global_load_lds_dwordx4 v[216:217], off
	s_waitcnt vmcnt(8)
	s_waitcnt lgkmcnt(0)
	s_barrier
	s_waitcnt lgkmcnt(0)
	v_mfma_f32_16x16x32_bf16 v[124:127], v[128:131], v[180:183], v[124:127]
	v_mfma_f32_16x16x32_bf16 v[120:123], v[136:139], v[180:183], v[120:123]
	v_mfma_f32_16x16x32_bf16 v[116:119], v[128:131], v[188:191], v[116:119]
	v_mfma_f32_16x16x32_bf16 v[112:115], v[136:139], v[188:191], v[112:115]
	v_mfma_f32_16x16x32_bf16 v[108:111], v[128:131], v[196:199], v[108:111]
	v_mfma_f32_16x16x32_bf16 v[104:107], v[136:139], v[196:199], v[104:107]
	v_mfma_f32_16x16x32_bf16 v[100:103], v[128:131], v[204:207], v[100:103]
	v_mfma_f32_16x16x32_bf16 v[96:99], v[136:139], v[204:207], v[96:99]
	v_mfma_f32_16x16x32_bf16 v[124:127], v[132:135], v[184:187], v[124:127]
	v_mfma_f32_16x16x32_bf16 v[120:123], v[140:143], v[184:187], v[120:123]
	v_mfma_f32_16x16x32_bf16 v[116:119], v[132:135], v[192:195], v[116:119]
	v_mfma_f32_16x16x32_bf16 v[112:115], v[140:143], v[192:195], v[112:115]
	v_mfma_f32_16x16x32_bf16 v[108:111], v[132:135], v[200:203], v[108:111]
	v_mfma_f32_16x16x32_bf16 v[104:107], v[140:143], v[200:203], v[104:107]
	v_mfma_f32_16x16x32_bf16 v[100:103], v[132:135], v[208:211], v[100:103]
	v_mfma_f32_16x16x32_bf16 v[96:99], v[140:143], v[208:211], v[96:99]
	v_mfma_f32_16x16x32_bf16 v[60:63], v[158:161], v[180:183], v[60:63]
	v_mfma_f32_16x16x32_bf16 v[56:59], v[172:175], v[180:183], v[56:59]
	v_mfma_f32_16x16x32_bf16 v[52:55], v[158:161], v[188:191], v[52:55]
	v_mfma_f32_16x16x32_bf16 v[48:51], v[172:175], v[188:191], v[48:51]
	v_mfma_f32_16x16x32_bf16 v[44:47], v[158:161], v[196:199], v[44:47]
	v_mfma_f32_16x16x32_bf16 v[40:43], v[172:175], v[196:199], v[40:43]
	v_mfma_f32_16x16x32_bf16 v[36:39], v[158:161], v[204:207], v[36:39]
	v_mfma_f32_16x16x32_bf16 v[32:35], v[172:175], v[204:207], v[32:35]
	v_mfma_f32_16x16x32_bf16 v[60:63], v[162:165], v[184:187], v[60:63]
	v_mfma_f32_16x16x32_bf16 v[56:59], v[176:179], v[184:187], v[56:59]
	v_mfma_f32_16x16x32_bf16 v[52:55], v[162:165], v[192:195], v[52:55]
	v_mfma_f32_16x16x32_bf16 v[48:51], v[176:179], v[192:195], v[48:51]
	v_mfma_f32_16x16x32_bf16 v[44:47], v[162:165], v[200:203], v[44:47]
	v_mfma_f32_16x16x32_bf16 v[40:43], v[176:179], v[200:203], v[40:43]
	v_mfma_f32_16x16x32_bf16 v[36:39], v[162:165], v[208:211], v[36:39]
	v_mfma_f32_16x16x32_bf16 v[32:35], v[176:179], v[208:211], v[32:35]
	s_barrier
	s_add_i32 s2, s55, s33
	v_lshl_add_u64 v[144:145], v[144:145], 0, s[6:7]
	s_mov_b32 m0, s2
	ds_read_b128 v[180:183], v171 offset:49152
	ds_read_b128 v[184:187], v171 offset:50176
	ds_read_b128 v[188:191], v171 offset:51200
	ds_read_b128 v[192:195], v171 offset:52224
	ds_read_b128 v[196:199], v171 offset:53248
	ds_read_b128 v[200:203], v171 offset:54272
	ds_read_b128 v[204:207], v171 offset:55296
	ds_read_b128 v[208:211], v171 offset:56320
	global_load_lds_dwordx4 v[144:145], off
	s_add_i32 m0, s2, 0x2000
	s_add_u32 s2, s30, 0xb0080
	v_lshl_add_u64 v[144:145], v[166:167], 0, s[6:7]
	s_addc_u32 s3, s31, 0
	s_add_i32 s30, s56, s33
	global_load_lds_dwordx4 v[144:145], off
	v_lshl_add_u64 v[144:145], s[2:3], 0, v[148:149]
	s_mov_b32 m0, s30
	s_nop 0
	global_load_lds_dwordx4 v[144:145], off
	v_lshl_add_u64 v[144:145], s[2:3], 0, v[152:153]
	s_add_i32 m0, s30, 0x2000
	s_nop 0
	global_load_lds_dwordx4 v[144:145], off
	v_lshl_add_u64 v[144:145], v[212:213], 0, s[6:7]
	s_mov_b32 m0, s42
	s_nop 0
	global_load_lds_dwordx4 v[144:145], off
	v_lshl_add_u64 v[144:145], v[214:215], 0, s[6:7]
	s_mov_b32 m0, s43
	s_nop 0
	global_load_lds_dwordx4 v[144:145], off
	s_waitcnt vmcnt(8)
	s_waitcnt lgkmcnt(0)
	s_barrier
	s_waitcnt lgkmcnt(0)
	v_mfma_f32_16x16x32_bf16 v[92:95], v[128:131], v[180:183], v[92:95]
	v_mfma_f32_16x16x32_bf16 v[88:91], v[136:139], v[180:183], v[88:91]
	v_mfma_f32_16x16x32_bf16 v[84:87], v[128:131], v[188:191], v[84:87]
	v_mfma_f32_16x16x32_bf16 v[80:83], v[136:139], v[188:191], v[80:83]
	v_mfma_f32_16x16x32_bf16 v[76:79], v[128:131], v[196:199], v[76:79]
	v_mfma_f32_16x16x32_bf16 v[72:75], v[136:139], v[196:199], v[72:75]
	v_mfma_f32_16x16x32_bf16 v[68:71], v[128:131], v[204:207], v[68:71]
	v_mfma_f32_16x16x32_bf16 v[64:67], v[136:139], v[204:207], v[64:67]
	v_mfma_f32_16x16x32_bf16 v[92:95], v[132:135], v[184:187], v[92:95]
	v_mfma_f32_16x16x32_bf16 v[88:91], v[140:143], v[184:187], v[88:91]
	v_mfma_f32_16x16x32_bf16 v[84:87], v[132:135], v[192:195], v[84:87]
	v_mfma_f32_16x16x32_bf16 v[80:83], v[140:143], v[192:195], v[80:83]
	v_mfma_f32_16x16x32_bf16 v[76:79], v[132:135], v[200:203], v[76:79]
	v_mfma_f32_16x16x32_bf16 v[72:75], v[140:143], v[200:203], v[72:75]
	v_mfma_f32_16x16x32_bf16 v[68:71], v[132:135], v[208:211], v[68:71]
	v_mfma_f32_16x16x32_bf16 v[64:67], v[140:143], v[208:211], v[64:67]
	v_mfma_f32_16x16x32_bf16 v[28:31], v[158:161], v[180:183], v[28:31]
	v_mfma_f32_16x16x32_bf16 v[24:27], v[172:175], v[180:183], v[24:27]
	v_mfma_f32_16x16x32_bf16 v[20:23], v[158:161], v[188:191], v[20:23]
	v_mfma_f32_16x16x32_bf16 v[16:19], v[172:175], v[188:191], v[16:19]
	v_mfma_f32_16x16x32_bf16 v[12:15], v[158:161], v[196:199], v[12:15]
	v_mfma_f32_16x16x32_bf16 v[8:11], v[172:175], v[196:199], v[8:11]
	v_mfma_f32_16x16x32_bf16 v[4:7], v[158:161], v[204:207], v[4:7]
	v_mfma_f32_16x16x32_bf16 v[0:3], v[172:175], v[204:207], v[0:3]
	v_mfma_f32_16x16x32_bf16 v[28:31], v[162:165], v[184:187], v[28:31]
	v_mfma_f32_16x16x32_bf16 v[24:27], v[176:179], v[184:187], v[24:27]
	v_mfma_f32_16x16x32_bf16 v[20:23], v[162:165], v[192:195], v[20:23]
	v_mfma_f32_16x16x32_bf16 v[16:19], v[176:179], v[192:195], v[16:19]
	v_mfma_f32_16x16x32_bf16 v[12:15], v[162:165], v[200:203], v[12:15]
	v_mfma_f32_16x16x32_bf16 v[8:11], v[176:179], v[200:203], v[8:11]
	v_mfma_f32_16x16x32_bf16 v[4:7], v[162:165], v[208:211], v[4:7]
	v_mfma_f32_16x16x32_bf16 v[0:3], v[176:179], v[208:211], v[0:3]
	s_barrier
	s_add_i32 s54, s54, 2
	s_add_u32 s52, s52, 0x100
	s_addc_u32 s53, s53, 0
	s_cmp_gt_u32 s54, 41
	s_mov_b64 s[2:3], s[24:25]
	s_cbranch_scc0 .LBB0_3759
